# outproj/gate epilogues: issue both halves (16 loads) of each stage_load_tile before the first wait
# speedup vs baseline: 1.0078x; 1.0078x over previous
; DI int otid() { int t = threadIdx.x; asm volatile("" : "+v"(t)); return t; }
; template <bool NT>
; DI void stage_load_tile(bf16_t* stg, const bf16_t* tilebase) {
;   const int tid = otid();
;   const int r0 = tid >> 5, c = tid & 31;
;   const unsigned o0 = (unsigned)(r0 * 1024 + c * 8);
;   __builtin_amdgcn_sched_barrier(0);
; #pragma unroll
;   for (int hf = 0; hf < 2; ++hf) {
; #pragma unroll
;     for (int it = 8 * hf; it < 8 * hf + 8; ++it) {
;       const u32x4* gp = (const u32x4*)(tilebase + (o0 + (unsigned)(it * 16 * 1024)));
;       stage_write16(stg, r0 + 16 * it, c, NT ? __builtin_nontemporal_load(gp) : *gp);
;     }
;     __builtin_amdgcn_sched_barrier(0);
;   }
; }
.LBB0_409:
	v_bfe_u32 v198, v167, 5, 1
	s_ashr_i32 s37, s36, 31
	s_lshl_b64 s[52:53], s[36:37], 19
	s_add_u32 s41, s80, s52
	v_mov_b32_e32 v160, v192
	s_addc_u32 s53, s81, s53
	s_lshl_b32 s52, s40, 1
	s_add_u32 s40, s41, s52
	v_and_b32_e32 v200, 31, v160
	v_ashrrev_i32_e32 v199, 5, v160
	v_lshlrev_b32_e32 v160, 3, v200
	s_addc_u32 s41, s53, 0
	v_lshl_or_b32 v160, v199, 10, v160
	v_add_u32_e32 v164, 0x4000, v160
	v_mov_b32_e32 v165, v161
	v_add_u32_e32 v172, 0x8000, v160
	v_mov_b32_e32 v173, v161
	v_add_u32_e32 v174, 0xc000, v160
	v_mov_b32_e32 v175, v161
	v_add_u32_e32 v180, 0x10000, v160
	v_mov_b32_e32 v181, v161
	v_add_u32_e32 v182, 0x14000, v160
	v_mov_b32_e32 v183, v161
	v_add_u32_e32 v188, 0x18000, v160
	v_mov_b32_e32 v189, v161
	v_add_u32_e32 v190, 0x1c000, v160
	v_mov_b32_e32 v191, v161
	v_lshl_add_u64 v[162:163], v[160:161], 1, s[40:41]
	v_lshl_add_u64 v[168:169], v[164:165], 1, s[40:41]
	v_lshl_add_u64 v[172:173], v[172:173], 1, s[40:41]
	v_lshl_add_u64 v[176:177], v[174:175], 1, s[40:41]
	v_lshl_add_u64 v[180:181], v[180:181], 1, s[40:41]
	v_lshl_add_u64 v[184:185], v[182:183], 1, s[40:41]
	v_lshl_add_u64 v[188:189], v[188:189], 1, s[40:41]
	v_lshl_add_u64 v[194:195], v[190:191], 1, s[40:41]
	global_load_dwordx4 v[162:165], v[162:163], off nt
	s_nop 0
	global_load_dwordx4 v[168:171], v[168:169], off nt
	s_nop 0
	global_load_dwordx4 v[172:175], v[172:173], off nt
	s_nop 0
	global_load_dwordx4 v[176:179], v[176:177], off nt
	s_nop 0
	global_load_dwordx4 v[180:183], v[180:181], off nt
	s_nop 0
	global_load_dwordx4 v[184:187], v[184:185], off nt
	s_nop 0
	global_load_dwordx4 v[188:191], v[188:189], off nt
	s_nop 0
	global_load_dwordx4 v[194:197], v[194:195], off nt
	v_add_u32_e32 v222, 0x20000, v160
	v_mov_b32_e32 v223, v161
	v_add_u32_e32 v224, 0x24000, v160
	v_mov_b32_e32 v225, v161
	v_add_u32_e32 v230, 0x28000, v160
	v_mov_b32_e32 v231, v161
	v_add_u32_e32 v232, 0x2c000, v160
	v_mov_b32_e32 v233, v161
	v_add_u32_e32 v238, 0x30000, v160
	v_mov_b32_e32 v239, v161
	v_add_u32_e32 v240, 0x34000, v160
	v_mov_b32_e32 v241, v161
	v_add_u32_e32 v248, 0x38000, v160
	v_mov_b32_e32 v249, v161
	v_add_u32_e32 v160, 0x3c000, v160
	v_lshl_add_u64 v[222:223], v[222:223], 1, s[40:41]
	v_lshl_add_u64 v[226:227], v[224:225], 1, s[40:41]
	v_lshl_add_u64 v[230:231], v[230:231], 1, s[40:41]
	v_lshl_add_u64 v[234:235], v[232:233], 1, s[40:41]
	v_lshl_add_u64 v[238:239], v[238:239], 1, s[40:41]
	v_lshl_add_u64 v[242:243], v[240:241], 1, s[40:41]
	v_lshl_add_u64 v[248:249], v[248:249], 1, s[40:41]
	v_lshl_add_u64 v[252:253], v[160:161], 1, s[40:41]
	global_load_dwordx4 v[222:225], v[222:223], off nt
	s_nop 0
	global_load_dwordx4 v[226:229], v[226:227], off nt
	s_nop 0
	global_load_dwordx4 v[230:233], v[230:231], off nt
	s_nop 0
	global_load_dwordx4 v[234:237], v[234:235], off nt
	s_nop 0
	global_load_dwordx4 v[238:241], v[238:239], off nt
	s_nop 0
	global_load_dwordx4 v[242:245], v[242:243], off nt
	s_nop 0
	global_load_dwordx4 v[248:251], v[248:249], off nt
	s_nop 0
	global_load_dwordx4 v[252:255], v[252:253], off nt
	v_mul_lo_u32 v199, v199, s48
	v_lshl_add_u32 v199, v200, 4, v199
	v_add_u32_e32 v200, 0x2080, v199
	v_add_u32_e32 v201, 0x4100, v199
	v_add_u32_e32 v202, 0x6180, v199
	v_add_u32_e32 v203, 0x8200, v199
	v_add_u32_e32 v204, 0xa280, v199
	v_add_u32_e32 v205, 0xc300, v199
	v_add_u32_e32 v206, 0xe380, v199
	s_waitcnt vmcnt(15)
	ds_write2_b64 v199, v[162:163], v[164:165] offset1:1
	s_waitcnt vmcnt(14)
	ds_write2_b64 v200, v[168:169], v[170:171] offset1:1
	s_waitcnt vmcnt(13)
	ds_write2_b64 v201, v[172:173], v[174:175] offset1:1
	s_waitcnt vmcnt(12)
	ds_write2_b64 v202, v[176:177], v[178:179] offset1:1
	s_waitcnt vmcnt(11)
	ds_write2_b64 v203, v[180:181], v[182:183] offset1:1
	s_waitcnt vmcnt(10)
	ds_write2_b64 v204, v[184:185], v[186:187] offset1:1
	s_waitcnt vmcnt(9)
	ds_write2_b64 v205, v[188:189], v[190:191] offset1:1
	s_waitcnt vmcnt(8)
	ds_write2_b64 v206, v[194:195], v[196:197] offset1:1
	v_add_u32_e32 v160, 0x10400, v199
	v_add_u32_e32 v200, 0x12480, v199
	v_add_u32_e32 v201, 0x14500, v199
	v_add_u32_e32 v202, 0x16580, v199
	v_add_u32_e32 v203, 0x18600, v199
	v_add_u32_e32 v204, 0x1a680, v199
	v_add_u32_e32 v205, 0x1c700, v199
	v_add_u32_e32 v199, 0x1e780, v199
	s_waitcnt vmcnt(7)
	ds_write2_b64 v160, v[222:223], v[224:225] offset1:1
	s_waitcnt vmcnt(6)
	ds_write2_b64 v200, v[226:227], v[228:229] offset1:1
	s_waitcnt vmcnt(5)
	ds_write2_b64 v201, v[230:231], v[232:233] offset1:1
	s_waitcnt vmcnt(4)
	ds_write2_b64 v202, v[234:235], v[236:237] offset1:1
	s_waitcnt vmcnt(3)
	ds_write2_b64 v203, v[238:239], v[240:241] offset1:1
	s_waitcnt vmcnt(2)
	ds_write2_b64 v204, v[242:243], v[244:245] offset1:1
	s_waitcnt vmcnt(1)
	ds_write2_b64 v205, v[248:249], v[250:251] offset1:1
	s_waitcnt vmcnt(0)
	ds_write2_b64 v199, v[252:253], v[254:255] offset1:1
	v_lshlrev_b32_e32 v160, 3, v198
	v_and_b32_e32 v163, 0xdf, v167
	v_and_or_b32 v164, v167, s43, v160
	v_ashrrev_i32_e32 v165, 7, v167
	v_mad_u32_u24 v167, v163, s48, v164
	s_waitcnt lgkmcnt(0)
	s_barrier
; DI unsigned pack2(float a, float b) { f32x2_t v = {a, b}; bf16x2_t r = __builtin_convertvector(v, bf16x2_t); return __builtin_bit_cast(unsigned, r); }
; DI float bflo(unsigned u) { return __uint_as_float(u << 16); }
; DI float bfhi(unsigned u) { return __uint_as_float(u & 0xffff0000u); }
; template <bool XF32>
; DI void phase_outproj(const Params& P, int layer, const void* xres, const bf16_t* og, unsigned char* smem, int L, int G) {
;     ...
; #pragma unroll
;     for (int j = 0; j < 2; ++j)
; #pragma unroll
;       for (int ch = 0; ch < 2; ++ch) {
;         float s1 = 0.f, s2 = 0.f;
; #pragma unroll
;         for (int i = 2 * ch; i < 2 * ch + 2; ++i)
; #pragma unroll
;           for (int q4 = 0; q4 < 4; ++q4) {
;             uint2* pp = (uint2*)(stg + (wn * 64 + j * 32 + r) * STG + wm * 128 + i * 32 + 8 * q4 + 4 * h);
;             const uint2 xv = *pp;
;             uint2 pk;
;             pk.x = pack2(DN_ALPHA * bflo(xv.x) + acc[i][j][4 * q4], DN_ALPHA * bfhi(xv.x) + acc[i][j][4 * q4 + 1]);
;             pk.y = pack2(DN_ALPHA * bflo(xv.y) + acc[i][j][4 * q4 + 2], DN_ALPHA * bfhi(xv.y) + acc[i][j][4 * q4 + 3]);
;             *pp = pk;
;             const float f0 = bflo(pk.x), f1 = bfhi(pk.x), f2 = bflo(pk.y), f3 = bfhi(pk.y);
;             s1 += (f0 + f1) + (f2 + f3); s2 += (f0 * f0 + f1 * f1) + (f2 * f2 + f3 * f3);
;             __builtin_amdgcn_sched_barrier(0);
;           }
	ds_read_b64 v[168:169], v167
	v_and_b32_e32 v162, 64, v166
	v_xor_b32_e32 v160, 32, v166
	v_add_u32_e32 v162, 64, v162
	v_cmp_lt_i32_e32 vcc, v160, v162
	v_or_b32_e32 v162, s51, v163
	v_and_b32_e32 v165, -2, v165
	v_ashrrev_i32_e32 v163, 31, v162
	s_waitcnt lgkmcnt(0)
	v_lshlrev_b32_e32 v170, 16, v168
	v_and_b32_e32 v171, 0xffff0000, v168
	v_lshlrev_b32_e32 v168, 16, v169
	v_and_b32_e32 v169, 0xffff0000, v169
	v_cndmask_b32_e32 v160, v166, v160, vcc
	v_lshl_add_u32 v206, s50, 2, v165
	v_lshlrev_b64 v[164:165], 7, v[162:163]
	v_pk_fma_f32 v[112:113], v[170:171], s[34:35], v[112:113] op_sel_hi:[1,0,1]
	v_pk_fma_f32 v[114:115], v[168:169], s[34:35], v[114:115] op_sel_hi:[1,0,1]
	v_lshlrev_b32_e32 v160, 2, v160
	v_cmp_eq_u32_e32 vcc, 0, v198
	v_lshl_add_u64 v[164:165], s[78:79], 0, v[164:165]
	v_cvt_pk_bf16_f32 v112, v112, v113
	v_cvt_pk_bf16_f32 v113, v114, v115
	ds_write_b64 v167, v[112:113]
	v_and_b32_e32 v114, 0xffff0000, v112
	v_lshlrev_b32_e32 v168, 16, v113
	ds_read_b64 v[170:171], v167 offset:16
	s_waitcnt lgkmcnt(0)
	v_lshlrev_b32_e32 v172, 16, v170
	v_and_b32_e32 v173, 0xffff0000, v170
	v_lshlrev_b32_e32 v170, 16, v171
	v_and_b32_e32 v171, 0xffff0000, v171
	v_pk_fma_f32 v[116:117], v[172:173], s[34:35], v[116:117] op_sel_hi:[1,0,1]
	v_pk_fma_f32 v[118:119], v[170:171], s[34:35], v[118:119] op_sel_hi:[1,0,1]
	v_cvt_pk_bf16_f32 v116, v116, v117
	v_cvt_pk_bf16_f32 v117, v118, v119
	ds_write_b64 v167, v[116:117] offset:16
	v_lshlrev_b32_e32 v118, 16, v117
	v_and_b32_e32 v119, 0xffff0000, v117
	v_lshlrev_b32_e32 v171, 16, v116
	v_and_b32_e32 v117, 0xffff0000, v116
	v_lshlrev_b32_e32 v170, 16, v112
	v_mov_b32_e32 v115, v171
	v_and_b32_e32 v116, 0xffff0000, v113
	v_mov_b32_e32 v169, v117
	v_pk_mul_f32 v[172:173], v[170:171], v[170:171]
	v_pk_mul_f32 v[174:175], v[114:115], v[114:115]
	v_pk_add_f32 v[114:115], v[170:171], v[114:115]
	v_pk_mul_f32 v[112:113], v[168:169], v[168:169]
	v_pk_mul_f32 v[176:177], v[116:117], v[116:117]
	v_pk_add_f32 v[168:169], v[116:117], v[168:169]
	v_mul_f32_e32 v178, v118, v118
	v_mov_b32_e32 v115, v173
	v_mov_b32_e32 v169, v177
	v_pk_fma_f32 v[178:179], v[118:119], v[118:119], v[178:179] op_sel_hi:[1,1,0]
	ds_read_b64 v[180:181], v167 offset:32
	s_waitcnt lgkmcnt(0)
	v_lshlrev_b32_e32 v182, 16, v180
	v_and_b32_e32 v183, 0xffff0000, v180
	v_lshlrev_b32_e32 v180, 16, v181
	v_and_b32_e32 v181, 0xffff0000, v181
	v_pk_fma_f32 v[120:121], v[182:183], s[34:35], v[120:121] op_sel_hi:[1,0,1]
	v_pk_fma_f32 v[122:123], v[180:181], s[34:35], v[122:123] op_sel_hi:[1,0,1]
	v_cvt_pk_bf16_f32 v120, v120, v121
	v_cvt_pk_bf16_f32 v121, v122, v123
	ds_write_b64 v167, v[120:121] offset:32
	v_lshlrev_b32_e32 v122, 16, v120
	v_and_b32_e32 v120, 0xffff0000, v120
	v_lshlrev_b32_e32 v180, 16, v121
	v_and_b32_e32 v182, 0xffff0000, v121
	v_mul_f32_e32 v123, v122, v122
	v_mul_f32_e32 v121, v120, v120
	v_mul_f32_e32 v181, v180, v180
	v_mul_f32_e32 v183, v182, v182
	ds_read_b64 v[184:185], v167 offset:48
	s_waitcnt lgkmcnt(0)
	v_lshlrev_b32_e32 v186, 16, v184
	v_and_b32_e32 v187, 0xffff0000, v184
	v_lshlrev_b32_e32 v184, 16, v185
	v_and_b32_e32 v185, 0xffff0000, v185
	v_pk_fma_f32 v[124:125], v[186:187], s[34:35], v[124:125] op_sel_hi:[1,0,1]
	v_pk_fma_f32 v[126:127], v[184:185], s[34:35], v[126:127] op_sel_hi:[1,0,1]
	v_cvt_pk_bf16_f32 v124, v124, v125
	v_cvt_pk_bf16_f32 v125, v126, v127
	ds_write_b64 v167, v[124:125] offset:48
	v_lshlrev_b32_e32 v126, 16, v124
	v_and_b32_e32 v124, 0xffff0000, v124
	v_lshlrev_b32_e32 v184, 16, v125
	v_and_b32_e32 v186, 0xffff0000, v125
	v_mul_f32_e32 v127, v126, v126
	v_mul_f32_e32 v125, v124, v124
	v_mul_f32_e32 v185, v184, v184
	v_mul_f32_e32 v187, v186, v186
	ds_read_b64 v[188:189], v167 offset:64
	s_waitcnt lgkmcnt(0)
	v_lshlrev_b32_e32 v190, 16, v188
	v_and_b32_e32 v191, 0xffff0000, v188
	v_lshlrev_b32_e32 v188, 16, v189
	v_and_b32_e32 v189, 0xffff0000, v189
	v_pk_fma_f32 v[96:97], v[190:191], s[34:35], v[96:97] op_sel_hi:[1,0,1]
	v_pk_fma_f32 v[98:99], v[188:189], s[34:35], v[98:99] op_sel_hi:[1,0,1]
	v_cvt_pk_bf16_f32 v96, v96, v97
	v_cvt_pk_bf16_f32 v97, v98, v99
	ds_write_b64 v167, v[96:97] offset:64
	v_lshlrev_b32_e32 v98, 16, v96
	v_and_b32_e32 v96, 0xffff0000, v96
	v_lshlrev_b32_e32 v188, 16, v97
	v_and_b32_e32 v190, 0xffff0000, v97
	v_mul_f32_e32 v99, v98, v98
	v_mul_f32_e32 v97, v96, v96
	v_mul_f32_e32 v189, v188, v188
	v_mul_f32_e32 v191, v190, v190
	ds_read_b64 v[194:195], v167 offset:80
	s_waitcnt lgkmcnt(0)
; DI unsigned pack2(float a, float b) { f32x2_t v = {a, b}; bf16x2_t r = __builtin_convertvector(v, bf16x2_t); return __builtin_bit_cast(unsigned, r); }
; DI float bflo(unsigned u) { return __uint_as_float(u << 16); }
; DI float bfhi(unsigned u) { return __uint_as_float(u & 0xffff0000u); }
; DI float shx(float v, int m) { return __shfl_xor(v, m, 64); }
; template <bool XF32>
; DI void phase_outproj(const Params& P, int layer, const void* xres, const bf16_t* og, unsigned char* smem, int L, int G) {
;     ...
; #pragma unroll
;     for (int j = 0; j < 2; ++j)
; #pragma unroll
;       for (int ch = 0; ch < 2; ++ch) {
;         float s1 = 0.f, s2 = 0.f;
; #pragma unroll
;         for (int i = 2 * ch; i < 2 * ch + 2; ++i)
; #pragma unroll
;           for (int q4 = 0; q4 < 4; ++q4) {
;             uint2* pp = (uint2*)(stg + (wn * 64 + j * 32 + r) * STG + wm * 128 + i * 32 + 8 * q4 + 4 * h);
;             const uint2 xv = *pp;
;             uint2 pk;
;             pk.x = pack2(DN_ALPHA * bflo(xv.x) + acc[i][j][4 * q4], DN_ALPHA * bfhi(xv.x) + acc[i][j][4 * q4 + 1]);
;             pk.y = pack2(DN_ALPHA * bflo(xv.y) + acc[i][j][4 * q4 + 2], DN_ALPHA * bfhi(xv.y) + acc[i][j][4 * q4 + 3]);
;             *pp = pk;
;             const float f0 = bflo(pk.x), f1 = bfhi(pk.x), f2 = bflo(pk.y), f3 = bfhi(pk.y);
;             s1 += (f0 + f1) + (f2 + f3); s2 += (f0 * f0 + f1 * f1) + (f2 * f2 + f3 * f3);
;             __builtin_amdgcn_sched_barrier(0);
;           }
;         s1 += shx(s1, 32); s2 += shx(s2, 32);
;         if (h == 0) {
;           const size_t row = (size_t)(mt * 256 + wn * 64 + j * 32 + r);
;           *(float2*)(stats + row * 32 + (nt * 4 + wm * 2 + ch) * 2) = make_float2(s1, s2);
;         }
;       }
	v_lshlrev_b32_e32 v196, 16, v194
	v_and_b32_e32 v197, 0xffff0000, v194
	v_lshlrev_b32_e32 v194, 16, v195
	v_and_b32_e32 v195, 0xffff0000, v195
	v_pk_fma_f32 v[100:101], v[196:197], s[34:35], v[100:101] op_sel_hi:[1,0,1]
	v_pk_fma_f32 v[102:103], v[194:195], s[34:35], v[102:103] op_sel_hi:[1,0,1]
	v_cvt_pk_bf16_f32 v100, v100, v101
	v_cvt_pk_bf16_f32 v101, v102, v103
	ds_write_b64 v167, v[100:101] offset:80
	v_lshlrev_b32_e32 v102, 16, v100
	v_and_b32_e32 v100, 0xffff0000, v100
	v_lshlrev_b32_e32 v194, 16, v101
	v_and_b32_e32 v196, 0xffff0000, v101
	v_mul_f32_e32 v101, v100, v100
	v_mul_f32_e32 v103, v102, v102
	v_mul_f32_e32 v195, v194, v194
	v_mul_f32_e32 v197, v196, v196
	ds_read_b64 v[198:199], v167 offset:96
	s_waitcnt lgkmcnt(0)
	v_lshlrev_b32_e32 v200, 16, v198
	v_and_b32_e32 v201, 0xffff0000, v198
	v_lshlrev_b32_e32 v198, 16, v199
	v_and_b32_e32 v199, 0xffff0000, v199
	v_pk_fma_f32 v[104:105], v[200:201], s[34:35], v[104:105] op_sel_hi:[1,0,1]
	v_pk_fma_f32 v[106:107], v[198:199], s[34:35], v[106:107] op_sel_hi:[1,0,1]
	v_cvt_pk_bf16_f32 v104, v104, v105
	v_cvt_pk_bf16_f32 v105, v106, v107
	ds_write_b64 v167, v[104:105] offset:96
	v_lshlrev_b32_e32 v106, 16, v104
	v_and_b32_e32 v104, 0xffff0000, v104
	v_lshlrev_b32_e32 v198, 16, v105
	v_and_b32_e32 v200, 0xffff0000, v105
	v_mul_f32_e32 v107, v106, v106
	v_mul_f32_e32 v105, v104, v104
	v_mul_f32_e32 v199, v198, v198
	v_mul_f32_e32 v201, v200, v200
	v_pk_mov_b32 v[170:171], v[170:171], v[172:173] op_sel:[1,0]
	v_pk_mov_b32 v[116:117], v[116:117], v[174:175] op_sel:[1,0]
	ds_read_b64 v[202:203], v167 offset:112
	v_pk_add_f32 v[116:117], v[170:171], v[116:117]
	v_mov_b32_e32 v170, v118
	v_mov_b32_e32 v171, v112
	v_pk_mov_b32 v[112:113], v[118:119], v[176:177] op_sel:[1,0]
	v_pk_add_f32 v[114:115], v[114:115], v[168:169]
	v_pk_add_f32 v[112:113], v[170:171], v[112:113]
	v_mov_b32_e32 v178, v161
	v_pk_add_f32 v[112:113], v[116:117], v[112:113]
	v_pk_add_f32 v[114:115], v[114:115], v[178:179]
	v_pk_add_f32 v[116:117], v[180:181], v[182:183]
	v_pk_add_f32 v[112:113], v[112:113], v[114:115]
	v_pk_add_f32 v[114:115], v[122:123], v[120:121]
	s_waitcnt lgkmcnt(0)
	v_lshlrev_b32_e32 v204, 16, v202
	v_pk_add_f32 v[114:115], v[114:115], v[116:117]
	v_pk_add_f32 v[116:117], v[184:185], v[186:187]
	v_pk_add_f32 v[112:113], v[112:113], v[114:115]
	v_pk_add_f32 v[114:115], v[126:127], v[124:125]
	v_and_b32_e32 v205, 0xffff0000, v202
	v_lshlrev_b32_e32 v202, 16, v203
	v_and_b32_e32 v203, 0xffff0000, v203
	v_pk_add_f32 v[114:115], v[114:115], v[116:117]
	v_pk_add_f32 v[96:97], v[98:99], v[96:97]
	v_pk_add_f32 v[98:99], v[188:189], v[190:191]
	v_pk_fma_f32 v[108:109], v[204:205], s[34:35], v[108:109] op_sel_hi:[1,0,1]
	v_pk_fma_f32 v[110:111], v[202:203], s[34:35], v[110:111] op_sel_hi:[1,0,1]
	v_pk_add_f32 v[112:113], v[112:113], v[114:115]
	v_pk_add_f32 v[96:97], v[96:97], v[98:99]
	v_pk_add_f32 v[98:99], v[102:103], v[100:101]
	v_pk_add_f32 v[100:101], v[194:195], v[196:197]
	v_cvt_pk_bf16_f32 v108, v108, v109
	v_cvt_pk_bf16_f32 v109, v110, v111
	v_pk_add_f32 v[96:97], v[112:113], v[96:97]
	v_pk_add_f32 v[98:99], v[98:99], v[100:101]
	ds_write_b64 v167, v[108:109] offset:112
	v_lshlrev_b32_e32 v110, 16, v108
	v_and_b32_e32 v108, 0xffff0000, v108
	v_lshlrev_b32_e32 v202, 16, v109
	v_and_b32_e32 v204, 0xffff0000, v109
	v_pk_add_f32 v[96:97], v[96:97], v[98:99]
	v_pk_add_f32 v[98:99], v[106:107], v[104:105]
	v_pk_add_f32 v[100:101], v[198:199], v[200:201]
	v_mul_f32_e32 v111, v110, v110
	v_mul_f32_e32 v109, v108, v108
	v_mul_f32_e32 v203, v202, v202
	v_mul_f32_e32 v205, v204, v204
	v_pk_add_f32 v[98:99], v[98:99], v[100:101]
	v_pk_add_f32 v[100:101], v[202:203], v[204:205]
	v_pk_add_f32 v[96:97], v[96:97], v[98:99]
	v_pk_add_f32 v[98:99], v[110:111], v[108:109]
	s_nop 0
	v_pk_add_f32 v[98:99], v[98:99], v[100:101]
	s_nop 0
	v_pk_add_f32 v[98:99], v[96:97], v[98:99]
	ds_bpermute_b32 v100, v160, v98
	ds_bpermute_b32 v101, v160, v99
	v_lshlrev_b32_e32 v96, 1, v206
	v_ashrrev_i32_e32 v97, 31, v96
	s_and_saveexec_b64 s[40:41], vcc
	s_cbranch_execz .LBB0_411
	v_lshl_add_u64 v[102:103], v[96:97], 2, v[164:165]
	s_waitcnt lgkmcnt(0)
	v_pk_add_f32 v[98:99], v[98:99], v[100:101]
	global_store_dwordx2 v[102:103], v[98:99], off

; DI unsigned pack2(float a, float b) { f32x2_t v = {a, b}; bf16x2_t r = __builtin_convertvector(v, bf16x2_t); return __builtin_bit_cast(unsigned, r); }
; DI float sigmoidf_(float x) { return __builtin_amdgcn_rcpf(1.f + __expf(-x)); }
; template <bool LAST>
; DI void phase_gate(const Params& P, int layer, unsigned char* smem, int L, int G) {
;     ...
;     unsigned gq[4][2][8];
; #pragma unroll
;     for (int i = 0; i < 4; ++i)
; #pragma unroll
;       for (int q4 = 0; q4 < 4; ++q4) {
;         const int fl = wm * 128 + i * 32 + 8 * q4 + 4 * h;
;         const f32x4 c1v = *(const f32x4*)(vecL + fl), c2v = *(const f32x4*)(vecL + 256 + fl);
;         const float c1a[4] = {c1v.x, c1v.y, c1v.z, c1v.w}, c2a[4] = {c2v.x, c2v.y, c2v.z, c2v.w};
; #pragma unroll
;         for (int j = 0; j < 2; ++j) {
;           const int lrow = wn * 64 + j * 32 + r;
;           const float mu = rowA[lrow], rstd = rowB[lrow];
;           float sg4[4];
; #pragma unroll
;           for (int e = 0; e < 4; ++e) sg4[e] = sigmoidf_(rstd * (accu[i][j][4 * q4 + e] - mu * c1a[e]) + c2a[e]);
;           gq[i][j][2 * q4] = pack2(sg4[0], sg4[1]); gq[i][j][2 * q4 + 1] = pack2(sg4[2], sg4[3]);
;         }
;         __builtin_amdgcn_sched_barrier(0);
;       }
.LBB0_479:
	v_lshrrev_b32_e32 v160, 1, v163
	v_lshrrev_b32_e32 v163, 3, v163
	v_and_b32_e32 v163, 4, v163
	v_and_or_b32 v160, v160, s43, v163
	v_lshlrev_b32_e32 v160, 2, v160
	v_add_u32_e32 v163, 0x24800, v160
	v_add_u32_e32 v164, 0x24c00, v160
	v_and_b32_e32 v167, 0x37c, v168
	ds_read_b128 v[170:173], v163
	ds_read_b128 v[174:177], v164
	v_or_b32_e32 v164, 0x24000, v167
	v_or_b32_e32 v166, 0x24080, v167
	v_or_b32_e32 v165, 0x24400, v167
	ds_read_b32 v168, v164
	ds_read_b32 v169, v165
	v_or_b32_e32 v167, 0x24480, v167
	ds_read_b32 v178, v166
	ds_read_b32 v179, v167
	s_waitcnt lgkmcnt(3)
	v_fma_f32 v112, -v170, v168, v112
	v_fma_f32 v113, -v171, v168, v113
	s_waitcnt lgkmcnt(1)
	v_fma_f32 v98, -v172, v178, v98
	v_fma_f32 v114, -v172, v168, v114
	v_fma_f32 v115, -v173, v168, v115
	v_fma_f32 v96, -v170, v178, v96
	v_fma_f32 v97, -v171, v178, v97
	s_waitcnt lgkmcnt(0)
	v_fma_f32 v98, v179, v98, v176
	v_fma_f32 v99, -v173, v178, v99
	v_fma_f32 v112, v169, v112, v174
	v_fma_f32 v113, v169, v113, v175
	v_fma_f32 v114, v169, v114, v176
	v_fma_f32 v115, v169, v115, v177
	v_fma_f32 v96, v179, v96, v174
	v_fma_f32 v97, v179, v97, v175
	v_mul_f32_e32 v98, 0xbfb8aa3b, v98
	v_fmac_f32_e32 v177, v179, v99
	v_mul_f32_e32 v112, 0xbfb8aa3b, v112
	v_mul_f32_e32 v113, 0xbfb8aa3b, v113
	v_mul_f32_e32 v114, 0xbfb8aa3b, v114
	v_mul_f32_e32 v115, 0xbfb8aa3b, v115
	v_mul_f32_e32 v96, 0xbfb8aa3b, v96
	v_mul_f32_e32 v97, 0xbfb8aa3b, v97
	v_exp_f32_e32 v98, v98
	v_mul_f32_e32 v99, 0xbfb8aa3b, v177
	v_exp_f32_e32 v112, v112
	v_exp_f32_e32 v113, v113
	v_exp_f32_e32 v114, v114
	v_exp_f32_e32 v115, v115
	v_exp_f32_e32 v96, v96
	v_exp_f32_e32 v97, v97
	v_exp_f32_e32 v99, v99
	v_add_f32_e32 v98, 1.0, v98
	v_add_f32_e32 v112, 1.0, v112
	v_add_f32_e32 v113, 1.0, v113
	v_add_f32_e32 v114, 1.0, v114
	v_add_f32_e32 v115, 1.0, v115
	v_add_f32_e32 v96, 1.0, v96
	v_add_f32_e32 v97, 1.0, v97
	v_rcp_f32_e32 v168, v98
	v_add_f32_e32 v98, 1.0, v99
	v_rcp_f32_e32 v112, v112
	v_rcp_f32_e32 v113, v113
	v_rcp_f32_e32 v114, v114
	v_rcp_f32_e32 v115, v115
	v_rcp_f32_e32 v96, v96
	v_rcp_f32_e32 v97, v97
	v_rcp_f32_e32 v169, v98
	v_cvt_pk_bf16_f32 v99, v112, v113
	v_cvt_pk_bf16_f32 v98, v114, v115
	v_cvt_pk_bf16_f32 v97, v96, v97
	v_cvt_pk_bf16_f32 v96, v168, v169
	v_add_u32_e32 v112, 0x24820, v160
	v_add_u32_e32 v168, 0x24c20, v160
	ds_read_b128 v[112:115], v112
	ds_read_b128 v[168:171], v168
	ds_read_b32 v172, v164
	ds_read_b32 v173, v165
	ds_read_b32 v174, v166
	ds_read_b32 v175, v167
	s_waitcnt lgkmcnt(3)
	v_fma_f32 v116, -v112, v172, v116
	v_fma_f32 v117, -v113, v172, v117
	s_waitcnt lgkmcnt(1)
	v_fma_f32 v102, -v114, v174, v102
	v_fma_f32 v118, -v114, v172, v118
	v_fma_f32 v119, -v115, v172, v119
	v_fma_f32 v100, -v112, v174, v100
	v_fma_f32 v101, -v113, v174, v101
	s_waitcnt lgkmcnt(0)
	v_fma_f32 v102, v175, v102, v170
	v_fma_f32 v103, -v115, v174, v103
	v_fma_f32 v116, v173, v116, v168
	v_fma_f32 v117, v173, v117, v169
	v_fma_f32 v118, v173, v118, v170
	v_fma_f32 v119, v173, v119, v171
	v_fma_f32 v100, v175, v100, v168
	v_fma_f32 v101, v175, v101, v169
	v_mul_f32_e32 v102, 0xbfb8aa3b, v102
	v_fmac_f32_e32 v171, v175, v103
	v_mul_f32_e32 v116, 0xbfb8aa3b, v116
	v_mul_f32_e32 v117, 0xbfb8aa3b, v117
	v_mul_f32_e32 v118, 0xbfb8aa3b, v118
	v_mul_f32_e32 v119, 0xbfb8aa3b, v119
	v_mul_f32_e32 v100, 0xbfb8aa3b, v100
	v_mul_f32_e32 v101, 0xbfb8aa3b, v101
	v_exp_f32_e32 v102, v102
	v_mul_f32_e32 v103, 0xbfb8aa3b, v171
	v_exp_f32_e32 v116, v116
	v_exp_f32_e32 v117, v117
	v_exp_f32_e32 v118, v118
	v_exp_f32_e32 v119, v119
	v_exp_f32_e32 v100, v100
	v_exp_f32_e32 v101, v101
	v_exp_f32_e32 v103, v103
	v_add_f32_e32 v102, 1.0, v102
	v_add_f32_e32 v116, 1.0, v116
	v_add_f32_e32 v117, 1.0, v117
	v_add_f32_e32 v118, 1.0, v118
	v_add_f32_e32 v119, 1.0, v119
	v_add_f32_e32 v100, 1.0, v100
	v_add_f32_e32 v101, 1.0, v101
	v_rcp_f32_e32 v113, v102
	v_add_f32_e32 v102, 1.0, v103
	v_rcp_f32_e32 v116, v116
	v_rcp_f32_e32 v117, v117
	v_rcp_f32_e32 v118, v118
	v_rcp_f32_e32 v112, v119
	v_rcp_f32_e32 v100, v100
	v_rcp_f32_e32 v101, v101
	v_rcp_f32_e32 v114, v102
	v_cvt_pk_bf16_f32 v103, v116, v117
	v_cvt_pk_bf16_f32 v102, v118, v112
	v_cvt_pk_bf16_f32 v101, v100, v101
	v_cvt_pk_bf16_f32 v100, v113, v114
	v_add_u32_e32 v112, 0x24840, v160
	v_add_u32_e32 v116, 0x24c40, v160
	ds_read_b128 v[112:115], v112
	ds_read_b128 v[116:119], v116
	ds_read_b32 v168, v164
	ds_read_b32 v169, v165
	ds_read_b32 v170, v166
	ds_read_b32 v171, v167
	s_waitcnt lgkmcnt(3)
	v_fma_f32 v120, -v112, v168, v120
	v_fma_f32 v121, -v113, v168, v121
	s_waitcnt lgkmcnt(1)
	v_fma_f32 v106, -v114, v170, v106
	v_fma_f32 v122, -v114, v168, v122
	v_fma_f32 v123, -v115, v168, v123
	v_fma_f32 v104, -v112, v170, v104
	v_fma_f32 v105, -v113, v170, v105
	s_waitcnt lgkmcnt(0)
	v_fma_f32 v106, v171, v106, v118
	v_fma_f32 v107, -v115, v170, v107
	v_fma_f32 v120, v169, v120, v116
	v_fma_f32 v121, v169, v121, v117
	v_fma_f32 v122, v169, v122, v118
	v_fma_f32 v123, v169, v123, v119
	v_fma_f32 v104, v171, v104, v116
	v_fma_f32 v105, v171, v105, v117
	v_mul_f32_e32 v106, 0xbfb8aa3b, v106
	v_fmac_f32_e32 v119, v171, v107
	v_mul_f32_e32 v120, 0xbfb8aa3b, v120
	v_mul_f32_e32 v121, 0xbfb8aa3b, v121
	v_mul_f32_e32 v122, 0xbfb8aa3b, v122
	v_mul_f32_e32 v123, 0xbfb8aa3b, v123
	v_mul_f32_e32 v104, 0xbfb8aa3b, v104
	v_mul_f32_e32 v105, 0xbfb8aa3b, v105
	v_exp_f32_e32 v106, v106
	v_mul_f32_e32 v107, 0xbfb8aa3b, v119
	v_exp_f32_e32 v120, v120
	v_exp_f32_e32 v121, v121
	v_exp_f32_e32 v122, v122
	v_exp_f32_e32 v123, v123
	v_exp_f32_e32 v104, v104
	v_exp_f32_e32 v105, v105
	v_exp_f32_e32 v107, v107
	v_add_f32_e32 v106, 1.0, v106
	v_add_f32_e32 v120, 1.0, v120
	v_add_f32_e32 v121, 1.0, v121
	v_add_f32_e32 v122, 1.0, v122
	v_add_f32_e32 v123, 1.0, v123
	v_add_f32_e32 v104, 1.0, v104
	v_add_f32_e32 v105, 1.0, v105
	v_rcp_f32_e32 v113, v106
	v_add_f32_e32 v106, 1.0, v107
	v_rcp_f32_e32 v120, v120
	v_rcp_f32_e32 v121, v121
	v_rcp_f32_e32 v122, v122
	v_rcp_f32_e32 v112, v123
	v_rcp_f32_e32 v104, v104
	v_rcp_f32_e32 v105, v105
	v_rcp_f32_e32 v114, v106
	v_cvt_pk_bf16_f32 v107, v120, v121
	v_cvt_pk_bf16_f32 v106, v122, v112
	v_cvt_pk_bf16_f32 v105, v104, v105
	v_cvt_pk_bf16_f32 v104, v113, v114
	v_add_u32_e32 v112, 0x24860, v160
	v_add_u32_e32 v116, 0x24c60, v160
	ds_read_b128 v[112:115], v112
	ds_read_b128 v[116:119], v116
	ds_read_b32 v120, v164
	ds_read_b32 v121, v165
	ds_read_b32 v122, v166
	ds_read_b32 v123, v167
	s_waitcnt lgkmcnt(3)
; DI unsigned pack2(float a, float b) { f32x2_t v = {a, b}; bf16x2_t r = __builtin_convertvector(v, bf16x2_t); return __builtin_bit_cast(unsigned, r); }
; DI float sigmoidf_(float x) { return __builtin_amdgcn_rcpf(1.f + __expf(-x)); }
; template <bool LAST>
; DI void phase_gate(const Params& P, int layer, unsigned char* smem, int L, int G) {
;     ...
;     unsigned gq[4][2][8];
; #pragma unroll
;     for (int i = 0; i < 4; ++i)
; #pragma unroll
;       for (int q4 = 0; q4 < 4; ++q4) {
;         const int fl = wm * 128 + i * 32 + 8 * q4 + 4 * h;
;         const f32x4 c1v = *(const f32x4*)(vecL + fl), c2v = *(const f32x4*)(vecL + 256 + fl);
;         const float c1a[4] = {c1v.x, c1v.y, c1v.z, c1v.w}, c2a[4] = {c2v.x, c2v.y, c2v.z, c2v.w};
; #pragma unroll
;         for (int j = 0; j < 2; ++j) {
;           const int lrow = wn * 64 + j * 32 + r;
;           const float mu = rowA[lrow], rstd = rowB[lrow];
;           float sg4[4];
; #pragma unroll
;           for (int e = 0; e < 4; ++e) sg4[e] = sigmoidf_(rstd * (accu[i][j][4 * q4 + e] - mu * c1a[e]) + c2a[e]);
;           gq[i][j][2 * q4] = pack2(sg4[0], sg4[1]); gq[i][j][2 * q4 + 1] = pack2(sg4[2], sg4[3]);
;         }
;         __builtin_amdgcn_sched_barrier(0);
;       }
	v_fma_f32 v125, -v113, v120, v125
	v_fma_f32 v124, -v112, v120, v124
	s_waitcnt lgkmcnt(1)
	v_fma_f32 v110, -v114, v122, v110
	v_fma_f32 v125, v121, v125, v117
	v_fma_f32 v126, -v114, v120, v126
	v_fma_f32 v120, -v115, v120, v127
	v_fma_f32 v108, -v112, v122, v108
	v_fma_f32 v109, -v113, v122, v109
	s_waitcnt lgkmcnt(0)
	v_fma_f32 v110, v123, v110, v118
	v_fma_f32 v111, -v115, v122, v111
	v_fma_f32 v124, v121, v124, v116
	v_mul_f32_e32 v125, 0xbfb8aa3b, v125
	v_fma_f32 v126, v121, v126, v118
	v_fma_f32 v120, v121, v120, v119
	v_fma_f32 v108, v123, v108, v116
	v_fma_f32 v109, v123, v109, v117
	v_mul_f32_e32 v110, 0xbfb8aa3b, v110
	v_fmac_f32_e32 v119, v123, v111
	v_mul_f32_e32 v124, 0xbfb8aa3b, v124
	v_exp_f32_e32 v125, v125
	v_mul_f32_e32 v126, 0xbfb8aa3b, v126
	v_mul_f32_e32 v120, 0xbfb8aa3b, v120
	v_mul_f32_e32 v108, 0xbfb8aa3b, v108
	v_mul_f32_e32 v109, 0xbfb8aa3b, v109
	v_exp_f32_e32 v110, v110
	v_mul_f32_e32 v111, 0xbfb8aa3b, v119
	v_exp_f32_e32 v124, v124
	v_exp_f32_e32 v126, v126
	v_exp_f32_e32 v120, v120
	v_exp_f32_e32 v108, v108
	v_exp_f32_e32 v109, v109
	v_exp_f32_e32 v111, v111
	v_add_f32_e32 v125, 1.0, v125
	v_add_f32_e32 v110, 1.0, v110
	v_add_f32_e32 v124, 1.0, v124
	v_rcp_f32_e32 v121, v125
	v_add_f32_e32 v125, 1.0, v126
	v_add_f32_e32 v120, 1.0, v120
	v_add_f32_e32 v108, 1.0, v108
	v_add_f32_e32 v109, 1.0, v109
	v_rcp_f32_e32 v113, v110
	v_add_f32_e32 v110, 1.0, v111
	v_rcp_f32_e32 v124, v124
	v_rcp_f32_e32 v125, v125
	v_rcp_f32_e32 v112, v120
	v_rcp_f32_e32 v108, v108
	v_rcp_f32_e32 v109, v109
	v_rcp_f32_e32 v114, v110
	v_cvt_pk_bf16_f32 v111, v124, v121
	v_cvt_pk_bf16_f32 v110, v125, v112
	v_cvt_pk_bf16_f32 v109, v108, v109
	v_cvt_pk_bf16_f32 v108, v113, v114
	v_add_u32_e32 v112, 0x24880, v160
	v_add_u32_e32 v116, 0x24c80, v160
	ds_read_b128 v[112:115], v112
	ds_read_b128 v[116:119], v116
	ds_read_b32 v120, v164
	ds_read_b32 v121, v165
	ds_read_b32 v122, v166
	ds_read_b32 v123, v167
	s_waitcnt lgkmcnt(3)
	v_fma_f32 v80, -v112, v120, v80
	v_fma_f32 v81, -v113, v120, v81
	s_waitcnt lgkmcnt(1)
	v_fma_f32 v66, -v114, v122, v66
	v_fma_f32 v82, -v114, v120, v82
	v_fma_f32 v83, -v115, v120, v83
	v_fma_f32 v64, -v112, v122, v64
	v_fma_f32 v65, -v113, v122, v65
	s_waitcnt lgkmcnt(0)
	v_fma_f32 v66, v123, v66, v118
	v_fma_f32 v67, -v115, v122, v67
	v_fma_f32 v80, v121, v80, v116
	v_fma_f32 v81, v121, v81, v117
	v_fma_f32 v82, v121, v82, v118
	v_fma_f32 v83, v121, v83, v119
	v_fma_f32 v64, v123, v64, v116
	v_fma_f32 v65, v123, v65, v117
	v_mul_f32_e32 v66, 0xbfb8aa3b, v66
	v_fmac_f32_e32 v119, v123, v67
	v_mul_f32_e32 v80, 0xbfb8aa3b, v80
	v_mul_f32_e32 v81, 0xbfb8aa3b, v81
	v_mul_f32_e32 v82, 0xbfb8aa3b, v82
	v_mul_f32_e32 v83, 0xbfb8aa3b, v83
	v_mul_f32_e32 v64, 0xbfb8aa3b, v64
	v_mul_f32_e32 v65, 0xbfb8aa3b, v65
	v_exp_f32_e32 v66, v66
	v_mul_f32_e32 v67, 0xbfb8aa3b, v119
	v_exp_f32_e32 v80, v80
	v_exp_f32_e32 v81, v81
	v_exp_f32_e32 v82, v82
	v_exp_f32_e32 v83, v83
	v_exp_f32_e32 v64, v64
	v_exp_f32_e32 v65, v65
	v_exp_f32_e32 v67, v67
	v_add_f32_e32 v66, 1.0, v66
	v_add_f32_e32 v80, 1.0, v80
	v_add_f32_e32 v81, 1.0, v81
	v_add_f32_e32 v82, 1.0, v82
	v_add_f32_e32 v83, 1.0, v83
	v_add_f32_e32 v64, 1.0, v64
	v_add_f32_e32 v65, 1.0, v65
	v_rcp_f32_e32 v112, v66
	v_add_f32_e32 v66, 1.0, v67
	v_rcp_f32_e32 v80, v80
	v_rcp_f32_e32 v81, v81
	v_rcp_f32_e32 v82, v82
	v_rcp_f32_e32 v83, v83
	v_rcp_f32_e32 v64, v64
	v_rcp_f32_e32 v65, v65
	v_rcp_f32_e32 v113, v66
	v_cvt_pk_bf16_f32 v67, v80, v81
	v_cvt_pk_bf16_f32 v66, v82, v83
	v_cvt_pk_bf16_f32 v65, v64, v65
	v_cvt_pk_bf16_f32 v64, v112, v113
	v_add_u32_e32 v80, 0x248a0, v160
	v_add_u32_e32 v112, 0x24ca0, v160
	ds_read_b128 v[80:83], v80
	ds_read_b128 v[112:115], v112
	ds_read_b32 v116, v164
	ds_read_b32 v117, v165
	ds_read_b32 v118, v166
	ds_read_b32 v119, v167
	s_waitcnt lgkmcnt(3)
	v_fma_f32 v84, -v80, v116, v84
	v_fma_f32 v85, -v81, v116, v85
	s_waitcnt lgkmcnt(1)
	v_fma_f32 v70, -v82, v118, v70
	v_fma_f32 v86, -v82, v116, v86
	v_fma_f32 v87, -v83, v116, v87
	v_fma_f32 v68, -v80, v118, v68
	v_fma_f32 v69, -v81, v118, v69
	s_waitcnt lgkmcnt(0)
	v_fma_f32 v70, v119, v70, v114
	v_fma_f32 v71, -v83, v118, v71
	v_fma_f32 v84, v117, v84, v112
	v_fma_f32 v85, v117, v85, v113
	v_fma_f32 v86, v117, v86, v114
	v_fma_f32 v87, v117, v87, v115
	v_fma_f32 v68, v119, v68, v112
	v_fma_f32 v69, v119, v69, v113
	v_mul_f32_e32 v70, 0xbfb8aa3b, v70
	v_fmac_f32_e32 v115, v119, v71
	v_mul_f32_e32 v84, 0xbfb8aa3b, v84
	v_mul_f32_e32 v85, 0xbfb8aa3b, v85
	v_mul_f32_e32 v86, 0xbfb8aa3b, v86
	v_mul_f32_e32 v87, 0xbfb8aa3b, v87
	v_mul_f32_e32 v68, 0xbfb8aa3b, v68
	v_mul_f32_e32 v69, 0xbfb8aa3b, v69
	v_exp_f32_e32 v70, v70
	v_mul_f32_e32 v71, 0xbfb8aa3b, v115
	v_exp_f32_e32 v84, v84
	v_exp_f32_e32 v85, v85
	v_exp_f32_e32 v86, v86
	v_exp_f32_e32 v87, v87
	v_exp_f32_e32 v68, v68
	v_exp_f32_e32 v69, v69
	v_exp_f32_e32 v71, v71
	v_add_f32_e32 v70, 1.0, v70
	v_add_f32_e32 v84, 1.0, v84
	v_add_f32_e32 v85, 1.0, v85
	v_add_f32_e32 v86, 1.0, v86
	v_add_f32_e32 v87, 1.0, v87
	v_add_f32_e32 v68, 1.0, v68
	v_add_f32_e32 v69, 1.0, v69
	v_rcp_f32_e32 v81, v70
	v_add_f32_e32 v70, 1.0, v71
	v_rcp_f32_e32 v84, v84
	v_rcp_f32_e32 v85, v85
	v_rcp_f32_e32 v86, v86
	v_rcp_f32_e32 v80, v87
	v_rcp_f32_e32 v68, v68
	v_rcp_f32_e32 v69, v69
	v_rcp_f32_e32 v82, v70
	v_cvt_pk_bf16_f32 v71, v84, v85
	v_cvt_pk_bf16_f32 v70, v86, v80
	v_cvt_pk_bf16_f32 v69, v68, v69
	v_cvt_pk_bf16_f32 v68, v81, v82
	v_add_u32_e32 v80, 0x248c0, v160
	v_add_u32_e32 v84, 0x24cc0, v160
	ds_read_b128 v[80:83], v80
	ds_read_b128 v[84:87], v84
	ds_read_b32 v112, v164
	ds_read_b32 v113, v165
	ds_read_b32 v114, v166
	ds_read_b32 v115, v167
	s_waitcnt lgkmcnt(3)
; DI unsigned pack2(float a, float b) { f32x2_t v = {a, b}; bf16x2_t r = __builtin_convertvector(v, bf16x2_t); return __builtin_bit_cast(unsigned, r); }
; DI float sigmoidf_(float x) { return __builtin_amdgcn_rcpf(1.f + __expf(-x)); }
; template <bool LAST>
; DI void phase_gate(const Params& P, int layer, unsigned char* smem, int L, int G) {
;     ...
;     unsigned gq[4][2][8];
; #pragma unroll
;     for (int i = 0; i < 4; ++i)
; #pragma unroll
;       for (int q4 = 0; q4 < 4; ++q4) {
;         const int fl = wm * 128 + i * 32 + 8 * q4 + 4 * h;
;         const f32x4 c1v = *(const f32x4*)(vecL + fl), c2v = *(const f32x4*)(vecL + 256 + fl);
;         const float c1a[4] = {c1v.x, c1v.y, c1v.z, c1v.w}, c2a[4] = {c2v.x, c2v.y, c2v.z, c2v.w};
; #pragma unroll
;         for (int j = 0; j < 2; ++j) {
;           const int lrow = wn * 64 + j * 32 + r;
;           const float mu = rowA[lrow], rstd = rowB[lrow];
;           float sg4[4];
; #pragma unroll
;           for (int e = 0; e < 4; ++e) sg4[e] = sigmoidf_(rstd * (accu[i][j][4 * q4 + e] - mu * c1a[e]) + c2a[e]);
;           gq[i][j][2 * q4] = pack2(sg4[0], sg4[1]); gq[i][j][2 * q4 + 1] = pack2(sg4[2], sg4[3]);
;         }
;         __builtin_amdgcn_sched_barrier(0);
;       }
	v_fma_f32 v88, -v80, v112, v88
	v_fma_f32 v89, -v81, v112, v89
	s_waitcnt lgkmcnt(1)
	v_fma_f32 v74, -v82, v114, v74
	v_fma_f32 v90, -v82, v112, v90
	v_fma_f32 v91, -v83, v112, v91
	v_fma_f32 v72, -v80, v114, v72
	v_fma_f32 v73, -v81, v114, v73
	s_waitcnt lgkmcnt(0)
	v_fma_f32 v74, v115, v74, v86
	v_fma_f32 v75, -v83, v114, v75
	v_fma_f32 v88, v113, v88, v84
	v_fma_f32 v89, v113, v89, v85
	v_fma_f32 v90, v113, v90, v86
	v_fma_f32 v91, v113, v91, v87
	v_fma_f32 v72, v115, v72, v84
	v_fma_f32 v73, v115, v73, v85
	v_mul_f32_e32 v74, 0xbfb8aa3b, v74
	v_fmac_f32_e32 v87, v115, v75
	v_mul_f32_e32 v88, 0xbfb8aa3b, v88
	v_mul_f32_e32 v89, 0xbfb8aa3b, v89
	v_mul_f32_e32 v90, 0xbfb8aa3b, v90
	v_mul_f32_e32 v91, 0xbfb8aa3b, v91
	v_mul_f32_e32 v72, 0xbfb8aa3b, v72
	v_mul_f32_e32 v73, 0xbfb8aa3b, v73
	v_exp_f32_e32 v74, v74
	v_mul_f32_e32 v75, 0xbfb8aa3b, v87
	v_exp_f32_e32 v88, v88
	v_exp_f32_e32 v89, v89
	v_exp_f32_e32 v90, v90
	v_exp_f32_e32 v91, v91
	v_exp_f32_e32 v72, v72
	v_exp_f32_e32 v73, v73
	v_exp_f32_e32 v75, v75
	v_add_f32_e32 v74, 1.0, v74
	v_add_f32_e32 v88, 1.0, v88
	v_add_f32_e32 v89, 1.0, v89
	v_add_f32_e32 v90, 1.0, v90
	v_add_f32_e32 v91, 1.0, v91
	v_add_f32_e32 v72, 1.0, v72
	v_add_f32_e32 v73, 1.0, v73
	v_rcp_f32_e32 v81, v74
	v_add_f32_e32 v74, 1.0, v75
	v_rcp_f32_e32 v88, v88
	v_rcp_f32_e32 v89, v89
	v_rcp_f32_e32 v90, v90
	v_rcp_f32_e32 v80, v91
	v_rcp_f32_e32 v72, v72
	v_rcp_f32_e32 v73, v73
	v_rcp_f32_e32 v82, v74
	v_cvt_pk_bf16_f32 v75, v88, v89
	v_cvt_pk_bf16_f32 v74, v90, v80
	v_cvt_pk_bf16_f32 v73, v72, v73
	v_cvt_pk_bf16_f32 v72, v81, v82
	v_add_u32_e32 v80, 0x248e0, v160
	v_add_u32_e32 v84, 0x24ce0, v160
	ds_read_b128 v[80:83], v80
	ds_read_b128 v[84:87], v84
	ds_read_b32 v88, v164
	ds_read_b32 v89, v165
	ds_read_b32 v90, v166
	ds_read_b32 v91, v167
	s_waitcnt lgkmcnt(3)
	v_fma_f32 v93, -v81, v88, v93
	v_fma_f32 v92, -v80, v88, v92
	s_waitcnt lgkmcnt(1)
	v_fma_f32 v78, -v82, v90, v78
	v_fma_f32 v93, v89, v93, v85
	v_fma_f32 v94, -v82, v88, v94
	v_fma_f32 v88, -v83, v88, v95
	v_fma_f32 v76, -v80, v90, v76
	v_fma_f32 v77, -v81, v90, v77
	s_waitcnt lgkmcnt(0)
	v_fma_f32 v78, v91, v78, v86
	v_fma_f32 v79, -v83, v90, v79
	v_fma_f32 v92, v89, v92, v84
	v_mul_f32_e32 v93, 0xbfb8aa3b, v93
	v_fma_f32 v94, v89, v94, v86
	v_fma_f32 v88, v89, v88, v87
	v_fma_f32 v76, v91, v76, v84
	v_fma_f32 v77, v91, v77, v85
	v_mul_f32_e32 v78, 0xbfb8aa3b, v78
	v_fmac_f32_e32 v87, v91, v79
	v_mul_f32_e32 v92, 0xbfb8aa3b, v92
	v_exp_f32_e32 v93, v93
	v_mul_f32_e32 v94, 0xbfb8aa3b, v94
	v_mul_f32_e32 v88, 0xbfb8aa3b, v88
	v_mul_f32_e32 v76, 0xbfb8aa3b, v76
	v_mul_f32_e32 v77, 0xbfb8aa3b, v77
	v_exp_f32_e32 v78, v78
	v_mul_f32_e32 v79, 0xbfb8aa3b, v87
	v_exp_f32_e32 v92, v92
	v_exp_f32_e32 v94, v94
	v_exp_f32_e32 v88, v88
	v_exp_f32_e32 v76, v76
	v_exp_f32_e32 v77, v77
	v_exp_f32_e32 v79, v79
	v_add_f32_e32 v93, 1.0, v93
	v_add_f32_e32 v78, 1.0, v78
	v_add_f32_e32 v92, 1.0, v92
	v_rcp_f32_e32 v89, v93
	v_add_f32_e32 v93, 1.0, v94
	v_add_f32_e32 v88, 1.0, v88
	v_add_f32_e32 v76, 1.0, v76
	v_add_f32_e32 v77, 1.0, v77
	v_rcp_f32_e32 v81, v78
	v_add_f32_e32 v78, 1.0, v79
	v_rcp_f32_e32 v92, v92
	v_rcp_f32_e32 v93, v93
	v_rcp_f32_e32 v80, v88
	v_rcp_f32_e32 v76, v76
	v_rcp_f32_e32 v77, v77
	v_rcp_f32_e32 v82, v78
	v_cvt_pk_bf16_f32 v79, v92, v89
	v_cvt_pk_bf16_f32 v78, v93, v80
	v_cvt_pk_bf16_f32 v77, v76, v77
	v_cvt_pk_bf16_f32 v76, v81, v82
	v_add_u32_e32 v80, 0x24900, v160
	v_add_u32_e32 v84, 0x24d00, v160
	ds_read_b128 v[80:83], v80
	ds_read_b128 v[84:87], v84
	ds_read_b32 v88, v164
	ds_read_b32 v89, v165
	ds_read_b32 v90, v166
	ds_read_b32 v91, v167
	s_waitcnt lgkmcnt(3)
	v_fma_f32 v48, -v80, v88, v48
	v_fma_f32 v49, -v81, v88, v49
	s_waitcnt lgkmcnt(1)
	v_fma_f32 v34, -v82, v90, v34
	v_fma_f32 v50, -v82, v88, v50
	v_fma_f32 v51, -v83, v88, v51
	v_fma_f32 v32, -v80, v90, v32
	v_fma_f32 v33, -v81, v90, v33
	s_waitcnt lgkmcnt(0)
	v_fma_f32 v34, v91, v34, v86
	v_fma_f32 v35, -v83, v90, v35
	v_fma_f32 v48, v89, v48, v84
	v_fma_f32 v49, v89, v49, v85
	v_fma_f32 v50, v89, v50, v86
	v_fma_f32 v51, v89, v51, v87
	v_fma_f32 v32, v91, v32, v84
	v_fma_f32 v33, v91, v33, v85
	v_mul_f32_e32 v34, 0xbfb8aa3b, v34
	v_fmac_f32_e32 v87, v91, v35
	v_mul_f32_e32 v48, 0xbfb8aa3b, v48
	v_mul_f32_e32 v49, 0xbfb8aa3b, v49
	v_mul_f32_e32 v50, 0xbfb8aa3b, v50
	v_mul_f32_e32 v51, 0xbfb8aa3b, v51
	v_mul_f32_e32 v32, 0xbfb8aa3b, v32
	v_mul_f32_e32 v33, 0xbfb8aa3b, v33
	v_exp_f32_e32 v34, v34
	v_mul_f32_e32 v35, 0xbfb8aa3b, v87
	v_exp_f32_e32 v48, v48
	v_exp_f32_e32 v49, v49
	v_exp_f32_e32 v50, v50
	v_exp_f32_e32 v51, v51
	v_exp_f32_e32 v32, v32
	v_exp_f32_e32 v33, v33
	v_exp_f32_e32 v35, v35
	v_add_f32_e32 v34, 1.0, v34
	v_add_f32_e32 v48, 1.0, v48
	v_add_f32_e32 v49, 1.0, v49
	v_add_f32_e32 v50, 1.0, v50
	v_add_f32_e32 v51, 1.0, v51
	v_add_f32_e32 v32, 1.0, v32
	v_add_f32_e32 v33, 1.0, v33
	v_rcp_f32_e32 v80, v34
	v_add_f32_e32 v34, 1.0, v35
	v_rcp_f32_e32 v48, v48
	v_rcp_f32_e32 v49, v49
	v_rcp_f32_e32 v50, v50
	v_rcp_f32_e32 v51, v51
	v_rcp_f32_e32 v32, v32
	v_rcp_f32_e32 v33, v33
	v_rcp_f32_e32 v81, v34
	v_cvt_pk_bf16_f32 v35, v48, v49
	v_cvt_pk_bf16_f32 v34, v50, v51
	v_cvt_pk_bf16_f32 v33, v32, v33
	v_cvt_pk_bf16_f32 v32, v80, v81
	v_add_u32_e32 v48, 0x24920, v160
	v_add_u32_e32 v80, 0x24d20, v160
	ds_read_b128 v[48:51], v48
	ds_read_b128 v[80:83], v80
	ds_read_b32 v84, v164
	ds_read_b32 v85, v165
	ds_read_b32 v86, v166
	ds_read_b32 v87, v167
	s_waitcnt lgkmcnt(3)
	v_fma_f32 v53, -v49, v84, v53
	v_fma_f32 v52, -v48, v84, v52
	s_waitcnt lgkmcnt(1)
	v_fma_f32 v36, -v48, v86, v36
	s_waitcnt lgkmcnt(0)
; DI unsigned pack2(float a, float b) { f32x2_t v = {a, b}; bf16x2_t r = __builtin_convertvector(v, bf16x2_t); return __builtin_bit_cast(unsigned, r); }
; DI float sigmoidf_(float x) { return __builtin_amdgcn_rcpf(1.f + __expf(-x)); }
; template <bool LAST>
; DI void phase_gate(const Params& P, int layer, unsigned char* smem, int L, int G) {
;     ...
;     unsigned gq[4][2][8];
; #pragma unroll
;     for (int i = 0; i < 4; ++i)
; #pragma unroll
;       for (int q4 = 0; q4 < 4; ++q4) {
;         const int fl = wm * 128 + i * 32 + 8 * q4 + 4 * h;
;         const f32x4 c1v = *(const f32x4*)(vecL + fl), c2v = *(const f32x4*)(vecL + 256 + fl);
;         const float c1a[4] = {c1v.x, c1v.y, c1v.z, c1v.w}, c2a[4] = {c2v.x, c2v.y, c2v.z, c2v.w};
; #pragma unroll
;         for (int j = 0; j < 2; ++j) {
;           const int lrow = wn * 64 + j * 32 + r;
;           const float mu = rowA[lrow], rstd = rowB[lrow];
;           float sg4[4];
; #pragma unroll
;           for (int e = 0; e < 4; ++e) sg4[e] = sigmoidf_(rstd * (accu[i][j][4 * q4 + e] - mu * c1a[e]) + c2a[e]);
;           gq[i][j][2 * q4] = pack2(sg4[0], sg4[1]); gq[i][j][2 * q4 + 1] = pack2(sg4[2], sg4[3]);
;         }
;         __builtin_amdgcn_sched_barrier(0);
;       }
	v_fma_f32 v36, v87, v36, v80
	v_fma_f32 v37, -v49, v86, v37
	v_mul_f32_e32 v36, 0xbfb8aa3b, v36
	v_fma_f32 v37, v87, v37, v81
	v_exp_f32_e32 v36, v36
	v_mul_f32_e32 v37, 0xbfb8aa3b, v37
	v_exp_f32_e32 v37, v37
	v_fma_f32 v54, -v50, v84, v54
	v_add_f32_e32 v36, 1.0, v36
	v_rcp_f32_e32 v49, v36
	v_add_f32_e32 v36, 1.0, v37
	v_fma_f32 v37, -v50, v86, v38
	v_fma_f32 v55, -v51, v84, v55
	v_fma_f32 v37, v87, v37, v82
	v_fma_f32 v38, -v51, v86, v39
	v_fma_f32 v52, v85, v52, v80
	v_fma_f32 v53, v85, v53, v81
	v_fma_f32 v54, v85, v54, v82
	v_fma_f32 v55, v85, v55, v83
	v_mul_f32_e32 v37, 0xbfb8aa3b, v37
	v_fmac_f32_e32 v83, v87, v38
	v_mul_f32_e32 v52, 0xbfb8aa3b, v52
	v_mul_f32_e32 v53, 0xbfb8aa3b, v53
	v_mul_f32_e32 v54, 0xbfb8aa3b, v54
	v_mul_f32_e32 v55, 0xbfb8aa3b, v55
	v_exp_f32_e32 v37, v37
	v_mul_f32_e32 v38, 0xbfb8aa3b, v83
	v_exp_f32_e32 v52, v52
	v_exp_f32_e32 v53, v53
	v_exp_f32_e32 v54, v54
	v_exp_f32_e32 v55, v55
	v_exp_f32_e32 v38, v38
	v_rcp_f32_e32 v39, v36
	v_add_f32_e32 v36, 1.0, v37
	v_add_f32_e32 v52, 1.0, v52
	v_add_f32_e32 v53, 1.0, v53
	v_add_f32_e32 v54, 1.0, v54
	v_add_f32_e32 v55, 1.0, v55
	v_rcp_f32_e32 v37, v36
	v_add_f32_e32 v36, 1.0, v38
	v_rcp_f32_e32 v52, v52
	v_rcp_f32_e32 v53, v53
	v_rcp_f32_e32 v54, v54
	v_rcp_f32_e32 v48, v55
	v_rcp_f32_e32 v38, v36
	v_cvt_pk_bf16_f32 v80, v52, v53
	v_cvt_pk_bf16_f32 v55, v49, v39
	v_cvt_pk_bf16_f32 v36, v54, v48
	v_cvt_pk_bf16_f32 v53, v37, v38
	v_add_u32_e32 v37, 0x24940, v160
	v_add_u32_e32 v38, 0x24d40, v160
	ds_read_b128 v[48:51], v37
	ds_read_b128 v[82:85], v38
	ds_read_b32 v37, v164
	ds_read_b32 v38, v165
	ds_read_b32 v39, v166
	ds_read_b32 v52, v167
	s_waitcnt lgkmcnt(3)
	v_fma_f32 v54, -v48, v37, v56
	v_fma_f32 v56, -v49, v37, v57
	s_waitcnt lgkmcnt(2)
	v_fma_f32 v56, v38, v56, v83
	v_fma_f32 v57, -v50, v37, v58
	v_fma_f32 v37, -v51, v37, v59
	s_waitcnt lgkmcnt(1)
	v_fma_f32 v40, -v48, v39, v40
	v_fma_f32 v41, -v49, v39, v41
	v_fma_f32 v42, -v50, v39, v42
	v_fma_f32 v39, -v51, v39, v43
	v_fma_f32 v54, v38, v54, v82
	v_mul_f32_e32 v56, 0xbfb8aa3b, v56
	v_fma_f32 v57, v38, v57, v84
	v_fma_f32 v37, v38, v37, v85
	s_waitcnt lgkmcnt(0)
	v_fma_f32 v40, v52, v40, v82
	v_fma_f32 v41, v52, v41, v83
	v_fma_f32 v42, v52, v42, v84
	v_fmac_f32_e32 v85, v52, v39
	v_mul_f32_e32 v54, 0xbfb8aa3b, v54
	v_exp_f32_e32 v56, v56
	v_mul_f32_e32 v57, 0xbfb8aa3b, v57
	v_mul_f32_e32 v37, 0xbfb8aa3b, v37
	v_mul_f32_e32 v40, 0xbfb8aa3b, v40
	v_mul_f32_e32 v41, 0xbfb8aa3b, v41
	v_mul_f32_e32 v42, 0xbfb8aa3b, v42
	v_mul_f32_e32 v39, 0xbfb8aa3b, v85
	v_exp_f32_e32 v54, v54
	v_exp_f32_e32 v57, v57
	v_exp_f32_e32 v37, v37
	v_exp_f32_e32 v40, v40
	v_exp_f32_e32 v41, v41
	v_exp_f32_e32 v42, v42
	v_exp_f32_e32 v39, v39
	v_add_f32_e32 v56, 1.0, v56
	v_add_f32_e32 v54, 1.0, v54
	v_rcp_f32_e32 v38, v56
	v_add_f32_e32 v56, 1.0, v57
	v_add_f32_e32 v37, 1.0, v37
	v_add_f32_e32 v40, 1.0, v40
	v_add_f32_e32 v41, 1.0, v41
	v_add_f32_e32 v42, 1.0, v42
	v_add_f32_e32 v39, 1.0, v39
	v_rcp_f32_e32 v54, v54
	v_rcp_f32_e32 v56, v56
	v_rcp_f32_e32 v37, v37
	v_rcp_f32_e32 v40, v40
	v_rcp_f32_e32 v41, v41
	v_rcp_f32_e32 v42, v42
	v_rcp_f32_e32 v39, v39
	v_cvt_pk_bf16_f32 v83, v54, v38
	v_cvt_pk_bf16_f32 v82, v56, v37
	v_cvt_pk_bf16_f32 v81, v40, v41
	v_cvt_pk_bf16_f32 v59, v42, v39
	v_add_u32_e32 v37, 0x24960, v160
	v_add_u32_e32 v42, 0x24d60, v160
	ds_read_b128 v[38:41], v37
	ds_read_b128 v[48:51], v42
	ds_read_b32 v37, v164
	ds_read_b32 v42, v165
	ds_read_b32 v43, v166
	ds_read_b32 v52, v167
	s_waitcnt lgkmcnt(3)
	v_fma_f32 v56, -v39, v37, v61
	v_fma_f32 v54, -v38, v37, v60
	s_waitcnt lgkmcnt(2)
	v_fma_f32 v56, v42, v56, v49
	v_fma_f32 v57, -v40, v37, v62
	v_fma_f32 v37, -v41, v37, v63
	s_waitcnt lgkmcnt(1)
	v_fma_f32 v38, -v38, v43, v44
	v_fma_f32 v39, -v39, v43, v45
	v_fma_f32 v40, -v40, v43, v46
	v_fma_f32 v41, -v41, v43, v47
	v_fma_f32 v54, v42, v54, v48
	v_mul_f32_e32 v56, 0xbfb8aa3b, v56
	v_fma_f32 v57, v42, v57, v50
	v_fma_f32 v37, v42, v37, v51
	s_waitcnt lgkmcnt(0)
	v_fma_f32 v38, v52, v38, v48
	v_fma_f32 v39, v52, v39, v49
	v_fma_f32 v40, v52, v40, v50
	v_fmac_f32_e32 v51, v52, v41
	v_mul_f32_e32 v54, 0xbfb8aa3b, v54
	v_exp_f32_e32 v56, v56
	v_mul_f32_e32 v57, 0xbfb8aa3b, v57
	v_mul_f32_e32 v37, 0xbfb8aa3b, v37
	v_mul_f32_e32 v38, 0xbfb8aa3b, v38
	v_mul_f32_e32 v39, 0xbfb8aa3b, v39
	v_mul_f32_e32 v40, 0xbfb8aa3b, v40
	v_mul_f32_e32 v41, 0xbfb8aa3b, v51
	v_exp_f32_e32 v54, v54
	v_exp_f32_e32 v57, v57
	v_exp_f32_e32 v37, v37
	v_exp_f32_e32 v38, v38
	v_exp_f32_e32 v39, v39
	v_exp_f32_e32 v40, v40
	v_exp_f32_e32 v41, v41
	v_add_f32_e32 v56, 1.0, v56
	v_add_f32_e32 v54, 1.0, v54
	v_rcp_f32_e32 v42, v56
	v_add_f32_e32 v56, 1.0, v57
	v_add_f32_e32 v37, 1.0, v37
	v_add_f32_e32 v38, 1.0, v38
	v_add_f32_e32 v39, 1.0, v39
	v_add_f32_e32 v40, 1.0, v40
	v_add_f32_e32 v41, 1.0, v41
	v_rcp_f32_e32 v54, v54
	v_rcp_f32_e32 v56, v56
	v_rcp_f32_e32 v37, v37
	v_rcp_f32_e32 v38, v38
	v_rcp_f32_e32 v39, v39
	v_rcp_f32_e32 v40, v40
	v_rcp_f32_e32 v41, v41
	v_cvt_pk_bf16_f32 v91, v54, v42
	v_cvt_pk_bf16_f32 v86, v56, v37
	v_cvt_pk_bf16_f32 v85, v38, v39
	v_cvt_pk_bf16_f32 v84, v40, v41
	v_add_u32_e32 v37, 0x24980, v160
	v_add_u32_e32 v42, 0x24d80, v160
	ds_read_b128 v[38:41], v37
	ds_read_b128 v[42:45], v42
	ds_read_b32 v37, v164
	ds_read_b32 v46, v165
	ds_read_b32 v47, v166
	ds_read_b32 v48, v167
	s_waitcnt lgkmcnt(3)
	v_fma_f32 v16, -v38, v37, v16
	v_fma_f32 v17, -v39, v37, v17
	v_fma_f32 v18, -v40, v37, v18
	v_fma_f32 v19, -v41, v37, v19
	s_waitcnt lgkmcnt(1)
	v_fma_f32 v0, -v38, v47, v0
	v_fma_f32 v1, -v39, v47, v1
	v_fma_f32 v2, -v40, v47, v2
	v_fma_f32 v3, -v41, v47, v3
	v_fma_f32 v16, v46, v16, v42
	v_fma_f32 v17, v46, v17, v43
	v_fma_f32 v18, v46, v18, v44
	v_fma_f32 v19, v46, v19, v45
	s_waitcnt lgkmcnt(0)
; DI unsigned pack2(float a, float b) { f32x2_t v = {a, b}; bf16x2_t r = __builtin_convertvector(v, bf16x2_t); return __builtin_bit_cast(unsigned, r); }
; DI float sigmoidf_(float x) { return __builtin_amdgcn_rcpf(1.f + __expf(-x)); }
; template <bool LAST>
; DI void phase_gate(const Params& P, int layer, unsigned char* smem, int L, int G) {
;     ...
;     unsigned gq[4][2][8];
; #pragma unroll
;     for (int i = 0; i < 4; ++i)
; #pragma unroll
;       for (int q4 = 0; q4 < 4; ++q4) {
;         const int fl = wm * 128 + i * 32 + 8 * q4 + 4 * h;
;         const f32x4 c1v = *(const f32x4*)(vecL + fl), c2v = *(const f32x4*)(vecL + 256 + fl);
;         const float c1a[4] = {c1v.x, c1v.y, c1v.z, c1v.w}, c2a[4] = {c2v.x, c2v.y, c2v.z, c2v.w};
; #pragma unroll
;         for (int j = 0; j < 2; ++j) {
;           const int lrow = wn * 64 + j * 32 + r;
;           const float mu = rowA[lrow], rstd = rowB[lrow];
;           float sg4[4];
; #pragma unroll
;           for (int e = 0; e < 4; ++e) sg4[e] = sigmoidf_(rstd * (accu[i][j][4 * q4 + e] - mu * c1a[e]) + c2a[e]);
;           gq[i][j][2 * q4] = pack2(sg4[0], sg4[1]); gq[i][j][2 * q4 + 1] = pack2(sg4[2], sg4[3]);
;         }
;         __builtin_amdgcn_sched_barrier(0);
;       }
	v_fma_f32 v0, v48, v0, v42
	v_fma_f32 v1, v48, v1, v43
	v_fma_f32 v2, v48, v2, v44
	v_fmac_f32_e32 v45, v48, v3
	v_mul_f32_e32 v16, 0xbfb8aa3b, v16
	v_mul_f32_e32 v17, 0xbfb8aa3b, v17
	v_mul_f32_e32 v18, 0xbfb8aa3b, v18
	v_mul_f32_e32 v19, 0xbfb8aa3b, v19
	v_mul_f32_e32 v0, 0xbfb8aa3b, v0
	v_mul_f32_e32 v1, 0xbfb8aa3b, v1
	v_mul_f32_e32 v2, 0xbfb8aa3b, v2
	v_mul_f32_e32 v3, 0xbfb8aa3b, v45
	v_exp_f32_e32 v16, v16
	v_exp_f32_e32 v17, v17
	v_exp_f32_e32 v18, v18
	v_exp_f32_e32 v19, v19
	v_exp_f32_e32 v0, v0
	v_exp_f32_e32 v1, v1
	v_exp_f32_e32 v2, v2
	v_exp_f32_e32 v3, v3
	v_add_f32_e32 v16, 1.0, v16
	v_add_f32_e32 v17, 1.0, v17
	v_add_f32_e32 v18, 1.0, v18
	v_add_f32_e32 v19, 1.0, v19
	v_add_f32_e32 v0, 1.0, v0
	v_add_f32_e32 v1, 1.0, v1
	v_add_f32_e32 v2, 1.0, v2
	v_add_f32_e32 v3, 1.0, v3
	v_rcp_f32_e32 v16, v16
	v_rcp_f32_e32 v17, v17
	v_rcp_f32_e32 v18, v18
	v_rcp_f32_e32 v19, v19
	v_rcp_f32_e32 v0, v0
	v_rcp_f32_e32 v1, v1
	v_rcp_f32_e32 v2, v2
	v_rcp_f32_e32 v37, v3
	v_cvt_pk_bf16_f32 v17, v16, v17
	v_cvt_pk_bf16_f32 v16, v18, v19
	v_cvt_pk_bf16_f32 v3, v0, v1
	v_cvt_pk_bf16_f32 v2, v2, v37
	v_add_u32_e32 v0, 0x249a0, v160
	v_add_u32_e32 v1, 0x24da0, v160
	ds_read_b128 v[38:41], v0
	ds_read_b128 v[42:45], v1
	ds_read_b32 v0, v164
	ds_read_b32 v1, v165
	ds_read_b32 v18, v166
	ds_read_b32 v19, v167
	s_waitcnt lgkmcnt(3)
	v_fma_f32 v21, -v39, v0, v21
	v_fma_f32 v20, -v38, v0, v20
	s_waitcnt lgkmcnt(1)
	v_fma_f32 v6, -v40, v18, v6
	v_fma_f32 v21, v1, v21, v43
	v_fma_f32 v22, -v40, v0, v22
	v_fma_f32 v0, -v41, v0, v23
	v_fma_f32 v4, -v38, v18, v4
	v_fma_f32 v5, -v39, v18, v5
	s_waitcnt lgkmcnt(0)
	v_fma_f32 v6, v19, v6, v44
	v_fma_f32 v7, -v41, v18, v7
	v_fma_f32 v20, v1, v20, v42
	v_mul_f32_e32 v21, 0xbfb8aa3b, v21
	v_fma_f32 v22, v1, v22, v44
	v_fma_f32 v0, v1, v0, v45
	v_fma_f32 v4, v19, v4, v42
	v_fma_f32 v5, v19, v5, v43
	v_mul_f32_e32 v6, 0xbfb8aa3b, v6
	v_fmac_f32_e32 v45, v19, v7
	v_mul_f32_e32 v20, 0xbfb8aa3b, v20
	v_exp_f32_e32 v21, v21
	v_mul_f32_e32 v22, 0xbfb8aa3b, v22
	v_mul_f32_e32 v0, 0xbfb8aa3b, v0
	v_mul_f32_e32 v4, 0xbfb8aa3b, v4
	v_mul_f32_e32 v5, 0xbfb8aa3b, v5
	v_exp_f32_e32 v6, v6
	v_mul_f32_e32 v7, 0xbfb8aa3b, v45
	v_exp_f32_e32 v20, v20
	v_exp_f32_e32 v22, v22
	v_exp_f32_e32 v0, v0
	v_exp_f32_e32 v4, v4
	v_exp_f32_e32 v5, v5
	v_exp_f32_e32 v7, v7
	v_add_f32_e32 v21, 1.0, v21
	v_add_f32_e32 v6, 1.0, v6
	v_add_f32_e32 v20, 1.0, v20
	v_rcp_f32_e32 v1, v21
	v_add_f32_e32 v21, 1.0, v22
	v_add_f32_e32 v0, 1.0, v0
	v_add_f32_e32 v4, 1.0, v4
	v_add_f32_e32 v5, 1.0, v5
	v_rcp_f32_e32 v18, v6
	v_add_f32_e32 v6, 1.0, v7
	v_rcp_f32_e32 v20, v20
	v_rcp_f32_e32 v21, v21
	v_rcp_f32_e32 v0, v0
	v_rcp_f32_e32 v4, v4
	v_rcp_f32_e32 v5, v5
	v_rcp_f32_e32 v19, v6
	v_cvt_pk_bf16_f32 v7, v20, v1
	v_cvt_pk_bf16_f32 v6, v21, v0
	v_cvt_pk_bf16_f32 v5, v4, v5
	v_cvt_pk_bf16_f32 v4, v18, v19
	v_add_u32_e32 v0, 0x249c0, v160
	v_add_u32_e32 v1, 0x24dc0, v160
	ds_read_b128 v[18:21], v0
	ds_read_b128 v[38:41], v1
	ds_read_b32 v0, v164
	ds_read_b32 v1, v165
	ds_read_b32 v22, v166
	ds_read_b32 v23, v167
	s_waitcnt lgkmcnt(3)
	v_fma_f32 v25, -v19, v0, v25
	v_fma_f32 v24, -v18, v0, v24
	s_waitcnt lgkmcnt(1)
	v_fma_f32 v9, -v19, v22, v9
	s_waitcnt lgkmcnt(0)
	v_fma_f32 v9, v23, v9, v39
	v_fma_f32 v10, -v20, v22, v10
	v_fma_f32 v25, v1, v25, v39
	v_fma_f32 v26, -v20, v0, v26
	v_fma_f32 v0, -v21, v0, v27
	v_fma_f32 v8, -v18, v22, v8
	v_mul_f32_e32 v9, 0xbfb8aa3b, v9
	v_fma_f32 v10, v23, v10, v40
	v_fma_f32 v11, -v21, v22, v11
	v_fma_f32 v24, v1, v24, v38
	v_mul_f32_e32 v25, 0xbfb8aa3b, v25
	v_fma_f32 v26, v1, v26, v40
	v_fma_f32 v0, v1, v0, v41
	v_fma_f32 v8, v23, v8, v38
	v_exp_f32_e32 v9, v9
	v_mul_f32_e32 v10, 0xbfb8aa3b, v10
	v_fmac_f32_e32 v41, v23, v11
	v_mul_f32_e32 v24, 0xbfb8aa3b, v24
	v_exp_f32_e32 v25, v25
	v_mul_f32_e32 v26, 0xbfb8aa3b, v26
	v_mul_f32_e32 v0, 0xbfb8aa3b, v0
	v_mul_f32_e32 v8, 0xbfb8aa3b, v8
	v_exp_f32_e32 v10, v10
	v_mul_f32_e32 v11, 0xbfb8aa3b, v41
	v_exp_f32_e32 v24, v24
	v_exp_f32_e32 v26, v26
	v_exp_f32_e32 v0, v0
	v_exp_f32_e32 v8, v8
	v_exp_f32_e32 v11, v11
	v_add_f32_e32 v9, 1.0, v9
	v_add_f32_e32 v25, 1.0, v25
	v_rcp_f32_e32 v18, v9
	v_add_f32_e32 v9, 1.0, v10
	v_add_f32_e32 v24, 1.0, v24
	v_rcp_f32_e32 v1, v25
	v_add_f32_e32 v25, 1.0, v26
	v_add_f32_e32 v0, 1.0, v0
	v_add_f32_e32 v8, 1.0, v8
	v_rcp_f32_e32 v10, v9
	v_add_f32_e32 v9, 1.0, v11
	v_rcp_f32_e32 v24, v24
	v_rcp_f32_e32 v25, v25
	v_rcp_f32_e32 v0, v0
	v_rcp_f32_e32 v8, v8
	v_rcp_f32_e32 v11, v9
	v_cvt_pk_bf16_f32 v27, v24, v1
	v_cvt_pk_bf16_f32 v9, v25, v0
	v_cvt_pk_bf16_f32 v19, v8, v18
	v_cvt_pk_bf16_f32 v8, v10, v11
	v_add_u32_e32 v0, 0x24de0, v160
	ds_read_b128 v[20:23], v163 offset:480
	ds_read_b32 v1, v164
	ds_read_b128 v[38:41], v0
	ds_read_b32 v0, v165
	ds_read_b32 v10, v166
	ds_read_b32 v18, v167
	s_waitcnt lgkmcnt(4)
	v_fma_f32 v24, -v21, v1, v29
	v_fma_f32 v11, -v20, v1, v28
	s_waitcnt lgkmcnt(2)
	v_fma_f32 v24, v0, v24, v39
	v_fma_f32 v25, -v22, v1, v30
	v_fma_f32 v1, -v23, v1, v31
	s_waitcnt lgkmcnt(1)
	v_fma_f32 v12, -v20, v10, v12
	v_fma_f32 v13, -v21, v10, v13
	v_fma_f32 v14, -v22, v10, v14
	v_fma_f32 v10, -v23, v10, v15
	v_fma_f32 v11, v0, v11, v38
	v_mul_f32_e32 v24, 0xbfb8aa3b, v24
	v_fma_f32 v25, v0, v25, v40
	v_fma_f32 v0, v0, v1, v41
	s_waitcnt lgkmcnt(0)
; DI unsigned pack2(float a, float b) { f32x2_t v = {a, b}; bf16x2_t r = __builtin_convertvector(v, bf16x2_t); return __builtin_bit_cast(unsigned, r); }
; DI float sigmoidf_(float x) { return __builtin_amdgcn_rcpf(1.f + __expf(-x)); }
; DI int otid() { int t = threadIdx.x; asm volatile("" : "+v"(t)); return t; }
; template <bool NT>
; DI void stage_load_tile(bf16_t* stg, const bf16_t* tilebase) {
;   const int tid = otid();
;   const int r0 = tid >> 5, c = tid & 31;
;   const unsigned o0 = (unsigned)(r0 * 1024 + c * 8);
;   __builtin_amdgcn_sched_barrier(0);
; #pragma unroll
;   for (int hf = 0; hf < 2; ++hf) {
; #pragma unroll
;     for (int it = 8 * hf; it < 8 * hf + 8; ++it) {
;       const u32x4* gp = (const u32x4*)(tilebase + (o0 + (unsigned)(it * 16 * 1024)));
;       stage_write16(stg, r0 + 16 * it, c, NT ? __builtin_nontemporal_load(gp) : *gp);
;     }
;     __builtin_amdgcn_sched_barrier(0);
;   }
; }
; template <bool LAST>
; DI void phase_gate(const Params& P, int layer, unsigned char* smem, int L, int G) {
;     ...
;           for (int e = 0; e < 4; ++e) sg4[e] = sigmoidf_(rstd * (accu[i][j][4 * q4 + e] - mu * c1a[e]) + c2a[e]);
;           gq[i][j][2 * q4] = pack2(sg4[0], sg4[1]); gq[i][j][2 * q4 + 1] = pack2(sg4[2], sg4[3]);
;         }
;         __builtin_amdgcn_sched_barrier(0);
;       }
;     stage_load_tile<true>(stg, PPb + (size_t)mt * 256 * 1024 + nt * 256);
	v_fma_f32 v12, v18, v12, v38
	v_fma_f32 v13, v18, v13, v39
	v_fma_f32 v14, v18, v14, v40
	v_fmac_f32_e32 v41, v18, v10
	v_mul_f32_e32 v11, 0xbfb8aa3b, v11
	v_exp_f32_e32 v24, v24
	v_mul_f32_e32 v25, 0xbfb8aa3b, v25
	v_mul_f32_e32 v0, 0xbfb8aa3b, v0
	v_mul_f32_e32 v12, 0xbfb8aa3b, v12
	v_mul_f32_e32 v13, 0xbfb8aa3b, v13
	v_mul_f32_e32 v14, 0xbfb8aa3b, v14
	v_mul_f32_e32 v10, 0xbfb8aa3b, v41
	v_exp_f32_e32 v11, v11
	v_exp_f32_e32 v25, v25
	v_exp_f32_e32 v0, v0
	v_exp_f32_e32 v12, v12
	v_exp_f32_e32 v13, v13
	v_exp_f32_e32 v14, v14
	v_exp_f32_e32 v10, v10
	v_add_f32_e32 v24, 1.0, v24
	v_add_f32_e32 v11, 1.0, v11
	v_rcp_f32_e32 v1, v24
	v_add_f32_e32 v24, 1.0, v25
	v_add_f32_e32 v0, 1.0, v0
	v_add_f32_e32 v12, 1.0, v12
	v_add_f32_e32 v13, 1.0, v13
	v_add_f32_e32 v14, 1.0, v14
	v_add_f32_e32 v10, 1.0, v10
	v_rcp_f32_e32 v11, v11
	v_rcp_f32_e32 v24, v24
	v_rcp_f32_e32 v0, v0
	v_rcp_f32_e32 v12, v12
	v_rcp_f32_e32 v13, v13
	v_rcp_f32_e32 v14, v14
	v_rcp_f32_e32 v10, v10
	v_cvt_pk_bf16_f32 v112, v11, v1
	v_cvt_pk_bf16_f32 v30, v24, v0
	v_cvt_pk_bf16_f32 v29, v12, v13
	v_cvt_pk_bf16_f32 v28, v14, v10
	s_ashr_i32 s25, s24, 31
	s_lshl_b64 s[24:25], s[24:25], 19
	v_mov_b32_e32 v10, v192
	s_add_u32 s30, s66, s24
	v_mov_b32_e32 v163, v161
	s_addc_u32 s31, s67, s25
	v_and_b32_e32 v26, 31, v10
	v_lshlrev_b64 v[0:1], 1, v[162:163]
	v_ashrrev_i32_e32 v18, 5, v10
	v_lshlrev_b32_e32 v10, 3, v26
	v_lshl_add_u64 v[14:15], s[30:31], 0, v[0:1]
	v_lshl_or_b32 v160, v18, 10, v10
	v_add_u32_e32 v12, 0x4000, v160
	v_mov_b32_e32 v13, v161
	v_add_u32_e32 v24, 0x8000, v160
	v_mov_b32_e32 v25, v161
	v_add_u32_e32 v38, 0xc000, v160
	v_mov_b32_e32 v39, v161
	v_lshl_add_u64 v[10:11], v[160:161], 1, v[14:15]
	v_lshl_add_u64 v[20:21], v[12:13], 1, v[14:15]
	v_lshl_add_u64 v[24:25], v[24:25], 1, v[14:15]
	v_lshl_add_u64 v[42:43], v[38:39], 1, v[14:15]
	global_load_dwordx4 v[10:13], v[10:11], off nt
	s_nop 0
	global_load_dwordx4 v[20:23], v[20:21], off nt
	s_nop 0
	global_load_dwordx4 v[38:41], v[24:25], off nt
	s_nop 0
	global_load_dwordx4 v[42:45], v[42:43], off nt
	v_add_u32_e32 v24, 0x10000, v160
	v_mov_b32_e32 v25, v161
	v_lshl_add_u64 v[24:25], v[24:25], 1, v[14:15]
	v_add_u32_e32 v46, 0x14000, v160
	v_mov_b32_e32 v47, v161
	v_lshl_add_u64 v[50:51], v[46:47], 1, v[14:15]
	global_load_dwordx4 v[46:49], v[24:25], off nt
	global_load_dwordx4 v[60:63], v[50:51], off nt
	v_add_u32_e32 v24, 0x18000, v160
	v_mov_b32_e32 v25, v161
	v_lshl_add_u64 v[24:25], v[24:25], 1, v[14:15]
	v_add_u32_e32 v50, 0x1c000, v160
	v_mov_b32_e32 v51, v161
	v_lshl_add_u64 v[50:51], v[50:51], 1, v[14:15]
	global_load_dwordx4 v[92:95], v[24:25], off nt
	global_load_dwordx4 v[114:117], v[50:51], off nt
	v_add_u32_e32 v218, 0x20000, v160
	v_mov_b32_e32 v219, v161
	v_add_u32_e32 v220, 0x24000, v160
	v_mov_b32_e32 v221, v161
	v_add_u32_e32 v252, 0x28000, v160
	v_mov_b32_e32 v253, v161
	v_add_u32_e32 v226, 0x2c000, v160
	v_mov_b32_e32 v227, v161
	v_lshl_add_u64 v[218:219], v[218:219], 1, v[14:15]
	v_lshl_add_u64 v[222:223], v[220:221], 1, v[14:15]
	v_lshl_add_u64 v[252:253], v[252:253], 1, v[14:15]
	v_lshl_add_u64 v[230:231], v[226:227], 1, v[14:15]
	global_load_dwordx4 v[218:221], v[218:219], off nt
	s_nop 0
	global_load_dwordx4 v[222:225], v[222:223], off nt
	s_nop 0
	global_load_dwordx4 v[226:229], v[252:253], off nt
	s_nop 0
	global_load_dwordx4 v[230:233], v[230:231], off nt
	v_add_u32_e32 v252, 0x30000, v160
	v_mov_b32_e32 v253, v161
	v_lshl_add_u64 v[252:253], v[252:253], 1, v[14:15]
	v_add_u32_e32 v234, 0x34000, v160
	v_mov_b32_e32 v235, v161
	v_lshl_add_u64 v[254:255], v[234:235], 1, v[14:15]
	global_load_dwordx4 v[234:237], v[252:253], off nt
	global_load_dwordx4 v[238:241], v[254:255], off nt
	v_add_u32_e32 v252, 0x38000, v160
	v_mov_b32_e32 v253, v161
	v_lshl_add_u64 v[252:253], v[252:253], 1, v[14:15]
	v_add_u32_e32 v160, 0x3c000, v160
	v_lshl_add_u64 v[190:191], v[160:161], 1, v[14:15]
	global_load_dwordx4 v[242:245], v[252:253], off nt
	global_load_dwordx4 v[248:251], v[190:191], off nt
	v_mul_lo_u32 v18, v18, s44
	v_lshl_add_u32 v18, v26, 4, v18
	v_add_u32_e32 v24, 0x2080, v18
	v_add_u32_e32 v25, 0x4100, v18
	v_add_u32_e32 v26, 0x6180, v18
	v_add_u32_e32 v31, 0x8200, v18
	v_add_u32_e32 v37, 0xa280, v18
	v_add_u32_e32 v50, 0xc300, v18
	v_add_u32_e32 v51, 0xe380, v18
	s_waitcnt vmcnt(15)
	ds_write2_b64 v18, v[10:11], v[12:13] offset1:1
	s_waitcnt vmcnt(14)
	ds_write2_b64 v24, v[20:21], v[22:23] offset1:1
	s_waitcnt vmcnt(13)
	ds_write2_b64 v25, v[38:39], v[40:41] offset1:1
	s_waitcnt vmcnt(12)
	ds_write2_b64 v26, v[42:43], v[44:45] offset1:1
	s_waitcnt vmcnt(11)
	ds_write2_b64 v31, v[46:47], v[48:49] offset1:1
	s_waitcnt vmcnt(10)
	ds_write2_b64 v37, v[60:61], v[62:63] offset1:1
	s_waitcnt vmcnt(9)
	ds_write2_b64 v50, v[92:93], v[94:95] offset1:1
	s_waitcnt vmcnt(8)
	ds_write2_b64 v51, v[114:115], v[116:117] offset1:1
	v_add_u32_e32 v14, 0x10400, v18
	v_add_u32_e32 v15, 0x12480, v18
	v_add_u32_e32 v24, 0x14500, v18
	v_add_u32_e32 v25, 0x16580, v18
	v_add_u32_e32 v26, 0x18600, v18
	v_add_u32_e32 v31, 0x1a680, v18
	v_add_u32_e32 v37, 0x1c700, v18
	v_add_u32_e32 v18, 0x1e780, v18
	s_waitcnt vmcnt(7)
	ds_write2_b64 v14, v[218:219], v[220:221] offset1:1
	s_waitcnt vmcnt(6)
	ds_write2_b64 v15, v[222:223], v[224:225] offset1:1
	s_waitcnt vmcnt(5)
	ds_write2_b64 v24, v[226:227], v[228:229] offset1:1
	s_waitcnt vmcnt(4)
	ds_write2_b64 v25, v[230:231], v[232:233] offset1:1
	s_waitcnt vmcnt(3)
	ds_write2_b64 v26, v[234:235], v[236:237] offset1:1
	s_waitcnt vmcnt(2)
	ds_write2_b64 v31, v[238:239], v[240:241] offset1:1
	s_waitcnt vmcnt(1)
	ds_write2_b64 v37, v[242:243], v[244:245] offset1:1
	s_waitcnt vmcnt(0)
	ds_write2_b64 v18, v[248:249], v[250:251] offset1:1
	v_mov_b32_e32 v10, v192
	s_waitcnt lgkmcnt(0)
	s_barrier
; DI unsigned pack2(float a, float b) { f32x2_t v = {a, b}; bf16x2_t r = __builtin_convertvector(v, bf16x2_t); return __builtin_bit_cast(unsigned, r); }
; DI float bflo(unsigned u) { return __uint_as_float(u << 16); }
; DI float bfhi(unsigned u) { return __uint_as_float(u & 0xffff0000u); }
; DI int otid() { int t = threadIdx.x; asm volatile("" : "+v"(t)); return t; }
; template <bool LAST>
; DI void phase_gate(const Params& P, int layer, unsigned char* smem, int L, int G) {
;     ...
;     {
;       const int tid1 = otid();
;       const int lane1 = tid1 & 63, w1 = tid1 >> 6, r1 = lane1 & 31, h1 = lane1 >> 5, wm1 = w1 >> 2, wn1 = w1 & 3;
; #pragma unroll
;       for (int i = 0; i < 4; ++i)
; #pragma unroll
;         for (int q4 = 0; q4 < 4; ++q4) {
; #pragma unroll
;           for (int j = 0; j < 2; ++j) {
;             const uint2 pv = *(const uint2*)(stg + (wn1 * 64 + j * 32 + r1) * STG + wm1 * 128 + i * 32 + 8 * q4 + 4 * h1);
;             const unsigned g0 = gq[i][j][2 * q4], g1 = gq[i][j][2 * q4 + 1];
;             gq[i][j][2 * q4] = pack2(bflo(g0) * bflo(pv.x), bfhi(g0) * bfhi(pv.x));
;             gq[i][j][2 * q4 + 1] = pack2(bflo(g1) * bflo(pv.y), bfhi(g1) * bfhi(pv.y));
;           }
;           __builtin_amdgcn_sched_barrier(0);
;         }
;     }
	v_and_b32_e32 v13, 0xffff0000, v99
	v_lshrrev_b32_e32 v12, 2, v10
	v_and_b32_e32 v12, 8, v12
	v_and_b32_e32 v11, 0xdf, v10
	v_and_or_b32 v10, v10, s42, v12
	v_mad_u32_u24 v113, v11, s44, v10
	ds_read_b64 v[10:11], v113
	ds_read_b64 v[14:15], v113 offset:16640
	v_lshlrev_b32_e32 v12, 16, v99
	s_waitcnt lgkmcnt(1)
	v_lshlrev_b32_e32 v20, 16, v10
	v_and_b32_e32 v21, 0xffff0000, v10
	v_pk_mul_f32 v[12:13], v[12:13], v[20:21]
	v_lshlrev_b32_e32 v10, 16, v11
	v_cvt_pk_bf16_f32 v31, v12, v13
	v_lshlrev_b32_e32 v12, 16, v98
	v_and_b32_e32 v13, 0xffff0000, v98
	v_and_b32_e32 v11, 0xffff0000, v11
	v_pk_mul_f32 v[10:11], v[12:13], v[10:11]
	s_waitcnt lgkmcnt(0)
	v_lshlrev_b32_e32 v12, 16, v14
	v_cvt_pk_bf16_f32 v98, v10, v11
	v_lshlrev_b32_e32 v10, 16, v97
	v_and_b32_e32 v11, 0xffff0000, v97
	v_and_b32_e32 v13, 0xffff0000, v14
	v_pk_mul_f32 v[10:11], v[10:11], v[12:13]
	v_lshlrev_b32_e32 v12, 16, v15
	v_cvt_pk_bf16_f32 v97, v10, v11
	v_lshlrev_b32_e32 v10, 16, v96
	v_and_b32_e32 v11, 0xffff0000, v96
	v_and_b32_e32 v13, 0xffff0000, v15
	v_pk_mul_f32 v[10:11], v[10:11], v[12:13]
	s_nop 0
	v_cvt_pk_bf16_f32 v96, v10, v11
	ds_read_b64 v[10:11], v113 offset:16
	ds_read_b64 v[14:15], v113 offset:16656
	v_lshlrev_b32_e32 v12, 16, v103
	v_and_b32_e32 v13, 0xffff0000, v103
	s_waitcnt lgkmcnt(1)
	v_lshlrev_b32_e32 v20, 16, v10
	v_and_b32_e32 v21, 0xffff0000, v10
	v_pk_mul_f32 v[12:13], v[12:13], v[20:21]
	v_lshlrev_b32_e32 v10, 16, v11
	v_cvt_pk_bf16_f32 v93, v12, v13
	v_lshlrev_b32_e32 v12, 16, v102
	v_and_b32_e32 v13, 0xffff0000, v102
	v_and_b32_e32 v11, 0xffff0000, v11
	v_pk_mul_f32 v[10:11], v[12:13], v[10:11]
	s_waitcnt lgkmcnt(0)
	v_lshlrev_b32_e32 v12, 16, v14
	v_cvt_pk_bf16_f32 v95, v10, v11
	v_lshlrev_b32_e32 v10, 16, v101
	v_and_b32_e32 v11, 0xffff0000, v101
	v_and_b32_e32 v13, 0xffff0000, v14
	v_pk_mul_f32 v[10:11], v[10:11], v[12:13]
	v_lshlrev_b32_e32 v12, 16, v15
	v_cvt_pk_bf16_f32 v92, v10, v11
	v_lshlrev_b32_e32 v10, 16, v100
	v_and_b32_e32 v11, 0xffff0000, v100
	v_and_b32_e32 v13, 0xffff0000, v15
	v_pk_mul_f32 v[10:11], v[10:11], v[12:13]
	s_nop 0
	v_cvt_pk_bf16_f32 v94, v10, v11
	ds_read_b64 v[10:11], v113 offset:32
	ds_read_b64 v[14:15], v113 offset:16672
	v_lshlrev_b32_e32 v12, 16, v107
	v_and_b32_e32 v13, 0xffff0000, v107
	s_waitcnt lgkmcnt(1)
	v_lshlrev_b32_e32 v20, 16, v10
	v_and_b32_e32 v21, 0xffff0000, v10
	v_pk_mul_f32 v[12:13], v[12:13], v[20:21]
	v_lshlrev_b32_e32 v10, 16, v11
	v_cvt_pk_bf16_f32 v88, v12, v13
	v_lshlrev_b32_e32 v12, 16, v106
	v_and_b32_e32 v13, 0xffff0000, v106
	v_and_b32_e32 v11, 0xffff0000, v11
	v_pk_mul_f32 v[10:11], v[12:13], v[10:11]
	s_waitcnt lgkmcnt(0)
	v_lshlrev_b32_e32 v12, 16, v14
	v_cvt_pk_bf16_f32 v90, v10, v11
	v_lshlrev_b32_e32 v10, 16, v105
	v_and_b32_e32 v11, 0xffff0000, v105
	v_and_b32_e32 v13, 0xffff0000, v14
	v_pk_mul_f32 v[10:11], v[10:11], v[12:13]
	v_lshlrev_b32_e32 v12, 16, v15
	v_cvt_pk_bf16_f32 v87, v10, v11
	v_lshlrev_b32_e32 v10, 16, v104
	v_and_b32_e32 v11, 0xffff0000, v104
	v_and_b32_e32 v13, 0xffff0000, v15
	v_pk_mul_f32 v[10:11], v[10:11], v[12:13]
	s_nop 0
	v_cvt_pk_bf16_f32 v89, v10, v11
	ds_read_b64 v[10:11], v113 offset:48
	ds_read_b64 v[14:15], v113 offset:16688
	v_lshlrev_b32_e32 v12, 16, v111
	v_and_b32_e32 v13, 0xffff0000, v111
	s_waitcnt lgkmcnt(1)
	v_lshlrev_b32_e32 v20, 16, v10
	v_and_b32_e32 v21, 0xffff0000, v10
	v_pk_mul_f32 v[12:13], v[12:13], v[20:21]
	v_lshlrev_b32_e32 v10, 16, v11
	v_cvt_pk_bf16_f32 v61, v12, v13
	v_lshlrev_b32_e32 v12, 16, v110
	v_and_b32_e32 v13, 0xffff0000, v110
	v_and_b32_e32 v11, 0xffff0000, v11
	v_pk_mul_f32 v[10:11], v[12:13], v[10:11]
	s_waitcnt lgkmcnt(0)
	v_lshlrev_b32_e32 v12, 16, v14
	v_cvt_pk_bf16_f32 v63, v10, v11
	v_lshlrev_b32_e32 v10, 16, v109
	v_and_b32_e32 v11, 0xffff0000, v109
	v_and_b32_e32 v13, 0xffff0000, v14
	v_pk_mul_f32 v[10:11], v[10:11], v[12:13]
	v_lshlrev_b32_e32 v12, 16, v15
	v_cvt_pk_bf16_f32 v60, v10, v11
	v_lshlrev_b32_e32 v10, 16, v108
	v_and_b32_e32 v11, 0xffff0000, v108
	v_and_b32_e32 v13, 0xffff0000, v15
	v_pk_mul_f32 v[10:11], v[10:11], v[12:13]
	s_nop 0
	v_cvt_pk_bf16_f32 v62, v10, v11
	ds_read_b64 v[10:11], v113 offset:64
	ds_read_b64 v[14:15], v113 offset:16704
	v_lshlrev_b32_e32 v12, 16, v67
	v_and_b32_e32 v13, 0xffff0000, v67
	s_waitcnt lgkmcnt(1)
	v_lshlrev_b32_e32 v20, 16, v10
	v_and_b32_e32 v21, 0xffff0000, v10
	v_pk_mul_f32 v[12:13], v[12:13], v[20:21]
	v_lshlrev_b32_e32 v10, 16, v11
	v_cvt_pk_bf16_f32 v56, v12, v13
	v_lshlrev_b32_e32 v12, 16, v66
	v_and_b32_e32 v13, 0xffff0000, v66
	v_and_b32_e32 v11, 0xffff0000, v11
	v_pk_mul_f32 v[10:11], v[12:13], v[10:11]
	s_waitcnt lgkmcnt(0)
	v_lshlrev_b32_e32 v12, 16, v14
	v_cvt_pk_bf16_f32 v58, v10, v11
	v_lshlrev_b32_e32 v10, 16, v65
	v_and_b32_e32 v11, 0xffff0000, v65
	v_and_b32_e32 v13, 0xffff0000, v14
	v_pk_mul_f32 v[10:11], v[10:11], v[12:13]
	v_lshlrev_b32_e32 v12, 16, v15
	v_cvt_pk_bf16_f32 v54, v10, v11
	v_lshlrev_b32_e32 v10, 16, v64
	v_and_b32_e32 v11, 0xffff0000, v64
	v_and_b32_e32 v13, 0xffff0000, v15
	v_pk_mul_f32 v[10:11], v[10:11], v[12:13]
	s_nop 0
	v_cvt_pk_bf16_f32 v57, v10, v11
	ds_read_b64 v[10:11], v113 offset:80
	ds_read_b64 v[14:15], v113 offset:16720
	v_lshlrev_b32_e32 v12, 16, v71
	v_and_b32_e32 v13, 0xffff0000, v71
	s_waitcnt lgkmcnt(1)
	v_lshlrev_b32_e32 v20, 16, v10
	v_and_b32_e32 v21, 0xffff0000, v10
	v_pk_mul_f32 v[12:13], v[12:13], v[20:21]
	v_lshlrev_b32_e32 v10, 16, v11
	v_cvt_pk_bf16_f32 v50, v12, v13
	v_lshlrev_b32_e32 v12, 16, v70
	v_and_b32_e32 v13, 0xffff0000, v70
	v_and_b32_e32 v11, 0xffff0000, v11
	v_pk_mul_f32 v[10:11], v[12:13], v[10:11]
	s_waitcnt lgkmcnt(0)
; DI unsigned pack2(float a, float b) { f32x2_t v = {a, b}; bf16x2_t r = __builtin_convertvector(v, bf16x2_t); return __builtin_bit_cast(unsigned, r); }
; DI float bflo(unsigned u) { return __uint_as_float(u << 16); }
; DI float bfhi(unsigned u) { return __uint_as_float(u & 0xffff0000u); }
; DI int otid() { int t = threadIdx.x; asm volatile("" : "+v"(t)); return t; }
; template <bool LAST>
; DI void phase_gate(const Params& P, int layer, unsigned char* smem, int L, int G) {
;     ...
;     {
;       const int tid1 = otid();
;       const int lane1 = tid1 & 63, w1 = tid1 >> 6, r1 = lane1 & 31, h1 = lane1 >> 5, wm1 = w1 >> 2, wn1 = w1 & 3;
; #pragma unroll
;       for (int i = 0; i < 4; ++i)
; #pragma unroll
;         for (int q4 = 0; q4 < 4; ++q4) {
; #pragma unroll
;           for (int j = 0; j < 2; ++j) {
;             const uint2 pv = *(const uint2*)(stg + (wn1 * 64 + j * 32 + r1) * STG + wm1 * 128 + i * 32 + 8 * q4 + 4 * h1);
;             const unsigned g0 = gq[i][j][2 * q4], g1 = gq[i][j][2 * q4 + 1];
;             gq[i][j][2 * q4] = pack2(bflo(g0) * bflo(pv.x), bfhi(g0) * bfhi(pv.x));
;             gq[i][j][2 * q4 + 1] = pack2(bflo(g1) * bflo(pv.y), bfhi(g1) * bfhi(pv.y));
;           }
;           __builtin_amdgcn_sched_barrier(0);
;         }
;     }
	v_lshlrev_b32_e32 v12, 16, v14
	v_cvt_pk_bf16_f32 v52, v10, v11
	v_lshlrev_b32_e32 v10, 16, v69
	v_and_b32_e32 v11, 0xffff0000, v69
	v_and_b32_e32 v13, 0xffff0000, v14
	v_pk_mul_f32 v[10:11], v[10:11], v[12:13]
	v_lshlrev_b32_e32 v12, 16, v15
	v_cvt_pk_bf16_f32 v49, v10, v11
	v_lshlrev_b32_e32 v10, 16, v68
	v_and_b32_e32 v11, 0xffff0000, v68
	v_and_b32_e32 v13, 0xffff0000, v15
	v_pk_mul_f32 v[10:11], v[10:11], v[12:13]
	s_nop 0
	v_cvt_pk_bf16_f32 v51, v10, v11
	ds_read_b64 v[10:11], v113 offset:96
	ds_read_b64 v[14:15], v113 offset:16736
	v_lshlrev_b32_e32 v12, 16, v75
	v_and_b32_e32 v13, 0xffff0000, v75
	s_waitcnt lgkmcnt(1)
	v_lshlrev_b32_e32 v20, 16, v10
	v_and_b32_e32 v21, 0xffff0000, v10
	v_pk_mul_f32 v[12:13], v[12:13], v[20:21]
	v_lshlrev_b32_e32 v10, 16, v11
	v_cvt_pk_bf16_f32 v46, v12, v13
	v_lshlrev_b32_e32 v12, 16, v74
	v_and_b32_e32 v13, 0xffff0000, v74
	v_and_b32_e32 v11, 0xffff0000, v11
	v_pk_mul_f32 v[10:11], v[12:13], v[10:11]
	s_waitcnt lgkmcnt(0)
	v_lshlrev_b32_e32 v12, 16, v14
	v_cvt_pk_bf16_f32 v48, v10, v11
	v_lshlrev_b32_e32 v10, 16, v73
	v_and_b32_e32 v11, 0xffff0000, v73
	v_and_b32_e32 v13, 0xffff0000, v14
	v_pk_mul_f32 v[10:11], v[10:11], v[12:13]
	v_lshlrev_b32_e32 v12, 16, v15
	v_cvt_pk_bf16_f32 v45, v10, v11
	v_lshlrev_b32_e32 v10, 16, v72
	v_and_b32_e32 v11, 0xffff0000, v72
	v_and_b32_e32 v13, 0xffff0000, v15
	v_pk_mul_f32 v[10:11], v[10:11], v[12:13]
	s_nop 0
	v_cvt_pk_bf16_f32 v47, v10, v11
	ds_read_b64 v[10:11], v113 offset:112
	ds_read_b64 v[14:15], v113 offset:16752
	v_lshlrev_b32_e32 v12, 16, v79
	v_and_b32_e32 v13, 0xffff0000, v79
	s_waitcnt lgkmcnt(1)
	v_lshlrev_b32_e32 v20, 16, v10
	v_and_b32_e32 v21, 0xffff0000, v10
	v_pk_mul_f32 v[12:13], v[12:13], v[20:21]
	v_lshlrev_b32_e32 v10, 16, v11
	v_cvt_pk_bf16_f32 v42, v12, v13
	v_lshlrev_b32_e32 v12, 16, v78
	v_and_b32_e32 v13, 0xffff0000, v78
	v_and_b32_e32 v11, 0xffff0000, v11
	v_pk_mul_f32 v[10:11], v[12:13], v[10:11]
	s_waitcnt lgkmcnt(0)
	v_lshlrev_b32_e32 v12, 16, v14
	v_cvt_pk_bf16_f32 v44, v10, v11
	v_lshlrev_b32_e32 v10, 16, v77
	v_and_b32_e32 v11, 0xffff0000, v77
	v_and_b32_e32 v13, 0xffff0000, v14
	v_pk_mul_f32 v[10:11], v[10:11], v[12:13]
	v_lshlrev_b32_e32 v12, 16, v15
	v_cvt_pk_bf16_f32 v41, v10, v11
	v_lshlrev_b32_e32 v10, 16, v76
	v_and_b32_e32 v11, 0xffff0000, v76
	v_and_b32_e32 v13, 0xffff0000, v15
	v_pk_mul_f32 v[10:11], v[10:11], v[12:13]
	s_nop 0
	v_cvt_pk_bf16_f32 v43, v10, v11
	ds_read_b64 v[10:11], v113 offset:128
	ds_read_b64 v[14:15], v113 offset:16768
	v_lshlrev_b32_e32 v12, 16, v35
	v_and_b32_e32 v13, 0xffff0000, v35
	s_waitcnt lgkmcnt(1)
	v_lshlrev_b32_e32 v20, 16, v10
	v_and_b32_e32 v21, 0xffff0000, v10
	v_pk_mul_f32 v[12:13], v[12:13], v[20:21]
	v_lshlrev_b32_e32 v10, 16, v11
	v_cvt_pk_bf16_f32 v38, v12, v13
	v_lshlrev_b32_e32 v12, 16, v34
	v_and_b32_e32 v13, 0xffff0000, v34
	v_and_b32_e32 v11, 0xffff0000, v11
	v_pk_mul_f32 v[10:11], v[12:13], v[10:11]
	s_waitcnt lgkmcnt(0)
	v_lshlrev_b32_e32 v12, 16, v14
	v_cvt_pk_bf16_f32 v40, v10, v11
	v_lshlrev_b32_e32 v10, 16, v33
	v_and_b32_e32 v11, 0xffff0000, v33
	v_and_b32_e32 v13, 0xffff0000, v14
	v_pk_mul_f32 v[10:11], v[10:11], v[12:13]
	v_lshlrev_b32_e32 v12, 16, v15
	v_cvt_pk_bf16_f32 v37, v10, v11
	v_lshlrev_b32_e32 v10, 16, v32
	v_and_b32_e32 v11, 0xffff0000, v32
	v_and_b32_e32 v13, 0xffff0000, v15
	v_pk_mul_f32 v[10:11], v[10:11], v[12:13]
	s_nop 0
	v_cvt_pk_bf16_f32 v39, v10, v11
	ds_read_b64 v[10:11], v113 offset:144
	ds_read_b64 v[14:15], v113 offset:16784
	v_lshlrev_b32_e32 v12, 16, v80
	v_and_b32_e32 v13, 0xffff0000, v80
	s_waitcnt lgkmcnt(1)
	v_lshlrev_b32_e32 v20, 16, v10
	v_and_b32_e32 v21, 0xffff0000, v10
	v_pk_mul_f32 v[12:13], v[12:13], v[20:21]
	v_lshlrev_b32_e32 v10, 16, v11
	v_cvt_pk_bf16_f32 v34, v12, v13
	v_lshlrev_b32_e32 v12, 16, v36
	v_and_b32_e32 v13, 0xffff0000, v36
	v_and_b32_e32 v11, 0xffff0000, v11
	v_pk_mul_f32 v[10:11], v[12:13], v[10:11]
	s_waitcnt lgkmcnt(0)
	v_lshlrev_b32_e32 v12, 16, v14
	v_cvt_pk_bf16_f32 v36, v10, v11
	v_lshlrev_b32_e32 v10, 16, v55
	v_and_b32_e32 v11, 0xffff0000, v55
	v_and_b32_e32 v13, 0xffff0000, v14
	v_pk_mul_f32 v[10:11], v[10:11], v[12:13]
	v_lshlrev_b32_e32 v12, 16, v15
	v_cvt_pk_bf16_f32 v32, v10, v11
	v_lshlrev_b32_e32 v10, 16, v53
	v_and_b32_e32 v11, 0xffff0000, v53
	v_and_b32_e32 v13, 0xffff0000, v15
	v_pk_mul_f32 v[10:11], v[10:11], v[12:13]
	s_nop 0
	v_cvt_pk_bf16_f32 v35, v10, v11
	ds_read_b64 v[10:11], v113 offset:160
	ds_read_b64 v[14:15], v113 offset:16800
	v_lshlrev_b32_e32 v12, 16, v83
	v_and_b32_e32 v13, 0xffff0000, v83
	s_waitcnt lgkmcnt(1)
	v_lshlrev_b32_e32 v20, 16, v10
	v_and_b32_e32 v21, 0xffff0000, v10
	v_pk_mul_f32 v[12:13], v[12:13], v[20:21]
	v_lshlrev_b32_e32 v10, 16, v11
	v_cvt_pk_bf16_f32 v24, v12, v13
	v_lshlrev_b32_e32 v12, 16, v82
	v_and_b32_e32 v13, 0xffff0000, v82
	v_and_b32_e32 v11, 0xffff0000, v11
	v_pk_mul_f32 v[10:11], v[12:13], v[10:11]
	s_waitcnt lgkmcnt(0)
	v_lshlrev_b32_e32 v12, 16, v14
	v_cvt_pk_bf16_f32 v26, v10, v11
	v_lshlrev_b32_e32 v10, 16, v81
	v_and_b32_e32 v11, 0xffff0000, v81
	v_and_b32_e32 v13, 0xffff0000, v14
	v_pk_mul_f32 v[10:11], v[10:11], v[12:13]
	v_lshlrev_b32_e32 v12, 16, v15
	v_cvt_pk_bf16_f32 v23, v10, v11
	v_lshlrev_b32_e32 v10, 16, v59
	v_and_b32_e32 v11, 0xffff0000, v59
	v_and_b32_e32 v13, 0xffff0000, v15
	v_pk_mul_f32 v[10:11], v[10:11], v[12:13]
	s_nop 0
	v_cvt_pk_bf16_f32 v25, v10, v11
	ds_read_b64 v[10:11], v113 offset:176
	ds_read_b64 v[14:15], v113 offset:16816
	v_lshlrev_b32_e32 v12, 16, v91
	v_and_b32_e32 v13, 0xffff0000, v91
	s_waitcnt lgkmcnt(1)
; DI unsigned pack2(float a, float b) { f32x2_t v = {a, b}; bf16x2_t r = __builtin_convertvector(v, bf16x2_t); return __builtin_bit_cast(unsigned, r); }
; DI float bflo(unsigned u) { return __uint_as_float(u << 16); }
; DI float bfhi(unsigned u) { return __uint_as_float(u & 0xffff0000u); }
; DI int otid() { int t = threadIdx.x; asm volatile("" : "+v"(t)); return t; }
; template <bool LAST>
; DI void phase_gate(const Params& P, int layer, unsigned char* smem, int L, int G) {
;     ...
;     {
;       const int tid1 = otid();
;       const int lane1 = tid1 & 63, w1 = tid1 >> 6, r1 = lane1 & 31, h1 = lane1 >> 5, wm1 = w1 >> 2, wn1 = w1 & 3;
; #pragma unroll
;       for (int i = 0; i < 4; ++i)
; #pragma unroll
;         for (int q4 = 0; q4 < 4; ++q4) {
; #pragma unroll
;           for (int j = 0; j < 2; ++j) {
;             const uint2 pv = *(const uint2*)(stg + (wn1 * 64 + j * 32 + r1) * STG + wm1 * 128 + i * 32 + 8 * q4 + 4 * h1);
;             const unsigned g0 = gq[i][j][2 * q4], g1 = gq[i][j][2 * q4 + 1];
;             gq[i][j][2 * q4] = pack2(bflo(g0) * bflo(pv.x), bfhi(g0) * bfhi(pv.x));
;             gq[i][j][2 * q4 + 1] = pack2(bflo(g1) * bflo(pv.y), bfhi(g1) * bfhi(pv.y));
;           }
;           __builtin_amdgcn_sched_barrier(0);
;         }
;     }
;     __syncthreads();
	v_lshlrev_b32_e32 v20, 16, v10
	v_and_b32_e32 v21, 0xffff0000, v10
	v_pk_mul_f32 v[12:13], v[12:13], v[20:21]
	v_lshlrev_b32_e32 v10, 16, v11
	v_cvt_pk_bf16_f32 v20, v12, v13
	v_lshlrev_b32_e32 v12, 16, v86
	v_and_b32_e32 v13, 0xffff0000, v86
	v_and_b32_e32 v11, 0xffff0000, v11
	v_pk_mul_f32 v[10:11], v[12:13], v[10:11]
	s_waitcnt lgkmcnt(0)
	v_lshlrev_b32_e32 v12, 16, v14
	v_cvt_pk_bf16_f32 v22, v10, v11
	v_lshlrev_b32_e32 v10, 16, v85
	v_and_b32_e32 v11, 0xffff0000, v85
	v_and_b32_e32 v13, 0xffff0000, v14
	v_pk_mul_f32 v[10:11], v[10:11], v[12:13]
	v_lshlrev_b32_e32 v12, 16, v15
	v_cvt_pk_bf16_f32 v18, v10, v11
	v_lshlrev_b32_e32 v10, 16, v84
	v_and_b32_e32 v11, 0xffff0000, v84
	v_and_b32_e32 v13, 0xffff0000, v15
	v_pk_mul_f32 v[10:11], v[10:11], v[12:13]
	s_nop 0
	v_cvt_pk_bf16_f32 v21, v10, v11
	ds_read_b64 v[10:11], v113 offset:192
	ds_read_b64 v[64:65], v113 offset:16832
	v_lshlrev_b32_e32 v12, 16, v17
	v_and_b32_e32 v13, 0xffff0000, v17
	s_waitcnt lgkmcnt(1)
	v_lshlrev_b32_e32 v14, 16, v10
	v_and_b32_e32 v15, 0xffff0000, v10
	v_pk_mul_f32 v[12:13], v[12:13], v[14:15]
	v_lshlrev_b32_e32 v10, 16, v11
	v_cvt_pk_bf16_f32 v15, v12, v13
	v_lshlrev_b32_e32 v12, 16, v16
	v_and_b32_e32 v13, 0xffff0000, v16
	v_and_b32_e32 v11, 0xffff0000, v11
	v_pk_mul_f32 v[10:11], v[12:13], v[10:11]
	s_waitcnt lgkmcnt(0)
	v_lshlrev_b32_e32 v12, 16, v64
	v_cvt_pk_bf16_f32 v17, v10, v11
	v_lshlrev_b32_e32 v10, 16, v3
	v_and_b32_e32 v11, 0xffff0000, v3
	v_and_b32_e32 v13, 0xffff0000, v64
	v_pk_mul_f32 v[10:11], v[10:11], v[12:13]
	v_lshlrev_b32_e32 v12, 16, v65
	v_cvt_pk_bf16_f32 v14, v10, v11
	v_lshlrev_b32_e32 v10, 16, v2
	v_and_b32_e32 v11, 0xffff0000, v2
	v_and_b32_e32 v13, 0xffff0000, v65
	v_pk_mul_f32 v[2:3], v[10:11], v[12:13]
	s_nop 0
	v_cvt_pk_bf16_f32 v16, v2, v3
	ds_read_b64 v[2:3], v113 offset:208
	ds_read_b64 v[64:65], v113 offset:16848
	v_lshlrev_b32_e32 v10, 16, v7
	v_and_b32_e32 v11, 0xffff0000, v7
	s_waitcnt lgkmcnt(1)
	v_lshlrev_b32_e32 v12, 16, v2
	v_and_b32_e32 v13, 0xffff0000, v2
	v_pk_mul_f32 v[10:11], v[10:11], v[12:13]
	v_lshlrev_b32_e32 v12, 16, v6
	v_lshlrev_b32_e32 v2, 16, v3
	v_and_b32_e32 v13, 0xffff0000, v6
	v_and_b32_e32 v3, 0xffff0000, v3
	v_pk_mul_f32 v[2:3], v[12:13], v[2:3]
	s_waitcnt lgkmcnt(0)
	v_lshlrev_b32_e32 v6, 16, v64
	v_cvt_pk_bf16_f32 v13, v2, v3
	v_lshlrev_b32_e32 v2, 16, v5
	v_and_b32_e32 v3, 0xffff0000, v5
	v_and_b32_e32 v7, 0xffff0000, v64
	v_pk_mul_f32 v[2:3], v[2:3], v[6:7]
	v_cvt_pk_bf16_f32 v11, v10, v11
	v_cvt_pk_bf16_f32 v10, v2, v3
	v_lshlrev_b32_e32 v2, 16, v4
	v_lshlrev_b32_e32 v6, 16, v65
	v_and_b32_e32 v3, 0xffff0000, v4
	v_and_b32_e32 v7, 0xffff0000, v65
	v_pk_mul_f32 v[2:3], v[2:3], v[6:7]
	s_nop 0
	v_cvt_pk_bf16_f32 v12, v2, v3
	ds_read_b64 v[2:3], v113 offset:224
	ds_read_b64 v[64:65], v113 offset:16864
	v_lshlrev_b32_e32 v4, 16, v27
	v_and_b32_e32 v5, 0xffff0000, v27
	s_waitcnt lgkmcnt(1)
	v_lshlrev_b32_e32 v6, 16, v2
	v_and_b32_e32 v7, 0xffff0000, v2
	v_pk_mul_f32 v[4:5], v[4:5], v[6:7]
	v_lshlrev_b32_e32 v2, 16, v3
	v_cvt_pk_bf16_f32 v7, v4, v5
	v_lshlrev_b32_e32 v4, 16, v9
	v_and_b32_e32 v5, 0xffff0000, v9
	v_and_b32_e32 v3, 0xffff0000, v3
	v_pk_mul_f32 v[2:3], v[4:5], v[2:3]
	s_waitcnt lgkmcnt(0)
	v_lshlrev_b32_e32 v4, 16, v64
	v_cvt_pk_bf16_f32 v9, v2, v3
	v_lshlrev_b32_e32 v2, 16, v19
	v_and_b32_e32 v3, 0xffff0000, v19
	v_and_b32_e32 v5, 0xffff0000, v64
	v_pk_mul_f32 v[2:3], v[2:3], v[4:5]
	v_lshlrev_b32_e32 v4, 16, v65
	v_cvt_pk_bf16_f32 v6, v2, v3
	v_lshlrev_b32_e32 v2, 16, v8
	v_and_b32_e32 v3, 0xffff0000, v8
	v_and_b32_e32 v5, 0xffff0000, v65
	v_pk_mul_f32 v[2:3], v[2:3], v[4:5]
	s_nop 0
	v_cvt_pk_bf16_f32 v8, v2, v3
	ds_read_b64 v[2:3], v113 offset:240
	ds_read_b64 v[64:65], v113 offset:16880
	v_lshlrev_b32_e32 v4, 16, v112
	v_and_b32_e32 v5, 0xffff0000, v112
	s_waitcnt lgkmcnt(1)
	v_lshlrev_b32_e32 v66, 16, v2
	v_and_b32_e32 v67, 0xffff0000, v2
	v_pk_mul_f32 v[4:5], v[4:5], v[66:67]
	v_lshlrev_b32_e32 v66, 16, v30
	v_lshlrev_b32_e32 v2, 16, v3
	v_and_b32_e32 v67, 0xffff0000, v30
	v_and_b32_e32 v3, 0xffff0000, v3
	v_pk_mul_f32 v[2:3], v[66:67], v[2:3]
	v_cvt_pk_bf16_f32 v4, v4, v5
	v_cvt_pk_bf16_f32 v5, v2, v3
	v_lshlrev_b32_e32 v2, 16, v29
	s_waitcnt lgkmcnt(0)
	v_lshlrev_b32_e32 v66, 16, v64
	v_and_b32_e32 v3, 0xffff0000, v29
	v_and_b32_e32 v67, 0xffff0000, v64
	v_pk_mul_f32 v[2:3], v[2:3], v[66:67]
	v_lshlrev_b32_e32 v66, 16, v28
	v_lshlrev_b32_e32 v64, 16, v65
	v_and_b32_e32 v67, 0xffff0000, v28
	v_and_b32_e32 v65, 0xffff0000, v65
	v_pk_mul_f32 v[28:29], v[66:67], v[64:65]
	v_cvt_pk_bf16_f32 v2, v2, v3
	v_cvt_pk_bf16_f32 v3, v28, v29
	v_mov_b32_e32 v19, v192
	s_barrier
; DI int otid() { int t = threadIdx.x; asm volatile("" : "+v"(t)); return t; }
; template <bool NT>
; DI void stage_load_tile(bf16_t* stg, const bf16_t* tilebase) {
;   const int tid = otid();
;   const int r0 = tid >> 5, c = tid & 31;
;   const unsigned o0 = (unsigned)(r0 * 1024 + c * 8);
;   __builtin_amdgcn_sched_barrier(0);
; #pragma unroll
;   for (int hf = 0; hf < 2; ++hf) {
; #pragma unroll
;     for (int it = 8 * hf; it < 8 * hf + 8; ++it) {
;       const u32x4* gp = (const u32x4*)(tilebase + (o0 + (unsigned)(it * 16 * 1024)));
;       stage_write16(stg, r0 + 16 * it, c, NT ? __builtin_nontemporal_load(gp) : *gp);
;     }
;     __builtin_amdgcn_sched_barrier(0);
;   }
; }
; template <bool LAST>
; DI void phase_gate(const Params& P, int layer, unsigned char* smem, int L, int G) {
;     ...
;     stage_load_tile<false>(stg, Sb + (size_t)mt * 256 * 1024 + nt * 256);
	s_add_u32 s30, s76, s24
	v_ashrrev_i32_e32 v27, 5, v19
	v_and_b32_e32 v19, 31, v19
	s_addc_u32 s31, s77, s25
	v_lshlrev_b32_e32 v30, 3, v19
	v_lshl_add_u64 v[28:29], s[30:31], 0, v[0:1]
	v_lshl_or_b32 v160, v27, 10, v30
	v_add_u32_e32 v66, 0x4000, v160
	v_mov_b32_e32 v67, v161
	v_add_u32_e32 v72, 0x8000, v160
	v_mov_b32_e32 v73, v161
	v_add_u32_e32 v74, 0xc000, v160
	v_mov_b32_e32 v75, v161
	v_add_u32_e32 v80, 0x10000, v160
	v_mov_b32_e32 v81, v161
	v_add_u32_e32 v82, 0x14000, v160
	v_mov_b32_e32 v83, v161
	v_lshl_add_u64 v[64:65], v[160:161], 1, v[28:29]
	v_lshl_add_u64 v[68:69], v[66:67], 1, v[28:29]
	v_lshl_add_u64 v[72:73], v[72:73], 1, v[28:29]
	v_lshl_add_u64 v[76:77], v[74:75], 1, v[28:29]
	v_lshl_add_u64 v[80:81], v[80:81], 1, v[28:29]
	v_lshl_add_u64 v[84:85], v[82:83], 1, v[28:29]
	global_load_dwordx4 v[64:67], v[64:65], off
	s_nop 0
	global_load_dwordx4 v[68:71], v[68:69], off
	s_nop 0
	global_load_dwordx4 v[72:75], v[72:73], off
	s_nop 0
	global_load_dwordx4 v[76:79], v[76:77], off
	s_nop 0
	global_load_dwordx4 v[80:83], v[80:81], off
	s_nop 0
	global_load_dwordx4 v[100:103], v[84:85], off
	v_add_u32_e32 v84, 0x18000, v160
	v_mov_b32_e32 v85, v161
	v_add_u32_e32 v104, 0x1c000, v160
	v_mov_b32_e32 v105, v161
	v_lshl_add_u64 v[84:85], v[84:85], 1, v[28:29]
	v_lshl_add_u64 v[108:109], v[104:105], 1, v[28:29]
	global_load_dwordx4 v[104:107], v[84:85], off
	s_nop 0
	global_load_dwordx4 v[108:111], v[108:109], off
	v_add_u32_e32 v218, 0x20000, v160
	v_mov_b32_e32 v219, v161
	v_add_u32_e32 v220, 0x24000, v160
	v_mov_b32_e32 v221, v161
	v_add_u32_e32 v226, 0x28000, v160
	v_mov_b32_e32 v227, v161
	v_add_u32_e32 v228, 0x2c000, v160
	v_mov_b32_e32 v229, v161
	v_add_u32_e32 v234, 0x30000, v160
	v_mov_b32_e32 v235, v161
	v_add_u32_e32 v236, 0x34000, v160
	v_mov_b32_e32 v237, v161
	v_lshl_add_u64 v[218:219], v[218:219], 1, v[28:29]
	v_lshl_add_u64 v[222:223], v[220:221], 1, v[28:29]
	v_lshl_add_u64 v[226:227], v[226:227], 1, v[28:29]
	v_lshl_add_u64 v[230:231], v[228:229], 1, v[28:29]
	v_lshl_add_u64 v[234:235], v[234:235], 1, v[28:29]
	v_lshl_add_u64 v[252:253], v[236:237], 1, v[28:29]
	global_load_dwordx4 v[218:221], v[218:219], off
	s_nop 0
	global_load_dwordx4 v[222:225], v[222:223], off
	s_nop 0
	global_load_dwordx4 v[226:229], v[226:227], off
	s_nop 0
	global_load_dwordx4 v[230:233], v[230:231], off
	s_nop 0
	global_load_dwordx4 v[234:237], v[234:235], off
	s_nop 0
	global_load_dwordx4 v[238:241], v[252:253], off
	v_add_u32_e32 v252, 0x38000, v160
	v_mov_b32_e32 v253, v161
	v_lshl_add_u64 v[252:253], v[252:253], 1, v[28:29]
	v_add_u32_e32 v160, 0x3c000, v160
	v_lshl_add_u64 v[190:191], v[160:161], 1, v[28:29]
	global_load_dwordx4 v[242:245], v[252:253], off
	global_load_dwordx4 v[248:251], v[190:191], off
	v_mul_lo_u32 v27, v27, s44
	v_lshl_add_u32 v19, v19, 4, v27
	v_add_u32_e32 v27, 0x2080, v19
	v_add_u32_e32 v30, 0x4100, v19
	v_add_u32_e32 v33, 0x6180, v19
	v_add_u32_e32 v53, 0x8200, v19
	v_add_u32_e32 v55, 0xa280, v19
	v_add_u32_e32 v59, 0xc300, v19
	v_add_u32_e32 v84, 0xe380, v19
	s_waitcnt vmcnt(15)
	ds_write2_b64 v19, v[64:65], v[66:67] offset1:1
	s_waitcnt vmcnt(14)
	ds_write2_b64 v27, v[68:69], v[70:71] offset1:1
	s_waitcnt vmcnt(13)
	ds_write2_b64 v30, v[72:73], v[74:75] offset1:1
	s_waitcnt vmcnt(12)
	ds_write2_b64 v33, v[76:77], v[78:79] offset1:1
	s_waitcnt vmcnt(11)
	ds_write2_b64 v53, v[80:81], v[82:83] offset1:1
	s_waitcnt vmcnt(10)
	ds_write2_b64 v55, v[100:101], v[102:103] offset1:1
	s_waitcnt vmcnt(9)
	ds_write2_b64 v59, v[104:105], v[106:107] offset1:1
	s_waitcnt vmcnt(8)
	ds_write2_b64 v84, v[108:109], v[110:111] offset1:1
	v_add_u32_e32 v27, 0x10400, v19
	v_add_u32_e32 v28, 0x12480, v19
	v_add_u32_e32 v29, 0x14500, v19
	v_add_u32_e32 v30, 0x16580, v19
	v_add_u32_e32 v33, 0x18600, v19
	v_add_u32_e32 v53, 0x1a680, v19
	v_add_u32_e32 v55, 0x1c700, v19
	v_add_u32_e32 v19, 0x1e780, v19
	s_waitcnt vmcnt(7)
	ds_write2_b64 v27, v[218:219], v[220:221] offset1:1
	s_waitcnt vmcnt(6)
	ds_write2_b64 v28, v[222:223], v[224:225] offset1:1
	s_waitcnt vmcnt(5)
	ds_write2_b64 v29, v[226:227], v[228:229] offset1:1
	s_waitcnt vmcnt(4)
	ds_write2_b64 v30, v[230:231], v[232:233] offset1:1
	s_waitcnt vmcnt(3)
	ds_write2_b64 v33, v[234:235], v[236:237] offset1:1
	s_waitcnt vmcnt(2)
	ds_write2_b64 v53, v[238:239], v[240:241] offset1:1
	s_waitcnt vmcnt(1)
	ds_write2_b64 v55, v[242:243], v[244:245] offset1:1
	s_waitcnt vmcnt(0)
	ds_write2_b64 v19, v[248:249], v[250:251] offset1:1
	v_mov_b32_e32 v19, v192
	s_waitcnt lgkmcnt(0)
	s_barrier
; DI unsigned pack2(float a, float b) { f32x2_t v = {a, b}; bf16x2_t r = __builtin_convertvector(v, bf16x2_t); return __builtin_bit_cast(unsigned, r); }
; DI float bflo(unsigned u) { return __uint_as_float(u << 16); }
; DI float bfhi(unsigned u) { return __uint_as_float(u & 0xffff0000u); }
; DI int otid() { int t = threadIdx.x; asm volatile("" : "+v"(t)); return t; }
; template <bool LAST>
; DI void phase_gate(const Params& P, int layer, unsigned char* smem, int L, int G) {
;     ...
;     const int tid2 = otid();
;     const int lane2 = tid2 & 63, w2 = tid2 >> 6, r2 = lane2 & 31, h2 = lane2 >> 5, wm2 = w2 >> 2, wn2 = w2 & 3;
; #pragma unroll
;     for (int i = 0; i < 4; ++i)
; #pragma unroll
;       for (int q4 = 0; q4 < 4; ++q4) {
;         const int fl = wm2 * 128 + i * 32 + 8 * q4 + 4 * h2;
;         const int f0 = nt * 256 + fl;
;         const f32x4 gv = *(const f32x4*)(vecL + 512 + fl), bv = *(const f32x4*)(vecL + 768 + fl);
;         const float ga[4] = {gv.x, gv.y, gv.z, gv.w}, ba[4] = {bv.x, bv.y, bv.z, bv.w};
; #pragma unroll
;         for (int j = 0; j < 2; ++j) {
;           const int lrow = wn2 * 64 + j * 32 + r2;
;           const float mu = rowA[lrow], rstd = rowB[lrow];
;           uint2* sp = (uint2*)(stg + lrow * STG + fl);
;           const uint2 sv = *sp;
;           const float sa[4] = {bflo(sv.x), bfhi(sv.x), bflo(sv.y), bfhi(sv.y)};
;           float y[4];
;           const float gg[4] = {bflo(gq[i][j][2 * q4]), bfhi(gq[i][j][2 * q4]), bflo(gq[i][j][2 * q4 + 1]), bfhi(gq[i][j][2 * q4 + 1])};
; #pragma unroll
;           for (int e = 0; e < 4; ++e) y[e] = (sa[e] - mu) * rstd * ga[e] + ba[e] + gg[e];
;           if (LAST) { f32x4 o = {y[0], y[1], y[2], y[3]}; *(f32x4*)(P.out + (size_t)(mt * 256 + lrow) * 1024 + f0) = o; }
;           else { uint2 pk; pk.x = pack2(y[0], y[1]); pk.y = pack2(y[2], y[3]); *sp = pk; }
;         }
;         __builtin_amdgcn_sched_barrier(0);
;       }
	v_lshlrev_b32_e32 v82, 16, v31
	v_lshrrev_b32_e32 v28, 3, v19
	v_ashrrev_i32_e32 v27, 1, v19
	v_and_b32_e32 v28, 4, v28
	v_and_or_b32 v30, v27, s45, v28
	v_and_b32_e32 v19, 0xdf, v19
	v_lshlrev_b32_e32 v27, 2, v30
	v_lshlrev_b32_e32 v33, 2, v19
	v_mul_u32_u24_e32 v19, 0x208, v19
	v_add_u32_e32 v28, 0x25000, v27
	v_lshl_add_u32 v19, v30, 1, v19
	v_add_u32_e32 v29, 0x25400, v27
	ds_read_b128 v[64:67], v28
	ds_read_b128 v[68:71], v29
	ds_read_b64 v[72:73], v19
	v_or_b32_e32 v29, 0x24000, v33
	v_or_b32_e32 v30, 0x24400, v33
	ds_read_b32 v74, v29
	ds_read_b32 v76, v30
	ds_read_b64 v[78:79], v19 offset:16640
	v_and_b32_e32 v83, 0xffff0000, v31
	s_waitcnt lgkmcnt(3)
	v_lshlrev_b32_e32 v80, 16, v72
	v_and_b32_e32 v81, 0xffff0000, v72
	v_lshlrev_b32_e32 v72, 16, v73
	v_and_b32_e32 v73, 0xffff0000, v73
	s_waitcnt lgkmcnt(2)
	v_pk_add_f32 v[80:81], v[80:81], v[74:75] op_sel_hi:[1,0] neg_lo:[0,1] neg_hi:[0,1]
	v_pk_add_f32 v[72:73], v[72:73], v[74:75] op_sel_hi:[1,0] neg_lo:[0,1] neg_hi:[0,1]
	s_waitcnt lgkmcnt(1)
	v_pk_mul_f32 v[80:81], v[76:77], v[80:81] op_sel_hi:[0,1]
	v_pk_mul_f32 v[72:73], v[76:77], v[72:73] op_sel_hi:[0,1]
	v_lshlrev_b32_e32 v84, 16, v98
	v_and_b32_e32 v85, 0xffff0000, v98
	v_pk_fma_f32 v[80:81], v[64:65], v[80:81], v[68:69]
	v_pk_fma_f32 v[72:73], v[66:67], v[72:73], v[70:71]
	v_pk_add_f32 v[80:81], v[80:81], v[82:83]
	v_pk_add_f32 v[72:73], v[72:73], v[84:85]
	v_cvt_pk_bf16_f32 v74, v80, v81
	v_cvt_pk_bf16_f32 v75, v72, v73
	ds_write_b64 v19, v[74:75]
	v_or_b32_e32 v31, 0x24080, v33
	v_or_b32_e32 v33, 0x24480, v33
	ds_read_b32 v72, v31
	ds_read_b32 v74, v33
	s_waitcnt lgkmcnt(3)
	v_lshlrev_b32_e32 v76, 16, v78
	v_and_b32_e32 v77, 0xffff0000, v78
	v_lshlrev_b32_e32 v78, 16, v79
	s_waitcnt lgkmcnt(1)
	v_pk_add_f32 v[76:77], v[76:77], v[72:73] op_sel_hi:[1,0] neg_lo:[0,1] neg_hi:[0,1]
	v_and_b32_e32 v79, 0xffff0000, v79
	s_waitcnt lgkmcnt(0)
	v_pk_mul_f32 v[76:77], v[74:75], v[76:77] op_sel_hi:[0,1]
	v_pk_fma_f32 v[64:65], v[64:65], v[76:77], v[68:69]
	v_pk_add_f32 v[68:69], v[78:79], v[72:73] op_sel_hi:[1,0] neg_lo:[0,1] neg_hi:[0,1]
	v_lshlrev_b32_e32 v80, 16, v97
	v_pk_mul_f32 v[68:69], v[74:75], v[68:69] op_sel_hi:[0,1]
	v_and_b32_e32 v81, 0xffff0000, v97
	v_lshlrev_b32_e32 v82, 16, v96
	v_and_b32_e32 v83, 0xffff0000, v96
	v_pk_fma_f32 v[66:67], v[66:67], v[68:69], v[70:71]
	v_pk_add_f32 v[64:65], v[64:65], v[80:81]
	v_pk_add_f32 v[66:67], v[66:67], v[82:83]
	v_cvt_pk_bf16_f32 v64, v64, v65
	v_cvt_pk_bf16_f32 v65, v66, v67
	ds_write_b64 v19, v[64:65] offset:16640
	v_add_u32_e32 v53, 0x25020, v27
	v_add_u32_e32 v55, 0x25420, v27
	ds_read_b64 v[72:73], v19 offset:16
	ds_read_b128 v[64:67], v53
	ds_read_b128 v[68:71], v55
	ds_read_b32 v74, v29
	ds_read_b32 v76, v30
	ds_read_b64 v[78:79], v19 offset:16656
	s_waitcnt lgkmcnt(5)
	v_lshlrev_b32_e32 v80, 16, v72
	v_and_b32_e32 v81, 0xffff0000, v72
	v_lshlrev_b32_e32 v72, 16, v73
	v_and_b32_e32 v73, 0xffff0000, v73
	s_waitcnt lgkmcnt(2)
	v_pk_add_f32 v[80:81], v[80:81], v[74:75] op_sel_hi:[1,0] neg_lo:[0,1] neg_hi:[0,1]
	v_pk_add_f32 v[72:73], v[72:73], v[74:75] op_sel_hi:[1,0] neg_lo:[0,1] neg_hi:[0,1]
	s_waitcnt lgkmcnt(1)
	v_pk_mul_f32 v[80:81], v[76:77], v[80:81] op_sel_hi:[0,1]
	v_pk_mul_f32 v[72:73], v[76:77], v[72:73] op_sel_hi:[0,1]
	v_lshlrev_b32_e32 v82, 16, v93
	v_and_b32_e32 v83, 0xffff0000, v93
	v_lshlrev_b32_e32 v84, 16, v95
	v_and_b32_e32 v85, 0xffff0000, v95
	v_pk_fma_f32 v[80:81], v[64:65], v[80:81], v[68:69]
	v_pk_fma_f32 v[72:73], v[66:67], v[72:73], v[70:71]
	v_pk_add_f32 v[80:81], v[80:81], v[82:83]
	v_pk_add_f32 v[72:73], v[72:73], v[84:85]
	v_cvt_pk_bf16_f32 v74, v80, v81
	v_cvt_pk_bf16_f32 v75, v72, v73
	ds_write_b64 v19, v[74:75] offset:16
	ds_read_b32 v72, v31
	ds_read_b32 v74, v33
	s_waitcnt lgkmcnt(3)
	v_lshlrev_b32_e32 v76, 16, v78
	v_and_b32_e32 v77, 0xffff0000, v78
	v_lshlrev_b32_e32 v78, 16, v79
	s_waitcnt lgkmcnt(1)
	v_pk_add_f32 v[76:77], v[76:77], v[72:73] op_sel_hi:[1,0] neg_lo:[0,1] neg_hi:[0,1]
	v_and_b32_e32 v79, 0xffff0000, v79
	s_waitcnt lgkmcnt(0)
	v_pk_mul_f32 v[76:77], v[74:75], v[76:77] op_sel_hi:[0,1]
	v_pk_fma_f32 v[64:65], v[64:65], v[76:77], v[68:69]
	v_pk_add_f32 v[68:69], v[78:79], v[72:73] op_sel_hi:[1,0] neg_lo:[0,1] neg_hi:[0,1]
	v_lshlrev_b32_e32 v80, 16, v92
	v_pk_mul_f32 v[68:69], v[74:75], v[68:69] op_sel_hi:[0,1]
	v_and_b32_e32 v81, 0xffff0000, v92
	v_lshlrev_b32_e32 v82, 16, v94
	v_and_b32_e32 v83, 0xffff0000, v94
	v_pk_fma_f32 v[66:67], v[66:67], v[68:69], v[70:71]
	v_pk_add_f32 v[64:65], v[64:65], v[80:81]
	v_pk_add_f32 v[66:67], v[66:67], v[82:83]
	v_cvt_pk_bf16_f32 v64, v64, v65
	v_cvt_pk_bf16_f32 v65, v66, v67
	ds_write_b64 v19, v[64:65] offset:16656
	v_add_u32_e32 v53, 0x25040, v27
	v_add_u32_e32 v55, 0x25440, v27
	ds_read_b64 v[72:73], v19 offset:32
	ds_read_b128 v[64:67], v53
	ds_read_b128 v[68:71], v55
	ds_read_b32 v74, v29
	ds_read_b32 v76, v30
	ds_read_b64 v[78:79], v19 offset:16672
	s_waitcnt lgkmcnt(5)
	v_lshlrev_b32_e32 v80, 16, v72
	v_and_b32_e32 v81, 0xffff0000, v72
	v_lshlrev_b32_e32 v72, 16, v73
	v_and_b32_e32 v73, 0xffff0000, v73
	s_waitcnt lgkmcnt(2)
	v_pk_add_f32 v[80:81], v[80:81], v[74:75] op_sel_hi:[1,0] neg_lo:[0,1] neg_hi:[0,1]
	v_pk_add_f32 v[72:73], v[72:73], v[74:75] op_sel_hi:[1,0] neg_lo:[0,1] neg_hi:[0,1]
	s_waitcnt lgkmcnt(1)
	v_pk_mul_f32 v[80:81], v[76:77], v[80:81] op_sel_hi:[0,1]
	v_pk_mul_f32 v[72:73], v[76:77], v[72:73] op_sel_hi:[0,1]
	v_lshlrev_b32_e32 v82, 16, v88
	v_and_b32_e32 v83, 0xffff0000, v88
	v_lshlrev_b32_e32 v84, 16, v90
	v_and_b32_e32 v85, 0xffff0000, v90
	v_pk_fma_f32 v[80:81], v[64:65], v[80:81], v[68:69]
	v_pk_fma_f32 v[72:73], v[66:67], v[72:73], v[70:71]
	v_pk_add_f32 v[80:81], v[80:81], v[82:83]
	v_pk_add_f32 v[72:73], v[72:73], v[84:85]
	v_cvt_pk_bf16_f32 v74, v80, v81
	v_cvt_pk_bf16_f32 v75, v72, v73
	ds_write_b64 v19, v[74:75] offset:32
	ds_read_b32 v72, v31
	ds_read_b32 v74, v33
	s_waitcnt lgkmcnt(3)
; DI unsigned pack2(float a, float b) { f32x2_t v = {a, b}; bf16x2_t r = __builtin_convertvector(v, bf16x2_t); return __builtin_bit_cast(unsigned, r); }
; DI float bflo(unsigned u) { return __uint_as_float(u << 16); }
; DI float bfhi(unsigned u) { return __uint_as_float(u & 0xffff0000u); }
; DI int otid() { int t = threadIdx.x; asm volatile("" : "+v"(t)); return t; }
; template <bool LAST>
; DI void phase_gate(const Params& P, int layer, unsigned char* smem, int L, int G) {
;     ...
;     const int tid2 = otid();
;     const int lane2 = tid2 & 63, w2 = tid2 >> 6, r2 = lane2 & 31, h2 = lane2 >> 5, wm2 = w2 >> 2, wn2 = w2 & 3;
; #pragma unroll
;     for (int i = 0; i < 4; ++i)
; #pragma unroll
;       for (int q4 = 0; q4 < 4; ++q4) {
;         const int fl = wm2 * 128 + i * 32 + 8 * q4 + 4 * h2;
;         const int f0 = nt * 256 + fl;
;         const f32x4 gv = *(const f32x4*)(vecL + 512 + fl), bv = *(const f32x4*)(vecL + 768 + fl);
;         const float ga[4] = {gv.x, gv.y, gv.z, gv.w}, ba[4] = {bv.x, bv.y, bv.z, bv.w};
; #pragma unroll
;         for (int j = 0; j < 2; ++j) {
;           const int lrow = wn2 * 64 + j * 32 + r2;
;           const float mu = rowA[lrow], rstd = rowB[lrow];
;           uint2* sp = (uint2*)(stg + lrow * STG + fl);
;           const uint2 sv = *sp;
;           const float sa[4] = {bflo(sv.x), bfhi(sv.x), bflo(sv.y), bfhi(sv.y)};
;           float y[4];
;           const float gg[4] = {bflo(gq[i][j][2 * q4]), bfhi(gq[i][j][2 * q4]), bflo(gq[i][j][2 * q4 + 1]), bfhi(gq[i][j][2 * q4 + 1])};
; #pragma unroll
;           for (int e = 0; e < 4; ++e) y[e] = (sa[e] - mu) * rstd * ga[e] + ba[e] + gg[e];
;           if (LAST) { f32x4 o = {y[0], y[1], y[2], y[3]}; *(f32x4*)(P.out + (size_t)(mt * 256 + lrow) * 1024 + f0) = o; }
;           else { uint2 pk; pk.x = pack2(y[0], y[1]); pk.y = pack2(y[2], y[3]); *sp = pk; }
;         }
;         __builtin_amdgcn_sched_barrier(0);
;       }
	v_lshlrev_b32_e32 v76, 16, v78
	v_and_b32_e32 v77, 0xffff0000, v78
	v_lshlrev_b32_e32 v78, 16, v79
	s_waitcnt lgkmcnt(1)
	v_pk_add_f32 v[76:77], v[76:77], v[72:73] op_sel_hi:[1,0] neg_lo:[0,1] neg_hi:[0,1]
	v_and_b32_e32 v79, 0xffff0000, v79
	s_waitcnt lgkmcnt(0)
	v_pk_mul_f32 v[76:77], v[74:75], v[76:77] op_sel_hi:[0,1]
	v_pk_fma_f32 v[64:65], v[64:65], v[76:77], v[68:69]
	v_pk_add_f32 v[68:69], v[78:79], v[72:73] op_sel_hi:[1,0] neg_lo:[0,1] neg_hi:[0,1]
	v_lshlrev_b32_e32 v80, 16, v87
	v_pk_mul_f32 v[68:69], v[74:75], v[68:69] op_sel_hi:[0,1]
	v_and_b32_e32 v81, 0xffff0000, v87
	v_lshlrev_b32_e32 v82, 16, v89
	v_and_b32_e32 v83, 0xffff0000, v89
	v_pk_fma_f32 v[66:67], v[66:67], v[68:69], v[70:71]
	v_pk_add_f32 v[64:65], v[64:65], v[80:81]
	v_pk_add_f32 v[66:67], v[66:67], v[82:83]
	v_cvt_pk_bf16_f32 v64, v64, v65
	v_cvt_pk_bf16_f32 v65, v66, v67
	ds_write_b64 v19, v[64:65] offset:16672
	v_add_u32_e32 v53, 0x25060, v27
	v_add_u32_e32 v55, 0x25460, v27
	ds_read_b64 v[72:73], v19 offset:48
	ds_read_b128 v[64:67], v53
	ds_read_b128 v[68:71], v55
	ds_read_b32 v74, v29
	ds_read_b32 v76, v30
	ds_read_b64 v[78:79], v19 offset:16688
	s_waitcnt lgkmcnt(5)
	v_lshlrev_b32_e32 v80, 16, v72
	v_and_b32_e32 v81, 0xffff0000, v72
	v_lshlrev_b32_e32 v72, 16, v73
	v_and_b32_e32 v73, 0xffff0000, v73
	s_waitcnt lgkmcnt(2)
	v_pk_add_f32 v[80:81], v[80:81], v[74:75] op_sel_hi:[1,0] neg_lo:[0,1] neg_hi:[0,1]
	v_pk_add_f32 v[72:73], v[72:73], v[74:75] op_sel_hi:[1,0] neg_lo:[0,1] neg_hi:[0,1]
	s_waitcnt lgkmcnt(1)
	v_pk_mul_f32 v[80:81], v[76:77], v[80:81] op_sel_hi:[0,1]
	v_pk_mul_f32 v[72:73], v[76:77], v[72:73] op_sel_hi:[0,1]
	v_lshlrev_b32_e32 v82, 16, v61
	v_and_b32_e32 v83, 0xffff0000, v61
	v_lshlrev_b32_e32 v84, 16, v63
	v_and_b32_e32 v85, 0xffff0000, v63
	v_pk_fma_f32 v[80:81], v[64:65], v[80:81], v[68:69]
	v_pk_fma_f32 v[72:73], v[66:67], v[72:73], v[70:71]
	v_pk_add_f32 v[80:81], v[80:81], v[82:83]
	v_pk_add_f32 v[72:73], v[72:73], v[84:85]
	v_cvt_pk_bf16_f32 v74, v80, v81
	v_cvt_pk_bf16_f32 v75, v72, v73
	ds_write_b64 v19, v[74:75] offset:48
	ds_read_b32 v72, v31
	ds_read_b32 v74, v33
	s_waitcnt lgkmcnt(3)
	v_lshlrev_b32_e32 v76, 16, v78
	v_and_b32_e32 v77, 0xffff0000, v78
	v_lshlrev_b32_e32 v80, 16, v60
	v_and_b32_e32 v81, 0xffff0000, v60
	v_lshlrev_b32_e32 v60, 16, v62
	v_and_b32_e32 v61, 0xffff0000, v62
	s_waitcnt lgkmcnt(1)
	v_pk_add_f32 v[62:63], v[76:77], v[72:73] op_sel_hi:[1,0] neg_lo:[0,1] neg_hi:[0,1]
	v_lshlrev_b32_e32 v78, 16, v79
	v_and_b32_e32 v79, 0xffff0000, v79
	s_waitcnt lgkmcnt(0)
	v_pk_mul_f32 v[62:63], v[74:75], v[62:63] op_sel_hi:[0,1]
	v_pk_fma_f32 v[62:63], v[64:65], v[62:63], v[68:69]
	v_pk_add_f32 v[64:65], v[78:79], v[72:73] op_sel_hi:[1,0] neg_lo:[0,1] neg_hi:[0,1]
	v_pk_add_f32 v[62:63], v[62:63], v[80:81]
	v_pk_mul_f32 v[64:65], v[74:75], v[64:65] op_sel_hi:[0,1]
	v_pk_fma_f32 v[64:65], v[66:67], v[64:65], v[70:71]
	v_cvt_pk_bf16_f32 v62, v62, v63
	v_pk_add_f32 v[60:61], v[64:65], v[60:61]
	s_nop 0
	v_cvt_pk_bf16_f32 v63, v60, v61
	ds_write_b64 v19, v[62:63] offset:16688
	v_add_u32_e32 v53, 0x25080, v27
	v_add_u32_e32 v55, 0x25480, v27
	ds_read_b64 v[68:69], v19 offset:64
	ds_read_b128 v[60:63], v53
	ds_read_b128 v[64:67], v55
	ds_read_b32 v70, v29
	ds_read_b32 v72, v30
	ds_read_b64 v[74:75], v19 offset:16704
	s_waitcnt lgkmcnt(5)
	v_lshlrev_b32_e32 v76, 16, v68
	v_and_b32_e32 v77, 0xffff0000, v68
	v_lshlrev_b32_e32 v68, 16, v69
	v_and_b32_e32 v69, 0xffff0000, v69
	v_lshlrev_b32_e32 v80, 16, v58
	v_and_b32_e32 v81, 0xffff0000, v58
	s_waitcnt lgkmcnt(2)
	v_pk_add_f32 v[58:59], v[76:77], v[70:71] op_sel_hi:[1,0] neg_lo:[0,1] neg_hi:[0,1]
	v_pk_add_f32 v[68:69], v[68:69], v[70:71] op_sel_hi:[1,0] neg_lo:[0,1] neg_hi:[0,1]
	s_waitcnt lgkmcnt(1)
	v_pk_mul_f32 v[58:59], v[72:73], v[58:59] op_sel_hi:[0,1]
	v_pk_mul_f32 v[68:69], v[72:73], v[68:69] op_sel_hi:[0,1]
	v_lshlrev_b32_e32 v78, 16, v56
	v_and_b32_e32 v79, 0xffff0000, v56
	v_pk_fma_f32 v[58:59], v[60:61], v[58:59], v[64:65]
	v_pk_fma_f32 v[68:69], v[62:63], v[68:69], v[66:67]
	v_pk_add_f32 v[58:59], v[58:59], v[78:79]
	v_pk_add_f32 v[68:69], v[68:69], v[80:81]
	v_cvt_pk_bf16_f32 v58, v58, v59
	v_cvt_pk_bf16_f32 v59, v68, v69
	ds_write_b64 v19, v[58:59] offset:64
	ds_read_b32 v56, v31
	ds_read_b32 v58, v33
	s_waitcnt lgkmcnt(3)
	v_lshlrev_b32_e32 v68, 16, v74
	v_and_b32_e32 v69, 0xffff0000, v74
	v_lshlrev_b32_e32 v70, 16, v75
	v_and_b32_e32 v71, 0xffff0000, v75
	v_lshlrev_b32_e32 v72, 16, v54
	v_and_b32_e32 v73, 0xffff0000, v54
	v_lshlrev_b32_e32 v54, 16, v57
	v_and_b32_e32 v55, 0xffff0000, v57
	s_waitcnt lgkmcnt(1)
	v_pk_add_f32 v[68:69], v[68:69], v[56:57] op_sel_hi:[1,0] neg_lo:[0,1] neg_hi:[0,1]
	v_pk_add_f32 v[56:57], v[70:71], v[56:57] op_sel_hi:[1,0] neg_lo:[0,1] neg_hi:[0,1]
	s_waitcnt lgkmcnt(0)
	v_pk_mul_f32 v[68:69], v[58:59], v[68:69] op_sel_hi:[0,1]
	v_pk_mul_f32 v[56:57], v[58:59], v[56:57] op_sel_hi:[0,1]
	v_pk_fma_f32 v[60:61], v[60:61], v[68:69], v[64:65]
	v_pk_fma_f32 v[56:57], v[62:63], v[56:57], v[66:67]
	v_pk_add_f32 v[60:61], v[60:61], v[72:73]
	v_pk_add_f32 v[54:55], v[56:57], v[54:55]
	v_cvt_pk_bf16_f32 v56, v60, v61
	v_cvt_pk_bf16_f32 v57, v54, v55
	ds_write_b64 v19, v[56:57] offset:16704
	v_add_u32_e32 v58, 0x254a0, v27
	v_add_u32_e32 v53, 0x250a0, v27
	ds_read_b64 v[62:63], v19 offset:80
	ds_read_b128 v[54:57], v53
	ds_read_b128 v[58:61], v58
	ds_read_b32 v64, v29
	ds_read_b32 v66, v30
	ds_read_b64 v[68:69], v19 offset:16720
	s_waitcnt lgkmcnt(5)
	v_lshlrev_b32_e32 v70, 16, v62
	v_and_b32_e32 v71, 0xffff0000, v62
	v_lshlrev_b32_e32 v62, 16, v63
	v_and_b32_e32 v63, 0xffff0000, v63
	v_lshlrev_b32_e32 v74, 16, v52
	v_and_b32_e32 v75, 0xffff0000, v52
	s_waitcnt lgkmcnt(2)
; DI unsigned pack2(float a, float b) { f32x2_t v = {a, b}; bf16x2_t r = __builtin_convertvector(v, bf16x2_t); return __builtin_bit_cast(unsigned, r); }
; DI float bflo(unsigned u) { return __uint_as_float(u << 16); }
; DI float bfhi(unsigned u) { return __uint_as_float(u & 0xffff0000u); }
; DI int otid() { int t = threadIdx.x; asm volatile("" : "+v"(t)); return t; }
; template <bool LAST>
; DI void phase_gate(const Params& P, int layer, unsigned char* smem, int L, int G) {
;     ...
;     const int tid2 = otid();
;     const int lane2 = tid2 & 63, w2 = tid2 >> 6, r2 = lane2 & 31, h2 = lane2 >> 5, wm2 = w2 >> 2, wn2 = w2 & 3;
; #pragma unroll
;     for (int i = 0; i < 4; ++i)
; #pragma unroll
;       for (int q4 = 0; q4 < 4; ++q4) {
;         const int fl = wm2 * 128 + i * 32 + 8 * q4 + 4 * h2;
;         const int f0 = nt * 256 + fl;
;         const f32x4 gv = *(const f32x4*)(vecL + 512 + fl), bv = *(const f32x4*)(vecL + 768 + fl);
;         const float ga[4] = {gv.x, gv.y, gv.z, gv.w}, ba[4] = {bv.x, bv.y, bv.z, bv.w};
; #pragma unroll
;         for (int j = 0; j < 2; ++j) {
;           const int lrow = wn2 * 64 + j * 32 + r2;
;           const float mu = rowA[lrow], rstd = rowB[lrow];
;           uint2* sp = (uint2*)(stg + lrow * STG + fl);
;           const uint2 sv = *sp;
;           const float sa[4] = {bflo(sv.x), bfhi(sv.x), bflo(sv.y), bfhi(sv.y)};
;           float y[4];
;           const float gg[4] = {bflo(gq[i][j][2 * q4]), bfhi(gq[i][j][2 * q4]), bflo(gq[i][j][2 * q4 + 1]), bfhi(gq[i][j][2 * q4 + 1])};
; #pragma unroll
;           for (int e = 0; e < 4; ++e) y[e] = (sa[e] - mu) * rstd * ga[e] + ba[e] + gg[e];
;           if (LAST) { f32x4 o = {y[0], y[1], y[2], y[3]}; *(f32x4*)(P.out + (size_t)(mt * 256 + lrow) * 1024 + f0) = o; }
;           else { uint2 pk; pk.x = pack2(y[0], y[1]); pk.y = pack2(y[2], y[3]); *sp = pk; }
;         }
;         __builtin_amdgcn_sched_barrier(0);
;       }
	v_pk_add_f32 v[52:53], v[70:71], v[64:65] op_sel_hi:[1,0] neg_lo:[0,1] neg_hi:[0,1]
	v_pk_add_f32 v[62:63], v[62:63], v[64:65] op_sel_hi:[1,0] neg_lo:[0,1] neg_hi:[0,1]
	s_waitcnt lgkmcnt(1)
	v_pk_mul_f32 v[52:53], v[66:67], v[52:53] op_sel_hi:[0,1]
	v_pk_mul_f32 v[62:63], v[66:67], v[62:63] op_sel_hi:[0,1]
	v_lshlrev_b32_e32 v72, 16, v50
	v_and_b32_e32 v73, 0xffff0000, v50
	v_pk_fma_f32 v[52:53], v[54:55], v[52:53], v[58:59]
	v_pk_fma_f32 v[62:63], v[56:57], v[62:63], v[60:61]
	v_pk_add_f32 v[52:53], v[52:53], v[72:73]
	v_pk_add_f32 v[62:63], v[62:63], v[74:75]
	v_cvt_pk_bf16_f32 v52, v52, v53
	v_cvt_pk_bf16_f32 v53, v62, v63
	ds_write_b64 v19, v[52:53] offset:80
	ds_read_b32 v50, v31
	ds_read_b32 v52, v33
	s_waitcnt lgkmcnt(3)
	v_lshlrev_b32_e32 v62, 16, v68
	v_and_b32_e32 v63, 0xffff0000, v68
	v_lshlrev_b32_e32 v64, 16, v69
	v_and_b32_e32 v65, 0xffff0000, v69
	v_lshlrev_b32_e32 v68, 16, v51
	v_and_b32_e32 v69, 0xffff0000, v51
	s_waitcnt lgkmcnt(1)
	v_pk_add_f32 v[62:63], v[62:63], v[50:51] op_sel_hi:[1,0] neg_lo:[0,1] neg_hi:[0,1]
	v_pk_add_f32 v[50:51], v[64:65], v[50:51] op_sel_hi:[1,0] neg_lo:[0,1] neg_hi:[0,1]
	s_waitcnt lgkmcnt(0)
	v_pk_mul_f32 v[62:63], v[52:53], v[62:63] op_sel_hi:[0,1]
	v_pk_mul_f32 v[50:51], v[52:53], v[50:51] op_sel_hi:[0,1]
	v_lshlrev_b32_e32 v66, 16, v49
	v_and_b32_e32 v67, 0xffff0000, v49
	v_pk_fma_f32 v[54:55], v[54:55], v[62:63], v[58:59]
	v_pk_fma_f32 v[50:51], v[56:57], v[50:51], v[60:61]
	v_pk_add_f32 v[54:55], v[54:55], v[66:67]
	v_pk_add_f32 v[50:51], v[50:51], v[68:69]
	v_cvt_pk_bf16_f32 v52, v54, v55
	v_cvt_pk_bf16_f32 v53, v50, v51
	ds_write_b64 v19, v[52:53] offset:16720
	v_add_u32_e32 v54, 0x254c0, v27
	v_add_u32_e32 v49, 0x250c0, v27
	ds_read_b64 v[58:59], v19 offset:96
	ds_read_b128 v[50:53], v49
	ds_read_b128 v[54:57], v54
	ds_read_b32 v60, v29
	ds_read_b32 v62, v30
	ds_read_b64 v[64:65], v19 offset:16736
	s_waitcnt lgkmcnt(5)
	v_lshlrev_b32_e32 v66, 16, v58
	v_and_b32_e32 v67, 0xffff0000, v58
	v_lshlrev_b32_e32 v58, 16, v59
	v_and_b32_e32 v59, 0xffff0000, v59
	v_lshlrev_b32_e32 v70, 16, v48
	v_and_b32_e32 v71, 0xffff0000, v48
	s_waitcnt lgkmcnt(2)
	v_pk_add_f32 v[48:49], v[66:67], v[60:61] op_sel_hi:[1,0] neg_lo:[0,1] neg_hi:[0,1]
	v_pk_add_f32 v[58:59], v[58:59], v[60:61] op_sel_hi:[1,0] neg_lo:[0,1] neg_hi:[0,1]
	s_waitcnt lgkmcnt(1)
	v_pk_mul_f32 v[48:49], v[62:63], v[48:49] op_sel_hi:[0,1]
	v_pk_mul_f32 v[58:59], v[62:63], v[58:59] op_sel_hi:[0,1]
	v_lshlrev_b32_e32 v68, 16, v46
	v_and_b32_e32 v69, 0xffff0000, v46
	v_pk_fma_f32 v[48:49], v[50:51], v[48:49], v[54:55]
	v_pk_fma_f32 v[58:59], v[52:53], v[58:59], v[56:57]
	v_pk_add_f32 v[48:49], v[48:49], v[68:69]
	v_pk_add_f32 v[58:59], v[58:59], v[70:71]
	v_cvt_pk_bf16_f32 v48, v48, v49
	v_cvt_pk_bf16_f32 v49, v58, v59
	ds_write_b64 v19, v[48:49] offset:96
	ds_read_b32 v46, v31
	ds_read_b32 v48, v33
	s_waitcnt lgkmcnt(3)
	v_lshlrev_b32_e32 v58, 16, v64
	v_and_b32_e32 v59, 0xffff0000, v64
	v_lshlrev_b32_e32 v60, 16, v65
	v_and_b32_e32 v61, 0xffff0000, v65
	v_lshlrev_b32_e32 v64, 16, v47
	v_and_b32_e32 v65, 0xffff0000, v47
	s_waitcnt lgkmcnt(1)
	v_pk_add_f32 v[58:59], v[58:59], v[46:47] op_sel_hi:[1,0] neg_lo:[0,1] neg_hi:[0,1]
	v_pk_add_f32 v[46:47], v[60:61], v[46:47] op_sel_hi:[1,0] neg_lo:[0,1] neg_hi:[0,1]
	s_waitcnt lgkmcnt(0)
	v_pk_mul_f32 v[58:59], v[48:49], v[58:59] op_sel_hi:[0,1]
	v_pk_mul_f32 v[46:47], v[48:49], v[46:47] op_sel_hi:[0,1]
	v_lshlrev_b32_e32 v62, 16, v45
	v_and_b32_e32 v63, 0xffff0000, v45
	v_pk_fma_f32 v[50:51], v[50:51], v[58:59], v[54:55]
	v_pk_fma_f32 v[46:47], v[52:53], v[46:47], v[56:57]
	v_pk_add_f32 v[50:51], v[50:51], v[62:63]
	v_pk_add_f32 v[46:47], v[46:47], v[64:65]
	v_cvt_pk_bf16_f32 v48, v50, v51
	v_cvt_pk_bf16_f32 v49, v46, v47
	ds_write_b64 v19, v[48:49] offset:16736
	v_add_u32_e32 v50, 0x254e0, v27
	v_add_u32_e32 v45, 0x250e0, v27
	ds_read_b64 v[54:55], v19 offset:112
	ds_read_b128 v[46:49], v45
	ds_read_b128 v[50:53], v50
	ds_read_b32 v56, v29
	ds_read_b32 v58, v30
	ds_read_b64 v[60:61], v19 offset:16752
	s_waitcnt lgkmcnt(5)
	v_lshlrev_b32_e32 v62, 16, v54
	v_and_b32_e32 v63, 0xffff0000, v54
	v_lshlrev_b32_e32 v54, 16, v55
	v_and_b32_e32 v55, 0xffff0000, v55
	v_lshlrev_b32_e32 v66, 16, v44
	v_and_b32_e32 v67, 0xffff0000, v44
	s_waitcnt lgkmcnt(2)
	v_pk_add_f32 v[44:45], v[62:63], v[56:57] op_sel_hi:[1,0] neg_lo:[0,1] neg_hi:[0,1]
	v_pk_add_f32 v[54:55], v[54:55], v[56:57] op_sel_hi:[1,0] neg_lo:[0,1] neg_hi:[0,1]
	s_waitcnt lgkmcnt(1)
	v_pk_mul_f32 v[44:45], v[58:59], v[44:45] op_sel_hi:[0,1]
	v_pk_mul_f32 v[54:55], v[58:59], v[54:55] op_sel_hi:[0,1]
	v_lshlrev_b32_e32 v64, 16, v42
	v_and_b32_e32 v65, 0xffff0000, v42
	v_pk_fma_f32 v[44:45], v[46:47], v[44:45], v[50:51]
	v_pk_fma_f32 v[54:55], v[48:49], v[54:55], v[52:53]
	v_pk_add_f32 v[44:45], v[44:45], v[64:65]
	v_pk_add_f32 v[54:55], v[54:55], v[66:67]
	v_cvt_pk_bf16_f32 v44, v44, v45
	v_cvt_pk_bf16_f32 v45, v54, v55
	ds_write_b64 v19, v[44:45] offset:112
	ds_read_b32 v42, v31
	ds_read_b32 v44, v33
	s_waitcnt lgkmcnt(3)
	v_lshlrev_b32_e32 v54, 16, v60
	v_and_b32_e32 v55, 0xffff0000, v60
	v_lshlrev_b32_e32 v56, 16, v61
	v_and_b32_e32 v57, 0xffff0000, v61
	v_lshlrev_b32_e32 v60, 16, v43
	v_and_b32_e32 v61, 0xffff0000, v43
	s_waitcnt lgkmcnt(1)
	v_pk_add_f32 v[54:55], v[54:55], v[42:43] op_sel_hi:[1,0] neg_lo:[0,1] neg_hi:[0,1]
	v_pk_add_f32 v[42:43], v[56:57], v[42:43] op_sel_hi:[1,0] neg_lo:[0,1] neg_hi:[0,1]
	s_waitcnt lgkmcnt(0)
; DI unsigned pack2(float a, float b) { f32x2_t v = {a, b}; bf16x2_t r = __builtin_convertvector(v, bf16x2_t); return __builtin_bit_cast(unsigned, r); }
; DI float bflo(unsigned u) { return __uint_as_float(u << 16); }
; DI float bfhi(unsigned u) { return __uint_as_float(u & 0xffff0000u); }
; DI int otid() { int t = threadIdx.x; asm volatile("" : "+v"(t)); return t; }
; template <bool LAST>
; DI void phase_gate(const Params& P, int layer, unsigned char* smem, int L, int G) {
;     ...
;     const int tid2 = otid();
;     const int lane2 = tid2 & 63, w2 = tid2 >> 6, r2 = lane2 & 31, h2 = lane2 >> 5, wm2 = w2 >> 2, wn2 = w2 & 3;
; #pragma unroll
;     for (int i = 0; i < 4; ++i)
; #pragma unroll
;       for (int q4 = 0; q4 < 4; ++q4) {
;         const int fl = wm2 * 128 + i * 32 + 8 * q4 + 4 * h2;
;         const int f0 = nt * 256 + fl;
;         const f32x4 gv = *(const f32x4*)(vecL + 512 + fl), bv = *(const f32x4*)(vecL + 768 + fl);
;         const float ga[4] = {gv.x, gv.y, gv.z, gv.w}, ba[4] = {bv.x, bv.y, bv.z, bv.w};
; #pragma unroll
;         for (int j = 0; j < 2; ++j) {
;           const int lrow = wn2 * 64 + j * 32 + r2;
;           const float mu = rowA[lrow], rstd = rowB[lrow];
;           uint2* sp = (uint2*)(stg + lrow * STG + fl);
;           const uint2 sv = *sp;
;           const float sa[4] = {bflo(sv.x), bfhi(sv.x), bflo(sv.y), bfhi(sv.y)};
;           float y[4];
;           const float gg[4] = {bflo(gq[i][j][2 * q4]), bfhi(gq[i][j][2 * q4]), bflo(gq[i][j][2 * q4 + 1]), bfhi(gq[i][j][2 * q4 + 1])};
; #pragma unroll
;           for (int e = 0; e < 4; ++e) y[e] = (sa[e] - mu) * rstd * ga[e] + ba[e] + gg[e];
;           if (LAST) { f32x4 o = {y[0], y[1], y[2], y[3]}; *(f32x4*)(P.out + (size_t)(mt * 256 + lrow) * 1024 + f0) = o; }
;           else { uint2 pk; pk.x = pack2(y[0], y[1]); pk.y = pack2(y[2], y[3]); *sp = pk; }
;         }
;         __builtin_amdgcn_sched_barrier(0);
;       }
	v_pk_mul_f32 v[54:55], v[44:45], v[54:55] op_sel_hi:[0,1]
	v_pk_mul_f32 v[42:43], v[44:45], v[42:43] op_sel_hi:[0,1]
	v_lshlrev_b32_e32 v58, 16, v41
	v_and_b32_e32 v59, 0xffff0000, v41
	v_pk_fma_f32 v[46:47], v[46:47], v[54:55], v[50:51]
	v_pk_fma_f32 v[42:43], v[48:49], v[42:43], v[52:53]
	v_pk_add_f32 v[46:47], v[46:47], v[58:59]
	v_pk_add_f32 v[42:43], v[42:43], v[60:61]
	v_cvt_pk_bf16_f32 v44, v46, v47
	v_cvt_pk_bf16_f32 v45, v42, v43
	ds_write_b64 v19, v[44:45] offset:16752
	v_add_u32_e32 v46, 0x25500, v27
	v_add_u32_e32 v41, 0x25100, v27
	ds_read_b64 v[50:51], v19 offset:128
	ds_read_b128 v[42:45], v41
	ds_read_b128 v[46:49], v46
	ds_read_b32 v52, v29
	ds_read_b32 v54, v30
	ds_read_b64 v[56:57], v19 offset:16768
	s_waitcnt lgkmcnt(5)
	v_lshlrev_b32_e32 v58, 16, v50
	v_and_b32_e32 v59, 0xffff0000, v50
	v_lshlrev_b32_e32 v50, 16, v51
	v_and_b32_e32 v51, 0xffff0000, v51
	v_lshlrev_b32_e32 v62, 16, v40
	v_and_b32_e32 v63, 0xffff0000, v40
	s_waitcnt lgkmcnt(2)
	v_pk_add_f32 v[40:41], v[58:59], v[52:53] op_sel_hi:[1,0] neg_lo:[0,1] neg_hi:[0,1]
	v_pk_add_f32 v[50:51], v[50:51], v[52:53] op_sel_hi:[1,0] neg_lo:[0,1] neg_hi:[0,1]
	s_waitcnt lgkmcnt(1)
	v_pk_mul_f32 v[40:41], v[54:55], v[40:41] op_sel_hi:[0,1]
	v_pk_mul_f32 v[50:51], v[54:55], v[50:51] op_sel_hi:[0,1]
	v_lshlrev_b32_e32 v60, 16, v38
	v_and_b32_e32 v61, 0xffff0000, v38
	v_pk_fma_f32 v[40:41], v[42:43], v[40:41], v[46:47]
	v_pk_fma_f32 v[50:51], v[44:45], v[50:51], v[48:49]
	v_pk_add_f32 v[40:41], v[40:41], v[60:61]
	v_pk_add_f32 v[50:51], v[50:51], v[62:63]
	v_cvt_pk_bf16_f32 v40, v40, v41
	v_cvt_pk_bf16_f32 v41, v50, v51
	ds_write_b64 v19, v[40:41] offset:128
	ds_read_b32 v38, v31
	ds_read_b32 v40, v33
	s_waitcnt lgkmcnt(3)
	v_lshlrev_b32_e32 v50, 16, v56
	v_and_b32_e32 v51, 0xffff0000, v56
	v_lshlrev_b32_e32 v52, 16, v57
	v_and_b32_e32 v53, 0xffff0000, v57
	v_lshlrev_b32_e32 v56, 16, v39
	v_and_b32_e32 v57, 0xffff0000, v39
	s_waitcnt lgkmcnt(1)
	v_pk_add_f32 v[50:51], v[50:51], v[38:39] op_sel_hi:[1,0] neg_lo:[0,1] neg_hi:[0,1]
	v_pk_add_f32 v[38:39], v[52:53], v[38:39] op_sel_hi:[1,0] neg_lo:[0,1] neg_hi:[0,1]
	s_waitcnt lgkmcnt(0)
	v_pk_mul_f32 v[50:51], v[40:41], v[50:51] op_sel_hi:[0,1]
	v_pk_mul_f32 v[38:39], v[40:41], v[38:39] op_sel_hi:[0,1]
	v_lshlrev_b32_e32 v54, 16, v37
	v_and_b32_e32 v55, 0xffff0000, v37
	v_pk_fma_f32 v[42:43], v[42:43], v[50:51], v[46:47]
	v_pk_fma_f32 v[38:39], v[44:45], v[38:39], v[48:49]
	v_pk_add_f32 v[42:43], v[42:43], v[54:55]
	v_pk_add_f32 v[38:39], v[38:39], v[56:57]
	v_cvt_pk_bf16_f32 v40, v42, v43
	v_cvt_pk_bf16_f32 v41, v38, v39
	ds_write_b64 v19, v[40:41] offset:16768
	v_add_u32_e32 v42, 0x25520, v27
	v_add_u32_e32 v37, 0x25120, v27
	ds_read_b64 v[46:47], v19 offset:144
	ds_read_b128 v[38:41], v37
	ds_read_b128 v[42:45], v42
	ds_read_b32 v48, v29
	ds_read_b32 v50, v30
	ds_read_b64 v[52:53], v19 offset:16784
	s_waitcnt lgkmcnt(5)
	v_lshlrev_b32_e32 v54, 16, v46
	v_and_b32_e32 v55, 0xffff0000, v46
	v_lshlrev_b32_e32 v46, 16, v47
	v_and_b32_e32 v47, 0xffff0000, v47
	v_lshlrev_b32_e32 v58, 16, v36
	v_and_b32_e32 v59, 0xffff0000, v36
	s_waitcnt lgkmcnt(2)
	v_pk_add_f32 v[36:37], v[54:55], v[48:49] op_sel_hi:[1,0] neg_lo:[0,1] neg_hi:[0,1]
	v_pk_add_f32 v[46:47], v[46:47], v[48:49] op_sel_hi:[1,0] neg_lo:[0,1] neg_hi:[0,1]
	s_waitcnt lgkmcnt(1)
	v_pk_mul_f32 v[36:37], v[50:51], v[36:37] op_sel_hi:[0,1]
	v_pk_mul_f32 v[46:47], v[50:51], v[46:47] op_sel_hi:[0,1]
	v_lshlrev_b32_e32 v56, 16, v34
	v_and_b32_e32 v57, 0xffff0000, v34
	v_pk_fma_f32 v[36:37], v[38:39], v[36:37], v[42:43]
	v_pk_fma_f32 v[46:47], v[40:41], v[46:47], v[44:45]
	v_pk_add_f32 v[36:37], v[36:37], v[56:57]
	v_pk_add_f32 v[46:47], v[46:47], v[58:59]
	v_cvt_pk_bf16_f32 v36, v36, v37
	v_cvt_pk_bf16_f32 v37, v46, v47
	ds_write_b64 v19, v[36:37] offset:144
	ds_read_b32 v34, v31
	ds_read_b32 v36, v33
	s_waitcnt lgkmcnt(3)
	v_lshlrev_b32_e32 v46, 16, v52
	v_and_b32_e32 v47, 0xffff0000, v52
	v_lshlrev_b32_e32 v48, 16, v53
	v_and_b32_e32 v49, 0xffff0000, v53
	v_lshlrev_b32_e32 v52, 16, v35
	v_and_b32_e32 v53, 0xffff0000, v35
	s_waitcnt lgkmcnt(1)
	v_pk_add_f32 v[46:47], v[46:47], v[34:35] op_sel_hi:[1,0] neg_lo:[0,1] neg_hi:[0,1]
	v_pk_add_f32 v[34:35], v[48:49], v[34:35] op_sel_hi:[1,0] neg_lo:[0,1] neg_hi:[0,1]
	s_waitcnt lgkmcnt(0)
	v_pk_mul_f32 v[46:47], v[36:37], v[46:47] op_sel_hi:[0,1]
	v_pk_mul_f32 v[34:35], v[36:37], v[34:35] op_sel_hi:[0,1]
	v_lshlrev_b32_e32 v50, 16, v32
	v_and_b32_e32 v51, 0xffff0000, v32
	v_pk_fma_f32 v[38:39], v[38:39], v[46:47], v[42:43]
	v_pk_fma_f32 v[34:35], v[40:41], v[34:35], v[44:45]
	v_pk_add_f32 v[38:39], v[38:39], v[50:51]
	v_pk_add_f32 v[34:35], v[34:35], v[52:53]
	v_cvt_pk_bf16_f32 v36, v38, v39
	v_cvt_pk_bf16_f32 v37, v34, v35
	ds_write_b64 v19, v[36:37] offset:16784
	v_add_u32_e32 v32, 0x25140, v27
	v_add_u32_e32 v38, 0x25540, v27
	ds_read_b64 v[42:43], v19 offset:160
	ds_read_b128 v[34:37], v32
	ds_read_b128 v[38:41], v38
	ds_read_b32 v32, v29
	ds_read_b32 v44, v30
	ds_read_b64 v[46:47], v19 offset:16800
	s_waitcnt lgkmcnt(5)
	v_lshlrev_b32_e32 v48, 16, v42
	v_and_b32_e32 v49, 0xffff0000, v42
	v_lshlrev_b32_e32 v42, 16, v43
	v_and_b32_e32 v43, 0xffff0000, v43
	s_waitcnt lgkmcnt(2)
	v_pk_add_f32 v[48:49], v[48:49], v[32:33] op_sel_hi:[1,0] neg_lo:[0,1] neg_hi:[0,1]
	v_pk_add_f32 v[42:43], v[42:43], v[32:33] op_sel_hi:[1,0] neg_lo:[0,1] neg_hi:[0,1]
	s_waitcnt lgkmcnt(1)
; DI unsigned pack2(float a, float b) { f32x2_t v = {a, b}; bf16x2_t r = __builtin_convertvector(v, bf16x2_t); return __builtin_bit_cast(unsigned, r); }
; DI float bflo(unsigned u) { return __uint_as_float(u << 16); }
; DI float bfhi(unsigned u) { return __uint_as_float(u & 0xffff0000u); }
; DI int otid() { int t = threadIdx.x; asm volatile("" : "+v"(t)); return t; }
; template <bool LAST>
; DI void phase_gate(const Params& P, int layer, unsigned char* smem, int L, int G) {
;     ...
;     const int tid2 = otid();
;     const int lane2 = tid2 & 63, w2 = tid2 >> 6, r2 = lane2 & 31, h2 = lane2 >> 5, wm2 = w2 >> 2, wn2 = w2 & 3;
; #pragma unroll
;     for (int i = 0; i < 4; ++i)
; #pragma unroll
;       for (int q4 = 0; q4 < 4; ++q4) {
;         const int fl = wm2 * 128 + i * 32 + 8 * q4 + 4 * h2;
;         const int f0 = nt * 256 + fl;
;         const f32x4 gv = *(const f32x4*)(vecL + 512 + fl), bv = *(const f32x4*)(vecL + 768 + fl);
;         const float ga[4] = {gv.x, gv.y, gv.z, gv.w}, ba[4] = {bv.x, bv.y, bv.z, bv.w};
; #pragma unroll
;         for (int j = 0; j < 2; ++j) {
;           const int lrow = wn2 * 64 + j * 32 + r2;
;           const float mu = rowA[lrow], rstd = rowB[lrow];
;           uint2* sp = (uint2*)(stg + lrow * STG + fl);
;           const uint2 sv = *sp;
;           const float sa[4] = {bflo(sv.x), bfhi(sv.x), bflo(sv.y), bfhi(sv.y)};
;           float y[4];
;           const float gg[4] = {bflo(gq[i][j][2 * q4]), bfhi(gq[i][j][2 * q4]), bflo(gq[i][j][2 * q4 + 1]), bfhi(gq[i][j][2 * q4 + 1])};
; #pragma unroll
;           for (int e = 0; e < 4; ++e) y[e] = (sa[e] - mu) * rstd * ga[e] + ba[e] + gg[e];
;           if (LAST) { f32x4 o = {y[0], y[1], y[2], y[3]}; *(f32x4*)(P.out + (size_t)(mt * 256 + lrow) * 1024 + f0) = o; }
;           else { uint2 pk; pk.x = pack2(y[0], y[1]); pk.y = pack2(y[2], y[3]); *sp = pk; }
;         }
;         __builtin_amdgcn_sched_barrier(0);
;       }
	v_pk_mul_f32 v[48:49], v[44:45], v[48:49] op_sel_hi:[0,1]
	v_pk_mul_f32 v[42:43], v[44:45], v[42:43] op_sel_hi:[0,1]
	v_lshlrev_b32_e32 v50, 16, v24
	v_and_b32_e32 v51, 0xffff0000, v24
	v_lshlrev_b32_e32 v52, 16, v26
	v_and_b32_e32 v53, 0xffff0000, v26
	v_pk_fma_f32 v[48:49], v[34:35], v[48:49], v[38:39]
	v_pk_fma_f32 v[42:43], v[36:37], v[42:43], v[40:41]
	v_pk_add_f32 v[48:49], v[48:49], v[50:51]
	v_pk_add_f32 v[42:43], v[42:43], v[52:53]
	v_cvt_pk_bf16_f32 v44, v48, v49
	v_cvt_pk_bf16_f32 v45, v42, v43
	ds_write_b64 v19, v[44:45] offset:160
	ds_read_b32 v24, v31
	ds_read_b32 v26, v33
	s_waitcnt lgkmcnt(3)
	v_lshlrev_b32_e32 v42, 16, v46
	v_and_b32_e32 v43, 0xffff0000, v46
	v_lshlrev_b32_e32 v44, 16, v47
	v_and_b32_e32 v45, 0xffff0000, v47
	v_lshlrev_b32_e32 v48, 16, v25
	v_and_b32_e32 v49, 0xffff0000, v25
	s_waitcnt lgkmcnt(1)
	v_pk_add_f32 v[42:43], v[42:43], v[24:25] op_sel_hi:[1,0] neg_lo:[0,1] neg_hi:[0,1]
	v_pk_add_f32 v[24:25], v[44:45], v[24:25] op_sel_hi:[1,0] neg_lo:[0,1] neg_hi:[0,1]
	s_waitcnt lgkmcnt(0)
	v_pk_mul_f32 v[42:43], v[26:27], v[42:43] op_sel_hi:[0,1]
	v_pk_mul_f32 v[24:25], v[26:27], v[24:25] op_sel_hi:[0,1]
	v_lshlrev_b32_e32 v46, 16, v23
	v_and_b32_e32 v47, 0xffff0000, v23
	v_pk_fma_f32 v[34:35], v[34:35], v[42:43], v[38:39]
	v_pk_fma_f32 v[24:25], v[36:37], v[24:25], v[40:41]
	v_pk_add_f32 v[34:35], v[34:35], v[46:47]
	v_pk_add_f32 v[24:25], v[24:25], v[48:49]
	v_cvt_pk_bf16_f32 v34, v34, v35
	v_cvt_pk_bf16_f32 v35, v24, v25
	ds_write_b64 v19, v[34:35] offset:16800
	v_add_u32_e32 v26, 0x25560, v27
	v_add_u32_e32 v23, 0x25160, v27
	ds_read_b64 v[24:25], v19 offset:176
	ds_read_b128 v[34:37], v23
	ds_read_b128 v[38:41], v26
	ds_read_b32 v26, v29
	ds_read_b32 v32, v30
	ds_read_b64 v[42:43], v19 offset:16816
	s_waitcnt lgkmcnt(5)
	v_lshlrev_b32_e32 v44, 16, v24
	v_and_b32_e32 v45, 0xffff0000, v24
	v_lshlrev_b32_e32 v24, 16, v25
	v_and_b32_e32 v25, 0xffff0000, v25
	v_lshlrev_b32_e32 v48, 16, v22
	v_and_b32_e32 v49, 0xffff0000, v22
	s_waitcnt lgkmcnt(2)
	v_pk_add_f32 v[22:23], v[44:45], v[26:27] op_sel_hi:[1,0] neg_lo:[0,1] neg_hi:[0,1]
	v_pk_add_f32 v[24:25], v[24:25], v[26:27] op_sel_hi:[1,0] neg_lo:[0,1] neg_hi:[0,1]
	s_waitcnt lgkmcnt(1)
	v_pk_mul_f32 v[22:23], v[32:33], v[22:23] op_sel_hi:[0,1]
	v_pk_mul_f32 v[24:25], v[32:33], v[24:25] op_sel_hi:[0,1]
	v_lshlrev_b32_e32 v46, 16, v20
	v_and_b32_e32 v47, 0xffff0000, v20
	v_pk_fma_f32 v[22:23], v[34:35], v[22:23], v[38:39]
	v_pk_fma_f32 v[24:25], v[36:37], v[24:25], v[40:41]
	v_pk_add_f32 v[22:23], v[22:23], v[46:47]
	v_pk_add_f32 v[24:25], v[24:25], v[48:49]
	v_cvt_pk_bf16_f32 v22, v22, v23
	v_cvt_pk_bf16_f32 v23, v24, v25
	ds_write_b64 v19, v[22:23] offset:176
	ds_read_b32 v20, v31
	ds_read_b32 v22, v33
	s_waitcnt lgkmcnt(3)
	v_lshlrev_b32_e32 v24, 16, v42
	v_and_b32_e32 v25, 0xffff0000, v42
	v_lshlrev_b32_e32 v42, 16, v43
	v_and_b32_e32 v43, 0xffff0000, v43
	v_lshlrev_b32_e32 v46, 16, v21
	v_and_b32_e32 v47, 0xffff0000, v21
	s_waitcnt lgkmcnt(1)
	v_pk_add_f32 v[24:25], v[24:25], v[20:21] op_sel_hi:[1,0] neg_lo:[0,1] neg_hi:[0,1]
	v_pk_add_f32 v[20:21], v[42:43], v[20:21] op_sel_hi:[1,0] neg_lo:[0,1] neg_hi:[0,1]
	s_waitcnt lgkmcnt(0)
	v_pk_mul_f32 v[24:25], v[22:23], v[24:25] op_sel_hi:[0,1]
	v_pk_mul_f32 v[20:21], v[22:23], v[20:21] op_sel_hi:[0,1]
	v_lshlrev_b32_e32 v44, 16, v18
	v_and_b32_e32 v45, 0xffff0000, v18
	v_pk_fma_f32 v[24:25], v[34:35], v[24:25], v[38:39]
	v_pk_fma_f32 v[20:21], v[36:37], v[20:21], v[40:41]
	v_pk_add_f32 v[24:25], v[24:25], v[44:45]
	v_pk_add_f32 v[20:21], v[20:21], v[46:47]
	v_cvt_pk_bf16_f32 v22, v24, v25
	v_cvt_pk_bf16_f32 v23, v20, v21
	ds_write_b64 v19, v[22:23] offset:16816
	v_add_u32_e32 v18, 0x25180, v27
	v_add_u32_e32 v26, 0x25580, v27
	ds_read_b64 v[24:25], v19 offset:192
	ds_read_b128 v[20:23], v18
	ds_read_b128 v[34:37], v26
	ds_read_b32 v18, v29
	ds_read_b32 v26, v30
	ds_read_b64 v[38:39], v19 offset:16832
	s_waitcnt lgkmcnt(5)
	v_lshlrev_b32_e32 v40, 16, v24
	v_and_b32_e32 v41, 0xffff0000, v24
	v_lshlrev_b32_e32 v24, 16, v25
	v_and_b32_e32 v25, 0xffff0000, v25
	s_waitcnt lgkmcnt(2)
	v_pk_add_f32 v[40:41], v[40:41], v[18:19] op_sel_hi:[1,0] neg_lo:[0,1] neg_hi:[0,1]
	v_pk_add_f32 v[24:25], v[24:25], v[18:19] op_sel_hi:[1,0] neg_lo:[0,1] neg_hi:[0,1]
	s_waitcnt lgkmcnt(1)
	v_pk_mul_f32 v[40:41], v[26:27], v[40:41] op_sel_hi:[0,1]
	v_pk_mul_f32 v[24:25], v[26:27], v[24:25] op_sel_hi:[0,1]
	v_lshlrev_b32_e32 v42, 16, v15
	v_and_b32_e32 v43, 0xffff0000, v15
	v_lshlrev_b32_e32 v44, 16, v17
	v_and_b32_e32 v45, 0xffff0000, v17
	v_pk_fma_f32 v[40:41], v[20:21], v[40:41], v[34:35]
	v_pk_fma_f32 v[24:25], v[22:23], v[24:25], v[36:37]
	v_pk_add_f32 v[40:41], v[40:41], v[42:43]
	v_pk_add_f32 v[24:25], v[24:25], v[44:45]
	v_cvt_pk_bf16_f32 v40, v40, v41
	v_cvt_pk_bf16_f32 v41, v24, v25
	ds_write_b64 v19, v[40:41] offset:192
	ds_read_b32 v18, v31
	ds_read_b32 v24, v33
	s_waitcnt lgkmcnt(3)
	v_lshlrev_b32_e32 v40, 16, v38
	v_and_b32_e32 v41, 0xffff0000, v38
	v_lshlrev_b32_e32 v42, 16, v14
	v_and_b32_e32 v43, 0xffff0000, v14
	v_lshlrev_b32_e32 v14, 16, v16
	v_and_b32_e32 v15, 0xffff0000, v16
	s_waitcnt lgkmcnt(1)
	v_pk_add_f32 v[16:17], v[40:41], v[18:19] op_sel_hi:[1,0] neg_lo:[0,1] neg_hi:[0,1]
	v_lshlrev_b32_e32 v38, 16, v39
	v_and_b32_e32 v39, 0xffff0000, v39
	s_waitcnt lgkmcnt(0)
; DI unsigned pack2(float a, float b) { f32x2_t v = {a, b}; bf16x2_t r = __builtin_convertvector(v, bf16x2_t); return __builtin_bit_cast(unsigned, r); }
; DI float bflo(unsigned u) { return __uint_as_float(u << 16); }
; DI float bfhi(unsigned u) { return __uint_as_float(u & 0xffff0000u); }
; DI int otid() { int t = threadIdx.x; asm volatile("" : "+v"(t)); return t; }
; template <bool LAST>
; DI void phase_gate(const Params& P, int layer, unsigned char* smem, int L, int G) {
;     ...
;     const int tid2 = otid();
;     const int lane2 = tid2 & 63, w2 = tid2 >> 6, r2 = lane2 & 31, h2 = lane2 >> 5, wm2 = w2 >> 2, wn2 = w2 & 3;
; #pragma unroll
;     for (int i = 0; i < 4; ++i)
; #pragma unroll
;       for (int q4 = 0; q4 < 4; ++q4) {
;         const int fl = wm2 * 128 + i * 32 + 8 * q4 + 4 * h2;
;         const int f0 = nt * 256 + fl;
;         const f32x4 gv = *(const f32x4*)(vecL + 512 + fl), bv = *(const f32x4*)(vecL + 768 + fl);
;         const float ga[4] = {gv.x, gv.y, gv.z, gv.w}, ba[4] = {bv.x, bv.y, bv.z, bv.w};
; #pragma unroll
;         for (int j = 0; j < 2; ++j) {
;           const int lrow = wn2 * 64 + j * 32 + r2;
;           const float mu = rowA[lrow], rstd = rowB[lrow];
;           uint2* sp = (uint2*)(stg + lrow * STG + fl);
;           const uint2 sv = *sp;
;           const float sa[4] = {bflo(sv.x), bfhi(sv.x), bflo(sv.y), bfhi(sv.y)};
;           float y[4];
;           const float gg[4] = {bflo(gq[i][j][2 * q4]), bfhi(gq[i][j][2 * q4]), bflo(gq[i][j][2 * q4 + 1]), bfhi(gq[i][j][2 * q4 + 1])};
; #pragma unroll
;           for (int e = 0; e < 4; ++e) y[e] = (sa[e] - mu) * rstd * ga[e] + ba[e] + gg[e];
;           if (LAST) { f32x4 o = {y[0], y[1], y[2], y[3]}; *(f32x4*)(P.out + (size_t)(mt * 256 + lrow) * 1024 + f0) = o; }
;           else { uint2 pk; pk.x = pack2(y[0], y[1]); pk.y = pack2(y[2], y[3]); *sp = pk; }
;         }
;         __builtin_amdgcn_sched_barrier(0);
;       }
;     __syncthreads();
;     if (!LAST) stage_store_tile(stg, xb + (size_t)mt * 256 * 1024 + nt * 256);
;     __syncthreads();
	v_pk_mul_f32 v[16:17], v[24:25], v[16:17] op_sel_hi:[0,1]
	v_pk_fma_f32 v[16:17], v[20:21], v[16:17], v[34:35]
	v_pk_add_f32 v[20:21], v[38:39], v[18:19] op_sel_hi:[1,0] neg_lo:[0,1] neg_hi:[0,1]
	v_pk_add_f32 v[16:17], v[16:17], v[42:43]
	v_pk_mul_f32 v[20:21], v[24:25], v[20:21] op_sel_hi:[0,1]
	v_pk_fma_f32 v[20:21], v[22:23], v[20:21], v[36:37]
	v_cvt_pk_bf16_f32 v16, v16, v17
	v_pk_add_f32 v[14:15], v[20:21], v[14:15]
	s_nop 0
	v_cvt_pk_bf16_f32 v17, v14, v15
	ds_write_b64 v19, v[16:17] offset:16832
	v_add_u32_e32 v14, 0x251a0, v27
	v_add_u32_e32 v18, 0x255a0, v27
	ds_read_b64 v[24:25], v19 offset:208
	ds_read_b128 v[14:17], v14
	ds_read_b128 v[20:23], v18
	ds_read_b32 v18, v29
	ds_read_b32 v26, v30
	ds_read_b64 v[34:35], v19 offset:16848
	s_waitcnt lgkmcnt(5)
	v_lshlrev_b32_e32 v36, 16, v24
	v_and_b32_e32 v37, 0xffff0000, v24
	v_lshlrev_b32_e32 v24, 16, v25
	v_and_b32_e32 v25, 0xffff0000, v25
	s_waitcnt lgkmcnt(2)
	v_pk_add_f32 v[36:37], v[36:37], v[18:19] op_sel_hi:[1,0] neg_lo:[0,1] neg_hi:[0,1]
	v_pk_add_f32 v[24:25], v[24:25], v[18:19] op_sel_hi:[1,0] neg_lo:[0,1] neg_hi:[0,1]
	s_waitcnt lgkmcnt(1)
	v_pk_mul_f32 v[36:37], v[26:27], v[36:37] op_sel_hi:[0,1]
	v_pk_mul_f32 v[24:25], v[26:27], v[24:25] op_sel_hi:[0,1]
	v_lshlrev_b32_e32 v38, 16, v11
	v_and_b32_e32 v39, 0xffff0000, v11
	v_lshlrev_b32_e32 v40, 16, v13
	v_and_b32_e32 v41, 0xffff0000, v13
	v_pk_fma_f32 v[36:37], v[14:15], v[36:37], v[20:21]
	v_pk_fma_f32 v[24:25], v[16:17], v[24:25], v[22:23]
	v_pk_add_f32 v[36:37], v[36:37], v[38:39]
	v_pk_add_f32 v[24:25], v[24:25], v[40:41]
	v_cvt_pk_bf16_f32 v36, v36, v37
	v_cvt_pk_bf16_f32 v37, v24, v25
	ds_write_b64 v19, v[36:37] offset:208
	ds_read_b32 v18, v31
	ds_read_b32 v24, v33
	s_waitcnt lgkmcnt(3)
	v_lshlrev_b32_e32 v36, 16, v34
	v_and_b32_e32 v37, 0xffff0000, v34
	v_lshlrev_b32_e32 v38, 16, v10
	v_and_b32_e32 v39, 0xffff0000, v10
	v_lshlrev_b32_e32 v10, 16, v12
	v_and_b32_e32 v11, 0xffff0000, v12
	s_waitcnt lgkmcnt(1)
	v_pk_add_f32 v[12:13], v[36:37], v[18:19] op_sel_hi:[1,0] neg_lo:[0,1] neg_hi:[0,1]
	v_lshlrev_b32_e32 v34, 16, v35
	v_and_b32_e32 v35, 0xffff0000, v35
	s_waitcnt lgkmcnt(0)
	v_pk_mul_f32 v[12:13], v[24:25], v[12:13] op_sel_hi:[0,1]
	v_pk_fma_f32 v[12:13], v[14:15], v[12:13], v[20:21]
	v_pk_add_f32 v[14:15], v[34:35], v[18:19] op_sel_hi:[1,0] neg_lo:[0,1] neg_hi:[0,1]
	v_pk_add_f32 v[12:13], v[12:13], v[38:39]
	v_pk_mul_f32 v[14:15], v[24:25], v[14:15] op_sel_hi:[0,1]
	v_pk_fma_f32 v[14:15], v[16:17], v[14:15], v[22:23]
	v_cvt_pk_bf16_f32 v12, v12, v13
	v_pk_add_f32 v[10:11], v[14:15], v[10:11]
	s_nop 0
	v_cvt_pk_bf16_f32 v13, v10, v11
	ds_write_b64 v19, v[12:13] offset:16848
	v_add_u32_e32 v10, 0x251c0, v27
	v_add_u32_e32 v14, 0x255c0, v27
	ds_read_b64 v[20:21], v19 offset:224
	ds_read_b128 v[10:13], v10
	ds_read_b128 v[14:17], v14
	ds_read_b32 v18, v29
	ds_read_b32 v22, v30
	ds_read_b64 v[24:25], v19 offset:16864
	s_waitcnt lgkmcnt(5)
	v_lshlrev_b32_e32 v34, 16, v20
	v_and_b32_e32 v35, 0xffff0000, v20
	v_lshlrev_b32_e32 v20, 16, v21
	v_and_b32_e32 v21, 0xffff0000, v21
	s_waitcnt lgkmcnt(2)
	v_pk_add_f32 v[34:35], v[34:35], v[18:19] op_sel_hi:[1,0] neg_lo:[0,1] neg_hi:[0,1]
	v_pk_add_f32 v[20:21], v[20:21], v[18:19] op_sel_hi:[1,0] neg_lo:[0,1] neg_hi:[0,1]
	s_waitcnt lgkmcnt(1)
	v_pk_mul_f32 v[34:35], v[22:23], v[34:35] op_sel_hi:[0,1]
	v_pk_mul_f32 v[20:21], v[22:23], v[20:21] op_sel_hi:[0,1]
	v_lshlrev_b32_e32 v36, 16, v7
	v_and_b32_e32 v37, 0xffff0000, v7
	v_lshlrev_b32_e32 v38, 16, v9
	v_and_b32_e32 v39, 0xffff0000, v9
	v_pk_fma_f32 v[34:35], v[10:11], v[34:35], v[14:15]
	v_pk_fma_f32 v[20:21], v[12:13], v[20:21], v[16:17]
	v_pk_add_f32 v[34:35], v[34:35], v[36:37]
	v_pk_add_f32 v[20:21], v[20:21], v[38:39]
	v_cvt_pk_bf16_f32 v22, v34, v35
	v_cvt_pk_bf16_f32 v23, v20, v21
	ds_write_b64 v19, v[22:23] offset:224
	ds_read_b32 v18, v31
	ds_read_b32 v20, v33
	s_waitcnt lgkmcnt(3)
	v_lshlrev_b32_e32 v22, 16, v24
	v_and_b32_e32 v23, 0xffff0000, v24
	v_lshlrev_b32_e32 v34, 16, v6
	v_and_b32_e32 v35, 0xffff0000, v6
	v_lshlrev_b32_e32 v6, 16, v8
	v_and_b32_e32 v7, 0xffff0000, v8
	s_waitcnt lgkmcnt(1)
	v_pk_add_f32 v[8:9], v[22:23], v[18:19] op_sel_hi:[1,0] neg_lo:[0,1] neg_hi:[0,1]
	v_lshlrev_b32_e32 v24, 16, v25
	v_and_b32_e32 v25, 0xffff0000, v25
	s_waitcnt lgkmcnt(0)
	v_pk_mul_f32 v[8:9], v[20:21], v[8:9] op_sel_hi:[0,1]
	v_pk_fma_f32 v[8:9], v[10:11], v[8:9], v[14:15]
	v_pk_add_f32 v[10:11], v[24:25], v[18:19] op_sel_hi:[1,0] neg_lo:[0,1] neg_hi:[0,1]
	v_pk_add_f32 v[8:9], v[8:9], v[34:35]
	v_pk_mul_f32 v[10:11], v[20:21], v[10:11] op_sel_hi:[0,1]
	v_pk_fma_f32 v[10:11], v[12:13], v[10:11], v[16:17]
	v_cvt_pk_bf16_f32 v8, v8, v9
	v_pk_add_f32 v[6:7], v[10:11], v[6:7]
	s_nop 0
	v_cvt_pk_bf16_f32 v9, v6, v7
	ds_write_b64 v19, v[8:9] offset:16864
	ds_read_b128 v[6:9], v28 offset:480
	ds_read_b64 v[14:15], v19 offset:240
	ds_read_b32 v16, v29
	ds_read_b32 v18, v30
	v_add_u32_e32 v10, 0x255e0, v27
	ds_read_b128 v[10:13], v10
	s_waitcnt lgkmcnt(3)
	v_lshlrev_b32_e32 v20, 16, v14
	v_and_b32_e32 v21, 0xffff0000, v14
	v_lshlrev_b32_e32 v14, 16, v15
	v_and_b32_e32 v15, 0xffff0000, v15
	s_waitcnt lgkmcnt(2)
	v_pk_add_f32 v[20:21], v[20:21], v[16:17] op_sel_hi:[1,0] neg_lo:[0,1] neg_hi:[0,1]
	v_pk_add_f32 v[14:15], v[14:15], v[16:17] op_sel_hi:[1,0] neg_lo:[0,1] neg_hi:[0,1]
	s_waitcnt lgkmcnt(1)
	v_pk_mul_f32 v[20:21], v[18:19], v[20:21] op_sel_hi:[0,1]
	v_pk_mul_f32 v[14:15], v[18:19], v[14:15] op_sel_hi:[0,1]
	v_lshlrev_b32_e32 v22, 16, v4
	v_and_b32_e32 v23, 0xffff0000, v4
	v_lshlrev_b32_e32 v4, 16, v5
	v_and_b32_e32 v5, 0xffff0000, v5
	s_waitcnt lgkmcnt(0)
	v_pk_fma_f32 v[20:21], v[6:7], v[20:21], v[10:11]
	v_pk_fma_f32 v[14:15], v[8:9], v[14:15], v[12:13]
	v_pk_add_f32 v[20:21], v[20:21], v[22:23]
	v_pk_add_f32 v[4:5], v[14:15], v[4:5]
	v_cvt_pk_bf16_f32 v14, v20, v21
	v_cvt_pk_bf16_f32 v15, v4, v5
	ds_write_b64 v19, v[14:15] offset:240
	ds_read_b32 v4, v33
	ds_read_b64 v[14:15], v19 offset:16880
	ds_read_b32 v16, v31
	v_lshlrev_b32_e32 v22, 16, v2
	v_and_b32_e32 v23, 0xffff0000, v2
	v_lshlrev_b32_e32 v2, 16, v3
	s_waitcnt lgkmcnt(1)
	v_lshlrev_b32_e32 v20, 16, v14
	v_and_b32_e32 v21, 0xffff0000, v14
	s_waitcnt lgkmcnt(0)
	v_pk_add_f32 v[20:21], v[20:21], v[16:17] op_sel_hi:[1,0] neg_lo:[0,1] neg_hi:[0,1]
	v_lshlrev_b32_e32 v14, 16, v15
	v_and_b32_e32 v15, 0xffff0000, v15
	v_pk_mul_f32 v[20:21], v[4:5], v[20:21] op_sel_hi:[0,1]
	v_pk_fma_f32 v[6:7], v[6:7], v[20:21], v[10:11]
	v_pk_add_f32 v[10:11], v[14:15], v[16:17] op_sel_hi:[1,0] neg_lo:[0,1] neg_hi:[0,1]
	v_and_b32_e32 v3, 0xffff0000, v3
	v_pk_mul_f32 v[4:5], v[4:5], v[10:11] op_sel_hi:[0,1]
	v_pk_fma_f32 v[4:5], v[8:9], v[4:5], v[12:13]
	v_pk_add_f32 v[6:7], v[6:7], v[22:23]
	v_pk_add_f32 v[2:3], v[4:5], v[2:3]
	v_cvt_pk_bf16_f32 v4, v6, v7
	v_cvt_pk_bf16_f32 v5, v2, v3
	ds_write_b64 v19, v[4:5] offset:16880
	s_add_u32 s24, s80, s24
	s_addc_u32 s25, s81, s25
	v_lshl_add_u64 v[8:9], s[24:25], 0, v[0:1]
	v_mov_b32_e32 v0, v192
	s_waitcnt lgkmcnt(0)
	s_barrier
; DI int otid() { int t = threadIdx.x; asm volatile("" : "+v"(t)); return t; }
; DI void stg16_nt(void* p, u32x4 v) { __builtin_nontemporal_store(v, (u32x4*)p); }
; DI void stage_store_tile(const bf16_t* stg, bf16_t* tilebase) {
;   const int tid = otid();
;   const int r0 = tid >> 5, c = tid & 31;
;   const unsigned o0 = (unsigned)(r0 * 1024 + c * 8);
; #pragma unroll
;   for (int it = 0; it < 16; ++it) stg16_nt(tilebase + (o0 + (unsigned)(it * 16 * 1024)), stage_read16(stg, r0 + 16 * it, c));
; }
; template <bool LAST>
; DI void phase_gate(const Params& P, int layer, unsigned char* smem, int L, int G) {
;     ...
;     if (!LAST) stage_store_tile(stg, xb + (size_t)mt * 256 * 1024 + nt * 256);
;     __syncthreads();
;   }
	s_add_i32 s36, s36, s74
	v_ashrrev_i32_e32 v4, 5, v0
	v_and_b32_e32 v0, 31, v0
	v_mul_lo_u32 v1, v4, s44
	v_lshl_add_u32 v12, v0, 4, v1
	v_lshlrev_b32_e32 v5, 3, v0
	ds_read2_b64 v[0:3], v12 offset1:1
	v_lshl_or_b32 v160, v4, 10, v5
	v_add_u32_e32 v4, 0x2080, v12
	ds_read2_b64 v[4:7], v4 offset1:1
	v_lshl_add_u64 v[10:11], v[160:161], 1, v[8:9]
	s_waitcnt lgkmcnt(1)
	global_store_dwordx4 v[10:11], v[0:3], off nt
	s_add_i32 s33, s33, s69
	s_add_i32 s34, s34, s35
	v_add_u32_e32 v0, 0x4000, v160
	v_mov_b32_e32 v1, v161
	v_lshl_add_u64 v[0:1], v[0:1], 1, v[8:9]
	s_waitcnt lgkmcnt(0)
	global_store_dwordx4 v[0:1], v[4:7], off nt
	v_add_u32_e32 v0, 0x4100, v12
	ds_read2_b64 v[0:3], v0 offset1:1
	v_add_u32_e32 v4, 0x8000, v160
	v_mov_b32_e32 v5, v161
	v_lshl_add_u64 v[10:11], v[4:5], 1, v[8:9]
	v_add_u32_e32 v4, 0x6180, v12
	ds_read2_b64 v[4:7], v4 offset1:1
	s_waitcnt lgkmcnt(1)
	global_store_dwordx4 v[10:11], v[0:3], off nt
	s_add_i32 s24, s70, s36
	s_cmpk_lt_i32 s24, 0x400
	v_add_u32_e32 v0, 0xc000, v160
	v_mov_b32_e32 v1, v161
	v_lshl_add_u64 v[0:1], v[0:1], 1, v[8:9]
	s_waitcnt lgkmcnt(0)
	global_store_dwordx4 v[0:1], v[4:7], off nt
	v_add_u32_e32 v0, 0x8200, v12
	ds_read2_b64 v[0:3], v0 offset1:1
	v_add_u32_e32 v4, 0x10000, v160
	v_mov_b32_e32 v5, v161
	v_lshl_add_u64 v[10:11], v[4:5], 1, v[8:9]
	v_add_u32_e32 v4, 0xa280, v12
	ds_read2_b64 v[4:7], v4 offset1:1
	s_waitcnt lgkmcnt(1)
	global_store_dwordx4 v[10:11], v[0:3], off nt
	s_nop 1
	v_add_u32_e32 v0, 0x14000, v160
	v_mov_b32_e32 v1, v161
	v_lshl_add_u64 v[0:1], v[0:1], 1, v[8:9]
	s_waitcnt lgkmcnt(0)
	global_store_dwordx4 v[0:1], v[4:7], off nt
	v_add_u32_e32 v0, 0xc300, v12
	ds_read2_b64 v[0:3], v0 offset1:1
	v_add_u32_e32 v4, 0x18000, v160
	v_mov_b32_e32 v5, v161
	v_lshl_add_u64 v[10:11], v[4:5], 1, v[8:9]
	v_add_u32_e32 v4, 0xe380, v12
	ds_read2_b64 v[4:7], v4 offset1:1
	s_waitcnt lgkmcnt(1)
	global_store_dwordx4 v[10:11], v[0:3], off nt
	s_nop 1
	v_add_u32_e32 v0, 0x1c000, v160
	v_mov_b32_e32 v1, v161
	v_lshl_add_u64 v[0:1], v[0:1], 1, v[8:9]
	s_waitcnt lgkmcnt(0)
	global_store_dwordx4 v[0:1], v[4:7], off nt
	v_add_u32_e32 v0, 0x10400, v12
	ds_read2_b64 v[0:3], v0 offset1:1
	v_add_u32_e32 v4, 0x20000, v160
	v_mov_b32_e32 v5, v161
	v_lshl_add_u64 v[10:11], v[4:5], 1, v[8:9]
	v_add_u32_e32 v4, 0x12480, v12
	ds_read2_b64 v[4:7], v4 offset1:1
	s_waitcnt lgkmcnt(1)
	global_store_dwordx4 v[10:11], v[0:3], off nt
	s_nop 1
	v_add_u32_e32 v0, 0x24000, v160
	v_mov_b32_e32 v1, v161
	v_lshl_add_u64 v[0:1], v[0:1], 1, v[8:9]
	s_waitcnt lgkmcnt(0)
	global_store_dwordx4 v[0:1], v[4:7], off nt
	v_add_u32_e32 v0, 0x14500, v12
	ds_read2_b64 v[0:3], v0 offset1:1
	v_add_u32_e32 v4, 0x28000, v160
	v_mov_b32_e32 v5, v161
	v_lshl_add_u64 v[10:11], v[4:5], 1, v[8:9]
	v_add_u32_e32 v4, 0x16580, v12
	ds_read2_b64 v[4:7], v4 offset1:1
	s_waitcnt lgkmcnt(1)
	global_store_dwordx4 v[10:11], v[0:3], off nt
	s_nop 1
	v_add_u32_e32 v0, 0x2c000, v160
	v_mov_b32_e32 v1, v161
	v_lshl_add_u64 v[0:1], v[0:1], 1, v[8:9]
	s_waitcnt lgkmcnt(0)
	global_store_dwordx4 v[0:1], v[4:7], off nt
	v_add_u32_e32 v0, 0x18600, v12
	ds_read2_b64 v[0:3], v0 offset1:1
	v_add_u32_e32 v4, 0x30000, v160
	v_mov_b32_e32 v5, v161
	v_lshl_add_u64 v[10:11], v[4:5], 1, v[8:9]
	v_add_u32_e32 v4, 0x1a680, v12
	ds_read2_b64 v[4:7], v4 offset1:1
	s_waitcnt lgkmcnt(1)
	global_store_dwordx4 v[10:11], v[0:3], off nt
	v_add_u32_e32 v10, 0x38000, v160
	v_mov_b32_e32 v11, v161
	v_add_u32_e32 v0, 0x34000, v160
	v_mov_b32_e32 v1, v161
	v_lshl_add_u64 v[0:1], v[0:1], 1, v[8:9]
	s_waitcnt lgkmcnt(0)
	global_store_dwordx4 v[0:1], v[4:7], off nt
	v_add_u32_e32 v0, 0x1c700, v12
	ds_read2_b64 v[0:3], v0 offset1:1
	v_add_u32_e32 v4, 0x1e780, v12
	ds_read2_b64 v[4:7], v4 offset1:1
	v_lshl_add_u64 v[10:11], v[10:11], 1, v[8:9]
	v_add_u32_e32 v160, 0x3c000, v160
	s_waitcnt lgkmcnt(1)
	global_store_dwordx4 v[10:11], v[0:3], off nt
	s_nop 1
	v_lshl_add_u64 v[0:1], v[160:161], 1, v[8:9]
	s_waitcnt lgkmcnt(0)
	global_store_dwordx4 v[0:1], v[4:7], off nt
	s_barrier
	s_cbranch_scc0 .LBB0_488

; DI int otid() { int t = threadIdx.x; asm volatile("" : "+v"(t)); return t; }
; template <bool NT>
; DI void stage_load_tile(bf16_t* stg, const bf16_t* tilebase) {
;   const int tid = otid();
;   const int r0 = tid >> 5, c = tid & 31;
;   const unsigned o0 = (unsigned)(r0 * 1024 + c * 8);
;   __builtin_amdgcn_sched_barrier(0);
; #pragma unroll
;   for (int hf = 0; hf < 2; ++hf) {
; #pragma unroll
;     for (int it = 8 * hf; it < 8 * hf + 8; ++it) {
;       const u32x4* gp = (const u32x4*)(tilebase + (o0 + (unsigned)(it * 16 * 1024)));
;       stage_write16(stg, r0 + 16 * it, c, NT ? __builtin_nontemporal_load(gp) : *gp);
;     }
;     __builtin_amdgcn_sched_barrier(0);
;   }
; }
; template <bool XF32>
; DI void phase_outproj(const Params& P, int layer, const void* xres, const bf16_t* og, unsigned char* smem, int L, int G) {
;     ...
;     stage_load_tile<true>(stg, (const bf16_t*)xres + (size_t)mt * 256 * 1024 + nt * 256);
.LBB0_850:
	v_bfe_u32 v198, v167, 5, 1
	s_ashr_i32 s15, s14, 31
	s_lshl_b64 s[34:35], s[14:15], 19
	s_add_u32 s21, s80, s34
	v_mov_b32_e32 v160, v192
	s_addc_u32 s35, s81, s35
	s_lshl_b32 s34, s20, 1
	s_add_u32 s20, s21, s34
	v_and_b32_e32 v200, 31, v160
	v_ashrrev_i32_e32 v199, 5, v160
	v_lshlrev_b32_e32 v160, 3, v200
	s_addc_u32 s21, s35, 0
	v_lshl_or_b32 v160, v199, 10, v160
	v_add_u32_e32 v164, 0x4000, v160
	v_mov_b32_e32 v165, v161
	v_add_u32_e32 v172, 0x8000, v160
	v_mov_b32_e32 v173, v161
	v_add_u32_e32 v174, 0xc000, v160
	v_mov_b32_e32 v175, v161
	v_add_u32_e32 v180, 0x10000, v160
	v_mov_b32_e32 v181, v161
	v_add_u32_e32 v182, 0x14000, v160
	v_mov_b32_e32 v183, v161
	v_add_u32_e32 v188, 0x18000, v160
	v_mov_b32_e32 v189, v161
	v_add_u32_e32 v190, 0x1c000, v160
	v_mov_b32_e32 v191, v161
	v_lshl_add_u64 v[162:163], v[160:161], 1, s[20:21]
	v_lshl_add_u64 v[168:169], v[164:165], 1, s[20:21]
	v_lshl_add_u64 v[172:173], v[172:173], 1, s[20:21]
	v_lshl_add_u64 v[176:177], v[174:175], 1, s[20:21]
	v_lshl_add_u64 v[180:181], v[180:181], 1, s[20:21]
	v_lshl_add_u64 v[184:185], v[182:183], 1, s[20:21]
	v_lshl_add_u64 v[188:189], v[188:189], 1, s[20:21]
	v_lshl_add_u64 v[194:195], v[190:191], 1, s[20:21]
	global_load_dwordx4 v[162:165], v[162:163], off nt
	s_nop 0
	global_load_dwordx4 v[168:171], v[168:169], off nt
	s_nop 0
	global_load_dwordx4 v[172:175], v[172:173], off nt
	s_nop 0
	global_load_dwordx4 v[176:179], v[176:177], off nt
	s_nop 0
	global_load_dwordx4 v[180:183], v[180:181], off nt
	s_nop 0
	global_load_dwordx4 v[184:187], v[184:185], off nt
	s_nop 0
	global_load_dwordx4 v[188:191], v[188:189], off nt
	s_nop 0
	global_load_dwordx4 v[194:197], v[194:195], off nt
	v_add_u32_e32 v222, 0x20000, v160
	v_mov_b32_e32 v223, v161
	v_add_u32_e32 v224, 0x24000, v160
	v_mov_b32_e32 v225, v161
	v_add_u32_e32 v230, 0x28000, v160
	v_mov_b32_e32 v231, v161
	v_add_u32_e32 v232, 0x2c000, v160
	v_mov_b32_e32 v233, v161
	v_add_u32_e32 v238, 0x30000, v160
	v_mov_b32_e32 v239, v161
	v_add_u32_e32 v240, 0x34000, v160
	v_mov_b32_e32 v241, v161
	v_add_u32_e32 v248, 0x38000, v160
	v_mov_b32_e32 v249, v161
	v_add_u32_e32 v160, 0x3c000, v160
	v_lshl_add_u64 v[222:223], v[222:223], 1, s[20:21]
	v_lshl_add_u64 v[226:227], v[224:225], 1, s[20:21]
	v_lshl_add_u64 v[230:231], v[230:231], 1, s[20:21]
	v_lshl_add_u64 v[234:235], v[232:233], 1, s[20:21]
	v_lshl_add_u64 v[238:239], v[238:239], 1, s[20:21]
	v_lshl_add_u64 v[242:243], v[240:241], 1, s[20:21]
	v_lshl_add_u64 v[248:249], v[248:249], 1, s[20:21]
	v_lshl_add_u64 v[252:253], v[160:161], 1, s[20:21]
	global_load_dwordx4 v[222:225], v[222:223], off nt
	s_nop 0
	global_load_dwordx4 v[226:229], v[226:227], off nt
	s_nop 0
	global_load_dwordx4 v[230:233], v[230:231], off nt
	s_nop 0
	global_load_dwordx4 v[234:237], v[234:235], off nt
	s_nop 0
	global_load_dwordx4 v[238:241], v[238:239], off nt
	s_nop 0
	global_load_dwordx4 v[242:245], v[242:243], off nt
	s_nop 0
	global_load_dwordx4 v[248:251], v[248:249], off nt
	s_nop 0
	global_load_dwordx4 v[252:255], v[252:253], off nt
	v_mul_lo_u32 v199, v199, s29
	v_lshl_add_u32 v199, v200, 4, v199
	v_add_u32_e32 v200, 0x2080, v199
	v_add_u32_e32 v201, 0x4100, v199
	v_add_u32_e32 v202, 0x6180, v199
	v_add_u32_e32 v203, 0x8200, v199
	v_add_u32_e32 v204, 0xa280, v199
	v_add_u32_e32 v205, 0xc300, v199
	v_add_u32_e32 v206, 0xe380, v199
	s_waitcnt vmcnt(15)
	ds_write2_b64 v199, v[162:163], v[164:165] offset1:1
	s_waitcnt vmcnt(14)
	ds_write2_b64 v200, v[168:169], v[170:171] offset1:1
	s_waitcnt vmcnt(13)
	ds_write2_b64 v201, v[172:173], v[174:175] offset1:1
	s_waitcnt vmcnt(12)
	ds_write2_b64 v202, v[176:177], v[178:179] offset1:1
	s_waitcnt vmcnt(11)
	ds_write2_b64 v203, v[180:181], v[182:183] offset1:1
	s_waitcnt vmcnt(10)
	ds_write2_b64 v204, v[184:185], v[186:187] offset1:1
	s_waitcnt vmcnt(9)
	ds_write2_b64 v205, v[188:189], v[190:191] offset1:1
	s_waitcnt vmcnt(8)
	ds_write2_b64 v206, v[194:195], v[196:197] offset1:1
	v_add_u32_e32 v160, 0x10400, v199
	v_add_u32_e32 v200, 0x12480, v199
	v_add_u32_e32 v201, 0x14500, v199
	v_add_u32_e32 v202, 0x16580, v199
	v_add_u32_e32 v203, 0x18600, v199
	v_add_u32_e32 v204, 0x1a680, v199
	v_add_u32_e32 v205, 0x1c700, v199
	v_add_u32_e32 v199, 0x1e780, v199
	s_waitcnt vmcnt(7)
	ds_write2_b64 v160, v[222:223], v[224:225] offset1:1
	s_waitcnt vmcnt(6)
	ds_write2_b64 v200, v[226:227], v[228:229] offset1:1
	s_waitcnt vmcnt(5)
	ds_write2_b64 v201, v[230:231], v[232:233] offset1:1
	s_waitcnt vmcnt(4)
	ds_write2_b64 v202, v[234:235], v[236:237] offset1:1
	s_waitcnt vmcnt(3)
	ds_write2_b64 v203, v[238:239], v[240:241] offset1:1
	s_waitcnt vmcnt(2)
	ds_write2_b64 v204, v[242:243], v[244:245] offset1:1
	s_waitcnt vmcnt(1)
	ds_write2_b64 v205, v[248:249], v[250:251] offset1:1
	s_waitcnt vmcnt(0)
	ds_write2_b64 v199, v[252:253], v[254:255] offset1:1
	v_lshlrev_b32_e32 v160, 3, v198
	v_and_b32_e32 v163, 0xdf, v167
	v_and_or_b32 v164, v167, s24, v160
	v_ashrrev_i32_e32 v165, 7, v167
	v_mad_u32_u24 v167, v163, s29, v164
	s_waitcnt lgkmcnt(0)
	s_barrier
; DI unsigned pack2(float a, float b) { f32x2_t v = {a, b}; bf16x2_t r = __builtin_convertvector(v, bf16x2_t); return __builtin_bit_cast(unsigned, r); }
; DI float bflo(unsigned u) { return __uint_as_float(u << 16); }
; DI float bfhi(unsigned u) { return __uint_as_float(u & 0xffff0000u); }
; DI float shx(float v, int m) { return __shfl_xor(v, m, 64); }
; template <bool XF32>
; DI void phase_outproj(const Params& P, int layer, const void* xres, const bf16_t* og, unsigned char* smem, int L, int G) {
;     ...
; #pragma unroll
;     for (int j = 0; j < 2; ++j)
; #pragma unroll
;       for (int ch = 0; ch < 2; ++ch) {
;         float s1 = 0.f, s2 = 0.f;
; #pragma unroll
;         for (int i = 2 * ch; i < 2 * ch + 2; ++i)
; #pragma unroll
;           for (int q4 = 0; q4 < 4; ++q4) {
;             uint2* pp = (uint2*)(stg + (wn * 64 + j * 32 + r) * STG + wm * 128 + i * 32 + 8 * q4 + 4 * h);
;             const uint2 xv = *pp;
;             uint2 pk;
;             pk.x = pack2(DN_ALPHA * bflo(xv.x) + acc[i][j][4 * q4], DN_ALPHA * bfhi(xv.x) + acc[i][j][4 * q4 + 1]);
;             pk.y = pack2(DN_ALPHA * bflo(xv.y) + acc[i][j][4 * q4 + 2], DN_ALPHA * bfhi(xv.y) + acc[i][j][4 * q4 + 3]);
;             *pp = pk;
;             const float f0 = bflo(pk.x), f1 = bfhi(pk.x), f2 = bflo(pk.y), f3 = bfhi(pk.y);
;             s1 += (f0 + f1) + (f2 + f3); s2 += (f0 * f0 + f1 * f1) + (f2 * f2 + f3 * f3);
;             __builtin_amdgcn_sched_barrier(0);
;           }
;         s1 += shx(s1, 32); s2 += shx(s2, 32);
;         if (h == 0) {
;           const size_t row = (size_t)(mt * 256 + wn * 64 + j * 32 + r);
;           *(float2*)(stats + row * 32 + (nt * 4 + wm * 2 + ch) * 2) = make_float2(s1, s2);
;         }
	ds_read_b64 v[168:169], v167
	v_and_b32_e32 v162, 64, v166
	v_xor_b32_e32 v160, 32, v166
	v_add_u32_e32 v162, 64, v162
	v_cmp_lt_i32_e32 vcc, v160, v162
	v_or_b32_e32 v162, s33, v163
	v_and_b32_e32 v165, -2, v165
	v_ashrrev_i32_e32 v163, 31, v162
	s_waitcnt lgkmcnt(0)
	v_lshlrev_b32_e32 v170, 16, v168
	v_and_b32_e32 v171, 0xffff0000, v168
	v_lshlrev_b32_e32 v168, 16, v169
	v_and_b32_e32 v169, 0xffff0000, v169
	v_cndmask_b32_e32 v160, v166, v160, vcc
	v_lshl_add_u32 v206, s31, 2, v165
	v_lshlrev_b64 v[164:165], 7, v[162:163]
	v_pk_fma_f32 v[112:113], v[170:171], s[12:13], v[112:113] op_sel_hi:[1,0,1]
	v_pk_fma_f32 v[114:115], v[168:169], s[12:13], v[114:115] op_sel_hi:[1,0,1]
	v_lshlrev_b32_e32 v160, 2, v160
	v_cmp_eq_u32_e32 vcc, 0, v198
	v_lshl_add_u64 v[164:165], s[78:79], 0, v[164:165]
	v_cvt_pk_bf16_f32 v112, v112, v113
	v_cvt_pk_bf16_f32 v113, v114, v115
	ds_write_b64 v167, v[112:113]
	v_and_b32_e32 v114, 0xffff0000, v112
	v_lshlrev_b32_e32 v168, 16, v113
	ds_read_b64 v[170:171], v167 offset:16
	s_waitcnt lgkmcnt(0)
	v_lshlrev_b32_e32 v172, 16, v170
	v_and_b32_e32 v173, 0xffff0000, v170
	v_lshlrev_b32_e32 v170, 16, v171
	v_and_b32_e32 v171, 0xffff0000, v171
	v_pk_fma_f32 v[116:117], v[172:173], s[12:13], v[116:117] op_sel_hi:[1,0,1]
	v_pk_fma_f32 v[118:119], v[170:171], s[12:13], v[118:119] op_sel_hi:[1,0,1]
	v_cvt_pk_bf16_f32 v116, v116, v117
	v_cvt_pk_bf16_f32 v117, v118, v119
	ds_write_b64 v167, v[116:117] offset:16
	v_lshlrev_b32_e32 v118, 16, v117
	v_and_b32_e32 v119, 0xffff0000, v117
	v_lshlrev_b32_e32 v171, 16, v116
	v_and_b32_e32 v117, 0xffff0000, v116
	v_lshlrev_b32_e32 v170, 16, v112
	v_mov_b32_e32 v115, v171
	v_and_b32_e32 v116, 0xffff0000, v113
	v_mov_b32_e32 v169, v117
	v_pk_mul_f32 v[172:173], v[170:171], v[170:171]
	v_pk_mul_f32 v[174:175], v[114:115], v[114:115]
	v_pk_add_f32 v[114:115], v[170:171], v[114:115]
	v_pk_mul_f32 v[112:113], v[168:169], v[168:169]
	v_pk_mul_f32 v[176:177], v[116:117], v[116:117]
	v_pk_add_f32 v[168:169], v[116:117], v[168:169]
	v_mul_f32_e32 v178, v118, v118
	v_mov_b32_e32 v115, v173
	v_mov_b32_e32 v169, v177
	v_pk_fma_f32 v[178:179], v[118:119], v[118:119], v[178:179] op_sel_hi:[1,1,0]
	ds_read_b64 v[180:181], v167 offset:32
	s_waitcnt lgkmcnt(0)
	v_lshlrev_b32_e32 v182, 16, v180
	v_and_b32_e32 v183, 0xffff0000, v180
	v_lshlrev_b32_e32 v180, 16, v181
	v_and_b32_e32 v181, 0xffff0000, v181
	v_pk_fma_f32 v[120:121], v[182:183], s[12:13], v[120:121] op_sel_hi:[1,0,1]
	v_pk_fma_f32 v[122:123], v[180:181], s[12:13], v[122:123] op_sel_hi:[1,0,1]
	v_cvt_pk_bf16_f32 v120, v120, v121
	v_cvt_pk_bf16_f32 v121, v122, v123
	ds_write_b64 v167, v[120:121] offset:32
	v_lshlrev_b32_e32 v122, 16, v120
	v_and_b32_e32 v120, 0xffff0000, v120
	v_lshlrev_b32_e32 v180, 16, v121
	v_and_b32_e32 v182, 0xffff0000, v121
	v_mul_f32_e32 v123, v122, v122
	v_mul_f32_e32 v121, v120, v120
	v_mul_f32_e32 v181, v180, v180
	v_mul_f32_e32 v183, v182, v182
	ds_read_b64 v[184:185], v167 offset:48
	s_waitcnt lgkmcnt(0)
	v_lshlrev_b32_e32 v186, 16, v184
	v_and_b32_e32 v187, 0xffff0000, v184
	v_lshlrev_b32_e32 v184, 16, v185
	v_and_b32_e32 v185, 0xffff0000, v185
	v_pk_fma_f32 v[124:125], v[186:187], s[12:13], v[124:125] op_sel_hi:[1,0,1]
	v_pk_fma_f32 v[126:127], v[184:185], s[12:13], v[126:127] op_sel_hi:[1,0,1]
	v_cvt_pk_bf16_f32 v124, v124, v125
	v_cvt_pk_bf16_f32 v125, v126, v127
	ds_write_b64 v167, v[124:125] offset:48
	v_lshlrev_b32_e32 v126, 16, v124
	v_and_b32_e32 v124, 0xffff0000, v124
	v_lshlrev_b32_e32 v184, 16, v125
	v_and_b32_e32 v186, 0xffff0000, v125
	v_mul_f32_e32 v127, v126, v126
	v_mul_f32_e32 v125, v124, v124
	v_mul_f32_e32 v185, v184, v184
	v_mul_f32_e32 v187, v186, v186
	ds_read_b64 v[188:189], v167 offset:64
	s_waitcnt lgkmcnt(0)
	v_lshlrev_b32_e32 v190, 16, v188
	v_and_b32_e32 v191, 0xffff0000, v188
	v_lshlrev_b32_e32 v188, 16, v189
	v_and_b32_e32 v189, 0xffff0000, v189
	v_pk_fma_f32 v[96:97], v[190:191], s[12:13], v[96:97] op_sel_hi:[1,0,1]
	v_pk_fma_f32 v[98:99], v[188:189], s[12:13], v[98:99] op_sel_hi:[1,0,1]
	v_cvt_pk_bf16_f32 v96, v96, v97
	v_cvt_pk_bf16_f32 v97, v98, v99
	ds_write_b64 v167, v[96:97] offset:64
	v_lshlrev_b32_e32 v98, 16, v96
	v_and_b32_e32 v96, 0xffff0000, v96
	v_lshlrev_b32_e32 v188, 16, v97
	v_and_b32_e32 v190, 0xffff0000, v97
	v_mul_f32_e32 v99, v98, v98
	v_mul_f32_e32 v97, v96, v96
	v_mul_f32_e32 v189, v188, v188
	v_mul_f32_e32 v191, v190, v190
	ds_read_b64 v[194:195], v167 offset:80
	s_waitcnt lgkmcnt(0)
; DI unsigned pack2(float a, float b) { f32x2_t v = {a, b}; bf16x2_t r = __builtin_convertvector(v, bf16x2_t); return __builtin_bit_cast(unsigned, r); }
; DI float bflo(unsigned u) { return __uint_as_float(u << 16); }
; DI float bfhi(unsigned u) { return __uint_as_float(u & 0xffff0000u); }
; DI float shx(float v, int m) { return __shfl_xor(v, m, 64); }
; template <bool XF32>
; DI void phase_outproj(const Params& P, int layer, const void* xres, const bf16_t* og, unsigned char* smem, int L, int G) {
;     ...
; #pragma unroll
;     for (int j = 0; j < 2; ++j)
; #pragma unroll
;       for (int ch = 0; ch < 2; ++ch) {
;         float s1 = 0.f, s2 = 0.f;
; #pragma unroll
;         for (int i = 2 * ch; i < 2 * ch + 2; ++i)
; #pragma unroll
;           for (int q4 = 0; q4 < 4; ++q4) {
;             uint2* pp = (uint2*)(stg + (wn * 64 + j * 32 + r) * STG + wm * 128 + i * 32 + 8 * q4 + 4 * h);
;             const uint2 xv = *pp;
;             uint2 pk;
;             pk.x = pack2(DN_ALPHA * bflo(xv.x) + acc[i][j][4 * q4], DN_ALPHA * bfhi(xv.x) + acc[i][j][4 * q4 + 1]);
;             pk.y = pack2(DN_ALPHA * bflo(xv.y) + acc[i][j][4 * q4 + 2], DN_ALPHA * bfhi(xv.y) + acc[i][j][4 * q4 + 3]);
;             *pp = pk;
;             const float f0 = bflo(pk.x), f1 = bfhi(pk.x), f2 = bflo(pk.y), f3 = bfhi(pk.y);
;             s1 += (f0 + f1) + (f2 + f3); s2 += (f0 * f0 + f1 * f1) + (f2 * f2 + f3 * f3);
;             __builtin_amdgcn_sched_barrier(0);
;           }
;         s1 += shx(s1, 32); s2 += shx(s2, 32);
;         if (h == 0) {
;           const size_t row = (size_t)(mt * 256 + wn * 64 + j * 32 + r);
;           *(float2*)(stats + row * 32 + (nt * 4 + wm * 2 + ch) * 2) = make_float2(s1, s2);
;         }
	v_lshlrev_b32_e32 v196, 16, v194
	v_and_b32_e32 v197, 0xffff0000, v194
	v_lshlrev_b32_e32 v194, 16, v195
	v_and_b32_e32 v195, 0xffff0000, v195
	v_pk_fma_f32 v[100:101], v[196:197], s[12:13], v[100:101] op_sel_hi:[1,0,1]
	v_pk_fma_f32 v[102:103], v[194:195], s[12:13], v[102:103] op_sel_hi:[1,0,1]
	v_cvt_pk_bf16_f32 v100, v100, v101
	v_cvt_pk_bf16_f32 v101, v102, v103
	ds_write_b64 v167, v[100:101] offset:80
	v_lshlrev_b32_e32 v102, 16, v100
	v_and_b32_e32 v100, 0xffff0000, v100
	v_lshlrev_b32_e32 v194, 16, v101
	v_and_b32_e32 v196, 0xffff0000, v101
	v_mul_f32_e32 v101, v100, v100
	v_mul_f32_e32 v103, v102, v102
	v_mul_f32_e32 v195, v194, v194
	v_mul_f32_e32 v197, v196, v196
	ds_read_b64 v[198:199], v167 offset:96
	s_waitcnt lgkmcnt(0)
	v_lshlrev_b32_e32 v200, 16, v198
	v_and_b32_e32 v201, 0xffff0000, v198
	v_lshlrev_b32_e32 v198, 16, v199
	v_and_b32_e32 v199, 0xffff0000, v199
	v_pk_fma_f32 v[104:105], v[200:201], s[12:13], v[104:105] op_sel_hi:[1,0,1]
	v_pk_fma_f32 v[106:107], v[198:199], s[12:13], v[106:107] op_sel_hi:[1,0,1]
	v_cvt_pk_bf16_f32 v104, v104, v105
	v_cvt_pk_bf16_f32 v105, v106, v107
	ds_write_b64 v167, v[104:105] offset:96
	v_lshlrev_b32_e32 v106, 16, v104
	v_and_b32_e32 v104, 0xffff0000, v104
	v_lshlrev_b32_e32 v198, 16, v105
	v_and_b32_e32 v200, 0xffff0000, v105
	v_mul_f32_e32 v107, v106, v106
	v_mul_f32_e32 v105, v104, v104
	v_mul_f32_e32 v199, v198, v198
	v_mul_f32_e32 v201, v200, v200
	v_pk_mov_b32 v[170:171], v[170:171], v[172:173] op_sel:[1,0]
	v_pk_mov_b32 v[116:117], v[116:117], v[174:175] op_sel:[1,0]
	ds_read_b64 v[202:203], v167 offset:112
	v_pk_add_f32 v[116:117], v[170:171], v[116:117]
	v_mov_b32_e32 v170, v118
	v_mov_b32_e32 v171, v112
	v_pk_mov_b32 v[112:113], v[118:119], v[176:177] op_sel:[1,0]
	v_pk_add_f32 v[114:115], v[114:115], v[168:169]
	v_pk_add_f32 v[112:113], v[170:171], v[112:113]
	v_mov_b32_e32 v178, v161
	v_pk_add_f32 v[112:113], v[116:117], v[112:113]
	v_pk_add_f32 v[114:115], v[114:115], v[178:179]
	v_pk_add_f32 v[116:117], v[180:181], v[182:183]
	v_pk_add_f32 v[112:113], v[112:113], v[114:115]
	v_pk_add_f32 v[114:115], v[122:123], v[120:121]
	s_waitcnt lgkmcnt(0)
	v_lshlrev_b32_e32 v204, 16, v202
	v_pk_add_f32 v[114:115], v[114:115], v[116:117]
	v_pk_add_f32 v[116:117], v[184:185], v[186:187]
	v_pk_add_f32 v[112:113], v[112:113], v[114:115]
	v_pk_add_f32 v[114:115], v[126:127], v[124:125]
	v_and_b32_e32 v205, 0xffff0000, v202
	v_lshlrev_b32_e32 v202, 16, v203
	v_and_b32_e32 v203, 0xffff0000, v203
	v_pk_add_f32 v[114:115], v[114:115], v[116:117]
	v_pk_add_f32 v[96:97], v[98:99], v[96:97]
	v_pk_add_f32 v[98:99], v[188:189], v[190:191]
	v_pk_fma_f32 v[108:109], v[204:205], s[12:13], v[108:109] op_sel_hi:[1,0,1]
	v_pk_fma_f32 v[110:111], v[202:203], s[12:13], v[110:111] op_sel_hi:[1,0,1]
	v_pk_add_f32 v[112:113], v[112:113], v[114:115]
	v_pk_add_f32 v[96:97], v[96:97], v[98:99]
	v_pk_add_f32 v[98:99], v[102:103], v[100:101]
	v_pk_add_f32 v[100:101], v[194:195], v[196:197]
	v_cvt_pk_bf16_f32 v108, v108, v109
	v_cvt_pk_bf16_f32 v109, v110, v111
	v_pk_add_f32 v[96:97], v[112:113], v[96:97]
	v_pk_add_f32 v[98:99], v[98:99], v[100:101]
	ds_write_b64 v167, v[108:109] offset:112
	v_lshlrev_b32_e32 v110, 16, v108
	v_and_b32_e32 v108, 0xffff0000, v108
	v_lshlrev_b32_e32 v202, 16, v109
	v_and_b32_e32 v204, 0xffff0000, v109
	v_pk_add_f32 v[96:97], v[96:97], v[98:99]
	v_pk_add_f32 v[98:99], v[106:107], v[104:105]
	v_pk_add_f32 v[100:101], v[198:199], v[200:201]
	v_mul_f32_e32 v111, v110, v110
	v_mul_f32_e32 v109, v108, v108
	v_mul_f32_e32 v203, v202, v202
	v_mul_f32_e32 v205, v204, v204
	v_pk_add_f32 v[98:99], v[98:99], v[100:101]
	v_pk_add_f32 v[100:101], v[202:203], v[204:205]
	v_pk_add_f32 v[96:97], v[96:97], v[98:99]
	v_pk_add_f32 v[98:99], v[110:111], v[108:109]
	s_nop 0
	v_pk_add_f32 v[98:99], v[98:99], v[100:101]
	s_nop 0
	v_pk_add_f32 v[98:99], v[96:97], v[98:99]
	ds_bpermute_b32 v100, v160, v98
	ds_bpermute_b32 v101, v160, v99
	v_lshlrev_b32_e32 v96, 1, v206
	v_ashrrev_i32_e32 v97, 31, v96
	s_and_saveexec_b64 s[20:21], vcc
	s_cbranch_execz .LBB0_852
	v_lshl_add_u64 v[102:103], v[96:97], 2, v[164:165]
	s_waitcnt lgkmcnt(0)
	v_pk_add_f32 v[98:99], v[98:99], v[100:101]
	global_store_dwordx2 v[102:103], v[98:99], off

; DI unsigned pack2(float a, float b) { f32x2_t v = {a, b}; bf16x2_t r = __builtin_convertvector(v, bf16x2_t); return __builtin_bit_cast(unsigned, r); }
; DI float sigmoidf_(float x) { return __builtin_amdgcn_rcpf(1.f + __expf(-x)); }
; template <bool LAST>
; DI void phase_gate(const Params& P, int layer, unsigned char* smem, int L, int G) {
;     ...
;     unsigned gq[4][2][8];
; #pragma unroll
;     for (int i = 0; i < 4; ++i)
; #pragma unroll
;       for (int q4 = 0; q4 < 4; ++q4) {
;         const int fl = wm * 128 + i * 32 + 8 * q4 + 4 * h;
;         const f32x4 c1v = *(const f32x4*)(vecL + fl), c2v = *(const f32x4*)(vecL + 256 + fl);
;         const float c1a[4] = {c1v.x, c1v.y, c1v.z, c1v.w}, c2a[4] = {c2v.x, c2v.y, c2v.z, c2v.w};
; #pragma unroll
;         for (int j = 0; j < 2; ++j) {
;           const int lrow = wn * 64 + j * 32 + r;
;           const float mu = rowA[lrow], rstd = rowB[lrow];
;           float sg4[4];
; #pragma unroll
;           for (int e = 0; e < 4; ++e) sg4[e] = sigmoidf_(rstd * (accu[i][j][4 * q4 + e] - mu * c1a[e]) + c2a[e]);
;           gq[i][j][2 * q4] = pack2(sg4[0], sg4[1]); gq[i][j][2 * q4 + 1] = pack2(sg4[2], sg4[3]);
;         }
;         __builtin_amdgcn_sched_barrier(0);
;       }
.LBB0_920:
	v_lshrrev_b32_e32 v160, 1, v163
	v_lshrrev_b32_e32 v163, 3, v163
	v_and_b32_e32 v163, 4, v163
	v_and_or_b32 v160, v160, s39, v163
	v_lshlrev_b32_e32 v160, 2, v160
	v_add_u32_e32 v163, 0x24800, v160
	v_add_u32_e32 v164, 0x24c00, v160
	v_and_b32_e32 v167, 0x37c, v168
	ds_read_b128 v[170:173], v163
	ds_read_b128 v[174:177], v164
	v_or_b32_e32 v164, 0x24000, v167
	v_or_b32_e32 v166, 0x24080, v167
	v_or_b32_e32 v165, 0x24400, v167
	ds_read_b32 v168, v164
	ds_read_b32 v169, v165
	v_or_b32_e32 v167, 0x24480, v167
	ds_read_b32 v178, v166
	ds_read_b32 v179, v167
	s_waitcnt lgkmcnt(3)
	v_fma_f32 v112, -v170, v168, v112
	v_fma_f32 v113, -v171, v168, v113
	s_waitcnt lgkmcnt(1)
	v_fma_f32 v98, -v172, v178, v98
	v_fma_f32 v114, -v172, v168, v114
	v_fma_f32 v115, -v173, v168, v115
	v_fma_f32 v96, -v170, v178, v96
	v_fma_f32 v97, -v171, v178, v97
	s_waitcnt lgkmcnt(0)
	v_fma_f32 v98, v179, v98, v176
	v_fma_f32 v99, -v173, v178, v99
	v_fma_f32 v112, v169, v112, v174
	v_fma_f32 v113, v169, v113, v175
	v_fma_f32 v114, v169, v114, v176
	v_fma_f32 v115, v169, v115, v177
	v_fma_f32 v96, v179, v96, v174
	v_fma_f32 v97, v179, v97, v175
	v_mul_f32_e32 v98, 0xbfb8aa3b, v98
	v_fmac_f32_e32 v177, v179, v99
	v_mul_f32_e32 v112, 0xbfb8aa3b, v112
	v_mul_f32_e32 v113, 0xbfb8aa3b, v113
	v_mul_f32_e32 v114, 0xbfb8aa3b, v114
	v_mul_f32_e32 v115, 0xbfb8aa3b, v115
	v_mul_f32_e32 v96, 0xbfb8aa3b, v96
	v_mul_f32_e32 v97, 0xbfb8aa3b, v97
	v_exp_f32_e32 v98, v98
	v_mul_f32_e32 v99, 0xbfb8aa3b, v177
	v_exp_f32_e32 v112, v112
	v_exp_f32_e32 v113, v113
	v_exp_f32_e32 v114, v114
	v_exp_f32_e32 v115, v115
	v_exp_f32_e32 v96, v96
	v_exp_f32_e32 v97, v97
	v_exp_f32_e32 v99, v99
	v_add_f32_e32 v98, 1.0, v98
	v_add_f32_e32 v112, 1.0, v112
	v_add_f32_e32 v113, 1.0, v113
	v_add_f32_e32 v114, 1.0, v114
	v_add_f32_e32 v115, 1.0, v115
	v_add_f32_e32 v96, 1.0, v96
	v_add_f32_e32 v97, 1.0, v97
	v_rcp_f32_e32 v168, v98
	v_add_f32_e32 v98, 1.0, v99
	v_rcp_f32_e32 v112, v112
	v_rcp_f32_e32 v113, v113
	v_rcp_f32_e32 v114, v114
	v_rcp_f32_e32 v115, v115
	v_rcp_f32_e32 v96, v96
	v_rcp_f32_e32 v97, v97
	v_rcp_f32_e32 v169, v98
	v_cvt_pk_bf16_f32 v99, v112, v113
	v_cvt_pk_bf16_f32 v98, v114, v115
	v_cvt_pk_bf16_f32 v97, v96, v97
	v_cvt_pk_bf16_f32 v96, v168, v169
	v_add_u32_e32 v112, 0x24820, v160
	v_add_u32_e32 v168, 0x24c20, v160
	ds_read_b128 v[112:115], v112
	ds_read_b128 v[168:171], v168
	ds_read_b32 v172, v164
	ds_read_b32 v173, v165
	ds_read_b32 v174, v166
	ds_read_b32 v175, v167
	s_waitcnt lgkmcnt(3)
	v_fma_f32 v116, -v112, v172, v116
	v_fma_f32 v117, -v113, v172, v117
	s_waitcnt lgkmcnt(1)
	v_fma_f32 v102, -v114, v174, v102
	v_fma_f32 v118, -v114, v172, v118
	v_fma_f32 v119, -v115, v172, v119
	v_fma_f32 v100, -v112, v174, v100
	v_fma_f32 v101, -v113, v174, v101
	s_waitcnt lgkmcnt(0)
	v_fma_f32 v102, v175, v102, v170
	v_fma_f32 v103, -v115, v174, v103
	v_fma_f32 v116, v173, v116, v168
	v_fma_f32 v117, v173, v117, v169
	v_fma_f32 v118, v173, v118, v170
	v_fma_f32 v119, v173, v119, v171
	v_fma_f32 v100, v175, v100, v168
	v_fma_f32 v101, v175, v101, v169
	v_mul_f32_e32 v102, 0xbfb8aa3b, v102
	v_fmac_f32_e32 v171, v175, v103
	v_mul_f32_e32 v116, 0xbfb8aa3b, v116
	v_mul_f32_e32 v117, 0xbfb8aa3b, v117
	v_mul_f32_e32 v118, 0xbfb8aa3b, v118
	v_mul_f32_e32 v119, 0xbfb8aa3b, v119
	v_mul_f32_e32 v100, 0xbfb8aa3b, v100
	v_mul_f32_e32 v101, 0xbfb8aa3b, v101
	v_exp_f32_e32 v102, v102
	v_mul_f32_e32 v103, 0xbfb8aa3b, v171
	v_exp_f32_e32 v116, v116
	v_exp_f32_e32 v117, v117
	v_exp_f32_e32 v118, v118
	v_exp_f32_e32 v119, v119
	v_exp_f32_e32 v100, v100
	v_exp_f32_e32 v101, v101
	v_exp_f32_e32 v103, v103
	v_add_f32_e32 v102, 1.0, v102
	v_add_f32_e32 v116, 1.0, v116
	v_add_f32_e32 v117, 1.0, v117
	v_add_f32_e32 v118, 1.0, v118
	v_add_f32_e32 v119, 1.0, v119
	v_add_f32_e32 v100, 1.0, v100
	v_add_f32_e32 v101, 1.0, v101
	v_rcp_f32_e32 v113, v102
	v_add_f32_e32 v102, 1.0, v103
	v_rcp_f32_e32 v116, v116
	v_rcp_f32_e32 v117, v117
	v_rcp_f32_e32 v118, v118
	v_rcp_f32_e32 v112, v119
	v_rcp_f32_e32 v100, v100
	v_rcp_f32_e32 v101, v101
	v_rcp_f32_e32 v114, v102
	v_cvt_pk_bf16_f32 v103, v116, v117
	v_cvt_pk_bf16_f32 v102, v118, v112
	v_cvt_pk_bf16_f32 v101, v100, v101
	v_cvt_pk_bf16_f32 v100, v113, v114
	v_add_u32_e32 v112, 0x24840, v160
	v_add_u32_e32 v116, 0x24c40, v160
	ds_read_b128 v[112:115], v112
	ds_read_b128 v[116:119], v116
	ds_read_b32 v168, v164
	ds_read_b32 v169, v165
	ds_read_b32 v170, v166
	ds_read_b32 v171, v167
	s_waitcnt lgkmcnt(3)
	v_fma_f32 v120, -v112, v168, v120
	v_fma_f32 v121, -v113, v168, v121
	s_waitcnt lgkmcnt(1)
	v_fma_f32 v106, -v114, v170, v106
	v_fma_f32 v122, -v114, v168, v122
	v_fma_f32 v123, -v115, v168, v123
	v_fma_f32 v104, -v112, v170, v104
	v_fma_f32 v105, -v113, v170, v105
	s_waitcnt lgkmcnt(0)
	v_fma_f32 v106, v171, v106, v118
	v_fma_f32 v107, -v115, v170, v107
	v_fma_f32 v120, v169, v120, v116
	v_fma_f32 v121, v169, v121, v117
	v_fma_f32 v122, v169, v122, v118
	v_fma_f32 v123, v169, v123, v119
	v_fma_f32 v104, v171, v104, v116
	v_fma_f32 v105, v171, v105, v117
	v_mul_f32_e32 v106, 0xbfb8aa3b, v106
	v_fmac_f32_e32 v119, v171, v107
	v_mul_f32_e32 v120, 0xbfb8aa3b, v120
	v_mul_f32_e32 v121, 0xbfb8aa3b, v121
	v_mul_f32_e32 v122, 0xbfb8aa3b, v122
	v_mul_f32_e32 v123, 0xbfb8aa3b, v123
	v_mul_f32_e32 v104, 0xbfb8aa3b, v104
	v_mul_f32_e32 v105, 0xbfb8aa3b, v105
	v_exp_f32_e32 v106, v106
	v_mul_f32_e32 v107, 0xbfb8aa3b, v119
	v_exp_f32_e32 v120, v120
	v_exp_f32_e32 v121, v121
	v_exp_f32_e32 v122, v122
	v_exp_f32_e32 v123, v123
	v_exp_f32_e32 v104, v104
	v_exp_f32_e32 v105, v105
	v_exp_f32_e32 v107, v107
	v_add_f32_e32 v106, 1.0, v106
	v_add_f32_e32 v120, 1.0, v120
	v_add_f32_e32 v121, 1.0, v121
	v_add_f32_e32 v122, 1.0, v122
	v_add_f32_e32 v123, 1.0, v123
	v_add_f32_e32 v104, 1.0, v104
	v_add_f32_e32 v105, 1.0, v105
	v_rcp_f32_e32 v113, v106
	v_add_f32_e32 v106, 1.0, v107
	v_rcp_f32_e32 v120, v120
	v_rcp_f32_e32 v121, v121
	v_rcp_f32_e32 v122, v122
	v_rcp_f32_e32 v112, v123
	v_rcp_f32_e32 v104, v104
	v_rcp_f32_e32 v105, v105
	v_rcp_f32_e32 v114, v106
	v_cvt_pk_bf16_f32 v107, v120, v121
	v_cvt_pk_bf16_f32 v106, v122, v112
	v_cvt_pk_bf16_f32 v105, v104, v105
	v_cvt_pk_bf16_f32 v104, v113, v114
	v_add_u32_e32 v112, 0x24860, v160
	v_add_u32_e32 v116, 0x24c60, v160
	ds_read_b128 v[112:115], v112
	ds_read_b128 v[116:119], v116
	ds_read_b32 v120, v164
	ds_read_b32 v121, v165
	ds_read_b32 v122, v166
	ds_read_b32 v123, v167
	s_waitcnt lgkmcnt(3)
; DI unsigned pack2(float a, float b) { f32x2_t v = {a, b}; bf16x2_t r = __builtin_convertvector(v, bf16x2_t); return __builtin_bit_cast(unsigned, r); }
; DI float sigmoidf_(float x) { return __builtin_amdgcn_rcpf(1.f + __expf(-x)); }
; template <bool LAST>
; DI void phase_gate(const Params& P, int layer, unsigned char* smem, int L, int G) {
;     ...
;     unsigned gq[4][2][8];
; #pragma unroll
;     for (int i = 0; i < 4; ++i)
; #pragma unroll
;       for (int q4 = 0; q4 < 4; ++q4) {
;         const int fl = wm * 128 + i * 32 + 8 * q4 + 4 * h;
;         const f32x4 c1v = *(const f32x4*)(vecL + fl), c2v = *(const f32x4*)(vecL + 256 + fl);
;         const float c1a[4] = {c1v.x, c1v.y, c1v.z, c1v.w}, c2a[4] = {c2v.x, c2v.y, c2v.z, c2v.w};
; #pragma unroll
;         for (int j = 0; j < 2; ++j) {
;           const int lrow = wn * 64 + j * 32 + r;
;           const float mu = rowA[lrow], rstd = rowB[lrow];
;           float sg4[4];
; #pragma unroll
;           for (int e = 0; e < 4; ++e) sg4[e] = sigmoidf_(rstd * (accu[i][j][4 * q4 + e] - mu * c1a[e]) + c2a[e]);
;           gq[i][j][2 * q4] = pack2(sg4[0], sg4[1]); gq[i][j][2 * q4 + 1] = pack2(sg4[2], sg4[3]);
;         }
;         __builtin_amdgcn_sched_barrier(0);
;       }
	v_fma_f32 v125, -v113, v120, v125
	v_fma_f32 v124, -v112, v120, v124
	s_waitcnt lgkmcnt(1)
	v_fma_f32 v110, -v114, v122, v110
	v_fma_f32 v125, v121, v125, v117
	v_fma_f32 v126, -v114, v120, v126
	v_fma_f32 v120, -v115, v120, v127
	v_fma_f32 v108, -v112, v122, v108
	v_fma_f32 v109, -v113, v122, v109
	s_waitcnt lgkmcnt(0)
	v_fma_f32 v110, v123, v110, v118
	v_fma_f32 v111, -v115, v122, v111
	v_fma_f32 v124, v121, v124, v116
	v_mul_f32_e32 v125, 0xbfb8aa3b, v125
	v_fma_f32 v126, v121, v126, v118
	v_fma_f32 v120, v121, v120, v119
	v_fma_f32 v108, v123, v108, v116
	v_fma_f32 v109, v123, v109, v117
	v_mul_f32_e32 v110, 0xbfb8aa3b, v110
	v_fmac_f32_e32 v119, v123, v111
	v_mul_f32_e32 v124, 0xbfb8aa3b, v124
	v_exp_f32_e32 v125, v125
	v_mul_f32_e32 v126, 0xbfb8aa3b, v126
	v_mul_f32_e32 v120, 0xbfb8aa3b, v120
	v_mul_f32_e32 v108, 0xbfb8aa3b, v108
	v_mul_f32_e32 v109, 0xbfb8aa3b, v109
	v_exp_f32_e32 v110, v110
	v_mul_f32_e32 v111, 0xbfb8aa3b, v119
	v_exp_f32_e32 v124, v124
	v_exp_f32_e32 v126, v126
	v_exp_f32_e32 v120, v120
	v_exp_f32_e32 v108, v108
	v_exp_f32_e32 v109, v109
	v_exp_f32_e32 v111, v111
	v_add_f32_e32 v125, 1.0, v125
	v_add_f32_e32 v110, 1.0, v110
	v_add_f32_e32 v124, 1.0, v124
	v_rcp_f32_e32 v121, v125
	v_add_f32_e32 v125, 1.0, v126
	v_add_f32_e32 v120, 1.0, v120
	v_add_f32_e32 v108, 1.0, v108
	v_add_f32_e32 v109, 1.0, v109
	v_rcp_f32_e32 v113, v110
	v_add_f32_e32 v110, 1.0, v111
	v_rcp_f32_e32 v124, v124
	v_rcp_f32_e32 v125, v125
	v_rcp_f32_e32 v112, v120
	v_rcp_f32_e32 v108, v108
	v_rcp_f32_e32 v109, v109
	v_rcp_f32_e32 v114, v110
	v_cvt_pk_bf16_f32 v111, v124, v121
	v_cvt_pk_bf16_f32 v110, v125, v112
	v_cvt_pk_bf16_f32 v109, v108, v109
	v_cvt_pk_bf16_f32 v108, v113, v114
	v_add_u32_e32 v112, 0x24880, v160
	v_add_u32_e32 v116, 0x24c80, v160
	ds_read_b128 v[112:115], v112
	ds_read_b128 v[116:119], v116
	ds_read_b32 v120, v164
	ds_read_b32 v121, v165
	ds_read_b32 v122, v166
	ds_read_b32 v123, v167
	s_waitcnt lgkmcnt(3)
	v_fma_f32 v80, -v112, v120, v80
	v_fma_f32 v81, -v113, v120, v81
	s_waitcnt lgkmcnt(1)
	v_fma_f32 v66, -v114, v122, v66
	v_fma_f32 v82, -v114, v120, v82
	v_fma_f32 v83, -v115, v120, v83
	v_fma_f32 v64, -v112, v122, v64
	v_fma_f32 v65, -v113, v122, v65
	s_waitcnt lgkmcnt(0)
	v_fma_f32 v66, v123, v66, v118
	v_fma_f32 v67, -v115, v122, v67
	v_fma_f32 v80, v121, v80, v116
	v_fma_f32 v81, v121, v81, v117
	v_fma_f32 v82, v121, v82, v118
	v_fma_f32 v83, v121, v83, v119
	v_fma_f32 v64, v123, v64, v116
	v_fma_f32 v65, v123, v65, v117
	v_mul_f32_e32 v66, 0xbfb8aa3b, v66
	v_fmac_f32_e32 v119, v123, v67
	v_mul_f32_e32 v80, 0xbfb8aa3b, v80
	v_mul_f32_e32 v81, 0xbfb8aa3b, v81
	v_mul_f32_e32 v82, 0xbfb8aa3b, v82
	v_mul_f32_e32 v83, 0xbfb8aa3b, v83
	v_mul_f32_e32 v64, 0xbfb8aa3b, v64
	v_mul_f32_e32 v65, 0xbfb8aa3b, v65
	v_exp_f32_e32 v66, v66
	v_mul_f32_e32 v67, 0xbfb8aa3b, v119
	v_exp_f32_e32 v80, v80
	v_exp_f32_e32 v81, v81
	v_exp_f32_e32 v82, v82
	v_exp_f32_e32 v83, v83
	v_exp_f32_e32 v64, v64
	v_exp_f32_e32 v65, v65
	v_exp_f32_e32 v67, v67
	v_add_f32_e32 v66, 1.0, v66
	v_add_f32_e32 v80, 1.0, v80
	v_add_f32_e32 v81, 1.0, v81
	v_add_f32_e32 v82, 1.0, v82
	v_add_f32_e32 v83, 1.0, v83
	v_add_f32_e32 v64, 1.0, v64
	v_add_f32_e32 v65, 1.0, v65
	v_rcp_f32_e32 v112, v66
	v_add_f32_e32 v66, 1.0, v67
	v_rcp_f32_e32 v80, v80
	v_rcp_f32_e32 v81, v81
	v_rcp_f32_e32 v82, v82
	v_rcp_f32_e32 v83, v83
	v_rcp_f32_e32 v64, v64
	v_rcp_f32_e32 v65, v65
	v_rcp_f32_e32 v113, v66
	v_cvt_pk_bf16_f32 v67, v80, v81
	v_cvt_pk_bf16_f32 v66, v82, v83
	v_cvt_pk_bf16_f32 v65, v64, v65
	v_cvt_pk_bf16_f32 v64, v112, v113
	v_add_u32_e32 v80, 0x248a0, v160
	v_add_u32_e32 v112, 0x24ca0, v160
	ds_read_b128 v[80:83], v80
	ds_read_b128 v[112:115], v112
	ds_read_b32 v116, v164
	ds_read_b32 v117, v165
	ds_read_b32 v118, v166
	ds_read_b32 v119, v167
	s_waitcnt lgkmcnt(3)
	v_fma_f32 v84, -v80, v116, v84
	v_fma_f32 v85, -v81, v116, v85
	s_waitcnt lgkmcnt(1)
	v_fma_f32 v70, -v82, v118, v70
	v_fma_f32 v86, -v82, v116, v86
	v_fma_f32 v87, -v83, v116, v87
	v_fma_f32 v68, -v80, v118, v68
	v_fma_f32 v69, -v81, v118, v69
	s_waitcnt lgkmcnt(0)
	v_fma_f32 v70, v119, v70, v114
	v_fma_f32 v71, -v83, v118, v71
	v_fma_f32 v84, v117, v84, v112
	v_fma_f32 v85, v117, v85, v113
	v_fma_f32 v86, v117, v86, v114
	v_fma_f32 v87, v117, v87, v115
	v_fma_f32 v68, v119, v68, v112
	v_fma_f32 v69, v119, v69, v113
	v_mul_f32_e32 v70, 0xbfb8aa3b, v70
	v_fmac_f32_e32 v115, v119, v71
	v_mul_f32_e32 v84, 0xbfb8aa3b, v84
	v_mul_f32_e32 v85, 0xbfb8aa3b, v85
	v_mul_f32_e32 v86, 0xbfb8aa3b, v86
	v_mul_f32_e32 v87, 0xbfb8aa3b, v87
	v_mul_f32_e32 v68, 0xbfb8aa3b, v68
	v_mul_f32_e32 v69, 0xbfb8aa3b, v69
	v_exp_f32_e32 v70, v70
	v_mul_f32_e32 v71, 0xbfb8aa3b, v115
	v_exp_f32_e32 v84, v84
	v_exp_f32_e32 v85, v85
	v_exp_f32_e32 v86, v86
	v_exp_f32_e32 v87, v87
	v_exp_f32_e32 v68, v68
	v_exp_f32_e32 v69, v69
	v_exp_f32_e32 v71, v71
	v_add_f32_e32 v70, 1.0, v70
	v_add_f32_e32 v84, 1.0, v84
	v_add_f32_e32 v85, 1.0, v85
	v_add_f32_e32 v86, 1.0, v86
	v_add_f32_e32 v87, 1.0, v87
	v_add_f32_e32 v68, 1.0, v68
	v_add_f32_e32 v69, 1.0, v69
	v_rcp_f32_e32 v81, v70
	v_add_f32_e32 v70, 1.0, v71
	v_rcp_f32_e32 v84, v84
	v_rcp_f32_e32 v85, v85
	v_rcp_f32_e32 v86, v86
	v_rcp_f32_e32 v80, v87
	v_rcp_f32_e32 v68, v68
	v_rcp_f32_e32 v69, v69
	v_rcp_f32_e32 v82, v70
	v_cvt_pk_bf16_f32 v71, v84, v85
	v_cvt_pk_bf16_f32 v70, v86, v80
	v_cvt_pk_bf16_f32 v69, v68, v69
	v_cvt_pk_bf16_f32 v68, v81, v82
	v_add_u32_e32 v80, 0x248c0, v160
	v_add_u32_e32 v84, 0x24cc0, v160
	ds_read_b128 v[80:83], v80
	ds_read_b128 v[84:87], v84
	ds_read_b32 v112, v164
	ds_read_b32 v113, v165
	ds_read_b32 v114, v166
	ds_read_b32 v115, v167
	s_waitcnt lgkmcnt(3)
; DI unsigned pack2(float a, float b) { f32x2_t v = {a, b}; bf16x2_t r = __builtin_convertvector(v, bf16x2_t); return __builtin_bit_cast(unsigned, r); }
; DI float sigmoidf_(float x) { return __builtin_amdgcn_rcpf(1.f + __expf(-x)); }
; template <bool LAST>
; DI void phase_gate(const Params& P, int layer, unsigned char* smem, int L, int G) {
;     ...
;     unsigned gq[4][2][8];
; #pragma unroll
;     for (int i = 0; i < 4; ++i)
; #pragma unroll
;       for (int q4 = 0; q4 < 4; ++q4) {
;         const int fl = wm * 128 + i * 32 + 8 * q4 + 4 * h;
;         const f32x4 c1v = *(const f32x4*)(vecL + fl), c2v = *(const f32x4*)(vecL + 256 + fl);
;         const float c1a[4] = {c1v.x, c1v.y, c1v.z, c1v.w}, c2a[4] = {c2v.x, c2v.y, c2v.z, c2v.w};
; #pragma unroll
;         for (int j = 0; j < 2; ++j) {
;           const int lrow = wn * 64 + j * 32 + r;
;           const float mu = rowA[lrow], rstd = rowB[lrow];
;           float sg4[4];
; #pragma unroll
;           for (int e = 0; e < 4; ++e) sg4[e] = sigmoidf_(rstd * (accu[i][j][4 * q4 + e] - mu * c1a[e]) + c2a[e]);
;           gq[i][j][2 * q4] = pack2(sg4[0], sg4[1]); gq[i][j][2 * q4 + 1] = pack2(sg4[2], sg4[3]);
;         }
;         __builtin_amdgcn_sched_barrier(0);
;       }
	v_fma_f32 v88, -v80, v112, v88
	v_fma_f32 v89, -v81, v112, v89
	s_waitcnt lgkmcnt(1)
	v_fma_f32 v74, -v82, v114, v74
	v_fma_f32 v90, -v82, v112, v90
	v_fma_f32 v91, -v83, v112, v91
	v_fma_f32 v72, -v80, v114, v72
	v_fma_f32 v73, -v81, v114, v73
	s_waitcnt lgkmcnt(0)
	v_fma_f32 v74, v115, v74, v86
	v_fma_f32 v75, -v83, v114, v75
	v_fma_f32 v88, v113, v88, v84
	v_fma_f32 v89, v113, v89, v85
	v_fma_f32 v90, v113, v90, v86
	v_fma_f32 v91, v113, v91, v87
	v_fma_f32 v72, v115, v72, v84
	v_fma_f32 v73, v115, v73, v85
	v_mul_f32_e32 v74, 0xbfb8aa3b, v74
	v_fmac_f32_e32 v87, v115, v75
	v_mul_f32_e32 v88, 0xbfb8aa3b, v88
	v_mul_f32_e32 v89, 0xbfb8aa3b, v89
	v_mul_f32_e32 v90, 0xbfb8aa3b, v90
	v_mul_f32_e32 v91, 0xbfb8aa3b, v91
	v_mul_f32_e32 v72, 0xbfb8aa3b, v72
	v_mul_f32_e32 v73, 0xbfb8aa3b, v73
	v_exp_f32_e32 v74, v74
	v_mul_f32_e32 v75, 0xbfb8aa3b, v87
	v_exp_f32_e32 v88, v88
	v_exp_f32_e32 v89, v89
	v_exp_f32_e32 v90, v90
	v_exp_f32_e32 v91, v91
	v_exp_f32_e32 v72, v72
	v_exp_f32_e32 v73, v73
	v_exp_f32_e32 v75, v75
	v_add_f32_e32 v74, 1.0, v74
	v_add_f32_e32 v88, 1.0, v88
	v_add_f32_e32 v89, 1.0, v89
	v_add_f32_e32 v90, 1.0, v90
	v_add_f32_e32 v91, 1.0, v91
	v_add_f32_e32 v72, 1.0, v72
	v_add_f32_e32 v73, 1.0, v73
	v_rcp_f32_e32 v81, v74
	v_add_f32_e32 v74, 1.0, v75
	v_rcp_f32_e32 v88, v88
	v_rcp_f32_e32 v89, v89
	v_rcp_f32_e32 v90, v90
	v_rcp_f32_e32 v80, v91
	v_rcp_f32_e32 v72, v72
	v_rcp_f32_e32 v73, v73
	v_rcp_f32_e32 v82, v74
	v_cvt_pk_bf16_f32 v75, v88, v89
	v_cvt_pk_bf16_f32 v74, v90, v80
	v_cvt_pk_bf16_f32 v73, v72, v73
	v_cvt_pk_bf16_f32 v72, v81, v82
	v_add_u32_e32 v80, 0x248e0, v160
	v_add_u32_e32 v84, 0x24ce0, v160
	ds_read_b128 v[80:83], v80
	ds_read_b128 v[84:87], v84
	ds_read_b32 v88, v164
	ds_read_b32 v89, v165
	ds_read_b32 v90, v166
	ds_read_b32 v91, v167
	s_waitcnt lgkmcnt(3)
	v_fma_f32 v93, -v81, v88, v93
	v_fma_f32 v92, -v80, v88, v92
	s_waitcnt lgkmcnt(1)
	v_fma_f32 v78, -v82, v90, v78
	v_fma_f32 v93, v89, v93, v85
	v_fma_f32 v94, -v82, v88, v94
	v_fma_f32 v88, -v83, v88, v95
	v_fma_f32 v76, -v80, v90, v76
	v_fma_f32 v77, -v81, v90, v77
	s_waitcnt lgkmcnt(0)
	v_fma_f32 v78, v91, v78, v86
	v_fma_f32 v79, -v83, v90, v79
	v_fma_f32 v92, v89, v92, v84
	v_mul_f32_e32 v93, 0xbfb8aa3b, v93
	v_fma_f32 v94, v89, v94, v86
	v_fma_f32 v88, v89, v88, v87
	v_fma_f32 v76, v91, v76, v84
	v_fma_f32 v77, v91, v77, v85
	v_mul_f32_e32 v78, 0xbfb8aa3b, v78
	v_fmac_f32_e32 v87, v91, v79
	v_mul_f32_e32 v92, 0xbfb8aa3b, v92
	v_exp_f32_e32 v93, v93
	v_mul_f32_e32 v94, 0xbfb8aa3b, v94
	v_mul_f32_e32 v88, 0xbfb8aa3b, v88
	v_mul_f32_e32 v76, 0xbfb8aa3b, v76
	v_mul_f32_e32 v77, 0xbfb8aa3b, v77
	v_exp_f32_e32 v78, v78
	v_mul_f32_e32 v79, 0xbfb8aa3b, v87
	v_exp_f32_e32 v92, v92
	v_exp_f32_e32 v94, v94
	v_exp_f32_e32 v88, v88
	v_exp_f32_e32 v76, v76
	v_exp_f32_e32 v77, v77
	v_exp_f32_e32 v79, v79
	v_add_f32_e32 v93, 1.0, v93
	v_add_f32_e32 v78, 1.0, v78
	v_add_f32_e32 v92, 1.0, v92
	v_rcp_f32_e32 v89, v93
	v_add_f32_e32 v93, 1.0, v94
	v_add_f32_e32 v88, 1.0, v88
	v_add_f32_e32 v76, 1.0, v76
	v_add_f32_e32 v77, 1.0, v77
	v_rcp_f32_e32 v81, v78
	v_add_f32_e32 v78, 1.0, v79
	v_rcp_f32_e32 v92, v92
	v_rcp_f32_e32 v93, v93
	v_rcp_f32_e32 v80, v88
	v_rcp_f32_e32 v76, v76
	v_rcp_f32_e32 v77, v77
	v_rcp_f32_e32 v82, v78
	v_cvt_pk_bf16_f32 v79, v92, v89
	v_cvt_pk_bf16_f32 v78, v93, v80
	v_cvt_pk_bf16_f32 v77, v76, v77
	v_cvt_pk_bf16_f32 v76, v81, v82
	v_add_u32_e32 v80, 0x24900, v160
	v_add_u32_e32 v84, 0x24d00, v160
	ds_read_b128 v[80:83], v80
	ds_read_b128 v[84:87], v84
	ds_read_b32 v88, v164
	ds_read_b32 v89, v165
	ds_read_b32 v90, v166
	ds_read_b32 v91, v167
	s_waitcnt lgkmcnt(3)
	v_fma_f32 v48, -v80, v88, v48
	v_fma_f32 v49, -v81, v88, v49
	s_waitcnt lgkmcnt(1)
	v_fma_f32 v34, -v82, v90, v34
	v_fma_f32 v50, -v82, v88, v50
	v_fma_f32 v51, -v83, v88, v51
	v_fma_f32 v32, -v80, v90, v32
	v_fma_f32 v33, -v81, v90, v33
	s_waitcnt lgkmcnt(0)
	v_fma_f32 v34, v91, v34, v86
	v_fma_f32 v35, -v83, v90, v35
	v_fma_f32 v48, v89, v48, v84
	v_fma_f32 v49, v89, v49, v85
	v_fma_f32 v50, v89, v50, v86
	v_fma_f32 v51, v89, v51, v87
	v_fma_f32 v32, v91, v32, v84
	v_fma_f32 v33, v91, v33, v85
	v_mul_f32_e32 v34, 0xbfb8aa3b, v34
	v_fmac_f32_e32 v87, v91, v35
	v_mul_f32_e32 v48, 0xbfb8aa3b, v48
	v_mul_f32_e32 v49, 0xbfb8aa3b, v49
	v_mul_f32_e32 v50, 0xbfb8aa3b, v50
	v_mul_f32_e32 v51, 0xbfb8aa3b, v51
	v_mul_f32_e32 v32, 0xbfb8aa3b, v32
	v_mul_f32_e32 v33, 0xbfb8aa3b, v33
	v_exp_f32_e32 v34, v34
	v_mul_f32_e32 v35, 0xbfb8aa3b, v87
	v_exp_f32_e32 v48, v48
	v_exp_f32_e32 v49, v49
	v_exp_f32_e32 v50, v50
	v_exp_f32_e32 v51, v51
	v_exp_f32_e32 v32, v32
	v_exp_f32_e32 v33, v33
	v_exp_f32_e32 v35, v35
	v_add_f32_e32 v34, 1.0, v34
	v_add_f32_e32 v48, 1.0, v48
	v_add_f32_e32 v49, 1.0, v49
	v_add_f32_e32 v50, 1.0, v50
	v_add_f32_e32 v51, 1.0, v51
	v_add_f32_e32 v32, 1.0, v32
	v_add_f32_e32 v33, 1.0, v33
	v_rcp_f32_e32 v80, v34
	v_add_f32_e32 v34, 1.0, v35
	v_rcp_f32_e32 v48, v48
	v_rcp_f32_e32 v49, v49
	v_rcp_f32_e32 v50, v50
	v_rcp_f32_e32 v51, v51
	v_rcp_f32_e32 v32, v32
	v_rcp_f32_e32 v33, v33
	v_rcp_f32_e32 v81, v34
	v_cvt_pk_bf16_f32 v35, v48, v49
	v_cvt_pk_bf16_f32 v34, v50, v51
	v_cvt_pk_bf16_f32 v33, v32, v33
	v_cvt_pk_bf16_f32 v32, v80, v81
	v_add_u32_e32 v48, 0x24920, v160
	v_add_u32_e32 v80, 0x24d20, v160
	ds_read_b128 v[48:51], v48
	ds_read_b128 v[80:83], v80
	ds_read_b32 v84, v164
	ds_read_b32 v85, v165
	ds_read_b32 v86, v166
	ds_read_b32 v87, v167
	s_waitcnt lgkmcnt(3)
	v_fma_f32 v53, -v49, v84, v53
	v_fma_f32 v52, -v48, v84, v52
	s_waitcnt lgkmcnt(1)
	v_fma_f32 v36, -v48, v86, v36
	s_waitcnt lgkmcnt(0)
; DI unsigned pack2(float a, float b) { f32x2_t v = {a, b}; bf16x2_t r = __builtin_convertvector(v, bf16x2_t); return __builtin_bit_cast(unsigned, r); }
; DI float sigmoidf_(float x) { return __builtin_amdgcn_rcpf(1.f + __expf(-x)); }
; template <bool LAST>
; DI void phase_gate(const Params& P, int layer, unsigned char* smem, int L, int G) {
;     ...
;     unsigned gq[4][2][8];
; #pragma unroll
;     for (int i = 0; i < 4; ++i)
; #pragma unroll
;       for (int q4 = 0; q4 < 4; ++q4) {
;         const int fl = wm * 128 + i * 32 + 8 * q4 + 4 * h;
;         const f32x4 c1v = *(const f32x4*)(vecL + fl), c2v = *(const f32x4*)(vecL + 256 + fl);
;         const float c1a[4] = {c1v.x, c1v.y, c1v.z, c1v.w}, c2a[4] = {c2v.x, c2v.y, c2v.z, c2v.w};
; #pragma unroll
;         for (int j = 0; j < 2; ++j) {
;           const int lrow = wn * 64 + j * 32 + r;
;           const float mu = rowA[lrow], rstd = rowB[lrow];
;           float sg4[4];
; #pragma unroll
;           for (int e = 0; e < 4; ++e) sg4[e] = sigmoidf_(rstd * (accu[i][j][4 * q4 + e] - mu * c1a[e]) + c2a[e]);
;           gq[i][j][2 * q4] = pack2(sg4[0], sg4[1]); gq[i][j][2 * q4 + 1] = pack2(sg4[2], sg4[3]);
;         }
;         __builtin_amdgcn_sched_barrier(0);
;       }
	v_fma_f32 v36, v87, v36, v80
	v_fma_f32 v37, -v49, v86, v37
	v_mul_f32_e32 v36, 0xbfb8aa3b, v36
	v_fma_f32 v37, v87, v37, v81
	v_exp_f32_e32 v36, v36
	v_mul_f32_e32 v37, 0xbfb8aa3b, v37
	v_exp_f32_e32 v37, v37
	v_fma_f32 v54, -v50, v84, v54
	v_add_f32_e32 v36, 1.0, v36
	v_rcp_f32_e32 v49, v36
	v_add_f32_e32 v36, 1.0, v37
	v_fma_f32 v37, -v50, v86, v38
	v_fma_f32 v55, -v51, v84, v55
	v_fma_f32 v37, v87, v37, v82
	v_fma_f32 v38, -v51, v86, v39
	v_fma_f32 v52, v85, v52, v80
	v_fma_f32 v53, v85, v53, v81
	v_fma_f32 v54, v85, v54, v82
	v_fma_f32 v55, v85, v55, v83
	v_mul_f32_e32 v37, 0xbfb8aa3b, v37
	v_fmac_f32_e32 v83, v87, v38
	v_mul_f32_e32 v52, 0xbfb8aa3b, v52
	v_mul_f32_e32 v53, 0xbfb8aa3b, v53
	v_mul_f32_e32 v54, 0xbfb8aa3b, v54
	v_mul_f32_e32 v55, 0xbfb8aa3b, v55
	v_exp_f32_e32 v37, v37
	v_mul_f32_e32 v38, 0xbfb8aa3b, v83
	v_exp_f32_e32 v52, v52
	v_exp_f32_e32 v53, v53
	v_exp_f32_e32 v54, v54
	v_exp_f32_e32 v55, v55
	v_exp_f32_e32 v38, v38
	v_rcp_f32_e32 v39, v36
	v_add_f32_e32 v36, 1.0, v37
	v_add_f32_e32 v52, 1.0, v52
	v_add_f32_e32 v53, 1.0, v53
	v_add_f32_e32 v54, 1.0, v54
	v_add_f32_e32 v55, 1.0, v55
	v_rcp_f32_e32 v37, v36
	v_add_f32_e32 v36, 1.0, v38
	v_rcp_f32_e32 v52, v52
	v_rcp_f32_e32 v53, v53
	v_rcp_f32_e32 v54, v54
	v_rcp_f32_e32 v48, v55
	v_rcp_f32_e32 v38, v36
	v_cvt_pk_bf16_f32 v80, v52, v53
	v_cvt_pk_bf16_f32 v55, v49, v39
	v_cvt_pk_bf16_f32 v36, v54, v48
	v_cvt_pk_bf16_f32 v53, v37, v38
	v_add_u32_e32 v37, 0x24940, v160
	v_add_u32_e32 v38, 0x24d40, v160
	ds_read_b128 v[48:51], v37
	ds_read_b128 v[82:85], v38
	ds_read_b32 v37, v164
	ds_read_b32 v38, v165
	ds_read_b32 v39, v166
	ds_read_b32 v52, v167
	s_waitcnt lgkmcnt(3)
	v_fma_f32 v54, -v48, v37, v56
	v_fma_f32 v56, -v49, v37, v57
	s_waitcnt lgkmcnt(2)
	v_fma_f32 v56, v38, v56, v83
	v_fma_f32 v57, -v50, v37, v58
	v_fma_f32 v37, -v51, v37, v59
	s_waitcnt lgkmcnt(1)
	v_fma_f32 v40, -v48, v39, v40
	v_fma_f32 v41, -v49, v39, v41
	v_fma_f32 v42, -v50, v39, v42
	v_fma_f32 v39, -v51, v39, v43
	v_fma_f32 v54, v38, v54, v82
	v_mul_f32_e32 v56, 0xbfb8aa3b, v56
	v_fma_f32 v57, v38, v57, v84
	v_fma_f32 v37, v38, v37, v85
	s_waitcnt lgkmcnt(0)
	v_fma_f32 v40, v52, v40, v82
	v_fma_f32 v41, v52, v41, v83
	v_fma_f32 v42, v52, v42, v84
	v_fmac_f32_e32 v85, v52, v39
	v_mul_f32_e32 v54, 0xbfb8aa3b, v54
	v_exp_f32_e32 v56, v56
	v_mul_f32_e32 v57, 0xbfb8aa3b, v57
	v_mul_f32_e32 v37, 0xbfb8aa3b, v37
	v_mul_f32_e32 v40, 0xbfb8aa3b, v40
	v_mul_f32_e32 v41, 0xbfb8aa3b, v41
	v_mul_f32_e32 v42, 0xbfb8aa3b, v42
	v_mul_f32_e32 v39, 0xbfb8aa3b, v85
	v_exp_f32_e32 v54, v54
	v_exp_f32_e32 v57, v57
	v_exp_f32_e32 v37, v37
	v_exp_f32_e32 v40, v40
	v_exp_f32_e32 v41, v41
	v_exp_f32_e32 v42, v42
	v_exp_f32_e32 v39, v39
	v_add_f32_e32 v56, 1.0, v56
	v_add_f32_e32 v54, 1.0, v54
	v_rcp_f32_e32 v38, v56
	v_add_f32_e32 v56, 1.0, v57
	v_add_f32_e32 v37, 1.0, v37
	v_add_f32_e32 v40, 1.0, v40
	v_add_f32_e32 v41, 1.0, v41
	v_add_f32_e32 v42, 1.0, v42
	v_add_f32_e32 v39, 1.0, v39
	v_rcp_f32_e32 v54, v54
	v_rcp_f32_e32 v56, v56
	v_rcp_f32_e32 v37, v37
	v_rcp_f32_e32 v40, v40
	v_rcp_f32_e32 v41, v41
	v_rcp_f32_e32 v42, v42
	v_rcp_f32_e32 v39, v39
	v_cvt_pk_bf16_f32 v83, v54, v38
	v_cvt_pk_bf16_f32 v82, v56, v37
	v_cvt_pk_bf16_f32 v81, v40, v41
	v_cvt_pk_bf16_f32 v59, v42, v39
	v_add_u32_e32 v37, 0x24960, v160
	v_add_u32_e32 v42, 0x24d60, v160
	ds_read_b128 v[38:41], v37
	ds_read_b128 v[48:51], v42
	ds_read_b32 v37, v164
	ds_read_b32 v42, v165
	ds_read_b32 v43, v166
	ds_read_b32 v52, v167
	s_waitcnt lgkmcnt(3)
	v_fma_f32 v56, -v39, v37, v61
	v_fma_f32 v54, -v38, v37, v60
	s_waitcnt lgkmcnt(2)
	v_fma_f32 v56, v42, v56, v49
	v_fma_f32 v57, -v40, v37, v62
	v_fma_f32 v37, -v41, v37, v63
	s_waitcnt lgkmcnt(1)
	v_fma_f32 v38, -v38, v43, v44
	v_fma_f32 v39, -v39, v43, v45
	v_fma_f32 v40, -v40, v43, v46
	v_fma_f32 v41, -v41, v43, v47
	v_fma_f32 v54, v42, v54, v48
	v_mul_f32_e32 v56, 0xbfb8aa3b, v56
	v_fma_f32 v57, v42, v57, v50
	v_fma_f32 v37, v42, v37, v51
	s_waitcnt lgkmcnt(0)
	v_fma_f32 v38, v52, v38, v48
	v_fma_f32 v39, v52, v39, v49
	v_fma_f32 v40, v52, v40, v50
	v_fmac_f32_e32 v51, v52, v41
	v_mul_f32_e32 v54, 0xbfb8aa3b, v54
	v_exp_f32_e32 v56, v56
	v_mul_f32_e32 v57, 0xbfb8aa3b, v57
	v_mul_f32_e32 v37, 0xbfb8aa3b, v37
	v_mul_f32_e32 v38, 0xbfb8aa3b, v38
	v_mul_f32_e32 v39, 0xbfb8aa3b, v39
	v_mul_f32_e32 v40, 0xbfb8aa3b, v40
	v_mul_f32_e32 v41, 0xbfb8aa3b, v51
	v_exp_f32_e32 v54, v54
	v_exp_f32_e32 v57, v57
	v_exp_f32_e32 v37, v37
	v_exp_f32_e32 v38, v38
	v_exp_f32_e32 v39, v39
	v_exp_f32_e32 v40, v40
	v_exp_f32_e32 v41, v41
	v_add_f32_e32 v56, 1.0, v56
	v_add_f32_e32 v54, 1.0, v54
	v_rcp_f32_e32 v42, v56
	v_add_f32_e32 v56, 1.0, v57
	v_add_f32_e32 v37, 1.0, v37
	v_add_f32_e32 v38, 1.0, v38
	v_add_f32_e32 v39, 1.0, v39
	v_add_f32_e32 v40, 1.0, v40
	v_add_f32_e32 v41, 1.0, v41
	v_rcp_f32_e32 v54, v54
	v_rcp_f32_e32 v56, v56
	v_rcp_f32_e32 v37, v37
	v_rcp_f32_e32 v38, v38
	v_rcp_f32_e32 v39, v39
	v_rcp_f32_e32 v40, v40
	v_rcp_f32_e32 v41, v41
	v_cvt_pk_bf16_f32 v91, v54, v42
	v_cvt_pk_bf16_f32 v86, v56, v37
	v_cvt_pk_bf16_f32 v85, v38, v39
	v_cvt_pk_bf16_f32 v84, v40, v41
	v_add_u32_e32 v37, 0x24980, v160
	v_add_u32_e32 v42, 0x24d80, v160
	ds_read_b128 v[38:41], v37
	ds_read_b128 v[42:45], v42
	ds_read_b32 v37, v164
	ds_read_b32 v46, v165
	ds_read_b32 v47, v166
	ds_read_b32 v48, v167
	s_waitcnt lgkmcnt(3)
	v_fma_f32 v16, -v38, v37, v16
	v_fma_f32 v17, -v39, v37, v17
	v_fma_f32 v18, -v40, v37, v18
	v_fma_f32 v19, -v41, v37, v19
	s_waitcnt lgkmcnt(1)
	v_fma_f32 v0, -v38, v47, v0
	v_fma_f32 v1, -v39, v47, v1
	v_fma_f32 v2, -v40, v47, v2
	v_fma_f32 v3, -v41, v47, v3
	v_fma_f32 v16, v46, v16, v42
	v_fma_f32 v17, v46, v17, v43
	v_fma_f32 v18, v46, v18, v44
	v_fma_f32 v19, v46, v19, v45
	s_waitcnt lgkmcnt(0)
; DI unsigned pack2(float a, float b) { f32x2_t v = {a, b}; bf16x2_t r = __builtin_convertvector(v, bf16x2_t); return __builtin_bit_cast(unsigned, r); }
; DI float sigmoidf_(float x) { return __builtin_amdgcn_rcpf(1.f + __expf(-x)); }
; template <bool LAST>
; DI void phase_gate(const Params& P, int layer, unsigned char* smem, int L, int G) {
;     ...
;     unsigned gq[4][2][8];
; #pragma unroll
;     for (int i = 0; i < 4; ++i)
; #pragma unroll
;       for (int q4 = 0; q4 < 4; ++q4) {
;         const int fl = wm * 128 + i * 32 + 8 * q4 + 4 * h;
;         const f32x4 c1v = *(const f32x4*)(vecL + fl), c2v = *(const f32x4*)(vecL + 256 + fl);
;         const float c1a[4] = {c1v.x, c1v.y, c1v.z, c1v.w}, c2a[4] = {c2v.x, c2v.y, c2v.z, c2v.w};
; #pragma unroll
;         for (int j = 0; j < 2; ++j) {
;           const int lrow = wn * 64 + j * 32 + r;
;           const float mu = rowA[lrow], rstd = rowB[lrow];
;           float sg4[4];
; #pragma unroll
;           for (int e = 0; e < 4; ++e) sg4[e] = sigmoidf_(rstd * (accu[i][j][4 * q4 + e] - mu * c1a[e]) + c2a[e]);
;           gq[i][j][2 * q4] = pack2(sg4[0], sg4[1]); gq[i][j][2 * q4 + 1] = pack2(sg4[2], sg4[3]);
;         }
;         __builtin_amdgcn_sched_barrier(0);
;       }
	v_fma_f32 v0, v48, v0, v42
	v_fma_f32 v1, v48, v1, v43
	v_fma_f32 v2, v48, v2, v44
	v_fmac_f32_e32 v45, v48, v3
	v_mul_f32_e32 v16, 0xbfb8aa3b, v16
	v_mul_f32_e32 v17, 0xbfb8aa3b, v17
	v_mul_f32_e32 v18, 0xbfb8aa3b, v18
	v_mul_f32_e32 v19, 0xbfb8aa3b, v19
	v_mul_f32_e32 v0, 0xbfb8aa3b, v0
	v_mul_f32_e32 v1, 0xbfb8aa3b, v1
	v_mul_f32_e32 v2, 0xbfb8aa3b, v2
	v_mul_f32_e32 v3, 0xbfb8aa3b, v45
	v_exp_f32_e32 v16, v16
	v_exp_f32_e32 v17, v17
	v_exp_f32_e32 v18, v18
	v_exp_f32_e32 v19, v19
	v_exp_f32_e32 v0, v0
	v_exp_f32_e32 v1, v1
	v_exp_f32_e32 v2, v2
	v_exp_f32_e32 v3, v3
	v_add_f32_e32 v16, 1.0, v16
	v_add_f32_e32 v17, 1.0, v17
	v_add_f32_e32 v18, 1.0, v18
	v_add_f32_e32 v19, 1.0, v19
	v_add_f32_e32 v0, 1.0, v0
	v_add_f32_e32 v1, 1.0, v1
	v_add_f32_e32 v2, 1.0, v2
	v_add_f32_e32 v3, 1.0, v3
	v_rcp_f32_e32 v16, v16
	v_rcp_f32_e32 v17, v17
	v_rcp_f32_e32 v18, v18
	v_rcp_f32_e32 v19, v19
	v_rcp_f32_e32 v0, v0
	v_rcp_f32_e32 v1, v1
	v_rcp_f32_e32 v2, v2
	v_rcp_f32_e32 v37, v3
	v_cvt_pk_bf16_f32 v17, v16, v17
	v_cvt_pk_bf16_f32 v16, v18, v19
	v_cvt_pk_bf16_f32 v3, v0, v1
	v_cvt_pk_bf16_f32 v2, v2, v37
	v_add_u32_e32 v0, 0x249a0, v160
	v_add_u32_e32 v1, 0x24da0, v160
	ds_read_b128 v[38:41], v0
	ds_read_b128 v[42:45], v1
	ds_read_b32 v0, v164
	ds_read_b32 v1, v165
	ds_read_b32 v18, v166
	ds_read_b32 v19, v167
	s_waitcnt lgkmcnt(3)
	v_fma_f32 v21, -v39, v0, v21
	v_fma_f32 v20, -v38, v0, v20
	s_waitcnt lgkmcnt(1)
	v_fma_f32 v6, -v40, v18, v6
	v_fma_f32 v21, v1, v21, v43
	v_fma_f32 v22, -v40, v0, v22
	v_fma_f32 v0, -v41, v0, v23
	v_fma_f32 v4, -v38, v18, v4
	v_fma_f32 v5, -v39, v18, v5
	s_waitcnt lgkmcnt(0)
	v_fma_f32 v6, v19, v6, v44
	v_fma_f32 v7, -v41, v18, v7
	v_fma_f32 v20, v1, v20, v42
	v_mul_f32_e32 v21, 0xbfb8aa3b, v21
	v_fma_f32 v22, v1, v22, v44
	v_fma_f32 v0, v1, v0, v45
	v_fma_f32 v4, v19, v4, v42
	v_fma_f32 v5, v19, v5, v43
	v_mul_f32_e32 v6, 0xbfb8aa3b, v6
	v_fmac_f32_e32 v45, v19, v7
	v_mul_f32_e32 v20, 0xbfb8aa3b, v20
	v_exp_f32_e32 v21, v21
	v_mul_f32_e32 v22, 0xbfb8aa3b, v22
	v_mul_f32_e32 v0, 0xbfb8aa3b, v0
	v_mul_f32_e32 v4, 0xbfb8aa3b, v4
	v_mul_f32_e32 v5, 0xbfb8aa3b, v5
	v_exp_f32_e32 v6, v6
	v_mul_f32_e32 v7, 0xbfb8aa3b, v45
	v_exp_f32_e32 v20, v20
	v_exp_f32_e32 v22, v22
	v_exp_f32_e32 v0, v0
	v_exp_f32_e32 v4, v4
	v_exp_f32_e32 v5, v5
	v_exp_f32_e32 v7, v7
	v_add_f32_e32 v21, 1.0, v21
	v_add_f32_e32 v6, 1.0, v6
	v_add_f32_e32 v20, 1.0, v20
	v_rcp_f32_e32 v1, v21
	v_add_f32_e32 v21, 1.0, v22
	v_add_f32_e32 v0, 1.0, v0
	v_add_f32_e32 v4, 1.0, v4
	v_add_f32_e32 v5, 1.0, v5
	v_rcp_f32_e32 v18, v6
	v_add_f32_e32 v6, 1.0, v7
	v_rcp_f32_e32 v20, v20
	v_rcp_f32_e32 v21, v21
	v_rcp_f32_e32 v0, v0
	v_rcp_f32_e32 v4, v4
	v_rcp_f32_e32 v5, v5
	v_rcp_f32_e32 v19, v6
	v_cvt_pk_bf16_f32 v7, v20, v1
	v_cvt_pk_bf16_f32 v6, v21, v0
	v_cvt_pk_bf16_f32 v5, v4, v5
	v_cvt_pk_bf16_f32 v4, v18, v19
	v_add_u32_e32 v0, 0x249c0, v160
	v_add_u32_e32 v1, 0x24dc0, v160
	ds_read_b128 v[18:21], v0
	ds_read_b128 v[38:41], v1
	ds_read_b32 v0, v164
	ds_read_b32 v1, v165
	ds_read_b32 v22, v166
	ds_read_b32 v23, v167
	s_waitcnt lgkmcnt(3)
	v_fma_f32 v25, -v19, v0, v25
	v_fma_f32 v24, -v18, v0, v24
	s_waitcnt lgkmcnt(1)
	v_fma_f32 v9, -v19, v22, v9
	s_waitcnt lgkmcnt(0)
	v_fma_f32 v9, v23, v9, v39
	v_fma_f32 v10, -v20, v22, v10
	v_fma_f32 v25, v1, v25, v39
	v_fma_f32 v26, -v20, v0, v26
	v_fma_f32 v0, -v21, v0, v27
	v_fma_f32 v8, -v18, v22, v8
	v_mul_f32_e32 v9, 0xbfb8aa3b, v9
	v_fma_f32 v10, v23, v10, v40
	v_fma_f32 v11, -v21, v22, v11
	v_fma_f32 v24, v1, v24, v38
	v_mul_f32_e32 v25, 0xbfb8aa3b, v25
	v_fma_f32 v26, v1, v26, v40
	v_fma_f32 v0, v1, v0, v41
	v_fma_f32 v8, v23, v8, v38
	v_exp_f32_e32 v9, v9
	v_mul_f32_e32 v10, 0xbfb8aa3b, v10
	v_fmac_f32_e32 v41, v23, v11
	v_mul_f32_e32 v24, 0xbfb8aa3b, v24
	v_exp_f32_e32 v25, v25
	v_mul_f32_e32 v26, 0xbfb8aa3b, v26
	v_mul_f32_e32 v0, 0xbfb8aa3b, v0
	v_mul_f32_e32 v8, 0xbfb8aa3b, v8
	v_exp_f32_e32 v10, v10
	v_mul_f32_e32 v11, 0xbfb8aa3b, v41
	v_exp_f32_e32 v24, v24
	v_exp_f32_e32 v26, v26
	v_exp_f32_e32 v0, v0
	v_exp_f32_e32 v8, v8
	v_exp_f32_e32 v11, v11
	v_add_f32_e32 v9, 1.0, v9
	v_add_f32_e32 v25, 1.0, v25
	v_rcp_f32_e32 v18, v9
	v_add_f32_e32 v9, 1.0, v10
	v_add_f32_e32 v24, 1.0, v24
	v_rcp_f32_e32 v1, v25
	v_add_f32_e32 v25, 1.0, v26
	v_add_f32_e32 v0, 1.0, v0
	v_add_f32_e32 v8, 1.0, v8
	v_rcp_f32_e32 v10, v9
	v_add_f32_e32 v9, 1.0, v11
	v_rcp_f32_e32 v24, v24
	v_rcp_f32_e32 v25, v25
	v_rcp_f32_e32 v0, v0
	v_rcp_f32_e32 v8, v8
	v_rcp_f32_e32 v11, v9
	v_cvt_pk_bf16_f32 v27, v24, v1
	v_cvt_pk_bf16_f32 v9, v25, v0
	v_cvt_pk_bf16_f32 v19, v8, v18
	v_cvt_pk_bf16_f32 v8, v10, v11
	v_add_u32_e32 v0, 0x24de0, v160
	ds_read_b128 v[20:23], v163 offset:480
	ds_read_b32 v1, v164
	ds_read_b128 v[38:41], v0
	ds_read_b32 v0, v165
	ds_read_b32 v10, v166
	ds_read_b32 v18, v167
	s_waitcnt lgkmcnt(4)
	v_fma_f32 v24, -v21, v1, v29
	v_fma_f32 v11, -v20, v1, v28
	s_waitcnt lgkmcnt(2)
	v_fma_f32 v24, v0, v24, v39
	v_fma_f32 v25, -v22, v1, v30
	v_fma_f32 v1, -v23, v1, v31
	s_waitcnt lgkmcnt(1)
	v_fma_f32 v12, -v20, v10, v12
	v_fma_f32 v13, -v21, v10, v13
	v_fma_f32 v14, -v22, v10, v14
	v_fma_f32 v10, -v23, v10, v15
	v_fma_f32 v11, v0, v11, v38
	v_mul_f32_e32 v24, 0xbfb8aa3b, v24
	v_fma_f32 v25, v0, v25, v40
	v_fma_f32 v0, v0, v1, v41
	s_waitcnt lgkmcnt(0)
; DI unsigned pack2(float a, float b) { f32x2_t v = {a, b}; bf16x2_t r = __builtin_convertvector(v, bf16x2_t); return __builtin_bit_cast(unsigned, r); }
; DI float sigmoidf_(float x) { return __builtin_amdgcn_rcpf(1.f + __expf(-x)); }
; DI int otid() { int t = threadIdx.x; asm volatile("" : "+v"(t)); return t; }
; template <bool NT>
; DI void stage_load_tile(bf16_t* stg, const bf16_t* tilebase) {
;   const int tid = otid();
;   const int r0 = tid >> 5, c = tid & 31;
;   const unsigned o0 = (unsigned)(r0 * 1024 + c * 8);
;   __builtin_amdgcn_sched_barrier(0);
; #pragma unroll
;   for (int hf = 0; hf < 2; ++hf) {
; #pragma unroll
;     for (int it = 8 * hf; it < 8 * hf + 8; ++it) {
;       const u32x4* gp = (const u32x4*)(tilebase + (o0 + (unsigned)(it * 16 * 1024)));
;       stage_write16(stg, r0 + 16 * it, c, NT ? __builtin_nontemporal_load(gp) : *gp);
;     }
;     __builtin_amdgcn_sched_barrier(0);
;   }
; }
; template <bool LAST>
; DI void phase_gate(const Params& P, int layer, unsigned char* smem, int L, int G) {
;     ...
;           for (int e = 0; e < 4; ++e) sg4[e] = sigmoidf_(rstd * (accu[i][j][4 * q4 + e] - mu * c1a[e]) + c2a[e]);
;           gq[i][j][2 * q4] = pack2(sg4[0], sg4[1]); gq[i][j][2 * q4 + 1] = pack2(sg4[2], sg4[3]);
;         }
;         __builtin_amdgcn_sched_barrier(0);
;       }
;     stage_load_tile<true>(stg, PPb + (size_t)mt * 256 * 1024 + nt * 256);
	v_fma_f32 v12, v18, v12, v38
	v_fma_f32 v13, v18, v13, v39
	v_fma_f32 v14, v18, v14, v40
	v_fmac_f32_e32 v41, v18, v10
	v_mul_f32_e32 v11, 0xbfb8aa3b, v11
	v_exp_f32_e32 v24, v24
	v_mul_f32_e32 v25, 0xbfb8aa3b, v25
	v_mul_f32_e32 v0, 0xbfb8aa3b, v0
	v_mul_f32_e32 v12, 0xbfb8aa3b, v12
	v_mul_f32_e32 v13, 0xbfb8aa3b, v13
	v_mul_f32_e32 v14, 0xbfb8aa3b, v14
	v_mul_f32_e32 v10, 0xbfb8aa3b, v41
	v_exp_f32_e32 v11, v11
	v_exp_f32_e32 v25, v25
	v_exp_f32_e32 v0, v0
	v_exp_f32_e32 v12, v12
	v_exp_f32_e32 v13, v13
	v_exp_f32_e32 v14, v14
	v_exp_f32_e32 v10, v10
	v_add_f32_e32 v24, 1.0, v24
	v_add_f32_e32 v11, 1.0, v11
	v_rcp_f32_e32 v1, v24
	v_add_f32_e32 v24, 1.0, v25
	v_add_f32_e32 v0, 1.0, v0
	v_add_f32_e32 v12, 1.0, v12
	v_add_f32_e32 v13, 1.0, v13
	v_add_f32_e32 v14, 1.0, v14
	v_add_f32_e32 v10, 1.0, v10
	v_rcp_f32_e32 v11, v11
	v_rcp_f32_e32 v24, v24
	v_rcp_f32_e32 v0, v0
	v_rcp_f32_e32 v12, v12
	v_rcp_f32_e32 v13, v13
	v_rcp_f32_e32 v14, v14
	v_rcp_f32_e32 v10, v10
	v_cvt_pk_bf16_f32 v112, v11, v1
	v_cvt_pk_bf16_f32 v30, v24, v0
	v_cvt_pk_bf16_f32 v29, v12, v13
	v_cvt_pk_bf16_f32 v28, v14, v10
	s_ashr_i32 s25, s24, 31
	s_lshl_b64 s[24:25], s[24:25], 19
	v_mov_b32_e32 v10, v192
	s_add_u32 s26, s66, s24
	v_mov_b32_e32 v163, v161
	s_addc_u32 s27, s67, s25
	v_and_b32_e32 v26, 31, v10
	v_lshlrev_b64 v[0:1], 1, v[162:163]
	v_ashrrev_i32_e32 v18, 5, v10
	v_lshlrev_b32_e32 v10, 3, v26
	v_lshl_add_u64 v[14:15], s[26:27], 0, v[0:1]
	v_lshl_or_b32 v160, v18, 10, v10
	v_add_u32_e32 v12, 0x4000, v160
	v_mov_b32_e32 v13, v161
	v_add_u32_e32 v24, 0x8000, v160
	v_mov_b32_e32 v25, v161
	v_add_u32_e32 v38, 0xc000, v160
	v_mov_b32_e32 v39, v161
	v_lshl_add_u64 v[10:11], v[160:161], 1, v[14:15]
	v_lshl_add_u64 v[20:21], v[12:13], 1, v[14:15]
	v_lshl_add_u64 v[24:25], v[24:25], 1, v[14:15]
	v_lshl_add_u64 v[42:43], v[38:39], 1, v[14:15]
	global_load_dwordx4 v[10:13], v[10:11], off nt
	s_nop 0
	global_load_dwordx4 v[20:23], v[20:21], off nt
	s_nop 0
	global_load_dwordx4 v[38:41], v[24:25], off nt
	s_nop 0
	global_load_dwordx4 v[42:45], v[42:43], off nt
	v_add_u32_e32 v24, 0x10000, v160
	v_mov_b32_e32 v25, v161
	v_lshl_add_u64 v[24:25], v[24:25], 1, v[14:15]
	v_add_u32_e32 v46, 0x14000, v160
	v_mov_b32_e32 v47, v161
	v_lshl_add_u64 v[50:51], v[46:47], 1, v[14:15]
	global_load_dwordx4 v[46:49], v[24:25], off nt
	global_load_dwordx4 v[60:63], v[50:51], off nt
	v_add_u32_e32 v24, 0x18000, v160
	v_mov_b32_e32 v25, v161
	v_lshl_add_u64 v[24:25], v[24:25], 1, v[14:15]
	v_add_u32_e32 v50, 0x1c000, v160
	v_mov_b32_e32 v51, v161
	v_lshl_add_u64 v[50:51], v[50:51], 1, v[14:15]
	global_load_dwordx4 v[92:95], v[24:25], off nt
	global_load_dwordx4 v[114:117], v[50:51], off nt
	v_add_u32_e32 v218, 0x20000, v160
	v_mov_b32_e32 v219, v161
	v_add_u32_e32 v220, 0x24000, v160
	v_mov_b32_e32 v221, v161
	v_add_u32_e32 v252, 0x28000, v160
	v_mov_b32_e32 v253, v161
	v_add_u32_e32 v226, 0x2c000, v160
	v_mov_b32_e32 v227, v161
	v_lshl_add_u64 v[218:219], v[218:219], 1, v[14:15]
	v_lshl_add_u64 v[222:223], v[220:221], 1, v[14:15]
	v_lshl_add_u64 v[252:253], v[252:253], 1, v[14:15]
	v_lshl_add_u64 v[230:231], v[226:227], 1, v[14:15]
	global_load_dwordx4 v[218:221], v[218:219], off nt
	s_nop 0
	global_load_dwordx4 v[222:225], v[222:223], off nt
	s_nop 0
	global_load_dwordx4 v[226:229], v[252:253], off nt
	s_nop 0
	global_load_dwordx4 v[230:233], v[230:231], off nt
	v_add_u32_e32 v252, 0x30000, v160
	v_mov_b32_e32 v253, v161
	v_lshl_add_u64 v[252:253], v[252:253], 1, v[14:15]
	v_add_u32_e32 v234, 0x34000, v160
	v_mov_b32_e32 v235, v161
	v_lshl_add_u64 v[254:255], v[234:235], 1, v[14:15]
	global_load_dwordx4 v[234:237], v[252:253], off nt
	global_load_dwordx4 v[238:241], v[254:255], off nt
	v_add_u32_e32 v252, 0x38000, v160
	v_mov_b32_e32 v253, v161
	v_lshl_add_u64 v[252:253], v[252:253], 1, v[14:15]
	v_add_u32_e32 v160, 0x3c000, v160
	v_lshl_add_u64 v[190:191], v[160:161], 1, v[14:15]
	global_load_dwordx4 v[242:245], v[252:253], off nt
	global_load_dwordx4 v[248:251], v[190:191], off nt
	v_mul_lo_u32 v18, v18, s40
	v_lshl_add_u32 v18, v26, 4, v18
	v_add_u32_e32 v24, 0x2080, v18
	v_add_u32_e32 v25, 0x4100, v18
	v_add_u32_e32 v26, 0x6180, v18
	v_add_u32_e32 v31, 0x8200, v18
	v_add_u32_e32 v37, 0xa280, v18
	v_add_u32_e32 v50, 0xc300, v18
	v_add_u32_e32 v51, 0xe380, v18
	s_waitcnt vmcnt(15)
	ds_write2_b64 v18, v[10:11], v[12:13] offset1:1
	s_waitcnt vmcnt(14)
	ds_write2_b64 v24, v[20:21], v[22:23] offset1:1
	s_waitcnt vmcnt(13)
	ds_write2_b64 v25, v[38:39], v[40:41] offset1:1
	s_waitcnt vmcnt(12)
	ds_write2_b64 v26, v[42:43], v[44:45] offset1:1
	s_waitcnt vmcnt(11)
	ds_write2_b64 v31, v[46:47], v[48:49] offset1:1
	s_waitcnt vmcnt(10)
	ds_write2_b64 v37, v[60:61], v[62:63] offset1:1
	s_waitcnt vmcnt(9)
	ds_write2_b64 v50, v[92:93], v[94:95] offset1:1
	s_waitcnt vmcnt(8)
	ds_write2_b64 v51, v[114:115], v[116:117] offset1:1
	v_add_u32_e32 v14, 0x10400, v18
	v_add_u32_e32 v15, 0x12480, v18
	v_add_u32_e32 v24, 0x14500, v18
	v_add_u32_e32 v25, 0x16580, v18
	v_add_u32_e32 v26, 0x18600, v18
	v_add_u32_e32 v31, 0x1a680, v18
	v_add_u32_e32 v37, 0x1c700, v18
	v_add_u32_e32 v18, 0x1e780, v18
	s_waitcnt vmcnt(7)
	ds_write2_b64 v14, v[218:219], v[220:221] offset1:1
	s_waitcnt vmcnt(6)
	ds_write2_b64 v15, v[222:223], v[224:225] offset1:1
	s_waitcnt vmcnt(5)
	ds_write2_b64 v24, v[226:227], v[228:229] offset1:1
	s_waitcnt vmcnt(4)
	ds_write2_b64 v25, v[230:231], v[232:233] offset1:1
	s_waitcnt vmcnt(3)
	ds_write2_b64 v26, v[234:235], v[236:237] offset1:1
	s_waitcnt vmcnt(2)
	ds_write2_b64 v31, v[238:239], v[240:241] offset1:1
	s_waitcnt vmcnt(1)
	ds_write2_b64 v37, v[242:243], v[244:245] offset1:1
	s_waitcnt vmcnt(0)
	ds_write2_b64 v18, v[248:249], v[250:251] offset1:1
	v_mov_b32_e32 v10, v192
	s_waitcnt lgkmcnt(0)
	s_barrier
; DI unsigned pack2(float a, float b) { f32x2_t v = {a, b}; bf16x2_t r = __builtin_convertvector(v, bf16x2_t); return __builtin_bit_cast(unsigned, r); }
; DI float bflo(unsigned u) { return __uint_as_float(u << 16); }
; DI float bfhi(unsigned u) { return __uint_as_float(u & 0xffff0000u); }
; DI int otid() { int t = threadIdx.x; asm volatile("" : "+v"(t)); return t; }
; template <bool LAST>
; DI void phase_gate(const Params& P, int layer, unsigned char* smem, int L, int G) {
;     ...
;     {
;       const int tid1 = otid();
;       const int lane1 = tid1 & 63, w1 = tid1 >> 6, r1 = lane1 & 31, h1 = lane1 >> 5, wm1 = w1 >> 2, wn1 = w1 & 3;
; #pragma unroll
;       for (int i = 0; i < 4; ++i)
; #pragma unroll
;         for (int q4 = 0; q4 < 4; ++q4) {
; #pragma unroll
;           for (int j = 0; j < 2; ++j) {
;             const uint2 pv = *(const uint2*)(stg + (wn1 * 64 + j * 32 + r1) * STG + wm1 * 128 + i * 32 + 8 * q4 + 4 * h1);
;             const unsigned g0 = gq[i][j][2 * q4], g1 = gq[i][j][2 * q4 + 1];
;             gq[i][j][2 * q4] = pack2(bflo(g0) * bflo(pv.x), bfhi(g0) * bfhi(pv.x));
;             gq[i][j][2 * q4 + 1] = pack2(bflo(g1) * bflo(pv.y), bfhi(g1) * bfhi(pv.y));
;           }
;           __builtin_amdgcn_sched_barrier(0);
;         }
;     }
	v_and_b32_e32 v13, 0xffff0000, v99
	v_lshrrev_b32_e32 v12, 2, v10
	v_and_b32_e32 v12, 8, v12
	v_and_b32_e32 v11, 0xdf, v10
	v_and_or_b32 v10, v10, s38, v12
	v_mad_u32_u24 v113, v11, s40, v10
	ds_read_b64 v[10:11], v113
	ds_read_b64 v[14:15], v113 offset:16640
	v_lshlrev_b32_e32 v12, 16, v99
	s_waitcnt lgkmcnt(1)
	v_lshlrev_b32_e32 v20, 16, v10
	v_and_b32_e32 v21, 0xffff0000, v10
	v_pk_mul_f32 v[12:13], v[12:13], v[20:21]
	v_lshlrev_b32_e32 v10, 16, v11
	v_cvt_pk_bf16_f32 v31, v12, v13
	v_lshlrev_b32_e32 v12, 16, v98
	v_and_b32_e32 v13, 0xffff0000, v98
	v_and_b32_e32 v11, 0xffff0000, v11
	v_pk_mul_f32 v[10:11], v[12:13], v[10:11]
	s_waitcnt lgkmcnt(0)
	v_lshlrev_b32_e32 v12, 16, v14
	v_cvt_pk_bf16_f32 v98, v10, v11
	v_lshlrev_b32_e32 v10, 16, v97
	v_and_b32_e32 v11, 0xffff0000, v97
	v_and_b32_e32 v13, 0xffff0000, v14
	v_pk_mul_f32 v[10:11], v[10:11], v[12:13]
	v_lshlrev_b32_e32 v12, 16, v15
	v_cvt_pk_bf16_f32 v97, v10, v11
	v_lshlrev_b32_e32 v10, 16, v96
	v_and_b32_e32 v11, 0xffff0000, v96
	v_and_b32_e32 v13, 0xffff0000, v15
	v_pk_mul_f32 v[10:11], v[10:11], v[12:13]
	s_nop 0
	v_cvt_pk_bf16_f32 v96, v10, v11
	ds_read_b64 v[10:11], v113 offset:16
	ds_read_b64 v[14:15], v113 offset:16656
	v_lshlrev_b32_e32 v12, 16, v103
	v_and_b32_e32 v13, 0xffff0000, v103
	s_waitcnt lgkmcnt(1)
	v_lshlrev_b32_e32 v20, 16, v10
	v_and_b32_e32 v21, 0xffff0000, v10
	v_pk_mul_f32 v[12:13], v[12:13], v[20:21]
	v_lshlrev_b32_e32 v10, 16, v11
	v_cvt_pk_bf16_f32 v93, v12, v13
	v_lshlrev_b32_e32 v12, 16, v102
	v_and_b32_e32 v13, 0xffff0000, v102
	v_and_b32_e32 v11, 0xffff0000, v11
	v_pk_mul_f32 v[10:11], v[12:13], v[10:11]
	s_waitcnt lgkmcnt(0)
	v_lshlrev_b32_e32 v12, 16, v14
	v_cvt_pk_bf16_f32 v95, v10, v11
	v_lshlrev_b32_e32 v10, 16, v101
	v_and_b32_e32 v11, 0xffff0000, v101
	v_and_b32_e32 v13, 0xffff0000, v14
	v_pk_mul_f32 v[10:11], v[10:11], v[12:13]
	v_lshlrev_b32_e32 v12, 16, v15
	v_cvt_pk_bf16_f32 v92, v10, v11
	v_lshlrev_b32_e32 v10, 16, v100
	v_and_b32_e32 v11, 0xffff0000, v100
	v_and_b32_e32 v13, 0xffff0000, v15
	v_pk_mul_f32 v[10:11], v[10:11], v[12:13]
	s_nop 0
	v_cvt_pk_bf16_f32 v94, v10, v11
	ds_read_b64 v[10:11], v113 offset:32
	ds_read_b64 v[14:15], v113 offset:16672
	v_lshlrev_b32_e32 v12, 16, v107
	v_and_b32_e32 v13, 0xffff0000, v107
	s_waitcnt lgkmcnt(1)
	v_lshlrev_b32_e32 v20, 16, v10
	v_and_b32_e32 v21, 0xffff0000, v10
	v_pk_mul_f32 v[12:13], v[12:13], v[20:21]
	v_lshlrev_b32_e32 v10, 16, v11
	v_cvt_pk_bf16_f32 v88, v12, v13
	v_lshlrev_b32_e32 v12, 16, v106
	v_and_b32_e32 v13, 0xffff0000, v106
	v_and_b32_e32 v11, 0xffff0000, v11
	v_pk_mul_f32 v[10:11], v[12:13], v[10:11]
	s_waitcnt lgkmcnt(0)
	v_lshlrev_b32_e32 v12, 16, v14
	v_cvt_pk_bf16_f32 v90, v10, v11
	v_lshlrev_b32_e32 v10, 16, v105
	v_and_b32_e32 v11, 0xffff0000, v105
	v_and_b32_e32 v13, 0xffff0000, v14
	v_pk_mul_f32 v[10:11], v[10:11], v[12:13]
	v_lshlrev_b32_e32 v12, 16, v15
	v_cvt_pk_bf16_f32 v87, v10, v11
	v_lshlrev_b32_e32 v10, 16, v104
	v_and_b32_e32 v11, 0xffff0000, v104
	v_and_b32_e32 v13, 0xffff0000, v15
	v_pk_mul_f32 v[10:11], v[10:11], v[12:13]
	s_nop 0
	v_cvt_pk_bf16_f32 v89, v10, v11
	ds_read_b64 v[10:11], v113 offset:48
	ds_read_b64 v[14:15], v113 offset:16688
	v_lshlrev_b32_e32 v12, 16, v111
	v_and_b32_e32 v13, 0xffff0000, v111
	s_waitcnt lgkmcnt(1)
	v_lshlrev_b32_e32 v20, 16, v10
	v_and_b32_e32 v21, 0xffff0000, v10
	v_pk_mul_f32 v[12:13], v[12:13], v[20:21]
	v_lshlrev_b32_e32 v10, 16, v11
	v_cvt_pk_bf16_f32 v61, v12, v13
	v_lshlrev_b32_e32 v12, 16, v110
	v_and_b32_e32 v13, 0xffff0000, v110
	v_and_b32_e32 v11, 0xffff0000, v11
	v_pk_mul_f32 v[10:11], v[12:13], v[10:11]
	s_waitcnt lgkmcnt(0)
	v_lshlrev_b32_e32 v12, 16, v14
	v_cvt_pk_bf16_f32 v63, v10, v11
	v_lshlrev_b32_e32 v10, 16, v109
	v_and_b32_e32 v11, 0xffff0000, v109
	v_and_b32_e32 v13, 0xffff0000, v14
	v_pk_mul_f32 v[10:11], v[10:11], v[12:13]
	v_lshlrev_b32_e32 v12, 16, v15
	v_cvt_pk_bf16_f32 v60, v10, v11
	v_lshlrev_b32_e32 v10, 16, v108
	v_and_b32_e32 v11, 0xffff0000, v108
	v_and_b32_e32 v13, 0xffff0000, v15
	v_pk_mul_f32 v[10:11], v[10:11], v[12:13]
	s_nop 0
	v_cvt_pk_bf16_f32 v62, v10, v11
	ds_read_b64 v[10:11], v113 offset:64
	ds_read_b64 v[14:15], v113 offset:16704
	v_lshlrev_b32_e32 v12, 16, v67
	v_and_b32_e32 v13, 0xffff0000, v67
	s_waitcnt lgkmcnt(1)
	v_lshlrev_b32_e32 v20, 16, v10
	v_and_b32_e32 v21, 0xffff0000, v10
	v_pk_mul_f32 v[12:13], v[12:13], v[20:21]
	v_lshlrev_b32_e32 v10, 16, v11
	v_cvt_pk_bf16_f32 v56, v12, v13
	v_lshlrev_b32_e32 v12, 16, v66
	v_and_b32_e32 v13, 0xffff0000, v66
	v_and_b32_e32 v11, 0xffff0000, v11
	v_pk_mul_f32 v[10:11], v[12:13], v[10:11]
	s_waitcnt lgkmcnt(0)
	v_lshlrev_b32_e32 v12, 16, v14
	v_cvt_pk_bf16_f32 v58, v10, v11
	v_lshlrev_b32_e32 v10, 16, v65
	v_and_b32_e32 v11, 0xffff0000, v65
	v_and_b32_e32 v13, 0xffff0000, v14
	v_pk_mul_f32 v[10:11], v[10:11], v[12:13]
	v_lshlrev_b32_e32 v12, 16, v15
	v_cvt_pk_bf16_f32 v54, v10, v11
	v_lshlrev_b32_e32 v10, 16, v64
	v_and_b32_e32 v11, 0xffff0000, v64
	v_and_b32_e32 v13, 0xffff0000, v15
	v_pk_mul_f32 v[10:11], v[10:11], v[12:13]
	s_nop 0
	v_cvt_pk_bf16_f32 v57, v10, v11
	ds_read_b64 v[10:11], v113 offset:80
	ds_read_b64 v[14:15], v113 offset:16720
	v_lshlrev_b32_e32 v12, 16, v71
	v_and_b32_e32 v13, 0xffff0000, v71
	s_waitcnt lgkmcnt(1)
	v_lshlrev_b32_e32 v20, 16, v10
	v_and_b32_e32 v21, 0xffff0000, v10
	v_pk_mul_f32 v[12:13], v[12:13], v[20:21]
	v_lshlrev_b32_e32 v10, 16, v11
	v_cvt_pk_bf16_f32 v50, v12, v13
	v_lshlrev_b32_e32 v12, 16, v70
	v_and_b32_e32 v13, 0xffff0000, v70
	v_and_b32_e32 v11, 0xffff0000, v11
	v_pk_mul_f32 v[10:11], v[12:13], v[10:11]
	s_waitcnt lgkmcnt(0)
; DI unsigned pack2(float a, float b) { f32x2_t v = {a, b}; bf16x2_t r = __builtin_convertvector(v, bf16x2_t); return __builtin_bit_cast(unsigned, r); }
; DI float bflo(unsigned u) { return __uint_as_float(u << 16); }
; DI float bfhi(unsigned u) { return __uint_as_float(u & 0xffff0000u); }
; DI int otid() { int t = threadIdx.x; asm volatile("" : "+v"(t)); return t; }
; template <bool LAST>
; DI void phase_gate(const Params& P, int layer, unsigned char* smem, int L, int G) {
;     ...
;     {
;       const int tid1 = otid();
;       const int lane1 = tid1 & 63, w1 = tid1 >> 6, r1 = lane1 & 31, h1 = lane1 >> 5, wm1 = w1 >> 2, wn1 = w1 & 3;
; #pragma unroll
;       for (int i = 0; i < 4; ++i)
; #pragma unroll
;         for (int q4 = 0; q4 < 4; ++q4) {
; #pragma unroll
;           for (int j = 0; j < 2; ++j) {
;             const uint2 pv = *(const uint2*)(stg + (wn1 * 64 + j * 32 + r1) * STG + wm1 * 128 + i * 32 + 8 * q4 + 4 * h1);
;             const unsigned g0 = gq[i][j][2 * q4], g1 = gq[i][j][2 * q4 + 1];
;             gq[i][j][2 * q4] = pack2(bflo(g0) * bflo(pv.x), bfhi(g0) * bfhi(pv.x));
;             gq[i][j][2 * q4 + 1] = pack2(bflo(g1) * bflo(pv.y), bfhi(g1) * bfhi(pv.y));
;           }
;           __builtin_amdgcn_sched_barrier(0);
;         }
;     }
	v_lshlrev_b32_e32 v12, 16, v14
	v_cvt_pk_bf16_f32 v52, v10, v11
	v_lshlrev_b32_e32 v10, 16, v69
	v_and_b32_e32 v11, 0xffff0000, v69
	v_and_b32_e32 v13, 0xffff0000, v14
	v_pk_mul_f32 v[10:11], v[10:11], v[12:13]
	v_lshlrev_b32_e32 v12, 16, v15
	v_cvt_pk_bf16_f32 v49, v10, v11
	v_lshlrev_b32_e32 v10, 16, v68
	v_and_b32_e32 v11, 0xffff0000, v68
	v_and_b32_e32 v13, 0xffff0000, v15
	v_pk_mul_f32 v[10:11], v[10:11], v[12:13]
	s_nop 0
	v_cvt_pk_bf16_f32 v51, v10, v11
	ds_read_b64 v[10:11], v113 offset:96
	ds_read_b64 v[14:15], v113 offset:16736
	v_lshlrev_b32_e32 v12, 16, v75
	v_and_b32_e32 v13, 0xffff0000, v75
	s_waitcnt lgkmcnt(1)
	v_lshlrev_b32_e32 v20, 16, v10
	v_and_b32_e32 v21, 0xffff0000, v10
	v_pk_mul_f32 v[12:13], v[12:13], v[20:21]
	v_lshlrev_b32_e32 v10, 16, v11
	v_cvt_pk_bf16_f32 v46, v12, v13
	v_lshlrev_b32_e32 v12, 16, v74
	v_and_b32_e32 v13, 0xffff0000, v74
	v_and_b32_e32 v11, 0xffff0000, v11
	v_pk_mul_f32 v[10:11], v[12:13], v[10:11]
	s_waitcnt lgkmcnt(0)
	v_lshlrev_b32_e32 v12, 16, v14
	v_cvt_pk_bf16_f32 v48, v10, v11
	v_lshlrev_b32_e32 v10, 16, v73
	v_and_b32_e32 v11, 0xffff0000, v73
	v_and_b32_e32 v13, 0xffff0000, v14
	v_pk_mul_f32 v[10:11], v[10:11], v[12:13]
	v_lshlrev_b32_e32 v12, 16, v15
	v_cvt_pk_bf16_f32 v45, v10, v11
	v_lshlrev_b32_e32 v10, 16, v72
	v_and_b32_e32 v11, 0xffff0000, v72
	v_and_b32_e32 v13, 0xffff0000, v15
	v_pk_mul_f32 v[10:11], v[10:11], v[12:13]
	s_nop 0
	v_cvt_pk_bf16_f32 v47, v10, v11
	ds_read_b64 v[10:11], v113 offset:112
	ds_read_b64 v[14:15], v113 offset:16752
	v_lshlrev_b32_e32 v12, 16, v79
	v_and_b32_e32 v13, 0xffff0000, v79
	s_waitcnt lgkmcnt(1)
	v_lshlrev_b32_e32 v20, 16, v10
	v_and_b32_e32 v21, 0xffff0000, v10
	v_pk_mul_f32 v[12:13], v[12:13], v[20:21]
	v_lshlrev_b32_e32 v10, 16, v11
	v_cvt_pk_bf16_f32 v42, v12, v13
	v_lshlrev_b32_e32 v12, 16, v78
	v_and_b32_e32 v13, 0xffff0000, v78
	v_and_b32_e32 v11, 0xffff0000, v11
	v_pk_mul_f32 v[10:11], v[12:13], v[10:11]
	s_waitcnt lgkmcnt(0)
	v_lshlrev_b32_e32 v12, 16, v14
	v_cvt_pk_bf16_f32 v44, v10, v11
	v_lshlrev_b32_e32 v10, 16, v77
	v_and_b32_e32 v11, 0xffff0000, v77
	v_and_b32_e32 v13, 0xffff0000, v14
	v_pk_mul_f32 v[10:11], v[10:11], v[12:13]
	v_lshlrev_b32_e32 v12, 16, v15
	v_cvt_pk_bf16_f32 v41, v10, v11
	v_lshlrev_b32_e32 v10, 16, v76
	v_and_b32_e32 v11, 0xffff0000, v76
	v_and_b32_e32 v13, 0xffff0000, v15
	v_pk_mul_f32 v[10:11], v[10:11], v[12:13]
	s_nop 0
	v_cvt_pk_bf16_f32 v43, v10, v11
	ds_read_b64 v[10:11], v113 offset:128
	ds_read_b64 v[14:15], v113 offset:16768
	v_lshlrev_b32_e32 v12, 16, v35
	v_and_b32_e32 v13, 0xffff0000, v35
	s_waitcnt lgkmcnt(1)
	v_lshlrev_b32_e32 v20, 16, v10
	v_and_b32_e32 v21, 0xffff0000, v10
	v_pk_mul_f32 v[12:13], v[12:13], v[20:21]
	v_lshlrev_b32_e32 v10, 16, v11
	v_cvt_pk_bf16_f32 v38, v12, v13
	v_lshlrev_b32_e32 v12, 16, v34
	v_and_b32_e32 v13, 0xffff0000, v34
	v_and_b32_e32 v11, 0xffff0000, v11
	v_pk_mul_f32 v[10:11], v[12:13], v[10:11]
	s_waitcnt lgkmcnt(0)
	v_lshlrev_b32_e32 v12, 16, v14
	v_cvt_pk_bf16_f32 v40, v10, v11
	v_lshlrev_b32_e32 v10, 16, v33
	v_and_b32_e32 v11, 0xffff0000, v33
	v_and_b32_e32 v13, 0xffff0000, v14
	v_pk_mul_f32 v[10:11], v[10:11], v[12:13]
	v_lshlrev_b32_e32 v12, 16, v15
	v_cvt_pk_bf16_f32 v37, v10, v11
	v_lshlrev_b32_e32 v10, 16, v32
	v_and_b32_e32 v11, 0xffff0000, v32
	v_and_b32_e32 v13, 0xffff0000, v15
	v_pk_mul_f32 v[10:11], v[10:11], v[12:13]
	s_nop 0
	v_cvt_pk_bf16_f32 v39, v10, v11
	ds_read_b64 v[10:11], v113 offset:144
	ds_read_b64 v[14:15], v113 offset:16784
	v_lshlrev_b32_e32 v12, 16, v80
	v_and_b32_e32 v13, 0xffff0000, v80
	s_waitcnt lgkmcnt(1)
	v_lshlrev_b32_e32 v20, 16, v10
	v_and_b32_e32 v21, 0xffff0000, v10
	v_pk_mul_f32 v[12:13], v[12:13], v[20:21]
	v_lshlrev_b32_e32 v10, 16, v11
	v_cvt_pk_bf16_f32 v34, v12, v13
	v_lshlrev_b32_e32 v12, 16, v36
	v_and_b32_e32 v13, 0xffff0000, v36
	v_and_b32_e32 v11, 0xffff0000, v11
	v_pk_mul_f32 v[10:11], v[12:13], v[10:11]
	s_waitcnt lgkmcnt(0)
	v_lshlrev_b32_e32 v12, 16, v14
	v_cvt_pk_bf16_f32 v36, v10, v11
	v_lshlrev_b32_e32 v10, 16, v55
	v_and_b32_e32 v11, 0xffff0000, v55
	v_and_b32_e32 v13, 0xffff0000, v14
	v_pk_mul_f32 v[10:11], v[10:11], v[12:13]
	v_lshlrev_b32_e32 v12, 16, v15
	v_cvt_pk_bf16_f32 v32, v10, v11
	v_lshlrev_b32_e32 v10, 16, v53
	v_and_b32_e32 v11, 0xffff0000, v53
	v_and_b32_e32 v13, 0xffff0000, v15
	v_pk_mul_f32 v[10:11], v[10:11], v[12:13]
	s_nop 0
	v_cvt_pk_bf16_f32 v35, v10, v11
	ds_read_b64 v[10:11], v113 offset:160
	ds_read_b64 v[14:15], v113 offset:16800
	v_lshlrev_b32_e32 v12, 16, v83
	v_and_b32_e32 v13, 0xffff0000, v83
	s_waitcnt lgkmcnt(1)
	v_lshlrev_b32_e32 v20, 16, v10
	v_and_b32_e32 v21, 0xffff0000, v10
	v_pk_mul_f32 v[12:13], v[12:13], v[20:21]
	v_lshlrev_b32_e32 v10, 16, v11
	v_cvt_pk_bf16_f32 v24, v12, v13
	v_lshlrev_b32_e32 v12, 16, v82
	v_and_b32_e32 v13, 0xffff0000, v82
	v_and_b32_e32 v11, 0xffff0000, v11
	v_pk_mul_f32 v[10:11], v[12:13], v[10:11]
	s_waitcnt lgkmcnt(0)
	v_lshlrev_b32_e32 v12, 16, v14
	v_cvt_pk_bf16_f32 v26, v10, v11
	v_lshlrev_b32_e32 v10, 16, v81
	v_and_b32_e32 v11, 0xffff0000, v81
	v_and_b32_e32 v13, 0xffff0000, v14
	v_pk_mul_f32 v[10:11], v[10:11], v[12:13]
	v_lshlrev_b32_e32 v12, 16, v15
	v_cvt_pk_bf16_f32 v23, v10, v11
	v_lshlrev_b32_e32 v10, 16, v59
	v_and_b32_e32 v11, 0xffff0000, v59
	v_and_b32_e32 v13, 0xffff0000, v15
	v_pk_mul_f32 v[10:11], v[10:11], v[12:13]
	s_nop 0
	v_cvt_pk_bf16_f32 v25, v10, v11
	ds_read_b64 v[10:11], v113 offset:176
	ds_read_b64 v[14:15], v113 offset:16816
	v_lshlrev_b32_e32 v12, 16, v91
	v_and_b32_e32 v13, 0xffff0000, v91
	s_waitcnt lgkmcnt(1)
; DI unsigned pack2(float a, float b) { f32x2_t v = {a, b}; bf16x2_t r = __builtin_convertvector(v, bf16x2_t); return __builtin_bit_cast(unsigned, r); }
; DI float bflo(unsigned u) { return __uint_as_float(u << 16); }
; DI float bfhi(unsigned u) { return __uint_as_float(u & 0xffff0000u); }
; DI int otid() { int t = threadIdx.x; asm volatile("" : "+v"(t)); return t; }
; template <bool LAST>
; DI void phase_gate(const Params& P, int layer, unsigned char* smem, int L, int G) {
;     ...
;     {
;       const int tid1 = otid();
;       const int lane1 = tid1 & 63, w1 = tid1 >> 6, r1 = lane1 & 31, h1 = lane1 >> 5, wm1 = w1 >> 2, wn1 = w1 & 3;
; #pragma unroll
;       for (int i = 0; i < 4; ++i)
; #pragma unroll
;         for (int q4 = 0; q4 < 4; ++q4) {
; #pragma unroll
;           for (int j = 0; j < 2; ++j) {
;             const uint2 pv = *(const uint2*)(stg + (wn1 * 64 + j * 32 + r1) * STG + wm1 * 128 + i * 32 + 8 * q4 + 4 * h1);
;             const unsigned g0 = gq[i][j][2 * q4], g1 = gq[i][j][2 * q4 + 1];
;             gq[i][j][2 * q4] = pack2(bflo(g0) * bflo(pv.x), bfhi(g0) * bfhi(pv.x));
;             gq[i][j][2 * q4 + 1] = pack2(bflo(g1) * bflo(pv.y), bfhi(g1) * bfhi(pv.y));
;           }
;           __builtin_amdgcn_sched_barrier(0);
;         }
;     }
;     __syncthreads();
	v_lshlrev_b32_e32 v20, 16, v10
	v_and_b32_e32 v21, 0xffff0000, v10
	v_pk_mul_f32 v[12:13], v[12:13], v[20:21]
	v_lshlrev_b32_e32 v10, 16, v11
	v_cvt_pk_bf16_f32 v20, v12, v13
	v_lshlrev_b32_e32 v12, 16, v86
	v_and_b32_e32 v13, 0xffff0000, v86
	v_and_b32_e32 v11, 0xffff0000, v11
	v_pk_mul_f32 v[10:11], v[12:13], v[10:11]
	s_waitcnt lgkmcnt(0)
	v_lshlrev_b32_e32 v12, 16, v14
	v_cvt_pk_bf16_f32 v22, v10, v11
	v_lshlrev_b32_e32 v10, 16, v85
	v_and_b32_e32 v11, 0xffff0000, v85
	v_and_b32_e32 v13, 0xffff0000, v14
	v_pk_mul_f32 v[10:11], v[10:11], v[12:13]
	v_lshlrev_b32_e32 v12, 16, v15
	v_cvt_pk_bf16_f32 v18, v10, v11
	v_lshlrev_b32_e32 v10, 16, v84
	v_and_b32_e32 v11, 0xffff0000, v84
	v_and_b32_e32 v13, 0xffff0000, v15
	v_pk_mul_f32 v[10:11], v[10:11], v[12:13]
	s_nop 0
	v_cvt_pk_bf16_f32 v21, v10, v11
	ds_read_b64 v[10:11], v113 offset:192
	ds_read_b64 v[64:65], v113 offset:16832
	v_lshlrev_b32_e32 v12, 16, v17
	v_and_b32_e32 v13, 0xffff0000, v17
	s_waitcnt lgkmcnt(1)
	v_lshlrev_b32_e32 v14, 16, v10
	v_and_b32_e32 v15, 0xffff0000, v10
	v_pk_mul_f32 v[12:13], v[12:13], v[14:15]
	v_lshlrev_b32_e32 v10, 16, v11
	v_cvt_pk_bf16_f32 v15, v12, v13
	v_lshlrev_b32_e32 v12, 16, v16
	v_and_b32_e32 v13, 0xffff0000, v16
	v_and_b32_e32 v11, 0xffff0000, v11
	v_pk_mul_f32 v[10:11], v[12:13], v[10:11]
	s_waitcnt lgkmcnt(0)
	v_lshlrev_b32_e32 v12, 16, v64
	v_cvt_pk_bf16_f32 v17, v10, v11
	v_lshlrev_b32_e32 v10, 16, v3
	v_and_b32_e32 v11, 0xffff0000, v3
	v_and_b32_e32 v13, 0xffff0000, v64
	v_pk_mul_f32 v[10:11], v[10:11], v[12:13]
	v_lshlrev_b32_e32 v12, 16, v65
	v_cvt_pk_bf16_f32 v14, v10, v11
	v_lshlrev_b32_e32 v10, 16, v2
	v_and_b32_e32 v11, 0xffff0000, v2
	v_and_b32_e32 v13, 0xffff0000, v65
	v_pk_mul_f32 v[2:3], v[10:11], v[12:13]
	s_nop 0
	v_cvt_pk_bf16_f32 v16, v2, v3
	ds_read_b64 v[2:3], v113 offset:208
	ds_read_b64 v[64:65], v113 offset:16848
	v_lshlrev_b32_e32 v10, 16, v7
	v_and_b32_e32 v11, 0xffff0000, v7
	s_waitcnt lgkmcnt(1)
	v_lshlrev_b32_e32 v12, 16, v2
	v_and_b32_e32 v13, 0xffff0000, v2
	v_pk_mul_f32 v[10:11], v[10:11], v[12:13]
	v_lshlrev_b32_e32 v12, 16, v6
	v_lshlrev_b32_e32 v2, 16, v3
	v_and_b32_e32 v13, 0xffff0000, v6
	v_and_b32_e32 v3, 0xffff0000, v3
	v_pk_mul_f32 v[2:3], v[12:13], v[2:3]
	s_waitcnt lgkmcnt(0)
	v_lshlrev_b32_e32 v6, 16, v64
	v_cvt_pk_bf16_f32 v13, v2, v3
	v_lshlrev_b32_e32 v2, 16, v5
	v_and_b32_e32 v3, 0xffff0000, v5
	v_and_b32_e32 v7, 0xffff0000, v64
	v_pk_mul_f32 v[2:3], v[2:3], v[6:7]
	v_cvt_pk_bf16_f32 v11, v10, v11
	v_cvt_pk_bf16_f32 v10, v2, v3
	v_lshlrev_b32_e32 v2, 16, v4
	v_lshlrev_b32_e32 v6, 16, v65
	v_and_b32_e32 v3, 0xffff0000, v4
	v_and_b32_e32 v7, 0xffff0000, v65
	v_pk_mul_f32 v[2:3], v[2:3], v[6:7]
	s_nop 0
	v_cvt_pk_bf16_f32 v12, v2, v3
	ds_read_b64 v[2:3], v113 offset:224
	ds_read_b64 v[64:65], v113 offset:16864
	v_lshlrev_b32_e32 v4, 16, v27
	v_and_b32_e32 v5, 0xffff0000, v27
	s_waitcnt lgkmcnt(1)
	v_lshlrev_b32_e32 v6, 16, v2
	v_and_b32_e32 v7, 0xffff0000, v2
	v_pk_mul_f32 v[4:5], v[4:5], v[6:7]
	v_lshlrev_b32_e32 v2, 16, v3
	v_cvt_pk_bf16_f32 v7, v4, v5
	v_lshlrev_b32_e32 v4, 16, v9
	v_and_b32_e32 v5, 0xffff0000, v9
	v_and_b32_e32 v3, 0xffff0000, v3
	v_pk_mul_f32 v[2:3], v[4:5], v[2:3]
	s_waitcnt lgkmcnt(0)
	v_lshlrev_b32_e32 v4, 16, v64
	v_cvt_pk_bf16_f32 v9, v2, v3
	v_lshlrev_b32_e32 v2, 16, v19
	v_and_b32_e32 v3, 0xffff0000, v19
	v_and_b32_e32 v5, 0xffff0000, v64
	v_pk_mul_f32 v[2:3], v[2:3], v[4:5]
	v_lshlrev_b32_e32 v4, 16, v65
	v_cvt_pk_bf16_f32 v6, v2, v3
	v_lshlrev_b32_e32 v2, 16, v8
	v_and_b32_e32 v3, 0xffff0000, v8
	v_and_b32_e32 v5, 0xffff0000, v65
	v_pk_mul_f32 v[2:3], v[2:3], v[4:5]
	s_nop 0
	v_cvt_pk_bf16_f32 v8, v2, v3
	ds_read_b64 v[2:3], v113 offset:240
	ds_read_b64 v[64:65], v113 offset:16880
	v_lshlrev_b32_e32 v4, 16, v112
	v_and_b32_e32 v5, 0xffff0000, v112
	s_waitcnt lgkmcnt(1)
	v_lshlrev_b32_e32 v66, 16, v2
	v_and_b32_e32 v67, 0xffff0000, v2
	v_pk_mul_f32 v[4:5], v[4:5], v[66:67]
	v_lshlrev_b32_e32 v66, 16, v30
	v_lshlrev_b32_e32 v2, 16, v3
	v_and_b32_e32 v67, 0xffff0000, v30
	v_and_b32_e32 v3, 0xffff0000, v3
	v_pk_mul_f32 v[2:3], v[66:67], v[2:3]
	v_cvt_pk_bf16_f32 v4, v4, v5
	v_cvt_pk_bf16_f32 v5, v2, v3
	v_lshlrev_b32_e32 v2, 16, v29
	s_waitcnt lgkmcnt(0)
	v_lshlrev_b32_e32 v66, 16, v64
	v_and_b32_e32 v3, 0xffff0000, v29
	v_and_b32_e32 v67, 0xffff0000, v64
	v_pk_mul_f32 v[2:3], v[2:3], v[66:67]
	v_lshlrev_b32_e32 v66, 16, v28
	v_lshlrev_b32_e32 v64, 16, v65
	v_and_b32_e32 v67, 0xffff0000, v28
	v_and_b32_e32 v65, 0xffff0000, v65
	v_pk_mul_f32 v[28:29], v[66:67], v[64:65]
	v_cvt_pk_bf16_f32 v2, v2, v3
	v_cvt_pk_bf16_f32 v3, v28, v29
	v_mov_b32_e32 v19, v192
	s_barrier
; DI int otid() { int t = threadIdx.x; asm volatile("" : "+v"(t)); return t; }
; template <bool NT>
; DI void stage_load_tile(bf16_t* stg, const bf16_t* tilebase) {
;   const int tid = otid();
;   const int r0 = tid >> 5, c = tid & 31;
;   const unsigned o0 = (unsigned)(r0 * 1024 + c * 8);
;   __builtin_amdgcn_sched_barrier(0);
; #pragma unroll
;   for (int hf = 0; hf < 2; ++hf) {
; #pragma unroll
;     for (int it = 8 * hf; it < 8 * hf + 8; ++it) {
;       const u32x4* gp = (const u32x4*)(tilebase + (o0 + (unsigned)(it * 16 * 1024)));
;       stage_write16(stg, r0 + 16 * it, c, NT ? __builtin_nontemporal_load(gp) : *gp);
;     }
;     __builtin_amdgcn_sched_barrier(0);
;   }
; }
; template <bool LAST>
; DI void phase_gate(const Params& P, int layer, unsigned char* smem, int L, int G) {
;     ...
;     stage_load_tile<false>(stg, Sb + (size_t)mt * 256 * 1024 + nt * 256);
	s_add_u32 s26, s76, s24
	v_ashrrev_i32_e32 v27, 5, v19
	v_and_b32_e32 v19, 31, v19
	s_addc_u32 s27, s77, s25
	v_lshlrev_b32_e32 v30, 3, v19
	v_lshl_add_u64 v[28:29], s[26:27], 0, v[0:1]
	v_lshl_or_b32 v160, v27, 10, v30
	v_add_u32_e32 v66, 0x4000, v160
	v_mov_b32_e32 v67, v161
	v_add_u32_e32 v72, 0x8000, v160
	v_mov_b32_e32 v73, v161
	v_add_u32_e32 v74, 0xc000, v160
	v_mov_b32_e32 v75, v161
	v_add_u32_e32 v80, 0x10000, v160
	v_mov_b32_e32 v81, v161
	v_add_u32_e32 v82, 0x14000, v160
	v_mov_b32_e32 v83, v161
	v_lshl_add_u64 v[64:65], v[160:161], 1, v[28:29]
	v_lshl_add_u64 v[68:69], v[66:67], 1, v[28:29]
	v_lshl_add_u64 v[72:73], v[72:73], 1, v[28:29]
	v_lshl_add_u64 v[76:77], v[74:75], 1, v[28:29]
	v_lshl_add_u64 v[80:81], v[80:81], 1, v[28:29]
	v_lshl_add_u64 v[84:85], v[82:83], 1, v[28:29]
	global_load_dwordx4 v[64:67], v[64:65], off
	s_nop 0
	global_load_dwordx4 v[68:71], v[68:69], off
	s_nop 0
	global_load_dwordx4 v[72:75], v[72:73], off
	s_nop 0
	global_load_dwordx4 v[76:79], v[76:77], off
	s_nop 0
	global_load_dwordx4 v[80:83], v[80:81], off
	s_nop 0
	global_load_dwordx4 v[100:103], v[84:85], off
	v_add_u32_e32 v84, 0x18000, v160
	v_mov_b32_e32 v85, v161
	v_add_u32_e32 v104, 0x1c000, v160
	v_mov_b32_e32 v105, v161
	v_lshl_add_u64 v[84:85], v[84:85], 1, v[28:29]
	v_lshl_add_u64 v[108:109], v[104:105], 1, v[28:29]
	global_load_dwordx4 v[104:107], v[84:85], off
	s_nop 0
	global_load_dwordx4 v[108:111], v[108:109], off
	v_add_u32_e32 v218, 0x20000, v160
	v_mov_b32_e32 v219, v161
	v_add_u32_e32 v220, 0x24000, v160
	v_mov_b32_e32 v221, v161
	v_add_u32_e32 v226, 0x28000, v160
	v_mov_b32_e32 v227, v161
	v_add_u32_e32 v228, 0x2c000, v160
	v_mov_b32_e32 v229, v161
	v_add_u32_e32 v234, 0x30000, v160
	v_mov_b32_e32 v235, v161
	v_add_u32_e32 v236, 0x34000, v160
	v_mov_b32_e32 v237, v161
	v_lshl_add_u64 v[218:219], v[218:219], 1, v[28:29]
	v_lshl_add_u64 v[222:223], v[220:221], 1, v[28:29]
	v_lshl_add_u64 v[226:227], v[226:227], 1, v[28:29]
	v_lshl_add_u64 v[230:231], v[228:229], 1, v[28:29]
	v_lshl_add_u64 v[234:235], v[234:235], 1, v[28:29]
	v_lshl_add_u64 v[252:253], v[236:237], 1, v[28:29]
	global_load_dwordx4 v[218:221], v[218:219], off
	s_nop 0
	global_load_dwordx4 v[222:225], v[222:223], off
	s_nop 0
	global_load_dwordx4 v[226:229], v[226:227], off
	s_nop 0
	global_load_dwordx4 v[230:233], v[230:231], off
	s_nop 0
	global_load_dwordx4 v[234:237], v[234:235], off
	s_nop 0
	global_load_dwordx4 v[238:241], v[252:253], off
	v_add_u32_e32 v252, 0x38000, v160
	v_mov_b32_e32 v253, v161
	v_lshl_add_u64 v[252:253], v[252:253], 1, v[28:29]
	v_add_u32_e32 v160, 0x3c000, v160
	v_lshl_add_u64 v[190:191], v[160:161], 1, v[28:29]
	global_load_dwordx4 v[242:245], v[252:253], off
	global_load_dwordx4 v[248:251], v[190:191], off
	v_mul_lo_u32 v27, v27, s40
	v_lshl_add_u32 v19, v19, 4, v27
	v_add_u32_e32 v27, 0x2080, v19
	v_add_u32_e32 v30, 0x4100, v19
	v_add_u32_e32 v33, 0x6180, v19
	v_add_u32_e32 v53, 0x8200, v19
	v_add_u32_e32 v55, 0xa280, v19
	v_add_u32_e32 v59, 0xc300, v19
	v_add_u32_e32 v84, 0xe380, v19
	s_waitcnt vmcnt(15)
	ds_write2_b64 v19, v[64:65], v[66:67] offset1:1
	s_waitcnt vmcnt(14)
	ds_write2_b64 v27, v[68:69], v[70:71] offset1:1
	s_waitcnt vmcnt(13)
	ds_write2_b64 v30, v[72:73], v[74:75] offset1:1
	s_waitcnt vmcnt(12)
	ds_write2_b64 v33, v[76:77], v[78:79] offset1:1
	s_waitcnt vmcnt(11)
	ds_write2_b64 v53, v[80:81], v[82:83] offset1:1
	s_waitcnt vmcnt(10)
	ds_write2_b64 v55, v[100:101], v[102:103] offset1:1
	s_waitcnt vmcnt(9)
	ds_write2_b64 v59, v[104:105], v[106:107] offset1:1
	s_waitcnt vmcnt(8)
	ds_write2_b64 v84, v[108:109], v[110:111] offset1:1
	v_add_u32_e32 v27, 0x10400, v19
	v_add_u32_e32 v28, 0x12480, v19
	v_add_u32_e32 v29, 0x14500, v19
	v_add_u32_e32 v30, 0x16580, v19
	v_add_u32_e32 v33, 0x18600, v19
	v_add_u32_e32 v53, 0x1a680, v19
	v_add_u32_e32 v55, 0x1c700, v19
	v_add_u32_e32 v19, 0x1e780, v19
	s_waitcnt vmcnt(7)
	ds_write2_b64 v27, v[218:219], v[220:221] offset1:1
	s_waitcnt vmcnt(6)
	ds_write2_b64 v28, v[222:223], v[224:225] offset1:1
	s_waitcnt vmcnt(5)
	ds_write2_b64 v29, v[226:227], v[228:229] offset1:1
	s_waitcnt vmcnt(4)
	ds_write2_b64 v30, v[230:231], v[232:233] offset1:1
	s_waitcnt vmcnt(3)
	ds_write2_b64 v33, v[234:235], v[236:237] offset1:1
	s_waitcnt vmcnt(2)
	ds_write2_b64 v53, v[238:239], v[240:241] offset1:1
	s_waitcnt vmcnt(1)
	ds_write2_b64 v55, v[242:243], v[244:245] offset1:1
	s_waitcnt vmcnt(0)
	ds_write2_b64 v19, v[248:249], v[250:251] offset1:1
	v_mov_b32_e32 v19, v192
	s_waitcnt lgkmcnt(0)
	s_barrier
; DI unsigned pack2(float a, float b) { f32x2_t v = {a, b}; bf16x2_t r = __builtin_convertvector(v, bf16x2_t); return __builtin_bit_cast(unsigned, r); }
; DI float bflo(unsigned u) { return __uint_as_float(u << 16); }
; DI float bfhi(unsigned u) { return __uint_as_float(u & 0xffff0000u); }
; DI int otid() { int t = threadIdx.x; asm volatile("" : "+v"(t)); return t; }
; template <bool LAST>
; DI void phase_gate(const Params& P, int layer, unsigned char* smem, int L, int G) {
;     ...
;     const int tid2 = otid();
;     const int lane2 = tid2 & 63, w2 = tid2 >> 6, r2 = lane2 & 31, h2 = lane2 >> 5, wm2 = w2 >> 2, wn2 = w2 & 3;
; #pragma unroll
;     for (int i = 0; i < 4; ++i)
; #pragma unroll
;       for (int q4 = 0; q4 < 4; ++q4) {
;         const int fl = wm2 * 128 + i * 32 + 8 * q4 + 4 * h2;
;         const int f0 = nt * 256 + fl;
;         const f32x4 gv = *(const f32x4*)(vecL + 512 + fl), bv = *(const f32x4*)(vecL + 768 + fl);
;         const float ga[4] = {gv.x, gv.y, gv.z, gv.w}, ba[4] = {bv.x, bv.y, bv.z, bv.w};
; #pragma unroll
;         for (int j = 0; j < 2; ++j) {
;           const int lrow = wn2 * 64 + j * 32 + r2;
;           const float mu = rowA[lrow], rstd = rowB[lrow];
;           uint2* sp = (uint2*)(stg + lrow * STG + fl);
;           const uint2 sv = *sp;
;           const float sa[4] = {bflo(sv.x), bfhi(sv.x), bflo(sv.y), bfhi(sv.y)};
;           float y[4];
;           const float gg[4] = {bflo(gq[i][j][2 * q4]), bfhi(gq[i][j][2 * q4]), bflo(gq[i][j][2 * q4 + 1]), bfhi(gq[i][j][2 * q4 + 1])};
; #pragma unroll
;           for (int e = 0; e < 4; ++e) y[e] = (sa[e] - mu) * rstd * ga[e] + ba[e] + gg[e];
;           if (LAST) { f32x4 o = {y[0], y[1], y[2], y[3]}; *(f32x4*)(P.out + (size_t)(mt * 256 + lrow) * 1024 + f0) = o; }
;           else { uint2 pk; pk.x = pack2(y[0], y[1]); pk.y = pack2(y[2], y[3]); *sp = pk; }
;         }
;         __builtin_amdgcn_sched_barrier(0);
;       }
	v_lshlrev_b32_e32 v82, 16, v31
	v_lshrrev_b32_e32 v28, 3, v19
	v_ashrrev_i32_e32 v27, 1, v19
	v_and_b32_e32 v28, 4, v28
	v_and_or_b32 v30, v27, s41, v28
	v_and_b32_e32 v19, 0xdf, v19
	v_lshlrev_b32_e32 v27, 2, v30
	v_lshlrev_b32_e32 v33, 2, v19
	v_mul_u32_u24_e32 v19, 0x208, v19
	v_add_u32_e32 v28, 0x25000, v27
	v_lshl_add_u32 v19, v30, 1, v19
	v_add_u32_e32 v29, 0x25400, v27
	ds_read_b128 v[64:67], v28
	ds_read_b128 v[68:71], v29
	ds_read_b64 v[72:73], v19
	v_or_b32_e32 v29, 0x24000, v33
	v_or_b32_e32 v30, 0x24400, v33
	ds_read_b32 v74, v29
	ds_read_b32 v76, v30
	ds_read_b64 v[78:79], v19 offset:16640
	v_and_b32_e32 v83, 0xffff0000, v31
	s_waitcnt lgkmcnt(3)
	v_lshlrev_b32_e32 v80, 16, v72
	v_and_b32_e32 v81, 0xffff0000, v72
	v_lshlrev_b32_e32 v72, 16, v73
	v_and_b32_e32 v73, 0xffff0000, v73
	s_waitcnt lgkmcnt(2)
	v_pk_add_f32 v[80:81], v[80:81], v[74:75] op_sel_hi:[1,0] neg_lo:[0,1] neg_hi:[0,1]
	v_pk_add_f32 v[72:73], v[72:73], v[74:75] op_sel_hi:[1,0] neg_lo:[0,1] neg_hi:[0,1]
	s_waitcnt lgkmcnt(1)
	v_pk_mul_f32 v[80:81], v[76:77], v[80:81] op_sel_hi:[0,1]
	v_pk_mul_f32 v[72:73], v[76:77], v[72:73] op_sel_hi:[0,1]
	v_lshlrev_b32_e32 v84, 16, v98
	v_and_b32_e32 v85, 0xffff0000, v98
	v_pk_fma_f32 v[80:81], v[64:65], v[80:81], v[68:69]
	v_pk_fma_f32 v[72:73], v[66:67], v[72:73], v[70:71]
	v_pk_add_f32 v[80:81], v[80:81], v[82:83]
	v_pk_add_f32 v[72:73], v[72:73], v[84:85]
	v_cvt_pk_bf16_f32 v74, v80, v81
	v_cvt_pk_bf16_f32 v75, v72, v73
	ds_write_b64 v19, v[74:75]
	v_or_b32_e32 v31, 0x24080, v33
	v_or_b32_e32 v33, 0x24480, v33
	ds_read_b32 v72, v31
	ds_read_b32 v74, v33
	s_waitcnt lgkmcnt(3)
	v_lshlrev_b32_e32 v76, 16, v78
	v_and_b32_e32 v77, 0xffff0000, v78
	v_lshlrev_b32_e32 v78, 16, v79
	s_waitcnt lgkmcnt(1)
	v_pk_add_f32 v[76:77], v[76:77], v[72:73] op_sel_hi:[1,0] neg_lo:[0,1] neg_hi:[0,1]
	v_and_b32_e32 v79, 0xffff0000, v79
	s_waitcnt lgkmcnt(0)
	v_pk_mul_f32 v[76:77], v[74:75], v[76:77] op_sel_hi:[0,1]
	v_pk_fma_f32 v[64:65], v[64:65], v[76:77], v[68:69]
	v_pk_add_f32 v[68:69], v[78:79], v[72:73] op_sel_hi:[1,0] neg_lo:[0,1] neg_hi:[0,1]
	v_lshlrev_b32_e32 v80, 16, v97
	v_pk_mul_f32 v[68:69], v[74:75], v[68:69] op_sel_hi:[0,1]
	v_and_b32_e32 v81, 0xffff0000, v97
	v_lshlrev_b32_e32 v82, 16, v96
	v_and_b32_e32 v83, 0xffff0000, v96
	v_pk_fma_f32 v[66:67], v[66:67], v[68:69], v[70:71]
	v_pk_add_f32 v[64:65], v[64:65], v[80:81]
	v_pk_add_f32 v[66:67], v[66:67], v[82:83]
	v_cvt_pk_bf16_f32 v64, v64, v65
	v_cvt_pk_bf16_f32 v65, v66, v67
	ds_write_b64 v19, v[64:65] offset:16640
	v_add_u32_e32 v53, 0x25020, v27
	v_add_u32_e32 v55, 0x25420, v27
	ds_read_b64 v[72:73], v19 offset:16
	ds_read_b128 v[64:67], v53
	ds_read_b128 v[68:71], v55
	ds_read_b32 v74, v29
	ds_read_b32 v76, v30
	ds_read_b64 v[78:79], v19 offset:16656
	s_waitcnt lgkmcnt(5)
	v_lshlrev_b32_e32 v80, 16, v72
	v_and_b32_e32 v81, 0xffff0000, v72
	v_lshlrev_b32_e32 v72, 16, v73
	v_and_b32_e32 v73, 0xffff0000, v73
	s_waitcnt lgkmcnt(2)
	v_pk_add_f32 v[80:81], v[80:81], v[74:75] op_sel_hi:[1,0] neg_lo:[0,1] neg_hi:[0,1]
	v_pk_add_f32 v[72:73], v[72:73], v[74:75] op_sel_hi:[1,0] neg_lo:[0,1] neg_hi:[0,1]
	s_waitcnt lgkmcnt(1)
	v_pk_mul_f32 v[80:81], v[76:77], v[80:81] op_sel_hi:[0,1]
	v_pk_mul_f32 v[72:73], v[76:77], v[72:73] op_sel_hi:[0,1]
	v_lshlrev_b32_e32 v82, 16, v93
	v_and_b32_e32 v83, 0xffff0000, v93
	v_lshlrev_b32_e32 v84, 16, v95
	v_and_b32_e32 v85, 0xffff0000, v95
	v_pk_fma_f32 v[80:81], v[64:65], v[80:81], v[68:69]
	v_pk_fma_f32 v[72:73], v[66:67], v[72:73], v[70:71]
	v_pk_add_f32 v[80:81], v[80:81], v[82:83]
	v_pk_add_f32 v[72:73], v[72:73], v[84:85]
	v_cvt_pk_bf16_f32 v74, v80, v81
	v_cvt_pk_bf16_f32 v75, v72, v73
	ds_write_b64 v19, v[74:75] offset:16
	ds_read_b32 v72, v31
	ds_read_b32 v74, v33
	s_waitcnt lgkmcnt(3)
	v_lshlrev_b32_e32 v76, 16, v78
	v_and_b32_e32 v77, 0xffff0000, v78
	v_lshlrev_b32_e32 v78, 16, v79
	s_waitcnt lgkmcnt(1)
	v_pk_add_f32 v[76:77], v[76:77], v[72:73] op_sel_hi:[1,0] neg_lo:[0,1] neg_hi:[0,1]
	v_and_b32_e32 v79, 0xffff0000, v79
	s_waitcnt lgkmcnt(0)
	v_pk_mul_f32 v[76:77], v[74:75], v[76:77] op_sel_hi:[0,1]
	v_pk_fma_f32 v[64:65], v[64:65], v[76:77], v[68:69]
	v_pk_add_f32 v[68:69], v[78:79], v[72:73] op_sel_hi:[1,0] neg_lo:[0,1] neg_hi:[0,1]
	v_lshlrev_b32_e32 v80, 16, v92
	v_pk_mul_f32 v[68:69], v[74:75], v[68:69] op_sel_hi:[0,1]
	v_and_b32_e32 v81, 0xffff0000, v92
	v_lshlrev_b32_e32 v82, 16, v94
	v_and_b32_e32 v83, 0xffff0000, v94
	v_pk_fma_f32 v[66:67], v[66:67], v[68:69], v[70:71]
	v_pk_add_f32 v[64:65], v[64:65], v[80:81]
	v_pk_add_f32 v[66:67], v[66:67], v[82:83]
	v_cvt_pk_bf16_f32 v64, v64, v65
	v_cvt_pk_bf16_f32 v65, v66, v67
	ds_write_b64 v19, v[64:65] offset:16656
	v_add_u32_e32 v53, 0x25040, v27
	v_add_u32_e32 v55, 0x25440, v27
	ds_read_b64 v[72:73], v19 offset:32
	ds_read_b128 v[64:67], v53
	ds_read_b128 v[68:71], v55
	ds_read_b32 v74, v29
	ds_read_b32 v76, v30
	ds_read_b64 v[78:79], v19 offset:16672
	s_waitcnt lgkmcnt(5)
	v_lshlrev_b32_e32 v80, 16, v72
	v_and_b32_e32 v81, 0xffff0000, v72
	v_lshlrev_b32_e32 v72, 16, v73
	v_and_b32_e32 v73, 0xffff0000, v73
	s_waitcnt lgkmcnt(2)
	v_pk_add_f32 v[80:81], v[80:81], v[74:75] op_sel_hi:[1,0] neg_lo:[0,1] neg_hi:[0,1]
	v_pk_add_f32 v[72:73], v[72:73], v[74:75] op_sel_hi:[1,0] neg_lo:[0,1] neg_hi:[0,1]
	s_waitcnt lgkmcnt(1)
	v_pk_mul_f32 v[80:81], v[76:77], v[80:81] op_sel_hi:[0,1]
	v_pk_mul_f32 v[72:73], v[76:77], v[72:73] op_sel_hi:[0,1]
	v_lshlrev_b32_e32 v82, 16, v88
	v_and_b32_e32 v83, 0xffff0000, v88
	v_lshlrev_b32_e32 v84, 16, v90
	v_and_b32_e32 v85, 0xffff0000, v90
	v_pk_fma_f32 v[80:81], v[64:65], v[80:81], v[68:69]
	v_pk_fma_f32 v[72:73], v[66:67], v[72:73], v[70:71]
	v_pk_add_f32 v[80:81], v[80:81], v[82:83]
	v_pk_add_f32 v[72:73], v[72:73], v[84:85]
	v_cvt_pk_bf16_f32 v74, v80, v81
	v_cvt_pk_bf16_f32 v75, v72, v73
	ds_write_b64 v19, v[74:75] offset:32
	ds_read_b32 v72, v31
	ds_read_b32 v74, v33
	s_waitcnt lgkmcnt(3)
; DI unsigned pack2(float a, float b) { f32x2_t v = {a, b}; bf16x2_t r = __builtin_convertvector(v, bf16x2_t); return __builtin_bit_cast(unsigned, r); }
; DI float bflo(unsigned u) { return __uint_as_float(u << 16); }
; DI float bfhi(unsigned u) { return __uint_as_float(u & 0xffff0000u); }
; template <bool LAST>
; DI void phase_gate(const Params& P, int layer, unsigned char* smem, int L, int G) {
;     ...
; #pragma unroll
;     for (int i = 0; i < 4; ++i)
; #pragma unroll
;       for (int q4 = 0; q4 < 4; ++q4) {
;         const int fl = wm2 * 128 + i * 32 + 8 * q4 + 4 * h2;
;         const int f0 = nt * 256 + fl;
;         const f32x4 gv = *(const f32x4*)(vecL + 512 + fl), bv = *(const f32x4*)(vecL + 768 + fl);
;         const float ga[4] = {gv.x, gv.y, gv.z, gv.w}, ba[4] = {bv.x, bv.y, bv.z, bv.w};
; #pragma unroll
;         for (int j = 0; j < 2; ++j) {
;           const int lrow = wn2 * 64 + j * 32 + r2;
;           const float mu = rowA[lrow], rstd = rowB[lrow];
;           uint2* sp = (uint2*)(stg + lrow * STG + fl);
;           const uint2 sv = *sp;
;           const float sa[4] = {bflo(sv.x), bfhi(sv.x), bflo(sv.y), bfhi(sv.y)};
;           float y[4];
;           const float gg[4] = {bflo(gq[i][j][2 * q4]), bfhi(gq[i][j][2 * q4]), bflo(gq[i][j][2 * q4 + 1]), bfhi(gq[i][j][2 * q4 + 1])};
; #pragma unroll
;           for (int e = 0; e < 4; ++e) y[e] = (sa[e] - mu) * rstd * ga[e] + ba[e] + gg[e];
;           if (LAST) { f32x4 o = {y[0], y[1], y[2], y[3]}; *(f32x4*)(P.out + (size_t)(mt * 256 + lrow) * 1024 + f0) = o; }
;           else { uint2 pk; pk.x = pack2(y[0], y[1]); pk.y = pack2(y[2], y[3]); *sp = pk; }
;         }
;         __builtin_amdgcn_sched_barrier(0);
;       }
	v_lshlrev_b32_e32 v76, 16, v78
	v_and_b32_e32 v77, 0xffff0000, v78
	v_lshlrev_b32_e32 v78, 16, v79
	s_waitcnt lgkmcnt(1)
	v_pk_add_f32 v[76:77], v[76:77], v[72:73] op_sel_hi:[1,0] neg_lo:[0,1] neg_hi:[0,1]
	v_and_b32_e32 v79, 0xffff0000, v79
	s_waitcnt lgkmcnt(0)
	v_pk_mul_f32 v[76:77], v[74:75], v[76:77] op_sel_hi:[0,1]
	v_pk_fma_f32 v[64:65], v[64:65], v[76:77], v[68:69]
	v_pk_add_f32 v[68:69], v[78:79], v[72:73] op_sel_hi:[1,0] neg_lo:[0,1] neg_hi:[0,1]
	v_lshlrev_b32_e32 v80, 16, v87
	v_pk_mul_f32 v[68:69], v[74:75], v[68:69] op_sel_hi:[0,1]
	v_and_b32_e32 v81, 0xffff0000, v87
	v_lshlrev_b32_e32 v82, 16, v89
	v_and_b32_e32 v83, 0xffff0000, v89
	v_pk_fma_f32 v[66:67], v[66:67], v[68:69], v[70:71]
	v_pk_add_f32 v[64:65], v[64:65], v[80:81]
	v_pk_add_f32 v[66:67], v[66:67], v[82:83]
	v_cvt_pk_bf16_f32 v64, v64, v65
	v_cvt_pk_bf16_f32 v65, v66, v67
	ds_write_b64 v19, v[64:65] offset:16672
	v_add_u32_e32 v53, 0x25060, v27
	v_add_u32_e32 v55, 0x25460, v27
	ds_read_b64 v[72:73], v19 offset:48
	ds_read_b128 v[64:67], v53
	ds_read_b128 v[68:71], v55
	ds_read_b32 v74, v29
	ds_read_b32 v76, v30
	ds_read_b64 v[78:79], v19 offset:16688
	s_waitcnt lgkmcnt(5)
	v_lshlrev_b32_e32 v80, 16, v72
	v_and_b32_e32 v81, 0xffff0000, v72
	v_lshlrev_b32_e32 v72, 16, v73
	v_and_b32_e32 v73, 0xffff0000, v73
	s_waitcnt lgkmcnt(2)
	v_pk_add_f32 v[80:81], v[80:81], v[74:75] op_sel_hi:[1,0] neg_lo:[0,1] neg_hi:[0,1]
	v_pk_add_f32 v[72:73], v[72:73], v[74:75] op_sel_hi:[1,0] neg_lo:[0,1] neg_hi:[0,1]
	s_waitcnt lgkmcnt(1)
	v_pk_mul_f32 v[80:81], v[76:77], v[80:81] op_sel_hi:[0,1]
	v_pk_mul_f32 v[72:73], v[76:77], v[72:73] op_sel_hi:[0,1]
	v_lshlrev_b32_e32 v82, 16, v61
	v_and_b32_e32 v83, 0xffff0000, v61
	v_lshlrev_b32_e32 v84, 16, v63
	v_and_b32_e32 v85, 0xffff0000, v63
	v_pk_fma_f32 v[80:81], v[64:65], v[80:81], v[68:69]
	v_pk_fma_f32 v[72:73], v[66:67], v[72:73], v[70:71]
	v_pk_add_f32 v[80:81], v[80:81], v[82:83]
	v_pk_add_f32 v[72:73], v[72:73], v[84:85]
	v_cvt_pk_bf16_f32 v74, v80, v81
	v_cvt_pk_bf16_f32 v75, v72, v73
	ds_write_b64 v19, v[74:75] offset:48
	ds_read_b32 v72, v31
	ds_read_b32 v74, v33
	s_waitcnt lgkmcnt(3)
	v_lshlrev_b32_e32 v76, 16, v78
	v_and_b32_e32 v77, 0xffff0000, v78
	v_lshlrev_b32_e32 v80, 16, v60
	v_and_b32_e32 v81, 0xffff0000, v60
	v_lshlrev_b32_e32 v60, 16, v62
	v_and_b32_e32 v61, 0xffff0000, v62
	s_waitcnt lgkmcnt(1)
	v_pk_add_f32 v[62:63], v[76:77], v[72:73] op_sel_hi:[1,0] neg_lo:[0,1] neg_hi:[0,1]
	v_lshlrev_b32_e32 v78, 16, v79
	v_and_b32_e32 v79, 0xffff0000, v79
	s_waitcnt lgkmcnt(0)
	v_pk_mul_f32 v[62:63], v[74:75], v[62:63] op_sel_hi:[0,1]
	v_pk_fma_f32 v[62:63], v[64:65], v[62:63], v[68:69]
	v_pk_add_f32 v[64:65], v[78:79], v[72:73] op_sel_hi:[1,0] neg_lo:[0,1] neg_hi:[0,1]
	v_pk_add_f32 v[62:63], v[62:63], v[80:81]
	v_pk_mul_f32 v[64:65], v[74:75], v[64:65] op_sel_hi:[0,1]
	v_pk_fma_f32 v[64:65], v[66:67], v[64:65], v[70:71]
	v_cvt_pk_bf16_f32 v62, v62, v63
	v_pk_add_f32 v[60:61], v[64:65], v[60:61]
	s_nop 0
	v_cvt_pk_bf16_f32 v63, v60, v61
	ds_write_b64 v19, v[62:63] offset:16688
	v_add_u32_e32 v53, 0x25080, v27
	v_add_u32_e32 v55, 0x25480, v27
	ds_read_b64 v[68:69], v19 offset:64
	ds_read_b128 v[60:63], v53
	ds_read_b128 v[64:67], v55
	ds_read_b32 v70, v29
	ds_read_b32 v72, v30
	ds_read_b64 v[74:75], v19 offset:16704
	s_waitcnt lgkmcnt(5)
	v_lshlrev_b32_e32 v76, 16, v68
	v_and_b32_e32 v77, 0xffff0000, v68
	v_lshlrev_b32_e32 v68, 16, v69
	v_and_b32_e32 v69, 0xffff0000, v69
	v_lshlrev_b32_e32 v80, 16, v58
	v_and_b32_e32 v81, 0xffff0000, v58
	s_waitcnt lgkmcnt(2)
	v_pk_add_f32 v[58:59], v[76:77], v[70:71] op_sel_hi:[1,0] neg_lo:[0,1] neg_hi:[0,1]
	v_pk_add_f32 v[68:69], v[68:69], v[70:71] op_sel_hi:[1,0] neg_lo:[0,1] neg_hi:[0,1]
	s_waitcnt lgkmcnt(1)
	v_pk_mul_f32 v[58:59], v[72:73], v[58:59] op_sel_hi:[0,1]
	v_pk_mul_f32 v[68:69], v[72:73], v[68:69] op_sel_hi:[0,1]
	v_lshlrev_b32_e32 v78, 16, v56
	v_and_b32_e32 v79, 0xffff0000, v56
	v_pk_fma_f32 v[58:59], v[60:61], v[58:59], v[64:65]
	v_pk_fma_f32 v[68:69], v[62:63], v[68:69], v[66:67]
	v_pk_add_f32 v[58:59], v[58:59], v[78:79]
	v_pk_add_f32 v[68:69], v[68:69], v[80:81]
	v_cvt_pk_bf16_f32 v58, v58, v59
	v_cvt_pk_bf16_f32 v59, v68, v69
	ds_write_b64 v19, v[58:59] offset:64
	ds_read_b32 v56, v31
	ds_read_b32 v58, v33
	s_waitcnt lgkmcnt(3)
	v_lshlrev_b32_e32 v68, 16, v74
	v_and_b32_e32 v69, 0xffff0000, v74
	v_lshlrev_b32_e32 v70, 16, v75
	v_and_b32_e32 v71, 0xffff0000, v75
	v_lshlrev_b32_e32 v72, 16, v54
	v_and_b32_e32 v73, 0xffff0000, v54
	v_lshlrev_b32_e32 v54, 16, v57
	v_and_b32_e32 v55, 0xffff0000, v57
	s_waitcnt lgkmcnt(1)
	v_pk_add_f32 v[68:69], v[68:69], v[56:57] op_sel_hi:[1,0] neg_lo:[0,1] neg_hi:[0,1]
	v_pk_add_f32 v[56:57], v[70:71], v[56:57] op_sel_hi:[1,0] neg_lo:[0,1] neg_hi:[0,1]
	s_waitcnt lgkmcnt(0)
	v_pk_mul_f32 v[68:69], v[58:59], v[68:69] op_sel_hi:[0,1]
	v_pk_mul_f32 v[56:57], v[58:59], v[56:57] op_sel_hi:[0,1]
	v_pk_fma_f32 v[60:61], v[60:61], v[68:69], v[64:65]
	v_pk_fma_f32 v[56:57], v[62:63], v[56:57], v[66:67]
	v_pk_add_f32 v[60:61], v[60:61], v[72:73]
	v_pk_add_f32 v[54:55], v[56:57], v[54:55]
	v_cvt_pk_bf16_f32 v56, v60, v61
	v_cvt_pk_bf16_f32 v57, v54, v55
	ds_write_b64 v19, v[56:57] offset:16704
	v_add_u32_e32 v58, 0x254a0, v27
	v_add_u32_e32 v53, 0x250a0, v27
	ds_read_b64 v[62:63], v19 offset:80
	ds_read_b128 v[54:57], v53
	ds_read_b128 v[58:61], v58
	ds_read_b32 v64, v29
	ds_read_b32 v66, v30
	ds_read_b64 v[68:69], v19 offset:16720
	s_waitcnt lgkmcnt(5)
	v_lshlrev_b32_e32 v70, 16, v62
	v_and_b32_e32 v71, 0xffff0000, v62
	v_lshlrev_b32_e32 v62, 16, v63
	v_and_b32_e32 v63, 0xffff0000, v63
	v_lshlrev_b32_e32 v74, 16, v52
	v_and_b32_e32 v75, 0xffff0000, v52
	s_waitcnt lgkmcnt(2)
; DI unsigned pack2(float a, float b) { f32x2_t v = {a, b}; bf16x2_t r = __builtin_convertvector(v, bf16x2_t); return __builtin_bit_cast(unsigned, r); }
; DI float bflo(unsigned u) { return __uint_as_float(u << 16); }
; DI float bfhi(unsigned u) { return __uint_as_float(u & 0xffff0000u); }
; template <bool LAST>
; DI void phase_gate(const Params& P, int layer, unsigned char* smem, int L, int G) {
;     ...
; #pragma unroll
;     for (int i = 0; i < 4; ++i)
; #pragma unroll
;       for (int q4 = 0; q4 < 4; ++q4) {
;         const int fl = wm2 * 128 + i * 32 + 8 * q4 + 4 * h2;
;         const int f0 = nt * 256 + fl;
;         const f32x4 gv = *(const f32x4*)(vecL + 512 + fl), bv = *(const f32x4*)(vecL + 768 + fl);
;         const float ga[4] = {gv.x, gv.y, gv.z, gv.w}, ba[4] = {bv.x, bv.y, bv.z, bv.w};
; #pragma unroll
;         for (int j = 0; j < 2; ++j) {
;           const int lrow = wn2 * 64 + j * 32 + r2;
;           const float mu = rowA[lrow], rstd = rowB[lrow];
;           uint2* sp = (uint2*)(stg + lrow * STG + fl);
;           const uint2 sv = *sp;
;           const float sa[4] = {bflo(sv.x), bfhi(sv.x), bflo(sv.y), bfhi(sv.y)};
;           float y[4];
;           const float gg[4] = {bflo(gq[i][j][2 * q4]), bfhi(gq[i][j][2 * q4]), bflo(gq[i][j][2 * q4 + 1]), bfhi(gq[i][j][2 * q4 + 1])};
; #pragma unroll
;           for (int e = 0; e < 4; ++e) y[e] = (sa[e] - mu) * rstd * ga[e] + ba[e] + gg[e];
;           if (LAST) { f32x4 o = {y[0], y[1], y[2], y[3]}; *(f32x4*)(P.out + (size_t)(mt * 256 + lrow) * 1024 + f0) = o; }
;           else { uint2 pk; pk.x = pack2(y[0], y[1]); pk.y = pack2(y[2], y[3]); *sp = pk; }
;         }
;         __builtin_amdgcn_sched_barrier(0);
;       }
	v_pk_add_f32 v[52:53], v[70:71], v[64:65] op_sel_hi:[1,0] neg_lo:[0,1] neg_hi:[0,1]
	v_pk_add_f32 v[62:63], v[62:63], v[64:65] op_sel_hi:[1,0] neg_lo:[0,1] neg_hi:[0,1]
	s_waitcnt lgkmcnt(1)
	v_pk_mul_f32 v[52:53], v[66:67], v[52:53] op_sel_hi:[0,1]
	v_pk_mul_f32 v[62:63], v[66:67], v[62:63] op_sel_hi:[0,1]
	v_lshlrev_b32_e32 v72, 16, v50
	v_and_b32_e32 v73, 0xffff0000, v50
	v_pk_fma_f32 v[52:53], v[54:55], v[52:53], v[58:59]
	v_pk_fma_f32 v[62:63], v[56:57], v[62:63], v[60:61]
	v_pk_add_f32 v[52:53], v[52:53], v[72:73]
	v_pk_add_f32 v[62:63], v[62:63], v[74:75]
	v_cvt_pk_bf16_f32 v52, v52, v53
	v_cvt_pk_bf16_f32 v53, v62, v63
	ds_write_b64 v19, v[52:53] offset:80
	ds_read_b32 v50, v31
	ds_read_b32 v52, v33
	s_waitcnt lgkmcnt(3)
	v_lshlrev_b32_e32 v62, 16, v68
	v_and_b32_e32 v63, 0xffff0000, v68
	v_lshlrev_b32_e32 v64, 16, v69
	v_and_b32_e32 v65, 0xffff0000, v69
	v_lshlrev_b32_e32 v68, 16, v51
	v_and_b32_e32 v69, 0xffff0000, v51
	s_waitcnt lgkmcnt(1)
	v_pk_add_f32 v[62:63], v[62:63], v[50:51] op_sel_hi:[1,0] neg_lo:[0,1] neg_hi:[0,1]
	v_pk_add_f32 v[50:51], v[64:65], v[50:51] op_sel_hi:[1,0] neg_lo:[0,1] neg_hi:[0,1]
	s_waitcnt lgkmcnt(0)
	v_pk_mul_f32 v[62:63], v[52:53], v[62:63] op_sel_hi:[0,1]
	v_pk_mul_f32 v[50:51], v[52:53], v[50:51] op_sel_hi:[0,1]
	v_lshlrev_b32_e32 v66, 16, v49
	v_and_b32_e32 v67, 0xffff0000, v49
	v_pk_fma_f32 v[54:55], v[54:55], v[62:63], v[58:59]
	v_pk_fma_f32 v[50:51], v[56:57], v[50:51], v[60:61]
	v_pk_add_f32 v[54:55], v[54:55], v[66:67]
	v_pk_add_f32 v[50:51], v[50:51], v[68:69]
	v_cvt_pk_bf16_f32 v52, v54, v55
	v_cvt_pk_bf16_f32 v53, v50, v51
	ds_write_b64 v19, v[52:53] offset:16720
	v_add_u32_e32 v54, 0x254c0, v27
	v_add_u32_e32 v49, 0x250c0, v27
	ds_read_b64 v[58:59], v19 offset:96
	ds_read_b128 v[50:53], v49
	ds_read_b128 v[54:57], v54
	ds_read_b32 v60, v29
	ds_read_b32 v62, v30
	ds_read_b64 v[64:65], v19 offset:16736
	s_waitcnt lgkmcnt(5)
	v_lshlrev_b32_e32 v66, 16, v58
	v_and_b32_e32 v67, 0xffff0000, v58
	v_lshlrev_b32_e32 v58, 16, v59
	v_and_b32_e32 v59, 0xffff0000, v59
	v_lshlrev_b32_e32 v70, 16, v48
	v_and_b32_e32 v71, 0xffff0000, v48
	s_waitcnt lgkmcnt(2)
	v_pk_add_f32 v[48:49], v[66:67], v[60:61] op_sel_hi:[1,0] neg_lo:[0,1] neg_hi:[0,1]
	v_pk_add_f32 v[58:59], v[58:59], v[60:61] op_sel_hi:[1,0] neg_lo:[0,1] neg_hi:[0,1]
	s_waitcnt lgkmcnt(1)
	v_pk_mul_f32 v[48:49], v[62:63], v[48:49] op_sel_hi:[0,1]
	v_pk_mul_f32 v[58:59], v[62:63], v[58:59] op_sel_hi:[0,1]
	v_lshlrev_b32_e32 v68, 16, v46
	v_and_b32_e32 v69, 0xffff0000, v46
	v_pk_fma_f32 v[48:49], v[50:51], v[48:49], v[54:55]
	v_pk_fma_f32 v[58:59], v[52:53], v[58:59], v[56:57]
	v_pk_add_f32 v[48:49], v[48:49], v[68:69]
	v_pk_add_f32 v[58:59], v[58:59], v[70:71]
	v_cvt_pk_bf16_f32 v48, v48, v49
	v_cvt_pk_bf16_f32 v49, v58, v59
	ds_write_b64 v19, v[48:49] offset:96
	ds_read_b32 v46, v31
	ds_read_b32 v48, v33
	s_waitcnt lgkmcnt(3)
	v_lshlrev_b32_e32 v58, 16, v64
	v_and_b32_e32 v59, 0xffff0000, v64
	v_lshlrev_b32_e32 v60, 16, v65
	v_and_b32_e32 v61, 0xffff0000, v65
	v_lshlrev_b32_e32 v64, 16, v47
	v_and_b32_e32 v65, 0xffff0000, v47
	s_waitcnt lgkmcnt(1)
	v_pk_add_f32 v[58:59], v[58:59], v[46:47] op_sel_hi:[1,0] neg_lo:[0,1] neg_hi:[0,1]
	v_pk_add_f32 v[46:47], v[60:61], v[46:47] op_sel_hi:[1,0] neg_lo:[0,1] neg_hi:[0,1]
	s_waitcnt lgkmcnt(0)
	v_pk_mul_f32 v[58:59], v[48:49], v[58:59] op_sel_hi:[0,1]
	v_pk_mul_f32 v[46:47], v[48:49], v[46:47] op_sel_hi:[0,1]
	v_lshlrev_b32_e32 v62, 16, v45
	v_and_b32_e32 v63, 0xffff0000, v45
	v_pk_fma_f32 v[50:51], v[50:51], v[58:59], v[54:55]
	v_pk_fma_f32 v[46:47], v[52:53], v[46:47], v[56:57]
	v_pk_add_f32 v[50:51], v[50:51], v[62:63]
	v_pk_add_f32 v[46:47], v[46:47], v[64:65]
	v_cvt_pk_bf16_f32 v48, v50, v51
	v_cvt_pk_bf16_f32 v49, v46, v47
	ds_write_b64 v19, v[48:49] offset:16736
	v_add_u32_e32 v50, 0x254e0, v27
	v_add_u32_e32 v45, 0x250e0, v27
	ds_read_b64 v[54:55], v19 offset:112
	ds_read_b128 v[46:49], v45
	ds_read_b128 v[50:53], v50
	ds_read_b32 v56, v29
	ds_read_b32 v58, v30
	ds_read_b64 v[60:61], v19 offset:16752
	s_waitcnt lgkmcnt(5)
	v_lshlrev_b32_e32 v62, 16, v54
	v_and_b32_e32 v63, 0xffff0000, v54
	v_lshlrev_b32_e32 v54, 16, v55
	v_and_b32_e32 v55, 0xffff0000, v55
	v_lshlrev_b32_e32 v66, 16, v44
	v_and_b32_e32 v67, 0xffff0000, v44
	s_waitcnt lgkmcnt(2)
	v_pk_add_f32 v[44:45], v[62:63], v[56:57] op_sel_hi:[1,0] neg_lo:[0,1] neg_hi:[0,1]
	v_pk_add_f32 v[54:55], v[54:55], v[56:57] op_sel_hi:[1,0] neg_lo:[0,1] neg_hi:[0,1]
	s_waitcnt lgkmcnt(1)
	v_pk_mul_f32 v[44:45], v[58:59], v[44:45] op_sel_hi:[0,1]
	v_pk_mul_f32 v[54:55], v[58:59], v[54:55] op_sel_hi:[0,1]
	v_lshlrev_b32_e32 v64, 16, v42
	v_and_b32_e32 v65, 0xffff0000, v42
	v_pk_fma_f32 v[44:45], v[46:47], v[44:45], v[50:51]
	v_pk_fma_f32 v[54:55], v[48:49], v[54:55], v[52:53]
	v_pk_add_f32 v[44:45], v[44:45], v[64:65]
	v_pk_add_f32 v[54:55], v[54:55], v[66:67]
	v_cvt_pk_bf16_f32 v44, v44, v45
	v_cvt_pk_bf16_f32 v45, v54, v55
	ds_write_b64 v19, v[44:45] offset:112
	ds_read_b32 v42, v31
	ds_read_b32 v44, v33
	s_waitcnt lgkmcnt(3)
	v_lshlrev_b32_e32 v54, 16, v60
	v_and_b32_e32 v55, 0xffff0000, v60
	v_lshlrev_b32_e32 v56, 16, v61
	v_and_b32_e32 v57, 0xffff0000, v61
	v_lshlrev_b32_e32 v60, 16, v43
	v_and_b32_e32 v61, 0xffff0000, v43
	s_waitcnt lgkmcnt(1)
	v_pk_add_f32 v[54:55], v[54:55], v[42:43] op_sel_hi:[1,0] neg_lo:[0,1] neg_hi:[0,1]
	v_pk_add_f32 v[42:43], v[56:57], v[42:43] op_sel_hi:[1,0] neg_lo:[0,1] neg_hi:[0,1]
	s_waitcnt lgkmcnt(0)
; DI unsigned pack2(float a, float b) { f32x2_t v = {a, b}; bf16x2_t r = __builtin_convertvector(v, bf16x2_t); return __builtin_bit_cast(unsigned, r); }
; DI float bflo(unsigned u) { return __uint_as_float(u << 16); }
; DI float bfhi(unsigned u) { return __uint_as_float(u & 0xffff0000u); }
; template <bool LAST>
; DI void phase_gate(const Params& P, int layer, unsigned char* smem, int L, int G) {
;     ...
; #pragma unroll
;     for (int i = 0; i < 4; ++i)
; #pragma unroll
;       for (int q4 = 0; q4 < 4; ++q4) {
;         const int fl = wm2 * 128 + i * 32 + 8 * q4 + 4 * h2;
;         const int f0 = nt * 256 + fl;
;         const f32x4 gv = *(const f32x4*)(vecL + 512 + fl), bv = *(const f32x4*)(vecL + 768 + fl);
;         const float ga[4] = {gv.x, gv.y, gv.z, gv.w}, ba[4] = {bv.x, bv.y, bv.z, bv.w};
; #pragma unroll
;         for (int j = 0; j < 2; ++j) {
;           const int lrow = wn2 * 64 + j * 32 + r2;
;           const float mu = rowA[lrow], rstd = rowB[lrow];
;           uint2* sp = (uint2*)(stg + lrow * STG + fl);
;           const uint2 sv = *sp;
;           const float sa[4] = {bflo(sv.x), bfhi(sv.x), bflo(sv.y), bfhi(sv.y)};
;           float y[4];
;           const float gg[4] = {bflo(gq[i][j][2 * q4]), bfhi(gq[i][j][2 * q4]), bflo(gq[i][j][2 * q4 + 1]), bfhi(gq[i][j][2 * q4 + 1])};
; #pragma unroll
;           for (int e = 0; e < 4; ++e) y[e] = (sa[e] - mu) * rstd * ga[e] + ba[e] + gg[e];
;           if (LAST) { f32x4 o = {y[0], y[1], y[2], y[3]}; *(f32x4*)(P.out + (size_t)(mt * 256 + lrow) * 1024 + f0) = o; }
;           else { uint2 pk; pk.x = pack2(y[0], y[1]); pk.y = pack2(y[2], y[3]); *sp = pk; }
;         }
;         __builtin_amdgcn_sched_barrier(0);
;       }
	v_pk_mul_f32 v[54:55], v[44:45], v[54:55] op_sel_hi:[0,1]
	v_pk_mul_f32 v[42:43], v[44:45], v[42:43] op_sel_hi:[0,1]
	v_lshlrev_b32_e32 v58, 16, v41
	v_and_b32_e32 v59, 0xffff0000, v41
	v_pk_fma_f32 v[46:47], v[46:47], v[54:55], v[50:51]
	v_pk_fma_f32 v[42:43], v[48:49], v[42:43], v[52:53]
	v_pk_add_f32 v[46:47], v[46:47], v[58:59]
	v_pk_add_f32 v[42:43], v[42:43], v[60:61]
	v_cvt_pk_bf16_f32 v44, v46, v47
	v_cvt_pk_bf16_f32 v45, v42, v43
	ds_write_b64 v19, v[44:45] offset:16752
	v_add_u32_e32 v46, 0x25500, v27
	v_add_u32_e32 v41, 0x25100, v27
	ds_read_b64 v[50:51], v19 offset:128
	ds_read_b128 v[42:45], v41
	ds_read_b128 v[46:49], v46
	ds_read_b32 v52, v29
	ds_read_b32 v54, v30
	ds_read_b64 v[56:57], v19 offset:16768
	s_waitcnt lgkmcnt(5)
	v_lshlrev_b32_e32 v58, 16, v50
	v_and_b32_e32 v59, 0xffff0000, v50
	v_lshlrev_b32_e32 v50, 16, v51
	v_and_b32_e32 v51, 0xffff0000, v51
	v_lshlrev_b32_e32 v62, 16, v40
	v_and_b32_e32 v63, 0xffff0000, v40
	s_waitcnt lgkmcnt(2)
	v_pk_add_f32 v[40:41], v[58:59], v[52:53] op_sel_hi:[1,0] neg_lo:[0,1] neg_hi:[0,1]
	v_pk_add_f32 v[50:51], v[50:51], v[52:53] op_sel_hi:[1,0] neg_lo:[0,1] neg_hi:[0,1]
	s_waitcnt lgkmcnt(1)
	v_pk_mul_f32 v[40:41], v[54:55], v[40:41] op_sel_hi:[0,1]
	v_pk_mul_f32 v[50:51], v[54:55], v[50:51] op_sel_hi:[0,1]
	v_lshlrev_b32_e32 v60, 16, v38
	v_and_b32_e32 v61, 0xffff0000, v38
	v_pk_fma_f32 v[40:41], v[42:43], v[40:41], v[46:47]
	v_pk_fma_f32 v[50:51], v[44:45], v[50:51], v[48:49]
	v_pk_add_f32 v[40:41], v[40:41], v[60:61]
	v_pk_add_f32 v[50:51], v[50:51], v[62:63]
	v_cvt_pk_bf16_f32 v40, v40, v41
	v_cvt_pk_bf16_f32 v41, v50, v51
	ds_write_b64 v19, v[40:41] offset:128
	ds_read_b32 v38, v31
	ds_read_b32 v40, v33
	s_waitcnt lgkmcnt(3)
	v_lshlrev_b32_e32 v50, 16, v56
	v_and_b32_e32 v51, 0xffff0000, v56
	v_lshlrev_b32_e32 v52, 16, v57
	v_and_b32_e32 v53, 0xffff0000, v57
	v_lshlrev_b32_e32 v56, 16, v39
	v_and_b32_e32 v57, 0xffff0000, v39
	s_waitcnt lgkmcnt(1)
	v_pk_add_f32 v[50:51], v[50:51], v[38:39] op_sel_hi:[1,0] neg_lo:[0,1] neg_hi:[0,1]
	v_pk_add_f32 v[38:39], v[52:53], v[38:39] op_sel_hi:[1,0] neg_lo:[0,1] neg_hi:[0,1]
	s_waitcnt lgkmcnt(0)
	v_pk_mul_f32 v[50:51], v[40:41], v[50:51] op_sel_hi:[0,1]
	v_pk_mul_f32 v[38:39], v[40:41], v[38:39] op_sel_hi:[0,1]
	v_lshlrev_b32_e32 v54, 16, v37
	v_and_b32_e32 v55, 0xffff0000, v37
	v_pk_fma_f32 v[42:43], v[42:43], v[50:51], v[46:47]
	v_pk_fma_f32 v[38:39], v[44:45], v[38:39], v[48:49]
	v_pk_add_f32 v[42:43], v[42:43], v[54:55]
	v_pk_add_f32 v[38:39], v[38:39], v[56:57]
	v_cvt_pk_bf16_f32 v40, v42, v43
	v_cvt_pk_bf16_f32 v41, v38, v39
	ds_write_b64 v19, v[40:41] offset:16768
	v_add_u32_e32 v42, 0x25520, v27
	v_add_u32_e32 v37, 0x25120, v27
	ds_read_b64 v[46:47], v19 offset:144
	ds_read_b128 v[38:41], v37
	ds_read_b128 v[42:45], v42
	ds_read_b32 v48, v29
	ds_read_b32 v50, v30
	ds_read_b64 v[52:53], v19 offset:16784
	s_waitcnt lgkmcnt(5)
	v_lshlrev_b32_e32 v54, 16, v46
	v_and_b32_e32 v55, 0xffff0000, v46
	v_lshlrev_b32_e32 v46, 16, v47
	v_and_b32_e32 v47, 0xffff0000, v47
	v_lshlrev_b32_e32 v58, 16, v36
	v_and_b32_e32 v59, 0xffff0000, v36
	s_waitcnt lgkmcnt(2)
	v_pk_add_f32 v[36:37], v[54:55], v[48:49] op_sel_hi:[1,0] neg_lo:[0,1] neg_hi:[0,1]
	v_pk_add_f32 v[46:47], v[46:47], v[48:49] op_sel_hi:[1,0] neg_lo:[0,1] neg_hi:[0,1]
	s_waitcnt lgkmcnt(1)
	v_pk_mul_f32 v[36:37], v[50:51], v[36:37] op_sel_hi:[0,1]
	v_pk_mul_f32 v[46:47], v[50:51], v[46:47] op_sel_hi:[0,1]
	v_lshlrev_b32_e32 v56, 16, v34
	v_and_b32_e32 v57, 0xffff0000, v34
	v_pk_fma_f32 v[36:37], v[38:39], v[36:37], v[42:43]
	v_pk_fma_f32 v[46:47], v[40:41], v[46:47], v[44:45]
	v_pk_add_f32 v[36:37], v[36:37], v[56:57]
	v_pk_add_f32 v[46:47], v[46:47], v[58:59]
	v_cvt_pk_bf16_f32 v36, v36, v37
	v_cvt_pk_bf16_f32 v37, v46, v47
	ds_write_b64 v19, v[36:37] offset:144
	ds_read_b32 v34, v31
	ds_read_b32 v36, v33
	s_waitcnt lgkmcnt(3)
	v_lshlrev_b32_e32 v46, 16, v52
	v_and_b32_e32 v47, 0xffff0000, v52
	v_lshlrev_b32_e32 v48, 16, v53
	v_and_b32_e32 v49, 0xffff0000, v53
	v_lshlrev_b32_e32 v52, 16, v35
	v_and_b32_e32 v53, 0xffff0000, v35
	s_waitcnt lgkmcnt(1)
	v_pk_add_f32 v[46:47], v[46:47], v[34:35] op_sel_hi:[1,0] neg_lo:[0,1] neg_hi:[0,1]
	v_pk_add_f32 v[34:35], v[48:49], v[34:35] op_sel_hi:[1,0] neg_lo:[0,1] neg_hi:[0,1]
	s_waitcnt lgkmcnt(0)
	v_pk_mul_f32 v[46:47], v[36:37], v[46:47] op_sel_hi:[0,1]
	v_pk_mul_f32 v[34:35], v[36:37], v[34:35] op_sel_hi:[0,1]
	v_lshlrev_b32_e32 v50, 16, v32
	v_and_b32_e32 v51, 0xffff0000, v32
	v_pk_fma_f32 v[38:39], v[38:39], v[46:47], v[42:43]
	v_pk_fma_f32 v[34:35], v[40:41], v[34:35], v[44:45]
	v_pk_add_f32 v[38:39], v[38:39], v[50:51]
	v_pk_add_f32 v[34:35], v[34:35], v[52:53]
	v_cvt_pk_bf16_f32 v36, v38, v39
	v_cvt_pk_bf16_f32 v37, v34, v35
	ds_write_b64 v19, v[36:37] offset:16784
	v_add_u32_e32 v32, 0x25140, v27
	v_add_u32_e32 v38, 0x25540, v27
	ds_read_b64 v[42:43], v19 offset:160
	ds_read_b128 v[34:37], v32
	ds_read_b128 v[38:41], v38
	ds_read_b32 v32, v29
	ds_read_b32 v44, v30
	ds_read_b64 v[46:47], v19 offset:16800
	s_waitcnt lgkmcnt(5)
	v_lshlrev_b32_e32 v48, 16, v42
	v_and_b32_e32 v49, 0xffff0000, v42
	v_lshlrev_b32_e32 v42, 16, v43
	v_and_b32_e32 v43, 0xffff0000, v43
	s_waitcnt lgkmcnt(2)
	v_pk_add_f32 v[48:49], v[48:49], v[32:33] op_sel_hi:[1,0] neg_lo:[0,1] neg_hi:[0,1]
	v_pk_add_f32 v[42:43], v[42:43], v[32:33] op_sel_hi:[1,0] neg_lo:[0,1] neg_hi:[0,1]
	s_waitcnt lgkmcnt(1)
; DI unsigned pack2(float a, float b) { f32x2_t v = {a, b}; bf16x2_t r = __builtin_convertvector(v, bf16x2_t); return __builtin_bit_cast(unsigned, r); }
; DI float bflo(unsigned u) { return __uint_as_float(u << 16); }
; DI float bfhi(unsigned u) { return __uint_as_float(u & 0xffff0000u); }
; template <bool LAST>
; DI void phase_gate(const Params& P, int layer, unsigned char* smem, int L, int G) {
;     ...
; #pragma unroll
;     for (int i = 0; i < 4; ++i)
; #pragma unroll
;       for (int q4 = 0; q4 < 4; ++q4) {
;         const int fl = wm2 * 128 + i * 32 + 8 * q4 + 4 * h2;
;         const int f0 = nt * 256 + fl;
;         const f32x4 gv = *(const f32x4*)(vecL + 512 + fl), bv = *(const f32x4*)(vecL + 768 + fl);
;         const float ga[4] = {gv.x, gv.y, gv.z, gv.w}, ba[4] = {bv.x, bv.y, bv.z, bv.w};
; #pragma unroll
;         for (int j = 0; j < 2; ++j) {
;           const int lrow = wn2 * 64 + j * 32 + r2;
;           const float mu = rowA[lrow], rstd = rowB[lrow];
;           uint2* sp = (uint2*)(stg + lrow * STG + fl);
;           const uint2 sv = *sp;
;           const float sa[4] = {bflo(sv.x), bfhi(sv.x), bflo(sv.y), bfhi(sv.y)};
;           float y[4];
;           const float gg[4] = {bflo(gq[i][j][2 * q4]), bfhi(gq[i][j][2 * q4]), bflo(gq[i][j][2 * q4 + 1]), bfhi(gq[i][j][2 * q4 + 1])};
; #pragma unroll
;           for (int e = 0; e < 4; ++e) y[e] = (sa[e] - mu) * rstd * ga[e] + ba[e] + gg[e];
;           if (LAST) { f32x4 o = {y[0], y[1], y[2], y[3]}; *(f32x4*)(P.out + (size_t)(mt * 256 + lrow) * 1024 + f0) = o; }
;           else { uint2 pk; pk.x = pack2(y[0], y[1]); pk.y = pack2(y[2], y[3]); *sp = pk; }
;         }
;         __builtin_amdgcn_sched_barrier(0);
;       }
	v_pk_mul_f32 v[48:49], v[44:45], v[48:49] op_sel_hi:[0,1]
	v_pk_mul_f32 v[42:43], v[44:45], v[42:43] op_sel_hi:[0,1]
	v_lshlrev_b32_e32 v50, 16, v24
	v_and_b32_e32 v51, 0xffff0000, v24
	v_lshlrev_b32_e32 v52, 16, v26
	v_and_b32_e32 v53, 0xffff0000, v26
	v_pk_fma_f32 v[48:49], v[34:35], v[48:49], v[38:39]
	v_pk_fma_f32 v[42:43], v[36:37], v[42:43], v[40:41]
	v_pk_add_f32 v[48:49], v[48:49], v[50:51]
	v_pk_add_f32 v[42:43], v[42:43], v[52:53]
	v_cvt_pk_bf16_f32 v44, v48, v49
	v_cvt_pk_bf16_f32 v45, v42, v43
	ds_write_b64 v19, v[44:45] offset:160
	ds_read_b32 v24, v31
	ds_read_b32 v26, v33
	s_waitcnt lgkmcnt(3)
	v_lshlrev_b32_e32 v42, 16, v46
	v_and_b32_e32 v43, 0xffff0000, v46
	v_lshlrev_b32_e32 v44, 16, v47
	v_and_b32_e32 v45, 0xffff0000, v47
	v_lshlrev_b32_e32 v48, 16, v25
	v_and_b32_e32 v49, 0xffff0000, v25
	s_waitcnt lgkmcnt(1)
	v_pk_add_f32 v[42:43], v[42:43], v[24:25] op_sel_hi:[1,0] neg_lo:[0,1] neg_hi:[0,1]
	v_pk_add_f32 v[24:25], v[44:45], v[24:25] op_sel_hi:[1,0] neg_lo:[0,1] neg_hi:[0,1]
	s_waitcnt lgkmcnt(0)
	v_pk_mul_f32 v[42:43], v[26:27], v[42:43] op_sel_hi:[0,1]
	v_pk_mul_f32 v[24:25], v[26:27], v[24:25] op_sel_hi:[0,1]
	v_lshlrev_b32_e32 v46, 16, v23
	v_and_b32_e32 v47, 0xffff0000, v23
	v_pk_fma_f32 v[34:35], v[34:35], v[42:43], v[38:39]
	v_pk_fma_f32 v[24:25], v[36:37], v[24:25], v[40:41]
	v_pk_add_f32 v[34:35], v[34:35], v[46:47]
	v_pk_add_f32 v[24:25], v[24:25], v[48:49]
	v_cvt_pk_bf16_f32 v34, v34, v35
	v_cvt_pk_bf16_f32 v35, v24, v25
	ds_write_b64 v19, v[34:35] offset:16800
	v_add_u32_e32 v26, 0x25560, v27
	v_add_u32_e32 v23, 0x25160, v27
	ds_read_b64 v[24:25], v19 offset:176
	ds_read_b128 v[34:37], v23
	ds_read_b128 v[38:41], v26
	ds_read_b32 v26, v29
	ds_read_b32 v32, v30
	ds_read_b64 v[42:43], v19 offset:16816
	s_waitcnt lgkmcnt(5)
	v_lshlrev_b32_e32 v44, 16, v24
	v_and_b32_e32 v45, 0xffff0000, v24
	v_lshlrev_b32_e32 v24, 16, v25
	v_and_b32_e32 v25, 0xffff0000, v25
	v_lshlrev_b32_e32 v48, 16, v22
	v_and_b32_e32 v49, 0xffff0000, v22
	s_waitcnt lgkmcnt(2)
	v_pk_add_f32 v[22:23], v[44:45], v[26:27] op_sel_hi:[1,0] neg_lo:[0,1] neg_hi:[0,1]
	v_pk_add_f32 v[24:25], v[24:25], v[26:27] op_sel_hi:[1,0] neg_lo:[0,1] neg_hi:[0,1]
	s_waitcnt lgkmcnt(1)
	v_pk_mul_f32 v[22:23], v[32:33], v[22:23] op_sel_hi:[0,1]
	v_pk_mul_f32 v[24:25], v[32:33], v[24:25] op_sel_hi:[0,1]
	v_lshlrev_b32_e32 v46, 16, v20
	v_and_b32_e32 v47, 0xffff0000, v20
	v_pk_fma_f32 v[22:23], v[34:35], v[22:23], v[38:39]
	v_pk_fma_f32 v[24:25], v[36:37], v[24:25], v[40:41]
	v_pk_add_f32 v[22:23], v[22:23], v[46:47]
	v_pk_add_f32 v[24:25], v[24:25], v[48:49]
	v_cvt_pk_bf16_f32 v22, v22, v23
	v_cvt_pk_bf16_f32 v23, v24, v25
	ds_write_b64 v19, v[22:23] offset:176
	ds_read_b32 v20, v31
	ds_read_b32 v22, v33
	s_waitcnt lgkmcnt(3)
	v_lshlrev_b32_e32 v24, 16, v42
	v_and_b32_e32 v25, 0xffff0000, v42
	v_lshlrev_b32_e32 v42, 16, v43
	v_and_b32_e32 v43, 0xffff0000, v43
	v_lshlrev_b32_e32 v46, 16, v21
	v_and_b32_e32 v47, 0xffff0000, v21
	s_waitcnt lgkmcnt(1)
	v_pk_add_f32 v[24:25], v[24:25], v[20:21] op_sel_hi:[1,0] neg_lo:[0,1] neg_hi:[0,1]
	v_pk_add_f32 v[20:21], v[42:43], v[20:21] op_sel_hi:[1,0] neg_lo:[0,1] neg_hi:[0,1]
	s_waitcnt lgkmcnt(0)
	v_pk_mul_f32 v[24:25], v[22:23], v[24:25] op_sel_hi:[0,1]
	v_pk_mul_f32 v[20:21], v[22:23], v[20:21] op_sel_hi:[0,1]
	v_lshlrev_b32_e32 v44, 16, v18
	v_and_b32_e32 v45, 0xffff0000, v18
	v_pk_fma_f32 v[24:25], v[34:35], v[24:25], v[38:39]
	v_pk_fma_f32 v[20:21], v[36:37], v[20:21], v[40:41]
	v_pk_add_f32 v[24:25], v[24:25], v[44:45]
	v_pk_add_f32 v[20:21], v[20:21], v[46:47]
	v_cvt_pk_bf16_f32 v22, v24, v25
	v_cvt_pk_bf16_f32 v23, v20, v21
	ds_write_b64 v19, v[22:23] offset:16816
	v_add_u32_e32 v18, 0x25180, v27
	v_add_u32_e32 v26, 0x25580, v27
	ds_read_b64 v[24:25], v19 offset:192
	ds_read_b128 v[20:23], v18
	ds_read_b128 v[34:37], v26
	ds_read_b32 v18, v29
	ds_read_b32 v26, v30
	ds_read_b64 v[38:39], v19 offset:16832
	s_waitcnt lgkmcnt(5)
	v_lshlrev_b32_e32 v40, 16, v24
	v_and_b32_e32 v41, 0xffff0000, v24
	v_lshlrev_b32_e32 v24, 16, v25
	v_and_b32_e32 v25, 0xffff0000, v25
	s_waitcnt lgkmcnt(2)
	v_pk_add_f32 v[40:41], v[40:41], v[18:19] op_sel_hi:[1,0] neg_lo:[0,1] neg_hi:[0,1]
	v_pk_add_f32 v[24:25], v[24:25], v[18:19] op_sel_hi:[1,0] neg_lo:[0,1] neg_hi:[0,1]
	s_waitcnt lgkmcnt(1)
	v_pk_mul_f32 v[40:41], v[26:27], v[40:41] op_sel_hi:[0,1]
	v_pk_mul_f32 v[24:25], v[26:27], v[24:25] op_sel_hi:[0,1]
	v_lshlrev_b32_e32 v42, 16, v15
	v_and_b32_e32 v43, 0xffff0000, v15
	v_lshlrev_b32_e32 v44, 16, v17
	v_and_b32_e32 v45, 0xffff0000, v17
	v_pk_fma_f32 v[40:41], v[20:21], v[40:41], v[34:35]
	v_pk_fma_f32 v[24:25], v[22:23], v[24:25], v[36:37]
	v_pk_add_f32 v[40:41], v[40:41], v[42:43]
	v_pk_add_f32 v[24:25], v[24:25], v[44:45]
	v_cvt_pk_bf16_f32 v40, v40, v41
	v_cvt_pk_bf16_f32 v41, v24, v25
	ds_write_b64 v19, v[40:41] offset:192
	ds_read_b32 v18, v31
	ds_read_b32 v24, v33
	s_waitcnt lgkmcnt(3)
	v_lshlrev_b32_e32 v40, 16, v38
	v_and_b32_e32 v41, 0xffff0000, v38
	v_lshlrev_b32_e32 v42, 16, v14
	v_and_b32_e32 v43, 0xffff0000, v14
	v_lshlrev_b32_e32 v14, 16, v16
	v_and_b32_e32 v15, 0xffff0000, v16
	s_waitcnt lgkmcnt(1)
	v_pk_add_f32 v[16:17], v[40:41], v[18:19] op_sel_hi:[1,0] neg_lo:[0,1] neg_hi:[0,1]
	v_lshlrev_b32_e32 v38, 16, v39
	v_and_b32_e32 v39, 0xffff0000, v39
	s_waitcnt lgkmcnt(0)
; DI unsigned pack2(float a, float b) { f32x2_t v = {a, b}; bf16x2_t r = __builtin_convertvector(v, bf16x2_t); return __builtin_bit_cast(unsigned, r); }
; DI float bflo(unsigned u) { return __uint_as_float(u << 16); }
; DI float bfhi(unsigned u) { return __uint_as_float(u & 0xffff0000u); }
; template <bool LAST>
; DI void phase_gate(const Params& P, int layer, unsigned char* smem, int L, int G) {
;     ...
; #pragma unroll
;     for (int i = 0; i < 4; ++i)
; #pragma unroll
;       for (int q4 = 0; q4 < 4; ++q4) {
;         const int fl = wm2 * 128 + i * 32 + 8 * q4 + 4 * h2;
;         const int f0 = nt * 256 + fl;
;         const f32x4 gv = *(const f32x4*)(vecL + 512 + fl), bv = *(const f32x4*)(vecL + 768 + fl);
;         const float ga[4] = {gv.x, gv.y, gv.z, gv.w}, ba[4] = {bv.x, bv.y, bv.z, bv.w};
; #pragma unroll
;         for (int j = 0; j < 2; ++j) {
;           const int lrow = wn2 * 64 + j * 32 + r2;
;           const float mu = rowA[lrow], rstd = rowB[lrow];
;           uint2* sp = (uint2*)(stg + lrow * STG + fl);
;           const uint2 sv = *sp;
;           const float sa[4] = {bflo(sv.x), bfhi(sv.x), bflo(sv.y), bfhi(sv.y)};
;           float y[4];
;           const float gg[4] = {bflo(gq[i][j][2 * q4]), bfhi(gq[i][j][2 * q4]), bflo(gq[i][j][2 * q4 + 1]), bfhi(gq[i][j][2 * q4 + 1])};
; #pragma unroll
;           for (int e = 0; e < 4; ++e) y[e] = (sa[e] - mu) * rstd * ga[e] + ba[e] + gg[e];
;           if (LAST) { f32x4 o = {y[0], y[1], y[2], y[3]}; *(f32x4*)(P.out + (size_t)(mt * 256 + lrow) * 1024 + f0) = o; }
;           else { uint2 pk; pk.x = pack2(y[0], y[1]); pk.y = pack2(y[2], y[3]); *sp = pk; }
;         }
;         __builtin_amdgcn_sched_barrier(0);
;       }
;     __syncthreads();
	v_pk_mul_f32 v[16:17], v[24:25], v[16:17] op_sel_hi:[0,1]
	v_pk_fma_f32 v[16:17], v[20:21], v[16:17], v[34:35]
	v_pk_add_f32 v[20:21], v[38:39], v[18:19] op_sel_hi:[1,0] neg_lo:[0,1] neg_hi:[0,1]
	v_pk_add_f32 v[16:17], v[16:17], v[42:43]
	v_pk_mul_f32 v[20:21], v[24:25], v[20:21] op_sel_hi:[0,1]
	v_pk_fma_f32 v[20:21], v[22:23], v[20:21], v[36:37]
	v_cvt_pk_bf16_f32 v16, v16, v17
	v_pk_add_f32 v[14:15], v[20:21], v[14:15]
	s_nop 0
	v_cvt_pk_bf16_f32 v17, v14, v15
	ds_write_b64 v19, v[16:17] offset:16832
	v_add_u32_e32 v14, 0x251a0, v27
	v_add_u32_e32 v18, 0x255a0, v27
	ds_read_b64 v[24:25], v19 offset:208
	ds_read_b128 v[14:17], v14
	ds_read_b128 v[20:23], v18
	ds_read_b32 v18, v29
	ds_read_b32 v26, v30
	ds_read_b64 v[34:35], v19 offset:16848
	s_waitcnt lgkmcnt(5)
	v_lshlrev_b32_e32 v36, 16, v24
	v_and_b32_e32 v37, 0xffff0000, v24
	v_lshlrev_b32_e32 v24, 16, v25
	v_and_b32_e32 v25, 0xffff0000, v25
	s_waitcnt lgkmcnt(2)
	v_pk_add_f32 v[36:37], v[36:37], v[18:19] op_sel_hi:[1,0] neg_lo:[0,1] neg_hi:[0,1]
	v_pk_add_f32 v[24:25], v[24:25], v[18:19] op_sel_hi:[1,0] neg_lo:[0,1] neg_hi:[0,1]
	s_waitcnt lgkmcnt(1)
	v_pk_mul_f32 v[36:37], v[26:27], v[36:37] op_sel_hi:[0,1]
	v_pk_mul_f32 v[24:25], v[26:27], v[24:25] op_sel_hi:[0,1]
	v_lshlrev_b32_e32 v38, 16, v11
	v_and_b32_e32 v39, 0xffff0000, v11
	v_lshlrev_b32_e32 v40, 16, v13
	v_and_b32_e32 v41, 0xffff0000, v13
	v_pk_fma_f32 v[36:37], v[14:15], v[36:37], v[20:21]
	v_pk_fma_f32 v[24:25], v[16:17], v[24:25], v[22:23]
	v_pk_add_f32 v[36:37], v[36:37], v[38:39]
	v_pk_add_f32 v[24:25], v[24:25], v[40:41]
	v_cvt_pk_bf16_f32 v36, v36, v37
	v_cvt_pk_bf16_f32 v37, v24, v25
	ds_write_b64 v19, v[36:37] offset:208
	ds_read_b32 v18, v31
	ds_read_b32 v24, v33
	s_waitcnt lgkmcnt(3)
	v_lshlrev_b32_e32 v36, 16, v34
	v_and_b32_e32 v37, 0xffff0000, v34
	v_lshlrev_b32_e32 v38, 16, v10
	v_and_b32_e32 v39, 0xffff0000, v10
	v_lshlrev_b32_e32 v10, 16, v12
	v_and_b32_e32 v11, 0xffff0000, v12
	s_waitcnt lgkmcnt(1)
	v_pk_add_f32 v[12:13], v[36:37], v[18:19] op_sel_hi:[1,0] neg_lo:[0,1] neg_hi:[0,1]
	v_lshlrev_b32_e32 v34, 16, v35
	v_and_b32_e32 v35, 0xffff0000, v35
	s_waitcnt lgkmcnt(0)
	v_pk_mul_f32 v[12:13], v[24:25], v[12:13] op_sel_hi:[0,1]
	v_pk_fma_f32 v[12:13], v[14:15], v[12:13], v[20:21]
	v_pk_add_f32 v[14:15], v[34:35], v[18:19] op_sel_hi:[1,0] neg_lo:[0,1] neg_hi:[0,1]
	v_pk_add_f32 v[12:13], v[12:13], v[38:39]
	v_pk_mul_f32 v[14:15], v[24:25], v[14:15] op_sel_hi:[0,1]
	v_pk_fma_f32 v[14:15], v[16:17], v[14:15], v[22:23]
	v_cvt_pk_bf16_f32 v12, v12, v13
	v_pk_add_f32 v[10:11], v[14:15], v[10:11]
	s_nop 0
	v_cvt_pk_bf16_f32 v13, v10, v11
	ds_write_b64 v19, v[12:13] offset:16848
	v_add_u32_e32 v10, 0x251c0, v27
	v_add_u32_e32 v14, 0x255c0, v27
	ds_read_b64 v[20:21], v19 offset:224
	ds_read_b128 v[10:13], v10
	ds_read_b128 v[14:17], v14
	ds_read_b32 v18, v29
	ds_read_b32 v22, v30
	ds_read_b64 v[24:25], v19 offset:16864
	s_waitcnt lgkmcnt(5)
	v_lshlrev_b32_e32 v34, 16, v20
	v_and_b32_e32 v35, 0xffff0000, v20
	v_lshlrev_b32_e32 v20, 16, v21
	v_and_b32_e32 v21, 0xffff0000, v21
	s_waitcnt lgkmcnt(2)
	v_pk_add_f32 v[34:35], v[34:35], v[18:19] op_sel_hi:[1,0] neg_lo:[0,1] neg_hi:[0,1]
	v_pk_add_f32 v[20:21], v[20:21], v[18:19] op_sel_hi:[1,0] neg_lo:[0,1] neg_hi:[0,1]
	s_waitcnt lgkmcnt(1)
	v_pk_mul_f32 v[34:35], v[22:23], v[34:35] op_sel_hi:[0,1]
	v_pk_mul_f32 v[20:21], v[22:23], v[20:21] op_sel_hi:[0,1]
	v_lshlrev_b32_e32 v36, 16, v7
	v_and_b32_e32 v37, 0xffff0000, v7
	v_lshlrev_b32_e32 v38, 16, v9
	v_and_b32_e32 v39, 0xffff0000, v9
	v_pk_fma_f32 v[34:35], v[10:11], v[34:35], v[14:15]
	v_pk_fma_f32 v[20:21], v[12:13], v[20:21], v[16:17]
	v_pk_add_f32 v[34:35], v[34:35], v[36:37]
	v_pk_add_f32 v[20:21], v[20:21], v[38:39]
	v_cvt_pk_bf16_f32 v22, v34, v35
	v_cvt_pk_bf16_f32 v23, v20, v21
	ds_write_b64 v19, v[22:23] offset:224
	ds_read_b32 v18, v31
	ds_read_b32 v20, v33
	s_waitcnt lgkmcnt(3)
	v_lshlrev_b32_e32 v22, 16, v24
	v_and_b32_e32 v23, 0xffff0000, v24
	v_lshlrev_b32_e32 v34, 16, v6
	v_and_b32_e32 v35, 0xffff0000, v6
	v_lshlrev_b32_e32 v6, 16, v8
	v_and_b32_e32 v7, 0xffff0000, v8
	s_waitcnt lgkmcnt(1)
	v_pk_add_f32 v[8:9], v[22:23], v[18:19] op_sel_hi:[1,0] neg_lo:[0,1] neg_hi:[0,1]
	v_lshlrev_b32_e32 v24, 16, v25
	v_and_b32_e32 v25, 0xffff0000, v25
	s_waitcnt lgkmcnt(0)
	v_pk_mul_f32 v[8:9], v[20:21], v[8:9] op_sel_hi:[0,1]
	v_pk_fma_f32 v[8:9], v[10:11], v[8:9], v[14:15]
	v_pk_add_f32 v[10:11], v[24:25], v[18:19] op_sel_hi:[1,0] neg_lo:[0,1] neg_hi:[0,1]
	v_pk_add_f32 v[8:9], v[8:9], v[34:35]
	v_pk_mul_f32 v[10:11], v[20:21], v[10:11] op_sel_hi:[0,1]
	v_pk_fma_f32 v[10:11], v[12:13], v[10:11], v[16:17]
	v_cvt_pk_bf16_f32 v8, v8, v9
	v_pk_add_f32 v[6:7], v[10:11], v[6:7]
	s_nop 0
	v_cvt_pk_bf16_f32 v9, v6, v7
	ds_write_b64 v19, v[8:9] offset:16864
	ds_read_b128 v[6:9], v28 offset:480
	ds_read_b64 v[14:15], v19 offset:240
	ds_read_b32 v16, v29
	ds_read_b32 v18, v30
	v_add_u32_e32 v10, 0x255e0, v27
	ds_read_b128 v[10:13], v10
	s_waitcnt lgkmcnt(3)
	v_lshlrev_b32_e32 v20, 16, v14
	v_and_b32_e32 v21, 0xffff0000, v14
	v_lshlrev_b32_e32 v14, 16, v15
	v_and_b32_e32 v15, 0xffff0000, v15
	s_waitcnt lgkmcnt(2)
	v_pk_add_f32 v[20:21], v[20:21], v[16:17] op_sel_hi:[1,0] neg_lo:[0,1] neg_hi:[0,1]
	v_pk_add_f32 v[14:15], v[14:15], v[16:17] op_sel_hi:[1,0] neg_lo:[0,1] neg_hi:[0,1]
	s_waitcnt lgkmcnt(1)
	v_pk_mul_f32 v[20:21], v[18:19], v[20:21] op_sel_hi:[0,1]
	v_pk_mul_f32 v[14:15], v[18:19], v[14:15] op_sel_hi:[0,1]
	v_lshlrev_b32_e32 v22, 16, v4
	v_and_b32_e32 v23, 0xffff0000, v4
	v_lshlrev_b32_e32 v4, 16, v5
	v_and_b32_e32 v5, 0xffff0000, v5
	s_waitcnt lgkmcnt(0)
	v_pk_fma_f32 v[20:21], v[6:7], v[20:21], v[10:11]
	v_pk_fma_f32 v[14:15], v[8:9], v[14:15], v[12:13]
	v_pk_add_f32 v[20:21], v[20:21], v[22:23]
	v_pk_add_f32 v[4:5], v[14:15], v[4:5]
	v_cvt_pk_bf16_f32 v14, v20, v21
	v_cvt_pk_bf16_f32 v15, v4, v5
	ds_write_b64 v19, v[14:15] offset:240
	ds_read_b32 v4, v33
	ds_read_b64 v[14:15], v19 offset:16880
	ds_read_b32 v16, v31
	v_lshlrev_b32_e32 v22, 16, v2
	v_and_b32_e32 v23, 0xffff0000, v2
	v_lshlrev_b32_e32 v2, 16, v3
	s_waitcnt lgkmcnt(1)
	v_lshlrev_b32_e32 v20, 16, v14
	v_and_b32_e32 v21, 0xffff0000, v14
	s_waitcnt lgkmcnt(0)
	v_pk_add_f32 v[20:21], v[20:21], v[16:17] op_sel_hi:[1,0] neg_lo:[0,1] neg_hi:[0,1]
	v_lshlrev_b32_e32 v14, 16, v15
	v_and_b32_e32 v15, 0xffff0000, v15
	v_pk_mul_f32 v[20:21], v[4:5], v[20:21] op_sel_hi:[0,1]
	v_pk_fma_f32 v[6:7], v[6:7], v[20:21], v[10:11]
	v_pk_add_f32 v[10:11], v[14:15], v[16:17] op_sel_hi:[1,0] neg_lo:[0,1] neg_hi:[0,1]
	v_and_b32_e32 v3, 0xffff0000, v3
	v_pk_mul_f32 v[4:5], v[4:5], v[10:11] op_sel_hi:[0,1]
	v_pk_fma_f32 v[4:5], v[8:9], v[4:5], v[12:13]
	v_pk_add_f32 v[6:7], v[6:7], v[22:23]
	v_pk_add_f32 v[2:3], v[4:5], v[2:3]
	v_cvt_pk_bf16_f32 v4, v6, v7
	v_cvt_pk_bf16_f32 v5, v2, v3
	ds_write_b64 v19, v[4:5] offset:16880
	s_add_u32 s24, s80, s24
	s_addc_u32 s25, s81, s25
	v_lshl_add_u64 v[8:9], s[24:25], 0, v[0:1]
	v_mov_b32_e32 v0, v192
	s_waitcnt lgkmcnt(0)
	s_barrier
; DI int otid() { int t = threadIdx.x; asm volatile("" : "+v"(t)); return t; }
; DI void stg16_nt(void* p, u32x4 v) { __builtin_nontemporal_store(v, (u32x4*)p); }
; DI void stage_store_tile(const bf16_t* stg, bf16_t* tilebase) {
;   const int tid = otid();
;   const int r0 = tid >> 5, c = tid & 31;
;   const unsigned o0 = (unsigned)(r0 * 1024 + c * 8);
; #pragma unroll
;   for (int it = 0; it < 16; ++it) stg16_nt(tilebase + (o0 + (unsigned)(it * 16 * 1024)), stage_read16(stg, r0 + 16 * it, c));
; }
; template <bool LAST>
; DI void phase_gate(const Params& P, int layer, unsigned char* smem, int L, int G) {
;     ...
;     if (!LAST) stage_store_tile(stg, xb + (size_t)mt * 256 * 1024 + nt * 256);
;     __syncthreads();
	s_add_i32 s31, s31, s74
	v_ashrrev_i32_e32 v4, 5, v0
	v_and_b32_e32 v0, 31, v0
	v_mul_lo_u32 v1, v4, s40
	v_lshl_add_u32 v12, v0, 4, v1
	v_lshlrev_b32_e32 v5, 3, v0
	ds_read2_b64 v[0:3], v12 offset1:1
	v_lshl_or_b32 v160, v4, 10, v5
	v_add_u32_e32 v4, 0x2080, v12
	ds_read2_b64 v[4:7], v4 offset1:1
	v_lshl_add_u64 v[10:11], v[160:161], 1, v[8:9]
	s_waitcnt lgkmcnt(1)
	global_store_dwordx4 v[10:11], v[0:3], off nt
	s_add_i32 s28, s28, s69
	s_add_i32 s29, s29, s30
	v_add_u32_e32 v0, 0x4000, v160
	v_mov_b32_e32 v1, v161
	v_lshl_add_u64 v[0:1], v[0:1], 1, v[8:9]
	s_waitcnt lgkmcnt(0)
	global_store_dwordx4 v[0:1], v[4:7], off nt
	v_add_u32_e32 v0, 0x4100, v12
	ds_read2_b64 v[0:3], v0 offset1:1
	v_add_u32_e32 v4, 0x8000, v160
	v_mov_b32_e32 v5, v161
	v_lshl_add_u64 v[10:11], v[4:5], 1, v[8:9]
	v_add_u32_e32 v4, 0x6180, v12
	ds_read2_b64 v[4:7], v4 offset1:1
	s_waitcnt lgkmcnt(1)
	global_store_dwordx4 v[10:11], v[0:3], off nt
	s_add_i32 s24, s70, s31
	s_cmpk_lt_i32 s24, 0x400
	v_add_u32_e32 v0, 0xc000, v160
	v_mov_b32_e32 v1, v161
	v_lshl_add_u64 v[0:1], v[0:1], 1, v[8:9]
	s_waitcnt lgkmcnt(0)
	global_store_dwordx4 v[0:1], v[4:7], off nt
	v_add_u32_e32 v0, 0x8200, v12
	ds_read2_b64 v[0:3], v0 offset1:1
	v_add_u32_e32 v4, 0x10000, v160
	v_mov_b32_e32 v5, v161
	v_lshl_add_u64 v[10:11], v[4:5], 1, v[8:9]
	v_add_u32_e32 v4, 0xa280, v12
	ds_read2_b64 v[4:7], v4 offset1:1
	s_waitcnt lgkmcnt(1)
	global_store_dwordx4 v[10:11], v[0:3], off nt
	s_nop 1
	v_add_u32_e32 v0, 0x14000, v160
	v_mov_b32_e32 v1, v161
	v_lshl_add_u64 v[0:1], v[0:1], 1, v[8:9]
	s_waitcnt lgkmcnt(0)
	global_store_dwordx4 v[0:1], v[4:7], off nt
	v_add_u32_e32 v0, 0xc300, v12
	ds_read2_b64 v[0:3], v0 offset1:1
	v_add_u32_e32 v4, 0x18000, v160
	v_mov_b32_e32 v5, v161
	v_lshl_add_u64 v[10:11], v[4:5], 1, v[8:9]
	v_add_u32_e32 v4, 0xe380, v12
	ds_read2_b64 v[4:7], v4 offset1:1
	s_waitcnt lgkmcnt(1)
	global_store_dwordx4 v[10:11], v[0:3], off nt
	s_nop 1
	v_add_u32_e32 v0, 0x1c000, v160
	v_mov_b32_e32 v1, v161
	v_lshl_add_u64 v[0:1], v[0:1], 1, v[8:9]
	s_waitcnt lgkmcnt(0)
	global_store_dwordx4 v[0:1], v[4:7], off nt
	v_add_u32_e32 v0, 0x10400, v12
	ds_read2_b64 v[0:3], v0 offset1:1
	v_add_u32_e32 v4, 0x20000, v160
	v_mov_b32_e32 v5, v161
	v_lshl_add_u64 v[10:11], v[4:5], 1, v[8:9]
	v_add_u32_e32 v4, 0x12480, v12
	ds_read2_b64 v[4:7], v4 offset1:1
	s_waitcnt lgkmcnt(1)
	global_store_dwordx4 v[10:11], v[0:3], off nt
	s_nop 1
	v_add_u32_e32 v0, 0x24000, v160
	v_mov_b32_e32 v1, v161
	v_lshl_add_u64 v[0:1], v[0:1], 1, v[8:9]
	s_waitcnt lgkmcnt(0)
	global_store_dwordx4 v[0:1], v[4:7], off nt
	v_add_u32_e32 v0, 0x14500, v12
	ds_read2_b64 v[0:3], v0 offset1:1
	v_add_u32_e32 v4, 0x28000, v160
	v_mov_b32_e32 v5, v161
	v_lshl_add_u64 v[10:11], v[4:5], 1, v[8:9]
	v_add_u32_e32 v4, 0x16580, v12
	ds_read2_b64 v[4:7], v4 offset1:1
	s_waitcnt lgkmcnt(1)
	global_store_dwordx4 v[10:11], v[0:3], off nt
	s_nop 1
	v_add_u32_e32 v0, 0x2c000, v160
	v_mov_b32_e32 v1, v161
	v_lshl_add_u64 v[0:1], v[0:1], 1, v[8:9]
	s_waitcnt lgkmcnt(0)
	global_store_dwordx4 v[0:1], v[4:7], off nt
	v_add_u32_e32 v0, 0x18600, v12
	ds_read2_b64 v[0:3], v0 offset1:1
	v_add_u32_e32 v4, 0x30000, v160
	v_mov_b32_e32 v5, v161
	v_lshl_add_u64 v[10:11], v[4:5], 1, v[8:9]
	v_add_u32_e32 v4, 0x1a680, v12
	ds_read2_b64 v[4:7], v4 offset1:1
	s_waitcnt lgkmcnt(1)
	global_store_dwordx4 v[10:11], v[0:3], off nt
	v_add_u32_e32 v10, 0x38000, v160
	v_mov_b32_e32 v11, v161
	v_add_u32_e32 v0, 0x34000, v160
	v_mov_b32_e32 v1, v161
	v_lshl_add_u64 v[0:1], v[0:1], 1, v[8:9]
	s_waitcnt lgkmcnt(0)
	global_store_dwordx4 v[0:1], v[4:7], off nt
	v_add_u32_e32 v0, 0x1c700, v12
	ds_read2_b64 v[0:3], v0 offset1:1
	v_add_u32_e32 v4, 0x1e780, v12
	ds_read2_b64 v[4:7], v4 offset1:1
	v_lshl_add_u64 v[10:11], v[10:11], 1, v[8:9]
	v_add_u32_e32 v160, 0x3c000, v160
	s_waitcnt lgkmcnt(1)
	global_store_dwordx4 v[10:11], v[0:3], off nt
	s_nop 1
	v_lshl_add_u64 v[0:1], v[160:161], 1, v[8:9]
	s_waitcnt lgkmcnt(0)
	global_store_dwordx4 v[0:1], v[4:7], off nt
	s_barrier
	s_cbranch_scc0 .LBB0_929

; DI int otid() { int t = threadIdx.x; asm volatile("" : "+v"(t)); return t; }
; template <bool NT>
; DI void stage_load_tile(bf16_t* stg, const bf16_t* tilebase) {
;   const int tid = otid();
;   const int r0 = tid >> 5, c = tid & 31;
;   const unsigned o0 = (unsigned)(r0 * 1024 + c * 8);
;   __builtin_amdgcn_sched_barrier(0);
; #pragma unroll
;   for (int hf = 0; hf < 2; ++hf) {
; #pragma unroll
;     for (int it = 8 * hf; it < 8 * hf + 8; ++it) {
;       const u32x4* gp = (const u32x4*)(tilebase + (o0 + (unsigned)(it * 16 * 1024)));
;       stage_write16(stg, r0 + 16 * it, c, NT ? __builtin_nontemporal_load(gp) : *gp);
;     }
;     __builtin_amdgcn_sched_barrier(0);
;   }
; }
; template <bool XF32>
; DI void phase_outproj(const Params& P, int layer, const void* xres, const bf16_t* og, unsigned char* smem, int L, int G) {
;     ...
;     stage_load_tile<true>(stg, (const bf16_t*)xres + (size_t)mt * 256 * 1024 + nt * 256);
.LBB0_1428:
	v_bfe_u32 v198, v167, 5, 1
	s_ashr_i32 s11, s10, 31
	s_lshl_b64 s[28:29], s[10:11], 19
	s_add_u32 s15, s80, s28
	v_mov_b32_e32 v160, v192
	s_addc_u32 s28, s81, s29
	s_lshl_b32 s27, s14, 1
	s_add_u32 s14, s15, s27
	v_and_b32_e32 v200, 31, v160
	v_ashrrev_i32_e32 v199, 5, v160
	v_lshlrev_b32_e32 v160, 3, v200
	s_addc_u32 s15, s28, 0
	v_lshl_or_b32 v160, v199, 10, v160
	v_add_u32_e32 v164, 0x4000, v160
	v_mov_b32_e32 v165, v161
	v_add_u32_e32 v172, 0x8000, v160
	v_mov_b32_e32 v173, v161
	v_add_u32_e32 v174, 0xc000, v160
	v_mov_b32_e32 v175, v161
	v_add_u32_e32 v180, 0x10000, v160
	v_mov_b32_e32 v181, v161
	v_add_u32_e32 v182, 0x14000, v160
	v_mov_b32_e32 v183, v161
	v_add_u32_e32 v188, 0x18000, v160
	v_mov_b32_e32 v189, v161
	v_add_u32_e32 v190, 0x1c000, v160
	v_mov_b32_e32 v191, v161
	v_lshl_add_u64 v[162:163], v[160:161], 1, s[14:15]
	v_lshl_add_u64 v[168:169], v[164:165], 1, s[14:15]
	v_lshl_add_u64 v[172:173], v[172:173], 1, s[14:15]
	v_lshl_add_u64 v[176:177], v[174:175], 1, s[14:15]
	v_lshl_add_u64 v[180:181], v[180:181], 1, s[14:15]
	v_lshl_add_u64 v[184:185], v[182:183], 1, s[14:15]
	v_lshl_add_u64 v[188:189], v[188:189], 1, s[14:15]
	v_lshl_add_u64 v[194:195], v[190:191], 1, s[14:15]
	global_load_dwordx4 v[162:165], v[162:163], off nt
	s_nop 0
	global_load_dwordx4 v[168:171], v[168:169], off nt
	s_nop 0
	global_load_dwordx4 v[172:175], v[172:173], off nt
	s_nop 0
	global_load_dwordx4 v[176:179], v[176:177], off nt
	s_nop 0
	global_load_dwordx4 v[180:183], v[180:181], off nt
	s_nop 0
	global_load_dwordx4 v[184:187], v[184:185], off nt
	s_nop 0
	global_load_dwordx4 v[188:191], v[188:189], off nt
	s_nop 0
	global_load_dwordx4 v[194:197], v[194:195], off nt
	v_add_u32_e32 v222, 0x20000, v160
	v_mov_b32_e32 v223, v161
	v_add_u32_e32 v224, 0x24000, v160
	v_mov_b32_e32 v225, v161
	v_add_u32_e32 v230, 0x28000, v160
	v_mov_b32_e32 v231, v161
	v_add_u32_e32 v232, 0x2c000, v160
	v_mov_b32_e32 v233, v161
	v_add_u32_e32 v238, 0x30000, v160
	v_mov_b32_e32 v239, v161
	v_add_u32_e32 v240, 0x34000, v160
	v_mov_b32_e32 v241, v161
	v_add_u32_e32 v248, 0x38000, v160
	v_mov_b32_e32 v249, v161
	v_add_u32_e32 v160, 0x3c000, v160
	v_lshl_add_u64 v[222:223], v[222:223], 1, s[14:15]
	v_lshl_add_u64 v[226:227], v[224:225], 1, s[14:15]
	v_lshl_add_u64 v[230:231], v[230:231], 1, s[14:15]
	v_lshl_add_u64 v[234:235], v[232:233], 1, s[14:15]
	v_lshl_add_u64 v[238:239], v[238:239], 1, s[14:15]
	v_lshl_add_u64 v[242:243], v[240:241], 1, s[14:15]
	v_lshl_add_u64 v[248:249], v[248:249], 1, s[14:15]
	v_lshl_add_u64 v[252:253], v[160:161], 1, s[14:15]
	global_load_dwordx4 v[222:225], v[222:223], off nt
	s_nop 0
	global_load_dwordx4 v[226:229], v[226:227], off nt
	s_nop 0
	global_load_dwordx4 v[230:233], v[230:231], off nt
	s_nop 0
	global_load_dwordx4 v[234:237], v[234:235], off nt
	s_nop 0
	global_load_dwordx4 v[238:241], v[238:239], off nt
	s_nop 0
	global_load_dwordx4 v[242:245], v[242:243], off nt
	s_nop 0
	global_load_dwordx4 v[248:251], v[248:249], off nt
	s_nop 0
	global_load_dwordx4 v[252:255], v[252:253], off nt
	v_mul_lo_u32 v199, v199, s23
	v_lshl_add_u32 v199, v200, 4, v199
	v_add_u32_e32 v200, 0x2080, v199
	v_add_u32_e32 v201, 0x4100, v199
	v_add_u32_e32 v202, 0x6180, v199
	v_add_u32_e32 v203, 0x8200, v199
	v_add_u32_e32 v204, 0xa280, v199
	v_add_u32_e32 v205, 0xc300, v199
	v_add_u32_e32 v206, 0xe380, v199
	s_waitcnt vmcnt(15)
	ds_write2_b64 v199, v[162:163], v[164:165] offset1:1
	s_waitcnt vmcnt(14)
	ds_write2_b64 v200, v[168:169], v[170:171] offset1:1
	s_waitcnt vmcnt(13)
	ds_write2_b64 v201, v[172:173], v[174:175] offset1:1
	s_waitcnt vmcnt(12)
	ds_write2_b64 v202, v[176:177], v[178:179] offset1:1
	s_waitcnt vmcnt(11)
	ds_write2_b64 v203, v[180:181], v[182:183] offset1:1
	s_waitcnt vmcnt(10)
	ds_write2_b64 v204, v[184:185], v[186:187] offset1:1
	s_waitcnt vmcnt(9)
	ds_write2_b64 v205, v[188:189], v[190:191] offset1:1
	s_waitcnt vmcnt(8)
	ds_write2_b64 v206, v[194:195], v[196:197] offset1:1
	v_add_u32_e32 v160, 0x10400, v199
	v_add_u32_e32 v200, 0x12480, v199
	v_add_u32_e32 v201, 0x14500, v199
	v_add_u32_e32 v202, 0x16580, v199
	v_add_u32_e32 v203, 0x18600, v199
	v_add_u32_e32 v204, 0x1a680, v199
	v_add_u32_e32 v205, 0x1c700, v199
	v_add_u32_e32 v199, 0x1e780, v199
	s_waitcnt vmcnt(7)
	ds_write2_b64 v160, v[222:223], v[224:225] offset1:1
	s_waitcnt vmcnt(6)
	ds_write2_b64 v200, v[226:227], v[228:229] offset1:1
	s_waitcnt vmcnt(5)
	ds_write2_b64 v201, v[230:231], v[232:233] offset1:1
	s_waitcnt vmcnt(4)
	ds_write2_b64 v202, v[234:235], v[236:237] offset1:1
	s_waitcnt vmcnt(3)
	ds_write2_b64 v203, v[238:239], v[240:241] offset1:1
	s_waitcnt vmcnt(2)
	ds_write2_b64 v204, v[242:243], v[244:245] offset1:1
	s_waitcnt vmcnt(1)
	ds_write2_b64 v205, v[248:249], v[250:251] offset1:1
	s_waitcnt vmcnt(0)
	ds_write2_b64 v199, v[252:253], v[254:255] offset1:1
	v_lshlrev_b32_e32 v160, 3, v198
	v_and_b32_e32 v163, 0xdf, v167
	v_and_or_b32 v164, v167, s18, v160
	v_ashrrev_i32_e32 v165, 7, v167
	v_mad_u32_u24 v167, v163, s23, v164
	s_waitcnt lgkmcnt(0)
	s_barrier
; DI unsigned pack2(float a, float b) { f32x2_t v = {a, b}; bf16x2_t r = __builtin_convertvector(v, bf16x2_t); return __builtin_bit_cast(unsigned, r); }
; DI float bflo(unsigned u) { return __uint_as_float(u << 16); }
; DI float bfhi(unsigned u) { return __uint_as_float(u & 0xffff0000u); }
; template <bool XF32>
; DI void phase_outproj(const Params& P, int layer, const void* xres, const bf16_t* og, unsigned char* smem, int L, int G) {
;     ...
; #pragma unroll
;     for (int j = 0; j < 2; ++j)
; #pragma unroll
;       for (int ch = 0; ch < 2; ++ch) {
;         float s1 = 0.f, s2 = 0.f;
; #pragma unroll
;         for (int i = 2 * ch; i < 2 * ch + 2; ++i)
; #pragma unroll
;           for (int q4 = 0; q4 < 4; ++q4) {
;             uint2* pp = (uint2*)(stg + (wn * 64 + j * 32 + r) * STG + wm * 128 + i * 32 + 8 * q4 + 4 * h);
;             const uint2 xv = *pp;
;             uint2 pk;
;             pk.x = pack2(DN_ALPHA * bflo(xv.x) + acc[i][j][4 * q4], DN_ALPHA * bfhi(xv.x) + acc[i][j][4 * q4 + 1]);
;             pk.y = pack2(DN_ALPHA * bflo(xv.y) + acc[i][j][4 * q4 + 2], DN_ALPHA * bfhi(xv.y) + acc[i][j][4 * q4 + 3]);
;             *pp = pk;
;             const float f0 = bflo(pk.x), f1 = bfhi(pk.x), f2 = bflo(pk.y), f3 = bfhi(pk.y);
;             s1 += (f0 + f1) + (f2 + f3); s2 += (f0 * f0 + f1 * f1) + (f2 * f2 + f3 * f3);
;             __builtin_amdgcn_sched_barrier(0);
;           }
	ds_read_b64 v[168:169], v167
	v_and_b32_e32 v162, 64, v166
	v_xor_b32_e32 v160, 32, v166
	v_add_u32_e32 v162, 64, v162
	v_cmp_lt_i32_e32 vcc, v160, v162
	v_or_b32_e32 v162, s26, v163
	v_and_b32_e32 v165, -2, v165
	v_ashrrev_i32_e32 v163, 31, v162
	s_waitcnt lgkmcnt(0)
	v_lshlrev_b32_e32 v170, 16, v168
	v_and_b32_e32 v171, 0xffff0000, v168
	v_lshlrev_b32_e32 v168, 16, v169
	v_and_b32_e32 v169, 0xffff0000, v169
	v_cndmask_b32_e32 v160, v166, v160, vcc
	v_lshl_add_u32 v206, s25, 2, v165
	v_lshlrev_b64 v[164:165], 7, v[162:163]
	v_pk_fma_f32 v[112:113], v[170:171], s[8:9], v[112:113] op_sel_hi:[1,0,1]
	v_pk_fma_f32 v[114:115], v[168:169], s[8:9], v[114:115] op_sel_hi:[1,0,1]
	v_lshlrev_b32_e32 v160, 2, v160
	v_cmp_eq_u32_e32 vcc, 0, v198
	v_lshl_add_u64 v[164:165], s[78:79], 0, v[164:165]
	v_cvt_pk_bf16_f32 v112, v112, v113
	v_cvt_pk_bf16_f32 v113, v114, v115
	ds_write_b64 v167, v[112:113]
	v_and_b32_e32 v114, 0xffff0000, v112
	v_lshlrev_b32_e32 v168, 16, v113
	ds_read_b64 v[170:171], v167 offset:16
	s_waitcnt lgkmcnt(0)
	v_lshlrev_b32_e32 v172, 16, v170
	v_and_b32_e32 v173, 0xffff0000, v170
	v_lshlrev_b32_e32 v170, 16, v171
	v_and_b32_e32 v171, 0xffff0000, v171
	v_pk_fma_f32 v[116:117], v[172:173], s[8:9], v[116:117] op_sel_hi:[1,0,1]
	v_pk_fma_f32 v[118:119], v[170:171], s[8:9], v[118:119] op_sel_hi:[1,0,1]
	v_cvt_pk_bf16_f32 v116, v116, v117
	v_cvt_pk_bf16_f32 v117, v118, v119
	ds_write_b64 v167, v[116:117] offset:16
	v_lshlrev_b32_e32 v118, 16, v117
	v_and_b32_e32 v119, 0xffff0000, v117
	v_lshlrev_b32_e32 v171, 16, v116
	v_and_b32_e32 v117, 0xffff0000, v116
	v_lshlrev_b32_e32 v170, 16, v112
	v_mov_b32_e32 v115, v171
	v_and_b32_e32 v116, 0xffff0000, v113
	v_mov_b32_e32 v169, v117
	v_pk_mul_f32 v[172:173], v[170:171], v[170:171]
	v_pk_mul_f32 v[174:175], v[114:115], v[114:115]
	v_pk_add_f32 v[114:115], v[170:171], v[114:115]
	v_pk_mul_f32 v[112:113], v[168:169], v[168:169]
	v_pk_mul_f32 v[176:177], v[116:117], v[116:117]
	v_pk_add_f32 v[168:169], v[116:117], v[168:169]
	v_mul_f32_e32 v178, v118, v118
	v_mov_b32_e32 v115, v173
	v_mov_b32_e32 v169, v177
	v_pk_fma_f32 v[178:179], v[118:119], v[118:119], v[178:179] op_sel_hi:[1,1,0]
	ds_read_b64 v[180:181], v167 offset:32
	s_waitcnt lgkmcnt(0)
	v_lshlrev_b32_e32 v182, 16, v180
	v_and_b32_e32 v183, 0xffff0000, v180
	v_lshlrev_b32_e32 v180, 16, v181
	v_and_b32_e32 v181, 0xffff0000, v181
	v_pk_fma_f32 v[120:121], v[182:183], s[8:9], v[120:121] op_sel_hi:[1,0,1]
	v_pk_fma_f32 v[122:123], v[180:181], s[8:9], v[122:123] op_sel_hi:[1,0,1]
	v_cvt_pk_bf16_f32 v120, v120, v121
	v_cvt_pk_bf16_f32 v121, v122, v123
	ds_write_b64 v167, v[120:121] offset:32
	v_lshlrev_b32_e32 v122, 16, v120
	v_and_b32_e32 v120, 0xffff0000, v120
	v_lshlrev_b32_e32 v180, 16, v121
	v_and_b32_e32 v182, 0xffff0000, v121
	v_mul_f32_e32 v123, v122, v122
	v_mul_f32_e32 v121, v120, v120
	v_mul_f32_e32 v181, v180, v180
	v_mul_f32_e32 v183, v182, v182
	ds_read_b64 v[184:185], v167 offset:48
	s_waitcnt lgkmcnt(0)
	v_lshlrev_b32_e32 v186, 16, v184
	v_and_b32_e32 v187, 0xffff0000, v184
	v_lshlrev_b32_e32 v184, 16, v185
	v_and_b32_e32 v185, 0xffff0000, v185
	v_pk_fma_f32 v[124:125], v[186:187], s[8:9], v[124:125] op_sel_hi:[1,0,1]
	v_pk_fma_f32 v[126:127], v[184:185], s[8:9], v[126:127] op_sel_hi:[1,0,1]
	v_cvt_pk_bf16_f32 v124, v124, v125
	v_cvt_pk_bf16_f32 v125, v126, v127
	ds_write_b64 v167, v[124:125] offset:48
	v_lshlrev_b32_e32 v126, 16, v124
	v_and_b32_e32 v124, 0xffff0000, v124
	v_lshlrev_b32_e32 v184, 16, v125
	v_and_b32_e32 v186, 0xffff0000, v125
	v_mul_f32_e32 v127, v126, v126
	v_mul_f32_e32 v125, v124, v124
	v_mul_f32_e32 v185, v184, v184
	v_mul_f32_e32 v187, v186, v186
	ds_read_b64 v[188:189], v167 offset:64
	s_waitcnt lgkmcnt(0)
	v_lshlrev_b32_e32 v190, 16, v188
	v_and_b32_e32 v191, 0xffff0000, v188
	v_lshlrev_b32_e32 v188, 16, v189
	v_and_b32_e32 v189, 0xffff0000, v189
	v_pk_fma_f32 v[96:97], v[190:191], s[8:9], v[96:97] op_sel_hi:[1,0,1]
	v_pk_fma_f32 v[98:99], v[188:189], s[8:9], v[98:99] op_sel_hi:[1,0,1]
	v_cvt_pk_bf16_f32 v96, v96, v97
	v_cvt_pk_bf16_f32 v97, v98, v99
	ds_write_b64 v167, v[96:97] offset:64
	v_lshlrev_b32_e32 v98, 16, v96
	v_and_b32_e32 v96, 0xffff0000, v96
	v_lshlrev_b32_e32 v188, 16, v97
	v_and_b32_e32 v190, 0xffff0000, v97
	v_mul_f32_e32 v99, v98, v98
	v_mul_f32_e32 v97, v96, v96
	v_mul_f32_e32 v189, v188, v188
	v_mul_f32_e32 v191, v190, v190
	ds_read_b64 v[194:195], v167 offset:80
	s_waitcnt lgkmcnt(0)
; DI unsigned pack2(float a, float b) { f32x2_t v = {a, b}; bf16x2_t r = __builtin_convertvector(v, bf16x2_t); return __builtin_bit_cast(unsigned, r); }
; DI float bflo(unsigned u) { return __uint_as_float(u << 16); }
; DI float bfhi(unsigned u) { return __uint_as_float(u & 0xffff0000u); }
; DI float shx(float v, int m) { return __shfl_xor(v, m, 64); }
; template <bool XF32>
; DI void phase_outproj(const Params& P, int layer, const void* xres, const bf16_t* og, unsigned char* smem, int L, int G) {
;     ...
; #pragma unroll
;     for (int j = 0; j < 2; ++j)
; #pragma unroll
;       for (int ch = 0; ch < 2; ++ch) {
;         float s1 = 0.f, s2 = 0.f;
; #pragma unroll
;         for (int i = 2 * ch; i < 2 * ch + 2; ++i)
; #pragma unroll
;           for (int q4 = 0; q4 < 4; ++q4) {
;             uint2* pp = (uint2*)(stg + (wn * 64 + j * 32 + r) * STG + wm * 128 + i * 32 + 8 * q4 + 4 * h);
;             const uint2 xv = *pp;
;             uint2 pk;
;             pk.x = pack2(DN_ALPHA * bflo(xv.x) + acc[i][j][4 * q4], DN_ALPHA * bfhi(xv.x) + acc[i][j][4 * q4 + 1]);
;             pk.y = pack2(DN_ALPHA * bflo(xv.y) + acc[i][j][4 * q4 + 2], DN_ALPHA * bfhi(xv.y) + acc[i][j][4 * q4 + 3]);
;             *pp = pk;
;             const float f0 = bflo(pk.x), f1 = bfhi(pk.x), f2 = bflo(pk.y), f3 = bfhi(pk.y);
;             s1 += (f0 + f1) + (f2 + f3); s2 += (f0 * f0 + f1 * f1) + (f2 * f2 + f3 * f3);
;             __builtin_amdgcn_sched_barrier(0);
;           }
;         s1 += shx(s1, 32); s2 += shx(s2, 32);
;         if (h == 0) {
;           const size_t row = (size_t)(mt * 256 + wn * 64 + j * 32 + r);
;           *(float2*)(stats + row * 32 + (nt * 4 + wm * 2 + ch) * 2) = make_float2(s1, s2);
;         }
;       }
	v_lshlrev_b32_e32 v196, 16, v194
	v_and_b32_e32 v197, 0xffff0000, v194
	v_lshlrev_b32_e32 v194, 16, v195
	v_and_b32_e32 v195, 0xffff0000, v195
	v_pk_fma_f32 v[100:101], v[196:197], s[8:9], v[100:101] op_sel_hi:[1,0,1]
	v_pk_fma_f32 v[102:103], v[194:195], s[8:9], v[102:103] op_sel_hi:[1,0,1]
	v_cvt_pk_bf16_f32 v100, v100, v101
	v_cvt_pk_bf16_f32 v101, v102, v103
	ds_write_b64 v167, v[100:101] offset:80
	v_lshlrev_b32_e32 v102, 16, v100
	v_and_b32_e32 v100, 0xffff0000, v100
	v_lshlrev_b32_e32 v194, 16, v101
	v_and_b32_e32 v196, 0xffff0000, v101
	v_mul_f32_e32 v101, v100, v100
	v_mul_f32_e32 v103, v102, v102
	v_mul_f32_e32 v195, v194, v194
	v_mul_f32_e32 v197, v196, v196
	ds_read_b64 v[198:199], v167 offset:96
	s_waitcnt lgkmcnt(0)
	v_lshlrev_b32_e32 v200, 16, v198
	v_and_b32_e32 v201, 0xffff0000, v198
	v_lshlrev_b32_e32 v198, 16, v199
	v_and_b32_e32 v199, 0xffff0000, v199
	v_pk_fma_f32 v[104:105], v[200:201], s[8:9], v[104:105] op_sel_hi:[1,0,1]
	v_pk_fma_f32 v[106:107], v[198:199], s[8:9], v[106:107] op_sel_hi:[1,0,1]
	v_cvt_pk_bf16_f32 v104, v104, v105
	v_cvt_pk_bf16_f32 v105, v106, v107
	ds_write_b64 v167, v[104:105] offset:96
	v_lshlrev_b32_e32 v106, 16, v104
	v_and_b32_e32 v104, 0xffff0000, v104
	v_lshlrev_b32_e32 v198, 16, v105
	v_and_b32_e32 v200, 0xffff0000, v105
	v_mul_f32_e32 v107, v106, v106
	v_mul_f32_e32 v105, v104, v104
	v_mul_f32_e32 v199, v198, v198
	v_mul_f32_e32 v201, v200, v200
	v_pk_mov_b32 v[170:171], v[170:171], v[172:173] op_sel:[1,0]
	v_pk_mov_b32 v[116:117], v[116:117], v[174:175] op_sel:[1,0]
	ds_read_b64 v[202:203], v167 offset:112
	v_pk_add_f32 v[116:117], v[170:171], v[116:117]
	v_mov_b32_e32 v170, v118
	v_mov_b32_e32 v171, v112
	v_pk_mov_b32 v[112:113], v[118:119], v[176:177] op_sel:[1,0]
	v_pk_add_f32 v[114:115], v[114:115], v[168:169]
	v_pk_add_f32 v[112:113], v[170:171], v[112:113]
	v_mov_b32_e32 v178, v161
	v_pk_add_f32 v[112:113], v[116:117], v[112:113]
	v_pk_add_f32 v[114:115], v[114:115], v[178:179]
	v_pk_add_f32 v[116:117], v[180:181], v[182:183]
	v_pk_add_f32 v[112:113], v[112:113], v[114:115]
	v_pk_add_f32 v[114:115], v[122:123], v[120:121]
	s_waitcnt lgkmcnt(0)
	v_lshlrev_b32_e32 v204, 16, v202
	v_pk_add_f32 v[114:115], v[114:115], v[116:117]
	v_pk_add_f32 v[116:117], v[184:185], v[186:187]
	v_pk_add_f32 v[112:113], v[112:113], v[114:115]
	v_pk_add_f32 v[114:115], v[126:127], v[124:125]
	v_and_b32_e32 v205, 0xffff0000, v202
	v_lshlrev_b32_e32 v202, 16, v203
	v_and_b32_e32 v203, 0xffff0000, v203
	v_pk_add_f32 v[114:115], v[114:115], v[116:117]
	v_pk_add_f32 v[96:97], v[98:99], v[96:97]
	v_pk_add_f32 v[98:99], v[188:189], v[190:191]
	v_pk_fma_f32 v[108:109], v[204:205], s[8:9], v[108:109] op_sel_hi:[1,0,1]
	v_pk_fma_f32 v[110:111], v[202:203], s[8:9], v[110:111] op_sel_hi:[1,0,1]
	v_pk_add_f32 v[112:113], v[112:113], v[114:115]
	v_pk_add_f32 v[96:97], v[96:97], v[98:99]
	v_pk_add_f32 v[98:99], v[102:103], v[100:101]
	v_pk_add_f32 v[100:101], v[194:195], v[196:197]
	v_cvt_pk_bf16_f32 v108, v108, v109
	v_cvt_pk_bf16_f32 v109, v110, v111
	v_pk_add_f32 v[96:97], v[112:113], v[96:97]
	v_pk_add_f32 v[98:99], v[98:99], v[100:101]
	ds_write_b64 v167, v[108:109] offset:112
	v_lshlrev_b32_e32 v110, 16, v108
	v_and_b32_e32 v108, 0xffff0000, v108
	v_lshlrev_b32_e32 v202, 16, v109
	v_and_b32_e32 v204, 0xffff0000, v109
	v_pk_add_f32 v[96:97], v[96:97], v[98:99]
	v_pk_add_f32 v[98:99], v[106:107], v[104:105]
	v_pk_add_f32 v[100:101], v[198:199], v[200:201]
	v_mul_f32_e32 v111, v110, v110
	v_mul_f32_e32 v109, v108, v108
	v_mul_f32_e32 v203, v202, v202
	v_mul_f32_e32 v205, v204, v204
	v_pk_add_f32 v[98:99], v[98:99], v[100:101]
	v_pk_add_f32 v[100:101], v[202:203], v[204:205]
	v_pk_add_f32 v[96:97], v[96:97], v[98:99]
	v_pk_add_f32 v[98:99], v[110:111], v[108:109]
	s_nop 0
	v_pk_add_f32 v[98:99], v[98:99], v[100:101]
	s_nop 0
	v_pk_add_f32 v[98:99], v[96:97], v[98:99]
	ds_bpermute_b32 v100, v160, v98
	ds_bpermute_b32 v101, v160, v99
	v_lshlrev_b32_e32 v96, 1, v206
	v_ashrrev_i32_e32 v97, 31, v96
	s_and_saveexec_b64 s[14:15], vcc
	s_cbranch_execz .LBB0_1430
	v_lshl_add_u64 v[102:103], v[96:97], 2, v[164:165]
	s_waitcnt lgkmcnt(0)
	v_pk_add_f32 v[98:99], v[98:99], v[100:101]
	global_store_dwordx2 v[102:103], v[98:99], off

; DI unsigned pack2(float a, float b) { f32x2_t v = {a, b}; bf16x2_t r = __builtin_convertvector(v, bf16x2_t); return __builtin_bit_cast(unsigned, r); }
; DI float sigmoidf_(float x) { return __builtin_amdgcn_rcpf(1.f + __expf(-x)); }
; template <bool LAST>
; DI void phase_gate(const Params& P, int layer, unsigned char* smem, int L, int G) {
;     ...
;     unsigned gq[4][2][8];
; #pragma unroll
;     for (int i = 0; i < 4; ++i)
; #pragma unroll
;       for (int q4 = 0; q4 < 4; ++q4) {
;         const int fl = wm * 128 + i * 32 + 8 * q4 + 4 * h;
;         const f32x4 c1v = *(const f32x4*)(vecL + fl), c2v = *(const f32x4*)(vecL + 256 + fl);
;         const float c1a[4] = {c1v.x, c1v.y, c1v.z, c1v.w}, c2a[4] = {c2v.x, c2v.y, c2v.z, c2v.w};
; #pragma unroll
;         for (int j = 0; j < 2; ++j) {
;           const int lrow = wn * 64 + j * 32 + r;
;           const float mu = rowA[lrow], rstd = rowB[lrow];
;           float sg4[4];
; #pragma unroll
;           for (int e = 0; e < 4; ++e) sg4[e] = sigmoidf_(rstd * (accu[i][j][4 * q4 + e] - mu * c1a[e]) + c2a[e]);
;           gq[i][j][2 * q4] = pack2(sg4[0], sg4[1]); gq[i][j][2 * q4 + 1] = pack2(sg4[2], sg4[3]);
;         }
;         __builtin_amdgcn_sched_barrier(0);
;       }
.LBB0_1498:
	v_lshrrev_b32_e32 v160, 1, v163
	v_lshrrev_b32_e32 v163, 3, v163
	v_and_b32_e32 v163, 4, v163
	v_and_or_b32 v160, v160, s33, v163
	v_lshlrev_b32_e32 v160, 2, v160
	v_add_u32_e32 v163, 0x24800, v160
	v_add_u32_e32 v164, 0x24c00, v160
	v_and_b32_e32 v167, 0x37c, v168
	ds_read_b128 v[170:173], v163
	ds_read_b128 v[174:177], v164
	v_or_b32_e32 v164, 0x24000, v167
	v_or_b32_e32 v166, 0x24080, v167
	v_or_b32_e32 v165, 0x24400, v167
	ds_read_b32 v168, v164
	ds_read_b32 v169, v165
	v_or_b32_e32 v167, 0x24480, v167
	ds_read_b32 v178, v166
	ds_read_b32 v179, v167
	s_waitcnt lgkmcnt(3)
	v_fma_f32 v112, -v170, v168, v112
	v_fma_f32 v113, -v171, v168, v113
	s_waitcnt lgkmcnt(1)
	v_fma_f32 v98, -v172, v178, v98
	v_fma_f32 v114, -v172, v168, v114
	v_fma_f32 v115, -v173, v168, v115
	v_fma_f32 v96, -v170, v178, v96
	v_fma_f32 v97, -v171, v178, v97
	s_waitcnt lgkmcnt(0)
	v_fma_f32 v98, v179, v98, v176
	v_fma_f32 v99, -v173, v178, v99
	v_fma_f32 v112, v169, v112, v174
	v_fma_f32 v113, v169, v113, v175
	v_fma_f32 v114, v169, v114, v176
	v_fma_f32 v115, v169, v115, v177
	v_fma_f32 v96, v179, v96, v174
	v_fma_f32 v97, v179, v97, v175
	v_mul_f32_e32 v98, 0xbfb8aa3b, v98
	v_fmac_f32_e32 v177, v179, v99
	v_mul_f32_e32 v112, 0xbfb8aa3b, v112
	v_mul_f32_e32 v113, 0xbfb8aa3b, v113
	v_mul_f32_e32 v114, 0xbfb8aa3b, v114
	v_mul_f32_e32 v115, 0xbfb8aa3b, v115
	v_mul_f32_e32 v96, 0xbfb8aa3b, v96
	v_mul_f32_e32 v97, 0xbfb8aa3b, v97
	v_exp_f32_e32 v98, v98
	v_mul_f32_e32 v99, 0xbfb8aa3b, v177
	v_exp_f32_e32 v112, v112
	v_exp_f32_e32 v113, v113
	v_exp_f32_e32 v114, v114
	v_exp_f32_e32 v115, v115
	v_exp_f32_e32 v96, v96
	v_exp_f32_e32 v97, v97
	v_exp_f32_e32 v99, v99
	v_add_f32_e32 v98, 1.0, v98
	v_add_f32_e32 v112, 1.0, v112
	v_add_f32_e32 v113, 1.0, v113
	v_add_f32_e32 v114, 1.0, v114
	v_add_f32_e32 v115, 1.0, v115
	v_add_f32_e32 v96, 1.0, v96
	v_add_f32_e32 v97, 1.0, v97
	v_rcp_f32_e32 v168, v98
	v_add_f32_e32 v98, 1.0, v99
	v_rcp_f32_e32 v112, v112
	v_rcp_f32_e32 v113, v113
	v_rcp_f32_e32 v114, v114
	v_rcp_f32_e32 v115, v115
	v_rcp_f32_e32 v96, v96
	v_rcp_f32_e32 v97, v97
	v_rcp_f32_e32 v169, v98
	v_cvt_pk_bf16_f32 v99, v112, v113
	v_cvt_pk_bf16_f32 v98, v114, v115
	v_cvt_pk_bf16_f32 v97, v96, v97
	v_cvt_pk_bf16_f32 v96, v168, v169
	v_add_u32_e32 v112, 0x24820, v160
	v_add_u32_e32 v168, 0x24c20, v160
	ds_read_b128 v[112:115], v112
	ds_read_b128 v[168:171], v168
	ds_read_b32 v172, v164
	ds_read_b32 v173, v165
	ds_read_b32 v174, v166
	ds_read_b32 v175, v167
	s_waitcnt lgkmcnt(3)
	v_fma_f32 v116, -v112, v172, v116
	v_fma_f32 v117, -v113, v172, v117
	s_waitcnt lgkmcnt(1)
	v_fma_f32 v102, -v114, v174, v102
	v_fma_f32 v118, -v114, v172, v118
	v_fma_f32 v119, -v115, v172, v119
	v_fma_f32 v100, -v112, v174, v100
	v_fma_f32 v101, -v113, v174, v101
	s_waitcnt lgkmcnt(0)
	v_fma_f32 v102, v175, v102, v170
	v_fma_f32 v103, -v115, v174, v103
	v_fma_f32 v116, v173, v116, v168
	v_fma_f32 v117, v173, v117, v169
	v_fma_f32 v118, v173, v118, v170
	v_fma_f32 v119, v173, v119, v171
	v_fma_f32 v100, v175, v100, v168
	v_fma_f32 v101, v175, v101, v169
	v_mul_f32_e32 v102, 0xbfb8aa3b, v102
	v_fmac_f32_e32 v171, v175, v103
	v_mul_f32_e32 v116, 0xbfb8aa3b, v116
	v_mul_f32_e32 v117, 0xbfb8aa3b, v117
	v_mul_f32_e32 v118, 0xbfb8aa3b, v118
	v_mul_f32_e32 v119, 0xbfb8aa3b, v119
	v_mul_f32_e32 v100, 0xbfb8aa3b, v100
	v_mul_f32_e32 v101, 0xbfb8aa3b, v101
	v_exp_f32_e32 v102, v102
	v_mul_f32_e32 v103, 0xbfb8aa3b, v171
	v_exp_f32_e32 v116, v116
	v_exp_f32_e32 v117, v117
	v_exp_f32_e32 v118, v118
	v_exp_f32_e32 v119, v119
	v_exp_f32_e32 v100, v100
	v_exp_f32_e32 v101, v101
	v_exp_f32_e32 v103, v103
	v_add_f32_e32 v102, 1.0, v102
	v_add_f32_e32 v116, 1.0, v116
	v_add_f32_e32 v117, 1.0, v117
	v_add_f32_e32 v118, 1.0, v118
	v_add_f32_e32 v119, 1.0, v119
	v_add_f32_e32 v100, 1.0, v100
	v_add_f32_e32 v101, 1.0, v101
	v_rcp_f32_e32 v113, v102
	v_add_f32_e32 v102, 1.0, v103
	v_rcp_f32_e32 v116, v116
	v_rcp_f32_e32 v117, v117
	v_rcp_f32_e32 v118, v118
	v_rcp_f32_e32 v112, v119
	v_rcp_f32_e32 v100, v100
	v_rcp_f32_e32 v101, v101
	v_rcp_f32_e32 v114, v102
	v_cvt_pk_bf16_f32 v103, v116, v117
	v_cvt_pk_bf16_f32 v102, v118, v112
	v_cvt_pk_bf16_f32 v101, v100, v101
	v_cvt_pk_bf16_f32 v100, v113, v114
	v_add_u32_e32 v112, 0x24840, v160
	v_add_u32_e32 v116, 0x24c40, v160
	ds_read_b128 v[112:115], v112
	ds_read_b128 v[116:119], v116
	ds_read_b32 v168, v164
	ds_read_b32 v169, v165
	ds_read_b32 v170, v166
	ds_read_b32 v171, v167
	s_waitcnt lgkmcnt(3)
	v_fma_f32 v120, -v112, v168, v120
	v_fma_f32 v121, -v113, v168, v121
	s_waitcnt lgkmcnt(1)
	v_fma_f32 v106, -v114, v170, v106
	v_fma_f32 v122, -v114, v168, v122
	v_fma_f32 v123, -v115, v168, v123
	v_fma_f32 v104, -v112, v170, v104
	v_fma_f32 v105, -v113, v170, v105
	s_waitcnt lgkmcnt(0)
	v_fma_f32 v106, v171, v106, v118
	v_fma_f32 v107, -v115, v170, v107
	v_fma_f32 v120, v169, v120, v116
	v_fma_f32 v121, v169, v121, v117
	v_fma_f32 v122, v169, v122, v118
	v_fma_f32 v123, v169, v123, v119
	v_fma_f32 v104, v171, v104, v116
	v_fma_f32 v105, v171, v105, v117
	v_mul_f32_e32 v106, 0xbfb8aa3b, v106
	v_fmac_f32_e32 v119, v171, v107
	v_mul_f32_e32 v120, 0xbfb8aa3b, v120
	v_mul_f32_e32 v121, 0xbfb8aa3b, v121
	v_mul_f32_e32 v122, 0xbfb8aa3b, v122
	v_mul_f32_e32 v123, 0xbfb8aa3b, v123
	v_mul_f32_e32 v104, 0xbfb8aa3b, v104
	v_mul_f32_e32 v105, 0xbfb8aa3b, v105
	v_exp_f32_e32 v106, v106
	v_mul_f32_e32 v107, 0xbfb8aa3b, v119
	v_exp_f32_e32 v120, v120
	v_exp_f32_e32 v121, v121
	v_exp_f32_e32 v122, v122
	v_exp_f32_e32 v123, v123
	v_exp_f32_e32 v104, v104
	v_exp_f32_e32 v105, v105
	v_exp_f32_e32 v107, v107
	v_add_f32_e32 v106, 1.0, v106
	v_add_f32_e32 v120, 1.0, v120
	v_add_f32_e32 v121, 1.0, v121
	v_add_f32_e32 v122, 1.0, v122
	v_add_f32_e32 v123, 1.0, v123
	v_add_f32_e32 v104, 1.0, v104
	v_add_f32_e32 v105, 1.0, v105
	v_rcp_f32_e32 v113, v106
	v_add_f32_e32 v106, 1.0, v107
	v_rcp_f32_e32 v120, v120
	v_rcp_f32_e32 v121, v121
	v_rcp_f32_e32 v122, v122
	v_rcp_f32_e32 v112, v123
	v_rcp_f32_e32 v104, v104
	v_rcp_f32_e32 v105, v105
	v_rcp_f32_e32 v114, v106
	v_cvt_pk_bf16_f32 v107, v120, v121
	v_cvt_pk_bf16_f32 v106, v122, v112
	v_cvt_pk_bf16_f32 v105, v104, v105
	v_cvt_pk_bf16_f32 v104, v113, v114
	v_add_u32_e32 v112, 0x24860, v160
	v_add_u32_e32 v116, 0x24c60, v160
	ds_read_b128 v[112:115], v112
	ds_read_b128 v[116:119], v116
	ds_read_b32 v120, v164
	ds_read_b32 v121, v165
	ds_read_b32 v122, v166
	ds_read_b32 v123, v167
	s_waitcnt lgkmcnt(3)
; DI unsigned pack2(float a, float b) { f32x2_t v = {a, b}; bf16x2_t r = __builtin_convertvector(v, bf16x2_t); return __builtin_bit_cast(unsigned, r); }
; DI float sigmoidf_(float x) { return __builtin_amdgcn_rcpf(1.f + __expf(-x)); }
; template <bool LAST>
; DI void phase_gate(const Params& P, int layer, unsigned char* smem, int L, int G) {
;     ...
;     unsigned gq[4][2][8];
; #pragma unroll
;     for (int i = 0; i < 4; ++i)
; #pragma unroll
;       for (int q4 = 0; q4 < 4; ++q4) {
;         const int fl = wm * 128 + i * 32 + 8 * q4 + 4 * h;
;         const f32x4 c1v = *(const f32x4*)(vecL + fl), c2v = *(const f32x4*)(vecL + 256 + fl);
;         const float c1a[4] = {c1v.x, c1v.y, c1v.z, c1v.w}, c2a[4] = {c2v.x, c2v.y, c2v.z, c2v.w};
; #pragma unroll
;         for (int j = 0; j < 2; ++j) {
;           const int lrow = wn * 64 + j * 32 + r;
;           const float mu = rowA[lrow], rstd = rowB[lrow];
;           float sg4[4];
; #pragma unroll
;           for (int e = 0; e < 4; ++e) sg4[e] = sigmoidf_(rstd * (accu[i][j][4 * q4 + e] - mu * c1a[e]) + c2a[e]);
;           gq[i][j][2 * q4] = pack2(sg4[0], sg4[1]); gq[i][j][2 * q4 + 1] = pack2(sg4[2], sg4[3]);
;         }
;         __builtin_amdgcn_sched_barrier(0);
;       }
	v_fma_f32 v125, -v113, v120, v125
	v_fma_f32 v124, -v112, v120, v124
	s_waitcnt lgkmcnt(1)
	v_fma_f32 v110, -v114, v122, v110
	v_fma_f32 v125, v121, v125, v117
	v_fma_f32 v126, -v114, v120, v126
	v_fma_f32 v120, -v115, v120, v127
	v_fma_f32 v108, -v112, v122, v108
	v_fma_f32 v109, -v113, v122, v109
	s_waitcnt lgkmcnt(0)
	v_fma_f32 v110, v123, v110, v118
	v_fma_f32 v111, -v115, v122, v111
	v_fma_f32 v124, v121, v124, v116
	v_mul_f32_e32 v125, 0xbfb8aa3b, v125
	v_fma_f32 v126, v121, v126, v118
	v_fma_f32 v120, v121, v120, v119
	v_fma_f32 v108, v123, v108, v116
	v_fma_f32 v109, v123, v109, v117
	v_mul_f32_e32 v110, 0xbfb8aa3b, v110
	v_fmac_f32_e32 v119, v123, v111
	v_mul_f32_e32 v124, 0xbfb8aa3b, v124
	v_exp_f32_e32 v125, v125
	v_mul_f32_e32 v126, 0xbfb8aa3b, v126
	v_mul_f32_e32 v120, 0xbfb8aa3b, v120
	v_mul_f32_e32 v108, 0xbfb8aa3b, v108
	v_mul_f32_e32 v109, 0xbfb8aa3b, v109
	v_exp_f32_e32 v110, v110
	v_mul_f32_e32 v111, 0xbfb8aa3b, v119
	v_exp_f32_e32 v124, v124
	v_exp_f32_e32 v126, v126
	v_exp_f32_e32 v120, v120
	v_exp_f32_e32 v108, v108
	v_exp_f32_e32 v109, v109
	v_exp_f32_e32 v111, v111
	v_add_f32_e32 v125, 1.0, v125
	v_add_f32_e32 v110, 1.0, v110
	v_add_f32_e32 v124, 1.0, v124
	v_rcp_f32_e32 v121, v125
	v_add_f32_e32 v125, 1.0, v126
	v_add_f32_e32 v120, 1.0, v120
	v_add_f32_e32 v108, 1.0, v108
	v_add_f32_e32 v109, 1.0, v109
	v_rcp_f32_e32 v113, v110
	v_add_f32_e32 v110, 1.0, v111
	v_rcp_f32_e32 v124, v124
	v_rcp_f32_e32 v125, v125
	v_rcp_f32_e32 v112, v120
	v_rcp_f32_e32 v108, v108
	v_rcp_f32_e32 v109, v109
	v_rcp_f32_e32 v114, v110
	v_cvt_pk_bf16_f32 v111, v124, v121
	v_cvt_pk_bf16_f32 v110, v125, v112
	v_cvt_pk_bf16_f32 v109, v108, v109
	v_cvt_pk_bf16_f32 v108, v113, v114
	v_add_u32_e32 v112, 0x24880, v160
	v_add_u32_e32 v116, 0x24c80, v160
	ds_read_b128 v[112:115], v112
	ds_read_b128 v[116:119], v116
	ds_read_b32 v120, v164
	ds_read_b32 v121, v165
	ds_read_b32 v122, v166
	ds_read_b32 v123, v167
	s_waitcnt lgkmcnt(3)
	v_fma_f32 v80, -v112, v120, v80
	v_fma_f32 v81, -v113, v120, v81
	s_waitcnt lgkmcnt(1)
	v_fma_f32 v66, -v114, v122, v66
	v_fma_f32 v82, -v114, v120, v82
	v_fma_f32 v83, -v115, v120, v83
	v_fma_f32 v64, -v112, v122, v64
	v_fma_f32 v65, -v113, v122, v65
	s_waitcnt lgkmcnt(0)
	v_fma_f32 v66, v123, v66, v118
	v_fma_f32 v67, -v115, v122, v67
	v_fma_f32 v80, v121, v80, v116
	v_fma_f32 v81, v121, v81, v117
	v_fma_f32 v82, v121, v82, v118
	v_fma_f32 v83, v121, v83, v119
	v_fma_f32 v64, v123, v64, v116
	v_fma_f32 v65, v123, v65, v117
	v_mul_f32_e32 v66, 0xbfb8aa3b, v66
	v_fmac_f32_e32 v119, v123, v67
	v_mul_f32_e32 v80, 0xbfb8aa3b, v80
	v_mul_f32_e32 v81, 0xbfb8aa3b, v81
	v_mul_f32_e32 v82, 0xbfb8aa3b, v82
	v_mul_f32_e32 v83, 0xbfb8aa3b, v83
	v_mul_f32_e32 v64, 0xbfb8aa3b, v64
	v_mul_f32_e32 v65, 0xbfb8aa3b, v65
	v_exp_f32_e32 v66, v66
	v_mul_f32_e32 v67, 0xbfb8aa3b, v119
	v_exp_f32_e32 v80, v80
	v_exp_f32_e32 v81, v81
	v_exp_f32_e32 v82, v82
	v_exp_f32_e32 v83, v83
	v_exp_f32_e32 v64, v64
	v_exp_f32_e32 v65, v65
	v_exp_f32_e32 v67, v67
	v_add_f32_e32 v66, 1.0, v66
	v_add_f32_e32 v80, 1.0, v80
	v_add_f32_e32 v81, 1.0, v81
	v_add_f32_e32 v82, 1.0, v82
	v_add_f32_e32 v83, 1.0, v83
	v_add_f32_e32 v64, 1.0, v64
	v_add_f32_e32 v65, 1.0, v65
	v_rcp_f32_e32 v112, v66
	v_add_f32_e32 v66, 1.0, v67
	v_rcp_f32_e32 v80, v80
	v_rcp_f32_e32 v81, v81
	v_rcp_f32_e32 v82, v82
	v_rcp_f32_e32 v83, v83
	v_rcp_f32_e32 v64, v64
	v_rcp_f32_e32 v65, v65
	v_rcp_f32_e32 v113, v66
	v_cvt_pk_bf16_f32 v67, v80, v81
	v_cvt_pk_bf16_f32 v66, v82, v83
	v_cvt_pk_bf16_f32 v65, v64, v65
	v_cvt_pk_bf16_f32 v64, v112, v113
	v_add_u32_e32 v80, 0x248a0, v160
	v_add_u32_e32 v112, 0x24ca0, v160
	ds_read_b128 v[80:83], v80
	ds_read_b128 v[112:115], v112
	ds_read_b32 v116, v164
	ds_read_b32 v117, v165
	ds_read_b32 v118, v166
	ds_read_b32 v119, v167
	s_waitcnt lgkmcnt(3)
	v_fma_f32 v84, -v80, v116, v84
	v_fma_f32 v85, -v81, v116, v85
	s_waitcnt lgkmcnt(1)
	v_fma_f32 v70, -v82, v118, v70
	v_fma_f32 v86, -v82, v116, v86
	v_fma_f32 v87, -v83, v116, v87
	v_fma_f32 v68, -v80, v118, v68
	v_fma_f32 v69, -v81, v118, v69
	s_waitcnt lgkmcnt(0)
	v_fma_f32 v70, v119, v70, v114
	v_fma_f32 v71, -v83, v118, v71
	v_fma_f32 v84, v117, v84, v112
	v_fma_f32 v85, v117, v85, v113
	v_fma_f32 v86, v117, v86, v114
	v_fma_f32 v87, v117, v87, v115
	v_fma_f32 v68, v119, v68, v112
	v_fma_f32 v69, v119, v69, v113
	v_mul_f32_e32 v70, 0xbfb8aa3b, v70
	v_fmac_f32_e32 v115, v119, v71
	v_mul_f32_e32 v84, 0xbfb8aa3b, v84
	v_mul_f32_e32 v85, 0xbfb8aa3b, v85
	v_mul_f32_e32 v86, 0xbfb8aa3b, v86
	v_mul_f32_e32 v87, 0xbfb8aa3b, v87
	v_mul_f32_e32 v68, 0xbfb8aa3b, v68
	v_mul_f32_e32 v69, 0xbfb8aa3b, v69
	v_exp_f32_e32 v70, v70
	v_mul_f32_e32 v71, 0xbfb8aa3b, v115
	v_exp_f32_e32 v84, v84
	v_exp_f32_e32 v85, v85
	v_exp_f32_e32 v86, v86
	v_exp_f32_e32 v87, v87
	v_exp_f32_e32 v68, v68
	v_exp_f32_e32 v69, v69
	v_exp_f32_e32 v71, v71
	v_add_f32_e32 v70, 1.0, v70
	v_add_f32_e32 v84, 1.0, v84
	v_add_f32_e32 v85, 1.0, v85
	v_add_f32_e32 v86, 1.0, v86
	v_add_f32_e32 v87, 1.0, v87
	v_add_f32_e32 v68, 1.0, v68
	v_add_f32_e32 v69, 1.0, v69
	v_rcp_f32_e32 v81, v70
	v_add_f32_e32 v70, 1.0, v71
	v_rcp_f32_e32 v84, v84
	v_rcp_f32_e32 v85, v85
	v_rcp_f32_e32 v86, v86
	v_rcp_f32_e32 v80, v87
	v_rcp_f32_e32 v68, v68
	v_rcp_f32_e32 v69, v69
	v_rcp_f32_e32 v82, v70
	v_cvt_pk_bf16_f32 v71, v84, v85
	v_cvt_pk_bf16_f32 v70, v86, v80
	v_cvt_pk_bf16_f32 v69, v68, v69
	v_cvt_pk_bf16_f32 v68, v81, v82
	v_add_u32_e32 v80, 0x248c0, v160
	v_add_u32_e32 v84, 0x24cc0, v160
	ds_read_b128 v[80:83], v80
	ds_read_b128 v[84:87], v84
	ds_read_b32 v112, v164
	ds_read_b32 v113, v165
	ds_read_b32 v114, v166
	ds_read_b32 v115, v167
	s_waitcnt lgkmcnt(3)
; DI unsigned pack2(float a, float b) { f32x2_t v = {a, b}; bf16x2_t r = __builtin_convertvector(v, bf16x2_t); return __builtin_bit_cast(unsigned, r); }
; DI float sigmoidf_(float x) { return __builtin_amdgcn_rcpf(1.f + __expf(-x)); }
; template <bool LAST>
; DI void phase_gate(const Params& P, int layer, unsigned char* smem, int L, int G) {
;     ...
;     unsigned gq[4][2][8];
; #pragma unroll
;     for (int i = 0; i < 4; ++i)
; #pragma unroll
;       for (int q4 = 0; q4 < 4; ++q4) {
;         const int fl = wm * 128 + i * 32 + 8 * q4 + 4 * h;
;         const f32x4 c1v = *(const f32x4*)(vecL + fl), c2v = *(const f32x4*)(vecL + 256 + fl);
;         const float c1a[4] = {c1v.x, c1v.y, c1v.z, c1v.w}, c2a[4] = {c2v.x, c2v.y, c2v.z, c2v.w};
; #pragma unroll
;         for (int j = 0; j < 2; ++j) {
;           const int lrow = wn * 64 + j * 32 + r;
;           const float mu = rowA[lrow], rstd = rowB[lrow];
;           float sg4[4];
; #pragma unroll
;           for (int e = 0; e < 4; ++e) sg4[e] = sigmoidf_(rstd * (accu[i][j][4 * q4 + e] - mu * c1a[e]) + c2a[e]);
;           gq[i][j][2 * q4] = pack2(sg4[0], sg4[1]); gq[i][j][2 * q4 + 1] = pack2(sg4[2], sg4[3]);
;         }
;         __builtin_amdgcn_sched_barrier(0);
;       }
	v_fma_f32 v88, -v80, v112, v88
	v_fma_f32 v89, -v81, v112, v89
	s_waitcnt lgkmcnt(1)
	v_fma_f32 v74, -v82, v114, v74
	v_fma_f32 v90, -v82, v112, v90
	v_fma_f32 v91, -v83, v112, v91
	v_fma_f32 v72, -v80, v114, v72
	v_fma_f32 v73, -v81, v114, v73
	s_waitcnt lgkmcnt(0)
	v_fma_f32 v74, v115, v74, v86
	v_fma_f32 v75, -v83, v114, v75
	v_fma_f32 v88, v113, v88, v84
	v_fma_f32 v89, v113, v89, v85
	v_fma_f32 v90, v113, v90, v86
	v_fma_f32 v91, v113, v91, v87
	v_fma_f32 v72, v115, v72, v84
	v_fma_f32 v73, v115, v73, v85
	v_mul_f32_e32 v74, 0xbfb8aa3b, v74
	v_fmac_f32_e32 v87, v115, v75
	v_mul_f32_e32 v88, 0xbfb8aa3b, v88
	v_mul_f32_e32 v89, 0xbfb8aa3b, v89
	v_mul_f32_e32 v90, 0xbfb8aa3b, v90
	v_mul_f32_e32 v91, 0xbfb8aa3b, v91
	v_mul_f32_e32 v72, 0xbfb8aa3b, v72
	v_mul_f32_e32 v73, 0xbfb8aa3b, v73
	v_exp_f32_e32 v74, v74
	v_mul_f32_e32 v75, 0xbfb8aa3b, v87
	v_exp_f32_e32 v88, v88
	v_exp_f32_e32 v89, v89
	v_exp_f32_e32 v90, v90
	v_exp_f32_e32 v91, v91
	v_exp_f32_e32 v72, v72
	v_exp_f32_e32 v73, v73
	v_exp_f32_e32 v75, v75
	v_add_f32_e32 v74, 1.0, v74
	v_add_f32_e32 v88, 1.0, v88
	v_add_f32_e32 v89, 1.0, v89
	v_add_f32_e32 v90, 1.0, v90
	v_add_f32_e32 v91, 1.0, v91
	v_add_f32_e32 v72, 1.0, v72
	v_add_f32_e32 v73, 1.0, v73
	v_rcp_f32_e32 v81, v74
	v_add_f32_e32 v74, 1.0, v75
	v_rcp_f32_e32 v88, v88
	v_rcp_f32_e32 v89, v89
	v_rcp_f32_e32 v90, v90
	v_rcp_f32_e32 v80, v91
	v_rcp_f32_e32 v72, v72
	v_rcp_f32_e32 v73, v73
	v_rcp_f32_e32 v82, v74
	v_cvt_pk_bf16_f32 v75, v88, v89
	v_cvt_pk_bf16_f32 v74, v90, v80
	v_cvt_pk_bf16_f32 v73, v72, v73
	v_cvt_pk_bf16_f32 v72, v81, v82
	v_add_u32_e32 v80, 0x248e0, v160
	v_add_u32_e32 v84, 0x24ce0, v160
	ds_read_b128 v[80:83], v80
	ds_read_b128 v[84:87], v84
	ds_read_b32 v88, v164
	ds_read_b32 v89, v165
	ds_read_b32 v90, v166
	ds_read_b32 v91, v167
	s_waitcnt lgkmcnt(3)
	v_fma_f32 v93, -v81, v88, v93
	v_fma_f32 v92, -v80, v88, v92
	s_waitcnt lgkmcnt(1)
	v_fma_f32 v78, -v82, v90, v78
	v_fma_f32 v93, v89, v93, v85
	v_fma_f32 v94, -v82, v88, v94
	v_fma_f32 v88, -v83, v88, v95
	v_fma_f32 v76, -v80, v90, v76
	v_fma_f32 v77, -v81, v90, v77
	s_waitcnt lgkmcnt(0)
	v_fma_f32 v78, v91, v78, v86
	v_fma_f32 v79, -v83, v90, v79
	v_fma_f32 v92, v89, v92, v84
	v_mul_f32_e32 v93, 0xbfb8aa3b, v93
	v_fma_f32 v94, v89, v94, v86
	v_fma_f32 v88, v89, v88, v87
	v_fma_f32 v76, v91, v76, v84
	v_fma_f32 v77, v91, v77, v85
	v_mul_f32_e32 v78, 0xbfb8aa3b, v78
	v_fmac_f32_e32 v87, v91, v79
	v_mul_f32_e32 v92, 0xbfb8aa3b, v92
	v_exp_f32_e32 v93, v93
	v_mul_f32_e32 v94, 0xbfb8aa3b, v94
	v_mul_f32_e32 v88, 0xbfb8aa3b, v88
	v_mul_f32_e32 v76, 0xbfb8aa3b, v76
	v_mul_f32_e32 v77, 0xbfb8aa3b, v77
	v_exp_f32_e32 v78, v78
	v_mul_f32_e32 v79, 0xbfb8aa3b, v87
	v_exp_f32_e32 v92, v92
	v_exp_f32_e32 v94, v94
	v_exp_f32_e32 v88, v88
	v_exp_f32_e32 v76, v76
	v_exp_f32_e32 v77, v77
	v_exp_f32_e32 v79, v79
	v_add_f32_e32 v93, 1.0, v93
	v_add_f32_e32 v78, 1.0, v78
	v_add_f32_e32 v92, 1.0, v92
	v_rcp_f32_e32 v89, v93
	v_add_f32_e32 v93, 1.0, v94
	v_add_f32_e32 v88, 1.0, v88
	v_add_f32_e32 v76, 1.0, v76
	v_add_f32_e32 v77, 1.0, v77
	v_rcp_f32_e32 v81, v78
	v_add_f32_e32 v78, 1.0, v79
	v_rcp_f32_e32 v92, v92
	v_rcp_f32_e32 v93, v93
	v_rcp_f32_e32 v80, v88
	v_rcp_f32_e32 v76, v76
	v_rcp_f32_e32 v77, v77
	v_rcp_f32_e32 v82, v78
	v_cvt_pk_bf16_f32 v79, v92, v89
	v_cvt_pk_bf16_f32 v78, v93, v80
	v_cvt_pk_bf16_f32 v77, v76, v77
	v_cvt_pk_bf16_f32 v76, v81, v82
	v_add_u32_e32 v80, 0x24900, v160
	v_add_u32_e32 v84, 0x24d00, v160
	ds_read_b128 v[80:83], v80
	ds_read_b128 v[84:87], v84
	ds_read_b32 v88, v164
	ds_read_b32 v89, v165
	ds_read_b32 v90, v166
	ds_read_b32 v91, v167
	s_waitcnt lgkmcnt(3)
	v_fma_f32 v48, -v80, v88, v48
	v_fma_f32 v49, -v81, v88, v49
	s_waitcnt lgkmcnt(1)
	v_fma_f32 v34, -v82, v90, v34
	v_fma_f32 v50, -v82, v88, v50
	v_fma_f32 v51, -v83, v88, v51
	v_fma_f32 v32, -v80, v90, v32
	v_fma_f32 v33, -v81, v90, v33
	s_waitcnt lgkmcnt(0)
	v_fma_f32 v34, v91, v34, v86
	v_fma_f32 v35, -v83, v90, v35
	v_fma_f32 v48, v89, v48, v84
	v_fma_f32 v49, v89, v49, v85
	v_fma_f32 v50, v89, v50, v86
	v_fma_f32 v51, v89, v51, v87
	v_fma_f32 v32, v91, v32, v84
	v_fma_f32 v33, v91, v33, v85
	v_mul_f32_e32 v34, 0xbfb8aa3b, v34
	v_fmac_f32_e32 v87, v91, v35
	v_mul_f32_e32 v48, 0xbfb8aa3b, v48
	v_mul_f32_e32 v49, 0xbfb8aa3b, v49
	v_mul_f32_e32 v50, 0xbfb8aa3b, v50
	v_mul_f32_e32 v51, 0xbfb8aa3b, v51
	v_mul_f32_e32 v32, 0xbfb8aa3b, v32
	v_mul_f32_e32 v33, 0xbfb8aa3b, v33
	v_exp_f32_e32 v34, v34
	v_mul_f32_e32 v35, 0xbfb8aa3b, v87
	v_exp_f32_e32 v48, v48
	v_exp_f32_e32 v49, v49
	v_exp_f32_e32 v50, v50
	v_exp_f32_e32 v51, v51
	v_exp_f32_e32 v32, v32
	v_exp_f32_e32 v33, v33
	v_exp_f32_e32 v35, v35
	v_add_f32_e32 v34, 1.0, v34
	v_add_f32_e32 v48, 1.0, v48
	v_add_f32_e32 v49, 1.0, v49
	v_add_f32_e32 v50, 1.0, v50
	v_add_f32_e32 v51, 1.0, v51
	v_add_f32_e32 v32, 1.0, v32
	v_add_f32_e32 v33, 1.0, v33
	v_rcp_f32_e32 v80, v34
	v_add_f32_e32 v34, 1.0, v35
	v_rcp_f32_e32 v48, v48
	v_rcp_f32_e32 v49, v49
	v_rcp_f32_e32 v50, v50
	v_rcp_f32_e32 v51, v51
	v_rcp_f32_e32 v32, v32
	v_rcp_f32_e32 v33, v33
	v_rcp_f32_e32 v81, v34
	v_cvt_pk_bf16_f32 v35, v48, v49
	v_cvt_pk_bf16_f32 v34, v50, v51
	v_cvt_pk_bf16_f32 v33, v32, v33
	v_cvt_pk_bf16_f32 v32, v80, v81
	v_add_u32_e32 v48, 0x24920, v160
	v_add_u32_e32 v80, 0x24d20, v160
	ds_read_b128 v[48:51], v48
	ds_read_b128 v[80:83], v80
	ds_read_b32 v84, v164
	ds_read_b32 v85, v165
	ds_read_b32 v86, v166
	ds_read_b32 v87, v167
	s_waitcnt lgkmcnt(3)
	v_fma_f32 v53, -v49, v84, v53
	v_fma_f32 v52, -v48, v84, v52
	s_waitcnt lgkmcnt(1)
	v_fma_f32 v36, -v48, v86, v36
	s_waitcnt lgkmcnt(0)
; DI unsigned pack2(float a, float b) { f32x2_t v = {a, b}; bf16x2_t r = __builtin_convertvector(v, bf16x2_t); return __builtin_bit_cast(unsigned, r); }
; DI float sigmoidf_(float x) { return __builtin_amdgcn_rcpf(1.f + __expf(-x)); }
; template <bool LAST>
; DI void phase_gate(const Params& P, int layer, unsigned char* smem, int L, int G) {
;     ...
;     unsigned gq[4][2][8];
; #pragma unroll
;     for (int i = 0; i < 4; ++i)
; #pragma unroll
;       for (int q4 = 0; q4 < 4; ++q4) {
;         const int fl = wm * 128 + i * 32 + 8 * q4 + 4 * h;
;         const f32x4 c1v = *(const f32x4*)(vecL + fl), c2v = *(const f32x4*)(vecL + 256 + fl);
;         const float c1a[4] = {c1v.x, c1v.y, c1v.z, c1v.w}, c2a[4] = {c2v.x, c2v.y, c2v.z, c2v.w};
; #pragma unroll
;         for (int j = 0; j < 2; ++j) {
;           const int lrow = wn * 64 + j * 32 + r;
;           const float mu = rowA[lrow], rstd = rowB[lrow];
;           float sg4[4];
; #pragma unroll
;           for (int e = 0; e < 4; ++e) sg4[e] = sigmoidf_(rstd * (accu[i][j][4 * q4 + e] - mu * c1a[e]) + c2a[e]);
;           gq[i][j][2 * q4] = pack2(sg4[0], sg4[1]); gq[i][j][2 * q4 + 1] = pack2(sg4[2], sg4[3]);
;         }
;         __builtin_amdgcn_sched_barrier(0);
;       }
	v_fma_f32 v36, v87, v36, v80
	v_fma_f32 v37, -v49, v86, v37
	v_mul_f32_e32 v36, 0xbfb8aa3b, v36
	v_fma_f32 v37, v87, v37, v81
	v_exp_f32_e32 v36, v36
	v_mul_f32_e32 v37, 0xbfb8aa3b, v37
	v_exp_f32_e32 v37, v37
	v_fma_f32 v54, -v50, v84, v54
	v_add_f32_e32 v36, 1.0, v36
	v_rcp_f32_e32 v49, v36
	v_add_f32_e32 v36, 1.0, v37
	v_fma_f32 v37, -v50, v86, v38
	v_fma_f32 v55, -v51, v84, v55
	v_fma_f32 v37, v87, v37, v82
	v_fma_f32 v38, -v51, v86, v39
	v_fma_f32 v52, v85, v52, v80
	v_fma_f32 v53, v85, v53, v81
	v_fma_f32 v54, v85, v54, v82
	v_fma_f32 v55, v85, v55, v83
	v_mul_f32_e32 v37, 0xbfb8aa3b, v37
	v_fmac_f32_e32 v83, v87, v38
	v_mul_f32_e32 v52, 0xbfb8aa3b, v52
	v_mul_f32_e32 v53, 0xbfb8aa3b, v53
	v_mul_f32_e32 v54, 0xbfb8aa3b, v54
	v_mul_f32_e32 v55, 0xbfb8aa3b, v55
	v_exp_f32_e32 v37, v37
	v_mul_f32_e32 v38, 0xbfb8aa3b, v83
	v_exp_f32_e32 v52, v52
	v_exp_f32_e32 v53, v53
	v_exp_f32_e32 v54, v54
	v_exp_f32_e32 v55, v55
	v_exp_f32_e32 v38, v38
	v_rcp_f32_e32 v39, v36
	v_add_f32_e32 v36, 1.0, v37
	v_add_f32_e32 v52, 1.0, v52
	v_add_f32_e32 v53, 1.0, v53
	v_add_f32_e32 v54, 1.0, v54
	v_add_f32_e32 v55, 1.0, v55
	v_rcp_f32_e32 v37, v36
	v_add_f32_e32 v36, 1.0, v38
	v_rcp_f32_e32 v52, v52
	v_rcp_f32_e32 v53, v53
	v_rcp_f32_e32 v54, v54
	v_rcp_f32_e32 v48, v55
	v_rcp_f32_e32 v38, v36
	v_cvt_pk_bf16_f32 v80, v52, v53
	v_cvt_pk_bf16_f32 v55, v49, v39
	v_cvt_pk_bf16_f32 v36, v54, v48
	v_cvt_pk_bf16_f32 v53, v37, v38
	v_add_u32_e32 v37, 0x24940, v160
	v_add_u32_e32 v38, 0x24d40, v160
	ds_read_b128 v[48:51], v37
	ds_read_b128 v[82:85], v38
	ds_read_b32 v37, v164
	ds_read_b32 v38, v165
	ds_read_b32 v39, v166
	ds_read_b32 v52, v167
	s_waitcnt lgkmcnt(3)
	v_fma_f32 v54, -v48, v37, v56
	v_fma_f32 v56, -v49, v37, v57
	s_waitcnt lgkmcnt(2)
	v_fma_f32 v56, v38, v56, v83
	v_fma_f32 v57, -v50, v37, v58
	v_fma_f32 v37, -v51, v37, v59
	s_waitcnt lgkmcnt(1)
	v_fma_f32 v40, -v48, v39, v40
	v_fma_f32 v41, -v49, v39, v41
	v_fma_f32 v42, -v50, v39, v42
	v_fma_f32 v39, -v51, v39, v43
	v_fma_f32 v54, v38, v54, v82
	v_mul_f32_e32 v56, 0xbfb8aa3b, v56
	v_fma_f32 v57, v38, v57, v84
	v_fma_f32 v37, v38, v37, v85
	s_waitcnt lgkmcnt(0)
	v_fma_f32 v40, v52, v40, v82
	v_fma_f32 v41, v52, v41, v83
	v_fma_f32 v42, v52, v42, v84
	v_fmac_f32_e32 v85, v52, v39
	v_mul_f32_e32 v54, 0xbfb8aa3b, v54
	v_exp_f32_e32 v56, v56
	v_mul_f32_e32 v57, 0xbfb8aa3b, v57
	v_mul_f32_e32 v37, 0xbfb8aa3b, v37
	v_mul_f32_e32 v40, 0xbfb8aa3b, v40
	v_mul_f32_e32 v41, 0xbfb8aa3b, v41
	v_mul_f32_e32 v42, 0xbfb8aa3b, v42
	v_mul_f32_e32 v39, 0xbfb8aa3b, v85
	v_exp_f32_e32 v54, v54
	v_exp_f32_e32 v57, v57
	v_exp_f32_e32 v37, v37
	v_exp_f32_e32 v40, v40
	v_exp_f32_e32 v41, v41
	v_exp_f32_e32 v42, v42
	v_exp_f32_e32 v39, v39
	v_add_f32_e32 v56, 1.0, v56
	v_add_f32_e32 v54, 1.0, v54
	v_rcp_f32_e32 v38, v56
	v_add_f32_e32 v56, 1.0, v57
	v_add_f32_e32 v37, 1.0, v37
	v_add_f32_e32 v40, 1.0, v40
	v_add_f32_e32 v41, 1.0, v41
	v_add_f32_e32 v42, 1.0, v42
	v_add_f32_e32 v39, 1.0, v39
	v_rcp_f32_e32 v54, v54
	v_rcp_f32_e32 v56, v56
	v_rcp_f32_e32 v37, v37
	v_rcp_f32_e32 v40, v40
	v_rcp_f32_e32 v41, v41
	v_rcp_f32_e32 v42, v42
	v_rcp_f32_e32 v39, v39
	v_cvt_pk_bf16_f32 v83, v54, v38
	v_cvt_pk_bf16_f32 v82, v56, v37
	v_cvt_pk_bf16_f32 v81, v40, v41
	v_cvt_pk_bf16_f32 v59, v42, v39
	v_add_u32_e32 v37, 0x24960, v160
	v_add_u32_e32 v42, 0x24d60, v160
	ds_read_b128 v[38:41], v37
	ds_read_b128 v[48:51], v42
	ds_read_b32 v37, v164
	ds_read_b32 v42, v165
	ds_read_b32 v43, v166
	ds_read_b32 v52, v167
	s_waitcnt lgkmcnt(3)
	v_fma_f32 v56, -v39, v37, v61
	v_fma_f32 v54, -v38, v37, v60
	s_waitcnt lgkmcnt(2)
	v_fma_f32 v56, v42, v56, v49
	v_fma_f32 v57, -v40, v37, v62
	v_fma_f32 v37, -v41, v37, v63
	s_waitcnt lgkmcnt(1)
	v_fma_f32 v38, -v38, v43, v44
	v_fma_f32 v39, -v39, v43, v45
	v_fma_f32 v40, -v40, v43, v46
	v_fma_f32 v41, -v41, v43, v47
	v_fma_f32 v54, v42, v54, v48
	v_mul_f32_e32 v56, 0xbfb8aa3b, v56
	v_fma_f32 v57, v42, v57, v50
	v_fma_f32 v37, v42, v37, v51
	s_waitcnt lgkmcnt(0)
	v_fma_f32 v38, v52, v38, v48
	v_fma_f32 v39, v52, v39, v49
	v_fma_f32 v40, v52, v40, v50
	v_fmac_f32_e32 v51, v52, v41
	v_mul_f32_e32 v54, 0xbfb8aa3b, v54
	v_exp_f32_e32 v56, v56
	v_mul_f32_e32 v57, 0xbfb8aa3b, v57
	v_mul_f32_e32 v37, 0xbfb8aa3b, v37
	v_mul_f32_e32 v38, 0xbfb8aa3b, v38
	v_mul_f32_e32 v39, 0xbfb8aa3b, v39
	v_mul_f32_e32 v40, 0xbfb8aa3b, v40
	v_mul_f32_e32 v41, 0xbfb8aa3b, v51
	v_exp_f32_e32 v54, v54
	v_exp_f32_e32 v57, v57
	v_exp_f32_e32 v37, v37
	v_exp_f32_e32 v38, v38
	v_exp_f32_e32 v39, v39
	v_exp_f32_e32 v40, v40
	v_exp_f32_e32 v41, v41
	v_add_f32_e32 v56, 1.0, v56
	v_add_f32_e32 v54, 1.0, v54
	v_rcp_f32_e32 v42, v56
	v_add_f32_e32 v56, 1.0, v57
	v_add_f32_e32 v37, 1.0, v37
	v_add_f32_e32 v38, 1.0, v38
	v_add_f32_e32 v39, 1.0, v39
	v_add_f32_e32 v40, 1.0, v40
	v_add_f32_e32 v41, 1.0, v41
	v_rcp_f32_e32 v54, v54
	v_rcp_f32_e32 v56, v56
	v_rcp_f32_e32 v37, v37
	v_rcp_f32_e32 v38, v38
	v_rcp_f32_e32 v39, v39
	v_rcp_f32_e32 v40, v40
	v_rcp_f32_e32 v41, v41
	v_cvt_pk_bf16_f32 v91, v54, v42
	v_cvt_pk_bf16_f32 v86, v56, v37
	v_cvt_pk_bf16_f32 v85, v38, v39
	v_cvt_pk_bf16_f32 v84, v40, v41
	v_add_u32_e32 v37, 0x24980, v160
	v_add_u32_e32 v42, 0x24d80, v160
	ds_read_b128 v[38:41], v37
	ds_read_b128 v[42:45], v42
	ds_read_b32 v37, v164
	ds_read_b32 v46, v165
	ds_read_b32 v47, v166
	ds_read_b32 v48, v167
	s_waitcnt lgkmcnt(3)
	v_fma_f32 v16, -v38, v37, v16
	v_fma_f32 v17, -v39, v37, v17
	v_fma_f32 v18, -v40, v37, v18
	v_fma_f32 v19, -v41, v37, v19
	s_waitcnt lgkmcnt(1)
	v_fma_f32 v0, -v38, v47, v0
	v_fma_f32 v1, -v39, v47, v1
	v_fma_f32 v2, -v40, v47, v2
	v_fma_f32 v3, -v41, v47, v3
	v_fma_f32 v16, v46, v16, v42
	v_fma_f32 v17, v46, v17, v43
	v_fma_f32 v18, v46, v18, v44
	v_fma_f32 v19, v46, v19, v45
	s_waitcnt lgkmcnt(0)
; DI unsigned pack2(float a, float b) { f32x2_t v = {a, b}; bf16x2_t r = __builtin_convertvector(v, bf16x2_t); return __builtin_bit_cast(unsigned, r); }
; DI float sigmoidf_(float x) { return __builtin_amdgcn_rcpf(1.f + __expf(-x)); }
; template <bool LAST>
; DI void phase_gate(const Params& P, int layer, unsigned char* smem, int L, int G) {
;     ...
;     unsigned gq[4][2][8];
; #pragma unroll
;     for (int i = 0; i < 4; ++i)
; #pragma unroll
;       for (int q4 = 0; q4 < 4; ++q4) {
;         const int fl = wm * 128 + i * 32 + 8 * q4 + 4 * h;
;         const f32x4 c1v = *(const f32x4*)(vecL + fl), c2v = *(const f32x4*)(vecL + 256 + fl);
;         const float c1a[4] = {c1v.x, c1v.y, c1v.z, c1v.w}, c2a[4] = {c2v.x, c2v.y, c2v.z, c2v.w};
; #pragma unroll
;         for (int j = 0; j < 2; ++j) {
;           const int lrow = wn * 64 + j * 32 + r;
;           const float mu = rowA[lrow], rstd = rowB[lrow];
;           float sg4[4];
; #pragma unroll
;           for (int e = 0; e < 4; ++e) sg4[e] = sigmoidf_(rstd * (accu[i][j][4 * q4 + e] - mu * c1a[e]) + c2a[e]);
;           gq[i][j][2 * q4] = pack2(sg4[0], sg4[1]); gq[i][j][2 * q4 + 1] = pack2(sg4[2], sg4[3]);
;         }
;         __builtin_amdgcn_sched_barrier(0);
;       }
	v_fma_f32 v0, v48, v0, v42
	v_fma_f32 v1, v48, v1, v43
	v_fma_f32 v2, v48, v2, v44
	v_fmac_f32_e32 v45, v48, v3
	v_mul_f32_e32 v16, 0xbfb8aa3b, v16
	v_mul_f32_e32 v17, 0xbfb8aa3b, v17
	v_mul_f32_e32 v18, 0xbfb8aa3b, v18
	v_mul_f32_e32 v19, 0xbfb8aa3b, v19
	v_mul_f32_e32 v0, 0xbfb8aa3b, v0
	v_mul_f32_e32 v1, 0xbfb8aa3b, v1
	v_mul_f32_e32 v2, 0xbfb8aa3b, v2
	v_mul_f32_e32 v3, 0xbfb8aa3b, v45
	v_exp_f32_e32 v16, v16
	v_exp_f32_e32 v17, v17
	v_exp_f32_e32 v18, v18
	v_exp_f32_e32 v19, v19
	v_exp_f32_e32 v0, v0
	v_exp_f32_e32 v1, v1
	v_exp_f32_e32 v2, v2
	v_exp_f32_e32 v3, v3
	v_add_f32_e32 v16, 1.0, v16
	v_add_f32_e32 v17, 1.0, v17
	v_add_f32_e32 v18, 1.0, v18
	v_add_f32_e32 v19, 1.0, v19
	v_add_f32_e32 v0, 1.0, v0
	v_add_f32_e32 v1, 1.0, v1
	v_add_f32_e32 v2, 1.0, v2
	v_add_f32_e32 v3, 1.0, v3
	v_rcp_f32_e32 v16, v16
	v_rcp_f32_e32 v17, v17
	v_rcp_f32_e32 v18, v18
	v_rcp_f32_e32 v19, v19
	v_rcp_f32_e32 v0, v0
	v_rcp_f32_e32 v1, v1
	v_rcp_f32_e32 v2, v2
	v_rcp_f32_e32 v37, v3
	v_cvt_pk_bf16_f32 v17, v16, v17
	v_cvt_pk_bf16_f32 v16, v18, v19
	v_cvt_pk_bf16_f32 v3, v0, v1
	v_cvt_pk_bf16_f32 v2, v2, v37
	v_add_u32_e32 v0, 0x249a0, v160
	v_add_u32_e32 v1, 0x24da0, v160
	ds_read_b128 v[38:41], v0
	ds_read_b128 v[42:45], v1
	ds_read_b32 v0, v164
	ds_read_b32 v1, v165
	ds_read_b32 v18, v166
	ds_read_b32 v19, v167
	s_waitcnt lgkmcnt(3)
	v_fma_f32 v21, -v39, v0, v21
	v_fma_f32 v20, -v38, v0, v20
	s_waitcnt lgkmcnt(1)
	v_fma_f32 v6, -v40, v18, v6
	v_fma_f32 v21, v1, v21, v43
	v_fma_f32 v22, -v40, v0, v22
	v_fma_f32 v0, -v41, v0, v23
	v_fma_f32 v4, -v38, v18, v4
	v_fma_f32 v5, -v39, v18, v5
	s_waitcnt lgkmcnt(0)
	v_fma_f32 v6, v19, v6, v44
	v_fma_f32 v7, -v41, v18, v7
	v_fma_f32 v20, v1, v20, v42
	v_mul_f32_e32 v21, 0xbfb8aa3b, v21
	v_fma_f32 v22, v1, v22, v44
	v_fma_f32 v0, v1, v0, v45
	v_fma_f32 v4, v19, v4, v42
	v_fma_f32 v5, v19, v5, v43
	v_mul_f32_e32 v6, 0xbfb8aa3b, v6
	v_fmac_f32_e32 v45, v19, v7
	v_mul_f32_e32 v20, 0xbfb8aa3b, v20
	v_exp_f32_e32 v21, v21
	v_mul_f32_e32 v22, 0xbfb8aa3b, v22
	v_mul_f32_e32 v0, 0xbfb8aa3b, v0
	v_mul_f32_e32 v4, 0xbfb8aa3b, v4
	v_mul_f32_e32 v5, 0xbfb8aa3b, v5
	v_exp_f32_e32 v6, v6
	v_mul_f32_e32 v7, 0xbfb8aa3b, v45
	v_exp_f32_e32 v20, v20
	v_exp_f32_e32 v22, v22
	v_exp_f32_e32 v0, v0
	v_exp_f32_e32 v4, v4
	v_exp_f32_e32 v5, v5
	v_exp_f32_e32 v7, v7
	v_add_f32_e32 v21, 1.0, v21
	v_add_f32_e32 v6, 1.0, v6
	v_add_f32_e32 v20, 1.0, v20
	v_rcp_f32_e32 v1, v21
	v_add_f32_e32 v21, 1.0, v22
	v_add_f32_e32 v0, 1.0, v0
	v_add_f32_e32 v4, 1.0, v4
	v_add_f32_e32 v5, 1.0, v5
	v_rcp_f32_e32 v18, v6
	v_add_f32_e32 v6, 1.0, v7
	v_rcp_f32_e32 v20, v20
	v_rcp_f32_e32 v21, v21
	v_rcp_f32_e32 v0, v0
	v_rcp_f32_e32 v4, v4
	v_rcp_f32_e32 v5, v5
	v_rcp_f32_e32 v19, v6
	v_cvt_pk_bf16_f32 v7, v20, v1
	v_cvt_pk_bf16_f32 v6, v21, v0
	v_cvt_pk_bf16_f32 v5, v4, v5
	v_cvt_pk_bf16_f32 v4, v18, v19
	v_add_u32_e32 v0, 0x249c0, v160
	v_add_u32_e32 v1, 0x24dc0, v160
	ds_read_b128 v[18:21], v0
	ds_read_b128 v[38:41], v1
	ds_read_b32 v0, v164
	ds_read_b32 v1, v165
	ds_read_b32 v22, v166
	ds_read_b32 v23, v167
	s_waitcnt lgkmcnt(3)
	v_fma_f32 v25, -v19, v0, v25
	v_fma_f32 v24, -v18, v0, v24
	s_waitcnt lgkmcnt(1)
	v_fma_f32 v9, -v19, v22, v9
	s_waitcnt lgkmcnt(0)
	v_fma_f32 v9, v23, v9, v39
	v_fma_f32 v10, -v20, v22, v10
	v_fma_f32 v25, v1, v25, v39
	v_fma_f32 v26, -v20, v0, v26
	v_fma_f32 v0, -v21, v0, v27
	v_fma_f32 v8, -v18, v22, v8
	v_mul_f32_e32 v9, 0xbfb8aa3b, v9
	v_fma_f32 v10, v23, v10, v40
	v_fma_f32 v11, -v21, v22, v11
	v_fma_f32 v24, v1, v24, v38
	v_mul_f32_e32 v25, 0xbfb8aa3b, v25
	v_fma_f32 v26, v1, v26, v40
	v_fma_f32 v0, v1, v0, v41
	v_fma_f32 v8, v23, v8, v38
	v_exp_f32_e32 v9, v9
	v_mul_f32_e32 v10, 0xbfb8aa3b, v10
	v_fmac_f32_e32 v41, v23, v11
	v_mul_f32_e32 v24, 0xbfb8aa3b, v24
	v_exp_f32_e32 v25, v25
	v_mul_f32_e32 v26, 0xbfb8aa3b, v26
	v_mul_f32_e32 v0, 0xbfb8aa3b, v0
	v_mul_f32_e32 v8, 0xbfb8aa3b, v8
	v_exp_f32_e32 v10, v10
	v_mul_f32_e32 v11, 0xbfb8aa3b, v41
	v_exp_f32_e32 v24, v24
	v_exp_f32_e32 v26, v26
	v_exp_f32_e32 v0, v0
	v_exp_f32_e32 v8, v8
	v_exp_f32_e32 v11, v11
	v_add_f32_e32 v9, 1.0, v9
	v_add_f32_e32 v25, 1.0, v25
	v_rcp_f32_e32 v18, v9
	v_add_f32_e32 v9, 1.0, v10
	v_add_f32_e32 v24, 1.0, v24
	v_rcp_f32_e32 v1, v25
	v_add_f32_e32 v25, 1.0, v26
	v_add_f32_e32 v0, 1.0, v0
	v_add_f32_e32 v8, 1.0, v8
	v_rcp_f32_e32 v10, v9
	v_add_f32_e32 v9, 1.0, v11
	v_rcp_f32_e32 v24, v24
	v_rcp_f32_e32 v25, v25
	v_rcp_f32_e32 v0, v0
	v_rcp_f32_e32 v8, v8
	v_rcp_f32_e32 v11, v9
	v_cvt_pk_bf16_f32 v27, v24, v1
	v_cvt_pk_bf16_f32 v9, v25, v0
	v_cvt_pk_bf16_f32 v19, v8, v18
	v_cvt_pk_bf16_f32 v8, v10, v11
	v_add_u32_e32 v0, 0x24de0, v160
	ds_read_b128 v[20:23], v163 offset:480
	ds_read_b32 v1, v164
	ds_read_b128 v[38:41], v0
	ds_read_b32 v0, v165
	ds_read_b32 v10, v166
	ds_read_b32 v18, v167
	s_waitcnt lgkmcnt(4)
	v_fma_f32 v24, -v21, v1, v29
	v_fma_f32 v11, -v20, v1, v28
	s_waitcnt lgkmcnt(2)
	v_fma_f32 v24, v0, v24, v39
	v_fma_f32 v25, -v22, v1, v30
	v_fma_f32 v1, -v23, v1, v31
	s_waitcnt lgkmcnt(1)
	v_fma_f32 v12, -v20, v10, v12
	v_fma_f32 v13, -v21, v10, v13
	v_fma_f32 v14, -v22, v10, v14
	v_fma_f32 v10, -v23, v10, v15
	v_fma_f32 v11, v0, v11, v38
	v_mul_f32_e32 v24, 0xbfb8aa3b, v24
	v_fma_f32 v25, v0, v25, v40
	v_fma_f32 v0, v0, v1, v41
	s_waitcnt lgkmcnt(0)
; DI unsigned pack2(float a, float b) { f32x2_t v = {a, b}; bf16x2_t r = __builtin_convertvector(v, bf16x2_t); return __builtin_bit_cast(unsigned, r); }
; DI float sigmoidf_(float x) { return __builtin_amdgcn_rcpf(1.f + __expf(-x)); }
; DI int otid() { int t = threadIdx.x; asm volatile("" : "+v"(t)); return t; }
; template <bool NT>
; DI void stage_load_tile(bf16_t* stg, const bf16_t* tilebase) {
;   const int tid = otid();
;   const int r0 = tid >> 5, c = tid & 31;
;   const unsigned o0 = (unsigned)(r0 * 1024 + c * 8);
;   __builtin_amdgcn_sched_barrier(0);
; #pragma unroll
;   for (int hf = 0; hf < 2; ++hf) {
; #pragma unroll
;     for (int it = 8 * hf; it < 8 * hf + 8; ++it) {
;       const u32x4* gp = (const u32x4*)(tilebase + (o0 + (unsigned)(it * 16 * 1024)));
;       stage_write16(stg, r0 + 16 * it, c, NT ? __builtin_nontemporal_load(gp) : *gp);
;     }
;     __builtin_amdgcn_sched_barrier(0);
;   }
; }
; template <bool LAST>
; DI void phase_gate(const Params& P, int layer, unsigned char* smem, int L, int G) {
;     ...
;           float sg4[4];
; #pragma unroll
;           for (int e = 0; e < 4; ++e) sg4[e] = sigmoidf_(rstd * (accu[i][j][4 * q4 + e] - mu * c1a[e]) + c2a[e]);
;           gq[i][j][2 * q4] = pack2(sg4[0], sg4[1]); gq[i][j][2 * q4 + 1] = pack2(sg4[2], sg4[3]);
;         }
;         __builtin_amdgcn_sched_barrier(0);
;       }
	v_fma_f32 v12, v18, v12, v38
	v_fma_f32 v13, v18, v13, v39
	v_fma_f32 v14, v18, v14, v40
	v_fmac_f32_e32 v41, v18, v10
	v_mul_f32_e32 v11, 0xbfb8aa3b, v11
	v_exp_f32_e32 v24, v24
	v_mul_f32_e32 v25, 0xbfb8aa3b, v25
	v_mul_f32_e32 v0, 0xbfb8aa3b, v0
	v_mul_f32_e32 v12, 0xbfb8aa3b, v12
	v_mul_f32_e32 v13, 0xbfb8aa3b, v13
	v_mul_f32_e32 v14, 0xbfb8aa3b, v14
	v_mul_f32_e32 v10, 0xbfb8aa3b, v41
	v_exp_f32_e32 v11, v11
	v_exp_f32_e32 v25, v25
	v_exp_f32_e32 v0, v0
	v_exp_f32_e32 v12, v12
	v_exp_f32_e32 v13, v13
	v_exp_f32_e32 v14, v14
	v_exp_f32_e32 v10, v10
	v_add_f32_e32 v24, 1.0, v24
	v_add_f32_e32 v11, 1.0, v11
	v_rcp_f32_e32 v1, v24
	v_add_f32_e32 v24, 1.0, v25
	v_add_f32_e32 v0, 1.0, v0
	v_add_f32_e32 v12, 1.0, v12
	v_add_f32_e32 v13, 1.0, v13
	v_add_f32_e32 v14, 1.0, v14
	v_add_f32_e32 v10, 1.0, v10
	v_rcp_f32_e32 v11, v11
	v_rcp_f32_e32 v24, v24
	v_rcp_f32_e32 v0, v0
	v_rcp_f32_e32 v12, v12
	v_rcp_f32_e32 v13, v13
	v_rcp_f32_e32 v14, v14
	v_rcp_f32_e32 v10, v10
	v_cvt_pk_bf16_f32 v112, v11, v1
	v_cvt_pk_bf16_f32 v30, v24, v0
	v_cvt_pk_bf16_f32 v29, v12, v13
	v_cvt_pk_bf16_f32 v28, v14, v10
	s_ashr_i32 s19, s18, 31
	s_lshl_b64 s[18:19], s[18:19], 19
	v_mov_b32_e32 v10, v192
	s_add_u32 s20, s66, s18
	v_mov_b32_e32 v163, v161
	s_addc_u32 s21, s67, s19
	v_and_b32_e32 v26, 31, v10
	v_lshlrev_b64 v[0:1], 1, v[162:163]
	v_ashrrev_i32_e32 v18, 5, v10
	v_lshlrev_b32_e32 v10, 3, v26
	v_lshl_add_u64 v[14:15], s[20:21], 0, v[0:1]
	v_lshl_or_b32 v160, v18, 10, v10
	v_add_u32_e32 v12, 0x4000, v160
	v_mov_b32_e32 v13, v161
	v_add_u32_e32 v24, 0x8000, v160
	v_mov_b32_e32 v25, v161
	v_add_u32_e32 v38, 0xc000, v160
	v_mov_b32_e32 v39, v161
	v_lshl_add_u64 v[10:11], v[160:161], 1, v[14:15]
	v_lshl_add_u64 v[20:21], v[12:13], 1, v[14:15]
	v_lshl_add_u64 v[24:25], v[24:25], 1, v[14:15]
	v_lshl_add_u64 v[42:43], v[38:39], 1, v[14:15]
	global_load_dwordx4 v[10:13], v[10:11], off nt
	s_nop 0
	global_load_dwordx4 v[20:23], v[20:21], off nt
	s_nop 0
	global_load_dwordx4 v[38:41], v[24:25], off nt
	s_nop 0
	global_load_dwordx4 v[42:45], v[42:43], off nt
	v_add_u32_e32 v24, 0x10000, v160
	v_mov_b32_e32 v25, v161
	v_lshl_add_u64 v[24:25], v[24:25], 1, v[14:15]
	v_add_u32_e32 v46, 0x14000, v160
	v_mov_b32_e32 v47, v161
	v_lshl_add_u64 v[50:51], v[46:47], 1, v[14:15]
	global_load_dwordx4 v[46:49], v[24:25], off nt
	global_load_dwordx4 v[60:63], v[50:51], off nt
	v_add_u32_e32 v24, 0x18000, v160
	v_mov_b32_e32 v25, v161
	v_lshl_add_u64 v[24:25], v[24:25], 1, v[14:15]
	v_add_u32_e32 v50, 0x1c000, v160
	v_mov_b32_e32 v51, v161
	v_lshl_add_u64 v[50:51], v[50:51], 1, v[14:15]
	global_load_dwordx4 v[92:95], v[24:25], off nt
	global_load_dwordx4 v[114:117], v[50:51], off nt
	v_add_u32_e32 v218, 0x20000, v160
	v_mov_b32_e32 v219, v161
	v_add_u32_e32 v220, 0x24000, v160
	v_mov_b32_e32 v221, v161
	v_add_u32_e32 v252, 0x28000, v160
	v_mov_b32_e32 v253, v161
	v_add_u32_e32 v226, 0x2c000, v160
	v_mov_b32_e32 v227, v161
	v_lshl_add_u64 v[218:219], v[218:219], 1, v[14:15]
	v_lshl_add_u64 v[222:223], v[220:221], 1, v[14:15]
	v_lshl_add_u64 v[252:253], v[252:253], 1, v[14:15]
	v_lshl_add_u64 v[230:231], v[226:227], 1, v[14:15]
	global_load_dwordx4 v[218:221], v[218:219], off nt
	s_nop 0
	global_load_dwordx4 v[222:225], v[222:223], off nt
	s_nop 0
	global_load_dwordx4 v[226:229], v[252:253], off nt
	s_nop 0
	global_load_dwordx4 v[230:233], v[230:231], off nt
	v_add_u32_e32 v252, 0x30000, v160
	v_mov_b32_e32 v253, v161
	v_lshl_add_u64 v[252:253], v[252:253], 1, v[14:15]
	v_add_u32_e32 v234, 0x34000, v160
	v_mov_b32_e32 v235, v161
	v_lshl_add_u64 v[254:255], v[234:235], 1, v[14:15]
	global_load_dwordx4 v[234:237], v[252:253], off nt
	global_load_dwordx4 v[238:241], v[254:255], off nt
	v_add_u32_e32 v252, 0x38000, v160
	v_mov_b32_e32 v253, v161
	v_lshl_add_u64 v[252:253], v[252:253], 1, v[14:15]
	v_add_u32_e32 v160, 0x3c000, v160
	v_lshl_add_u64 v[190:191], v[160:161], 1, v[14:15]
	global_load_dwordx4 v[242:245], v[252:253], off nt
	global_load_dwordx4 v[248:251], v[190:191], off nt
	v_mul_lo_u32 v18, v18, s34
	v_lshl_add_u32 v18, v26, 4, v18
	v_add_u32_e32 v24, 0x2080, v18
	v_add_u32_e32 v25, 0x4100, v18
	v_add_u32_e32 v26, 0x6180, v18
	v_add_u32_e32 v31, 0x8200, v18
	v_add_u32_e32 v37, 0xa280, v18
	v_add_u32_e32 v50, 0xc300, v18
	v_add_u32_e32 v51, 0xe380, v18
	s_waitcnt vmcnt(15)
	ds_write2_b64 v18, v[10:11], v[12:13] offset1:1
	s_waitcnt vmcnt(14)
	ds_write2_b64 v24, v[20:21], v[22:23] offset1:1
	s_waitcnt vmcnt(13)
	ds_write2_b64 v25, v[38:39], v[40:41] offset1:1
	s_waitcnt vmcnt(12)
	ds_write2_b64 v26, v[42:43], v[44:45] offset1:1
	s_waitcnt vmcnt(11)
	ds_write2_b64 v31, v[46:47], v[48:49] offset1:1
	s_waitcnt vmcnt(10)
	ds_write2_b64 v37, v[60:61], v[62:63] offset1:1
	s_waitcnt vmcnt(9)
	ds_write2_b64 v50, v[92:93], v[94:95] offset1:1
	s_waitcnt vmcnt(8)
	ds_write2_b64 v51, v[114:115], v[116:117] offset1:1
	v_add_u32_e32 v14, 0x10400, v18
	v_add_u32_e32 v15, 0x12480, v18
	v_add_u32_e32 v24, 0x14500, v18
	v_add_u32_e32 v25, 0x16580, v18
	v_add_u32_e32 v26, 0x18600, v18
	v_add_u32_e32 v31, 0x1a680, v18
	v_add_u32_e32 v37, 0x1c700, v18
	v_add_u32_e32 v18, 0x1e780, v18
	s_waitcnt vmcnt(7)
	ds_write2_b64 v14, v[218:219], v[220:221] offset1:1
	s_waitcnt vmcnt(6)
	ds_write2_b64 v15, v[222:223], v[224:225] offset1:1
	s_waitcnt vmcnt(5)
	ds_write2_b64 v24, v[226:227], v[228:229] offset1:1
	s_waitcnt vmcnt(4)
	ds_write2_b64 v25, v[230:231], v[232:233] offset1:1
	s_waitcnt vmcnt(3)
	ds_write2_b64 v26, v[234:235], v[236:237] offset1:1
	s_waitcnt vmcnt(2)
	ds_write2_b64 v31, v[238:239], v[240:241] offset1:1
	s_waitcnt vmcnt(1)
	ds_write2_b64 v37, v[242:243], v[244:245] offset1:1
	s_waitcnt vmcnt(0)
	ds_write2_b64 v18, v[248:249], v[250:251] offset1:1
	v_mov_b32_e32 v10, v192
	s_waitcnt lgkmcnt(0)
	s_barrier
; DI unsigned pack2(float a, float b) { f32x2_t v = {a, b}; bf16x2_t r = __builtin_convertvector(v, bf16x2_t); return __builtin_bit_cast(unsigned, r); }
; DI float bflo(unsigned u) { return __uint_as_float(u << 16); }
; DI float bfhi(unsigned u) { return __uint_as_float(u & 0xffff0000u); }
; DI int otid() { int t = threadIdx.x; asm volatile("" : "+v"(t)); return t; }
; template <bool LAST>
; DI void phase_gate(const Params& P, int layer, unsigned char* smem, int L, int G) {
;     ...
;     {
;       const int tid1 = otid();
;       const int lane1 = tid1 & 63, w1 = tid1 >> 6, r1 = lane1 & 31, h1 = lane1 >> 5, wm1 = w1 >> 2, wn1 = w1 & 3;
; #pragma unroll
;       for (int i = 0; i < 4; ++i)
; #pragma unroll
;         for (int q4 = 0; q4 < 4; ++q4) {
; #pragma unroll
;           for (int j = 0; j < 2; ++j) {
;             const uint2 pv = *(const uint2*)(stg + (wn1 * 64 + j * 32 + r1) * STG + wm1 * 128 + i * 32 + 8 * q4 + 4 * h1);
;             const unsigned g0 = gq[i][j][2 * q4], g1 = gq[i][j][2 * q4 + 1];
;             gq[i][j][2 * q4] = pack2(bflo(g0) * bflo(pv.x), bfhi(g0) * bfhi(pv.x));
;             gq[i][j][2 * q4 + 1] = pack2(bflo(g1) * bflo(pv.y), bfhi(g1) * bfhi(pv.y));
;           }
;           __builtin_amdgcn_sched_barrier(0);
;         }
;     }
;     __syncthreads();
	v_and_b32_e32 v13, 0xffff0000, v99
	v_lshrrev_b32_e32 v12, 2, v10
	v_and_b32_e32 v12, 8, v12
	v_and_b32_e32 v11, 0xdf, v10
	v_and_or_b32 v10, v10, s31, v12
	v_mad_u32_u24 v113, v11, s34, v10
	ds_read_b64 v[10:11], v113
	ds_read_b64 v[14:15], v113 offset:16640
	v_lshlrev_b32_e32 v12, 16, v99
	s_waitcnt lgkmcnt(1)
	v_lshlrev_b32_e32 v20, 16, v10
	v_and_b32_e32 v21, 0xffff0000, v10
	v_pk_mul_f32 v[12:13], v[12:13], v[20:21]
	v_lshlrev_b32_e32 v10, 16, v11
	v_cvt_pk_bf16_f32 v31, v12, v13
	v_lshlrev_b32_e32 v12, 16, v98
	v_and_b32_e32 v13, 0xffff0000, v98
	v_and_b32_e32 v11, 0xffff0000, v11
	v_pk_mul_f32 v[10:11], v[12:13], v[10:11]
	s_waitcnt lgkmcnt(0)
	v_lshlrev_b32_e32 v12, 16, v14
	v_cvt_pk_bf16_f32 v98, v10, v11
	v_lshlrev_b32_e32 v10, 16, v97
	v_and_b32_e32 v11, 0xffff0000, v97
	v_and_b32_e32 v13, 0xffff0000, v14
	v_pk_mul_f32 v[10:11], v[10:11], v[12:13]
	v_lshlrev_b32_e32 v12, 16, v15
	v_cvt_pk_bf16_f32 v97, v10, v11
	v_lshlrev_b32_e32 v10, 16, v96
	v_and_b32_e32 v11, 0xffff0000, v96
	v_and_b32_e32 v13, 0xffff0000, v15
	v_pk_mul_f32 v[10:11], v[10:11], v[12:13]
	s_nop 0
	v_cvt_pk_bf16_f32 v96, v10, v11
	ds_read_b64 v[10:11], v113 offset:16
	ds_read_b64 v[14:15], v113 offset:16656
	v_lshlrev_b32_e32 v12, 16, v103
	v_and_b32_e32 v13, 0xffff0000, v103
	s_waitcnt lgkmcnt(1)
	v_lshlrev_b32_e32 v20, 16, v10
	v_and_b32_e32 v21, 0xffff0000, v10
	v_pk_mul_f32 v[12:13], v[12:13], v[20:21]
	v_lshlrev_b32_e32 v10, 16, v11
	v_cvt_pk_bf16_f32 v93, v12, v13
	v_lshlrev_b32_e32 v12, 16, v102
	v_and_b32_e32 v13, 0xffff0000, v102
	v_and_b32_e32 v11, 0xffff0000, v11
	v_pk_mul_f32 v[10:11], v[12:13], v[10:11]
	s_waitcnt lgkmcnt(0)
	v_lshlrev_b32_e32 v12, 16, v14
	v_cvt_pk_bf16_f32 v95, v10, v11
	v_lshlrev_b32_e32 v10, 16, v101
	v_and_b32_e32 v11, 0xffff0000, v101
	v_and_b32_e32 v13, 0xffff0000, v14
	v_pk_mul_f32 v[10:11], v[10:11], v[12:13]
	v_lshlrev_b32_e32 v12, 16, v15
	v_cvt_pk_bf16_f32 v92, v10, v11
	v_lshlrev_b32_e32 v10, 16, v100
	v_and_b32_e32 v11, 0xffff0000, v100
	v_and_b32_e32 v13, 0xffff0000, v15
	v_pk_mul_f32 v[10:11], v[10:11], v[12:13]
	s_nop 0
	v_cvt_pk_bf16_f32 v94, v10, v11
	ds_read_b64 v[10:11], v113 offset:32
	ds_read_b64 v[14:15], v113 offset:16672
	v_lshlrev_b32_e32 v12, 16, v107
	v_and_b32_e32 v13, 0xffff0000, v107
	s_waitcnt lgkmcnt(1)
	v_lshlrev_b32_e32 v20, 16, v10
	v_and_b32_e32 v21, 0xffff0000, v10
	v_pk_mul_f32 v[12:13], v[12:13], v[20:21]
	v_lshlrev_b32_e32 v10, 16, v11
	v_cvt_pk_bf16_f32 v88, v12, v13
	v_lshlrev_b32_e32 v12, 16, v106
	v_and_b32_e32 v13, 0xffff0000, v106
	v_and_b32_e32 v11, 0xffff0000, v11
	v_pk_mul_f32 v[10:11], v[12:13], v[10:11]
	s_waitcnt lgkmcnt(0)
	v_lshlrev_b32_e32 v12, 16, v14
	v_cvt_pk_bf16_f32 v90, v10, v11
	v_lshlrev_b32_e32 v10, 16, v105
	v_and_b32_e32 v11, 0xffff0000, v105
	v_and_b32_e32 v13, 0xffff0000, v14
	v_pk_mul_f32 v[10:11], v[10:11], v[12:13]
	v_lshlrev_b32_e32 v12, 16, v15
	v_cvt_pk_bf16_f32 v87, v10, v11
	v_lshlrev_b32_e32 v10, 16, v104
	v_and_b32_e32 v11, 0xffff0000, v104
	v_and_b32_e32 v13, 0xffff0000, v15
	v_pk_mul_f32 v[10:11], v[10:11], v[12:13]
	s_nop 0
	v_cvt_pk_bf16_f32 v89, v10, v11
	ds_read_b64 v[10:11], v113 offset:48
	ds_read_b64 v[14:15], v113 offset:16688
	v_lshlrev_b32_e32 v12, 16, v111
	v_and_b32_e32 v13, 0xffff0000, v111
	s_waitcnt lgkmcnt(1)
	v_lshlrev_b32_e32 v20, 16, v10
	v_and_b32_e32 v21, 0xffff0000, v10
	v_pk_mul_f32 v[12:13], v[12:13], v[20:21]
	v_lshlrev_b32_e32 v10, 16, v11
	v_cvt_pk_bf16_f32 v61, v12, v13
	v_lshlrev_b32_e32 v12, 16, v110
	v_and_b32_e32 v13, 0xffff0000, v110
	v_and_b32_e32 v11, 0xffff0000, v11
	v_pk_mul_f32 v[10:11], v[12:13], v[10:11]
	s_waitcnt lgkmcnt(0)
	v_lshlrev_b32_e32 v12, 16, v14
	v_cvt_pk_bf16_f32 v63, v10, v11
	v_lshlrev_b32_e32 v10, 16, v109
	v_and_b32_e32 v11, 0xffff0000, v109
	v_and_b32_e32 v13, 0xffff0000, v14
	v_pk_mul_f32 v[10:11], v[10:11], v[12:13]
	v_lshlrev_b32_e32 v12, 16, v15
	v_cvt_pk_bf16_f32 v60, v10, v11
	v_lshlrev_b32_e32 v10, 16, v108
	v_and_b32_e32 v11, 0xffff0000, v108
	v_and_b32_e32 v13, 0xffff0000, v15
	v_pk_mul_f32 v[10:11], v[10:11], v[12:13]
	s_nop 0
	v_cvt_pk_bf16_f32 v62, v10, v11
	ds_read_b64 v[10:11], v113 offset:64
	ds_read_b64 v[14:15], v113 offset:16704
	v_lshlrev_b32_e32 v12, 16, v67
	v_and_b32_e32 v13, 0xffff0000, v67
	s_waitcnt lgkmcnt(1)
	v_lshlrev_b32_e32 v20, 16, v10
	v_and_b32_e32 v21, 0xffff0000, v10
	v_pk_mul_f32 v[12:13], v[12:13], v[20:21]
	v_lshlrev_b32_e32 v10, 16, v11
	v_cvt_pk_bf16_f32 v56, v12, v13
	v_lshlrev_b32_e32 v12, 16, v66
	v_and_b32_e32 v13, 0xffff0000, v66
	v_and_b32_e32 v11, 0xffff0000, v11
	v_pk_mul_f32 v[10:11], v[12:13], v[10:11]
	s_waitcnt lgkmcnt(0)
	v_lshlrev_b32_e32 v12, 16, v14
	v_cvt_pk_bf16_f32 v58, v10, v11
	v_lshlrev_b32_e32 v10, 16, v65
	v_and_b32_e32 v11, 0xffff0000, v65
	v_and_b32_e32 v13, 0xffff0000, v14
	v_pk_mul_f32 v[10:11], v[10:11], v[12:13]
	v_lshlrev_b32_e32 v12, 16, v15
	v_cvt_pk_bf16_f32 v54, v10, v11
	v_lshlrev_b32_e32 v10, 16, v64
	v_and_b32_e32 v11, 0xffff0000, v64
	v_and_b32_e32 v13, 0xffff0000, v15
	v_pk_mul_f32 v[10:11], v[10:11], v[12:13]
	s_nop 0
	v_cvt_pk_bf16_f32 v57, v10, v11
	ds_read_b64 v[10:11], v113 offset:80
	ds_read_b64 v[14:15], v113 offset:16720
	v_lshlrev_b32_e32 v12, 16, v71
	v_and_b32_e32 v13, 0xffff0000, v71
	s_waitcnt lgkmcnt(1)
	v_lshlrev_b32_e32 v20, 16, v10
	v_and_b32_e32 v21, 0xffff0000, v10
	v_pk_mul_f32 v[12:13], v[12:13], v[20:21]
	v_lshlrev_b32_e32 v10, 16, v11
	v_cvt_pk_bf16_f32 v50, v12, v13
	v_lshlrev_b32_e32 v12, 16, v70
	v_and_b32_e32 v13, 0xffff0000, v70
	v_and_b32_e32 v11, 0xffff0000, v11
	v_pk_mul_f32 v[10:11], v[12:13], v[10:11]
	s_waitcnt lgkmcnt(0)
; DI unsigned pack2(float a, float b) { f32x2_t v = {a, b}; bf16x2_t r = __builtin_convertvector(v, bf16x2_t); return __builtin_bit_cast(unsigned, r); }
; DI float bflo(unsigned u) { return __uint_as_float(u << 16); }
; DI float bfhi(unsigned u) { return __uint_as_float(u & 0xffff0000u); }
; DI int otid() { int t = threadIdx.x; asm volatile("" : "+v"(t)); return t; }
; template <bool LAST>
; DI void phase_gate(const Params& P, int layer, unsigned char* smem, int L, int G) {
;     ...
;     {
;       const int tid1 = otid();
;       const int lane1 = tid1 & 63, w1 = tid1 >> 6, r1 = lane1 & 31, h1 = lane1 >> 5, wm1 = w1 >> 2, wn1 = w1 & 3;
; #pragma unroll
;       for (int i = 0; i < 4; ++i)
; #pragma unroll
;         for (int q4 = 0; q4 < 4; ++q4) {
; #pragma unroll
;           for (int j = 0; j < 2; ++j) {
;             const uint2 pv = *(const uint2*)(stg + (wn1 * 64 + j * 32 + r1) * STG + wm1 * 128 + i * 32 + 8 * q4 + 4 * h1);
;             const unsigned g0 = gq[i][j][2 * q4], g1 = gq[i][j][2 * q4 + 1];
;             gq[i][j][2 * q4] = pack2(bflo(g0) * bflo(pv.x), bfhi(g0) * bfhi(pv.x));
;             gq[i][j][2 * q4 + 1] = pack2(bflo(g1) * bflo(pv.y), bfhi(g1) * bfhi(pv.y));
;           }
;           __builtin_amdgcn_sched_barrier(0);
;         }
;     }
;     __syncthreads();
	v_lshlrev_b32_e32 v12, 16, v14
	v_cvt_pk_bf16_f32 v52, v10, v11
	v_lshlrev_b32_e32 v10, 16, v69
	v_and_b32_e32 v11, 0xffff0000, v69
	v_and_b32_e32 v13, 0xffff0000, v14
	v_pk_mul_f32 v[10:11], v[10:11], v[12:13]
	v_lshlrev_b32_e32 v12, 16, v15
	v_cvt_pk_bf16_f32 v49, v10, v11
	v_lshlrev_b32_e32 v10, 16, v68
	v_and_b32_e32 v11, 0xffff0000, v68
	v_and_b32_e32 v13, 0xffff0000, v15
	v_pk_mul_f32 v[10:11], v[10:11], v[12:13]
	s_nop 0
	v_cvt_pk_bf16_f32 v51, v10, v11
	ds_read_b64 v[10:11], v113 offset:96
	ds_read_b64 v[14:15], v113 offset:16736
	v_lshlrev_b32_e32 v12, 16, v75
	v_and_b32_e32 v13, 0xffff0000, v75
	s_waitcnt lgkmcnt(1)
	v_lshlrev_b32_e32 v20, 16, v10
	v_and_b32_e32 v21, 0xffff0000, v10
	v_pk_mul_f32 v[12:13], v[12:13], v[20:21]
	v_lshlrev_b32_e32 v10, 16, v11
	v_cvt_pk_bf16_f32 v46, v12, v13
	v_lshlrev_b32_e32 v12, 16, v74
	v_and_b32_e32 v13, 0xffff0000, v74
	v_and_b32_e32 v11, 0xffff0000, v11
	v_pk_mul_f32 v[10:11], v[12:13], v[10:11]
	s_waitcnt lgkmcnt(0)
	v_lshlrev_b32_e32 v12, 16, v14
	v_cvt_pk_bf16_f32 v48, v10, v11
	v_lshlrev_b32_e32 v10, 16, v73
	v_and_b32_e32 v11, 0xffff0000, v73
	v_and_b32_e32 v13, 0xffff0000, v14
	v_pk_mul_f32 v[10:11], v[10:11], v[12:13]
	v_lshlrev_b32_e32 v12, 16, v15
	v_cvt_pk_bf16_f32 v45, v10, v11
	v_lshlrev_b32_e32 v10, 16, v72
	v_and_b32_e32 v11, 0xffff0000, v72
	v_and_b32_e32 v13, 0xffff0000, v15
	v_pk_mul_f32 v[10:11], v[10:11], v[12:13]
	s_nop 0
	v_cvt_pk_bf16_f32 v47, v10, v11
	ds_read_b64 v[10:11], v113 offset:112
	ds_read_b64 v[14:15], v113 offset:16752
	v_lshlrev_b32_e32 v12, 16, v79
	v_and_b32_e32 v13, 0xffff0000, v79
	s_waitcnt lgkmcnt(1)
	v_lshlrev_b32_e32 v20, 16, v10
	v_and_b32_e32 v21, 0xffff0000, v10
	v_pk_mul_f32 v[12:13], v[12:13], v[20:21]
	v_lshlrev_b32_e32 v10, 16, v11
	v_cvt_pk_bf16_f32 v42, v12, v13
	v_lshlrev_b32_e32 v12, 16, v78
	v_and_b32_e32 v13, 0xffff0000, v78
	v_and_b32_e32 v11, 0xffff0000, v11
	v_pk_mul_f32 v[10:11], v[12:13], v[10:11]
	s_waitcnt lgkmcnt(0)
	v_lshlrev_b32_e32 v12, 16, v14
	v_cvt_pk_bf16_f32 v44, v10, v11
	v_lshlrev_b32_e32 v10, 16, v77
	v_and_b32_e32 v11, 0xffff0000, v77
	v_and_b32_e32 v13, 0xffff0000, v14
	v_pk_mul_f32 v[10:11], v[10:11], v[12:13]
	v_lshlrev_b32_e32 v12, 16, v15
	v_cvt_pk_bf16_f32 v41, v10, v11
	v_lshlrev_b32_e32 v10, 16, v76
	v_and_b32_e32 v11, 0xffff0000, v76
	v_and_b32_e32 v13, 0xffff0000, v15
	v_pk_mul_f32 v[10:11], v[10:11], v[12:13]
	s_nop 0
	v_cvt_pk_bf16_f32 v43, v10, v11
	ds_read_b64 v[10:11], v113 offset:128
	ds_read_b64 v[14:15], v113 offset:16768
	v_lshlrev_b32_e32 v12, 16, v35
	v_and_b32_e32 v13, 0xffff0000, v35
	s_waitcnt lgkmcnt(1)
	v_lshlrev_b32_e32 v20, 16, v10
	v_and_b32_e32 v21, 0xffff0000, v10
	v_pk_mul_f32 v[12:13], v[12:13], v[20:21]
	v_lshlrev_b32_e32 v10, 16, v11
	v_cvt_pk_bf16_f32 v38, v12, v13
	v_lshlrev_b32_e32 v12, 16, v34
	v_and_b32_e32 v13, 0xffff0000, v34
	v_and_b32_e32 v11, 0xffff0000, v11
	v_pk_mul_f32 v[10:11], v[12:13], v[10:11]
	s_waitcnt lgkmcnt(0)
	v_lshlrev_b32_e32 v12, 16, v14
	v_cvt_pk_bf16_f32 v40, v10, v11
	v_lshlrev_b32_e32 v10, 16, v33
	v_and_b32_e32 v11, 0xffff0000, v33
	v_and_b32_e32 v13, 0xffff0000, v14
	v_pk_mul_f32 v[10:11], v[10:11], v[12:13]
	v_lshlrev_b32_e32 v12, 16, v15
	v_cvt_pk_bf16_f32 v37, v10, v11
	v_lshlrev_b32_e32 v10, 16, v32
	v_and_b32_e32 v11, 0xffff0000, v32
	v_and_b32_e32 v13, 0xffff0000, v15
	v_pk_mul_f32 v[10:11], v[10:11], v[12:13]
	s_nop 0
	v_cvt_pk_bf16_f32 v39, v10, v11
	ds_read_b64 v[10:11], v113 offset:144
	ds_read_b64 v[14:15], v113 offset:16784
	v_lshlrev_b32_e32 v12, 16, v80
	v_and_b32_e32 v13, 0xffff0000, v80
	s_waitcnt lgkmcnt(1)
	v_lshlrev_b32_e32 v20, 16, v10
	v_and_b32_e32 v21, 0xffff0000, v10
	v_pk_mul_f32 v[12:13], v[12:13], v[20:21]
	v_lshlrev_b32_e32 v10, 16, v11
	v_cvt_pk_bf16_f32 v34, v12, v13
	v_lshlrev_b32_e32 v12, 16, v36
	v_and_b32_e32 v13, 0xffff0000, v36
	v_and_b32_e32 v11, 0xffff0000, v11
	v_pk_mul_f32 v[10:11], v[12:13], v[10:11]
	s_waitcnt lgkmcnt(0)
	v_lshlrev_b32_e32 v12, 16, v14
	v_cvt_pk_bf16_f32 v36, v10, v11
	v_lshlrev_b32_e32 v10, 16, v55
	v_and_b32_e32 v11, 0xffff0000, v55
	v_and_b32_e32 v13, 0xffff0000, v14
	v_pk_mul_f32 v[10:11], v[10:11], v[12:13]
	v_lshlrev_b32_e32 v12, 16, v15
	v_cvt_pk_bf16_f32 v32, v10, v11
	v_lshlrev_b32_e32 v10, 16, v53
	v_and_b32_e32 v11, 0xffff0000, v53
	v_and_b32_e32 v13, 0xffff0000, v15
	v_pk_mul_f32 v[10:11], v[10:11], v[12:13]
	s_nop 0
	v_cvt_pk_bf16_f32 v35, v10, v11
	ds_read_b64 v[10:11], v113 offset:160
	ds_read_b64 v[14:15], v113 offset:16800
	v_lshlrev_b32_e32 v12, 16, v83
	v_and_b32_e32 v13, 0xffff0000, v83
	s_waitcnt lgkmcnt(1)
	v_lshlrev_b32_e32 v20, 16, v10
	v_and_b32_e32 v21, 0xffff0000, v10
	v_pk_mul_f32 v[12:13], v[12:13], v[20:21]
	v_lshlrev_b32_e32 v10, 16, v11
	v_cvt_pk_bf16_f32 v24, v12, v13
	v_lshlrev_b32_e32 v12, 16, v82
	v_and_b32_e32 v13, 0xffff0000, v82
	v_and_b32_e32 v11, 0xffff0000, v11
	v_pk_mul_f32 v[10:11], v[12:13], v[10:11]
	s_waitcnt lgkmcnt(0)
	v_lshlrev_b32_e32 v12, 16, v14
	v_cvt_pk_bf16_f32 v26, v10, v11
	v_lshlrev_b32_e32 v10, 16, v81
	v_and_b32_e32 v11, 0xffff0000, v81
	v_and_b32_e32 v13, 0xffff0000, v14
	v_pk_mul_f32 v[10:11], v[10:11], v[12:13]
	v_lshlrev_b32_e32 v12, 16, v15
	v_cvt_pk_bf16_f32 v23, v10, v11
	v_lshlrev_b32_e32 v10, 16, v59
	v_and_b32_e32 v11, 0xffff0000, v59
	v_and_b32_e32 v13, 0xffff0000, v15
	v_pk_mul_f32 v[10:11], v[10:11], v[12:13]
	s_nop 0
	v_cvt_pk_bf16_f32 v25, v10, v11
	ds_read_b64 v[10:11], v113 offset:176
	ds_read_b64 v[14:15], v113 offset:16816
	v_lshlrev_b32_e32 v12, 16, v91
	v_and_b32_e32 v13, 0xffff0000, v91
	s_waitcnt lgkmcnt(1)
; DI unsigned pack2(float a, float b) { f32x2_t v = {a, b}; bf16x2_t r = __builtin_convertvector(v, bf16x2_t); return __builtin_bit_cast(unsigned, r); }
; DI float bflo(unsigned u) { return __uint_as_float(u << 16); }
; DI float bfhi(unsigned u) { return __uint_as_float(u & 0xffff0000u); }
; DI int otid() { int t = threadIdx.x; asm volatile("" : "+v"(t)); return t; }
; template <bool LAST>
; DI void phase_gate(const Params& P, int layer, unsigned char* smem, int L, int G) {
;     ...
;     {
;       const int tid1 = otid();
;       const int lane1 = tid1 & 63, w1 = tid1 >> 6, r1 = lane1 & 31, h1 = lane1 >> 5, wm1 = w1 >> 2, wn1 = w1 & 3;
; #pragma unroll
;       for (int i = 0; i < 4; ++i)
; #pragma unroll
;         for (int q4 = 0; q4 < 4; ++q4) {
; #pragma unroll
;           for (int j = 0; j < 2; ++j) {
;             const uint2 pv = *(const uint2*)(stg + (wn1 * 64 + j * 32 + r1) * STG + wm1 * 128 + i * 32 + 8 * q4 + 4 * h1);
;             const unsigned g0 = gq[i][j][2 * q4], g1 = gq[i][j][2 * q4 + 1];
;             gq[i][j][2 * q4] = pack2(bflo(g0) * bflo(pv.x), bfhi(g0) * bfhi(pv.x));
;             gq[i][j][2 * q4 + 1] = pack2(bflo(g1) * bflo(pv.y), bfhi(g1) * bfhi(pv.y));
;           }
;           __builtin_amdgcn_sched_barrier(0);
;         }
;     }
;     __syncthreads();
	v_lshlrev_b32_e32 v20, 16, v10
	v_and_b32_e32 v21, 0xffff0000, v10
	v_pk_mul_f32 v[12:13], v[12:13], v[20:21]
	v_lshlrev_b32_e32 v10, 16, v11
	v_cvt_pk_bf16_f32 v20, v12, v13
	v_lshlrev_b32_e32 v12, 16, v86
	v_and_b32_e32 v13, 0xffff0000, v86
	v_and_b32_e32 v11, 0xffff0000, v11
	v_pk_mul_f32 v[10:11], v[12:13], v[10:11]
	s_waitcnt lgkmcnt(0)
	v_lshlrev_b32_e32 v12, 16, v14
	v_cvt_pk_bf16_f32 v22, v10, v11
	v_lshlrev_b32_e32 v10, 16, v85
	v_and_b32_e32 v11, 0xffff0000, v85
	v_and_b32_e32 v13, 0xffff0000, v14
	v_pk_mul_f32 v[10:11], v[10:11], v[12:13]
	v_lshlrev_b32_e32 v12, 16, v15
	v_cvt_pk_bf16_f32 v18, v10, v11
	v_lshlrev_b32_e32 v10, 16, v84
	v_and_b32_e32 v11, 0xffff0000, v84
	v_and_b32_e32 v13, 0xffff0000, v15
	v_pk_mul_f32 v[10:11], v[10:11], v[12:13]
	s_nop 0
	v_cvt_pk_bf16_f32 v21, v10, v11
	ds_read_b64 v[10:11], v113 offset:192
	ds_read_b64 v[64:65], v113 offset:16832
	v_lshlrev_b32_e32 v12, 16, v17
	v_and_b32_e32 v13, 0xffff0000, v17
	s_waitcnt lgkmcnt(1)
	v_lshlrev_b32_e32 v14, 16, v10
	v_and_b32_e32 v15, 0xffff0000, v10
	v_pk_mul_f32 v[12:13], v[12:13], v[14:15]
	v_lshlrev_b32_e32 v10, 16, v11
	v_cvt_pk_bf16_f32 v15, v12, v13
	v_lshlrev_b32_e32 v12, 16, v16
	v_and_b32_e32 v13, 0xffff0000, v16
	v_and_b32_e32 v11, 0xffff0000, v11
	v_pk_mul_f32 v[10:11], v[12:13], v[10:11]
	s_waitcnt lgkmcnt(0)
	v_lshlrev_b32_e32 v12, 16, v64
	v_cvt_pk_bf16_f32 v17, v10, v11
	v_lshlrev_b32_e32 v10, 16, v3
	v_and_b32_e32 v11, 0xffff0000, v3
	v_and_b32_e32 v13, 0xffff0000, v64
	v_pk_mul_f32 v[10:11], v[10:11], v[12:13]
	v_lshlrev_b32_e32 v12, 16, v65
	v_cvt_pk_bf16_f32 v14, v10, v11
	v_lshlrev_b32_e32 v10, 16, v2
	v_and_b32_e32 v11, 0xffff0000, v2
	v_and_b32_e32 v13, 0xffff0000, v65
	v_pk_mul_f32 v[2:3], v[10:11], v[12:13]
	s_nop 0
	v_cvt_pk_bf16_f32 v16, v2, v3
	ds_read_b64 v[2:3], v113 offset:208
	ds_read_b64 v[64:65], v113 offset:16848
	v_lshlrev_b32_e32 v10, 16, v7
	v_and_b32_e32 v11, 0xffff0000, v7
	s_waitcnt lgkmcnt(1)
	v_lshlrev_b32_e32 v12, 16, v2
	v_and_b32_e32 v13, 0xffff0000, v2
	v_pk_mul_f32 v[10:11], v[10:11], v[12:13]
	v_lshlrev_b32_e32 v12, 16, v6
	v_lshlrev_b32_e32 v2, 16, v3
	v_and_b32_e32 v13, 0xffff0000, v6
	v_and_b32_e32 v3, 0xffff0000, v3
	v_pk_mul_f32 v[2:3], v[12:13], v[2:3]
	s_waitcnt lgkmcnt(0)
	v_lshlrev_b32_e32 v6, 16, v64
	v_cvt_pk_bf16_f32 v13, v2, v3
	v_lshlrev_b32_e32 v2, 16, v5
	v_and_b32_e32 v3, 0xffff0000, v5
	v_and_b32_e32 v7, 0xffff0000, v64
	v_pk_mul_f32 v[2:3], v[2:3], v[6:7]
	v_cvt_pk_bf16_f32 v11, v10, v11
	v_cvt_pk_bf16_f32 v10, v2, v3
	v_lshlrev_b32_e32 v2, 16, v4
	v_lshlrev_b32_e32 v6, 16, v65
	v_and_b32_e32 v3, 0xffff0000, v4
	v_and_b32_e32 v7, 0xffff0000, v65
	v_pk_mul_f32 v[2:3], v[2:3], v[6:7]
	s_nop 0
	v_cvt_pk_bf16_f32 v12, v2, v3
	ds_read_b64 v[2:3], v113 offset:224
	ds_read_b64 v[64:65], v113 offset:16864
	v_lshlrev_b32_e32 v4, 16, v27
	v_and_b32_e32 v5, 0xffff0000, v27
	s_waitcnt lgkmcnt(1)
	v_lshlrev_b32_e32 v6, 16, v2
	v_and_b32_e32 v7, 0xffff0000, v2
	v_pk_mul_f32 v[4:5], v[4:5], v[6:7]
	v_lshlrev_b32_e32 v2, 16, v3
	v_cvt_pk_bf16_f32 v7, v4, v5
	v_lshlrev_b32_e32 v4, 16, v9
	v_and_b32_e32 v5, 0xffff0000, v9
	v_and_b32_e32 v3, 0xffff0000, v3
	v_pk_mul_f32 v[2:3], v[4:5], v[2:3]
	s_waitcnt lgkmcnt(0)
	v_lshlrev_b32_e32 v4, 16, v64
	v_cvt_pk_bf16_f32 v9, v2, v3
	v_lshlrev_b32_e32 v2, 16, v19
	v_and_b32_e32 v3, 0xffff0000, v19
	v_and_b32_e32 v5, 0xffff0000, v64
	v_pk_mul_f32 v[2:3], v[2:3], v[4:5]
	v_lshlrev_b32_e32 v4, 16, v65
	v_cvt_pk_bf16_f32 v6, v2, v3
	v_lshlrev_b32_e32 v2, 16, v8
	v_and_b32_e32 v3, 0xffff0000, v8
	v_and_b32_e32 v5, 0xffff0000, v65
	v_pk_mul_f32 v[2:3], v[2:3], v[4:5]
	s_nop 0
	v_cvt_pk_bf16_f32 v8, v2, v3
	ds_read_b64 v[2:3], v113 offset:240
	ds_read_b64 v[64:65], v113 offset:16880
	v_lshlrev_b32_e32 v4, 16, v112
	v_and_b32_e32 v5, 0xffff0000, v112
	s_waitcnt lgkmcnt(1)
	v_lshlrev_b32_e32 v66, 16, v2
	v_and_b32_e32 v67, 0xffff0000, v2
	v_pk_mul_f32 v[4:5], v[4:5], v[66:67]
	v_lshlrev_b32_e32 v66, 16, v30
	v_lshlrev_b32_e32 v2, 16, v3
	v_and_b32_e32 v67, 0xffff0000, v30
	v_and_b32_e32 v3, 0xffff0000, v3
	v_pk_mul_f32 v[2:3], v[66:67], v[2:3]
	v_cvt_pk_bf16_f32 v4, v4, v5
	v_cvt_pk_bf16_f32 v5, v2, v3
	v_lshlrev_b32_e32 v2, 16, v29
	s_waitcnt lgkmcnt(0)
	v_lshlrev_b32_e32 v66, 16, v64
	v_and_b32_e32 v3, 0xffff0000, v29
	v_and_b32_e32 v67, 0xffff0000, v64
	v_pk_mul_f32 v[2:3], v[2:3], v[66:67]
	v_lshlrev_b32_e32 v66, 16, v28
	v_lshlrev_b32_e32 v64, 16, v65
	v_and_b32_e32 v67, 0xffff0000, v28
	v_and_b32_e32 v65, 0xffff0000, v65
	v_pk_mul_f32 v[28:29], v[66:67], v[64:65]
	v_cvt_pk_bf16_f32 v2, v2, v3
	v_cvt_pk_bf16_f32 v3, v28, v29
	v_mov_b32_e32 v19, v192
	s_barrier
; DI int otid() { int t = threadIdx.x; asm volatile("" : "+v"(t)); return t; }
; template <bool NT>
; DI void stage_load_tile(bf16_t* stg, const bf16_t* tilebase) {
;   const int tid = otid();
;   const int r0 = tid >> 5, c = tid & 31;
;   const unsigned o0 = (unsigned)(r0 * 1024 + c * 8);
;   __builtin_amdgcn_sched_barrier(0);
; #pragma unroll
;   for (int hf = 0; hf < 2; ++hf) {
; #pragma unroll
;     for (int it = 8 * hf; it < 8 * hf + 8; ++it) {
;       const u32x4* gp = (const u32x4*)(tilebase + (o0 + (unsigned)(it * 16 * 1024)));
;       stage_write16(stg, r0 + 16 * it, c, NT ? __builtin_nontemporal_load(gp) : *gp);
;     }
;     __builtin_amdgcn_sched_barrier(0);
;   }
; }
; template <bool LAST>
; DI void phase_gate(const Params& P, int layer, unsigned char* smem, int L, int G) {
;     ...
;     stage_load_tile<false>(stg, Sb + (size_t)mt * 256 * 1024 + nt * 256);
	s_add_u32 s20, s76, s18
	v_ashrrev_i32_e32 v27, 5, v19
	v_and_b32_e32 v19, 31, v19
	s_addc_u32 s21, s77, s19
	v_lshlrev_b32_e32 v30, 3, v19
	v_lshl_add_u64 v[28:29], s[20:21], 0, v[0:1]
	v_lshl_or_b32 v160, v27, 10, v30
	v_add_u32_e32 v66, 0x4000, v160
	v_mov_b32_e32 v67, v161
	v_add_u32_e32 v72, 0x8000, v160
	v_mov_b32_e32 v73, v161
	v_add_u32_e32 v74, 0xc000, v160
	v_mov_b32_e32 v75, v161
	v_add_u32_e32 v80, 0x10000, v160
	v_mov_b32_e32 v81, v161
	v_add_u32_e32 v82, 0x14000, v160
	v_mov_b32_e32 v83, v161
	v_lshl_add_u64 v[64:65], v[160:161], 1, v[28:29]
	v_lshl_add_u64 v[68:69], v[66:67], 1, v[28:29]
	v_lshl_add_u64 v[72:73], v[72:73], 1, v[28:29]
	v_lshl_add_u64 v[76:77], v[74:75], 1, v[28:29]
	v_lshl_add_u64 v[80:81], v[80:81], 1, v[28:29]
	v_lshl_add_u64 v[84:85], v[82:83], 1, v[28:29]
	global_load_dwordx4 v[64:67], v[64:65], off
	s_nop 0
	global_load_dwordx4 v[68:71], v[68:69], off
	s_nop 0
	global_load_dwordx4 v[72:75], v[72:73], off
	s_nop 0
	global_load_dwordx4 v[76:79], v[76:77], off
	s_nop 0
	global_load_dwordx4 v[80:83], v[80:81], off
	s_nop 0
	global_load_dwordx4 v[100:103], v[84:85], off
	v_add_u32_e32 v84, 0x18000, v160
	v_mov_b32_e32 v85, v161
	v_add_u32_e32 v104, 0x1c000, v160
	v_mov_b32_e32 v105, v161
	v_lshl_add_u64 v[84:85], v[84:85], 1, v[28:29]
	v_lshl_add_u64 v[108:109], v[104:105], 1, v[28:29]
	global_load_dwordx4 v[104:107], v[84:85], off
	s_nop 0
	global_load_dwordx4 v[108:111], v[108:109], off
	v_add_u32_e32 v218, 0x20000, v160
	v_mov_b32_e32 v219, v161
	v_add_u32_e32 v220, 0x24000, v160
	v_mov_b32_e32 v221, v161
	v_add_u32_e32 v226, 0x28000, v160
	v_mov_b32_e32 v227, v161
	v_add_u32_e32 v228, 0x2c000, v160
	v_mov_b32_e32 v229, v161
	v_add_u32_e32 v234, 0x30000, v160
	v_mov_b32_e32 v235, v161
	v_add_u32_e32 v236, 0x34000, v160
	v_mov_b32_e32 v237, v161
	v_lshl_add_u64 v[218:219], v[218:219], 1, v[28:29]
	v_lshl_add_u64 v[222:223], v[220:221], 1, v[28:29]
	v_lshl_add_u64 v[226:227], v[226:227], 1, v[28:29]
	v_lshl_add_u64 v[230:231], v[228:229], 1, v[28:29]
	v_lshl_add_u64 v[234:235], v[234:235], 1, v[28:29]
	v_lshl_add_u64 v[252:253], v[236:237], 1, v[28:29]
	global_load_dwordx4 v[218:221], v[218:219], off
	s_nop 0
	global_load_dwordx4 v[222:225], v[222:223], off
	s_nop 0
	global_load_dwordx4 v[226:229], v[226:227], off
	s_nop 0
	global_load_dwordx4 v[230:233], v[230:231], off
	s_nop 0
	global_load_dwordx4 v[234:237], v[234:235], off
	s_nop 0
	global_load_dwordx4 v[238:241], v[252:253], off
	v_add_u32_e32 v252, 0x38000, v160
	v_mov_b32_e32 v253, v161
	v_lshl_add_u64 v[252:253], v[252:253], 1, v[28:29]
	v_add_u32_e32 v160, 0x3c000, v160
	v_lshl_add_u64 v[190:191], v[160:161], 1, v[28:29]
	global_load_dwordx4 v[242:245], v[252:253], off
	global_load_dwordx4 v[248:251], v[190:191], off
	v_mul_lo_u32 v27, v27, s34
	v_lshl_add_u32 v19, v19, 4, v27
	v_add_u32_e32 v27, 0x2080, v19
	v_add_u32_e32 v30, 0x4100, v19
	v_add_u32_e32 v33, 0x6180, v19
	v_add_u32_e32 v53, 0x8200, v19
	v_add_u32_e32 v55, 0xa280, v19
	v_add_u32_e32 v59, 0xc300, v19
	v_add_u32_e32 v84, 0xe380, v19
	s_waitcnt vmcnt(15)
	ds_write2_b64 v19, v[64:65], v[66:67] offset1:1
	s_waitcnt vmcnt(14)
	ds_write2_b64 v27, v[68:69], v[70:71] offset1:1
	s_waitcnt vmcnt(13)
	ds_write2_b64 v30, v[72:73], v[74:75] offset1:1
	s_waitcnt vmcnt(12)
	ds_write2_b64 v33, v[76:77], v[78:79] offset1:1
	s_waitcnt vmcnt(11)
	ds_write2_b64 v53, v[80:81], v[82:83] offset1:1
	s_waitcnt vmcnt(10)
	ds_write2_b64 v55, v[100:101], v[102:103] offset1:1
	s_waitcnt vmcnt(9)
	ds_write2_b64 v59, v[104:105], v[106:107] offset1:1
	s_waitcnt vmcnt(8)
	ds_write2_b64 v84, v[108:109], v[110:111] offset1:1
	v_add_u32_e32 v27, 0x10400, v19
	v_add_u32_e32 v28, 0x12480, v19
	v_add_u32_e32 v29, 0x14500, v19
	v_add_u32_e32 v30, 0x16580, v19
	v_add_u32_e32 v33, 0x18600, v19
	v_add_u32_e32 v53, 0x1a680, v19
	v_add_u32_e32 v55, 0x1c700, v19
	v_add_u32_e32 v19, 0x1e780, v19
	s_waitcnt vmcnt(7)
	ds_write2_b64 v27, v[218:219], v[220:221] offset1:1
	s_waitcnt vmcnt(6)
	ds_write2_b64 v28, v[222:223], v[224:225] offset1:1
	s_waitcnt vmcnt(5)
	ds_write2_b64 v29, v[226:227], v[228:229] offset1:1
	s_waitcnt vmcnt(4)
	ds_write2_b64 v30, v[230:231], v[232:233] offset1:1
	s_waitcnt vmcnt(3)
	ds_write2_b64 v33, v[234:235], v[236:237] offset1:1
	s_waitcnt vmcnt(2)
	ds_write2_b64 v53, v[238:239], v[240:241] offset1:1
	s_waitcnt vmcnt(1)
	ds_write2_b64 v55, v[242:243], v[244:245] offset1:1
	s_waitcnt vmcnt(0)
	ds_write2_b64 v19, v[248:249], v[250:251] offset1:1
	v_mov_b32_e32 v19, v192
	s_waitcnt lgkmcnt(0)
	s_barrier
; DI unsigned pack2(float a, float b) { f32x2_t v = {a, b}; bf16x2_t r = __builtin_convertvector(v, bf16x2_t); return __builtin_bit_cast(unsigned, r); }
; DI float bflo(unsigned u) { return __uint_as_float(u << 16); }
; DI float bfhi(unsigned u) { return __uint_as_float(u & 0xffff0000u); }
; DI int otid() { int t = threadIdx.x; asm volatile("" : "+v"(t)); return t; }
; template <bool LAST>
; DI void phase_gate(const Params& P, int layer, unsigned char* smem, int L, int G) {
;     ...
;     const int tid2 = otid();
;     const int lane2 = tid2 & 63, w2 = tid2 >> 6, r2 = lane2 & 31, h2 = lane2 >> 5, wm2 = w2 >> 2, wn2 = w2 & 3;
; #pragma unroll
;     for (int i = 0; i < 4; ++i)
; #pragma unroll
;       for (int q4 = 0; q4 < 4; ++q4) {
;         const int fl = wm2 * 128 + i * 32 + 8 * q4 + 4 * h2;
;         const int f0 = nt * 256 + fl;
;         const f32x4 gv = *(const f32x4*)(vecL + 512 + fl), bv = *(const f32x4*)(vecL + 768 + fl);
;         const float ga[4] = {gv.x, gv.y, gv.z, gv.w}, ba[4] = {bv.x, bv.y, bv.z, bv.w};
; #pragma unroll
;         for (int j = 0; j < 2; ++j) {
;           const int lrow = wn2 * 64 + j * 32 + r2;
;           const float mu = rowA[lrow], rstd = rowB[lrow];
;           uint2* sp = (uint2*)(stg + lrow * STG + fl);
;           const uint2 sv = *sp;
;           const float sa[4] = {bflo(sv.x), bfhi(sv.x), bflo(sv.y), bfhi(sv.y)};
;           float y[4];
;           const float gg[4] = {bflo(gq[i][j][2 * q4]), bfhi(gq[i][j][2 * q4]), bflo(gq[i][j][2 * q4 + 1]), bfhi(gq[i][j][2 * q4 + 1])};
; #pragma unroll
;           for (int e = 0; e < 4; ++e) y[e] = (sa[e] - mu) * rstd * ga[e] + ba[e] + gg[e];
;           if (LAST) { f32x4 o = {y[0], y[1], y[2], y[3]}; *(f32x4*)(P.out + (size_t)(mt * 256 + lrow) * 1024 + f0) = o; }
;           else { uint2 pk; pk.x = pack2(y[0], y[1]); pk.y = pack2(y[2], y[3]); *sp = pk; }
;         }
;         __builtin_amdgcn_sched_barrier(0);
;       }
	v_lshlrev_b32_e32 v82, 16, v31
	v_lshrrev_b32_e32 v28, 3, v19
	v_ashrrev_i32_e32 v27, 1, v19
	v_and_b32_e32 v28, 4, v28
	v_and_or_b32 v30, v27, s35, v28
	v_and_b32_e32 v19, 0xdf, v19
	v_lshlrev_b32_e32 v27, 2, v30
	v_lshlrev_b32_e32 v33, 2, v19
	v_mul_u32_u24_e32 v19, 0x208, v19
	v_add_u32_e32 v28, 0x25000, v27
	v_lshl_add_u32 v19, v30, 1, v19
	v_add_u32_e32 v29, 0x25400, v27
	ds_read_b128 v[64:67], v28
	ds_read_b128 v[68:71], v29
	ds_read_b64 v[72:73], v19
	v_or_b32_e32 v29, 0x24000, v33
	v_or_b32_e32 v30, 0x24400, v33
	ds_read_b32 v74, v29
	ds_read_b32 v76, v30
	ds_read_b64 v[78:79], v19 offset:16640
	v_and_b32_e32 v83, 0xffff0000, v31
	s_waitcnt lgkmcnt(3)
	v_lshlrev_b32_e32 v80, 16, v72
	v_and_b32_e32 v81, 0xffff0000, v72
	v_lshlrev_b32_e32 v72, 16, v73
	v_and_b32_e32 v73, 0xffff0000, v73
	s_waitcnt lgkmcnt(2)
	v_pk_add_f32 v[80:81], v[80:81], v[74:75] op_sel_hi:[1,0] neg_lo:[0,1] neg_hi:[0,1]
	v_pk_add_f32 v[72:73], v[72:73], v[74:75] op_sel_hi:[1,0] neg_lo:[0,1] neg_hi:[0,1]
	s_waitcnt lgkmcnt(1)
	v_pk_mul_f32 v[80:81], v[76:77], v[80:81] op_sel_hi:[0,1]
	v_pk_mul_f32 v[72:73], v[76:77], v[72:73] op_sel_hi:[0,1]
	v_lshlrev_b32_e32 v84, 16, v98
	v_and_b32_e32 v85, 0xffff0000, v98
	v_pk_fma_f32 v[80:81], v[64:65], v[80:81], v[68:69]
	v_pk_fma_f32 v[72:73], v[66:67], v[72:73], v[70:71]
	v_pk_add_f32 v[80:81], v[80:81], v[82:83]
	v_pk_add_f32 v[72:73], v[72:73], v[84:85]
	v_cvt_pk_bf16_f32 v74, v80, v81
	v_cvt_pk_bf16_f32 v75, v72, v73
	ds_write_b64 v19, v[74:75]
	v_or_b32_e32 v31, 0x24080, v33
	v_or_b32_e32 v33, 0x24480, v33
	ds_read_b32 v72, v31
	ds_read_b32 v74, v33
	s_waitcnt lgkmcnt(3)
	v_lshlrev_b32_e32 v76, 16, v78
	v_and_b32_e32 v77, 0xffff0000, v78
	v_lshlrev_b32_e32 v78, 16, v79
	s_waitcnt lgkmcnt(1)
	v_pk_add_f32 v[76:77], v[76:77], v[72:73] op_sel_hi:[1,0] neg_lo:[0,1] neg_hi:[0,1]
	v_and_b32_e32 v79, 0xffff0000, v79
	s_waitcnt lgkmcnt(0)
	v_pk_mul_f32 v[76:77], v[74:75], v[76:77] op_sel_hi:[0,1]
	v_pk_fma_f32 v[64:65], v[64:65], v[76:77], v[68:69]
	v_pk_add_f32 v[68:69], v[78:79], v[72:73] op_sel_hi:[1,0] neg_lo:[0,1] neg_hi:[0,1]
	v_lshlrev_b32_e32 v80, 16, v97
	v_pk_mul_f32 v[68:69], v[74:75], v[68:69] op_sel_hi:[0,1]
	v_and_b32_e32 v81, 0xffff0000, v97
	v_lshlrev_b32_e32 v82, 16, v96
	v_and_b32_e32 v83, 0xffff0000, v96
	v_pk_fma_f32 v[66:67], v[66:67], v[68:69], v[70:71]
	v_pk_add_f32 v[64:65], v[64:65], v[80:81]
	v_pk_add_f32 v[66:67], v[66:67], v[82:83]
	v_cvt_pk_bf16_f32 v64, v64, v65
	v_cvt_pk_bf16_f32 v65, v66, v67
	ds_write_b64 v19, v[64:65] offset:16640
	v_add_u32_e32 v53, 0x25020, v27
	v_add_u32_e32 v55, 0x25420, v27
	ds_read_b64 v[72:73], v19 offset:16
	ds_read_b128 v[64:67], v53
	ds_read_b128 v[68:71], v55
	ds_read_b32 v74, v29
	ds_read_b32 v76, v30
	ds_read_b64 v[78:79], v19 offset:16656
	s_waitcnt lgkmcnt(5)
	v_lshlrev_b32_e32 v80, 16, v72
	v_and_b32_e32 v81, 0xffff0000, v72
	v_lshlrev_b32_e32 v72, 16, v73
	v_and_b32_e32 v73, 0xffff0000, v73
	s_waitcnt lgkmcnt(2)
	v_pk_add_f32 v[80:81], v[80:81], v[74:75] op_sel_hi:[1,0] neg_lo:[0,1] neg_hi:[0,1]
	v_pk_add_f32 v[72:73], v[72:73], v[74:75] op_sel_hi:[1,0] neg_lo:[0,1] neg_hi:[0,1]
	s_waitcnt lgkmcnt(1)
	v_pk_mul_f32 v[80:81], v[76:77], v[80:81] op_sel_hi:[0,1]
	v_pk_mul_f32 v[72:73], v[76:77], v[72:73] op_sel_hi:[0,1]
	v_lshlrev_b32_e32 v82, 16, v93
	v_and_b32_e32 v83, 0xffff0000, v93
	v_lshlrev_b32_e32 v84, 16, v95
	v_and_b32_e32 v85, 0xffff0000, v95
	v_pk_fma_f32 v[80:81], v[64:65], v[80:81], v[68:69]
	v_pk_fma_f32 v[72:73], v[66:67], v[72:73], v[70:71]
	v_pk_add_f32 v[80:81], v[80:81], v[82:83]
	v_pk_add_f32 v[72:73], v[72:73], v[84:85]
	v_cvt_pk_bf16_f32 v74, v80, v81
	v_cvt_pk_bf16_f32 v75, v72, v73
	ds_write_b64 v19, v[74:75] offset:16
	ds_read_b32 v72, v31
	ds_read_b32 v74, v33
	s_waitcnt lgkmcnt(3)
	v_lshlrev_b32_e32 v76, 16, v78
	v_and_b32_e32 v77, 0xffff0000, v78
	v_lshlrev_b32_e32 v78, 16, v79
	s_waitcnt lgkmcnt(1)
	v_pk_add_f32 v[76:77], v[76:77], v[72:73] op_sel_hi:[1,0] neg_lo:[0,1] neg_hi:[0,1]
	v_and_b32_e32 v79, 0xffff0000, v79
	s_waitcnt lgkmcnt(0)
	v_pk_mul_f32 v[76:77], v[74:75], v[76:77] op_sel_hi:[0,1]
	v_pk_fma_f32 v[64:65], v[64:65], v[76:77], v[68:69]
	v_pk_add_f32 v[68:69], v[78:79], v[72:73] op_sel_hi:[1,0] neg_lo:[0,1] neg_hi:[0,1]
	v_lshlrev_b32_e32 v80, 16, v92
	v_pk_mul_f32 v[68:69], v[74:75], v[68:69] op_sel_hi:[0,1]
	v_and_b32_e32 v81, 0xffff0000, v92
	v_lshlrev_b32_e32 v82, 16, v94
	v_and_b32_e32 v83, 0xffff0000, v94
	v_pk_fma_f32 v[66:67], v[66:67], v[68:69], v[70:71]
	v_pk_add_f32 v[64:65], v[64:65], v[80:81]
	v_pk_add_f32 v[66:67], v[66:67], v[82:83]
	v_cvt_pk_bf16_f32 v64, v64, v65
	v_cvt_pk_bf16_f32 v65, v66, v67
	ds_write_b64 v19, v[64:65] offset:16656
	v_add_u32_e32 v53, 0x25040, v27
	v_add_u32_e32 v55, 0x25440, v27
	ds_read_b64 v[72:73], v19 offset:32
	ds_read_b128 v[64:67], v53
	ds_read_b128 v[68:71], v55
	ds_read_b32 v74, v29
	ds_read_b32 v76, v30
	ds_read_b64 v[78:79], v19 offset:16672
	s_waitcnt lgkmcnt(5)
	v_lshlrev_b32_e32 v80, 16, v72
	v_and_b32_e32 v81, 0xffff0000, v72
	v_lshlrev_b32_e32 v72, 16, v73
	v_and_b32_e32 v73, 0xffff0000, v73
	s_waitcnt lgkmcnt(2)
	v_pk_add_f32 v[80:81], v[80:81], v[74:75] op_sel_hi:[1,0] neg_lo:[0,1] neg_hi:[0,1]
	v_pk_add_f32 v[72:73], v[72:73], v[74:75] op_sel_hi:[1,0] neg_lo:[0,1] neg_hi:[0,1]
	s_waitcnt lgkmcnt(1)
	v_pk_mul_f32 v[80:81], v[76:77], v[80:81] op_sel_hi:[0,1]
	v_pk_mul_f32 v[72:73], v[76:77], v[72:73] op_sel_hi:[0,1]
	v_lshlrev_b32_e32 v82, 16, v88
	v_and_b32_e32 v83, 0xffff0000, v88
	v_lshlrev_b32_e32 v84, 16, v90
	v_and_b32_e32 v85, 0xffff0000, v90
	v_pk_fma_f32 v[80:81], v[64:65], v[80:81], v[68:69]
	v_pk_fma_f32 v[72:73], v[66:67], v[72:73], v[70:71]
	v_pk_add_f32 v[80:81], v[80:81], v[82:83]
	v_pk_add_f32 v[72:73], v[72:73], v[84:85]
	v_cvt_pk_bf16_f32 v74, v80, v81
	v_cvt_pk_bf16_f32 v75, v72, v73
	ds_write_b64 v19, v[74:75] offset:32
	ds_read_b32 v72, v31
	ds_read_b32 v74, v33
	s_waitcnt lgkmcnt(3)
; DI unsigned pack2(float a, float b) { f32x2_t v = {a, b}; bf16x2_t r = __builtin_convertvector(v, bf16x2_t); return __builtin_bit_cast(unsigned, r); }
; DI float bflo(unsigned u) { return __uint_as_float(u << 16); }
; DI float bfhi(unsigned u) { return __uint_as_float(u & 0xffff0000u); }
; template <bool LAST>
; DI void phase_gate(const Params& P, int layer, unsigned char* smem, int L, int G) {
;     ...
; #pragma unroll
;     for (int i = 0; i < 4; ++i)
; #pragma unroll
;       for (int q4 = 0; q4 < 4; ++q4) {
;         const int fl = wm2 * 128 + i * 32 + 8 * q4 + 4 * h2;
;         const int f0 = nt * 256 + fl;
;         const f32x4 gv = *(const f32x4*)(vecL + 512 + fl), bv = *(const f32x4*)(vecL + 768 + fl);
;         const float ga[4] = {gv.x, gv.y, gv.z, gv.w}, ba[4] = {bv.x, bv.y, bv.z, bv.w};
; #pragma unroll
;         for (int j = 0; j < 2; ++j) {
;           const int lrow = wn2 * 64 + j * 32 + r2;
;           const float mu = rowA[lrow], rstd = rowB[lrow];
;           uint2* sp = (uint2*)(stg + lrow * STG + fl);
;           const uint2 sv = *sp;
;           const float sa[4] = {bflo(sv.x), bfhi(sv.x), bflo(sv.y), bfhi(sv.y)};
;           float y[4];
;           const float gg[4] = {bflo(gq[i][j][2 * q4]), bfhi(gq[i][j][2 * q4]), bflo(gq[i][j][2 * q4 + 1]), bfhi(gq[i][j][2 * q4 + 1])};
; #pragma unroll
;           for (int e = 0; e < 4; ++e) y[e] = (sa[e] - mu) * rstd * ga[e] + ba[e] + gg[e];
;           if (LAST) { f32x4 o = {y[0], y[1], y[2], y[3]}; *(f32x4*)(P.out + (size_t)(mt * 256 + lrow) * 1024 + f0) = o; }
;           else { uint2 pk; pk.x = pack2(y[0], y[1]); pk.y = pack2(y[2], y[3]); *sp = pk; }
;         }
;         __builtin_amdgcn_sched_barrier(0);
;       }
	v_lshlrev_b32_e32 v76, 16, v78
	v_and_b32_e32 v77, 0xffff0000, v78
	v_lshlrev_b32_e32 v78, 16, v79
	s_waitcnt lgkmcnt(1)
	v_pk_add_f32 v[76:77], v[76:77], v[72:73] op_sel_hi:[1,0] neg_lo:[0,1] neg_hi:[0,1]
	v_and_b32_e32 v79, 0xffff0000, v79
	s_waitcnt lgkmcnt(0)
	v_pk_mul_f32 v[76:77], v[74:75], v[76:77] op_sel_hi:[0,1]
	v_pk_fma_f32 v[64:65], v[64:65], v[76:77], v[68:69]
	v_pk_add_f32 v[68:69], v[78:79], v[72:73] op_sel_hi:[1,0] neg_lo:[0,1] neg_hi:[0,1]
	v_lshlrev_b32_e32 v80, 16, v87
	v_pk_mul_f32 v[68:69], v[74:75], v[68:69] op_sel_hi:[0,1]
	v_and_b32_e32 v81, 0xffff0000, v87
	v_lshlrev_b32_e32 v82, 16, v89
	v_and_b32_e32 v83, 0xffff0000, v89
	v_pk_fma_f32 v[66:67], v[66:67], v[68:69], v[70:71]
	v_pk_add_f32 v[64:65], v[64:65], v[80:81]
	v_pk_add_f32 v[66:67], v[66:67], v[82:83]
	v_cvt_pk_bf16_f32 v64, v64, v65
	v_cvt_pk_bf16_f32 v65, v66, v67
	ds_write_b64 v19, v[64:65] offset:16672
	v_add_u32_e32 v53, 0x25060, v27
	v_add_u32_e32 v55, 0x25460, v27
	ds_read_b64 v[72:73], v19 offset:48
	ds_read_b128 v[64:67], v53
	ds_read_b128 v[68:71], v55
	ds_read_b32 v74, v29
	ds_read_b32 v76, v30
	ds_read_b64 v[78:79], v19 offset:16688
	s_waitcnt lgkmcnt(5)
	v_lshlrev_b32_e32 v80, 16, v72
	v_and_b32_e32 v81, 0xffff0000, v72
	v_lshlrev_b32_e32 v72, 16, v73
	v_and_b32_e32 v73, 0xffff0000, v73
	s_waitcnt lgkmcnt(2)
	v_pk_add_f32 v[80:81], v[80:81], v[74:75] op_sel_hi:[1,0] neg_lo:[0,1] neg_hi:[0,1]
	v_pk_add_f32 v[72:73], v[72:73], v[74:75] op_sel_hi:[1,0] neg_lo:[0,1] neg_hi:[0,1]
	s_waitcnt lgkmcnt(1)
	v_pk_mul_f32 v[80:81], v[76:77], v[80:81] op_sel_hi:[0,1]
	v_pk_mul_f32 v[72:73], v[76:77], v[72:73] op_sel_hi:[0,1]
	v_lshlrev_b32_e32 v82, 16, v61
	v_and_b32_e32 v83, 0xffff0000, v61
	v_lshlrev_b32_e32 v84, 16, v63
	v_and_b32_e32 v85, 0xffff0000, v63
	v_pk_fma_f32 v[80:81], v[64:65], v[80:81], v[68:69]
	v_pk_fma_f32 v[72:73], v[66:67], v[72:73], v[70:71]
	v_pk_add_f32 v[80:81], v[80:81], v[82:83]
	v_pk_add_f32 v[72:73], v[72:73], v[84:85]
	v_cvt_pk_bf16_f32 v74, v80, v81
	v_cvt_pk_bf16_f32 v75, v72, v73
	ds_write_b64 v19, v[74:75] offset:48
	ds_read_b32 v72, v31
	ds_read_b32 v74, v33
	s_waitcnt lgkmcnt(3)
	v_lshlrev_b32_e32 v76, 16, v78
	v_and_b32_e32 v77, 0xffff0000, v78
	v_lshlrev_b32_e32 v80, 16, v60
	v_and_b32_e32 v81, 0xffff0000, v60
	v_lshlrev_b32_e32 v60, 16, v62
	v_and_b32_e32 v61, 0xffff0000, v62
	s_waitcnt lgkmcnt(1)
	v_pk_add_f32 v[62:63], v[76:77], v[72:73] op_sel_hi:[1,0] neg_lo:[0,1] neg_hi:[0,1]
	v_lshlrev_b32_e32 v78, 16, v79
	v_and_b32_e32 v79, 0xffff0000, v79
	s_waitcnt lgkmcnt(0)
	v_pk_mul_f32 v[62:63], v[74:75], v[62:63] op_sel_hi:[0,1]
	v_pk_fma_f32 v[62:63], v[64:65], v[62:63], v[68:69]
	v_pk_add_f32 v[64:65], v[78:79], v[72:73] op_sel_hi:[1,0] neg_lo:[0,1] neg_hi:[0,1]
	v_pk_add_f32 v[62:63], v[62:63], v[80:81]
	v_pk_mul_f32 v[64:65], v[74:75], v[64:65] op_sel_hi:[0,1]
	v_pk_fma_f32 v[64:65], v[66:67], v[64:65], v[70:71]
	v_cvt_pk_bf16_f32 v62, v62, v63
	v_pk_add_f32 v[60:61], v[64:65], v[60:61]
	s_nop 0
	v_cvt_pk_bf16_f32 v63, v60, v61
	ds_write_b64 v19, v[62:63] offset:16688
	v_add_u32_e32 v53, 0x25080, v27
	v_add_u32_e32 v55, 0x25480, v27
	ds_read_b64 v[68:69], v19 offset:64
	ds_read_b128 v[60:63], v53
	ds_read_b128 v[64:67], v55
	ds_read_b32 v70, v29
	ds_read_b32 v72, v30
	ds_read_b64 v[74:75], v19 offset:16704
	s_waitcnt lgkmcnt(5)
	v_lshlrev_b32_e32 v76, 16, v68
	v_and_b32_e32 v77, 0xffff0000, v68
	v_lshlrev_b32_e32 v68, 16, v69
	v_and_b32_e32 v69, 0xffff0000, v69
	v_lshlrev_b32_e32 v80, 16, v58
	v_and_b32_e32 v81, 0xffff0000, v58
	s_waitcnt lgkmcnt(2)
	v_pk_add_f32 v[58:59], v[76:77], v[70:71] op_sel_hi:[1,0] neg_lo:[0,1] neg_hi:[0,1]
	v_pk_add_f32 v[68:69], v[68:69], v[70:71] op_sel_hi:[1,0] neg_lo:[0,1] neg_hi:[0,1]
	s_waitcnt lgkmcnt(1)
	v_pk_mul_f32 v[58:59], v[72:73], v[58:59] op_sel_hi:[0,1]
	v_pk_mul_f32 v[68:69], v[72:73], v[68:69] op_sel_hi:[0,1]
	v_lshlrev_b32_e32 v78, 16, v56
	v_and_b32_e32 v79, 0xffff0000, v56
	v_pk_fma_f32 v[58:59], v[60:61], v[58:59], v[64:65]
	v_pk_fma_f32 v[68:69], v[62:63], v[68:69], v[66:67]
	v_pk_add_f32 v[58:59], v[58:59], v[78:79]
	v_pk_add_f32 v[68:69], v[68:69], v[80:81]
	v_cvt_pk_bf16_f32 v58, v58, v59
	v_cvt_pk_bf16_f32 v59, v68, v69
	ds_write_b64 v19, v[58:59] offset:64
	ds_read_b32 v56, v31
	ds_read_b32 v58, v33
	s_waitcnt lgkmcnt(3)
	v_lshlrev_b32_e32 v68, 16, v74
	v_and_b32_e32 v69, 0xffff0000, v74
	v_lshlrev_b32_e32 v70, 16, v75
	v_and_b32_e32 v71, 0xffff0000, v75
	v_lshlrev_b32_e32 v72, 16, v54
	v_and_b32_e32 v73, 0xffff0000, v54
	v_lshlrev_b32_e32 v54, 16, v57
	v_and_b32_e32 v55, 0xffff0000, v57
	s_waitcnt lgkmcnt(1)
	v_pk_add_f32 v[68:69], v[68:69], v[56:57] op_sel_hi:[1,0] neg_lo:[0,1] neg_hi:[0,1]
	v_pk_add_f32 v[56:57], v[70:71], v[56:57] op_sel_hi:[1,0] neg_lo:[0,1] neg_hi:[0,1]
	s_waitcnt lgkmcnt(0)
	v_pk_mul_f32 v[68:69], v[58:59], v[68:69] op_sel_hi:[0,1]
	v_pk_mul_f32 v[56:57], v[58:59], v[56:57] op_sel_hi:[0,1]
	v_pk_fma_f32 v[60:61], v[60:61], v[68:69], v[64:65]
	v_pk_fma_f32 v[56:57], v[62:63], v[56:57], v[66:67]
	v_pk_add_f32 v[60:61], v[60:61], v[72:73]
	v_pk_add_f32 v[54:55], v[56:57], v[54:55]
	v_cvt_pk_bf16_f32 v56, v60, v61
	v_cvt_pk_bf16_f32 v57, v54, v55
	ds_write_b64 v19, v[56:57] offset:16704
	v_add_u32_e32 v58, 0x254a0, v27
	v_add_u32_e32 v53, 0x250a0, v27
	ds_read_b64 v[62:63], v19 offset:80
	ds_read_b128 v[54:57], v53
	ds_read_b128 v[58:61], v58
	ds_read_b32 v64, v29
	ds_read_b32 v66, v30
	ds_read_b64 v[68:69], v19 offset:16720
	s_waitcnt lgkmcnt(5)
	v_lshlrev_b32_e32 v70, 16, v62
	v_and_b32_e32 v71, 0xffff0000, v62
	v_lshlrev_b32_e32 v62, 16, v63
	v_and_b32_e32 v63, 0xffff0000, v63
	v_lshlrev_b32_e32 v74, 16, v52
	v_and_b32_e32 v75, 0xffff0000, v52
	s_waitcnt lgkmcnt(2)
; DI unsigned pack2(float a, float b) { f32x2_t v = {a, b}; bf16x2_t r = __builtin_convertvector(v, bf16x2_t); return __builtin_bit_cast(unsigned, r); }
; DI float bflo(unsigned u) { return __uint_as_float(u << 16); }
; DI float bfhi(unsigned u) { return __uint_as_float(u & 0xffff0000u); }
; template <bool LAST>
; DI void phase_gate(const Params& P, int layer, unsigned char* smem, int L, int G) {
;     ...
; #pragma unroll
;     for (int i = 0; i < 4; ++i)
; #pragma unroll
;       for (int q4 = 0; q4 < 4; ++q4) {
;         const int fl = wm2 * 128 + i * 32 + 8 * q4 + 4 * h2;
;         const int f0 = nt * 256 + fl;
;         const f32x4 gv = *(const f32x4*)(vecL + 512 + fl), bv = *(const f32x4*)(vecL + 768 + fl);
;         const float ga[4] = {gv.x, gv.y, gv.z, gv.w}, ba[4] = {bv.x, bv.y, bv.z, bv.w};
; #pragma unroll
;         for (int j = 0; j < 2; ++j) {
;           const int lrow = wn2 * 64 + j * 32 + r2;
;           const float mu = rowA[lrow], rstd = rowB[lrow];
;           uint2* sp = (uint2*)(stg + lrow * STG + fl);
;           const uint2 sv = *sp;
;           const float sa[4] = {bflo(sv.x), bfhi(sv.x), bflo(sv.y), bfhi(sv.y)};
;           float y[4];
;           const float gg[4] = {bflo(gq[i][j][2 * q4]), bfhi(gq[i][j][2 * q4]), bflo(gq[i][j][2 * q4 + 1]), bfhi(gq[i][j][2 * q4 + 1])};
; #pragma unroll
;           for (int e = 0; e < 4; ++e) y[e] = (sa[e] - mu) * rstd * ga[e] + ba[e] + gg[e];
;           if (LAST) { f32x4 o = {y[0], y[1], y[2], y[3]}; *(f32x4*)(P.out + (size_t)(mt * 256 + lrow) * 1024 + f0) = o; }
;           else { uint2 pk; pk.x = pack2(y[0], y[1]); pk.y = pack2(y[2], y[3]); *sp = pk; }
;         }
;         __builtin_amdgcn_sched_barrier(0);
;       }
	v_pk_add_f32 v[52:53], v[70:71], v[64:65] op_sel_hi:[1,0] neg_lo:[0,1] neg_hi:[0,1]
	v_pk_add_f32 v[62:63], v[62:63], v[64:65] op_sel_hi:[1,0] neg_lo:[0,1] neg_hi:[0,1]
	s_waitcnt lgkmcnt(1)
	v_pk_mul_f32 v[52:53], v[66:67], v[52:53] op_sel_hi:[0,1]
	v_pk_mul_f32 v[62:63], v[66:67], v[62:63] op_sel_hi:[0,1]
	v_lshlrev_b32_e32 v72, 16, v50
	v_and_b32_e32 v73, 0xffff0000, v50
	v_pk_fma_f32 v[52:53], v[54:55], v[52:53], v[58:59]
	v_pk_fma_f32 v[62:63], v[56:57], v[62:63], v[60:61]
	v_pk_add_f32 v[52:53], v[52:53], v[72:73]
	v_pk_add_f32 v[62:63], v[62:63], v[74:75]
	v_cvt_pk_bf16_f32 v52, v52, v53
	v_cvt_pk_bf16_f32 v53, v62, v63
	ds_write_b64 v19, v[52:53] offset:80
	ds_read_b32 v50, v31
	ds_read_b32 v52, v33
	s_waitcnt lgkmcnt(3)
	v_lshlrev_b32_e32 v62, 16, v68
	v_and_b32_e32 v63, 0xffff0000, v68
	v_lshlrev_b32_e32 v64, 16, v69
	v_and_b32_e32 v65, 0xffff0000, v69
	v_lshlrev_b32_e32 v68, 16, v51
	v_and_b32_e32 v69, 0xffff0000, v51
	s_waitcnt lgkmcnt(1)
	v_pk_add_f32 v[62:63], v[62:63], v[50:51] op_sel_hi:[1,0] neg_lo:[0,1] neg_hi:[0,1]
	v_pk_add_f32 v[50:51], v[64:65], v[50:51] op_sel_hi:[1,0] neg_lo:[0,1] neg_hi:[0,1]
	s_waitcnt lgkmcnt(0)
	v_pk_mul_f32 v[62:63], v[52:53], v[62:63] op_sel_hi:[0,1]
	v_pk_mul_f32 v[50:51], v[52:53], v[50:51] op_sel_hi:[0,1]
	v_lshlrev_b32_e32 v66, 16, v49
	v_and_b32_e32 v67, 0xffff0000, v49
	v_pk_fma_f32 v[54:55], v[54:55], v[62:63], v[58:59]
	v_pk_fma_f32 v[50:51], v[56:57], v[50:51], v[60:61]
	v_pk_add_f32 v[54:55], v[54:55], v[66:67]
	v_pk_add_f32 v[50:51], v[50:51], v[68:69]
	v_cvt_pk_bf16_f32 v52, v54, v55
	v_cvt_pk_bf16_f32 v53, v50, v51
	ds_write_b64 v19, v[52:53] offset:16720
	v_add_u32_e32 v54, 0x254c0, v27
	v_add_u32_e32 v49, 0x250c0, v27
	ds_read_b64 v[58:59], v19 offset:96
	ds_read_b128 v[50:53], v49
	ds_read_b128 v[54:57], v54
	ds_read_b32 v60, v29
	ds_read_b32 v62, v30
	ds_read_b64 v[64:65], v19 offset:16736
	s_waitcnt lgkmcnt(5)
	v_lshlrev_b32_e32 v66, 16, v58
	v_and_b32_e32 v67, 0xffff0000, v58
	v_lshlrev_b32_e32 v58, 16, v59
	v_and_b32_e32 v59, 0xffff0000, v59
	v_lshlrev_b32_e32 v70, 16, v48
	v_and_b32_e32 v71, 0xffff0000, v48
	s_waitcnt lgkmcnt(2)
	v_pk_add_f32 v[48:49], v[66:67], v[60:61] op_sel_hi:[1,0] neg_lo:[0,1] neg_hi:[0,1]
	v_pk_add_f32 v[58:59], v[58:59], v[60:61] op_sel_hi:[1,0] neg_lo:[0,1] neg_hi:[0,1]
	s_waitcnt lgkmcnt(1)
	v_pk_mul_f32 v[48:49], v[62:63], v[48:49] op_sel_hi:[0,1]
	v_pk_mul_f32 v[58:59], v[62:63], v[58:59] op_sel_hi:[0,1]
	v_lshlrev_b32_e32 v68, 16, v46
	v_and_b32_e32 v69, 0xffff0000, v46
	v_pk_fma_f32 v[48:49], v[50:51], v[48:49], v[54:55]
	v_pk_fma_f32 v[58:59], v[52:53], v[58:59], v[56:57]
	v_pk_add_f32 v[48:49], v[48:49], v[68:69]
	v_pk_add_f32 v[58:59], v[58:59], v[70:71]
	v_cvt_pk_bf16_f32 v48, v48, v49
	v_cvt_pk_bf16_f32 v49, v58, v59
	ds_write_b64 v19, v[48:49] offset:96
	ds_read_b32 v46, v31
	ds_read_b32 v48, v33
	s_waitcnt lgkmcnt(3)
	v_lshlrev_b32_e32 v58, 16, v64
	v_and_b32_e32 v59, 0xffff0000, v64
	v_lshlrev_b32_e32 v60, 16, v65
	v_and_b32_e32 v61, 0xffff0000, v65
	v_lshlrev_b32_e32 v64, 16, v47
	v_and_b32_e32 v65, 0xffff0000, v47
	s_waitcnt lgkmcnt(1)
	v_pk_add_f32 v[58:59], v[58:59], v[46:47] op_sel_hi:[1,0] neg_lo:[0,1] neg_hi:[0,1]
	v_pk_add_f32 v[46:47], v[60:61], v[46:47] op_sel_hi:[1,0] neg_lo:[0,1] neg_hi:[0,1]
	s_waitcnt lgkmcnt(0)
	v_pk_mul_f32 v[58:59], v[48:49], v[58:59] op_sel_hi:[0,1]
	v_pk_mul_f32 v[46:47], v[48:49], v[46:47] op_sel_hi:[0,1]
	v_lshlrev_b32_e32 v62, 16, v45
	v_and_b32_e32 v63, 0xffff0000, v45
	v_pk_fma_f32 v[50:51], v[50:51], v[58:59], v[54:55]
	v_pk_fma_f32 v[46:47], v[52:53], v[46:47], v[56:57]
	v_pk_add_f32 v[50:51], v[50:51], v[62:63]
	v_pk_add_f32 v[46:47], v[46:47], v[64:65]
	v_cvt_pk_bf16_f32 v48, v50, v51
	v_cvt_pk_bf16_f32 v49, v46, v47
	ds_write_b64 v19, v[48:49] offset:16736
	v_add_u32_e32 v50, 0x254e0, v27
	v_add_u32_e32 v45, 0x250e0, v27
	ds_read_b64 v[54:55], v19 offset:112
	ds_read_b128 v[46:49], v45
	ds_read_b128 v[50:53], v50
	ds_read_b32 v56, v29
	ds_read_b32 v58, v30
	ds_read_b64 v[60:61], v19 offset:16752
	s_waitcnt lgkmcnt(5)
	v_lshlrev_b32_e32 v62, 16, v54
	v_and_b32_e32 v63, 0xffff0000, v54
	v_lshlrev_b32_e32 v54, 16, v55
	v_and_b32_e32 v55, 0xffff0000, v55
	v_lshlrev_b32_e32 v66, 16, v44
	v_and_b32_e32 v67, 0xffff0000, v44
	s_waitcnt lgkmcnt(2)
	v_pk_add_f32 v[44:45], v[62:63], v[56:57] op_sel_hi:[1,0] neg_lo:[0,1] neg_hi:[0,1]
	v_pk_add_f32 v[54:55], v[54:55], v[56:57] op_sel_hi:[1,0] neg_lo:[0,1] neg_hi:[0,1]
	s_waitcnt lgkmcnt(1)
	v_pk_mul_f32 v[44:45], v[58:59], v[44:45] op_sel_hi:[0,1]
	v_pk_mul_f32 v[54:55], v[58:59], v[54:55] op_sel_hi:[0,1]
	v_lshlrev_b32_e32 v64, 16, v42
	v_and_b32_e32 v65, 0xffff0000, v42
	v_pk_fma_f32 v[44:45], v[46:47], v[44:45], v[50:51]
	v_pk_fma_f32 v[54:55], v[48:49], v[54:55], v[52:53]
	v_pk_add_f32 v[44:45], v[44:45], v[64:65]
	v_pk_add_f32 v[54:55], v[54:55], v[66:67]
	v_cvt_pk_bf16_f32 v44, v44, v45
	v_cvt_pk_bf16_f32 v45, v54, v55
	ds_write_b64 v19, v[44:45] offset:112
	ds_read_b32 v42, v31
	ds_read_b32 v44, v33
	s_waitcnt lgkmcnt(3)
	v_lshlrev_b32_e32 v54, 16, v60
	v_and_b32_e32 v55, 0xffff0000, v60
	v_lshlrev_b32_e32 v56, 16, v61
	v_and_b32_e32 v57, 0xffff0000, v61
	v_lshlrev_b32_e32 v60, 16, v43
	v_and_b32_e32 v61, 0xffff0000, v43
	s_waitcnt lgkmcnt(1)
	v_pk_add_f32 v[54:55], v[54:55], v[42:43] op_sel_hi:[1,0] neg_lo:[0,1] neg_hi:[0,1]
	v_pk_add_f32 v[42:43], v[56:57], v[42:43] op_sel_hi:[1,0] neg_lo:[0,1] neg_hi:[0,1]
	s_waitcnt lgkmcnt(0)
; DI unsigned pack2(float a, float b) { f32x2_t v = {a, b}; bf16x2_t r = __builtin_convertvector(v, bf16x2_t); return __builtin_bit_cast(unsigned, r); }
; DI float bflo(unsigned u) { return __uint_as_float(u << 16); }
; DI float bfhi(unsigned u) { return __uint_as_float(u & 0xffff0000u); }
; template <bool LAST>
; DI void phase_gate(const Params& P, int layer, unsigned char* smem, int L, int G) {
;     ...
; #pragma unroll
;     for (int i = 0; i < 4; ++i)
; #pragma unroll
;       for (int q4 = 0; q4 < 4; ++q4) {
;         const int fl = wm2 * 128 + i * 32 + 8 * q4 + 4 * h2;
;         const int f0 = nt * 256 + fl;
;         const f32x4 gv = *(const f32x4*)(vecL + 512 + fl), bv = *(const f32x4*)(vecL + 768 + fl);
;         const float ga[4] = {gv.x, gv.y, gv.z, gv.w}, ba[4] = {bv.x, bv.y, bv.z, bv.w};
; #pragma unroll
;         for (int j = 0; j < 2; ++j) {
;           const int lrow = wn2 * 64 + j * 32 + r2;
;           const float mu = rowA[lrow], rstd = rowB[lrow];
;           uint2* sp = (uint2*)(stg + lrow * STG + fl);
;           const uint2 sv = *sp;
;           const float sa[4] = {bflo(sv.x), bfhi(sv.x), bflo(sv.y), bfhi(sv.y)};
;           float y[4];
;           const float gg[4] = {bflo(gq[i][j][2 * q4]), bfhi(gq[i][j][2 * q4]), bflo(gq[i][j][2 * q4 + 1]), bfhi(gq[i][j][2 * q4 + 1])};
; #pragma unroll
;           for (int e = 0; e < 4; ++e) y[e] = (sa[e] - mu) * rstd * ga[e] + ba[e] + gg[e];
;           if (LAST) { f32x4 o = {y[0], y[1], y[2], y[3]}; *(f32x4*)(P.out + (size_t)(mt * 256 + lrow) * 1024 + f0) = o; }
;           else { uint2 pk; pk.x = pack2(y[0], y[1]); pk.y = pack2(y[2], y[3]); *sp = pk; }
;         }
;         __builtin_amdgcn_sched_barrier(0);
;       }
	v_pk_mul_f32 v[54:55], v[44:45], v[54:55] op_sel_hi:[0,1]
	v_pk_mul_f32 v[42:43], v[44:45], v[42:43] op_sel_hi:[0,1]
	v_lshlrev_b32_e32 v58, 16, v41
	v_and_b32_e32 v59, 0xffff0000, v41
	v_pk_fma_f32 v[46:47], v[46:47], v[54:55], v[50:51]
	v_pk_fma_f32 v[42:43], v[48:49], v[42:43], v[52:53]
	v_pk_add_f32 v[46:47], v[46:47], v[58:59]
	v_pk_add_f32 v[42:43], v[42:43], v[60:61]
	v_cvt_pk_bf16_f32 v44, v46, v47
	v_cvt_pk_bf16_f32 v45, v42, v43
	ds_write_b64 v19, v[44:45] offset:16752
	v_add_u32_e32 v46, 0x25500, v27
	v_add_u32_e32 v41, 0x25100, v27
	ds_read_b64 v[50:51], v19 offset:128
	ds_read_b128 v[42:45], v41
	ds_read_b128 v[46:49], v46
	ds_read_b32 v52, v29
	ds_read_b32 v54, v30
	ds_read_b64 v[56:57], v19 offset:16768
	s_waitcnt lgkmcnt(5)
	v_lshlrev_b32_e32 v58, 16, v50
	v_and_b32_e32 v59, 0xffff0000, v50
	v_lshlrev_b32_e32 v50, 16, v51
	v_and_b32_e32 v51, 0xffff0000, v51
	v_lshlrev_b32_e32 v62, 16, v40
	v_and_b32_e32 v63, 0xffff0000, v40
	s_waitcnt lgkmcnt(2)
	v_pk_add_f32 v[40:41], v[58:59], v[52:53] op_sel_hi:[1,0] neg_lo:[0,1] neg_hi:[0,1]
	v_pk_add_f32 v[50:51], v[50:51], v[52:53] op_sel_hi:[1,0] neg_lo:[0,1] neg_hi:[0,1]
	s_waitcnt lgkmcnt(1)
	v_pk_mul_f32 v[40:41], v[54:55], v[40:41] op_sel_hi:[0,1]
	v_pk_mul_f32 v[50:51], v[54:55], v[50:51] op_sel_hi:[0,1]
	v_lshlrev_b32_e32 v60, 16, v38
	v_and_b32_e32 v61, 0xffff0000, v38
	v_pk_fma_f32 v[40:41], v[42:43], v[40:41], v[46:47]
	v_pk_fma_f32 v[50:51], v[44:45], v[50:51], v[48:49]
	v_pk_add_f32 v[40:41], v[40:41], v[60:61]
	v_pk_add_f32 v[50:51], v[50:51], v[62:63]
	v_cvt_pk_bf16_f32 v40, v40, v41
	v_cvt_pk_bf16_f32 v41, v50, v51
	ds_write_b64 v19, v[40:41] offset:128
	ds_read_b32 v38, v31
	ds_read_b32 v40, v33
	s_waitcnt lgkmcnt(3)
	v_lshlrev_b32_e32 v50, 16, v56
	v_and_b32_e32 v51, 0xffff0000, v56
	v_lshlrev_b32_e32 v52, 16, v57
	v_and_b32_e32 v53, 0xffff0000, v57
	v_lshlrev_b32_e32 v56, 16, v39
	v_and_b32_e32 v57, 0xffff0000, v39
	s_waitcnt lgkmcnt(1)
	v_pk_add_f32 v[50:51], v[50:51], v[38:39] op_sel_hi:[1,0] neg_lo:[0,1] neg_hi:[0,1]
	v_pk_add_f32 v[38:39], v[52:53], v[38:39] op_sel_hi:[1,0] neg_lo:[0,1] neg_hi:[0,1]
	s_waitcnt lgkmcnt(0)
	v_pk_mul_f32 v[50:51], v[40:41], v[50:51] op_sel_hi:[0,1]
	v_pk_mul_f32 v[38:39], v[40:41], v[38:39] op_sel_hi:[0,1]
	v_lshlrev_b32_e32 v54, 16, v37
	v_and_b32_e32 v55, 0xffff0000, v37
	v_pk_fma_f32 v[42:43], v[42:43], v[50:51], v[46:47]
	v_pk_fma_f32 v[38:39], v[44:45], v[38:39], v[48:49]
	v_pk_add_f32 v[42:43], v[42:43], v[54:55]
	v_pk_add_f32 v[38:39], v[38:39], v[56:57]
	v_cvt_pk_bf16_f32 v40, v42, v43
	v_cvt_pk_bf16_f32 v41, v38, v39
	ds_write_b64 v19, v[40:41] offset:16768
	v_add_u32_e32 v42, 0x25520, v27
	v_add_u32_e32 v37, 0x25120, v27
	ds_read_b64 v[46:47], v19 offset:144
	ds_read_b128 v[38:41], v37
	ds_read_b128 v[42:45], v42
	ds_read_b32 v48, v29
	ds_read_b32 v50, v30
	ds_read_b64 v[52:53], v19 offset:16784
	s_waitcnt lgkmcnt(5)
	v_lshlrev_b32_e32 v54, 16, v46
	v_and_b32_e32 v55, 0xffff0000, v46
	v_lshlrev_b32_e32 v46, 16, v47
	v_and_b32_e32 v47, 0xffff0000, v47
	v_lshlrev_b32_e32 v58, 16, v36
	v_and_b32_e32 v59, 0xffff0000, v36
	s_waitcnt lgkmcnt(2)
	v_pk_add_f32 v[36:37], v[54:55], v[48:49] op_sel_hi:[1,0] neg_lo:[0,1] neg_hi:[0,1]
	v_pk_add_f32 v[46:47], v[46:47], v[48:49] op_sel_hi:[1,0] neg_lo:[0,1] neg_hi:[0,1]
	s_waitcnt lgkmcnt(1)
	v_pk_mul_f32 v[36:37], v[50:51], v[36:37] op_sel_hi:[0,1]
	v_pk_mul_f32 v[46:47], v[50:51], v[46:47] op_sel_hi:[0,1]
	v_lshlrev_b32_e32 v56, 16, v34
	v_and_b32_e32 v57, 0xffff0000, v34
	v_pk_fma_f32 v[36:37], v[38:39], v[36:37], v[42:43]
	v_pk_fma_f32 v[46:47], v[40:41], v[46:47], v[44:45]
	v_pk_add_f32 v[36:37], v[36:37], v[56:57]
	v_pk_add_f32 v[46:47], v[46:47], v[58:59]
	v_cvt_pk_bf16_f32 v36, v36, v37
	v_cvt_pk_bf16_f32 v37, v46, v47
	ds_write_b64 v19, v[36:37] offset:144
	ds_read_b32 v34, v31
	ds_read_b32 v36, v33
	s_waitcnt lgkmcnt(3)
	v_lshlrev_b32_e32 v46, 16, v52
	v_and_b32_e32 v47, 0xffff0000, v52
	v_lshlrev_b32_e32 v48, 16, v53
	v_and_b32_e32 v49, 0xffff0000, v53
	v_lshlrev_b32_e32 v52, 16, v35
	v_and_b32_e32 v53, 0xffff0000, v35
	s_waitcnt lgkmcnt(1)
	v_pk_add_f32 v[46:47], v[46:47], v[34:35] op_sel_hi:[1,0] neg_lo:[0,1] neg_hi:[0,1]
	v_pk_add_f32 v[34:35], v[48:49], v[34:35] op_sel_hi:[1,0] neg_lo:[0,1] neg_hi:[0,1]
	s_waitcnt lgkmcnt(0)
	v_pk_mul_f32 v[46:47], v[36:37], v[46:47] op_sel_hi:[0,1]
	v_pk_mul_f32 v[34:35], v[36:37], v[34:35] op_sel_hi:[0,1]
	v_lshlrev_b32_e32 v50, 16, v32
	v_and_b32_e32 v51, 0xffff0000, v32
	v_pk_fma_f32 v[38:39], v[38:39], v[46:47], v[42:43]
	v_pk_fma_f32 v[34:35], v[40:41], v[34:35], v[44:45]
	v_pk_add_f32 v[38:39], v[38:39], v[50:51]
	v_pk_add_f32 v[34:35], v[34:35], v[52:53]
	v_cvt_pk_bf16_f32 v36, v38, v39
	v_cvt_pk_bf16_f32 v37, v34, v35
	ds_write_b64 v19, v[36:37] offset:16784
	v_add_u32_e32 v32, 0x25140, v27
	v_add_u32_e32 v38, 0x25540, v27
	ds_read_b64 v[42:43], v19 offset:160
	ds_read_b128 v[34:37], v32
	ds_read_b128 v[38:41], v38
	ds_read_b32 v32, v29
	ds_read_b32 v44, v30
	ds_read_b64 v[46:47], v19 offset:16800
	s_waitcnt lgkmcnt(5)
	v_lshlrev_b32_e32 v48, 16, v42
	v_and_b32_e32 v49, 0xffff0000, v42
	v_lshlrev_b32_e32 v42, 16, v43
	v_and_b32_e32 v43, 0xffff0000, v43
	s_waitcnt lgkmcnt(2)
	v_pk_add_f32 v[48:49], v[48:49], v[32:33] op_sel_hi:[1,0] neg_lo:[0,1] neg_hi:[0,1]
	v_pk_add_f32 v[42:43], v[42:43], v[32:33] op_sel_hi:[1,0] neg_lo:[0,1] neg_hi:[0,1]
	s_waitcnt lgkmcnt(1)
; DI unsigned pack2(float a, float b) { f32x2_t v = {a, b}; bf16x2_t r = __builtin_convertvector(v, bf16x2_t); return __builtin_bit_cast(unsigned, r); }
; DI float bflo(unsigned u) { return __uint_as_float(u << 16); }
; DI float bfhi(unsigned u) { return __uint_as_float(u & 0xffff0000u); }
; template <bool LAST>
; DI void phase_gate(const Params& P, int layer, unsigned char* smem, int L, int G) {
;     ...
; #pragma unroll
;     for (int i = 0; i < 4; ++i)
; #pragma unroll
;       for (int q4 = 0; q4 < 4; ++q4) {
;         const int fl = wm2 * 128 + i * 32 + 8 * q4 + 4 * h2;
;         const int f0 = nt * 256 + fl;
;         const f32x4 gv = *(const f32x4*)(vecL + 512 + fl), bv = *(const f32x4*)(vecL + 768 + fl);
;         const float ga[4] = {gv.x, gv.y, gv.z, gv.w}, ba[4] = {bv.x, bv.y, bv.z, bv.w};
; #pragma unroll
;         for (int j = 0; j < 2; ++j) {
;           const int lrow = wn2 * 64 + j * 32 + r2;
;           const float mu = rowA[lrow], rstd = rowB[lrow];
;           uint2* sp = (uint2*)(stg + lrow * STG + fl);
;           const uint2 sv = *sp;
;           const float sa[4] = {bflo(sv.x), bfhi(sv.x), bflo(sv.y), bfhi(sv.y)};
;           float y[4];
;           const float gg[4] = {bflo(gq[i][j][2 * q4]), bfhi(gq[i][j][2 * q4]), bflo(gq[i][j][2 * q4 + 1]), bfhi(gq[i][j][2 * q4 + 1])};
; #pragma unroll
;           for (int e = 0; e < 4; ++e) y[e] = (sa[e] - mu) * rstd * ga[e] + ba[e] + gg[e];
;           if (LAST) { f32x4 o = {y[0], y[1], y[2], y[3]}; *(f32x4*)(P.out + (size_t)(mt * 256 + lrow) * 1024 + f0) = o; }
;           else { uint2 pk; pk.x = pack2(y[0], y[1]); pk.y = pack2(y[2], y[3]); *sp = pk; }
;         }
;         __builtin_amdgcn_sched_barrier(0);
;       }
	v_pk_mul_f32 v[48:49], v[44:45], v[48:49] op_sel_hi:[0,1]
	v_pk_mul_f32 v[42:43], v[44:45], v[42:43] op_sel_hi:[0,1]
	v_lshlrev_b32_e32 v50, 16, v24
	v_and_b32_e32 v51, 0xffff0000, v24
	v_lshlrev_b32_e32 v52, 16, v26
	v_and_b32_e32 v53, 0xffff0000, v26
	v_pk_fma_f32 v[48:49], v[34:35], v[48:49], v[38:39]
	v_pk_fma_f32 v[42:43], v[36:37], v[42:43], v[40:41]
	v_pk_add_f32 v[48:49], v[48:49], v[50:51]
	v_pk_add_f32 v[42:43], v[42:43], v[52:53]
	v_cvt_pk_bf16_f32 v44, v48, v49
	v_cvt_pk_bf16_f32 v45, v42, v43
	ds_write_b64 v19, v[44:45] offset:160
	ds_read_b32 v24, v31
	ds_read_b32 v26, v33
	s_waitcnt lgkmcnt(3)
	v_lshlrev_b32_e32 v42, 16, v46
	v_and_b32_e32 v43, 0xffff0000, v46
	v_lshlrev_b32_e32 v44, 16, v47
	v_and_b32_e32 v45, 0xffff0000, v47
	v_lshlrev_b32_e32 v48, 16, v25
	v_and_b32_e32 v49, 0xffff0000, v25
	s_waitcnt lgkmcnt(1)
	v_pk_add_f32 v[42:43], v[42:43], v[24:25] op_sel_hi:[1,0] neg_lo:[0,1] neg_hi:[0,1]
	v_pk_add_f32 v[24:25], v[44:45], v[24:25] op_sel_hi:[1,0] neg_lo:[0,1] neg_hi:[0,1]
	s_waitcnt lgkmcnt(0)
	v_pk_mul_f32 v[42:43], v[26:27], v[42:43] op_sel_hi:[0,1]
	v_pk_mul_f32 v[24:25], v[26:27], v[24:25] op_sel_hi:[0,1]
	v_lshlrev_b32_e32 v46, 16, v23
	v_and_b32_e32 v47, 0xffff0000, v23
	v_pk_fma_f32 v[34:35], v[34:35], v[42:43], v[38:39]
	v_pk_fma_f32 v[24:25], v[36:37], v[24:25], v[40:41]
	v_pk_add_f32 v[34:35], v[34:35], v[46:47]
	v_pk_add_f32 v[24:25], v[24:25], v[48:49]
	v_cvt_pk_bf16_f32 v34, v34, v35
	v_cvt_pk_bf16_f32 v35, v24, v25
	ds_write_b64 v19, v[34:35] offset:16800
	v_add_u32_e32 v26, 0x25560, v27
	v_add_u32_e32 v23, 0x25160, v27
	ds_read_b64 v[24:25], v19 offset:176
	ds_read_b128 v[34:37], v23
	ds_read_b128 v[38:41], v26
	ds_read_b32 v26, v29
	ds_read_b32 v32, v30
	ds_read_b64 v[42:43], v19 offset:16816
	s_waitcnt lgkmcnt(5)
	v_lshlrev_b32_e32 v44, 16, v24
	v_and_b32_e32 v45, 0xffff0000, v24
	v_lshlrev_b32_e32 v24, 16, v25
	v_and_b32_e32 v25, 0xffff0000, v25
	v_lshlrev_b32_e32 v48, 16, v22
	v_and_b32_e32 v49, 0xffff0000, v22
	s_waitcnt lgkmcnt(2)
	v_pk_add_f32 v[22:23], v[44:45], v[26:27] op_sel_hi:[1,0] neg_lo:[0,1] neg_hi:[0,1]
	v_pk_add_f32 v[24:25], v[24:25], v[26:27] op_sel_hi:[1,0] neg_lo:[0,1] neg_hi:[0,1]
	s_waitcnt lgkmcnt(1)
	v_pk_mul_f32 v[22:23], v[32:33], v[22:23] op_sel_hi:[0,1]
	v_pk_mul_f32 v[24:25], v[32:33], v[24:25] op_sel_hi:[0,1]
	v_lshlrev_b32_e32 v46, 16, v20
	v_and_b32_e32 v47, 0xffff0000, v20
	v_pk_fma_f32 v[22:23], v[34:35], v[22:23], v[38:39]
	v_pk_fma_f32 v[24:25], v[36:37], v[24:25], v[40:41]
	v_pk_add_f32 v[22:23], v[22:23], v[46:47]
	v_pk_add_f32 v[24:25], v[24:25], v[48:49]
	v_cvt_pk_bf16_f32 v22, v22, v23
	v_cvt_pk_bf16_f32 v23, v24, v25
	ds_write_b64 v19, v[22:23] offset:176
	ds_read_b32 v20, v31
	ds_read_b32 v22, v33
	s_waitcnt lgkmcnt(3)
	v_lshlrev_b32_e32 v24, 16, v42
	v_and_b32_e32 v25, 0xffff0000, v42
	v_lshlrev_b32_e32 v42, 16, v43
	v_and_b32_e32 v43, 0xffff0000, v43
	v_lshlrev_b32_e32 v46, 16, v21
	v_and_b32_e32 v47, 0xffff0000, v21
	s_waitcnt lgkmcnt(1)
	v_pk_add_f32 v[24:25], v[24:25], v[20:21] op_sel_hi:[1,0] neg_lo:[0,1] neg_hi:[0,1]
	v_pk_add_f32 v[20:21], v[42:43], v[20:21] op_sel_hi:[1,0] neg_lo:[0,1] neg_hi:[0,1]
	s_waitcnt lgkmcnt(0)
	v_pk_mul_f32 v[24:25], v[22:23], v[24:25] op_sel_hi:[0,1]
	v_pk_mul_f32 v[20:21], v[22:23], v[20:21] op_sel_hi:[0,1]
	v_lshlrev_b32_e32 v44, 16, v18
	v_and_b32_e32 v45, 0xffff0000, v18
	v_pk_fma_f32 v[24:25], v[34:35], v[24:25], v[38:39]
	v_pk_fma_f32 v[20:21], v[36:37], v[20:21], v[40:41]
	v_pk_add_f32 v[24:25], v[24:25], v[44:45]
	v_pk_add_f32 v[20:21], v[20:21], v[46:47]
	v_cvt_pk_bf16_f32 v22, v24, v25
	v_cvt_pk_bf16_f32 v23, v20, v21
	ds_write_b64 v19, v[22:23] offset:16816
	v_add_u32_e32 v18, 0x25180, v27
	v_add_u32_e32 v26, 0x25580, v27
	ds_read_b64 v[24:25], v19 offset:192
	ds_read_b128 v[20:23], v18
	ds_read_b128 v[34:37], v26
	ds_read_b32 v18, v29
	ds_read_b32 v26, v30
	ds_read_b64 v[38:39], v19 offset:16832
	s_waitcnt lgkmcnt(5)
	v_lshlrev_b32_e32 v40, 16, v24
	v_and_b32_e32 v41, 0xffff0000, v24
	v_lshlrev_b32_e32 v24, 16, v25
	v_and_b32_e32 v25, 0xffff0000, v25
	s_waitcnt lgkmcnt(2)
	v_pk_add_f32 v[40:41], v[40:41], v[18:19] op_sel_hi:[1,0] neg_lo:[0,1] neg_hi:[0,1]
	v_pk_add_f32 v[24:25], v[24:25], v[18:19] op_sel_hi:[1,0] neg_lo:[0,1] neg_hi:[0,1]
	s_waitcnt lgkmcnt(1)
	v_pk_mul_f32 v[40:41], v[26:27], v[40:41] op_sel_hi:[0,1]
	v_pk_mul_f32 v[24:25], v[26:27], v[24:25] op_sel_hi:[0,1]
	v_lshlrev_b32_e32 v42, 16, v15
	v_and_b32_e32 v43, 0xffff0000, v15
	v_lshlrev_b32_e32 v44, 16, v17
	v_and_b32_e32 v45, 0xffff0000, v17
	v_pk_fma_f32 v[40:41], v[20:21], v[40:41], v[34:35]
	v_pk_fma_f32 v[24:25], v[22:23], v[24:25], v[36:37]
	v_pk_add_f32 v[40:41], v[40:41], v[42:43]
	v_pk_add_f32 v[24:25], v[24:25], v[44:45]
	v_cvt_pk_bf16_f32 v40, v40, v41
	v_cvt_pk_bf16_f32 v41, v24, v25
	ds_write_b64 v19, v[40:41] offset:192
	ds_read_b32 v18, v31
	ds_read_b32 v24, v33
	s_waitcnt lgkmcnt(3)
	v_lshlrev_b32_e32 v40, 16, v38
	v_and_b32_e32 v41, 0xffff0000, v38
	v_lshlrev_b32_e32 v42, 16, v14
	v_and_b32_e32 v43, 0xffff0000, v14
	v_lshlrev_b32_e32 v14, 16, v16
	v_and_b32_e32 v15, 0xffff0000, v16
	s_waitcnt lgkmcnt(1)
	v_pk_add_f32 v[16:17], v[40:41], v[18:19] op_sel_hi:[1,0] neg_lo:[0,1] neg_hi:[0,1]
	v_lshlrev_b32_e32 v38, 16, v39
	v_and_b32_e32 v39, 0xffff0000, v39
	s_waitcnt lgkmcnt(0)
; DI unsigned pack2(float a, float b) { f32x2_t v = {a, b}; bf16x2_t r = __builtin_convertvector(v, bf16x2_t); return __builtin_bit_cast(unsigned, r); }
; DI float bflo(unsigned u) { return __uint_as_float(u << 16); }
; DI float bfhi(unsigned u) { return __uint_as_float(u & 0xffff0000u); }
; template <bool LAST>
; DI void phase_gate(const Params& P, int layer, unsigned char* smem, int L, int G) {
;     ...
; #pragma unroll
;     for (int i = 0; i < 4; ++i)
; #pragma unroll
;       for (int q4 = 0; q4 < 4; ++q4) {
;         const int fl = wm2 * 128 + i * 32 + 8 * q4 + 4 * h2;
;         const int f0 = nt * 256 + fl;
;         const f32x4 gv = *(const f32x4*)(vecL + 512 + fl), bv = *(const f32x4*)(vecL + 768 + fl);
;         const float ga[4] = {gv.x, gv.y, gv.z, gv.w}, ba[4] = {bv.x, bv.y, bv.z, bv.w};
; #pragma unroll
;         for (int j = 0; j < 2; ++j) {
;           const int lrow = wn2 * 64 + j * 32 + r2;
;           const float mu = rowA[lrow], rstd = rowB[lrow];
;           uint2* sp = (uint2*)(stg + lrow * STG + fl);
;           const uint2 sv = *sp;
;           const float sa[4] = {bflo(sv.x), bfhi(sv.x), bflo(sv.y), bfhi(sv.y)};
;           float y[4];
;           const float gg[4] = {bflo(gq[i][j][2 * q4]), bfhi(gq[i][j][2 * q4]), bflo(gq[i][j][2 * q4 + 1]), bfhi(gq[i][j][2 * q4 + 1])};
; #pragma unroll
;           for (int e = 0; e < 4; ++e) y[e] = (sa[e] - mu) * rstd * ga[e] + ba[e] + gg[e];
;           if (LAST) { f32x4 o = {y[0], y[1], y[2], y[3]}; *(f32x4*)(P.out + (size_t)(mt * 256 + lrow) * 1024 + f0) = o; }
;           else { uint2 pk; pk.x = pack2(y[0], y[1]); pk.y = pack2(y[2], y[3]); *sp = pk; }
;         }
;         __builtin_amdgcn_sched_barrier(0);
;       }
;     __syncthreads();
	v_pk_mul_f32 v[16:17], v[24:25], v[16:17] op_sel_hi:[0,1]
	v_pk_fma_f32 v[16:17], v[20:21], v[16:17], v[34:35]
	v_pk_add_f32 v[20:21], v[38:39], v[18:19] op_sel_hi:[1,0] neg_lo:[0,1] neg_hi:[0,1]
	v_pk_add_f32 v[16:17], v[16:17], v[42:43]
	v_pk_mul_f32 v[20:21], v[24:25], v[20:21] op_sel_hi:[0,1]
	v_pk_fma_f32 v[20:21], v[22:23], v[20:21], v[36:37]
	v_cvt_pk_bf16_f32 v16, v16, v17
	v_pk_add_f32 v[14:15], v[20:21], v[14:15]
	s_nop 0
	v_cvt_pk_bf16_f32 v17, v14, v15
	ds_write_b64 v19, v[16:17] offset:16832
	v_add_u32_e32 v14, 0x251a0, v27
	v_add_u32_e32 v18, 0x255a0, v27
	ds_read_b64 v[24:25], v19 offset:208
	ds_read_b128 v[14:17], v14
	ds_read_b128 v[20:23], v18
	ds_read_b32 v18, v29
	ds_read_b32 v26, v30
	ds_read_b64 v[34:35], v19 offset:16848
	s_waitcnt lgkmcnt(5)
	v_lshlrev_b32_e32 v36, 16, v24
	v_and_b32_e32 v37, 0xffff0000, v24
	v_lshlrev_b32_e32 v24, 16, v25
	v_and_b32_e32 v25, 0xffff0000, v25
	s_waitcnt lgkmcnt(2)
	v_pk_add_f32 v[36:37], v[36:37], v[18:19] op_sel_hi:[1,0] neg_lo:[0,1] neg_hi:[0,1]
	v_pk_add_f32 v[24:25], v[24:25], v[18:19] op_sel_hi:[1,0] neg_lo:[0,1] neg_hi:[0,1]
	s_waitcnt lgkmcnt(1)
	v_pk_mul_f32 v[36:37], v[26:27], v[36:37] op_sel_hi:[0,1]
	v_pk_mul_f32 v[24:25], v[26:27], v[24:25] op_sel_hi:[0,1]
	v_lshlrev_b32_e32 v38, 16, v11
	v_and_b32_e32 v39, 0xffff0000, v11
	v_lshlrev_b32_e32 v40, 16, v13
	v_and_b32_e32 v41, 0xffff0000, v13
	v_pk_fma_f32 v[36:37], v[14:15], v[36:37], v[20:21]
	v_pk_fma_f32 v[24:25], v[16:17], v[24:25], v[22:23]
	v_pk_add_f32 v[36:37], v[36:37], v[38:39]
	v_pk_add_f32 v[24:25], v[24:25], v[40:41]
	v_cvt_pk_bf16_f32 v36, v36, v37
	v_cvt_pk_bf16_f32 v37, v24, v25
	ds_write_b64 v19, v[36:37] offset:208
	ds_read_b32 v18, v31
	ds_read_b32 v24, v33
	s_waitcnt lgkmcnt(3)
	v_lshlrev_b32_e32 v36, 16, v34
	v_and_b32_e32 v37, 0xffff0000, v34
	v_lshlrev_b32_e32 v38, 16, v10
	v_and_b32_e32 v39, 0xffff0000, v10
	v_lshlrev_b32_e32 v10, 16, v12
	v_and_b32_e32 v11, 0xffff0000, v12
	s_waitcnt lgkmcnt(1)
	v_pk_add_f32 v[12:13], v[36:37], v[18:19] op_sel_hi:[1,0] neg_lo:[0,1] neg_hi:[0,1]
	v_lshlrev_b32_e32 v34, 16, v35
	v_and_b32_e32 v35, 0xffff0000, v35
	s_waitcnt lgkmcnt(0)
	v_pk_mul_f32 v[12:13], v[24:25], v[12:13] op_sel_hi:[0,1]
	v_pk_fma_f32 v[12:13], v[14:15], v[12:13], v[20:21]
	v_pk_add_f32 v[14:15], v[34:35], v[18:19] op_sel_hi:[1,0] neg_lo:[0,1] neg_hi:[0,1]
	v_pk_add_f32 v[12:13], v[12:13], v[38:39]
	v_pk_mul_f32 v[14:15], v[24:25], v[14:15] op_sel_hi:[0,1]
	v_pk_fma_f32 v[14:15], v[16:17], v[14:15], v[22:23]
	v_cvt_pk_bf16_f32 v12, v12, v13
	v_pk_add_f32 v[10:11], v[14:15], v[10:11]
	s_nop 0
	v_cvt_pk_bf16_f32 v13, v10, v11
	ds_write_b64 v19, v[12:13] offset:16848
	v_add_u32_e32 v10, 0x251c0, v27
	v_add_u32_e32 v14, 0x255c0, v27
	ds_read_b64 v[20:21], v19 offset:224
	ds_read_b128 v[10:13], v10
	ds_read_b128 v[14:17], v14
	ds_read_b32 v18, v29
	ds_read_b32 v22, v30
	ds_read_b64 v[24:25], v19 offset:16864
	s_waitcnt lgkmcnt(5)
	v_lshlrev_b32_e32 v34, 16, v20
	v_and_b32_e32 v35, 0xffff0000, v20
	v_lshlrev_b32_e32 v20, 16, v21
	v_and_b32_e32 v21, 0xffff0000, v21
	s_waitcnt lgkmcnt(2)
	v_pk_add_f32 v[34:35], v[34:35], v[18:19] op_sel_hi:[1,0] neg_lo:[0,1] neg_hi:[0,1]
	v_pk_add_f32 v[20:21], v[20:21], v[18:19] op_sel_hi:[1,0] neg_lo:[0,1] neg_hi:[0,1]
	s_waitcnt lgkmcnt(1)
	v_pk_mul_f32 v[34:35], v[22:23], v[34:35] op_sel_hi:[0,1]
	v_pk_mul_f32 v[20:21], v[22:23], v[20:21] op_sel_hi:[0,1]
	v_lshlrev_b32_e32 v36, 16, v7
	v_and_b32_e32 v37, 0xffff0000, v7
	v_lshlrev_b32_e32 v38, 16, v9
	v_and_b32_e32 v39, 0xffff0000, v9
	v_pk_fma_f32 v[34:35], v[10:11], v[34:35], v[14:15]
	v_pk_fma_f32 v[20:21], v[12:13], v[20:21], v[16:17]
	v_pk_add_f32 v[34:35], v[34:35], v[36:37]
	v_pk_add_f32 v[20:21], v[20:21], v[38:39]
	v_cvt_pk_bf16_f32 v22, v34, v35
	v_cvt_pk_bf16_f32 v23, v20, v21
	ds_write_b64 v19, v[22:23] offset:224
	ds_read_b32 v18, v31
	ds_read_b32 v20, v33
	s_waitcnt lgkmcnt(3)
	v_lshlrev_b32_e32 v22, 16, v24
	v_and_b32_e32 v23, 0xffff0000, v24
	v_lshlrev_b32_e32 v34, 16, v6
	v_and_b32_e32 v35, 0xffff0000, v6
	v_lshlrev_b32_e32 v6, 16, v8
	v_and_b32_e32 v7, 0xffff0000, v8
	s_waitcnt lgkmcnt(1)
	v_pk_add_f32 v[8:9], v[22:23], v[18:19] op_sel_hi:[1,0] neg_lo:[0,1] neg_hi:[0,1]
	v_lshlrev_b32_e32 v24, 16, v25
	v_and_b32_e32 v25, 0xffff0000, v25
	s_waitcnt lgkmcnt(0)
	v_pk_mul_f32 v[8:9], v[20:21], v[8:9] op_sel_hi:[0,1]
	v_pk_fma_f32 v[8:9], v[10:11], v[8:9], v[14:15]
	v_pk_add_f32 v[10:11], v[24:25], v[18:19] op_sel_hi:[1,0] neg_lo:[0,1] neg_hi:[0,1]
	v_pk_add_f32 v[8:9], v[8:9], v[34:35]
	v_pk_mul_f32 v[10:11], v[20:21], v[10:11] op_sel_hi:[0,1]
	v_pk_fma_f32 v[10:11], v[12:13], v[10:11], v[16:17]
	v_cvt_pk_bf16_f32 v8, v8, v9
	v_pk_add_f32 v[6:7], v[10:11], v[6:7]
	s_nop 0
	v_cvt_pk_bf16_f32 v9, v6, v7
	ds_write_b64 v19, v[8:9] offset:16864
	ds_read_b128 v[6:9], v28 offset:480
	ds_read_b64 v[14:15], v19 offset:240
	ds_read_b32 v16, v29
	ds_read_b32 v18, v30
	v_add_u32_e32 v10, 0x255e0, v27
	ds_read_b128 v[10:13], v10
	s_waitcnt lgkmcnt(3)
	v_lshlrev_b32_e32 v20, 16, v14
	v_and_b32_e32 v21, 0xffff0000, v14
	v_lshlrev_b32_e32 v14, 16, v15
	v_and_b32_e32 v15, 0xffff0000, v15
	s_waitcnt lgkmcnt(2)
	v_pk_add_f32 v[20:21], v[20:21], v[16:17] op_sel_hi:[1,0] neg_lo:[0,1] neg_hi:[0,1]
	v_pk_add_f32 v[14:15], v[14:15], v[16:17] op_sel_hi:[1,0] neg_lo:[0,1] neg_hi:[0,1]
	s_waitcnt lgkmcnt(1)
	v_pk_mul_f32 v[20:21], v[18:19], v[20:21] op_sel_hi:[0,1]
	v_pk_mul_f32 v[14:15], v[18:19], v[14:15] op_sel_hi:[0,1]
	v_lshlrev_b32_e32 v22, 16, v4
	v_and_b32_e32 v23, 0xffff0000, v4
	v_lshlrev_b32_e32 v4, 16, v5
	v_and_b32_e32 v5, 0xffff0000, v5
	s_waitcnt lgkmcnt(0)
	v_pk_fma_f32 v[20:21], v[6:7], v[20:21], v[10:11]
	v_pk_fma_f32 v[14:15], v[8:9], v[14:15], v[12:13]
	v_pk_add_f32 v[20:21], v[20:21], v[22:23]
	v_pk_add_f32 v[4:5], v[14:15], v[4:5]
	v_cvt_pk_bf16_f32 v14, v20, v21
	v_cvt_pk_bf16_f32 v15, v4, v5
	ds_write_b64 v19, v[14:15] offset:240
	ds_read_b32 v4, v33
	ds_read_b64 v[14:15], v19 offset:16880
	ds_read_b32 v16, v31
	v_lshlrev_b32_e32 v22, 16, v2
	v_and_b32_e32 v23, 0xffff0000, v2
	v_lshlrev_b32_e32 v2, 16, v3
	s_waitcnt lgkmcnt(1)
	v_lshlrev_b32_e32 v20, 16, v14
	v_and_b32_e32 v21, 0xffff0000, v14
	s_waitcnt lgkmcnt(0)
	v_pk_add_f32 v[20:21], v[20:21], v[16:17] op_sel_hi:[1,0] neg_lo:[0,1] neg_hi:[0,1]
	v_lshlrev_b32_e32 v14, 16, v15
	v_and_b32_e32 v15, 0xffff0000, v15
	v_pk_mul_f32 v[20:21], v[4:5], v[20:21] op_sel_hi:[0,1]
	v_pk_fma_f32 v[6:7], v[6:7], v[20:21], v[10:11]
	v_pk_add_f32 v[10:11], v[14:15], v[16:17] op_sel_hi:[1,0] neg_lo:[0,1] neg_hi:[0,1]
	v_and_b32_e32 v3, 0xffff0000, v3
	v_pk_mul_f32 v[4:5], v[4:5], v[10:11] op_sel_hi:[0,1]
	v_pk_fma_f32 v[4:5], v[8:9], v[4:5], v[12:13]
	v_pk_add_f32 v[6:7], v[6:7], v[22:23]
	v_pk_add_f32 v[2:3], v[4:5], v[2:3]
	v_cvt_pk_bf16_f32 v4, v6, v7
	v_cvt_pk_bf16_f32 v5, v2, v3
	ds_write_b64 v19, v[4:5] offset:16880
	s_add_u32 s18, s80, s18
	s_addc_u32 s19, s81, s19
	v_lshl_add_u64 v[8:9], s[18:19], 0, v[0:1]
	v_mov_b32_e32 v0, v192
	s_waitcnt lgkmcnt(0)
	s_barrier
; DI int otid() { int t = threadIdx.x; asm volatile("" : "+v"(t)); return t; }
; DI void stg16_nt(void* p, u32x4 v) { __builtin_nontemporal_store(v, (u32x4*)p); }
; DI void stage_store_tile(const bf16_t* stg, bf16_t* tilebase) {
;   const int tid = otid();
;   const int r0 = tid >> 5, c = tid & 31;
;   const unsigned o0 = (unsigned)(r0 * 1024 + c * 8);
; #pragma unroll
;   for (int it = 0; it < 16; ++it) stg16_nt(tilebase + (o0 + (unsigned)(it * 16 * 1024)), stage_read16(stg, r0 + 16 * it, c));
; }
; template <bool LAST>
; DI void phase_gate(const Params& P, int layer, unsigned char* smem, int L, int G) {
;     ...
;     if (!LAST) stage_store_tile(stg, xb + (size_t)mt * 256 * 1024 + nt * 256);
;     __syncthreads();
	s_add_i32 s25, s25, s74
	v_ashrrev_i32_e32 v4, 5, v0
	v_and_b32_e32 v0, 31, v0
	v_mul_lo_u32 v1, v4, s34
	v_lshl_add_u32 v12, v0, 4, v1
	v_lshlrev_b32_e32 v5, 3, v0
	ds_read2_b64 v[0:3], v12 offset1:1
	v_lshl_or_b32 v160, v4, 10, v5
	v_add_u32_e32 v4, 0x2080, v12
	ds_read2_b64 v[4:7], v4 offset1:1
	v_lshl_add_u64 v[10:11], v[160:161], 1, v[8:9]
	s_waitcnt lgkmcnt(1)
	global_store_dwordx4 v[10:11], v[0:3], off nt
	s_add_i32 s22, s22, s69
	s_add_i32 s23, s23, s24
	v_add_u32_e32 v0, 0x4000, v160
	v_mov_b32_e32 v1, v161
	v_lshl_add_u64 v[0:1], v[0:1], 1, v[8:9]
	s_waitcnt lgkmcnt(0)
	global_store_dwordx4 v[0:1], v[4:7], off nt
	v_add_u32_e32 v0, 0x4100, v12
	ds_read2_b64 v[0:3], v0 offset1:1
	v_add_u32_e32 v4, 0x8000, v160
	v_mov_b32_e32 v5, v161
	v_lshl_add_u64 v[10:11], v[4:5], 1, v[8:9]
	v_add_u32_e32 v4, 0x6180, v12
	ds_read2_b64 v[4:7], v4 offset1:1
	s_waitcnt lgkmcnt(1)
	global_store_dwordx4 v[10:11], v[0:3], off nt
	s_add_i32 s18, s70, s25
	s_cmpk_lt_i32 s18, 0x400
	v_add_u32_e32 v0, 0xc000, v160
	v_mov_b32_e32 v1, v161
	v_lshl_add_u64 v[0:1], v[0:1], 1, v[8:9]
	s_waitcnt lgkmcnt(0)
	global_store_dwordx4 v[0:1], v[4:7], off nt
	v_add_u32_e32 v0, 0x8200, v12
	ds_read2_b64 v[0:3], v0 offset1:1
	v_add_u32_e32 v4, 0x10000, v160
	v_mov_b32_e32 v5, v161
	v_lshl_add_u64 v[10:11], v[4:5], 1, v[8:9]
	v_add_u32_e32 v4, 0xa280, v12
	ds_read2_b64 v[4:7], v4 offset1:1
	s_waitcnt lgkmcnt(1)
	global_store_dwordx4 v[10:11], v[0:3], off nt
	s_nop 1
	v_add_u32_e32 v0, 0x14000, v160
	v_mov_b32_e32 v1, v161
	v_lshl_add_u64 v[0:1], v[0:1], 1, v[8:9]
	s_waitcnt lgkmcnt(0)
	global_store_dwordx4 v[0:1], v[4:7], off nt
	v_add_u32_e32 v0, 0xc300, v12
	ds_read2_b64 v[0:3], v0 offset1:1
	v_add_u32_e32 v4, 0x18000, v160
	v_mov_b32_e32 v5, v161
	v_lshl_add_u64 v[10:11], v[4:5], 1, v[8:9]
	v_add_u32_e32 v4, 0xe380, v12
	ds_read2_b64 v[4:7], v4 offset1:1
	s_waitcnt lgkmcnt(1)
	global_store_dwordx4 v[10:11], v[0:3], off nt
	s_nop 1
	v_add_u32_e32 v0, 0x1c000, v160
	v_mov_b32_e32 v1, v161
	v_lshl_add_u64 v[0:1], v[0:1], 1, v[8:9]
	s_waitcnt lgkmcnt(0)
	global_store_dwordx4 v[0:1], v[4:7], off nt
	v_add_u32_e32 v0, 0x10400, v12
	ds_read2_b64 v[0:3], v0 offset1:1
	v_add_u32_e32 v4, 0x20000, v160
	v_mov_b32_e32 v5, v161
	v_lshl_add_u64 v[10:11], v[4:5], 1, v[8:9]
	v_add_u32_e32 v4, 0x12480, v12
	ds_read2_b64 v[4:7], v4 offset1:1
	s_waitcnt lgkmcnt(1)
	global_store_dwordx4 v[10:11], v[0:3], off nt
	s_nop 1
	v_add_u32_e32 v0, 0x24000, v160
	v_mov_b32_e32 v1, v161
	v_lshl_add_u64 v[0:1], v[0:1], 1, v[8:9]
	s_waitcnt lgkmcnt(0)
	global_store_dwordx4 v[0:1], v[4:7], off nt
	v_add_u32_e32 v0, 0x14500, v12
	ds_read2_b64 v[0:3], v0 offset1:1
	v_add_u32_e32 v4, 0x28000, v160
	v_mov_b32_e32 v5, v161
	v_lshl_add_u64 v[10:11], v[4:5], 1, v[8:9]
	v_add_u32_e32 v4, 0x16580, v12
	ds_read2_b64 v[4:7], v4 offset1:1
	s_waitcnt lgkmcnt(1)
	global_store_dwordx4 v[10:11], v[0:3], off nt
	s_nop 1
	v_add_u32_e32 v0, 0x2c000, v160
	v_mov_b32_e32 v1, v161
	v_lshl_add_u64 v[0:1], v[0:1], 1, v[8:9]
	s_waitcnt lgkmcnt(0)
	global_store_dwordx4 v[0:1], v[4:7], off nt
	v_add_u32_e32 v0, 0x18600, v12
	ds_read2_b64 v[0:3], v0 offset1:1
	v_add_u32_e32 v4, 0x30000, v160
	v_mov_b32_e32 v5, v161
	v_lshl_add_u64 v[10:11], v[4:5], 1, v[8:9]
	v_add_u32_e32 v4, 0x1a680, v12
	ds_read2_b64 v[4:7], v4 offset1:1
	s_waitcnt lgkmcnt(1)
	global_store_dwordx4 v[10:11], v[0:3], off nt
	v_add_u32_e32 v10, 0x38000, v160
	v_mov_b32_e32 v11, v161
	v_add_u32_e32 v0, 0x34000, v160
	v_mov_b32_e32 v1, v161
	v_lshl_add_u64 v[0:1], v[0:1], 1, v[8:9]
	s_waitcnt lgkmcnt(0)
	global_store_dwordx4 v[0:1], v[4:7], off nt
	v_add_u32_e32 v0, 0x1c700, v12
	ds_read2_b64 v[0:3], v0 offset1:1
	v_add_u32_e32 v4, 0x1e780, v12
	ds_read2_b64 v[4:7], v4 offset1:1
	v_lshl_add_u64 v[10:11], v[10:11], 1, v[8:9]
	v_add_u32_e32 v160, 0x3c000, v160
	s_waitcnt lgkmcnt(1)
	global_store_dwordx4 v[10:11], v[0:3], off nt
	s_nop 1
	v_lshl_add_u64 v[0:1], v[160:161], 1, v[8:9]
	s_waitcnt lgkmcnt(0)
	global_store_dwordx4 v[0:1], v[4:7], off nt
	s_barrier
	s_cbranch_scc0 .LBB0_1507

; DI int otid() { int t = threadIdx.x; asm volatile("" : "+v"(t)); return t; }
; template <bool NT>
; DI void stage_load_tile(bf16_t* stg, const bf16_t* tilebase) {
;   const int tid = otid();
;   const int r0 = tid >> 5, c = tid & 31;
;   const unsigned o0 = (unsigned)(r0 * 1024 + c * 8);
;   __builtin_amdgcn_sched_barrier(0);
; #pragma unroll
;   for (int hf = 0; hf < 2; ++hf) {
; #pragma unroll
;     for (int it = 8 * hf; it < 8 * hf + 8; ++it) {
;       const u32x4* gp = (const u32x4*)(tilebase + (o0 + (unsigned)(it * 16 * 1024)));
;       stage_write16(stg, r0 + 16 * it, c, NT ? __builtin_nontemporal_load(gp) : *gp);
;     }
;     __builtin_amdgcn_sched_barrier(0);
;   }
; }
; template <bool XF32>
; DI void phase_outproj(const Params& P, int layer, const void* xres, const bf16_t* og, unsigned char* smem, int L, int G) {
;     ...
;     stage_load_tile<true>(stg, (const bf16_t*)xres + (size_t)mt * 256 * 1024 + nt * 256);
;     __syncthreads();
.LBB0_1731:
	v_bfe_u32 v193, v167, 5, 1
	s_ashr_i32 s11, s10, 31
	s_lshl_b64 s[28:29], s[10:11], 19
	s_add_u32 s15, s80, s28
	v_mov_b32_e32 v160, v192
	s_addc_u32 s28, s81, s29
	s_lshl_b32 s27, s14, 1
	s_add_u32 s14, s15, s27
	v_and_b32_e32 v199, 31, v160
	v_ashrrev_i32_e32 v198, 5, v160
	v_lshlrev_b32_e32 v160, 3, v199
	s_addc_u32 s15, s28, 0
	v_lshl_or_b32 v160, v198, 10, v160
	v_add_u32_e32 v164, 0x4000, v160
	v_mov_b32_e32 v165, v161
	v_add_u32_e32 v172, 0x8000, v160
	v_mov_b32_e32 v173, v161
	v_add_u32_e32 v174, 0xc000, v160
	v_mov_b32_e32 v175, v161
	v_add_u32_e32 v180, 0x10000, v160
	v_mov_b32_e32 v181, v161
	v_add_u32_e32 v182, 0x14000, v160
	v_mov_b32_e32 v183, v161
	v_add_u32_e32 v188, 0x18000, v160
	v_mov_b32_e32 v189, v161
	v_add_u32_e32 v190, 0x1c000, v160
	v_mov_b32_e32 v191, v161
	v_lshl_add_u64 v[162:163], v[160:161], 1, s[14:15]
	v_lshl_add_u64 v[168:169], v[164:165], 1, s[14:15]
	v_lshl_add_u64 v[172:173], v[172:173], 1, s[14:15]
	v_lshl_add_u64 v[176:177], v[174:175], 1, s[14:15]
	v_lshl_add_u64 v[180:181], v[180:181], 1, s[14:15]
	v_lshl_add_u64 v[184:185], v[182:183], 1, s[14:15]
	v_lshl_add_u64 v[188:189], v[188:189], 1, s[14:15]
	v_lshl_add_u64 v[194:195], v[190:191], 1, s[14:15]
	global_load_dwordx4 v[162:165], v[162:163], off nt
	s_nop 0
	global_load_dwordx4 v[168:171], v[168:169], off nt
	s_nop 0
	global_load_dwordx4 v[172:175], v[172:173], off nt
	s_nop 0
	global_load_dwordx4 v[176:179], v[176:177], off nt
	s_nop 0
	global_load_dwordx4 v[180:183], v[180:181], off nt
	s_nop 0
	global_load_dwordx4 v[184:187], v[184:185], off nt
	s_nop 0
	global_load_dwordx4 v[188:191], v[188:189], off nt
	s_nop 0
	global_load_dwordx4 v[194:197], v[194:195], off nt
	v_add_u32_e32 v222, 0x20000, v160
	v_mov_b32_e32 v223, v161
	v_add_u32_e32 v224, 0x24000, v160
	v_mov_b32_e32 v225, v161
	v_add_u32_e32 v230, 0x28000, v160
	v_mov_b32_e32 v231, v161
	v_add_u32_e32 v232, 0x2c000, v160
	v_mov_b32_e32 v233, v161
	v_add_u32_e32 v238, 0x30000, v160
	v_mov_b32_e32 v239, v161
	v_add_u32_e32 v240, 0x34000, v160
	v_mov_b32_e32 v241, v161
	v_add_u32_e32 v248, 0x38000, v160
	v_mov_b32_e32 v249, v161
	v_add_u32_e32 v160, 0x3c000, v160
	v_lshl_add_u64 v[222:223], v[222:223], 1, s[14:15]
	v_lshl_add_u64 v[226:227], v[224:225], 1, s[14:15]
	v_lshl_add_u64 v[230:231], v[230:231], 1, s[14:15]
	v_lshl_add_u64 v[234:235], v[232:233], 1, s[14:15]
	v_lshl_add_u64 v[238:239], v[238:239], 1, s[14:15]
	v_lshl_add_u64 v[242:243], v[240:241], 1, s[14:15]
	v_lshl_add_u64 v[248:249], v[248:249], 1, s[14:15]
	v_lshl_add_u64 v[252:253], v[160:161], 1, s[14:15]
	global_load_dwordx4 v[222:225], v[222:223], off nt
	s_nop 0
	global_load_dwordx4 v[226:229], v[226:227], off nt
	s_nop 0
	global_load_dwordx4 v[230:233], v[230:231], off nt
	s_nop 0
	global_load_dwordx4 v[234:237], v[234:235], off nt
	s_nop 0
	global_load_dwordx4 v[238:241], v[238:239], off nt
	s_nop 0
	global_load_dwordx4 v[242:245], v[242:243], off nt
	s_nop 0
	global_load_dwordx4 v[248:251], v[248:249], off nt
	s_nop 0
	global_load_dwordx4 v[252:255], v[252:253], off nt
	v_mul_lo_u32 v198, v198, s23
	v_lshl_add_u32 v198, v199, 4, v198
	v_add_u32_e32 v199, 0x2080, v198
	v_add_u32_e32 v200, 0x4100, v198
	v_add_u32_e32 v201, 0x6180, v198
	v_add_u32_e32 v202, 0x8200, v198
	v_add_u32_e32 v203, 0xa280, v198
	v_add_u32_e32 v204, 0xc300, v198
	v_add_u32_e32 v205, 0xe380, v198
	s_waitcnt vmcnt(15)
	ds_write2_b64 v198, v[162:163], v[164:165] offset1:1
	s_waitcnt vmcnt(14)
	ds_write2_b64 v199, v[168:169], v[170:171] offset1:1
	s_waitcnt vmcnt(13)
	ds_write2_b64 v200, v[172:173], v[174:175] offset1:1
	s_waitcnt vmcnt(12)
	ds_write2_b64 v201, v[176:177], v[178:179] offset1:1
	s_waitcnt vmcnt(11)
	ds_write2_b64 v202, v[180:181], v[182:183] offset1:1
	s_waitcnt vmcnt(10)
	ds_write2_b64 v203, v[184:185], v[186:187] offset1:1
	s_waitcnt vmcnt(9)
	ds_write2_b64 v204, v[188:189], v[190:191] offset1:1
	s_waitcnt vmcnt(8)
	ds_write2_b64 v205, v[194:195], v[196:197] offset1:1
	v_add_u32_e32 v160, 0x10400, v198
	v_add_u32_e32 v199, 0x12480, v198
	v_add_u32_e32 v200, 0x14500, v198
	v_add_u32_e32 v201, 0x16580, v198
	v_add_u32_e32 v202, 0x18600, v198
	v_add_u32_e32 v203, 0x1a680, v198
	v_add_u32_e32 v204, 0x1c700, v198
	v_add_u32_e32 v198, 0x1e780, v198
	s_waitcnt vmcnt(7)
	ds_write2_b64 v160, v[222:223], v[224:225] offset1:1
	s_waitcnt vmcnt(6)
	ds_write2_b64 v199, v[226:227], v[228:229] offset1:1
	s_waitcnt vmcnt(5)
	ds_write2_b64 v200, v[230:231], v[232:233] offset1:1
	s_waitcnt vmcnt(4)
	ds_write2_b64 v201, v[234:235], v[236:237] offset1:1
	s_waitcnt vmcnt(3)
	ds_write2_b64 v202, v[238:239], v[240:241] offset1:1
	s_waitcnt vmcnt(2)
	ds_write2_b64 v203, v[242:243], v[244:245] offset1:1
	s_waitcnt vmcnt(1)
	ds_write2_b64 v204, v[248:249], v[250:251] offset1:1
	s_waitcnt vmcnt(0)
	ds_write2_b64 v198, v[252:253], v[254:255] offset1:1
	v_lshlrev_b32_e32 v160, 3, v193
	v_and_b32_e32 v163, 0xdf, v167
	v_and_or_b32 v164, v167, s18, v160
	v_ashrrev_i32_e32 v165, 7, v167
	v_mad_u32_u24 v167, v163, s23, v164
	s_waitcnt lgkmcnt(0)
	s_barrier
; DI unsigned pack2(float a, float b) { f32x2_t v = {a, b}; bf16x2_t r = __builtin_convertvector(v, bf16x2_t); return __builtin_bit_cast(unsigned, r); }
; DI float bflo(unsigned u) { return __uint_as_float(u << 16); }
; DI float bfhi(unsigned u) { return __uint_as_float(u & 0xffff0000u); }
; template <bool XF32>
; DI void phase_outproj(const Params& P, int layer, const void* xres, const bf16_t* og, unsigned char* smem, int L, int G) {
;     ...
; #pragma unroll
;     for (int j = 0; j < 2; ++j)
; #pragma unroll
;       for (int ch = 0; ch < 2; ++ch) {
;         float s1 = 0.f, s2 = 0.f;
; #pragma unroll
;         for (int i = 2 * ch; i < 2 * ch + 2; ++i)
; #pragma unroll
;           for (int q4 = 0; q4 < 4; ++q4) {
;             uint2* pp = (uint2*)(stg + (wn * 64 + j * 32 + r) * STG + wm * 128 + i * 32 + 8 * q4 + 4 * h);
;             const uint2 xv = *pp;
;             uint2 pk;
;             pk.x = pack2(DN_ALPHA * bflo(xv.x) + acc[i][j][4 * q4], DN_ALPHA * bfhi(xv.x) + acc[i][j][4 * q4 + 1]);
;             pk.y = pack2(DN_ALPHA * bflo(xv.y) + acc[i][j][4 * q4 + 2], DN_ALPHA * bfhi(xv.y) + acc[i][j][4 * q4 + 3]);
;             *pp = pk;
;             const float f0 = bflo(pk.x), f1 = bfhi(pk.x), f2 = bflo(pk.y), f3 = bfhi(pk.y);
;             s1 += (f0 + f1) + (f2 + f3); s2 += (f0 * f0 + f1 * f1) + (f2 * f2 + f3 * f3);
;             __builtin_amdgcn_sched_barrier(0);
;           }
	ds_read_b64 v[168:169], v167
	v_and_b32_e32 v162, 64, v166
	v_xor_b32_e32 v160, 32, v166
	v_add_u32_e32 v162, 64, v162
	v_cmp_lt_i32_e32 vcc, v160, v162
	v_or_b32_e32 v162, s26, v163
	v_and_b32_e32 v165, -2, v165
	v_ashrrev_i32_e32 v163, 31, v162
	s_waitcnt lgkmcnt(0)
	v_lshlrev_b32_e32 v170, 16, v168
	v_and_b32_e32 v171, 0xffff0000, v168
	v_lshlrev_b32_e32 v168, 16, v169
	v_and_b32_e32 v169, 0xffff0000, v169
	v_cndmask_b32_e32 v160, v166, v160, vcc
	v_cmp_eq_u32_e32 vcc, 0, v193
	v_lshl_add_u32 v193, s25, 2, v165
	v_lshlrev_b64 v[164:165], 7, v[162:163]
	v_pk_fma_f32 v[112:113], v[170:171], s[8:9], v[112:113] op_sel_hi:[1,0,1]
	v_pk_fma_f32 v[114:115], v[168:169], s[8:9], v[114:115] op_sel_hi:[1,0,1]
	v_lshlrev_b32_e32 v160, 2, v160
	v_lshl_add_u64 v[164:165], s[78:79], 0, v[164:165]
	v_cvt_pk_bf16_f32 v112, v112, v113
	v_cvt_pk_bf16_f32 v113, v114, v115
	ds_write_b64 v167, v[112:113]
	v_and_b32_e32 v114, 0xffff0000, v112
	v_lshlrev_b32_e32 v168, 16, v113
	ds_read_b64 v[170:171], v167 offset:16
	s_waitcnt lgkmcnt(0)
	v_lshlrev_b32_e32 v172, 16, v170
	v_and_b32_e32 v173, 0xffff0000, v170
	v_lshlrev_b32_e32 v170, 16, v171
	v_and_b32_e32 v171, 0xffff0000, v171
	v_pk_fma_f32 v[116:117], v[172:173], s[8:9], v[116:117] op_sel_hi:[1,0,1]
	v_pk_fma_f32 v[118:119], v[170:171], s[8:9], v[118:119] op_sel_hi:[1,0,1]
	v_cvt_pk_bf16_f32 v116, v116, v117
	v_cvt_pk_bf16_f32 v117, v118, v119
	ds_write_b64 v167, v[116:117] offset:16
	v_lshlrev_b32_e32 v118, 16, v117
	v_and_b32_e32 v119, 0xffff0000, v117
	v_lshlrev_b32_e32 v171, 16, v116
	v_and_b32_e32 v117, 0xffff0000, v116
	v_lshlrev_b32_e32 v170, 16, v112
	v_mov_b32_e32 v115, v171
	v_and_b32_e32 v116, 0xffff0000, v113
	v_mov_b32_e32 v169, v117
	v_pk_mul_f32 v[172:173], v[170:171], v[170:171]
	v_pk_mul_f32 v[174:175], v[114:115], v[114:115]
	v_pk_add_f32 v[114:115], v[170:171], v[114:115]
	v_pk_mul_f32 v[112:113], v[168:169], v[168:169]
	v_pk_mul_f32 v[176:177], v[116:117], v[116:117]
	v_pk_add_f32 v[168:169], v[116:117], v[168:169]
	v_mul_f32_e32 v178, v118, v118
	v_mov_b32_e32 v115, v173
	v_mov_b32_e32 v169, v177
	v_pk_fma_f32 v[178:179], v[118:119], v[118:119], v[178:179] op_sel_hi:[1,1,0]
	ds_read_b64 v[180:181], v167 offset:32
	s_waitcnt lgkmcnt(0)
	v_lshlrev_b32_e32 v182, 16, v180
	v_and_b32_e32 v183, 0xffff0000, v180
	v_lshlrev_b32_e32 v180, 16, v181
	v_and_b32_e32 v181, 0xffff0000, v181
	v_pk_fma_f32 v[120:121], v[182:183], s[8:9], v[120:121] op_sel_hi:[1,0,1]
	v_pk_fma_f32 v[122:123], v[180:181], s[8:9], v[122:123] op_sel_hi:[1,0,1]
	v_cvt_pk_bf16_f32 v120, v120, v121
	v_cvt_pk_bf16_f32 v121, v122, v123
	ds_write_b64 v167, v[120:121] offset:32
	v_lshlrev_b32_e32 v122, 16, v120
	v_and_b32_e32 v120, 0xffff0000, v120
	v_lshlrev_b32_e32 v180, 16, v121
	v_and_b32_e32 v182, 0xffff0000, v121
	v_mul_f32_e32 v123, v122, v122
	v_mul_f32_e32 v121, v120, v120
	v_mul_f32_e32 v181, v180, v180
	v_mul_f32_e32 v183, v182, v182
	ds_read_b64 v[184:185], v167 offset:48
	s_waitcnt lgkmcnt(0)
	v_lshlrev_b32_e32 v186, 16, v184
	v_and_b32_e32 v187, 0xffff0000, v184
	v_lshlrev_b32_e32 v184, 16, v185
	v_and_b32_e32 v185, 0xffff0000, v185
	v_pk_fma_f32 v[124:125], v[186:187], s[8:9], v[124:125] op_sel_hi:[1,0,1]
	v_pk_fma_f32 v[126:127], v[184:185], s[8:9], v[126:127] op_sel_hi:[1,0,1]
	v_cvt_pk_bf16_f32 v124, v124, v125
	v_cvt_pk_bf16_f32 v125, v126, v127
	ds_write_b64 v167, v[124:125] offset:48
	v_lshlrev_b32_e32 v126, 16, v124
	v_and_b32_e32 v124, 0xffff0000, v124
	v_lshlrev_b32_e32 v184, 16, v125
	v_and_b32_e32 v186, 0xffff0000, v125
	v_mul_f32_e32 v127, v126, v126
	v_mul_f32_e32 v125, v124, v124
	v_mul_f32_e32 v185, v184, v184
	v_mul_f32_e32 v187, v186, v186
	ds_read_b64 v[188:189], v167 offset:64
	s_waitcnt lgkmcnt(0)
	v_lshlrev_b32_e32 v190, 16, v188
	v_and_b32_e32 v191, 0xffff0000, v188
	v_lshlrev_b32_e32 v188, 16, v189
	v_and_b32_e32 v189, 0xffff0000, v189
	v_pk_fma_f32 v[96:97], v[190:191], s[8:9], v[96:97] op_sel_hi:[1,0,1]
	v_pk_fma_f32 v[98:99], v[188:189], s[8:9], v[98:99] op_sel_hi:[1,0,1]
	v_cvt_pk_bf16_f32 v96, v96, v97
	v_cvt_pk_bf16_f32 v97, v98, v99
	ds_write_b64 v167, v[96:97] offset:64
	v_lshlrev_b32_e32 v98, 16, v96
	v_and_b32_e32 v96, 0xffff0000, v96
	v_lshlrev_b32_e32 v188, 16, v97
	v_and_b32_e32 v190, 0xffff0000, v97
	v_mul_f32_e32 v99, v98, v98
	v_mul_f32_e32 v97, v96, v96
	v_mul_f32_e32 v189, v188, v188
	v_mul_f32_e32 v191, v190, v190
	ds_read_b64 v[194:195], v167 offset:80
	s_waitcnt lgkmcnt(0)
; DI unsigned pack2(float a, float b) { f32x2_t v = {a, b}; bf16x2_t r = __builtin_convertvector(v, bf16x2_t); return __builtin_bit_cast(unsigned, r); }
; DI float bflo(unsigned u) { return __uint_as_float(u << 16); }
; DI float bfhi(unsigned u) { return __uint_as_float(u & 0xffff0000u); }
; DI float shx(float v, int m) { return __shfl_xor(v, m, 64); }
; template <bool XF32>
; DI void phase_outproj(const Params& P, int layer, const void* xres, const bf16_t* og, unsigned char* smem, int L, int G) {
;     ...
; #pragma unroll
;     for (int j = 0; j < 2; ++j)
; #pragma unroll
;       for (int ch = 0; ch < 2; ++ch) {
;         float s1 = 0.f, s2 = 0.f;
; #pragma unroll
;         for (int i = 2 * ch; i < 2 * ch + 2; ++i)
; #pragma unroll
;           for (int q4 = 0; q4 < 4; ++q4) {
;             uint2* pp = (uint2*)(stg + (wn * 64 + j * 32 + r) * STG + wm * 128 + i * 32 + 8 * q4 + 4 * h);
;             const uint2 xv = *pp;
;             uint2 pk;
;             pk.x = pack2(DN_ALPHA * bflo(xv.x) + acc[i][j][4 * q4], DN_ALPHA * bfhi(xv.x) + acc[i][j][4 * q4 + 1]);
;             pk.y = pack2(DN_ALPHA * bflo(xv.y) + acc[i][j][4 * q4 + 2], DN_ALPHA * bfhi(xv.y) + acc[i][j][4 * q4 + 3]);
;             *pp = pk;
;             const float f0 = bflo(pk.x), f1 = bfhi(pk.x), f2 = bflo(pk.y), f3 = bfhi(pk.y);
;             s1 += (f0 + f1) + (f2 + f3); s2 += (f0 * f0 + f1 * f1) + (f2 * f2 + f3 * f3);
;             __builtin_amdgcn_sched_barrier(0);
;           }
;         s1 += shx(s1, 32); s2 += shx(s2, 32);
;         if (h == 0) {
;           const size_t row = (size_t)(mt * 256 + wn * 64 + j * 32 + r);
;           *(float2*)(stats + row * 32 + (nt * 4 + wm * 2 + ch) * 2) = make_float2(s1, s2);
;         }
;       }
	v_lshlrev_b32_e32 v196, 16, v194
	v_and_b32_e32 v197, 0xffff0000, v194
	v_lshlrev_b32_e32 v194, 16, v195
	v_and_b32_e32 v195, 0xffff0000, v195
	v_pk_fma_f32 v[100:101], v[196:197], s[8:9], v[100:101] op_sel_hi:[1,0,1]
	v_pk_fma_f32 v[102:103], v[194:195], s[8:9], v[102:103] op_sel_hi:[1,0,1]
	v_cvt_pk_bf16_f32 v100, v100, v101
	v_cvt_pk_bf16_f32 v101, v102, v103
	ds_write_b64 v167, v[100:101] offset:80
	v_lshlrev_b32_e32 v102, 16, v100
	v_and_b32_e32 v100, 0xffff0000, v100
	v_lshlrev_b32_e32 v194, 16, v101
	v_and_b32_e32 v196, 0xffff0000, v101
	v_mul_f32_e32 v101, v100, v100
	v_mul_f32_e32 v103, v102, v102
	v_mul_f32_e32 v195, v194, v194
	v_mul_f32_e32 v197, v196, v196
	ds_read_b64 v[198:199], v167 offset:96
	s_waitcnt lgkmcnt(0)
	v_lshlrev_b32_e32 v200, 16, v198
	v_and_b32_e32 v201, 0xffff0000, v198
	v_lshlrev_b32_e32 v198, 16, v199
	v_and_b32_e32 v199, 0xffff0000, v199
	v_pk_fma_f32 v[104:105], v[200:201], s[8:9], v[104:105] op_sel_hi:[1,0,1]
	v_pk_fma_f32 v[106:107], v[198:199], s[8:9], v[106:107] op_sel_hi:[1,0,1]
	v_cvt_pk_bf16_f32 v104, v104, v105
	v_cvt_pk_bf16_f32 v105, v106, v107
	ds_write_b64 v167, v[104:105] offset:96
	v_lshlrev_b32_e32 v106, 16, v104
	v_and_b32_e32 v104, 0xffff0000, v104
	v_lshlrev_b32_e32 v198, 16, v105
	v_and_b32_e32 v200, 0xffff0000, v105
	v_mul_f32_e32 v107, v106, v106
	v_mul_f32_e32 v105, v104, v104
	v_mul_f32_e32 v199, v198, v198
	v_mul_f32_e32 v201, v200, v200
	v_pk_mov_b32 v[170:171], v[170:171], v[172:173] op_sel:[1,0]
	v_pk_mov_b32 v[116:117], v[116:117], v[174:175] op_sel:[1,0]
	ds_read_b64 v[202:203], v167 offset:112
	v_pk_add_f32 v[116:117], v[170:171], v[116:117]
	v_mov_b32_e32 v170, v118
	v_mov_b32_e32 v171, v112
	v_pk_mov_b32 v[112:113], v[118:119], v[176:177] op_sel:[1,0]
	v_pk_add_f32 v[114:115], v[114:115], v[168:169]
	v_pk_add_f32 v[112:113], v[170:171], v[112:113]
	v_mov_b32_e32 v178, v161
	v_pk_add_f32 v[112:113], v[116:117], v[112:113]
	v_pk_add_f32 v[114:115], v[114:115], v[178:179]
	v_pk_add_f32 v[116:117], v[180:181], v[182:183]
	v_pk_add_f32 v[112:113], v[112:113], v[114:115]
	v_pk_add_f32 v[114:115], v[122:123], v[120:121]
	s_waitcnt lgkmcnt(0)
	v_lshlrev_b32_e32 v204, 16, v202
	v_pk_add_f32 v[114:115], v[114:115], v[116:117]
	v_pk_add_f32 v[116:117], v[184:185], v[186:187]
	v_pk_add_f32 v[112:113], v[112:113], v[114:115]
	v_pk_add_f32 v[114:115], v[126:127], v[124:125]
	v_and_b32_e32 v205, 0xffff0000, v202
	v_lshlrev_b32_e32 v202, 16, v203
	v_and_b32_e32 v203, 0xffff0000, v203
	v_pk_add_f32 v[114:115], v[114:115], v[116:117]
	v_pk_add_f32 v[96:97], v[98:99], v[96:97]
	v_pk_add_f32 v[98:99], v[188:189], v[190:191]
	v_pk_fma_f32 v[108:109], v[204:205], s[8:9], v[108:109] op_sel_hi:[1,0,1]
	v_pk_fma_f32 v[110:111], v[202:203], s[8:9], v[110:111] op_sel_hi:[1,0,1]
	v_pk_add_f32 v[112:113], v[112:113], v[114:115]
	v_pk_add_f32 v[96:97], v[96:97], v[98:99]
	v_pk_add_f32 v[98:99], v[102:103], v[100:101]
	v_pk_add_f32 v[100:101], v[194:195], v[196:197]
	v_cvt_pk_bf16_f32 v108, v108, v109
	v_cvt_pk_bf16_f32 v109, v110, v111
	v_pk_add_f32 v[96:97], v[112:113], v[96:97]
	v_pk_add_f32 v[98:99], v[98:99], v[100:101]
	ds_write_b64 v167, v[108:109] offset:112
	v_lshlrev_b32_e32 v110, 16, v108
	v_and_b32_e32 v108, 0xffff0000, v108
	v_lshlrev_b32_e32 v202, 16, v109
	v_and_b32_e32 v204, 0xffff0000, v109
	v_pk_add_f32 v[96:97], v[96:97], v[98:99]
	v_pk_add_f32 v[98:99], v[106:107], v[104:105]
	v_pk_add_f32 v[100:101], v[198:199], v[200:201]
	v_mul_f32_e32 v111, v110, v110
	v_mul_f32_e32 v109, v108, v108
	v_mul_f32_e32 v203, v202, v202
	v_mul_f32_e32 v205, v204, v204
	v_pk_add_f32 v[98:99], v[98:99], v[100:101]
	v_pk_add_f32 v[100:101], v[202:203], v[204:205]
	v_pk_add_f32 v[96:97], v[96:97], v[98:99]
	v_pk_add_f32 v[98:99], v[110:111], v[108:109]
	s_nop 0
	v_pk_add_f32 v[98:99], v[98:99], v[100:101]
	s_nop 0
	v_pk_add_f32 v[98:99], v[96:97], v[98:99]
	ds_bpermute_b32 v100, v160, v98
	ds_bpermute_b32 v101, v160, v99
	v_lshlrev_b32_e32 v96, 1, v193
	v_ashrrev_i32_e32 v97, 31, v96
	s_and_saveexec_b64 s[14:15], vcc
	s_cbranch_execz .LBB0_1733
	v_lshl_add_u64 v[102:103], v[96:97], 2, v[164:165]
	s_waitcnt lgkmcnt(0)
	v_pk_add_f32 v[98:99], v[98:99], v[100:101]
	global_store_dwordx2 v[102:103], v[98:99], off

; DI unsigned pack2(float a, float b) { f32x2_t v = {a, b}; bf16x2_t r = __builtin_convertvector(v, bf16x2_t); return __builtin_bit_cast(unsigned, r); }
; DI float sigmoidf_(float x) { return __builtin_amdgcn_rcpf(1.f + __expf(-x)); }
; template <bool LAST>
; DI void phase_gate(const Params& P, int layer, unsigned char* smem, int L, int G) {
;     ...
;     unsigned gq[4][2][8];
; #pragma unroll
;     for (int i = 0; i < 4; ++i)
; #pragma unroll
;       for (int q4 = 0; q4 < 4; ++q4) {
;         const int fl = wm * 128 + i * 32 + 8 * q4 + 4 * h;
;         const f32x4 c1v = *(const f32x4*)(vecL + fl), c2v = *(const f32x4*)(vecL + 256 + fl);
;         const float c1a[4] = {c1v.x, c1v.y, c1v.z, c1v.w}, c2a[4] = {c2v.x, c2v.y, c2v.z, c2v.w};
; #pragma unroll
;         for (int j = 0; j < 2; ++j) {
;           const int lrow = wn * 64 + j * 32 + r;
;           const float mu = rowA[lrow], rstd = rowB[lrow];
;           float sg4[4];
; #pragma unroll
;           for (int e = 0; e < 4; ++e) sg4[e] = sigmoidf_(rstd * (accu[i][j][4 * q4 + e] - mu * c1a[e]) + c2a[e]);
;           gq[i][j][2 * q4] = pack2(sg4[0], sg4[1]); gq[i][j][2 * q4 + 1] = pack2(sg4[2], sg4[3]);
;         }
;         __builtin_amdgcn_sched_barrier(0);
;       }
.LBB0_1801:
	v_lshrrev_b32_e32 v160, 1, v163
	v_lshrrev_b32_e32 v163, 3, v163
	v_and_b32_e32 v163, 4, v163
	v_and_or_b32 v160, v160, s33, v163
	v_lshlrev_b32_e32 v160, 2, v160
	v_add_u32_e32 v163, 0x24800, v160
	v_add_u32_e32 v164, 0x24c00, v160
	v_and_b32_e32 v167, 0x37c, v168
	ds_read_b128 v[170:173], v163
	ds_read_b128 v[174:177], v164
	v_or_b32_e32 v164, 0x24000, v167
	v_or_b32_e32 v166, 0x24080, v167
	v_or_b32_e32 v165, 0x24400, v167
	ds_read_b32 v168, v164
	ds_read_b32 v169, v165
	v_or_b32_e32 v167, 0x24480, v167
	ds_read_b32 v178, v166
	ds_read_b32 v179, v167
	s_waitcnt lgkmcnt(3)
	v_fma_f32 v112, -v170, v168, v112
	v_fma_f32 v113, -v171, v168, v113
	s_waitcnt lgkmcnt(1)
	v_fma_f32 v98, -v172, v178, v98
	v_fma_f32 v114, -v172, v168, v114
	v_fma_f32 v115, -v173, v168, v115
	v_fma_f32 v96, -v170, v178, v96
	v_fma_f32 v97, -v171, v178, v97
	s_waitcnt lgkmcnt(0)
	v_fma_f32 v98, v179, v98, v176
	v_fma_f32 v99, -v173, v178, v99
	v_fma_f32 v112, v169, v112, v174
	v_fma_f32 v113, v169, v113, v175
	v_fma_f32 v114, v169, v114, v176
	v_fma_f32 v115, v169, v115, v177
	v_fma_f32 v96, v179, v96, v174
	v_fma_f32 v97, v179, v97, v175
	v_mul_f32_e32 v98, 0xbfb8aa3b, v98
	v_fmac_f32_e32 v177, v179, v99
	v_mul_f32_e32 v112, 0xbfb8aa3b, v112
	v_mul_f32_e32 v113, 0xbfb8aa3b, v113
	v_mul_f32_e32 v114, 0xbfb8aa3b, v114
	v_mul_f32_e32 v115, 0xbfb8aa3b, v115
	v_mul_f32_e32 v96, 0xbfb8aa3b, v96
	v_mul_f32_e32 v97, 0xbfb8aa3b, v97
	v_exp_f32_e32 v98, v98
	v_mul_f32_e32 v99, 0xbfb8aa3b, v177
	v_exp_f32_e32 v112, v112
	v_exp_f32_e32 v113, v113
	v_exp_f32_e32 v114, v114
	v_exp_f32_e32 v115, v115
	v_exp_f32_e32 v96, v96
	v_exp_f32_e32 v97, v97
	v_exp_f32_e32 v99, v99
	v_add_f32_e32 v98, 1.0, v98
	v_add_f32_e32 v112, 1.0, v112
	v_add_f32_e32 v113, 1.0, v113
	v_add_f32_e32 v114, 1.0, v114
	v_add_f32_e32 v115, 1.0, v115
	v_add_f32_e32 v96, 1.0, v96
	v_add_f32_e32 v97, 1.0, v97
	v_rcp_f32_e32 v168, v98
	v_add_f32_e32 v98, 1.0, v99
	v_rcp_f32_e32 v112, v112
	v_rcp_f32_e32 v113, v113
	v_rcp_f32_e32 v114, v114
	v_rcp_f32_e32 v115, v115
	v_rcp_f32_e32 v96, v96
	v_rcp_f32_e32 v97, v97
	v_rcp_f32_e32 v169, v98
	v_cvt_pk_bf16_f32 v99, v112, v113
	v_cvt_pk_bf16_f32 v98, v114, v115
	v_cvt_pk_bf16_f32 v97, v96, v97
	v_cvt_pk_bf16_f32 v96, v168, v169
	v_add_u32_e32 v112, 0x24820, v160
	v_add_u32_e32 v168, 0x24c20, v160
	ds_read_b128 v[112:115], v112
	ds_read_b128 v[168:171], v168
	ds_read_b32 v172, v164
	ds_read_b32 v173, v165
	ds_read_b32 v174, v166
	ds_read_b32 v175, v167
	s_waitcnt lgkmcnt(3)
	v_fma_f32 v116, -v112, v172, v116
	v_fma_f32 v117, -v113, v172, v117
	s_waitcnt lgkmcnt(1)
	v_fma_f32 v102, -v114, v174, v102
	v_fma_f32 v118, -v114, v172, v118
	v_fma_f32 v119, -v115, v172, v119
	v_fma_f32 v100, -v112, v174, v100
	v_fma_f32 v101, -v113, v174, v101
	s_waitcnt lgkmcnt(0)
	v_fma_f32 v102, v175, v102, v170
	v_fma_f32 v103, -v115, v174, v103
	v_fma_f32 v116, v173, v116, v168
	v_fma_f32 v117, v173, v117, v169
	v_fma_f32 v118, v173, v118, v170
	v_fma_f32 v119, v173, v119, v171
	v_fma_f32 v100, v175, v100, v168
	v_fma_f32 v101, v175, v101, v169
	v_mul_f32_e32 v102, 0xbfb8aa3b, v102
	v_fmac_f32_e32 v171, v175, v103
	v_mul_f32_e32 v116, 0xbfb8aa3b, v116
	v_mul_f32_e32 v117, 0xbfb8aa3b, v117
	v_mul_f32_e32 v118, 0xbfb8aa3b, v118
	v_mul_f32_e32 v119, 0xbfb8aa3b, v119
	v_mul_f32_e32 v100, 0xbfb8aa3b, v100
	v_mul_f32_e32 v101, 0xbfb8aa3b, v101
	v_exp_f32_e32 v102, v102
	v_mul_f32_e32 v103, 0xbfb8aa3b, v171
	v_exp_f32_e32 v116, v116
	v_exp_f32_e32 v117, v117
	v_exp_f32_e32 v118, v118
	v_exp_f32_e32 v119, v119
	v_exp_f32_e32 v100, v100
	v_exp_f32_e32 v101, v101
	v_exp_f32_e32 v103, v103
	v_add_f32_e32 v102, 1.0, v102
	v_add_f32_e32 v116, 1.0, v116
	v_add_f32_e32 v117, 1.0, v117
	v_add_f32_e32 v118, 1.0, v118
	v_add_f32_e32 v119, 1.0, v119
	v_add_f32_e32 v100, 1.0, v100
	v_add_f32_e32 v101, 1.0, v101
	v_rcp_f32_e32 v113, v102
	v_add_f32_e32 v102, 1.0, v103
	v_rcp_f32_e32 v116, v116
	v_rcp_f32_e32 v117, v117
	v_rcp_f32_e32 v118, v118
	v_rcp_f32_e32 v112, v119
	v_rcp_f32_e32 v100, v100
	v_rcp_f32_e32 v101, v101
	v_rcp_f32_e32 v114, v102
	v_cvt_pk_bf16_f32 v103, v116, v117
	v_cvt_pk_bf16_f32 v102, v118, v112
	v_cvt_pk_bf16_f32 v101, v100, v101
	v_cvt_pk_bf16_f32 v100, v113, v114
	v_add_u32_e32 v112, 0x24840, v160
	v_add_u32_e32 v116, 0x24c40, v160
	ds_read_b128 v[112:115], v112
	ds_read_b128 v[116:119], v116
	ds_read_b32 v168, v164
	ds_read_b32 v169, v165
	ds_read_b32 v170, v166
	ds_read_b32 v171, v167
	s_waitcnt lgkmcnt(3)
	v_fma_f32 v120, -v112, v168, v120
	v_fma_f32 v121, -v113, v168, v121
	s_waitcnt lgkmcnt(1)
	v_fma_f32 v106, -v114, v170, v106
	v_fma_f32 v122, -v114, v168, v122
	v_fma_f32 v123, -v115, v168, v123
	v_fma_f32 v104, -v112, v170, v104
	v_fma_f32 v105, -v113, v170, v105
	s_waitcnt lgkmcnt(0)
	v_fma_f32 v106, v171, v106, v118
	v_fma_f32 v107, -v115, v170, v107
	v_fma_f32 v120, v169, v120, v116
	v_fma_f32 v121, v169, v121, v117
	v_fma_f32 v122, v169, v122, v118
	v_fma_f32 v123, v169, v123, v119
	v_fma_f32 v104, v171, v104, v116
	v_fma_f32 v105, v171, v105, v117
	v_mul_f32_e32 v106, 0xbfb8aa3b, v106
	v_fmac_f32_e32 v119, v171, v107
	v_mul_f32_e32 v120, 0xbfb8aa3b, v120
	v_mul_f32_e32 v121, 0xbfb8aa3b, v121
	v_mul_f32_e32 v122, 0xbfb8aa3b, v122
	v_mul_f32_e32 v123, 0xbfb8aa3b, v123
	v_mul_f32_e32 v104, 0xbfb8aa3b, v104
	v_mul_f32_e32 v105, 0xbfb8aa3b, v105
	v_exp_f32_e32 v106, v106
	v_mul_f32_e32 v107, 0xbfb8aa3b, v119
	v_exp_f32_e32 v120, v120
	v_exp_f32_e32 v121, v121
	v_exp_f32_e32 v122, v122
	v_exp_f32_e32 v123, v123
	v_exp_f32_e32 v104, v104
	v_exp_f32_e32 v105, v105
	v_exp_f32_e32 v107, v107
	v_add_f32_e32 v106, 1.0, v106
	v_add_f32_e32 v120, 1.0, v120
	v_add_f32_e32 v121, 1.0, v121
	v_add_f32_e32 v122, 1.0, v122
	v_add_f32_e32 v123, 1.0, v123
	v_add_f32_e32 v104, 1.0, v104
	v_add_f32_e32 v105, 1.0, v105
	v_rcp_f32_e32 v113, v106
	v_add_f32_e32 v106, 1.0, v107
	v_rcp_f32_e32 v120, v120
	v_rcp_f32_e32 v121, v121
	v_rcp_f32_e32 v122, v122
	v_rcp_f32_e32 v112, v123
	v_rcp_f32_e32 v104, v104
	v_rcp_f32_e32 v105, v105
	v_rcp_f32_e32 v114, v106
	v_cvt_pk_bf16_f32 v107, v120, v121
	v_cvt_pk_bf16_f32 v106, v122, v112
	v_cvt_pk_bf16_f32 v105, v104, v105
	v_cvt_pk_bf16_f32 v104, v113, v114
	v_add_u32_e32 v112, 0x24860, v160
	v_add_u32_e32 v116, 0x24c60, v160
	ds_read_b128 v[112:115], v112
	ds_read_b128 v[116:119], v116
	ds_read_b32 v120, v164
	ds_read_b32 v121, v165
	ds_read_b32 v122, v166
	ds_read_b32 v123, v167
	s_waitcnt lgkmcnt(3)
; DI unsigned pack2(float a, float b) { f32x2_t v = {a, b}; bf16x2_t r = __builtin_convertvector(v, bf16x2_t); return __builtin_bit_cast(unsigned, r); }
; DI float sigmoidf_(float x) { return __builtin_amdgcn_rcpf(1.f + __expf(-x)); }
; template <bool LAST>
; DI void phase_gate(const Params& P, int layer, unsigned char* smem, int L, int G) {
;     ...
;     unsigned gq[4][2][8];
; #pragma unroll
;     for (int i = 0; i < 4; ++i)
; #pragma unroll
;       for (int q4 = 0; q4 < 4; ++q4) {
;         const int fl = wm * 128 + i * 32 + 8 * q4 + 4 * h;
;         const f32x4 c1v = *(const f32x4*)(vecL + fl), c2v = *(const f32x4*)(vecL + 256 + fl);
;         const float c1a[4] = {c1v.x, c1v.y, c1v.z, c1v.w}, c2a[4] = {c2v.x, c2v.y, c2v.z, c2v.w};
; #pragma unroll
;         for (int j = 0; j < 2; ++j) {
;           const int lrow = wn * 64 + j * 32 + r;
;           const float mu = rowA[lrow], rstd = rowB[lrow];
;           float sg4[4];
; #pragma unroll
;           for (int e = 0; e < 4; ++e) sg4[e] = sigmoidf_(rstd * (accu[i][j][4 * q4 + e] - mu * c1a[e]) + c2a[e]);
;           gq[i][j][2 * q4] = pack2(sg4[0], sg4[1]); gq[i][j][2 * q4 + 1] = pack2(sg4[2], sg4[3]);
;         }
;         __builtin_amdgcn_sched_barrier(0);
;       }
	v_fma_f32 v125, -v113, v120, v125
	v_fma_f32 v124, -v112, v120, v124
	s_waitcnt lgkmcnt(1)
	v_fma_f32 v110, -v114, v122, v110
	v_fma_f32 v125, v121, v125, v117
	v_fma_f32 v126, -v114, v120, v126
	v_fma_f32 v120, -v115, v120, v127
	v_fma_f32 v108, -v112, v122, v108
	v_fma_f32 v109, -v113, v122, v109
	s_waitcnt lgkmcnt(0)
	v_fma_f32 v110, v123, v110, v118
	v_fma_f32 v111, -v115, v122, v111
	v_fma_f32 v124, v121, v124, v116
	v_mul_f32_e32 v125, 0xbfb8aa3b, v125
	v_fma_f32 v126, v121, v126, v118
	v_fma_f32 v120, v121, v120, v119
	v_fma_f32 v108, v123, v108, v116
	v_fma_f32 v109, v123, v109, v117
	v_mul_f32_e32 v110, 0xbfb8aa3b, v110
	v_fmac_f32_e32 v119, v123, v111
	v_mul_f32_e32 v124, 0xbfb8aa3b, v124
	v_exp_f32_e32 v125, v125
	v_mul_f32_e32 v126, 0xbfb8aa3b, v126
	v_mul_f32_e32 v120, 0xbfb8aa3b, v120
	v_mul_f32_e32 v108, 0xbfb8aa3b, v108
	v_mul_f32_e32 v109, 0xbfb8aa3b, v109
	v_exp_f32_e32 v110, v110
	v_mul_f32_e32 v111, 0xbfb8aa3b, v119
	v_exp_f32_e32 v124, v124
	v_exp_f32_e32 v126, v126
	v_exp_f32_e32 v120, v120
	v_exp_f32_e32 v108, v108
	v_exp_f32_e32 v109, v109
	v_exp_f32_e32 v111, v111
	v_add_f32_e32 v125, 1.0, v125
	v_add_f32_e32 v110, 1.0, v110
	v_add_f32_e32 v124, 1.0, v124
	v_rcp_f32_e32 v121, v125
	v_add_f32_e32 v125, 1.0, v126
	v_add_f32_e32 v120, 1.0, v120
	v_add_f32_e32 v108, 1.0, v108
	v_add_f32_e32 v109, 1.0, v109
	v_rcp_f32_e32 v113, v110
	v_add_f32_e32 v110, 1.0, v111
	v_rcp_f32_e32 v124, v124
	v_rcp_f32_e32 v125, v125
	v_rcp_f32_e32 v112, v120
	v_rcp_f32_e32 v108, v108
	v_rcp_f32_e32 v109, v109
	v_rcp_f32_e32 v114, v110
	v_cvt_pk_bf16_f32 v111, v124, v121
	v_cvt_pk_bf16_f32 v110, v125, v112
	v_cvt_pk_bf16_f32 v109, v108, v109
	v_cvt_pk_bf16_f32 v108, v113, v114
	v_add_u32_e32 v112, 0x24880, v160
	v_add_u32_e32 v116, 0x24c80, v160
	ds_read_b128 v[112:115], v112
	ds_read_b128 v[116:119], v116
	ds_read_b32 v120, v164
	ds_read_b32 v121, v165
	ds_read_b32 v122, v166
	ds_read_b32 v123, v167
	s_waitcnt lgkmcnt(3)
	v_fma_f32 v80, -v112, v120, v80
	v_fma_f32 v81, -v113, v120, v81
	s_waitcnt lgkmcnt(1)
	v_fma_f32 v66, -v114, v122, v66
	v_fma_f32 v82, -v114, v120, v82
	v_fma_f32 v83, -v115, v120, v83
	v_fma_f32 v64, -v112, v122, v64
	v_fma_f32 v65, -v113, v122, v65
	s_waitcnt lgkmcnt(0)
	v_fma_f32 v66, v123, v66, v118
	v_fma_f32 v67, -v115, v122, v67
	v_fma_f32 v80, v121, v80, v116
	v_fma_f32 v81, v121, v81, v117
	v_fma_f32 v82, v121, v82, v118
	v_fma_f32 v83, v121, v83, v119
	v_fma_f32 v64, v123, v64, v116
	v_fma_f32 v65, v123, v65, v117
	v_mul_f32_e32 v66, 0xbfb8aa3b, v66
	v_fmac_f32_e32 v119, v123, v67
	v_mul_f32_e32 v80, 0xbfb8aa3b, v80
	v_mul_f32_e32 v81, 0xbfb8aa3b, v81
	v_mul_f32_e32 v82, 0xbfb8aa3b, v82
	v_mul_f32_e32 v83, 0xbfb8aa3b, v83
	v_mul_f32_e32 v64, 0xbfb8aa3b, v64
	v_mul_f32_e32 v65, 0xbfb8aa3b, v65
	v_exp_f32_e32 v66, v66
	v_mul_f32_e32 v67, 0xbfb8aa3b, v119
	v_exp_f32_e32 v80, v80
	v_exp_f32_e32 v81, v81
	v_exp_f32_e32 v82, v82
	v_exp_f32_e32 v83, v83
	v_exp_f32_e32 v64, v64
	v_exp_f32_e32 v65, v65
	v_exp_f32_e32 v67, v67
	v_add_f32_e32 v66, 1.0, v66
	v_add_f32_e32 v80, 1.0, v80
	v_add_f32_e32 v81, 1.0, v81
	v_add_f32_e32 v82, 1.0, v82
	v_add_f32_e32 v83, 1.0, v83
	v_add_f32_e32 v64, 1.0, v64
	v_add_f32_e32 v65, 1.0, v65
	v_rcp_f32_e32 v112, v66
	v_add_f32_e32 v66, 1.0, v67
	v_rcp_f32_e32 v80, v80
	v_rcp_f32_e32 v81, v81
	v_rcp_f32_e32 v82, v82
	v_rcp_f32_e32 v83, v83
	v_rcp_f32_e32 v64, v64
	v_rcp_f32_e32 v65, v65
	v_rcp_f32_e32 v113, v66
	v_cvt_pk_bf16_f32 v67, v80, v81
	v_cvt_pk_bf16_f32 v66, v82, v83
	v_cvt_pk_bf16_f32 v65, v64, v65
	v_cvt_pk_bf16_f32 v64, v112, v113
	v_add_u32_e32 v80, 0x248a0, v160
	v_add_u32_e32 v112, 0x24ca0, v160
	ds_read_b128 v[80:83], v80
	ds_read_b128 v[112:115], v112
	ds_read_b32 v116, v164
	ds_read_b32 v117, v165
	ds_read_b32 v118, v166
	ds_read_b32 v119, v167
	s_waitcnt lgkmcnt(3)
	v_fma_f32 v84, -v80, v116, v84
	v_fma_f32 v85, -v81, v116, v85
	s_waitcnt lgkmcnt(1)
	v_fma_f32 v70, -v82, v118, v70
	v_fma_f32 v86, -v82, v116, v86
	v_fma_f32 v87, -v83, v116, v87
	v_fma_f32 v68, -v80, v118, v68
	v_fma_f32 v69, -v81, v118, v69
	s_waitcnt lgkmcnt(0)
	v_fma_f32 v70, v119, v70, v114
	v_fma_f32 v71, -v83, v118, v71
	v_fma_f32 v84, v117, v84, v112
	v_fma_f32 v85, v117, v85, v113
	v_fma_f32 v86, v117, v86, v114
	v_fma_f32 v87, v117, v87, v115
	v_fma_f32 v68, v119, v68, v112
	v_fma_f32 v69, v119, v69, v113
	v_mul_f32_e32 v70, 0xbfb8aa3b, v70
	v_fmac_f32_e32 v115, v119, v71
	v_mul_f32_e32 v84, 0xbfb8aa3b, v84
	v_mul_f32_e32 v85, 0xbfb8aa3b, v85
	v_mul_f32_e32 v86, 0xbfb8aa3b, v86
	v_mul_f32_e32 v87, 0xbfb8aa3b, v87
	v_mul_f32_e32 v68, 0xbfb8aa3b, v68
	v_mul_f32_e32 v69, 0xbfb8aa3b, v69
	v_exp_f32_e32 v70, v70
	v_mul_f32_e32 v71, 0xbfb8aa3b, v115
	v_exp_f32_e32 v84, v84
	v_exp_f32_e32 v85, v85
	v_exp_f32_e32 v86, v86
	v_exp_f32_e32 v87, v87
	v_exp_f32_e32 v68, v68
	v_exp_f32_e32 v69, v69
	v_exp_f32_e32 v71, v71
	v_add_f32_e32 v70, 1.0, v70
	v_add_f32_e32 v84, 1.0, v84
	v_add_f32_e32 v85, 1.0, v85
	v_add_f32_e32 v86, 1.0, v86
	v_add_f32_e32 v87, 1.0, v87
	v_add_f32_e32 v68, 1.0, v68
	v_add_f32_e32 v69, 1.0, v69
	v_rcp_f32_e32 v81, v70
	v_add_f32_e32 v70, 1.0, v71
	v_rcp_f32_e32 v84, v84
	v_rcp_f32_e32 v85, v85
	v_rcp_f32_e32 v86, v86
	v_rcp_f32_e32 v80, v87
	v_rcp_f32_e32 v68, v68
	v_rcp_f32_e32 v69, v69
	v_rcp_f32_e32 v82, v70
	v_cvt_pk_bf16_f32 v71, v84, v85
	v_cvt_pk_bf16_f32 v70, v86, v80
	v_cvt_pk_bf16_f32 v69, v68, v69
	v_cvt_pk_bf16_f32 v68, v81, v82
	v_add_u32_e32 v80, 0x248c0, v160
	v_add_u32_e32 v84, 0x24cc0, v160
	ds_read_b128 v[80:83], v80
	ds_read_b128 v[84:87], v84
	ds_read_b32 v112, v164
	ds_read_b32 v113, v165
	ds_read_b32 v114, v166
	ds_read_b32 v115, v167
	s_waitcnt lgkmcnt(3)
; DI unsigned pack2(float a, float b) { f32x2_t v = {a, b}; bf16x2_t r = __builtin_convertvector(v, bf16x2_t); return __builtin_bit_cast(unsigned, r); }
; DI float sigmoidf_(float x) { return __builtin_amdgcn_rcpf(1.f + __expf(-x)); }
; template <bool LAST>
; DI void phase_gate(const Params& P, int layer, unsigned char* smem, int L, int G) {
;     ...
;     unsigned gq[4][2][8];
; #pragma unroll
;     for (int i = 0; i < 4; ++i)
; #pragma unroll
;       for (int q4 = 0; q4 < 4; ++q4) {
;         const int fl = wm * 128 + i * 32 + 8 * q4 + 4 * h;
;         const f32x4 c1v = *(const f32x4*)(vecL + fl), c2v = *(const f32x4*)(vecL + 256 + fl);
;         const float c1a[4] = {c1v.x, c1v.y, c1v.z, c1v.w}, c2a[4] = {c2v.x, c2v.y, c2v.z, c2v.w};
; #pragma unroll
;         for (int j = 0; j < 2; ++j) {
;           const int lrow = wn * 64 + j * 32 + r;
;           const float mu = rowA[lrow], rstd = rowB[lrow];
;           float sg4[4];
; #pragma unroll
;           for (int e = 0; e < 4; ++e) sg4[e] = sigmoidf_(rstd * (accu[i][j][4 * q4 + e] - mu * c1a[e]) + c2a[e]);
;           gq[i][j][2 * q4] = pack2(sg4[0], sg4[1]); gq[i][j][2 * q4 + 1] = pack2(sg4[2], sg4[3]);
;         }
;         __builtin_amdgcn_sched_barrier(0);
;       }
	v_fma_f32 v88, -v80, v112, v88
	v_fma_f32 v89, -v81, v112, v89
	s_waitcnt lgkmcnt(1)
	v_fma_f32 v74, -v82, v114, v74
	v_fma_f32 v90, -v82, v112, v90
	v_fma_f32 v91, -v83, v112, v91
	v_fma_f32 v72, -v80, v114, v72
	v_fma_f32 v73, -v81, v114, v73
	s_waitcnt lgkmcnt(0)
	v_fma_f32 v74, v115, v74, v86
	v_fma_f32 v75, -v83, v114, v75
	v_fma_f32 v88, v113, v88, v84
	v_fma_f32 v89, v113, v89, v85
	v_fma_f32 v90, v113, v90, v86
	v_fma_f32 v91, v113, v91, v87
	v_fma_f32 v72, v115, v72, v84
	v_fma_f32 v73, v115, v73, v85
	v_mul_f32_e32 v74, 0xbfb8aa3b, v74
	v_fmac_f32_e32 v87, v115, v75
	v_mul_f32_e32 v88, 0xbfb8aa3b, v88
	v_mul_f32_e32 v89, 0xbfb8aa3b, v89
	v_mul_f32_e32 v90, 0xbfb8aa3b, v90
	v_mul_f32_e32 v91, 0xbfb8aa3b, v91
	v_mul_f32_e32 v72, 0xbfb8aa3b, v72
	v_mul_f32_e32 v73, 0xbfb8aa3b, v73
	v_exp_f32_e32 v74, v74
	v_mul_f32_e32 v75, 0xbfb8aa3b, v87
	v_exp_f32_e32 v88, v88
	v_exp_f32_e32 v89, v89
	v_exp_f32_e32 v90, v90
	v_exp_f32_e32 v91, v91
	v_exp_f32_e32 v72, v72
	v_exp_f32_e32 v73, v73
	v_exp_f32_e32 v75, v75
	v_add_f32_e32 v74, 1.0, v74
	v_add_f32_e32 v88, 1.0, v88
	v_add_f32_e32 v89, 1.0, v89
	v_add_f32_e32 v90, 1.0, v90
	v_add_f32_e32 v91, 1.0, v91
	v_add_f32_e32 v72, 1.0, v72
	v_add_f32_e32 v73, 1.0, v73
	v_rcp_f32_e32 v81, v74
	v_add_f32_e32 v74, 1.0, v75
	v_rcp_f32_e32 v88, v88
	v_rcp_f32_e32 v89, v89
	v_rcp_f32_e32 v90, v90
	v_rcp_f32_e32 v80, v91
	v_rcp_f32_e32 v72, v72
	v_rcp_f32_e32 v73, v73
	v_rcp_f32_e32 v82, v74
	v_cvt_pk_bf16_f32 v75, v88, v89
	v_cvt_pk_bf16_f32 v74, v90, v80
	v_cvt_pk_bf16_f32 v73, v72, v73
	v_cvt_pk_bf16_f32 v72, v81, v82
	v_add_u32_e32 v80, 0x248e0, v160
	v_add_u32_e32 v84, 0x24ce0, v160
	ds_read_b128 v[80:83], v80
	ds_read_b128 v[84:87], v84
	ds_read_b32 v88, v164
	ds_read_b32 v89, v165
	ds_read_b32 v90, v166
	ds_read_b32 v91, v167
	s_waitcnt lgkmcnt(3)
	v_fma_f32 v93, -v81, v88, v93
	v_fma_f32 v92, -v80, v88, v92
	s_waitcnt lgkmcnt(1)
	v_fma_f32 v78, -v82, v90, v78
	v_fma_f32 v93, v89, v93, v85
	v_fma_f32 v94, -v82, v88, v94
	v_fma_f32 v88, -v83, v88, v95
	v_fma_f32 v76, -v80, v90, v76
	v_fma_f32 v77, -v81, v90, v77
	s_waitcnt lgkmcnt(0)
	v_fma_f32 v78, v91, v78, v86
	v_fma_f32 v79, -v83, v90, v79
	v_fma_f32 v92, v89, v92, v84
	v_mul_f32_e32 v93, 0xbfb8aa3b, v93
	v_fma_f32 v94, v89, v94, v86
	v_fma_f32 v88, v89, v88, v87
	v_fma_f32 v76, v91, v76, v84
	v_fma_f32 v77, v91, v77, v85
	v_mul_f32_e32 v78, 0xbfb8aa3b, v78
	v_fmac_f32_e32 v87, v91, v79
	v_mul_f32_e32 v92, 0xbfb8aa3b, v92
	v_exp_f32_e32 v93, v93
	v_mul_f32_e32 v94, 0xbfb8aa3b, v94
	v_mul_f32_e32 v88, 0xbfb8aa3b, v88
	v_mul_f32_e32 v76, 0xbfb8aa3b, v76
	v_mul_f32_e32 v77, 0xbfb8aa3b, v77
	v_exp_f32_e32 v78, v78
	v_mul_f32_e32 v79, 0xbfb8aa3b, v87
	v_exp_f32_e32 v92, v92
	v_exp_f32_e32 v94, v94
	v_exp_f32_e32 v88, v88
	v_exp_f32_e32 v76, v76
	v_exp_f32_e32 v77, v77
	v_exp_f32_e32 v79, v79
	v_add_f32_e32 v93, 1.0, v93
	v_add_f32_e32 v78, 1.0, v78
	v_add_f32_e32 v92, 1.0, v92
	v_rcp_f32_e32 v89, v93
	v_add_f32_e32 v93, 1.0, v94
	v_add_f32_e32 v88, 1.0, v88
	v_add_f32_e32 v76, 1.0, v76
	v_add_f32_e32 v77, 1.0, v77
	v_rcp_f32_e32 v81, v78
	v_add_f32_e32 v78, 1.0, v79
	v_rcp_f32_e32 v92, v92
	v_rcp_f32_e32 v93, v93
	v_rcp_f32_e32 v80, v88
	v_rcp_f32_e32 v76, v76
	v_rcp_f32_e32 v77, v77
	v_rcp_f32_e32 v82, v78
	v_cvt_pk_bf16_f32 v79, v92, v89
	v_cvt_pk_bf16_f32 v78, v93, v80
	v_cvt_pk_bf16_f32 v77, v76, v77
	v_cvt_pk_bf16_f32 v76, v81, v82
	v_add_u32_e32 v80, 0x24900, v160
	v_add_u32_e32 v84, 0x24d00, v160
	ds_read_b128 v[80:83], v80
	ds_read_b128 v[84:87], v84
	ds_read_b32 v88, v164
	ds_read_b32 v89, v165
	ds_read_b32 v90, v166
	ds_read_b32 v91, v167
	s_waitcnt lgkmcnt(3)
	v_fma_f32 v48, -v80, v88, v48
	v_fma_f32 v49, -v81, v88, v49
	s_waitcnt lgkmcnt(1)
	v_fma_f32 v34, -v82, v90, v34
	v_fma_f32 v50, -v82, v88, v50
	v_fma_f32 v51, -v83, v88, v51
	v_fma_f32 v32, -v80, v90, v32
	v_fma_f32 v33, -v81, v90, v33
	s_waitcnt lgkmcnt(0)
	v_fma_f32 v34, v91, v34, v86
	v_fma_f32 v35, -v83, v90, v35
	v_fma_f32 v48, v89, v48, v84
	v_fma_f32 v49, v89, v49, v85
	v_fma_f32 v50, v89, v50, v86
	v_fma_f32 v51, v89, v51, v87
	v_fma_f32 v32, v91, v32, v84
	v_fma_f32 v33, v91, v33, v85
	v_mul_f32_e32 v34, 0xbfb8aa3b, v34
	v_fmac_f32_e32 v87, v91, v35
	v_mul_f32_e32 v48, 0xbfb8aa3b, v48
	v_mul_f32_e32 v49, 0xbfb8aa3b, v49
	v_mul_f32_e32 v50, 0xbfb8aa3b, v50
	v_mul_f32_e32 v51, 0xbfb8aa3b, v51
	v_mul_f32_e32 v32, 0xbfb8aa3b, v32
	v_mul_f32_e32 v33, 0xbfb8aa3b, v33
	v_exp_f32_e32 v34, v34
	v_mul_f32_e32 v35, 0xbfb8aa3b, v87
	v_exp_f32_e32 v48, v48
	v_exp_f32_e32 v49, v49
	v_exp_f32_e32 v50, v50
	v_exp_f32_e32 v51, v51
	v_exp_f32_e32 v32, v32
	v_exp_f32_e32 v33, v33
	v_exp_f32_e32 v35, v35
	v_add_f32_e32 v34, 1.0, v34
	v_add_f32_e32 v48, 1.0, v48
	v_add_f32_e32 v49, 1.0, v49
	v_add_f32_e32 v50, 1.0, v50
	v_add_f32_e32 v51, 1.0, v51
	v_add_f32_e32 v32, 1.0, v32
	v_add_f32_e32 v33, 1.0, v33
	v_rcp_f32_e32 v80, v34
	v_add_f32_e32 v34, 1.0, v35
	v_rcp_f32_e32 v48, v48
	v_rcp_f32_e32 v49, v49
	v_rcp_f32_e32 v50, v50
	v_rcp_f32_e32 v51, v51
	v_rcp_f32_e32 v32, v32
	v_rcp_f32_e32 v33, v33
	v_rcp_f32_e32 v81, v34
	v_cvt_pk_bf16_f32 v35, v48, v49
	v_cvt_pk_bf16_f32 v34, v50, v51
	v_cvt_pk_bf16_f32 v33, v32, v33
	v_cvt_pk_bf16_f32 v32, v80, v81
	v_add_u32_e32 v48, 0x24920, v160
	v_add_u32_e32 v80, 0x24d20, v160
	ds_read_b128 v[48:51], v48
	ds_read_b128 v[80:83], v80
	ds_read_b32 v84, v164
	ds_read_b32 v85, v165
	ds_read_b32 v86, v166
	ds_read_b32 v87, v167
	s_waitcnt lgkmcnt(3)
	v_fma_f32 v53, -v49, v84, v53
	v_fma_f32 v52, -v48, v84, v52
	s_waitcnt lgkmcnt(1)
	v_fma_f32 v36, -v48, v86, v36
	s_waitcnt lgkmcnt(0)
; DI unsigned pack2(float a, float b) { f32x2_t v = {a, b}; bf16x2_t r = __builtin_convertvector(v, bf16x2_t); return __builtin_bit_cast(unsigned, r); }
; DI float sigmoidf_(float x) { return __builtin_amdgcn_rcpf(1.f + __expf(-x)); }
; template <bool LAST>
; DI void phase_gate(const Params& P, int layer, unsigned char* smem, int L, int G) {
;     ...
;     unsigned gq[4][2][8];
; #pragma unroll
;     for (int i = 0; i < 4; ++i)
; #pragma unroll
;       for (int q4 = 0; q4 < 4; ++q4) {
;         const int fl = wm * 128 + i * 32 + 8 * q4 + 4 * h;
;         const f32x4 c1v = *(const f32x4*)(vecL + fl), c2v = *(const f32x4*)(vecL + 256 + fl);
;         const float c1a[4] = {c1v.x, c1v.y, c1v.z, c1v.w}, c2a[4] = {c2v.x, c2v.y, c2v.z, c2v.w};
; #pragma unroll
;         for (int j = 0; j < 2; ++j) {
;           const int lrow = wn * 64 + j * 32 + r;
;           const float mu = rowA[lrow], rstd = rowB[lrow];
;           float sg4[4];
; #pragma unroll
;           for (int e = 0; e < 4; ++e) sg4[e] = sigmoidf_(rstd * (accu[i][j][4 * q4 + e] - mu * c1a[e]) + c2a[e]);
;           gq[i][j][2 * q4] = pack2(sg4[0], sg4[1]); gq[i][j][2 * q4 + 1] = pack2(sg4[2], sg4[3]);
;         }
;         __builtin_amdgcn_sched_barrier(0);
;       }
	v_fma_f32 v36, v87, v36, v80
	v_fma_f32 v37, -v49, v86, v37
	v_mul_f32_e32 v36, 0xbfb8aa3b, v36
	v_fma_f32 v37, v87, v37, v81
	v_exp_f32_e32 v36, v36
	v_mul_f32_e32 v37, 0xbfb8aa3b, v37
	v_exp_f32_e32 v37, v37
	v_fma_f32 v54, -v50, v84, v54
	v_add_f32_e32 v36, 1.0, v36
	v_rcp_f32_e32 v49, v36
	v_add_f32_e32 v36, 1.0, v37
	v_fma_f32 v37, -v50, v86, v38
	v_fma_f32 v55, -v51, v84, v55
	v_fma_f32 v37, v87, v37, v82
	v_fma_f32 v38, -v51, v86, v39
	v_fma_f32 v52, v85, v52, v80
	v_fma_f32 v53, v85, v53, v81
	v_fma_f32 v54, v85, v54, v82
	v_fma_f32 v55, v85, v55, v83
	v_mul_f32_e32 v37, 0xbfb8aa3b, v37
	v_fmac_f32_e32 v83, v87, v38
	v_mul_f32_e32 v52, 0xbfb8aa3b, v52
	v_mul_f32_e32 v53, 0xbfb8aa3b, v53
	v_mul_f32_e32 v54, 0xbfb8aa3b, v54
	v_mul_f32_e32 v55, 0xbfb8aa3b, v55
	v_exp_f32_e32 v37, v37
	v_mul_f32_e32 v38, 0xbfb8aa3b, v83
	v_exp_f32_e32 v52, v52
	v_exp_f32_e32 v53, v53
	v_exp_f32_e32 v54, v54
	v_exp_f32_e32 v55, v55
	v_exp_f32_e32 v38, v38
	v_rcp_f32_e32 v39, v36
	v_add_f32_e32 v36, 1.0, v37
	v_add_f32_e32 v52, 1.0, v52
	v_add_f32_e32 v53, 1.0, v53
	v_add_f32_e32 v54, 1.0, v54
	v_add_f32_e32 v55, 1.0, v55
	v_rcp_f32_e32 v37, v36
	v_add_f32_e32 v36, 1.0, v38
	v_rcp_f32_e32 v52, v52
	v_rcp_f32_e32 v53, v53
	v_rcp_f32_e32 v54, v54
	v_rcp_f32_e32 v48, v55
	v_rcp_f32_e32 v50, v36
	v_cvt_pk_bf16_f32 v80, v52, v53
	v_cvt_pk_bf16_f32 v38, v49, v39
	v_cvt_pk_bf16_f32 v36, v54, v48
	v_cvt_pk_bf16_f32 v37, v37, v50
	v_add_u32_e32 v39, 0x24940, v160
	v_add_u32_e32 v52, 0x24d40, v160
	ds_read_b128 v[48:51], v39
	ds_read_b128 v[52:55], v52
	ds_read_b32 v39, v164
	ds_read_b32 v81, v165
	ds_read_b32 v82, v166
	ds_read_b32 v83, v167
	s_waitcnt lgkmcnt(3)
	v_fma_f32 v56, -v48, v39, v56
	v_fma_f32 v57, -v49, v39, v57
	v_fma_f32 v58, -v50, v39, v58
	v_fma_f32 v39, -v51, v39, v59
	s_waitcnt lgkmcnt(1)
	v_fma_f32 v40, -v48, v82, v40
	v_fma_f32 v41, -v49, v82, v41
	v_fma_f32 v42, -v50, v82, v42
	v_fma_f32 v43, -v51, v82, v43
	v_fma_f32 v56, v81, v56, v52
	v_fma_f32 v57, v81, v57, v53
	v_fma_f32 v58, v81, v58, v54
	v_fma_f32 v39, v81, v39, v55
	s_waitcnt lgkmcnt(0)
	v_fma_f32 v40, v83, v40, v52
	v_fma_f32 v41, v83, v41, v53
	v_fma_f32 v42, v83, v42, v54
	v_fmac_f32_e32 v55, v83, v43
	v_mul_f32_e32 v56, 0xbfb8aa3b, v56
	v_mul_f32_e32 v57, 0xbfb8aa3b, v57
	v_mul_f32_e32 v58, 0xbfb8aa3b, v58
	v_mul_f32_e32 v39, 0xbfb8aa3b, v39
	v_mul_f32_e32 v40, 0xbfb8aa3b, v40
	v_mul_f32_e32 v41, 0xbfb8aa3b, v41
	v_mul_f32_e32 v42, 0xbfb8aa3b, v42
	v_mul_f32_e32 v43, 0xbfb8aa3b, v55
	v_exp_f32_e32 v56, v56
	v_exp_f32_e32 v57, v57
	v_exp_f32_e32 v58, v58
	v_exp_f32_e32 v39, v39
	v_exp_f32_e32 v40, v40
	v_exp_f32_e32 v41, v41
	v_exp_f32_e32 v42, v42
	v_exp_f32_e32 v43, v43
	v_add_f32_e32 v56, 1.0, v56
	v_add_f32_e32 v57, 1.0, v57
	v_add_f32_e32 v58, 1.0, v58
	v_add_f32_e32 v39, 1.0, v39
	v_add_f32_e32 v40, 1.0, v40
	v_add_f32_e32 v41, 1.0, v41
	v_add_f32_e32 v42, 1.0, v42
	v_add_f32_e32 v43, 1.0, v43
	v_rcp_f32_e32 v56, v56
	v_rcp_f32_e32 v57, v57
	v_rcp_f32_e32 v58, v58
	v_rcp_f32_e32 v39, v39
	v_rcp_f32_e32 v40, v40
	v_rcp_f32_e32 v41, v41
	v_rcp_f32_e32 v42, v42
	v_rcp_f32_e32 v43, v43
	v_cvt_pk_bf16_f32 v87, v56, v57
	v_cvt_pk_bf16_f32 v83, v58, v39
	v_cvt_pk_bf16_f32 v82, v40, v41
	v_cvt_pk_bf16_f32 v81, v42, v43
	v_add_u32_e32 v39, 0x24960, v160
	v_add_u32_e32 v48, 0x24d60, v160
	ds_read_b128 v[40:43], v39
	ds_read_b128 v[48:51], v48
	ds_read_b32 v39, v164
	ds_read_b32 v52, v165
	ds_read_b32 v53, v166
	ds_read_b32 v54, v167
	s_waitcnt lgkmcnt(3)
	v_fma_f32 v56, -v41, v39, v61
	v_fma_f32 v55, -v40, v39, v60
	s_waitcnt lgkmcnt(2)
	v_fma_f32 v56, v52, v56, v49
	v_fma_f32 v57, -v42, v39, v62
	v_fma_f32 v39, -v43, v39, v63
	s_waitcnt lgkmcnt(1)
	v_fma_f32 v40, -v40, v53, v44
	v_fma_f32 v41, -v41, v53, v45
	v_fma_f32 v42, -v42, v53, v46
	v_fma_f32 v43, -v43, v53, v47
	v_fma_f32 v55, v52, v55, v48
	v_mul_f32_e32 v56, 0xbfb8aa3b, v56
	v_fma_f32 v57, v52, v57, v50
	v_fma_f32 v39, v52, v39, v51
	s_waitcnt lgkmcnt(0)
	v_fma_f32 v40, v54, v40, v48
	v_fma_f32 v41, v54, v41, v49
	v_fma_f32 v42, v54, v42, v50
	v_fmac_f32_e32 v51, v54, v43
	v_mul_f32_e32 v55, 0xbfb8aa3b, v55
	v_exp_f32_e32 v56, v56
	v_mul_f32_e32 v57, 0xbfb8aa3b, v57
	v_mul_f32_e32 v39, 0xbfb8aa3b, v39
	v_mul_f32_e32 v40, 0xbfb8aa3b, v40
	v_mul_f32_e32 v41, 0xbfb8aa3b, v41
	v_mul_f32_e32 v42, 0xbfb8aa3b, v42
	v_mul_f32_e32 v43, 0xbfb8aa3b, v51
	v_exp_f32_e32 v55, v55
	v_exp_f32_e32 v57, v57
	v_exp_f32_e32 v39, v39
	v_exp_f32_e32 v40, v40
	v_exp_f32_e32 v41, v41
	v_exp_f32_e32 v42, v42
	v_exp_f32_e32 v43, v43
	v_add_f32_e32 v56, 1.0, v56
	v_add_f32_e32 v55, 1.0, v55
	v_rcp_f32_e32 v52, v56
	v_add_f32_e32 v56, 1.0, v57
	v_add_f32_e32 v39, 1.0, v39
	v_add_f32_e32 v40, 1.0, v40
	v_add_f32_e32 v41, 1.0, v41
	v_add_f32_e32 v42, 1.0, v42
	v_add_f32_e32 v43, 1.0, v43
	v_rcp_f32_e32 v55, v55
	v_rcp_f32_e32 v56, v56
	v_rcp_f32_e32 v39, v39
	v_rcp_f32_e32 v40, v40
	v_rcp_f32_e32 v41, v41
	v_rcp_f32_e32 v42, v42
	v_rcp_f32_e32 v43, v43
	v_cvt_pk_bf16_f32 v93, v55, v52
	v_cvt_pk_bf16_f32 v90, v56, v39
	v_cvt_pk_bf16_f32 v89, v40, v41
	v_cvt_pk_bf16_f32 v88, v42, v43
	v_add_u32_e32 v39, 0x24980, v160
	v_add_u32_e32 v44, 0x24d80, v160
	ds_read_b128 v[40:43], v39
	ds_read_b128 v[44:47], v44
	ds_read_b32 v39, v164
	ds_read_b32 v48, v165
	ds_read_b32 v49, v166
	ds_read_b32 v50, v167
	s_waitcnt lgkmcnt(3)
	v_fma_f32 v16, -v40, v39, v16
	v_fma_f32 v17, -v41, v39, v17
	v_fma_f32 v18, -v42, v39, v18
	v_fma_f32 v19, -v43, v39, v19
	s_waitcnt lgkmcnt(1)
	v_fma_f32 v0, -v40, v49, v0
	v_fma_f32 v1, -v41, v49, v1
	v_fma_f32 v2, -v42, v49, v2
	v_fma_f32 v3, -v43, v49, v3
	v_fma_f32 v16, v48, v16, v44
	v_fma_f32 v17, v48, v17, v45
	v_fma_f32 v18, v48, v18, v46
	v_fma_f32 v19, v48, v19, v47
	s_waitcnt lgkmcnt(0)
; DI unsigned pack2(float a, float b) { f32x2_t v = {a, b}; bf16x2_t r = __builtin_convertvector(v, bf16x2_t); return __builtin_bit_cast(unsigned, r); }
; DI float sigmoidf_(float x) { return __builtin_amdgcn_rcpf(1.f + __expf(-x)); }
; template <bool LAST>
; DI void phase_gate(const Params& P, int layer, unsigned char* smem, int L, int G) {
;     ...
;     unsigned gq[4][2][8];
; #pragma unroll
;     for (int i = 0; i < 4; ++i)
; #pragma unroll
;       for (int q4 = 0; q4 < 4; ++q4) {
;         const int fl = wm * 128 + i * 32 + 8 * q4 + 4 * h;
;         const f32x4 c1v = *(const f32x4*)(vecL + fl), c2v = *(const f32x4*)(vecL + 256 + fl);
;         const float c1a[4] = {c1v.x, c1v.y, c1v.z, c1v.w}, c2a[4] = {c2v.x, c2v.y, c2v.z, c2v.w};
; #pragma unroll
;         for (int j = 0; j < 2; ++j) {
;           const int lrow = wn * 64 + j * 32 + r;
;           const float mu = rowA[lrow], rstd = rowB[lrow];
;           float sg4[4];
; #pragma unroll
;           for (int e = 0; e < 4; ++e) sg4[e] = sigmoidf_(rstd * (accu[i][j][4 * q4 + e] - mu * c1a[e]) + c2a[e]);
;           gq[i][j][2 * q4] = pack2(sg4[0], sg4[1]); gq[i][j][2 * q4 + 1] = pack2(sg4[2], sg4[3]);
;         }
;         __builtin_amdgcn_sched_barrier(0);
;       }
	v_fma_f32 v0, v50, v0, v44
	v_fma_f32 v1, v50, v1, v45
	v_fma_f32 v2, v50, v2, v46
	v_fmac_f32_e32 v47, v50, v3
	v_mul_f32_e32 v16, 0xbfb8aa3b, v16
	v_mul_f32_e32 v17, 0xbfb8aa3b, v17
	v_mul_f32_e32 v18, 0xbfb8aa3b, v18
	v_mul_f32_e32 v19, 0xbfb8aa3b, v19
	v_mul_f32_e32 v0, 0xbfb8aa3b, v0
	v_mul_f32_e32 v1, 0xbfb8aa3b, v1
	v_mul_f32_e32 v2, 0xbfb8aa3b, v2
	v_mul_f32_e32 v3, 0xbfb8aa3b, v47
	v_exp_f32_e32 v16, v16
	v_exp_f32_e32 v17, v17
	v_exp_f32_e32 v18, v18
	v_exp_f32_e32 v19, v19
	v_exp_f32_e32 v0, v0
	v_exp_f32_e32 v1, v1
	v_exp_f32_e32 v2, v2
	v_exp_f32_e32 v3, v3
	v_add_f32_e32 v16, 1.0, v16
	v_add_f32_e32 v17, 1.0, v17
	v_add_f32_e32 v18, 1.0, v18
	v_add_f32_e32 v19, 1.0, v19
	v_add_f32_e32 v0, 1.0, v0
	v_add_f32_e32 v1, 1.0, v1
	v_add_f32_e32 v2, 1.0, v2
	v_add_f32_e32 v3, 1.0, v3
	v_rcp_f32_e32 v16, v16
	v_rcp_f32_e32 v17, v17
	v_rcp_f32_e32 v18, v18
	v_rcp_f32_e32 v19, v19
	v_rcp_f32_e32 v0, v0
	v_rcp_f32_e32 v1, v1
	v_rcp_f32_e32 v2, v2
	v_rcp_f32_e32 v3, v3
	v_cvt_pk_bf16_f32 v17, v16, v17
	v_cvt_pk_bf16_f32 v19, v18, v19
	v_cvt_pk_bf16_f32 v16, v0, v1
	v_cvt_pk_bf16_f32 v18, v2, v3
	v_add_u32_e32 v0, 0x249a0, v160
	v_add_u32_e32 v39, 0x24da0, v160
	ds_read_b128 v[0:3], v0
	ds_read_b128 v[40:43], v39
	ds_read_b32 v39, v164
	ds_read_b32 v44, v165
	ds_read_b32 v45, v166
	ds_read_b32 v46, v167
	s_waitcnt lgkmcnt(3)
	v_fma_f32 v20, -v0, v39, v20
	v_fma_f32 v21, -v1, v39, v21
	v_fma_f32 v22, -v2, v39, v22
	v_fma_f32 v23, -v3, v39, v23
	s_waitcnt lgkmcnt(1)
	v_fma_f32 v0, -v0, v45, v4
	v_fma_f32 v1, -v1, v45, v5
	v_fma_f32 v2, -v2, v45, v6
	v_fma_f32 v3, -v3, v45, v7
	v_fma_f32 v20, v44, v20, v40
	v_fma_f32 v21, v44, v21, v41
	v_fma_f32 v22, v44, v22, v42
	v_fma_f32 v23, v44, v23, v43
	s_waitcnt lgkmcnt(0)
	v_fma_f32 v0, v46, v0, v40
	v_fma_f32 v1, v46, v1, v41
	v_fma_f32 v2, v46, v2, v42
	v_fmac_f32_e32 v43, v46, v3
	v_mul_f32_e32 v20, 0xbfb8aa3b, v20
	v_mul_f32_e32 v21, 0xbfb8aa3b, v21
	v_mul_f32_e32 v22, 0xbfb8aa3b, v22
	v_mul_f32_e32 v23, 0xbfb8aa3b, v23
	v_mul_f32_e32 v0, 0xbfb8aa3b, v0
	v_mul_f32_e32 v1, 0xbfb8aa3b, v1
	v_mul_f32_e32 v2, 0xbfb8aa3b, v2
	v_mul_f32_e32 v3, 0xbfb8aa3b, v43
	v_exp_f32_e32 v20, v20
	v_exp_f32_e32 v21, v21
	v_exp_f32_e32 v22, v22
	v_exp_f32_e32 v23, v23
	v_exp_f32_e32 v0, v0
	v_exp_f32_e32 v1, v1
	v_exp_f32_e32 v2, v2
	v_exp_f32_e32 v3, v3
	v_add_f32_e32 v20, 1.0, v20
	v_add_f32_e32 v21, 1.0, v21
	v_add_f32_e32 v22, 1.0, v22
	v_add_f32_e32 v23, 1.0, v23
	v_add_f32_e32 v0, 1.0, v0
	v_add_f32_e32 v1, 1.0, v1
	v_add_f32_e32 v2, 1.0, v2
	v_add_f32_e32 v3, 1.0, v3
	v_rcp_f32_e32 v20, v20
	v_rcp_f32_e32 v21, v21
	v_rcp_f32_e32 v22, v22
	v_rcp_f32_e32 v4, v23
	v_rcp_f32_e32 v0, v0
	v_rcp_f32_e32 v1, v1
	v_rcp_f32_e32 v2, v2
	v_rcp_f32_e32 v3, v3
	v_cvt_pk_bf16_f32 v7, v20, v21
	v_cvt_pk_bf16_f32 v6, v22, v4
	v_cvt_pk_bf16_f32 v5, v0, v1
	v_cvt_pk_bf16_f32 v4, v2, v3
	v_add_u32_e32 v0, 0x249c0, v160
	v_add_u32_e32 v20, 0x24dc0, v160
	ds_read_b128 v[0:3], v0
	ds_read_b128 v[20:23], v20
	ds_read_b32 v39, v164
	ds_read_b32 v40, v165
	ds_read_b32 v41, v166
	ds_read_b32 v42, v167
	s_waitcnt lgkmcnt(3)
	v_fma_f32 v24, -v0, v39, v24
	v_fma_f32 v25, -v1, v39, v25
	v_fma_f32 v26, -v2, v39, v26
	v_fma_f32 v27, -v3, v39, v27
	s_waitcnt lgkmcnt(1)
	v_fma_f32 v0, -v0, v41, v8
	v_fma_f32 v1, -v1, v41, v9
	v_fma_f32 v2, -v2, v41, v10
	v_fma_f32 v3, -v3, v41, v11
	v_fma_f32 v24, v40, v24, v20
	v_fma_f32 v25, v40, v25, v21
	v_fma_f32 v26, v40, v26, v22
	v_fma_f32 v27, v40, v27, v23
	s_waitcnt lgkmcnt(0)
	v_fma_f32 v0, v42, v0, v20
	v_fma_f32 v1, v42, v1, v21
	v_fma_f32 v2, v42, v2, v22
	v_fmac_f32_e32 v23, v42, v3
	v_mul_f32_e32 v24, 0xbfb8aa3b, v24
	v_mul_f32_e32 v25, 0xbfb8aa3b, v25
	v_mul_f32_e32 v26, 0xbfb8aa3b, v26
	v_mul_f32_e32 v27, 0xbfb8aa3b, v27
	v_mul_f32_e32 v0, 0xbfb8aa3b, v0
	v_mul_f32_e32 v1, 0xbfb8aa3b, v1
	v_mul_f32_e32 v2, 0xbfb8aa3b, v2
	v_mul_f32_e32 v3, 0xbfb8aa3b, v23
	v_exp_f32_e32 v24, v24
	v_exp_f32_e32 v25, v25
	v_exp_f32_e32 v26, v26
	v_exp_f32_e32 v27, v27
	v_exp_f32_e32 v0, v0
	v_exp_f32_e32 v1, v1
	v_exp_f32_e32 v2, v2
	v_exp_f32_e32 v3, v3
	v_add_f32_e32 v24, 1.0, v24
	v_add_f32_e32 v25, 1.0, v25
	v_add_f32_e32 v26, 1.0, v26
	v_add_f32_e32 v27, 1.0, v27
	v_add_f32_e32 v0, 1.0, v0
	v_add_f32_e32 v1, 1.0, v1
	v_add_f32_e32 v2, 1.0, v2
	v_add_f32_e32 v3, 1.0, v3
	v_rcp_f32_e32 v24, v24
	v_rcp_f32_e32 v25, v25
	v_rcp_f32_e32 v26, v26
	v_rcp_f32_e32 v8, v27
	v_rcp_f32_e32 v0, v0
	v_rcp_f32_e32 v1, v1
	v_rcp_f32_e32 v2, v2
	v_rcp_f32_e32 v3, v3
	v_cvt_pk_bf16_f32 v9, v24, v25
	v_cvt_pk_bf16_f32 v11, v26, v8
	v_cvt_pk_bf16_f32 v8, v0, v1
	v_cvt_pk_bf16_f32 v10, v2, v3
	v_add_u32_e32 v20, 0x24de0, v160
	ds_read_b128 v[0:3], v163 offset:480
	ds_read_b32 v24, v164
	ds_read_b128 v[20:23], v20
	ds_read_b32 v25, v165
	ds_read_b32 v26, v166
	s_waitcnt lgkmcnt(3)
	v_fma_f32 v27, -v0, v24, v28
	ds_read_b32 v28, v167
	v_fma_f32 v29, -v1, v24, v29
	s_waitcnt lgkmcnt(2)
	v_fma_f32 v29, v25, v29, v21
	v_fma_f32 v30, -v2, v24, v30
	v_fma_f32 v24, -v3, v24, v31
	s_waitcnt lgkmcnt(1)
	v_fma_f32 v0, -v0, v26, v12
	v_fma_f32 v1, -v1, v26, v13
	v_fma_f32 v2, -v2, v26, v14
	v_fma_f32 v3, -v3, v26, v15
	v_fma_f32 v27, v25, v27, v20
	v_mul_f32_e32 v29, 0xbfb8aa3b, v29
	v_fma_f32 v30, v25, v30, v22
	v_fma_f32 v24, v25, v24, v23
	s_waitcnt lgkmcnt(0)
; DI unsigned pack2(float a, float b) { f32x2_t v = {a, b}; bf16x2_t r = __builtin_convertvector(v, bf16x2_t); return __builtin_bit_cast(unsigned, r); }
; DI float sigmoidf_(float x) { return __builtin_amdgcn_rcpf(1.f + __expf(-x)); }
; DI int otid() { int t = threadIdx.x; asm volatile("" : "+v"(t)); return t; }
; template <bool NT>
; DI void stage_load_tile(bf16_t* stg, const bf16_t* tilebase) {
;   const int tid = otid();
;   const int r0 = tid >> 5, c = tid & 31;
;   const unsigned o0 = (unsigned)(r0 * 1024 + c * 8);
;   __builtin_amdgcn_sched_barrier(0);
; #pragma unroll
;   for (int hf = 0; hf < 2; ++hf) {
; #pragma unroll
;     for (int it = 8 * hf; it < 8 * hf + 8; ++it) {
;       const u32x4* gp = (const u32x4*)(tilebase + (o0 + (unsigned)(it * 16 * 1024)));
;       stage_write16(stg, r0 + 16 * it, c, NT ? __builtin_nontemporal_load(gp) : *gp);
;     }
;     __builtin_amdgcn_sched_barrier(0);
;   }
; }
; template <bool LAST>
; DI void phase_gate(const Params& P, int layer, unsigned char* smem, int L, int G) {
;     ...
;           const float mu = rowA[lrow], rstd = rowB[lrow];
;           float sg4[4];
; #pragma unroll
;           for (int e = 0; e < 4; ++e) sg4[e] = sigmoidf_(rstd * (accu[i][j][4 * q4 + e] - mu * c1a[e]) + c2a[e]);
;           gq[i][j][2 * q4] = pack2(sg4[0], sg4[1]); gq[i][j][2 * q4 + 1] = pack2(sg4[2], sg4[3]);
;         }
;         __builtin_amdgcn_sched_barrier(0);
;       }
	v_fma_f32 v0, v28, v0, v20
	v_fma_f32 v1, v28, v1, v21
	v_fma_f32 v2, v28, v2, v22
	v_fmac_f32_e32 v23, v28, v3
	v_mul_f32_e32 v27, 0xbfb8aa3b, v27
	v_exp_f32_e32 v29, v29
	v_mul_f32_e32 v30, 0xbfb8aa3b, v30
	v_mul_f32_e32 v24, 0xbfb8aa3b, v24
	v_mul_f32_e32 v0, 0xbfb8aa3b, v0
	v_mul_f32_e32 v1, 0xbfb8aa3b, v1
	v_mul_f32_e32 v2, 0xbfb8aa3b, v2
	v_mul_f32_e32 v3, 0xbfb8aa3b, v23
	v_exp_f32_e32 v27, v27
	v_exp_f32_e32 v30, v30
	v_exp_f32_e32 v24, v24
	v_exp_f32_e32 v0, v0
	v_exp_f32_e32 v1, v1
	v_exp_f32_e32 v2, v2
	v_exp_f32_e32 v3, v3
	v_add_f32_e32 v29, 1.0, v29
	v_add_f32_e32 v27, 1.0, v27
	v_rcp_f32_e32 v25, v29
	v_add_f32_e32 v29, 1.0, v30
	v_add_f32_e32 v24, 1.0, v24
	v_add_f32_e32 v0, 1.0, v0
	v_add_f32_e32 v1, 1.0, v1
	v_add_f32_e32 v2, 1.0, v2
	v_add_f32_e32 v3, 1.0, v3
	v_rcp_f32_e32 v27, v27
	v_rcp_f32_e32 v29, v29
	v_rcp_f32_e32 v12, v24
	v_rcp_f32_e32 v0, v0
	v_rcp_f32_e32 v1, v1
	v_rcp_f32_e32 v2, v2
	v_rcp_f32_e32 v3, v3
	v_cvt_pk_bf16_f32 v31, v27, v25
	v_cvt_pk_bf16_f32 v30, v29, v12
	v_cvt_pk_bf16_f32 v29, v0, v1
	v_cvt_pk_bf16_f32 v24, v2, v3
	s_ashr_i32 s19, s18, 31
	s_lshl_b64 s[18:19], s[18:19], 19
	v_mov_b32_e32 v12, v192
	s_add_u32 s20, s66, s18
	v_mov_b32_e32 v163, v161
	s_addc_u32 s21, s67, s19
	v_and_b32_e32 v28, 31, v12
	v_lshlrev_b64 v[0:1], 1, v[162:163]
	v_ashrrev_i32_e32 v25, 5, v12
	v_lshlrev_b32_e32 v12, 3, v28
	v_lshl_add_u64 v[2:3], s[20:21], 0, v[0:1]
	v_lshl_or_b32 v160, v25, 10, v12
	v_add_u32_e32 v12, 0x4000, v160
	v_mov_b32_e32 v13, v161
	v_lshl_add_u64 v[26:27], v[160:161], 1, v[2:3]
	v_lshl_add_u64 v[40:41], v[12:13], 1, v[2:3]
	global_load_dwordx4 v[12:15], v[26:27], off nt
	global_load_dwordx4 v[20:23], v[40:41], off nt
	v_add_u32_e32 v26, 0x8000, v160
	v_mov_b32_e32 v27, v161
	v_add_u32_e32 v40, 0xc000, v160
	v_mov_b32_e32 v41, v161
	v_lshl_add_u64 v[26:27], v[26:27], 1, v[2:3]
	v_lshl_add_u64 v[48:49], v[40:41], 1, v[2:3]
	global_load_dwordx4 v[40:43], v[26:27], off nt
	global_load_dwordx4 v[44:47], v[48:49], off nt
	v_add_u32_e32 v26, 0x10000, v160
	v_mov_b32_e32 v27, v161
	v_add_u32_e32 v48, 0x14000, v160
	v_mov_b32_e32 v49, v161
	v_lshl_add_u64 v[26:27], v[26:27], 1, v[2:3]
	v_lshl_add_u64 v[52:53], v[48:49], 1, v[2:3]
	global_load_dwordx4 v[48:51], v[26:27], off nt
	s_nop 0
	global_load_dwordx4 v[52:55], v[52:53], off nt
	v_add_u32_e32 v26, 0x18000, v160
	v_mov_b32_e32 v27, v161
	v_add_u32_e32 v56, 0x1c000, v160
	v_mov_b32_e32 v57, v161
	v_lshl_add_u64 v[26:27], v[26:27], 1, v[2:3]
	v_lshl_add_u64 v[60:61], v[56:57], 1, v[2:3]
	global_load_dwordx4 v[56:59], v[26:27], off nt
	s_nop 0
	global_load_dwordx4 v[60:63], v[60:61], off nt
	v_add_u32_e32 v218, 0x20000, v160
	v_mov_b32_e32 v219, v161
	v_add_u32_e32 v220, 0x24000, v160
	v_mov_b32_e32 v221, v161
	v_add_u32_e32 v252, 0x28000, v160
	v_mov_b32_e32 v253, v161
	v_add_u32_e32 v226, 0x2c000, v160
	v_mov_b32_e32 v227, v161
	v_lshl_add_u64 v[218:219], v[218:219], 1, v[2:3]
	v_lshl_add_u64 v[222:223], v[220:221], 1, v[2:3]
	v_lshl_add_u64 v[252:253], v[252:253], 1, v[2:3]
	v_lshl_add_u64 v[234:235], v[226:227], 1, v[2:3]
	global_load_dwordx4 v[218:221], v[218:219], off nt
	s_nop 0
	global_load_dwordx4 v[222:225], v[222:223], off nt
	s_nop 0
	global_load_dwordx4 v[226:229], v[252:253], off nt
	global_load_dwordx4 v[230:233], v[234:235], off nt
	v_add_u32_e32 v252, 0x30000, v160
	v_mov_b32_e32 v253, v161
	v_add_u32_e32 v234, 0x34000, v160
	v_mov_b32_e32 v235, v161
	v_lshl_add_u64 v[252:253], v[252:253], 1, v[2:3]
	v_lshl_add_u64 v[238:239], v[234:235], 1, v[2:3]
	global_load_dwordx4 v[234:237], v[252:253], off nt
	s_nop 0
	global_load_dwordx4 v[238:241], v[238:239], off nt
	v_add_u32_e32 v252, 0x38000, v160
	v_mov_b32_e32 v253, v161
	v_lshl_add_u64 v[252:253], v[252:253], 1, v[2:3]
	v_add_u32_e32 v160, 0x3c000, v160
	v_lshl_add_u64 v[190:191], v[160:161], 1, v[2:3]
	global_load_dwordx4 v[242:245], v[252:253], off nt
	global_load_dwordx4 v[248:251], v[190:191], off nt
	v_mul_lo_u32 v25, v25, s34
	v_lshl_add_u32 v25, v28, 4, v25
	v_add_u32_e32 v26, 0x2080, v25
	v_add_u32_e32 v27, 0x4100, v25
	v_add_u32_e32 v28, 0x6180, v25
	v_add_u32_e32 v39, 0x8200, v25
	v_add_u32_e32 v84, 0xa280, v25
	v_add_u32_e32 v85, 0xc300, v25
	v_add_u32_e32 v86, 0xe380, v25
	s_waitcnt vmcnt(15)
	ds_write2_b64 v25, v[12:13], v[14:15] offset1:1
	s_waitcnt vmcnt(14)
	ds_write2_b64 v26, v[20:21], v[22:23] offset1:1
	s_waitcnt vmcnt(13)
	ds_write2_b64 v27, v[40:41], v[42:43] offset1:1
	s_waitcnt vmcnt(12)
	ds_write2_b64 v28, v[44:45], v[46:47] offset1:1
	s_waitcnt vmcnt(11)
	ds_write2_b64 v39, v[48:49], v[50:51] offset1:1
	s_waitcnt vmcnt(10)
	ds_write2_b64 v84, v[52:53], v[54:55] offset1:1
	s_waitcnt vmcnt(9)
	ds_write2_b64 v85, v[56:57], v[58:59] offset1:1
	s_waitcnt vmcnt(8)
	ds_write2_b64 v86, v[60:61], v[62:63] offset1:1
	v_add_u32_e32 v2, 0x10400, v25
	v_add_u32_e32 v3, 0x12480, v25
	v_add_u32_e32 v26, 0x14500, v25
	v_add_u32_e32 v27, 0x16580, v25
	v_add_u32_e32 v28, 0x18600, v25
	v_add_u32_e32 v39, 0x1a680, v25
	v_add_u32_e32 v84, 0x1c700, v25
	v_add_u32_e32 v25, 0x1e780, v25
	s_waitcnt vmcnt(7)
	ds_write2_b64 v2, v[218:219], v[220:221] offset1:1
	s_waitcnt vmcnt(6)
	ds_write2_b64 v3, v[222:223], v[224:225] offset1:1
	s_waitcnt vmcnt(5)
	ds_write2_b64 v26, v[226:227], v[228:229] offset1:1
	s_waitcnt vmcnt(4)
	ds_write2_b64 v27, v[230:231], v[232:233] offset1:1
	s_waitcnt vmcnt(3)
	ds_write2_b64 v28, v[234:235], v[236:237] offset1:1
	s_waitcnt vmcnt(2)
	ds_write2_b64 v39, v[238:239], v[240:241] offset1:1
	s_waitcnt vmcnt(1)
	ds_write2_b64 v84, v[242:243], v[244:245] offset1:1
	s_waitcnt vmcnt(0)
	ds_write2_b64 v25, v[248:249], v[250:251] offset1:1
	v_mov_b32_e32 v2, v192
	s_waitcnt lgkmcnt(0)
	s_barrier
; DI unsigned pack2(float a, float b) { f32x2_t v = {a, b}; bf16x2_t r = __builtin_convertvector(v, bf16x2_t); return __builtin_bit_cast(unsigned, r); }
; DI float bflo(unsigned u) { return __uint_as_float(u << 16); }
; DI float bfhi(unsigned u) { return __uint_as_float(u & 0xffff0000u); }
; DI int otid() { int t = threadIdx.x; asm volatile("" : "+v"(t)); return t; }
; template <bool LAST>
; DI void phase_gate(const Params& P, int layer, unsigned char* smem, int L, int G) {
;     ...
;     {
;       const int tid1 = otid();
;       const int lane1 = tid1 & 63, w1 = tid1 >> 6, r1 = lane1 & 31, h1 = lane1 >> 5, wm1 = w1 >> 2, wn1 = w1 & 3;
; #pragma unroll
;       for (int i = 0; i < 4; ++i)
; #pragma unroll
;         for (int q4 = 0; q4 < 4; ++q4) {
; #pragma unroll
;           for (int j = 0; j < 2; ++j) {
;             const uint2 pv = *(const uint2*)(stg + (wn1 * 64 + j * 32 + r1) * STG + wm1 * 128 + i * 32 + 8 * q4 + 4 * h1);
;             const unsigned g0 = gq[i][j][2 * q4], g1 = gq[i][j][2 * q4 + 1];
;             gq[i][j][2 * q4] = pack2(bflo(g0) * bflo(pv.x), bfhi(g0) * bfhi(pv.x));
;             gq[i][j][2 * q4 + 1] = pack2(bflo(g1) * bflo(pv.y), bfhi(g1) * bfhi(pv.y));
;           }
;           __builtin_amdgcn_sched_barrier(0);
;         }
;     }
;     __syncthreads();
	v_and_b32_e32 v13, 0xffff0000, v99
	v_lshrrev_b32_e32 v12, 2, v2
	v_and_b32_e32 v12, 8, v12
	v_and_b32_e32 v3, 0xdf, v2
	v_and_or_b32 v2, v2, s31, v12
	v_mad_u32_u24 v112, v3, s34, v2
	ds_read_b64 v[2:3], v112
	ds_read_b64 v[14:15], v112 offset:16640
	v_lshlrev_b32_e32 v12, 16, v99
	s_waitcnt lgkmcnt(1)
	v_lshlrev_b32_e32 v20, 16, v2
	v_and_b32_e32 v21, 0xffff0000, v2
	v_pk_mul_f32 v[12:13], v[12:13], v[20:21]
	v_lshlrev_b32_e32 v2, 16, v3
	v_cvt_pk_bf16_f32 v99, v12, v13
	v_lshlrev_b32_e32 v12, 16, v98
	v_and_b32_e32 v13, 0xffff0000, v98
	v_and_b32_e32 v3, 0xffff0000, v3
	v_pk_mul_f32 v[2:3], v[12:13], v[2:3]
	s_waitcnt lgkmcnt(0)
	v_lshlrev_b32_e32 v12, 16, v14
	v_cvt_pk_bf16_f32 v98, v2, v3
	v_lshlrev_b32_e32 v2, 16, v97
	v_and_b32_e32 v3, 0xffff0000, v97
	v_and_b32_e32 v13, 0xffff0000, v14
	v_pk_mul_f32 v[2:3], v[2:3], v[12:13]
	v_lshlrev_b32_e32 v12, 16, v15
	v_cvt_pk_bf16_f32 v94, v2, v3
	v_lshlrev_b32_e32 v2, 16, v96
	v_and_b32_e32 v3, 0xffff0000, v96
	v_and_b32_e32 v13, 0xffff0000, v15
	v_pk_mul_f32 v[2:3], v[2:3], v[12:13]
	s_nop 0
	v_cvt_pk_bf16_f32 v95, v2, v3
	ds_read_b64 v[2:3], v112 offset:16
	ds_read_b64 v[14:15], v112 offset:16656
	v_lshlrev_b32_e32 v12, 16, v103
	v_and_b32_e32 v13, 0xffff0000, v103
	s_waitcnt lgkmcnt(1)
	v_lshlrev_b32_e32 v20, 16, v2
	v_and_b32_e32 v21, 0xffff0000, v2
	v_pk_mul_f32 v[12:13], v[12:13], v[20:21]
	v_lshlrev_b32_e32 v20, 16, v3
	v_cvt_pk_bf16_f32 v2, v12, v13
	v_lshlrev_b32_e32 v12, 16, v102
	v_and_b32_e32 v13, 0xffff0000, v102
	v_and_b32_e32 v21, 0xffff0000, v3
	v_pk_mul_f32 v[12:13], v[12:13], v[20:21]
	s_waitcnt lgkmcnt(0)
	v_lshlrev_b32_e32 v20, 16, v14
	v_cvt_pk_bf16_f32 v3, v12, v13
	v_lshlrev_b32_e32 v12, 16, v101
	v_and_b32_e32 v13, 0xffff0000, v101
	v_and_b32_e32 v21, 0xffff0000, v14
	v_pk_mul_f32 v[12:13], v[12:13], v[20:21]
	v_lshlrev_b32_e32 v14, 16, v15
	v_cvt_pk_bf16_f32 v91, v12, v13
	v_lshlrev_b32_e32 v12, 16, v100
	v_and_b32_e32 v13, 0xffff0000, v100
	v_and_b32_e32 v15, 0xffff0000, v15
	v_pk_mul_f32 v[12:13], v[12:13], v[14:15]
	s_nop 0
	v_cvt_pk_bf16_f32 v92, v12, v13
	ds_read_b64 v[12:13], v112 offset:32
	ds_read_b64 v[20:21], v112 offset:16672
	v_lshlrev_b32_e32 v14, 16, v107
	v_and_b32_e32 v15, 0xffff0000, v107
	s_waitcnt lgkmcnt(1)
	v_lshlrev_b32_e32 v22, 16, v12
	v_and_b32_e32 v23, 0xffff0000, v12
	v_pk_mul_f32 v[14:15], v[14:15], v[22:23]
	v_lshlrev_b32_e32 v12, 16, v13
	v_cvt_pk_bf16_f32 v84, v14, v15
	v_lshlrev_b32_e32 v14, 16, v106
	v_and_b32_e32 v15, 0xffff0000, v106
	v_and_b32_e32 v13, 0xffff0000, v13
	v_pk_mul_f32 v[12:13], v[14:15], v[12:13]
	s_waitcnt lgkmcnt(0)
	v_lshlrev_b32_e32 v14, 16, v20
	v_cvt_pk_bf16_f32 v86, v12, v13
	v_lshlrev_b32_e32 v12, 16, v105
	v_and_b32_e32 v13, 0xffff0000, v105
	v_and_b32_e32 v15, 0xffff0000, v20
	v_pk_mul_f32 v[12:13], v[12:13], v[14:15]
	v_lshlrev_b32_e32 v14, 16, v21
	v_cvt_pk_bf16_f32 v63, v12, v13
	v_lshlrev_b32_e32 v12, 16, v104
	v_and_b32_e32 v13, 0xffff0000, v104
	v_and_b32_e32 v15, 0xffff0000, v21
	v_pk_mul_f32 v[12:13], v[12:13], v[14:15]
	s_nop 0
	v_cvt_pk_bf16_f32 v85, v12, v13
	ds_read_b64 v[12:13], v112 offset:48
	ds_read_b64 v[20:21], v112 offset:16688
	v_lshlrev_b32_e32 v14, 16, v111
	v_and_b32_e32 v15, 0xffff0000, v111
	s_waitcnt lgkmcnt(1)
	v_lshlrev_b32_e32 v22, 16, v12
	v_and_b32_e32 v23, 0xffff0000, v12
	v_pk_mul_f32 v[14:15], v[14:15], v[22:23]
	v_lshlrev_b32_e32 v12, 16, v13
	v_cvt_pk_bf16_f32 v60, v14, v15
	v_lshlrev_b32_e32 v14, 16, v110
	v_and_b32_e32 v15, 0xffff0000, v110
	v_and_b32_e32 v13, 0xffff0000, v13
	v_pk_mul_f32 v[12:13], v[14:15], v[12:13]
	s_waitcnt lgkmcnt(0)
	v_lshlrev_b32_e32 v14, 16, v20
	v_cvt_pk_bf16_f32 v62, v12, v13
	v_lshlrev_b32_e32 v12, 16, v109
	v_and_b32_e32 v13, 0xffff0000, v109
	v_and_b32_e32 v15, 0xffff0000, v20
	v_pk_mul_f32 v[12:13], v[12:13], v[14:15]
	v_lshlrev_b32_e32 v14, 16, v21
	v_cvt_pk_bf16_f32 v59, v12, v13
	v_lshlrev_b32_e32 v12, 16, v108
	v_and_b32_e32 v13, 0xffff0000, v108
	v_and_b32_e32 v15, 0xffff0000, v21
	v_pk_mul_f32 v[12:13], v[12:13], v[14:15]
	s_nop 0
	v_cvt_pk_bf16_f32 v61, v12, v13
	ds_read_b64 v[12:13], v112 offset:64
	ds_read_b64 v[20:21], v112 offset:16704
	v_lshlrev_b32_e32 v14, 16, v67
	v_and_b32_e32 v15, 0xffff0000, v67
	s_waitcnt lgkmcnt(1)
	v_lshlrev_b32_e32 v22, 16, v12
	v_and_b32_e32 v23, 0xffff0000, v12
	v_pk_mul_f32 v[14:15], v[14:15], v[22:23]
	v_lshlrev_b32_e32 v12, 16, v13
	v_cvt_pk_bf16_f32 v56, v14, v15
	v_lshlrev_b32_e32 v14, 16, v66
	v_and_b32_e32 v15, 0xffff0000, v66
	v_and_b32_e32 v13, 0xffff0000, v13
	v_pk_mul_f32 v[12:13], v[14:15], v[12:13]
	s_waitcnt lgkmcnt(0)
	v_lshlrev_b32_e32 v14, 16, v20
	v_cvt_pk_bf16_f32 v58, v12, v13
	v_lshlrev_b32_e32 v12, 16, v65
	v_and_b32_e32 v13, 0xffff0000, v65
	v_and_b32_e32 v15, 0xffff0000, v20
	v_pk_mul_f32 v[12:13], v[12:13], v[14:15]
	v_lshlrev_b32_e32 v14, 16, v21
	v_cvt_pk_bf16_f32 v55, v12, v13
	v_lshlrev_b32_e32 v12, 16, v64
	v_and_b32_e32 v13, 0xffff0000, v64
	v_and_b32_e32 v15, 0xffff0000, v21
	v_pk_mul_f32 v[12:13], v[12:13], v[14:15]
	s_nop 0
	v_cvt_pk_bf16_f32 v57, v12, v13
	ds_read_b64 v[12:13], v112 offset:80
	ds_read_b64 v[20:21], v112 offset:16720
	v_lshlrev_b32_e32 v14, 16, v71
	v_and_b32_e32 v15, 0xffff0000, v71
	s_waitcnt lgkmcnt(1)
	v_lshlrev_b32_e32 v22, 16, v12
	v_and_b32_e32 v23, 0xffff0000, v12
	v_pk_mul_f32 v[14:15], v[14:15], v[22:23]
	v_lshlrev_b32_e32 v12, 16, v13
	v_cvt_pk_bf16_f32 v52, v14, v15
	v_lshlrev_b32_e32 v14, 16, v70
	v_and_b32_e32 v15, 0xffff0000, v70
	v_and_b32_e32 v13, 0xffff0000, v13
	v_pk_mul_f32 v[12:13], v[14:15], v[12:13]
	s_waitcnt lgkmcnt(0)
; DI unsigned pack2(float a, float b) { f32x2_t v = {a, b}; bf16x2_t r = __builtin_convertvector(v, bf16x2_t); return __builtin_bit_cast(unsigned, r); }
; DI float bflo(unsigned u) { return __uint_as_float(u << 16); }
; DI float bfhi(unsigned u) { return __uint_as_float(u & 0xffff0000u); }
; template <bool LAST>
; DI void phase_gate(const Params& P, int layer, unsigned char* smem, int L, int G) {
;     ...
; #pragma unroll
;       for (int i = 0; i < 4; ++i)
; #pragma unroll
;         for (int q4 = 0; q4 < 4; ++q4) {
; #pragma unroll
;           for (int j = 0; j < 2; ++j) {
;             const uint2 pv = *(const uint2*)(stg + (wn1 * 64 + j * 32 + r1) * STG + wm1 * 128 + i * 32 + 8 * q4 + 4 * h1);
;             const unsigned g0 = gq[i][j][2 * q4], g1 = gq[i][j][2 * q4 + 1];
;             gq[i][j][2 * q4] = pack2(bflo(g0) * bflo(pv.x), bfhi(g0) * bfhi(pv.x));
;             gq[i][j][2 * q4 + 1] = pack2(bflo(g1) * bflo(pv.y), bfhi(g1) * bfhi(pv.y));
;           }
;           __builtin_amdgcn_sched_barrier(0);
;         }
	v_lshlrev_b32_e32 v14, 16, v20
	v_cvt_pk_bf16_f32 v54, v12, v13
	v_lshlrev_b32_e32 v12, 16, v69
	v_and_b32_e32 v13, 0xffff0000, v69
	v_and_b32_e32 v15, 0xffff0000, v20
	v_pk_mul_f32 v[12:13], v[12:13], v[14:15]
	v_lshlrev_b32_e32 v14, 16, v21
	v_cvt_pk_bf16_f32 v51, v12, v13
	v_lshlrev_b32_e32 v12, 16, v68
	v_and_b32_e32 v13, 0xffff0000, v68
	v_and_b32_e32 v15, 0xffff0000, v21
	v_pk_mul_f32 v[12:13], v[12:13], v[14:15]
	s_nop 0
	v_cvt_pk_bf16_f32 v53, v12, v13
	ds_read_b64 v[12:13], v112 offset:96
	ds_read_b64 v[20:21], v112 offset:16736
	v_lshlrev_b32_e32 v14, 16, v75
	v_and_b32_e32 v15, 0xffff0000, v75
	s_waitcnt lgkmcnt(1)
	v_lshlrev_b32_e32 v22, 16, v12
	v_and_b32_e32 v23, 0xffff0000, v12
	v_pk_mul_f32 v[14:15], v[14:15], v[22:23]
	v_lshlrev_b32_e32 v12, 16, v13
	v_cvt_pk_bf16_f32 v48, v14, v15
	v_lshlrev_b32_e32 v14, 16, v74
	v_and_b32_e32 v15, 0xffff0000, v74
	v_and_b32_e32 v13, 0xffff0000, v13
	v_pk_mul_f32 v[12:13], v[14:15], v[12:13]
	s_waitcnt lgkmcnt(0)
	v_lshlrev_b32_e32 v14, 16, v20
	v_cvt_pk_bf16_f32 v50, v12, v13
	v_lshlrev_b32_e32 v12, 16, v73
	v_and_b32_e32 v13, 0xffff0000, v73
	v_and_b32_e32 v15, 0xffff0000, v20
	v_pk_mul_f32 v[12:13], v[12:13], v[14:15]
	v_lshlrev_b32_e32 v14, 16, v21
	v_cvt_pk_bf16_f32 v47, v12, v13
	v_lshlrev_b32_e32 v12, 16, v72
	v_and_b32_e32 v13, 0xffff0000, v72
	v_and_b32_e32 v15, 0xffff0000, v21
	v_pk_mul_f32 v[12:13], v[12:13], v[14:15]
	s_nop 0
	v_cvt_pk_bf16_f32 v49, v12, v13
	ds_read_b64 v[12:13], v112 offset:112
	ds_read_b64 v[20:21], v112 offset:16752
	v_lshlrev_b32_e32 v14, 16, v79
	v_and_b32_e32 v15, 0xffff0000, v79
	s_waitcnt lgkmcnt(1)
	v_lshlrev_b32_e32 v22, 16, v12
	v_and_b32_e32 v23, 0xffff0000, v12
	v_pk_mul_f32 v[14:15], v[14:15], v[22:23]
	v_lshlrev_b32_e32 v12, 16, v13
	v_cvt_pk_bf16_f32 v44, v14, v15
	v_lshlrev_b32_e32 v14, 16, v78
	v_and_b32_e32 v15, 0xffff0000, v78
	v_and_b32_e32 v13, 0xffff0000, v13
	v_pk_mul_f32 v[12:13], v[14:15], v[12:13]
	s_waitcnt lgkmcnt(0)
	v_lshlrev_b32_e32 v14, 16, v20
	v_cvt_pk_bf16_f32 v46, v12, v13
	v_lshlrev_b32_e32 v12, 16, v77
	v_and_b32_e32 v13, 0xffff0000, v77
	v_and_b32_e32 v15, 0xffff0000, v20
	v_pk_mul_f32 v[12:13], v[12:13], v[14:15]
	v_lshlrev_b32_e32 v14, 16, v21
	v_cvt_pk_bf16_f32 v43, v12, v13
	v_lshlrev_b32_e32 v12, 16, v76
	v_and_b32_e32 v13, 0xffff0000, v76
	v_and_b32_e32 v15, 0xffff0000, v21
	v_pk_mul_f32 v[12:13], v[12:13], v[14:15]
	s_nop 0
	v_cvt_pk_bf16_f32 v45, v12, v13
	ds_read_b64 v[12:13], v112 offset:128
	ds_read_b64 v[20:21], v112 offset:16768
	v_lshlrev_b32_e32 v14, 16, v35
	v_and_b32_e32 v15, 0xffff0000, v35
	s_waitcnt lgkmcnt(1)
	v_lshlrev_b32_e32 v22, 16, v12
	v_and_b32_e32 v23, 0xffff0000, v12
	v_pk_mul_f32 v[14:15], v[14:15], v[22:23]
	v_lshlrev_b32_e32 v12, 16, v13
	v_cvt_pk_bf16_f32 v40, v14, v15
	v_lshlrev_b32_e32 v14, 16, v34
	v_and_b32_e32 v15, 0xffff0000, v34
	v_and_b32_e32 v13, 0xffff0000, v13
	v_pk_mul_f32 v[12:13], v[14:15], v[12:13]
	s_waitcnt lgkmcnt(0)
	v_lshlrev_b32_e32 v14, 16, v20
	v_cvt_pk_bf16_f32 v42, v12, v13
	v_lshlrev_b32_e32 v12, 16, v33
	v_and_b32_e32 v13, 0xffff0000, v33
	v_and_b32_e32 v15, 0xffff0000, v20
	v_pk_mul_f32 v[12:13], v[12:13], v[14:15]
	v_lshlrev_b32_e32 v14, 16, v21
	v_cvt_pk_bf16_f32 v39, v12, v13
	v_lshlrev_b32_e32 v12, 16, v32
	v_and_b32_e32 v13, 0xffff0000, v32
	v_and_b32_e32 v15, 0xffff0000, v21
	v_pk_mul_f32 v[12:13], v[12:13], v[14:15]
	s_nop 0
	v_cvt_pk_bf16_f32 v41, v12, v13
	ds_read_b64 v[12:13], v112 offset:144
	ds_read_b64 v[20:21], v112 offset:16784
	v_lshlrev_b32_e32 v14, 16, v80
	v_and_b32_e32 v15, 0xffff0000, v80
	s_waitcnt lgkmcnt(1)
	v_lshlrev_b32_e32 v22, 16, v12
	v_and_b32_e32 v23, 0xffff0000, v12
	v_pk_mul_f32 v[14:15], v[14:15], v[22:23]
	v_lshlrev_b32_e32 v12, 16, v13
	v_cvt_pk_bf16_f32 v34, v14, v15
	v_lshlrev_b32_e32 v14, 16, v36
	v_and_b32_e32 v15, 0xffff0000, v36
	v_and_b32_e32 v13, 0xffff0000, v13
	v_pk_mul_f32 v[12:13], v[14:15], v[12:13]
	s_waitcnt lgkmcnt(0)
	v_lshlrev_b32_e32 v14, 16, v20
	v_cvt_pk_bf16_f32 v36, v12, v13
	v_lshlrev_b32_e32 v12, 16, v38
	v_and_b32_e32 v13, 0xffff0000, v38
	v_and_b32_e32 v15, 0xffff0000, v20
	v_pk_mul_f32 v[12:13], v[12:13], v[14:15]
	v_lshlrev_b32_e32 v14, 16, v21
	v_cvt_pk_bf16_f32 v33, v12, v13
	v_lshlrev_b32_e32 v12, 16, v37
	v_and_b32_e32 v13, 0xffff0000, v37
	v_and_b32_e32 v15, 0xffff0000, v21
	v_pk_mul_f32 v[12:13], v[12:13], v[14:15]
	s_nop 0
	v_cvt_pk_bf16_f32 v35, v12, v13
	ds_read_b64 v[12:13], v112 offset:160
	ds_read_b64 v[20:21], v112 offset:16800
	v_lshlrev_b32_e32 v14, 16, v87
	v_and_b32_e32 v15, 0xffff0000, v87
	s_waitcnt lgkmcnt(1)
	v_lshlrev_b32_e32 v22, 16, v12
	v_and_b32_e32 v23, 0xffff0000, v12
	v_pk_mul_f32 v[14:15], v[14:15], v[22:23]
	v_lshlrev_b32_e32 v12, 16, v13
	v_cvt_pk_bf16_f32 v26, v14, v15
	v_lshlrev_b32_e32 v14, 16, v83
	v_and_b32_e32 v15, 0xffff0000, v83
	v_and_b32_e32 v13, 0xffff0000, v13
	v_pk_mul_f32 v[12:13], v[14:15], v[12:13]
	s_waitcnt lgkmcnt(0)
	v_lshlrev_b32_e32 v14, 16, v20
	v_cvt_pk_bf16_f32 v28, v12, v13
	v_lshlrev_b32_e32 v12, 16, v82
	v_and_b32_e32 v13, 0xffff0000, v82
	v_and_b32_e32 v15, 0xffff0000, v20
	v_pk_mul_f32 v[12:13], v[12:13], v[14:15]
	v_lshlrev_b32_e32 v14, 16, v21
	v_cvt_pk_bf16_f32 v25, v12, v13
	v_lshlrev_b32_e32 v12, 16, v81
	v_and_b32_e32 v13, 0xffff0000, v81
	v_and_b32_e32 v15, 0xffff0000, v21
	v_pk_mul_f32 v[12:13], v[12:13], v[14:15]
	s_nop 0
	v_cvt_pk_bf16_f32 v27, v12, v13
	ds_read_b64 v[12:13], v112 offset:176
	ds_read_b64 v[64:65], v112 offset:16816
	v_lshlrev_b32_e32 v14, 16, v93
	v_and_b32_e32 v15, 0xffff0000, v93
	s_waitcnt lgkmcnt(1)
; DI unsigned pack2(float a, float b) { f32x2_t v = {a, b}; bf16x2_t r = __builtin_convertvector(v, bf16x2_t); return __builtin_bit_cast(unsigned, r); }
; DI float bflo(unsigned u) { return __uint_as_float(u << 16); }
; DI float bfhi(unsigned u) { return __uint_as_float(u & 0xffff0000u); }
; DI int otid() { int t = threadIdx.x; asm volatile("" : "+v"(t)); return t; }
; template <bool LAST>
; DI void phase_gate(const Params& P, int layer, unsigned char* smem, int L, int G) {
;     ...
;     {
;       const int tid1 = otid();
;       const int lane1 = tid1 & 63, w1 = tid1 >> 6, r1 = lane1 & 31, h1 = lane1 >> 5, wm1 = w1 >> 2, wn1 = w1 & 3;
; #pragma unroll
;       for (int i = 0; i < 4; ++i)
; #pragma unroll
;         for (int q4 = 0; q4 < 4; ++q4) {
; #pragma unroll
;           for (int j = 0; j < 2; ++j) {
;             const uint2 pv = *(const uint2*)(stg + (wn1 * 64 + j * 32 + r1) * STG + wm1 * 128 + i * 32 + 8 * q4 + 4 * h1);
;             const unsigned g0 = gq[i][j][2 * q4], g1 = gq[i][j][2 * q4 + 1];
;             gq[i][j][2 * q4] = pack2(bflo(g0) * bflo(pv.x), bfhi(g0) * bfhi(pv.x));
;             gq[i][j][2 * q4 + 1] = pack2(bflo(g1) * bflo(pv.y), bfhi(g1) * bfhi(pv.y));
;           }
;           __builtin_amdgcn_sched_barrier(0);
;         }
;     }
;     __syncthreads();
	v_lshlrev_b32_e32 v20, 16, v12
	v_and_b32_e32 v21, 0xffff0000, v12
	v_pk_mul_f32 v[14:15], v[14:15], v[20:21]
	v_lshlrev_b32_e32 v12, 16, v13
	v_cvt_pk_bf16_f32 v21, v14, v15
	v_lshlrev_b32_e32 v14, 16, v90
	v_and_b32_e32 v15, 0xffff0000, v90
	v_and_b32_e32 v13, 0xffff0000, v13
	v_pk_mul_f32 v[12:13], v[14:15], v[12:13]
	s_waitcnt lgkmcnt(0)
	v_lshlrev_b32_e32 v14, 16, v64
	v_cvt_pk_bf16_f32 v23, v12, v13
	v_lshlrev_b32_e32 v12, 16, v89
	v_and_b32_e32 v13, 0xffff0000, v89
	v_and_b32_e32 v15, 0xffff0000, v64
	v_pk_mul_f32 v[12:13], v[12:13], v[14:15]
	v_lshlrev_b32_e32 v14, 16, v65
	v_cvt_pk_bf16_f32 v20, v12, v13
	v_lshlrev_b32_e32 v12, 16, v88
	v_and_b32_e32 v13, 0xffff0000, v88
	v_and_b32_e32 v15, 0xffff0000, v65
	v_pk_mul_f32 v[12:13], v[12:13], v[14:15]
	s_nop 0
	v_cvt_pk_bf16_f32 v22, v12, v13
	ds_read_b64 v[12:13], v112 offset:192
	ds_read_b64 v[64:65], v112 offset:16832
	v_lshlrev_b32_e32 v14, 16, v17
	v_and_b32_e32 v15, 0xffff0000, v17
	s_waitcnt lgkmcnt(1)
	v_lshlrev_b32_e32 v66, 16, v12
	v_and_b32_e32 v67, 0xffff0000, v12
	v_pk_mul_f32 v[14:15], v[14:15], v[66:67]
	v_lshlrev_b32_e32 v12, 16, v13
	v_cvt_pk_bf16_f32 v17, v14, v15
	v_lshlrev_b32_e32 v14, 16, v19
	v_and_b32_e32 v15, 0xffff0000, v19
	v_and_b32_e32 v13, 0xffff0000, v13
	v_pk_mul_f32 v[12:13], v[14:15], v[12:13]
	s_waitcnt lgkmcnt(0)
	v_lshlrev_b32_e32 v14, 16, v64
	v_cvt_pk_bf16_f32 v19, v12, v13
	v_lshlrev_b32_e32 v12, 16, v16
	v_and_b32_e32 v13, 0xffff0000, v16
	v_and_b32_e32 v15, 0xffff0000, v64
	v_pk_mul_f32 v[12:13], v[12:13], v[14:15]
	v_lshlrev_b32_e32 v14, 16, v65
	v_cvt_pk_bf16_f32 v16, v12, v13
	v_lshlrev_b32_e32 v12, 16, v18
	v_and_b32_e32 v13, 0xffff0000, v18
	v_and_b32_e32 v15, 0xffff0000, v65
	v_pk_mul_f32 v[12:13], v[12:13], v[14:15]
	s_nop 0
	v_cvt_pk_bf16_f32 v18, v12, v13
	ds_read_b64 v[14:15], v112 offset:208
	ds_read_b64 v[64:65], v112 offset:16848
	v_lshlrev_b32_e32 v12, 16, v7
	v_and_b32_e32 v13, 0xffff0000, v7
	s_waitcnt lgkmcnt(1)
	v_lshlrev_b32_e32 v66, 16, v14
	v_and_b32_e32 v67, 0xffff0000, v14
	v_pk_mul_f32 v[12:13], v[12:13], v[66:67]
	v_lshlrev_b32_e32 v66, 16, v6
	v_lshlrev_b32_e32 v14, 16, v15
	v_and_b32_e32 v67, 0xffff0000, v6
	v_and_b32_e32 v15, 0xffff0000, v15
	v_pk_mul_f32 v[6:7], v[66:67], v[14:15]
	s_waitcnt lgkmcnt(0)
	v_lshlrev_b32_e32 v66, 16, v64
	v_cvt_pk_bf16_f32 v15, v6, v7
	v_lshlrev_b32_e32 v6, 16, v5
	v_and_b32_e32 v7, 0xffff0000, v5
	v_and_b32_e32 v67, 0xffff0000, v64
	v_pk_mul_f32 v[6:7], v[6:7], v[66:67]
	v_cvt_pk_bf16_f32 v13, v12, v13
	v_cvt_pk_bf16_f32 v12, v6, v7
	v_lshlrev_b32_e32 v6, 16, v4
	v_lshlrev_b32_e32 v64, 16, v65
	v_and_b32_e32 v7, 0xffff0000, v4
	v_and_b32_e32 v65, 0xffff0000, v65
	v_pk_mul_f32 v[4:5], v[6:7], v[64:65]
	s_nop 0
	v_cvt_pk_bf16_f32 v14, v4, v5
	ds_read_b64 v[4:5], v112 offset:224
	ds_read_b64 v[64:65], v112 offset:16864
	v_lshlrev_b32_e32 v6, 16, v9
	v_and_b32_e32 v7, 0xffff0000, v9
	s_waitcnt lgkmcnt(1)
	v_lshlrev_b32_e32 v66, 16, v4
	v_and_b32_e32 v67, 0xffff0000, v4
	v_pk_mul_f32 v[6:7], v[6:7], v[66:67]
	v_lshlrev_b32_e32 v4, 16, v5
	v_cvt_pk_bf16_f32 v9, v6, v7
	v_lshlrev_b32_e32 v6, 16, v11
	v_and_b32_e32 v7, 0xffff0000, v11
	v_and_b32_e32 v5, 0xffff0000, v5
	v_pk_mul_f32 v[4:5], v[6:7], v[4:5]
	s_waitcnt lgkmcnt(0)
	v_lshlrev_b32_e32 v6, 16, v64
	v_cvt_pk_bf16_f32 v11, v4, v5
	v_lshlrev_b32_e32 v4, 16, v8
	v_and_b32_e32 v5, 0xffff0000, v8
	v_and_b32_e32 v7, 0xffff0000, v64
	v_pk_mul_f32 v[4:5], v[4:5], v[6:7]
	v_lshlrev_b32_e32 v6, 16, v65
	v_cvt_pk_bf16_f32 v8, v4, v5
	v_lshlrev_b32_e32 v4, 16, v10
	v_and_b32_e32 v5, 0xffff0000, v10
	v_and_b32_e32 v7, 0xffff0000, v65
	v_pk_mul_f32 v[4:5], v[4:5], v[6:7]
	s_nop 0
	v_cvt_pk_bf16_f32 v10, v4, v5
	ds_read_b64 v[4:5], v112 offset:240
	ds_read_b64 v[64:65], v112 offset:16880
	v_lshlrev_b32_e32 v6, 16, v31
	v_and_b32_e32 v7, 0xffff0000, v31
	s_waitcnt lgkmcnt(1)
	v_lshlrev_b32_e32 v66, 16, v4
	v_and_b32_e32 v67, 0xffff0000, v4
	v_pk_mul_f32 v[6:7], v[6:7], v[66:67]
	v_lshlrev_b32_e32 v66, 16, v30
	v_lshlrev_b32_e32 v4, 16, v5
	v_and_b32_e32 v67, 0xffff0000, v30
	v_and_b32_e32 v5, 0xffff0000, v5
	v_pk_mul_f32 v[4:5], v[66:67], v[4:5]
	v_cvt_pk_bf16_f32 v6, v6, v7
	v_cvt_pk_bf16_f32 v7, v4, v5
	v_lshlrev_b32_e32 v4, 16, v29
	s_waitcnt lgkmcnt(0)
	v_lshlrev_b32_e32 v30, 16, v64
	v_and_b32_e32 v5, 0xffff0000, v29
	v_and_b32_e32 v31, 0xffff0000, v64
	v_pk_mul_f32 v[4:5], v[4:5], v[30:31]
	v_lshlrev_b32_e32 v30, 16, v24
	v_lshlrev_b32_e32 v64, 16, v65
	v_and_b32_e32 v31, 0xffff0000, v24
	v_and_b32_e32 v65, 0xffff0000, v65
	v_pk_mul_f32 v[30:31], v[30:31], v[64:65]
	v_cvt_pk_bf16_f32 v4, v4, v5
	v_cvt_pk_bf16_f32 v5, v30, v31
	v_mov_b32_e32 v24, v192
	s_barrier
; DI int otid() { int t = threadIdx.x; asm volatile("" : "+v"(t)); return t; }
; template <bool NT>
; DI void stage_load_tile(bf16_t* stg, const bf16_t* tilebase) {
;   const int tid = otid();
;   const int r0 = tid >> 5, c = tid & 31;
;   const unsigned o0 = (unsigned)(r0 * 1024 + c * 8);
;   __builtin_amdgcn_sched_barrier(0);
; #pragma unroll
;   for (int hf = 0; hf < 2; ++hf) {
; #pragma unroll
;     for (int it = 8 * hf; it < 8 * hf + 8; ++it) {
;       const u32x4* gp = (const u32x4*)(tilebase + (o0 + (unsigned)(it * 16 * 1024)));
;       stage_write16(stg, r0 + 16 * it, c, NT ? __builtin_nontemporal_load(gp) : *gp);
;     }
;     __builtin_amdgcn_sched_barrier(0);
;   }
; }
; template <bool LAST>
; DI void phase_gate(const Params& P, int layer, unsigned char* smem, int L, int G) {
;     ...
;     stage_load_tile<false>(stg, Sb + (size_t)mt * 256 * 1024 + nt * 256);
;     __syncthreads();
	s_add_u32 s18, s76, s18
	v_ashrrev_i32_e32 v29, 5, v24
	v_and_b32_e32 v24, 31, v24
	s_addc_u32 s19, s77, s19
	v_lshlrev_b32_e32 v30, 3, v24
	v_lshl_add_u64 v[0:1], s[18:19], 0, v[0:1]
	v_lshl_or_b32 v160, v29, 10, v30
	v_add_u32_e32 v64, 0x4000, v160
	v_mov_b32_e32 v65, v161
	v_lshl_add_u64 v[30:31], v[160:161], 1, v[0:1]
	v_lshl_add_u64 v[68:69], v[64:65], 1, v[0:1]
	global_load_dwordx4 v[64:67], v[30:31], off
	s_nop 0
	global_load_dwordx4 v[68:71], v[68:69], off
	v_add_u32_e32 v30, 0x8000, v160
	v_mov_b32_e32 v31, v161
	v_lshl_add_u64 v[30:31], v[30:31], 1, v[0:1]
	v_add_u32_e32 v72, 0xc000, v160
	v_mov_b32_e32 v73, v161
	v_lshl_add_u64 v[80:81], v[72:73], 1, v[0:1]
	global_load_dwordx4 v[72:75], v[30:31], off
	global_load_dwordx4 v[76:79], v[80:81], off
	v_add_u32_e32 v30, 0x10000, v160
	v_mov_b32_e32 v31, v161
	v_lshl_add_u64 v[30:31], v[30:31], 1, v[0:1]
	v_add_u32_e32 v80, 0x14000, v160
	v_mov_b32_e32 v81, v161
	v_lshl_add_u64 v[88:89], v[80:81], 1, v[0:1]
	global_load_dwordx4 v[80:83], v[30:31], off
	global_load_dwordx4 v[100:103], v[88:89], off
	v_add_u32_e32 v30, 0x18000, v160
	v_mov_b32_e32 v31, v161
	v_lshl_add_u64 v[30:31], v[30:31], 1, v[0:1]
	v_add_u32_e32 v88, 0x1c000, v160
	v_mov_b32_e32 v89, v161
	v_lshl_add_u64 v[88:89], v[88:89], 1, v[0:1]
	global_load_dwordx4 v[104:107], v[30:31], off
	global_load_dwordx4 v[108:111], v[88:89], off
	v_add_u32_e32 v252, 0x20000, v160
	v_mov_b32_e32 v253, v161
	v_add_u32_e32 v218, 0x24000, v160
	v_mov_b32_e32 v219, v161
	v_lshl_add_u64 v[252:253], v[252:253], 1, v[0:1]
	v_lshl_add_u64 v[222:223], v[218:219], 1, v[0:1]
	global_load_dwordx4 v[218:221], v[252:253], off
	s_nop 0
	global_load_dwordx4 v[222:225], v[222:223], off
	v_add_u32_e32 v252, 0x28000, v160
	v_mov_b32_e32 v253, v161
	v_lshl_add_u64 v[252:253], v[252:253], 1, v[0:1]
	v_add_u32_e32 v226, 0x2c000, v160
	v_mov_b32_e32 v227, v161
	v_lshl_add_u64 v[234:235], v[226:227], 1, v[0:1]
	global_load_dwordx4 v[226:229], v[252:253], off
	global_load_dwordx4 v[230:233], v[234:235], off
	v_add_u32_e32 v252, 0x30000, v160
	v_mov_b32_e32 v253, v161
	v_lshl_add_u64 v[252:253], v[252:253], 1, v[0:1]
	v_add_u32_e32 v234, 0x34000, v160
	v_mov_b32_e32 v235, v161
	v_lshl_add_u64 v[254:255], v[234:235], 1, v[0:1]
	global_load_dwordx4 v[234:237], v[252:253], off
	global_load_dwordx4 v[238:241], v[254:255], off
	v_add_u32_e32 v252, 0x38000, v160
	v_mov_b32_e32 v253, v161
	v_lshl_add_u64 v[252:253], v[252:253], 1, v[0:1]
	v_add_u32_e32 v160, 0x3c000, v160
	v_lshl_add_u64 v[190:191], v[160:161], 1, v[0:1]
	global_load_dwordx4 v[242:245], v[252:253], off
	global_load_dwordx4 v[248:251], v[190:191], off
	v_mul_lo_u32 v29, v29, s34
	v_lshl_add_u32 v24, v24, 4, v29
	v_add_u32_e32 v29, 0x2080, v24
	v_add_u32_e32 v30, 0x4100, v24
	v_add_u32_e32 v31, 0x6180, v24
	v_add_u32_e32 v32, 0x8200, v24
	v_add_u32_e32 v37, 0xa280, v24
	v_add_u32_e32 v38, 0xc300, v24
	v_add_u32_e32 v87, 0xe380, v24
	s_waitcnt vmcnt(15)
	ds_write2_b64 v24, v[64:65], v[66:67] offset1:1
	s_waitcnt vmcnt(14)
	ds_write2_b64 v29, v[68:69], v[70:71] offset1:1
	s_waitcnt vmcnt(13)
	ds_write2_b64 v30, v[72:73], v[74:75] offset1:1
	s_waitcnt vmcnt(12)
	ds_write2_b64 v31, v[76:77], v[78:79] offset1:1
	s_waitcnt vmcnt(11)
	ds_write2_b64 v32, v[80:81], v[82:83] offset1:1
	s_waitcnt vmcnt(10)
	ds_write2_b64 v37, v[100:101], v[102:103] offset1:1
	s_waitcnt vmcnt(9)
	ds_write2_b64 v38, v[104:105], v[106:107] offset1:1
	s_waitcnt vmcnt(8)
	ds_write2_b64 v87, v[108:109], v[110:111] offset1:1
	v_add_u32_e32 v0, 0x10400, v24
	v_add_u32_e32 v1, 0x12480, v24
	v_add_u32_e32 v29, 0x14500, v24
	v_add_u32_e32 v30, 0x16580, v24
	v_add_u32_e32 v31, 0x18600, v24
	v_add_u32_e32 v32, 0x1a680, v24
	v_add_u32_e32 v37, 0x1c700, v24
	v_add_u32_e32 v24, 0x1e780, v24
	s_waitcnt vmcnt(7)
	ds_write2_b64 v0, v[218:219], v[220:221] offset1:1
	s_waitcnt vmcnt(6)
	ds_write2_b64 v1, v[222:223], v[224:225] offset1:1
	s_waitcnt vmcnt(5)
	ds_write2_b64 v29, v[226:227], v[228:229] offset1:1
	s_waitcnt vmcnt(4)
	ds_write2_b64 v30, v[230:231], v[232:233] offset1:1
	s_waitcnt vmcnt(3)
	ds_write2_b64 v31, v[234:235], v[236:237] offset1:1
	s_waitcnt vmcnt(2)
	ds_write2_b64 v32, v[238:239], v[240:241] offset1:1
	s_waitcnt vmcnt(1)
	ds_write2_b64 v37, v[242:243], v[244:245] offset1:1
	s_waitcnt vmcnt(0)
	ds_write2_b64 v24, v[248:249], v[250:251] offset1:1
	v_mov_b32_e32 v1, v192
	s_waitcnt lgkmcnt(0)
	s_barrier
; DI unsigned pack2(float a, float b) { f32x2_t v = {a, b}; bf16x2_t r = __builtin_convertvector(v, bf16x2_t); return __builtin_bit_cast(unsigned, r); }
; DI float bflo(unsigned u) { return __uint_as_float(u << 16); }
; DI float bfhi(unsigned u) { return __uint_as_float(u & 0xffff0000u); }
; template <bool LAST>
; DI void phase_gate(const Params& P, int layer, unsigned char* smem, int L, int G) {
;     ...
; #pragma unroll
;     for (int i = 0; i < 4; ++i)
; #pragma unroll
;       for (int q4 = 0; q4 < 4; ++q4) {
;         const int fl = wm2 * 128 + i * 32 + 8 * q4 + 4 * h2;
;         const int f0 = nt * 256 + fl;
;         const f32x4 gv = *(const f32x4*)(vecL + 512 + fl), bv = *(const f32x4*)(vecL + 768 + fl);
;         const float ga[4] = {gv.x, gv.y, gv.z, gv.w}, ba[4] = {bv.x, bv.y, bv.z, bv.w};
; #pragma unroll
;         for (int j = 0; j < 2; ++j) {
;           const int lrow = wn2 * 64 + j * 32 + r2;
;           const float mu = rowA[lrow], rstd = rowB[lrow];
;           uint2* sp = (uint2*)(stg + lrow * STG + fl);
;           const uint2 sv = *sp;
;           const float sa[4] = {bflo(sv.x), bfhi(sv.x), bflo(sv.y), bfhi(sv.y)};
;           float y[4];
;           const float gg[4] = {bflo(gq[i][j][2 * q4]), bfhi(gq[i][j][2 * q4]), bflo(gq[i][j][2 * q4 + 1]), bfhi(gq[i][j][2 * q4 + 1])};
; #pragma unroll
;           for (int e = 0; e < 4; ++e) y[e] = (sa[e] - mu) * rstd * ga[e] + ba[e] + gg[e];
;           if (LAST) { f32x4 o = {y[0], y[1], y[2], y[3]}; *(f32x4*)(P.out + (size_t)(mt * 256 + lrow) * 1024 + f0) = o; }
;           else { uint2 pk; pk.x = pack2(y[0], y[1]); pk.y = pack2(y[2], y[3]); *sp = pk; }
;         }
;         __builtin_amdgcn_sched_barrier(0);
	v_lshlrev_b32_e32 v74, 16, v98
	v_lshrrev_b32_e32 v24, 3, v1
	v_ashrrev_i32_e32 v0, 1, v1
	v_and_b32_e32 v24, 4, v24
	v_and_or_b32 v0, v0, s35, v24
	v_lshlrev_b32_e32 v29, 2, v0
	v_and_b32_e32 v1, 0xdf, v1
	v_add_u32_e32 v30, 0x25000, v29
	v_add_u32_e32 v24, 0x25400, v29
	ds_read_b128 v[64:67], v30
	ds_read_b128 v[68:71], v24
	v_mul_u32_u24_e32 v24, 0x208, v1
	v_lshl_add_u32 v24, v0, 1, v24
	ds_read_b64 v[72:73], v24
	v_lshlrev_b32_e32 v32, 2, v1
	v_or_b32_e32 v31, 0x24000, v32
	v_or_b32_e32 v32, 0x24400, v32
	ds_read_b32 v37, v31
	ds_read_b32 v38, v32
	ds_read_b64 v[78:79], v24 offset:16640
	s_waitcnt lgkmcnt(3)
	v_lshlrev_b32_e32 v80, 16, v73
	v_and_b32_e32 v81, 0xffff0000, v73
	s_waitcnt lgkmcnt(2)
	v_sub_f32_e32 v81, v81, v37
	v_sub_f32_e32 v80, v80, v37
	s_waitcnt lgkmcnt(1)
	v_pk_mul_f32 v[80:81], v[38:39], v[80:81] op_sel_hi:[0,1]
	v_and_b32_e32 v75, 0xffff0000, v98
	v_pk_fma_f32 v[80:81], v[66:67], v[80:81], v[70:71]
	v_lshlrev_b32_e32 v82, 16, v72
	v_and_b32_e32 v83, 0xffff0000, v72
	v_pk_add_f32 v[74:75], v[80:81], v[74:75]
	v_or_b32_e32 v80, s36, v1
	v_add_u32_e32 v76, v0, v162
	v_sub_f32_e32 v83, v83, v37
	v_sub_f32_e32 v82, v82, v37
	v_ashrrev_i32_e32 v81, 31, v80
	v_ashrrev_i32_e32 v77, 31, v76
	v_pk_mul_f32 v[82:83], v[38:39], v[82:83] op_sel_hi:[0,1]
	v_lshlrev_b64 v[80:81], 12, v[80:81]
	v_lshlrev_b32_e32 v72, 16, v99
	v_and_b32_e32 v73, 0xffff0000, v99
	v_pk_fma_f32 v[82:83], v[64:65], v[82:83], v[68:69]
	v_lshl_add_u64 v[80:81], s[94:95], 0, v[80:81]
	v_lshlrev_b64 v[76:77], 2, v[76:77]
	v_or_b32_e32 v1, 32, v1
	v_pk_add_f32 v[72:73], v[82:83], v[72:73]
	v_lshl_add_u64 v[82:83], v[80:81], 0, v[76:77]
	v_lshlrev_b32_e32 v38, 2, v1
	global_store_dwordx4 v[82:83], v[72:75], off
	v_or_b32_e32 v37, 0x24000, v38
	v_or_b32_e32 v38, 0x24400, v38
	ds_read_b32 v73, v37
	ds_read_b32 v72, v38
	s_waitcnt lgkmcnt(2)
	v_lshlrev_b32_e32 v87, 16, v78
	v_and_b32_e32 v88, 0xffff0000, v78
	v_lshlrev_b32_e32 v82, 16, v79
	s_waitcnt lgkmcnt(1)
	v_sub_f32_e32 v89, v88, v73
	v_sub_f32_e32 v88, v87, v73
	v_and_b32_e32 v83, 0xffff0000, v79
	s_waitcnt lgkmcnt(0)
	v_pk_mul_f32 v[88:89], v[72:73], v[88:89] op_sel_hi:[0,1]
	v_sub_f32_e32 v83, v83, v73
	v_sub_f32_e32 v82, v82, v73
	v_pk_fma_f32 v[64:65], v[64:65], v[88:89], v[68:69]
	v_or_b32_e32 v68, s36, v1
	v_pk_mul_f32 v[72:73], v[72:73], v[82:83] op_sel_hi:[0,1]
	v_ashrrev_i32_e32 v69, 31, v68
	v_lshlrev_b32_e32 v78, 16, v95
	v_and_b32_e32 v79, 0xffff0000, v95
	v_pk_fma_f32 v[66:67], v[66:67], v[72:73], v[70:71]
	v_lshlrev_b64 v[68:69], 12, v[68:69]
	v_lshlrev_b32_e32 v74, 16, v94
	v_and_b32_e32 v75, 0xffff0000, v94
	v_pk_add_f32 v[66:67], v[66:67], v[78:79]
	v_lshl_add_u64 v[78:79], s[94:95], 0, v[68:69]
	v_pk_add_f32 v[64:65], v[64:65], v[74:75]
	v_lshl_add_u64 v[68:69], v[78:79], 0, v[76:77]
	global_store_dwordx4 v[68:69], v[64:67], off
	v_add_u32_e32 v1, 0x25020, v29
	ds_read_b128 v[64:67], v1
	v_add_u32_e32 v1, 0x25420, v29
	ds_read_b64 v[72:73], v24 offset:16
	ds_read_b128 v[68:71], v1
	ds_read_b32 v1, v31
	ds_read_b32 v74, v32
	ds_read_b64 v[76:77], v24 offset:16656
	s_waitcnt lgkmcnt(4)
	v_lshlrev_b32_e32 v75, 16, v72
	v_and_b32_e32 v87, 0xffff0000, v72
	v_lshlrev_b32_e32 v82, 16, v73
	v_and_b32_e32 v83, 0xffff0000, v73
	s_waitcnt lgkmcnt(2)
	v_sub_f32_e32 v83, v83, v1
	v_sub_f32_e32 v82, v82, v1
	v_sub_f32_e32 v89, v87, v1
	v_sub_f32_e32 v88, v75, v1
	s_waitcnt lgkmcnt(1)
	v_pk_mul_f32 v[88:89], v[74:75], v[88:89] op_sel_hi:[0,1]
	v_pk_mul_f32 v[74:75], v[74:75], v[82:83] op_sel_hi:[0,1]
	ds_read_b32 v83, v37
	ds_read_b32 v82, v38
	v_ashrrev_i32_e32 v163, 31, v162
	v_ashrrev_i32_e32 v1, 31, v0
	v_lshl_add_u64 v[0:1], v[0:1], 0, v[162:163]
	v_lshlrev_b32_e32 v72, 16, v2
	v_and_b32_e32 v73, 0xffff0000, v2
	v_lshlrev_b32_e32 v2, 16, v3
	v_and_b32_e32 v3, 0xffff0000, v3
	v_pk_fma_f32 v[74:75], v[66:67], v[74:75], v[70:71]
	v_lshlrev_b64 v[0:1], 2, v[0:1]
	v_pk_add_f32 v[74:75], v[74:75], v[2:3]
	v_lshl_add_u64 v[2:3], v[80:81], 0, v[0:1]
	s_waitcnt lgkmcnt(2)
	v_lshlrev_b32_e32 v80, 16, v76
	v_and_b32_e32 v81, 0xffff0000, v76
	v_lshlrev_b32_e32 v76, 16, v77
	v_and_b32_e32 v77, 0xffff0000, v77
	v_pk_fma_f32 v[88:89], v[64:65], v[88:89], v[68:69]
	s_waitcnt lgkmcnt(1)
	v_sub_f32_e32 v77, v77, v83
	v_sub_f32_e32 v76, v76, v83
	v_sub_f32_e32 v81, v81, v83
	v_sub_f32_e32 v80, v80, v83
	v_pk_add_f32 v[72:73], v[88:89], v[72:73]
	s_waitcnt lgkmcnt(0)
	v_pk_mul_f32 v[80:81], v[82:83], v[80:81] op_sel_hi:[0,1]
	v_pk_mul_f32 v[76:77], v[82:83], v[76:77] op_sel_hi:[0,1]
	global_store_dwordx4 v[2:3], v[72:75], off offset:32
	v_pk_fma_f32 v[66:67], v[66:67], v[76:77], v[70:71]
	v_pk_fma_f32 v[64:65], v[64:65], v[80:81], v[68:69]
	v_lshlrev_b32_e32 v72, 16, v91
	v_and_b32_e32 v73, 0xffff0000, v91
	v_lshlrev_b32_e32 v74, 16, v92
	v_and_b32_e32 v75, 0xffff0000, v92
	v_pk_add_f32 v[66:67], v[66:67], v[74:75]
	v_pk_add_f32 v[64:65], v[64:65], v[72:73]
	v_lshl_add_u64 v[0:1], v[78:79], 0, v[0:1]
	global_store_dwordx4 v[0:1], v[64:67], off offset:32
	s_nop 1
	v_add_u32_e32 v64, 0x25040, v29
	v_add_u32_e32 v68, 0x25440, v29
	ds_read_b128 v[64:67], v64
	ds_read_b64 v[72:73], v24 offset:32
	ds_read_b128 v[68:71], v68
	ds_read_b32 v75, v31
	ds_read_b32 v74, v32
	ds_read_b64 v[76:77], v24 offset:16672
	s_waitcnt lgkmcnt(4)
	v_lshlrev_b32_e32 v82, 16, v72
	v_and_b32_e32 v83, 0xffff0000, v72
	v_lshlrev_b32_e32 v80, 16, v73
	v_and_b32_e32 v81, 0xffff0000, v73
	s_waitcnt lgkmcnt(2)
	v_sub_f32_e32 v81, v81, v75
	v_sub_f32_e32 v80, v80, v75
	v_sub_f32_e32 v83, v83, v75
	v_sub_f32_e32 v82, v82, v75
	s_waitcnt lgkmcnt(1)
; DI unsigned pack2(float a, float b) { f32x2_t v = {a, b}; bf16x2_t r = __builtin_convertvector(v, bf16x2_t); return __builtin_bit_cast(unsigned, r); }
; DI float bflo(unsigned u) { return __uint_as_float(u << 16); }
; DI float bfhi(unsigned u) { return __uint_as_float(u & 0xffff0000u); }
; template <bool LAST>
; DI void phase_gate(const Params& P, int layer, unsigned char* smem, int L, int G) {
;     ...
; #pragma unroll
;     for (int i = 0; i < 4; ++i)
; #pragma unroll
;       for (int q4 = 0; q4 < 4; ++q4) {
;         const int fl = wm2 * 128 + i * 32 + 8 * q4 + 4 * h2;
;         const int f0 = nt * 256 + fl;
;         const f32x4 gv = *(const f32x4*)(vecL + 512 + fl), bv = *(const f32x4*)(vecL + 768 + fl);
;         const float ga[4] = {gv.x, gv.y, gv.z, gv.w}, ba[4] = {bv.x, bv.y, bv.z, bv.w};
; #pragma unroll
;         for (int j = 0; j < 2; ++j) {
;           const int lrow = wn2 * 64 + j * 32 + r2;
;           const float mu = rowA[lrow], rstd = rowB[lrow];
;           uint2* sp = (uint2*)(stg + lrow * STG + fl);
;           const uint2 sv = *sp;
;           const float sa[4] = {bflo(sv.x), bfhi(sv.x), bflo(sv.y), bfhi(sv.y)};
;           float y[4];
;           const float gg[4] = {bflo(gq[i][j][2 * q4]), bfhi(gq[i][j][2 * q4]), bflo(gq[i][j][2 * q4 + 1]), bfhi(gq[i][j][2 * q4 + 1])};
; #pragma unroll
;           for (int e = 0; e < 4; ++e) y[e] = (sa[e] - mu) * rstd * ga[e] + ba[e] + gg[e];
;           if (LAST) { f32x4 o = {y[0], y[1], y[2], y[3]}; *(f32x4*)(P.out + (size_t)(mt * 256 + lrow) * 1024 + f0) = o; }
;           else { uint2 pk; pk.x = pack2(y[0], y[1]); pk.y = pack2(y[2], y[3]); *sp = pk; }
;         }
;         __builtin_amdgcn_sched_barrier(0);
	v_pk_mul_f32 v[82:83], v[74:75], v[82:83] op_sel_hi:[0,1]
	v_pk_mul_f32 v[74:75], v[74:75], v[80:81] op_sel_hi:[0,1]
	ds_read_b32 v81, v37
	ds_read_b32 v80, v38
	v_lshlrev_b32_e32 v78, 16, v86
	v_and_b32_e32 v79, 0xffff0000, v86
	v_pk_fma_f32 v[74:75], v[66:67], v[74:75], v[70:71]
	v_lshlrev_b32_e32 v72, 16, v84
	v_pk_add_f32 v[74:75], v[74:75], v[78:79]
	s_waitcnt lgkmcnt(2)
	v_lshlrev_b32_e32 v78, 16, v76
	v_and_b32_e32 v79, 0xffff0000, v76
	v_lshlrev_b32_e32 v76, 16, v77
	v_and_b32_e32 v77, 0xffff0000, v77
	v_and_b32_e32 v73, 0xffff0000, v84
	v_pk_fma_f32 v[82:83], v[64:65], v[82:83], v[68:69]
	s_waitcnt lgkmcnt(1)
	v_sub_f32_e32 v77, v77, v81
	v_sub_f32_e32 v76, v76, v81
	v_sub_f32_e32 v79, v79, v81
	v_sub_f32_e32 v78, v78, v81
	v_pk_add_f32 v[72:73], v[82:83], v[72:73]
	s_waitcnt lgkmcnt(0)
	v_pk_mul_f32 v[78:79], v[80:81], v[78:79] op_sel_hi:[0,1]
	v_pk_mul_f32 v[76:77], v[80:81], v[76:77] op_sel_hi:[0,1]
	global_store_dwordx4 v[2:3], v[72:75], off offset:64
	v_pk_fma_f32 v[66:67], v[66:67], v[76:77], v[70:71]
	v_pk_fma_f32 v[64:65], v[64:65], v[78:79], v[68:69]
	v_lshlrev_b32_e32 v72, 16, v63
	v_and_b32_e32 v73, 0xffff0000, v63
	v_lshlrev_b32_e32 v74, 16, v85
	v_and_b32_e32 v75, 0xffff0000, v85
	v_pk_add_f32 v[66:67], v[66:67], v[74:75]
	v_pk_add_f32 v[64:65], v[64:65], v[72:73]
	global_store_dwordx4 v[0:1], v[64:67], off offset:64
	v_add_u32_e32 v63, 0x25060, v29
	ds_read_b128 v[64:67], v63
	v_add_u32_e32 v63, 0x25460, v29
	ds_read_b64 v[72:73], v24 offset:48
	ds_read_b128 v[68:71], v63
	ds_read_b32 v75, v31
	ds_read_b32 v74, v32
	ds_read_b64 v[76:77], v24 offset:16688
	s_waitcnt lgkmcnt(4)
	v_lshlrev_b32_e32 v80, 16, v72
	v_and_b32_e32 v81, 0xffff0000, v72
	v_lshlrev_b32_e32 v82, 16, v73
	v_and_b32_e32 v63, 0xffff0000, v73
	v_lshlrev_b32_e32 v78, 16, v62
	v_and_b32_e32 v79, 0xffff0000, v62
	s_waitcnt lgkmcnt(2)
	v_sub_f32_e32 v63, v63, v75
	v_sub_f32_e32 v62, v82, v75
	v_sub_f32_e32 v81, v81, v75
	v_sub_f32_e32 v80, v80, v75
	v_lshlrev_b32_e32 v72, 16, v60
	v_and_b32_e32 v73, 0xffff0000, v60
	s_waitcnt lgkmcnt(1)
	v_pk_mul_f32 v[80:81], v[74:75], v[80:81] op_sel_hi:[0,1]
	v_pk_mul_f32 v[62:63], v[74:75], v[62:63] op_sel_hi:[0,1]
	ds_read_b32 v82, v37
	ds_read_b32 v60, v38
	v_pk_fma_f32 v[62:63], v[66:67], v[62:63], v[70:71]
	v_pk_fma_f32 v[80:81], v[64:65], v[80:81], v[68:69]
	v_pk_add_f32 v[74:75], v[62:63], v[78:79]
	v_pk_add_f32 v[72:73], v[80:81], v[72:73]
	global_store_dwordx4 v[2:3], v[72:75], off offset:96
	s_waitcnt lgkmcnt(2)
	v_lshlrev_b32_e32 v78, 16, v76
	v_and_b32_e32 v76, 0xffff0000, v76
	v_lshlrev_b32_e32 v74, 16, v77
	v_and_b32_e32 v75, 0xffff0000, v77
	s_waitcnt lgkmcnt(1)
	v_sub_f32_e32 v75, v75, v82
	v_sub_f32_e32 v74, v74, v82
	v_sub_f32_e32 v77, v76, v82
	v_sub_f32_e32 v76, v78, v82
	v_lshlrev_b32_e32 v62, 16, v61
	v_and_b32_e32 v63, 0xffff0000, v61
	s_waitcnt lgkmcnt(0)
	v_pk_mul_f32 v[76:77], v[60:61], v[76:77] op_sel_hi:[0,1]
	v_pk_mul_f32 v[60:61], v[60:61], v[74:75] op_sel_hi:[0,1]
	v_lshlrev_b32_e32 v72, 16, v59
	v_and_b32_e32 v73, 0xffff0000, v59
	v_pk_fma_f32 v[60:61], v[66:67], v[60:61], v[70:71]
	v_pk_fma_f32 v[64:65], v[64:65], v[76:77], v[68:69]
	v_pk_add_f32 v[62:63], v[60:61], v[62:63]
	v_pk_add_f32 v[60:61], v[64:65], v[72:73]
	global_store_dwordx4 v[0:1], v[60:63], off offset:96
	v_add_u32_e32 v59, 0x25080, v29
	ds_read_b128 v[60:63], v59
	v_add_u32_e32 v59, 0x25480, v29
	ds_read_b64 v[68:69], v24 offset:64
	ds_read_b128 v[64:67], v59
	ds_read_b32 v71, v31
	ds_read_b32 v70, v32
	ds_read_b64 v[72:73], v24 offset:16704
	s_waitcnt lgkmcnt(4)
	v_lshlrev_b32_e32 v76, 16, v68
	v_and_b32_e32 v77, 0xffff0000, v68
	v_lshlrev_b32_e32 v78, 16, v69
	v_and_b32_e32 v59, 0xffff0000, v69
	v_lshlrev_b32_e32 v74, 16, v58
	v_and_b32_e32 v75, 0xffff0000, v58
	s_waitcnt lgkmcnt(2)
	v_sub_f32_e32 v59, v59, v71
	v_sub_f32_e32 v58, v78, v71
	v_sub_f32_e32 v77, v77, v71
	v_sub_f32_e32 v76, v76, v71
	v_lshlrev_b32_e32 v68, 16, v56
	v_and_b32_e32 v69, 0xffff0000, v56
	s_waitcnt lgkmcnt(1)
	v_pk_mul_f32 v[76:77], v[70:71], v[76:77] op_sel_hi:[0,1]
	v_pk_mul_f32 v[58:59], v[70:71], v[58:59] op_sel_hi:[0,1]
	ds_read_b32 v78, v37
	ds_read_b32 v56, v38
	v_pk_fma_f32 v[58:59], v[62:63], v[58:59], v[66:67]
	v_pk_fma_f32 v[76:77], v[60:61], v[76:77], v[64:65]
	v_pk_add_f32 v[70:71], v[58:59], v[74:75]
	v_pk_add_f32 v[68:69], v[76:77], v[68:69]
	global_store_dwordx4 v[2:3], v[68:71], off offset:128
	s_waitcnt lgkmcnt(2)
	v_lshlrev_b32_e32 v74, 16, v72
	v_and_b32_e32 v72, 0xffff0000, v72
	v_lshlrev_b32_e32 v70, 16, v73
	v_and_b32_e32 v71, 0xffff0000, v73
	s_waitcnt lgkmcnt(1)
	v_sub_f32_e32 v71, v71, v78
	v_sub_f32_e32 v70, v70, v78
	v_sub_f32_e32 v73, v72, v78
	v_sub_f32_e32 v72, v74, v78
	v_lshlrev_b32_e32 v58, 16, v57
	v_and_b32_e32 v59, 0xffff0000, v57
	s_waitcnt lgkmcnt(0)
	v_pk_mul_f32 v[72:73], v[56:57], v[72:73] op_sel_hi:[0,1]
	v_pk_mul_f32 v[56:57], v[56:57], v[70:71] op_sel_hi:[0,1]
	v_lshlrev_b32_e32 v68, 16, v55
	v_and_b32_e32 v69, 0xffff0000, v55
	v_pk_fma_f32 v[56:57], v[62:63], v[56:57], v[66:67]
	v_pk_fma_f32 v[60:61], v[60:61], v[72:73], v[64:65]
	v_pk_add_f32 v[58:59], v[56:57], v[58:59]
	v_pk_add_f32 v[56:57], v[60:61], v[68:69]
	global_store_dwordx4 v[0:1], v[56:59], off offset:128
	v_add_u32_e32 v55, 0x250a0, v29
	ds_read_b128 v[56:59], v55
	v_add_u32_e32 v55, 0x254a0, v29
	ds_read_b64 v[64:65], v24 offset:80
	ds_read_b128 v[60:63], v55
	ds_read_b32 v67, v31
	ds_read_b32 v66, v32
	ds_read_b64 v[68:69], v24 offset:16720
	s_waitcnt lgkmcnt(4)
	v_lshlrev_b32_e32 v72, 16, v64
	v_and_b32_e32 v73, 0xffff0000, v64
	v_lshlrev_b32_e32 v74, 16, v65
	v_and_b32_e32 v55, 0xffff0000, v65
	v_lshlrev_b32_e32 v70, 16, v54
	v_and_b32_e32 v71, 0xffff0000, v54
	s_waitcnt lgkmcnt(2)
; DI unsigned pack2(float a, float b) { f32x2_t v = {a, b}; bf16x2_t r = __builtin_convertvector(v, bf16x2_t); return __builtin_bit_cast(unsigned, r); }
; DI float bflo(unsigned u) { return __uint_as_float(u << 16); }
; DI float bfhi(unsigned u) { return __uint_as_float(u & 0xffff0000u); }
; template <bool LAST>
; DI void phase_gate(const Params& P, int layer, unsigned char* smem, int L, int G) {
;     ...
; #pragma unroll
;     for (int i = 0; i < 4; ++i)
; #pragma unroll
;       for (int q4 = 0; q4 < 4; ++q4) {
;         const int fl = wm2 * 128 + i * 32 + 8 * q4 + 4 * h2;
;         const int f0 = nt * 256 + fl;
;         const f32x4 gv = *(const f32x4*)(vecL + 512 + fl), bv = *(const f32x4*)(vecL + 768 + fl);
;         const float ga[4] = {gv.x, gv.y, gv.z, gv.w}, ba[4] = {bv.x, bv.y, bv.z, bv.w};
; #pragma unroll
;         for (int j = 0; j < 2; ++j) {
;           const int lrow = wn2 * 64 + j * 32 + r2;
;           const float mu = rowA[lrow], rstd = rowB[lrow];
;           uint2* sp = (uint2*)(stg + lrow * STG + fl);
;           const uint2 sv = *sp;
;           const float sa[4] = {bflo(sv.x), bfhi(sv.x), bflo(sv.y), bfhi(sv.y)};
;           float y[4];
;           const float gg[4] = {bflo(gq[i][j][2 * q4]), bfhi(gq[i][j][2 * q4]), bflo(gq[i][j][2 * q4 + 1]), bfhi(gq[i][j][2 * q4 + 1])};
; #pragma unroll
;           for (int e = 0; e < 4; ++e) y[e] = (sa[e] - mu) * rstd * ga[e] + ba[e] + gg[e];
;           if (LAST) { f32x4 o = {y[0], y[1], y[2], y[3]}; *(f32x4*)(P.out + (size_t)(mt * 256 + lrow) * 1024 + f0) = o; }
;           else { uint2 pk; pk.x = pack2(y[0], y[1]); pk.y = pack2(y[2], y[3]); *sp = pk; }
;         }
;         __builtin_amdgcn_sched_barrier(0);
	v_sub_f32_e32 v55, v55, v67
	v_sub_f32_e32 v54, v74, v67
	v_sub_f32_e32 v73, v73, v67
	v_sub_f32_e32 v72, v72, v67
	v_lshlrev_b32_e32 v64, 16, v52
	v_and_b32_e32 v65, 0xffff0000, v52
	s_waitcnt lgkmcnt(1)
	v_pk_mul_f32 v[72:73], v[66:67], v[72:73] op_sel_hi:[0,1]
	v_pk_mul_f32 v[54:55], v[66:67], v[54:55] op_sel_hi:[0,1]
	ds_read_b32 v74, v37
	ds_read_b32 v52, v38
	v_pk_fma_f32 v[54:55], v[58:59], v[54:55], v[62:63]
	v_pk_fma_f32 v[72:73], v[56:57], v[72:73], v[60:61]
	v_pk_add_f32 v[66:67], v[54:55], v[70:71]
	v_pk_add_f32 v[64:65], v[72:73], v[64:65]
	global_store_dwordx4 v[2:3], v[64:67], off offset:160
	s_waitcnt lgkmcnt(2)
	v_lshlrev_b32_e32 v70, 16, v68
	v_and_b32_e32 v68, 0xffff0000, v68
	v_lshlrev_b32_e32 v66, 16, v69
	v_and_b32_e32 v67, 0xffff0000, v69
	s_waitcnt lgkmcnt(1)
	v_sub_f32_e32 v67, v67, v74
	v_sub_f32_e32 v66, v66, v74
	v_sub_f32_e32 v69, v68, v74
	v_sub_f32_e32 v68, v70, v74
	v_lshlrev_b32_e32 v54, 16, v53
	v_and_b32_e32 v55, 0xffff0000, v53
	s_waitcnt lgkmcnt(0)
	v_pk_mul_f32 v[68:69], v[52:53], v[68:69] op_sel_hi:[0,1]
	v_pk_mul_f32 v[52:53], v[52:53], v[66:67] op_sel_hi:[0,1]
	v_lshlrev_b32_e32 v64, 16, v51
	v_and_b32_e32 v65, 0xffff0000, v51
	v_pk_fma_f32 v[52:53], v[58:59], v[52:53], v[62:63]
	v_pk_fma_f32 v[56:57], v[56:57], v[68:69], v[60:61]
	v_pk_add_f32 v[54:55], v[52:53], v[54:55]
	v_pk_add_f32 v[52:53], v[56:57], v[64:65]
	global_store_dwordx4 v[0:1], v[52:55], off offset:160
	v_add_u32_e32 v51, 0x250c0, v29
	ds_read_b128 v[52:55], v51
	v_add_u32_e32 v51, 0x254c0, v29
	ds_read_b64 v[60:61], v24 offset:96
	ds_read_b128 v[56:59], v51
	ds_read_b32 v63, v31
	ds_read_b32 v62, v32
	ds_read_b64 v[64:65], v24 offset:16736
	s_waitcnt lgkmcnt(4)
	v_lshlrev_b32_e32 v68, 16, v60
	v_and_b32_e32 v69, 0xffff0000, v60
	v_lshlrev_b32_e32 v70, 16, v61
	v_and_b32_e32 v51, 0xffff0000, v61
	v_lshlrev_b32_e32 v66, 16, v50
	v_and_b32_e32 v67, 0xffff0000, v50
	s_waitcnt lgkmcnt(2)
	v_sub_f32_e32 v51, v51, v63
	v_sub_f32_e32 v50, v70, v63
	v_sub_f32_e32 v69, v69, v63
	v_sub_f32_e32 v68, v68, v63
	v_lshlrev_b32_e32 v60, 16, v48
	v_and_b32_e32 v61, 0xffff0000, v48
	s_waitcnt lgkmcnt(1)
	v_pk_mul_f32 v[68:69], v[62:63], v[68:69] op_sel_hi:[0,1]
	v_pk_mul_f32 v[50:51], v[62:63], v[50:51] op_sel_hi:[0,1]
	ds_read_b32 v70, v37
	ds_read_b32 v48, v38
	v_pk_fma_f32 v[50:51], v[54:55], v[50:51], v[58:59]
	v_pk_fma_f32 v[68:69], v[52:53], v[68:69], v[56:57]
	v_pk_add_f32 v[62:63], v[50:51], v[66:67]
	v_pk_add_f32 v[60:61], v[68:69], v[60:61]
	global_store_dwordx4 v[2:3], v[60:63], off offset:192
	s_waitcnt lgkmcnt(2)
	v_lshlrev_b32_e32 v66, 16, v64
	v_and_b32_e32 v64, 0xffff0000, v64
	v_lshlrev_b32_e32 v62, 16, v65
	v_and_b32_e32 v63, 0xffff0000, v65
	s_waitcnt lgkmcnt(1)
	v_sub_f32_e32 v63, v63, v70
	v_sub_f32_e32 v62, v62, v70
	v_sub_f32_e32 v65, v64, v70
	v_sub_f32_e32 v64, v66, v70
	v_lshlrev_b32_e32 v50, 16, v49
	v_and_b32_e32 v51, 0xffff0000, v49
	s_waitcnt lgkmcnt(0)
	v_pk_mul_f32 v[64:65], v[48:49], v[64:65] op_sel_hi:[0,1]
	v_pk_mul_f32 v[48:49], v[48:49], v[62:63] op_sel_hi:[0,1]
	v_lshlrev_b32_e32 v60, 16, v47
	v_and_b32_e32 v61, 0xffff0000, v47
	v_pk_fma_f32 v[48:49], v[54:55], v[48:49], v[58:59]
	v_pk_fma_f32 v[52:53], v[52:53], v[64:65], v[56:57]
	v_pk_add_f32 v[50:51], v[48:49], v[50:51]
	v_pk_add_f32 v[48:49], v[52:53], v[60:61]
	global_store_dwordx4 v[0:1], v[48:51], off offset:192
	v_add_u32_e32 v47, 0x250e0, v29
	ds_read_b128 v[48:51], v47
	v_add_u32_e32 v47, 0x254e0, v29
	ds_read_b64 v[56:57], v24 offset:112
	ds_read_b128 v[52:55], v47
	ds_read_b32 v59, v31
	ds_read_b32 v58, v32
	ds_read_b64 v[60:61], v24 offset:16752
	s_waitcnt lgkmcnt(4)
	v_lshlrev_b32_e32 v64, 16, v56
	v_and_b32_e32 v65, 0xffff0000, v56
	v_lshlrev_b32_e32 v66, 16, v57
	v_and_b32_e32 v47, 0xffff0000, v57
	v_lshlrev_b32_e32 v62, 16, v46
	v_and_b32_e32 v63, 0xffff0000, v46
	s_waitcnt lgkmcnt(2)
	v_sub_f32_e32 v47, v47, v59
	v_sub_f32_e32 v46, v66, v59
	v_sub_f32_e32 v65, v65, v59
	v_sub_f32_e32 v64, v64, v59
	v_lshlrev_b32_e32 v56, 16, v44
	v_and_b32_e32 v57, 0xffff0000, v44
	s_waitcnt lgkmcnt(1)
	v_pk_mul_f32 v[64:65], v[58:59], v[64:65] op_sel_hi:[0,1]
	v_pk_mul_f32 v[46:47], v[58:59], v[46:47] op_sel_hi:[0,1]
	ds_read_b32 v66, v37
	ds_read_b32 v44, v38
	v_pk_fma_f32 v[46:47], v[50:51], v[46:47], v[54:55]
	v_pk_fma_f32 v[64:65], v[48:49], v[64:65], v[52:53]
	v_pk_add_f32 v[58:59], v[46:47], v[62:63]
	v_pk_add_f32 v[56:57], v[64:65], v[56:57]
	global_store_dwordx4 v[2:3], v[56:59], off offset:224
	s_waitcnt lgkmcnt(2)
	v_lshlrev_b32_e32 v62, 16, v60
	v_and_b32_e32 v60, 0xffff0000, v60
	v_lshlrev_b32_e32 v58, 16, v61
	v_and_b32_e32 v59, 0xffff0000, v61
	s_waitcnt lgkmcnt(1)
	v_sub_f32_e32 v59, v59, v66
	v_sub_f32_e32 v58, v58, v66
	v_sub_f32_e32 v61, v60, v66
	v_sub_f32_e32 v60, v62, v66
	v_lshlrev_b32_e32 v46, 16, v45
	v_and_b32_e32 v47, 0xffff0000, v45
	s_waitcnt lgkmcnt(0)
	v_pk_mul_f32 v[60:61], v[44:45], v[60:61] op_sel_hi:[0,1]
	v_pk_mul_f32 v[44:45], v[44:45], v[58:59] op_sel_hi:[0,1]
	v_lshlrev_b32_e32 v56, 16, v43
	v_and_b32_e32 v57, 0xffff0000, v43
	v_pk_fma_f32 v[44:45], v[50:51], v[44:45], v[54:55]
	v_pk_fma_f32 v[48:49], v[48:49], v[60:61], v[52:53]
	v_pk_add_f32 v[46:47], v[44:45], v[46:47]
	v_pk_add_f32 v[44:45], v[48:49], v[56:57]
	global_store_dwordx4 v[0:1], v[44:47], off offset:224
	v_add_u32_e32 v43, 0x25100, v29
	ds_read_b128 v[44:47], v43
	v_add_u32_e32 v43, 0x25500, v29
	ds_read_b64 v[52:53], v24 offset:128
	ds_read_b128 v[48:51], v43
	ds_read_b32 v55, v31
	ds_read_b32 v54, v32
	ds_read_b64 v[56:57], v24 offset:16768
	s_waitcnt lgkmcnt(4)
; DI unsigned pack2(float a, float b) { f32x2_t v = {a, b}; bf16x2_t r = __builtin_convertvector(v, bf16x2_t); return __builtin_bit_cast(unsigned, r); }
; DI float bflo(unsigned u) { return __uint_as_float(u << 16); }
; DI float bfhi(unsigned u) { return __uint_as_float(u & 0xffff0000u); }
; template <bool LAST>
; DI void phase_gate(const Params& P, int layer, unsigned char* smem, int L, int G) {
;     ...
; #pragma unroll
;     for (int i = 0; i < 4; ++i)
; #pragma unroll
;       for (int q4 = 0; q4 < 4; ++q4) {
;         const int fl = wm2 * 128 + i * 32 + 8 * q4 + 4 * h2;
;         const int f0 = nt * 256 + fl;
;         const f32x4 gv = *(const f32x4*)(vecL + 512 + fl), bv = *(const f32x4*)(vecL + 768 + fl);
;         const float ga[4] = {gv.x, gv.y, gv.z, gv.w}, ba[4] = {bv.x, bv.y, bv.z, bv.w};
; #pragma unroll
;         for (int j = 0; j < 2; ++j) {
;           const int lrow = wn2 * 64 + j * 32 + r2;
;           const float mu = rowA[lrow], rstd = rowB[lrow];
;           uint2* sp = (uint2*)(stg + lrow * STG + fl);
;           const uint2 sv = *sp;
;           const float sa[4] = {bflo(sv.x), bfhi(sv.x), bflo(sv.y), bfhi(sv.y)};
;           float y[4];
;           const float gg[4] = {bflo(gq[i][j][2 * q4]), bfhi(gq[i][j][2 * q4]), bflo(gq[i][j][2 * q4 + 1]), bfhi(gq[i][j][2 * q4 + 1])};
; #pragma unroll
;           for (int e = 0; e < 4; ++e) y[e] = (sa[e] - mu) * rstd * ga[e] + ba[e] + gg[e];
;           if (LAST) { f32x4 o = {y[0], y[1], y[2], y[3]}; *(f32x4*)(P.out + (size_t)(mt * 256 + lrow) * 1024 + f0) = o; }
;           else { uint2 pk; pk.x = pack2(y[0], y[1]); pk.y = pack2(y[2], y[3]); *sp = pk; }
;         }
;         __builtin_amdgcn_sched_barrier(0);
	v_lshlrev_b32_e32 v60, 16, v52
	v_and_b32_e32 v61, 0xffff0000, v52
	v_lshlrev_b32_e32 v62, 16, v53
	v_and_b32_e32 v43, 0xffff0000, v53
	v_lshlrev_b32_e32 v58, 16, v42
	v_and_b32_e32 v59, 0xffff0000, v42
	s_waitcnt lgkmcnt(2)
	v_sub_f32_e32 v43, v43, v55
	v_sub_f32_e32 v42, v62, v55
	v_sub_f32_e32 v61, v61, v55
	v_sub_f32_e32 v60, v60, v55
	v_lshlrev_b32_e32 v52, 16, v40
	v_and_b32_e32 v53, 0xffff0000, v40
	s_waitcnt lgkmcnt(1)
	v_pk_mul_f32 v[60:61], v[54:55], v[60:61] op_sel_hi:[0,1]
	v_pk_mul_f32 v[42:43], v[54:55], v[42:43] op_sel_hi:[0,1]
	ds_read_b32 v62, v37
	ds_read_b32 v40, v38
	v_pk_fma_f32 v[42:43], v[46:47], v[42:43], v[50:51]
	v_pk_fma_f32 v[60:61], v[44:45], v[60:61], v[48:49]
	v_pk_add_f32 v[54:55], v[42:43], v[58:59]
	v_pk_add_f32 v[52:53], v[60:61], v[52:53]
	global_store_dwordx4 v[2:3], v[52:55], off offset:256
	s_waitcnt lgkmcnt(2)
	v_lshlrev_b32_e32 v58, 16, v56
	v_and_b32_e32 v56, 0xffff0000, v56
	v_lshlrev_b32_e32 v54, 16, v57
	v_and_b32_e32 v55, 0xffff0000, v57
	s_waitcnt lgkmcnt(1)
	v_sub_f32_e32 v55, v55, v62
	v_sub_f32_e32 v54, v54, v62
	v_sub_f32_e32 v57, v56, v62
	v_sub_f32_e32 v56, v58, v62
	v_lshlrev_b32_e32 v42, 16, v41
	v_and_b32_e32 v43, 0xffff0000, v41
	s_waitcnt lgkmcnt(0)
	v_pk_mul_f32 v[56:57], v[40:41], v[56:57] op_sel_hi:[0,1]
	v_pk_mul_f32 v[40:41], v[40:41], v[54:55] op_sel_hi:[0,1]
	v_lshlrev_b32_e32 v52, 16, v39
	v_and_b32_e32 v53, 0xffff0000, v39
	v_pk_fma_f32 v[40:41], v[46:47], v[40:41], v[50:51]
	v_pk_fma_f32 v[44:45], v[44:45], v[56:57], v[48:49]
	v_pk_add_f32 v[42:43], v[40:41], v[42:43]
	v_pk_add_f32 v[40:41], v[44:45], v[52:53]
	global_store_dwordx4 v[0:1], v[40:43], off offset:256
	v_add_u32_e32 v39, 0x25120, v29
	ds_read_b128 v[40:43], v39
	v_add_u32_e32 v39, 0x25520, v29
	ds_read_b64 v[48:49], v24 offset:144
	ds_read_b128 v[44:47], v39
	ds_read_b32 v39, v31
	ds_read_b32 v50, v32
	ds_read_b64 v[52:53], v24 offset:16784
	s_waitcnt lgkmcnt(4)
	v_lshlrev_b32_e32 v51, 16, v48
	v_and_b32_e32 v58, 0xffff0000, v48
	v_lshlrev_b32_e32 v56, 16, v49
	v_and_b32_e32 v57, 0xffff0000, v49
	v_lshlrev_b32_e32 v48, 16, v34
	v_and_b32_e32 v49, 0xffff0000, v34
	v_lshlrev_b32_e32 v54, 16, v36
	v_and_b32_e32 v55, 0xffff0000, v36
	s_waitcnt lgkmcnt(2)
	v_sub_f32_e32 v57, v57, v39
	v_sub_f32_e32 v56, v56, v39
	v_sub_f32_e32 v59, v58, v39
	v_sub_f32_e32 v58, v51, v39
	ds_read_b32 v36, v37
	ds_read_b32 v34, v38
	s_waitcnt lgkmcnt(3)
	v_pk_mul_f32 v[58:59], v[50:51], v[58:59] op_sel_hi:[0,1]
	v_pk_mul_f32 v[50:51], v[50:51], v[56:57] op_sel_hi:[0,1]
	v_pk_fma_f32 v[50:51], v[42:43], v[50:51], v[46:47]
	v_pk_fma_f32 v[56:57], v[40:41], v[58:59], v[44:45]
	v_pk_add_f32 v[50:51], v[50:51], v[54:55]
	s_waitcnt lgkmcnt(2)
	v_lshlrev_b32_e32 v39, 16, v52
	v_and_b32_e32 v54, 0xffff0000, v52
	v_lshlrev_b32_e32 v52, 16, v53
	v_and_b32_e32 v53, 0xffff0000, v53
	v_pk_add_f32 v[48:49], v[56:57], v[48:49]
	s_waitcnt lgkmcnt(1)
	v_sub_f32_e32 v53, v53, v36
	v_sub_f32_e32 v52, v52, v36
	v_sub_f32_e32 v55, v54, v36
	v_sub_f32_e32 v54, v39, v36
	global_store_dwordx4 v[2:3], v[48:51], off offset:288
	s_waitcnt lgkmcnt(0)
	v_pk_mul_f32 v[54:55], v[34:35], v[54:55] op_sel_hi:[0,1]
	v_pk_fma_f32 v[40:41], v[40:41], v[54:55], v[44:45]
	v_lshlrev_b32_e32 v50, 16, v35
	v_and_b32_e32 v51, 0xffff0000, v35
	v_pk_mul_f32 v[34:35], v[34:35], v[52:53] op_sel_hi:[0,1]
	v_lshlrev_b32_e32 v48, 16, v33
	v_and_b32_e32 v49, 0xffff0000, v33
	v_pk_fma_f32 v[34:35], v[42:43], v[34:35], v[46:47]
	v_pk_add_f32 v[40:41], v[40:41], v[48:49]
	v_pk_add_f32 v[42:43], v[34:35], v[50:51]
	global_store_dwordx4 v[0:1], v[40:43], off offset:288
	v_add_u32_e32 v33, 0x25140, v29
	ds_read_b128 v[40:43], v33
	v_add_u32_e32 v33, 0x25540, v29
	ds_read_b64 v[34:35], v24 offset:160
	ds_read_b128 v[44:47], v33
	ds_read_b32 v33, v31
	ds_read_b32 v36, v32
	ds_read_b64 v[52:53], v24 offset:16800
	s_waitcnt lgkmcnt(4)
	v_lshlrev_b32_e32 v39, 16, v34
	v_and_b32_e32 v54, 0xffff0000, v34
	v_lshlrev_b32_e32 v50, 16, v35
	v_and_b32_e32 v51, 0xffff0000, v35
	s_waitcnt lgkmcnt(2)
	v_sub_f32_e32 v51, v51, v33
	v_sub_f32_e32 v50, v50, v33
	v_sub_f32_e32 v55, v54, v33
	v_sub_f32_e32 v54, v39, v33
	v_lshlrev_b32_e32 v34, 16, v26
	v_and_b32_e32 v35, 0xffff0000, v26
	v_lshlrev_b32_e32 v48, 16, v28
	v_and_b32_e32 v49, 0xffff0000, v28
	s_waitcnt lgkmcnt(1)
	v_pk_mul_f32 v[54:55], v[36:37], v[54:55] op_sel_hi:[0,1]
	v_pk_mul_f32 v[50:51], v[36:37], v[50:51] op_sel_hi:[0,1]
	ds_read_b32 v28, v37
	ds_read_b32 v26, v38
	v_pk_fma_f32 v[50:51], v[42:43], v[50:51], v[46:47]
	v_pk_fma_f32 v[54:55], v[40:41], v[54:55], v[44:45]
	v_pk_add_f32 v[50:51], v[50:51], v[48:49]
	v_pk_add_f32 v[48:49], v[54:55], v[34:35]
	global_store_dwordx4 v[2:3], v[48:51], off offset:320
	s_waitcnt lgkmcnt(2)
	v_lshlrev_b32_e32 v33, 16, v52
	v_and_b32_e32 v36, 0xffff0000, v52
	v_lshlrev_b32_e32 v39, 16, v53
	v_and_b32_e32 v50, 0xffff0000, v53
	s_waitcnt lgkmcnt(1)
	v_sub_f32_e32 v51, v50, v28
	v_sub_f32_e32 v50, v39, v28
	v_sub_f32_e32 v53, v36, v28
	v_sub_f32_e32 v52, v33, v28
	v_lshlrev_b32_e32 v48, 16, v27
	v_and_b32_e32 v49, 0xffff0000, v27
	s_waitcnt lgkmcnt(0)
	v_pk_mul_f32 v[52:53], v[26:27], v[52:53] op_sel_hi:[0,1]
	v_pk_mul_f32 v[26:27], v[26:27], v[50:51] op_sel_hi:[0,1]
	v_lshlrev_b32_e32 v34, 16, v25
	v_and_b32_e32 v35, 0xffff0000, v25
	v_pk_fma_f32 v[26:27], v[42:43], v[26:27], v[46:47]
	v_pk_fma_f32 v[40:41], v[40:41], v[52:53], v[44:45]
	v_pk_add_f32 v[42:43], v[26:27], v[48:49]
	v_pk_add_f32 v[40:41], v[40:41], v[34:35]
	global_store_dwordx4 v[0:1], v[40:43], off offset:320
	v_add_u32_e32 v25, 0x25160, v29
	ds_read_b128 v[40:43], v25
	v_add_u32_e32 v25, 0x25560, v29
	ds_read_b64 v[26:27], v24 offset:176
	ds_read_b128 v[44:47], v25
	ds_read_b32 v25, v31
	ds_read_b32 v28, v32
	ds_read_b64 v[34:35], v24 offset:16816
	s_waitcnt lgkmcnt(4)
; DI unsigned pack2(float a, float b) { f32x2_t v = {a, b}; bf16x2_t r = __builtin_convertvector(v, bf16x2_t); return __builtin_bit_cast(unsigned, r); }
; DI float bflo(unsigned u) { return __uint_as_float(u << 16); }
; DI float bfhi(unsigned u) { return __uint_as_float(u & 0xffff0000u); }
; template <bool LAST>
; DI void phase_gate(const Params& P, int layer, unsigned char* smem, int L, int G) {
;     ...
; #pragma unroll
;     for (int i = 0; i < 4; ++i)
; #pragma unroll
;       for (int q4 = 0; q4 < 4; ++q4) {
;         const int fl = wm2 * 128 + i * 32 + 8 * q4 + 4 * h2;
;         const int f0 = nt * 256 + fl;
;         const f32x4 gv = *(const f32x4*)(vecL + 512 + fl), bv = *(const f32x4*)(vecL + 768 + fl);
;         const float ga[4] = {gv.x, gv.y, gv.z, gv.w}, ba[4] = {bv.x, bv.y, bv.z, bv.w};
; #pragma unroll
;         for (int j = 0; j < 2; ++j) {
;           const int lrow = wn2 * 64 + j * 32 + r2;
;           const float mu = rowA[lrow], rstd = rowB[lrow];
;           uint2* sp = (uint2*)(stg + lrow * STG + fl);
;           const uint2 sv = *sp;
;           const float sa[4] = {bflo(sv.x), bfhi(sv.x), bflo(sv.y), bfhi(sv.y)};
;           float y[4];
;           const float gg[4] = {bflo(gq[i][j][2 * q4]), bfhi(gq[i][j][2 * q4]), bflo(gq[i][j][2 * q4 + 1]), bfhi(gq[i][j][2 * q4 + 1])};
; #pragma unroll
;           for (int e = 0; e < 4; ++e) y[e] = (sa[e] - mu) * rstd * ga[e] + ba[e] + gg[e];
;           if (LAST) { f32x4 o = {y[0], y[1], y[2], y[3]}; *(f32x4*)(P.out + (size_t)(mt * 256 + lrow) * 1024 + f0) = o; }
;           else { uint2 pk; pk.x = pack2(y[0], y[1]); pk.y = pack2(y[2], y[3]); *sp = pk; }
;         }
;         __builtin_amdgcn_sched_barrier(0);
	v_lshlrev_b32_e32 v33, 16, v26
	v_and_b32_e32 v36, 0xffff0000, v26
	v_lshlrev_b32_e32 v39, 16, v27
	v_and_b32_e32 v50, 0xffff0000, v27
	s_waitcnt lgkmcnt(2)
	v_sub_f32_e32 v51, v50, v25
	v_sub_f32_e32 v50, v39, v25
	v_sub_f32_e32 v53, v36, v25
	v_sub_f32_e32 v52, v33, v25
	s_waitcnt lgkmcnt(1)
	v_pk_mul_f32 v[52:53], v[28:29], v[52:53] op_sel_hi:[0,1]
	v_pk_mul_f32 v[50:51], v[28:29], v[50:51] op_sel_hi:[0,1]
	ds_read_b32 v25, v37
	ds_read_b32 v28, v38
	v_lshlrev_b32_e32 v26, 16, v21
	v_and_b32_e32 v27, 0xffff0000, v21
	v_lshlrev_b32_e32 v48, 16, v23
	v_and_b32_e32 v49, 0xffff0000, v23
	v_pk_fma_f32 v[50:51], v[42:43], v[50:51], v[46:47]
	v_pk_fma_f32 v[52:53], v[40:41], v[52:53], v[44:45]
	s_waitcnt lgkmcnt(2)
	v_lshlrev_b32_e32 v33, 16, v34
	v_and_b32_e32 v34, 0xffff0000, v34
	v_lshlrev_b32_e32 v36, 16, v35
	v_and_b32_e32 v23, 0xffff0000, v35
	v_pk_add_f32 v[50:51], v[50:51], v[48:49]
	v_pk_add_f32 v[48:49], v[52:53], v[26:27]
	v_lshlrev_b32_e32 v26, 16, v20
	v_and_b32_e32 v27, 0xffff0000, v20
	v_lshlrev_b32_e32 v20, 16, v22
	v_and_b32_e32 v21, 0xffff0000, v22
	s_waitcnt lgkmcnt(1)
	v_sub_f32_e32 v23, v23, v25
	v_sub_f32_e32 v22, v36, v25
	v_sub_f32_e32 v35, v34, v25
	v_sub_f32_e32 v34, v33, v25
	s_waitcnt lgkmcnt(0)
	v_pk_mul_f32 v[34:35], v[28:29], v[34:35] op_sel_hi:[0,1]
	v_pk_mul_f32 v[22:23], v[28:29], v[22:23] op_sel_hi:[0,1]
	v_pk_fma_f32 v[22:23], v[42:43], v[22:23], v[46:47]
	v_pk_fma_f32 v[34:35], v[40:41], v[34:35], v[44:45]
	v_pk_add_f32 v[22:23], v[22:23], v[20:21]
	v_pk_add_f32 v[20:21], v[34:35], v[26:27]
	global_store_dwordx4 v[2:3], v[48:51], off offset:352
	global_store_dwordx4 v[0:1], v[20:23], off offset:352
	s_nop 1
	v_add_u32_e32 v20, 0x25180, v29
	v_add_u32_e32 v25, 0x25580, v29
	ds_read_b128 v[20:23], v20
	ds_read_b64 v[26:27], v24 offset:192
	ds_read_b128 v[40:43], v25
	ds_read_b32 v25, v31
	ds_read_b32 v28, v32
	ds_read_b64 v[34:35], v24 offset:16832
	s_waitcnt lgkmcnt(4)
	v_lshlrev_b32_e32 v33, 16, v26
	v_and_b32_e32 v36, 0xffff0000, v26
	v_lshlrev_b32_e32 v39, 16, v27
	v_and_b32_e32 v46, 0xffff0000, v27
	s_waitcnt lgkmcnt(2)
	v_sub_f32_e32 v47, v46, v25
	v_sub_f32_e32 v46, v39, v25
	v_sub_f32_e32 v49, v36, v25
	v_sub_f32_e32 v48, v33, v25
	s_waitcnt lgkmcnt(1)
	v_pk_mul_f32 v[48:49], v[28:29], v[48:49] op_sel_hi:[0,1]
	v_pk_mul_f32 v[46:47], v[28:29], v[46:47] op_sel_hi:[0,1]
	ds_read_b32 v25, v37
	ds_read_b32 v28, v38
	v_lshlrev_b32_e32 v26, 16, v17
	v_and_b32_e32 v27, 0xffff0000, v17
	v_lshlrev_b32_e32 v44, 16, v19
	v_and_b32_e32 v45, 0xffff0000, v19
	v_pk_fma_f32 v[46:47], v[22:23], v[46:47], v[42:43]
	v_pk_fma_f32 v[48:49], v[20:21], v[48:49], v[40:41]
	s_waitcnt lgkmcnt(2)
	v_lshlrev_b32_e32 v33, 16, v34
	v_and_b32_e32 v34, 0xffff0000, v34
	v_lshlrev_b32_e32 v36, 16, v35
	v_and_b32_e32 v19, 0xffff0000, v35
	v_pk_add_f32 v[46:47], v[46:47], v[44:45]
	v_pk_add_f32 v[44:45], v[48:49], v[26:27]
	v_lshlrev_b32_e32 v26, 16, v16
	v_and_b32_e32 v27, 0xffff0000, v16
	v_lshlrev_b32_e32 v16, 16, v18
	v_and_b32_e32 v17, 0xffff0000, v18
	s_waitcnt lgkmcnt(1)
	v_sub_f32_e32 v19, v19, v25
	v_sub_f32_e32 v18, v36, v25
	v_sub_f32_e32 v35, v34, v25
	v_sub_f32_e32 v34, v33, v25
	s_waitcnt lgkmcnt(0)
	v_pk_mul_f32 v[34:35], v[28:29], v[34:35] op_sel_hi:[0,1]
	v_pk_mul_f32 v[18:19], v[28:29], v[18:19] op_sel_hi:[0,1]
	v_pk_fma_f32 v[18:19], v[22:23], v[18:19], v[42:43]
	v_pk_fma_f32 v[20:21], v[20:21], v[34:35], v[40:41]
	v_pk_add_f32 v[18:19], v[18:19], v[16:17]
	v_pk_add_f32 v[16:17], v[20:21], v[26:27]
	global_store_dwordx4 v[2:3], v[44:47], off offset:384
	global_store_dwordx4 v[0:1], v[16:19], off offset:384
	s_nop 1
	v_add_u32_e32 v16, 0x251a0, v29
	v_add_u32_e32 v20, 0x255a0, v29
	ds_read_b128 v[16:19], v16
	ds_read_b64 v[26:27], v24 offset:208
	ds_read_b128 v[20:23], v20
	ds_read_b32 v25, v31
	ds_read_b32 v28, v32
	ds_read_b64 v[34:35], v24 offset:16848
	s_waitcnt lgkmcnt(4)
	v_lshlrev_b32_e32 v33, 16, v26
	v_and_b32_e32 v36, 0xffff0000, v26
	v_lshlrev_b32_e32 v39, 16, v27
	v_and_b32_e32 v42, 0xffff0000, v27
	s_waitcnt lgkmcnt(2)
	v_sub_f32_e32 v43, v42, v25
	v_sub_f32_e32 v42, v39, v25
	v_sub_f32_e32 v45, v36, v25
	v_sub_f32_e32 v44, v33, v25
	s_waitcnt lgkmcnt(1)
	v_pk_mul_f32 v[44:45], v[28:29], v[44:45] op_sel_hi:[0,1]
	v_pk_mul_f32 v[42:43], v[28:29], v[42:43] op_sel_hi:[0,1]
	ds_read_b32 v25, v37
	ds_read_b32 v28, v38
	v_lshlrev_b32_e32 v26, 16, v13
	v_and_b32_e32 v27, 0xffff0000, v13
	v_lshlrev_b32_e32 v40, 16, v15
	v_and_b32_e32 v41, 0xffff0000, v15
	v_pk_fma_f32 v[42:43], v[18:19], v[42:43], v[22:23]
	v_pk_fma_f32 v[44:45], v[16:17], v[44:45], v[20:21]
	s_waitcnt lgkmcnt(2)
; DI unsigned pack2(float a, float b) { f32x2_t v = {a, b}; bf16x2_t r = __builtin_convertvector(v, bf16x2_t); return __builtin_bit_cast(unsigned, r); }
; DI float bflo(unsigned u) { return __uint_as_float(u << 16); }
; DI float bfhi(unsigned u) { return __uint_as_float(u & 0xffff0000u); }
; template <bool LAST>
; DI void phase_gate(const Params& P, int layer, unsigned char* smem, int L, int G) {
;     ...
; #pragma unroll
;     for (int i = 0; i < 4; ++i)
; #pragma unroll
;       for (int q4 = 0; q4 < 4; ++q4) {
;         const int fl = wm2 * 128 + i * 32 + 8 * q4 + 4 * h2;
;         const int f0 = nt * 256 + fl;
;         const f32x4 gv = *(const f32x4*)(vecL + 512 + fl), bv = *(const f32x4*)(vecL + 768 + fl);
;         const float ga[4] = {gv.x, gv.y, gv.z, gv.w}, ba[4] = {bv.x, bv.y, bv.z, bv.w};
; #pragma unroll
;         for (int j = 0; j < 2; ++j) {
;           const int lrow = wn2 * 64 + j * 32 + r2;
;           const float mu = rowA[lrow], rstd = rowB[lrow];
;           uint2* sp = (uint2*)(stg + lrow * STG + fl);
;           const uint2 sv = *sp;
;           const float sa[4] = {bflo(sv.x), bfhi(sv.x), bflo(sv.y), bfhi(sv.y)};
;           float y[4];
;           const float gg[4] = {bflo(gq[i][j][2 * q4]), bfhi(gq[i][j][2 * q4]), bflo(gq[i][j][2 * q4 + 1]), bfhi(gq[i][j][2 * q4 + 1])};
; #pragma unroll
;           for (int e = 0; e < 4; ++e) y[e] = (sa[e] - mu) * rstd * ga[e] + ba[e] + gg[e];
;           if (LAST) { f32x4 o = {y[0], y[1], y[2], y[3]}; *(f32x4*)(P.out + (size_t)(mt * 256 + lrow) * 1024 + f0) = o; }
;           else { uint2 pk; pk.x = pack2(y[0], y[1]); pk.y = pack2(y[2], y[3]); *sp = pk; }
;         }
;         __builtin_amdgcn_sched_barrier(0);
;       }
;     __syncthreads();
;     if (!LAST) stage_store_tile(stg, xb + (size_t)mt * 256 * 1024 + nt * 256);
;     __syncthreads();
	v_lshlrev_b32_e32 v33, 16, v34
	v_and_b32_e32 v34, 0xffff0000, v34
	v_lshlrev_b32_e32 v36, 16, v35
	v_and_b32_e32 v15, 0xffff0000, v35
	v_pk_add_f32 v[42:43], v[42:43], v[40:41]
	v_pk_add_f32 v[40:41], v[44:45], v[26:27]
	v_lshlrev_b32_e32 v26, 16, v12
	v_and_b32_e32 v27, 0xffff0000, v12
	v_lshlrev_b32_e32 v12, 16, v14
	v_and_b32_e32 v13, 0xffff0000, v14
	s_waitcnt lgkmcnt(1)
	v_sub_f32_e32 v15, v15, v25
	v_sub_f32_e32 v14, v36, v25
	v_sub_f32_e32 v35, v34, v25
	v_sub_f32_e32 v34, v33, v25
	s_waitcnt lgkmcnt(0)
	v_pk_mul_f32 v[34:35], v[28:29], v[34:35] op_sel_hi:[0,1]
	v_pk_mul_f32 v[14:15], v[28:29], v[14:15] op_sel_hi:[0,1]
	v_pk_fma_f32 v[14:15], v[18:19], v[14:15], v[22:23]
	v_pk_fma_f32 v[16:17], v[16:17], v[34:35], v[20:21]
	v_pk_add_f32 v[14:15], v[14:15], v[12:13]
	v_pk_add_f32 v[12:13], v[16:17], v[26:27]
	global_store_dwordx4 v[2:3], v[40:43], off offset:416
	global_store_dwordx4 v[0:1], v[12:15], off offset:416
	s_nop 1
	v_add_u32_e32 v12, 0x251c0, v29
	v_add_u32_e32 v16, 0x255c0, v29
	ds_read_b128 v[12:15], v12
	ds_read_b64 v[20:21], v24 offset:224
	ds_read_b128 v[16:19], v16
	ds_read_b32 v23, v31
	ds_read_b32 v22, v32
	ds_read_b64 v[26:27], v24 offset:16864
	s_waitcnt lgkmcnt(4)
	v_lshlrev_b32_e32 v25, 16, v20
	v_and_b32_e32 v28, 0xffff0000, v20
	v_lshlrev_b32_e32 v33, 16, v21
	v_and_b32_e32 v36, 0xffff0000, v21
	s_waitcnt lgkmcnt(2)
	v_sub_f32_e32 v41, v36, v23
	v_sub_f32_e32 v40, v33, v23
	v_sub_f32_e32 v43, v28, v23
	v_sub_f32_e32 v42, v25, v23
	s_waitcnt lgkmcnt(1)
	v_pk_mul_f32 v[42:43], v[22:23], v[42:43] op_sel_hi:[0,1]
	v_pk_mul_f32 v[22:23], v[22:23], v[40:41] op_sel_hi:[0,1]
	ds_read_b32 v25, v37
	ds_read_b32 v28, v38
	v_lshlrev_b32_e32 v20, 16, v9
	v_and_b32_e32 v21, 0xffff0000, v9
	v_lshlrev_b32_e32 v34, 16, v11
	v_and_b32_e32 v35, 0xffff0000, v11
	v_pk_fma_f32 v[22:23], v[14:15], v[22:23], v[18:19]
	v_pk_fma_f32 v[40:41], v[12:13], v[42:43], v[16:17]
	v_pk_add_f32 v[22:23], v[22:23], v[34:35]
	v_pk_add_f32 v[20:21], v[40:41], v[20:21]
	global_store_dwordx4 v[2:3], v[20:23], off offset:448
	s_waitcnt lgkmcnt(2)
	v_and_b32_e32 v11, 0xffff0000, v27
	v_and_b32_e32 v9, 0xffff0000, v10
	v_lshlrev_b32_e32 v22, 16, v26
	v_and_b32_e32 v23, 0xffff0000, v26
	v_lshlrev_b32_e32 v26, 16, v27
	v_lshlrev_b32_e32 v20, 16, v8
	v_and_b32_e32 v21, 0xffff0000, v8
	v_lshlrev_b32_e32 v8, 16, v10
	s_waitcnt lgkmcnt(1)
	v_sub_f32_e32 v11, v11, v25
	v_sub_f32_e32 v10, v26, v25
	v_sub_f32_e32 v23, v23, v25
	v_sub_f32_e32 v22, v22, v25
	s_waitcnt lgkmcnt(0)
	v_pk_mul_f32 v[22:23], v[28:29], v[22:23] op_sel_hi:[0,1]
	v_pk_mul_f32 v[10:11], v[28:29], v[10:11] op_sel_hi:[0,1]
	v_pk_fma_f32 v[10:11], v[14:15], v[10:11], v[18:19]
	v_pk_fma_f32 v[12:13], v[12:13], v[22:23], v[16:17]
	v_pk_add_f32 v[10:11], v[10:11], v[8:9]
	v_pk_add_f32 v[8:9], v[12:13], v[20:21]
	global_store_dwordx4 v[0:1], v[8:11], off offset:448
	ds_read_b128 v[8:11], v30 offset:480
	ds_read_b64 v[16:17], v24 offset:240
	ds_read_b32 v19, v31
	ds_read_b32 v18, v32
	v_add_u32_e32 v12, 0x255e0, v29
	ds_read_b128 v[12:15], v12
	s_waitcnt lgkmcnt(3)
	v_lshlrev_b32_e32 v22, 16, v16
	v_and_b32_e32 v23, 0xffff0000, v16
	v_lshlrev_b32_e32 v20, 16, v17
	v_and_b32_e32 v21, 0xffff0000, v17
	s_waitcnt lgkmcnt(2)
	v_sub_f32_e32 v21, v21, v19
	v_sub_f32_e32 v20, v20, v19
	v_sub_f32_e32 v23, v23, v19
	v_sub_f32_e32 v22, v22, v19
	s_waitcnt lgkmcnt(1)
	v_pk_mul_f32 v[22:23], v[18:19], v[22:23] op_sel_hi:[0,1]
	v_pk_mul_f32 v[18:19], v[18:19], v[20:21] op_sel_hi:[0,1]
	ds_read_b32 v20, v38
	ds_read_b32 v21, v37
	ds_read_b64 v[24:25], v24 offset:16880
	v_lshlrev_b32_e32 v16, 16, v6
	v_and_b32_e32 v17, 0xffff0000, v6
	v_lshlrev_b32_e32 v6, 16, v7
	v_and_b32_e32 v7, 0xffff0000, v7
	s_waitcnt lgkmcnt(3)
	v_pk_fma_f32 v[18:19], v[10:11], v[18:19], v[14:15]
	v_pk_fma_f32 v[22:23], v[8:9], v[22:23], v[12:13]
	v_pk_add_f32 v[18:19], v[18:19], v[6:7]
	v_pk_add_f32 v[16:17], v[22:23], v[16:17]
	global_store_dwordx4 v[2:3], v[16:19], off offset:480
	s_waitcnt lgkmcnt(0)
	v_lshlrev_b32_e32 v6, 16, v25
	v_and_b32_e32 v7, 0xffff0000, v25
	v_lshlrev_b32_e32 v16, 16, v24
	v_and_b32_e32 v17, 0xffff0000, v24
	v_sub_f32_e32 v7, v7, v21
	v_sub_f32_e32 v6, v6, v21
	v_sub_f32_e32 v17, v17, v21
	v_sub_f32_e32 v16, v16, v21
	v_pk_mul_f32 v[16:17], v[20:21], v[16:17] op_sel_hi:[0,1]
	v_pk_mul_f32 v[6:7], v[20:21], v[6:7] op_sel_hi:[0,1]
	v_lshlrev_b32_e32 v2, 16, v4
	v_and_b32_e32 v3, 0xffff0000, v4
	v_lshlrev_b32_e32 v4, 16, v5
	v_and_b32_e32 v5, 0xffff0000, v5
	v_pk_fma_f32 v[6:7], v[10:11], v[6:7], v[14:15]
	v_pk_fma_f32 v[8:9], v[8:9], v[16:17], v[12:13]
	v_pk_add_f32 v[4:5], v[6:7], v[4:5]
	v_pk_add_f32 v[2:3], v[8:9], v[2:3]
	global_store_dwordx4 v[0:1], v[2:5], off offset:480
	s_add_i32 s25, s25, s74
	s_add_i32 s22, s22, s69
	s_add_i32 s23, s23, s24
	s_add_i32 s18, s70, s25
	s_cmpk_lt_i32 s18, 0x400
	s_barrier
	s_barrier
	s_cbranch_scc0 .LBB0_1810
